# GEMM K-loops: closing barrier of each 32-MFMA block moved up by 4 MFMAs (early arrival so the partner half starts while MFMAs are still queued)
# baseline (speedup 1.0000x reference)
; #define PG8_STAGE(bufoff, gbase, voff) do { _Pragma("unroll") for (int _i = 0; _i < 2; ++_i) \
;         __builtin_amdgcn_global_load_lds((const unsigned*)((const char*)(gbase) + (voff)[_i]), (PG8_LAS unsigned*)(lds + (bufoff) + ldsw + _i * 8192), 16, 0, 0); } while (0)
; #define PG8_LDA(dst, b, h) do { _Pragma("unroll") for (int m = 0; m < 4; ++m) _Pragma("unroll") for (int k = 0; k < 2; ++k) dst[m][k] = *(const PG8_LAS bf16x8*)(lds + PG8_SA(b, h) + aoff + m * 2048 + k * 1024); } while (0)
; #define PG8_LDB(dst, b, h) do { _Pragma("unroll") for (int n = 0; n < 2; ++n) _Pragma("unroll") for (int k = 0; k < 2; ++k) dst[n][k] = *(const PG8_LAS bf16x8*)(lds + PG8_SB(b, h) + boff + n * 2048 + k * 1024); } while (0)
; #define PG8_MMA(ai, bj, At, Bt) do { __builtin_amdgcn_s_setprio(1); _Pragma("unroll") for (int m = 0; m < 4; ++m) _Pragma("unroll") for (int n = 0; n < 2; ++n) _Pragma("unroll") for (int k = 0; k < 2; ++k) \
;         acc[ai][bj][m][n] = mma16<F16>(Bt[n][k], At[m][k], acc[ai][bj][m][n]); __builtin_amdgcn_s_setprio(0); } while (0)
; #define PG8_WAIT_V(n) asm volatile("s_waitcnt vmcnt(" #n ")" ::: "memory")
; template <class Epi, class Sched, bool ALIGN_EPI = false, bool SP2 = false, bool F16 = false>
; __device__ __forceinline__ void gemm_phase(PG8_LAS unsigned char* lds, const Gemm g, const Sched& S, const Epi& E, const int wid_in) {
;     ...
;             PG8_LDB(B0, 0, 0); PG8_LDB(B1, 0, 1); PG8_SCHED; PG8_LDA(At, 0, 0); PG8_STAGE(PG8_SA(1, 1), a1 + hstep, voffA);
;             PG8_WAIT_V(8); PG8_WAIT_L(0); PG8_BAR; PG8_MMA(0, 0, At, B0); PG8_MMA(0, 1, At, B1); PG8_BAR; PG8_SCHED;
;             PG8_LDA(At, 0, 1); PG8_STAGE(PG8_SB(0, 0), b2, voffB); PG8_STAGE(PG8_SB(0, 1), b2 + hstep, voffB); PG8_STAGE(PG8_SA(0, 0), a2, voffA);
;             PG8_WAIT_V(8); PG8_WAIT_L(0); PG8_BAR; PG8_MMA(1, 0, At, B0); PG8_MMA(1, 1, At, B1); PG8_BAR; PG8_SCHED;
;             PG8_LDB(B0, 1, 0); PG8_LDB(B1, 1, 1); PG8_SCHED; PG8_LDA(At, 1, 0); PG8_STAGE(PG8_SA(0, 1), a2 + hstep, voffA);
;             PG8_WAIT_V(8); PG8_WAIT_L(0); PG8_BAR; PG8_MMA(0, 0, At, B0); PG8_MMA(0, 1, At, B1); PG8_BAR; PG8_SCHED;
;             PG8_LDA(At, 1, 1); PG8_STAGE(PG8_SB(1, 0), b3, voffB); PG8_STAGE(PG8_SB(1, 1), b3 + hstep, voffB); PG8_STAGE(PG8_SA(1, 0), a3, voffA);
;             PG8_WAIT_V(8); PG8_WAIT_L(0); PG8_BAR; PG8_MMA(1, 0, At, B0); PG8_MMA(1, 1, At, B1); PG8_BAR; PG8_SCHED;
.LBB0_224:
	ds_read_b128 v[128:131], v184
	ds_read_b128 v[132:135], v184 offset:1024
	ds_read_b128 v[136:139], v184 offset:2048
	ds_read_b128 v[140:143], v184 offset:3072
	ds_read_b128 v[144:147], v185
	ds_read_b128 v[148:151], v185 offset:1024
	ds_read_b128 v[152:155], v185 offset:2048
	ds_read_b128 v[174:177], v185 offset:3072
	s_add_u32 s58, s56, 0xfffc0080
	s_addc_u32 s59, s57, -1
	s_cmp_eq_u32 s62, 12
	s_cselect_b32 s61, s9, s59
	s_cselect_b32 s60, s21, s58
	s_cselect_b32 s59, s42, s51
	s_cselect_b32 s58, s43, s49
	v_lshl_add_u64 v[178:179], s[56:57], 0, v[166:167]
	s_add_i32 m0, s83, 0xc000
	ds_read_b128 v[190:193], v186
	ds_read_b128 v[194:197], v186 offset:1024
	ds_read_b128 v[198:201], v186 offset:2048
	ds_read_b128 v[202:205], v186 offset:3072
	ds_read_b128 v[206:209], v186 offset:4096
	ds_read_b128 v[210:213], v186 offset:5120
	ds_read_b128 v[214:217], v186 offset:6144
	ds_read_b128 v[218:221], v186 offset:7168
	global_load_lds_dwordx4 v[178:179], off
	v_lshl_add_u64 v[178:179], s[56:57], 0, v[168:169]
	s_add_i32 m0, s83, 0xe000
	s_nop 0
	global_load_lds_dwordx4 v[178:179], off
	s_waitcnt vmcnt(8)
	s_waitcnt lgkmcnt(0)
	s_barrier
	s_setprio 1
	s_waitcnt lgkmcnt(0)
	v_mfma_f32_16x16x32_f16 v[124:127], v[128:131], v[190:193], v[124:127]
	v_mfma_f32_16x16x32_f16 v[120:123], v[136:139], v[190:193], v[120:123]
	v_mfma_f32_16x16x32_f16 v[108:111], v[128:131], v[198:201], v[108:111]
	v_mfma_f32_16x16x32_f16 v[104:107], v[136:139], v[198:201], v[104:107]
	v_mfma_f32_16x16x32_f16 v[92:95], v[128:131], v[206:209], v[92:95]
	v_mfma_f32_16x16x32_f16 v[88:91], v[136:139], v[206:209], v[88:91]
	v_mfma_f32_16x16x32_f16 v[76:79], v[128:131], v[214:217], v[76:79]
	v_mfma_f32_16x16x32_f16 v[72:75], v[136:139], v[214:217], v[72:75]
	v_mfma_f32_16x16x32_f16 v[124:127], v[132:135], v[194:197], v[124:127]
	v_mfma_f32_16x16x32_f16 v[120:123], v[140:143], v[194:197], v[120:123]
	v_mfma_f32_16x16x32_f16 v[108:111], v[132:135], v[202:205], v[108:111]
	v_mfma_f32_16x16x32_f16 v[104:107], v[140:143], v[202:205], v[104:107]
	v_mfma_f32_16x16x32_f16 v[92:95], v[132:135], v[210:213], v[92:95]
	v_mfma_f32_16x16x32_f16 v[88:91], v[140:143], v[210:213], v[88:91]
	v_mfma_f32_16x16x32_f16 v[76:79], v[132:135], v[218:221], v[76:79]
	v_mfma_f32_16x16x32_f16 v[72:75], v[140:143], v[218:221], v[72:75]
	s_setprio 0
	s_setprio 1
	v_mfma_f32_16x16x32_f16 v[116:119], v[144:147], v[190:193], v[116:119]
	v_mfma_f32_16x16x32_f16 v[112:115], v[152:155], v[190:193], v[112:115]
	v_mfma_f32_16x16x32_f16 v[100:103], v[144:147], v[198:201], v[100:103]
	v_mfma_f32_16x16x32_f16 v[96:99], v[152:155], v[198:201], v[96:99]
	v_mfma_f32_16x16x32_f16 v[84:87], v[144:147], v[206:209], v[84:87]
	v_mfma_f32_16x16x32_f16 v[80:83], v[152:155], v[206:209], v[80:83]
	v_mfma_f32_16x16x32_f16 v[68:71], v[144:147], v[214:217], v[68:71]
	v_mfma_f32_16x16x32_f16 v[64:67], v[152:155], v[214:217], v[64:67]
	v_mfma_f32_16x16x32_f16 v[116:119], v[148:151], v[194:197], v[116:119]
	v_mfma_f32_16x16x32_f16 v[112:115], v[174:177], v[194:197], v[112:115]
	v_mfma_f32_16x16x32_f16 v[100:103], v[148:151], v[202:205], v[100:103]
	v_mfma_f32_16x16x32_f16 v[96:99], v[174:177], v[202:205], v[96:99]
	s_barrier
	v_mfma_f32_16x16x32_f16 v[84:87], v[148:151], v[210:213], v[84:87]
	v_mfma_f32_16x16x32_f16 v[80:83], v[174:177], v[210:213], v[80:83]
	v_mfma_f32_16x16x32_f16 v[68:71], v[148:151], v[218:221], v[68:71]
	v_mfma_f32_16x16x32_f16 v[64:67], v[174:177], v[218:221], v[64:67]
	s_setprio 0
	s_add_i32 s63, s40, s68
	v_lshl_add_u64 v[178:179], s[58:59], 0, v[158:159]
	s_mov_b32 m0, s63
	ds_read_b128 v[190:193], v186 offset:16384
	ds_read_b128 v[194:197], v186 offset:17408
	ds_read_b128 v[198:201], v186 offset:18432
	ds_read_b128 v[202:205], v186 offset:19456
	ds_read_b128 v[206:209], v186 offset:20480
	ds_read_b128 v[210:213], v186 offset:21504
	ds_read_b128 v[214:217], v186 offset:22528
	ds_read_b128 v[218:221], v186 offset:23552
	global_load_lds_dwordx4 v[178:179], off
	s_add_i32 m0, s63, 0x2000
	s_add_u32 s64, s58, 0x40000
	v_lshl_add_u64 v[222:223], s[58:59], 0, v[162:163]
	s_addc_u32 s65, s59, 0
	s_add_i32 s63, s41, s68
	global_load_lds_dwordx4 v[222:223], off
	v_lshl_add_u64 v[224:225], s[64:65], 0, v[158:159]
	s_mov_b32 m0, s63
	v_lshl_add_u64 v[226:227], s[60:61], 0, v[160:161]
	global_load_lds_dwordx4 v[224:225], off
	v_lshl_add_u64 v[224:225], s[64:65], 0, v[162:163]
	s_add_i32 m0, s63, 0x2000
	s_nop 0
	global_load_lds_dwordx4 v[224:225], off
	v_lshl_add_u64 v[224:225], s[60:61], 0, v[156:157]
	s_mov_b32 m0, s83
	s_nop 0
	global_load_lds_dwordx4 v[224:225], off
	s_mov_b32 m0, s84
	s_nop 0
	global_load_lds_dwordx4 v[226:227], off
	s_waitcnt vmcnt(8)
	s_waitcnt lgkmcnt(0)
	s_barrier
; #define PG8_STAGE(bufoff, gbase, voff) do { _Pragma("unroll") for (int _i = 0; _i < 2; ++_i) \
;         __builtin_amdgcn_global_load_lds((const unsigned*)((const char*)(gbase) + (voff)[_i]), (PG8_LAS unsigned*)(lds + (bufoff) + ldsw + _i * 8192), 16, 0, 0); } while (0)
; #define PG8_LDA(dst, b, h) do { _Pragma("unroll") for (int m = 0; m < 4; ++m) _Pragma("unroll") for (int k = 0; k < 2; ++k) dst[m][k] = *(const PG8_LAS bf16x8*)(lds + PG8_SA(b, h) + aoff + m * 2048 + k * 1024); } while (0)
; #define PG8_LDB(dst, b, h) do { _Pragma("unroll") for (int n = 0; n < 2; ++n) _Pragma("unroll") for (int k = 0; k < 2; ++k) dst[n][k] = *(const PG8_LAS bf16x8*)(lds + PG8_SB(b, h) + boff + n * 2048 + k * 1024); } while (0)
; #define PG8_MMA(ai, bj, At, Bt) do { __builtin_amdgcn_s_setprio(1); _Pragma("unroll") for (int m = 0; m < 4; ++m) _Pragma("unroll") for (int n = 0; n < 2; ++n) _Pragma("unroll") for (int k = 0; k < 2; ++k) \
;         acc[ai][bj][m][n] = mma16<F16>(Bt[n][k], At[m][k], acc[ai][bj][m][n]); __builtin_amdgcn_s_setprio(0); } while (0)
; #define PG8_WAIT_V(n) asm volatile("s_waitcnt vmcnt(" #n ")" ::: "memory")
; template <class Epi, class Sched, bool ALIGN_EPI = false, bool SP2 = false, bool F16 = false>
; __device__ __forceinline__ void gemm_phase(PG8_LAS unsigned char* lds, const Gemm g, const Sched& S, const Epi& E, const int wid_in) {
;     ...
;             PG8_LDB(B0, 0, 0); PG8_LDB(B1, 0, 1); PG8_SCHED; PG8_LDA(At, 0, 0); PG8_STAGE(PG8_SA(1, 1), a1 + hstep, voffA);
;             PG8_WAIT_V(8); PG8_WAIT_L(0); PG8_BAR; PG8_MMA(0, 0, At, B0); PG8_MMA(0, 1, At, B1); PG8_BAR; PG8_SCHED;
;             PG8_LDA(At, 0, 1); PG8_STAGE(PG8_SB(0, 0), b2, voffB); PG8_STAGE(PG8_SB(0, 1), b2 + hstep, voffB); PG8_STAGE(PG8_SA(0, 0), a2, voffA);
;             PG8_WAIT_V(8); PG8_WAIT_L(0); PG8_BAR; PG8_MMA(1, 0, At, B0); PG8_MMA(1, 1, At, B1); PG8_BAR; PG8_SCHED;
;             PG8_LDB(B0, 1, 0); PG8_LDB(B1, 1, 1); PG8_SCHED; PG8_LDA(At, 1, 0); PG8_STAGE(PG8_SA(0, 1), a2 + hstep, voffA);
;             PG8_WAIT_V(8); PG8_WAIT_L(0); PG8_BAR; PG8_MMA(0, 0, At, B0); PG8_MMA(0, 1, At, B1); PG8_BAR; PG8_SCHED;
;             PG8_LDA(At, 1, 1); PG8_STAGE(PG8_SB(1, 0), b3, voffB); PG8_STAGE(PG8_SB(1, 1), b3 + hstep, voffB); PG8_STAGE(PG8_SA(1, 0), a3, voffA);
;             PG8_WAIT_V(8); PG8_WAIT_L(0); PG8_BAR; PG8_MMA(1, 0, At, B0); PG8_MMA(1, 1, At, B1); PG8_BAR; PG8_SCHED;
	s_setprio 1
	s_waitcnt lgkmcnt(0)
	v_mfma_f32_16x16x32_f16 v[60:63], v[128:131], v[190:193], v[60:63]
	v_mfma_f32_16x16x32_f16 v[56:59], v[136:139], v[190:193], v[56:59]
	v_mfma_f32_16x16x32_f16 v[44:47], v[128:131], v[198:201], v[44:47]
	v_mfma_f32_16x16x32_f16 v[40:43], v[136:139], v[198:201], v[40:43]
	v_mfma_f32_16x16x32_f16 v[28:31], v[128:131], v[206:209], v[28:31]
	v_mfma_f32_16x16x32_f16 v[24:27], v[136:139], v[206:209], v[24:27]
	v_mfma_f32_16x16x32_f16 v[12:15], v[128:131], v[214:217], v[12:15]
	v_mfma_f32_16x16x32_f16 v[8:11], v[136:139], v[214:217], v[8:11]
	v_mfma_f32_16x16x32_f16 v[60:63], v[132:135], v[194:197], v[60:63]
	v_mfma_f32_16x16x32_f16 v[56:59], v[140:143], v[194:197], v[56:59]
	v_mfma_f32_16x16x32_f16 v[44:47], v[132:135], v[202:205], v[44:47]
	v_mfma_f32_16x16x32_f16 v[40:43], v[140:143], v[202:205], v[40:43]
	v_mfma_f32_16x16x32_f16 v[28:31], v[132:135], v[210:213], v[28:31]
	v_mfma_f32_16x16x32_f16 v[24:27], v[140:143], v[210:213], v[24:27]
	v_mfma_f32_16x16x32_f16 v[12:15], v[132:135], v[218:221], v[12:15]
	v_mfma_f32_16x16x32_f16 v[8:11], v[140:143], v[218:221], v[8:11]
	s_setprio 0
	s_setprio 1
	v_mfma_f32_16x16x32_f16 v[52:55], v[144:147], v[190:193], v[52:55]
	v_mfma_f32_16x16x32_f16 v[48:51], v[152:155], v[190:193], v[48:51]
	v_mfma_f32_16x16x32_f16 v[36:39], v[144:147], v[198:201], v[36:39]
	v_mfma_f32_16x16x32_f16 v[32:35], v[152:155], v[198:201], v[32:35]
	v_mfma_f32_16x16x32_f16 v[20:23], v[144:147], v[206:209], v[20:23]
	v_mfma_f32_16x16x32_f16 v[16:19], v[152:155], v[206:209], v[16:19]
	v_mfma_f32_16x16x32_f16 v[4:7], v[144:147], v[214:217], v[4:7]
	v_mfma_f32_16x16x32_f16 v[0:3], v[152:155], v[214:217], v[0:3]
	v_mfma_f32_16x16x32_f16 v[52:55], v[148:151], v[194:197], v[52:55]
	v_mfma_f32_16x16x32_f16 v[48:51], v[174:177], v[194:197], v[48:51]
	v_mfma_f32_16x16x32_f16 v[36:39], v[148:151], v[202:205], v[36:39]
	v_mfma_f32_16x16x32_f16 v[32:35], v[174:177], v[202:205], v[32:35]
	s_barrier
	v_mfma_f32_16x16x32_f16 v[20:23], v[148:151], v[210:213], v[20:23]
	v_mfma_f32_16x16x32_f16 v[16:19], v[174:177], v[210:213], v[16:19]
	v_mfma_f32_16x16x32_f16 v[4:7], v[148:151], v[218:221], v[4:7]
	v_mfma_f32_16x16x32_f16 v[0:3], v[174:177], v[218:221], v[0:3]
	s_setprio 0
	s_add_i32 s63, 0, 0x18000
	s_add_i32 s64, 0, 0x1c000
	v_add_u32_e32 v140, s63, v183
	v_add_u32_e32 v165, s64, v183
	ds_read_b128 v[128:131], v140
	ds_read_b128 v[132:135], v140 offset:1024
	ds_read_b128 v[136:139], v140 offset:2048
	ds_read_b128 v[140:143], v140 offset:3072
	ds_read_b128 v[144:147], v165
	ds_read_b128 v[148:151], v165 offset:1024
	ds_read_b128 v[152:155], v165 offset:2048
	ds_read_b128 v[174:177], v165 offset:3072
	s_add_u32 s60, s60, 0x40000
	s_addc_u32 s61, s61, 0
	s_mov_b32 m0, s85
	v_lshl_add_u64 v[228:229], s[60:61], 0, v[156:157]
	ds_read_b128 v[190:193], v186 offset:32768
	ds_read_b128 v[194:197], v186 offset:33792
	ds_read_b128 v[198:201], v186 offset:34816
	ds_read_b128 v[202:205], v186 offset:35840
	ds_read_b128 v[206:209], v186 offset:36864
	ds_read_b128 v[210:213], v186 offset:37888
	ds_read_b128 v[214:217], v186 offset:38912
	ds_read_b128 v[218:221], v186 offset:39936
	global_load_lds_dwordx4 v[228:229], off
	v_lshl_add_u64 v[228:229], s[60:61], 0, v[160:161]
	s_mov_b32 m0, s86
	s_nop 0
	global_load_lds_dwordx4 v[228:229], off
	s_waitcnt vmcnt(8)
	s_waitcnt lgkmcnt(0)
	s_barrier
	s_setprio 1
	s_waitcnt lgkmcnt(0)
	v_mfma_f32_16x16x32_f16 v[124:127], v[128:131], v[190:193], v[124:127]
	v_mfma_f32_16x16x32_f16 v[120:123], v[136:139], v[190:193], v[120:123]
	v_mfma_f32_16x16x32_f16 v[108:111], v[128:131], v[198:201], v[108:111]
	v_mfma_f32_16x16x32_f16 v[104:107], v[136:139], v[198:201], v[104:107]
	v_mfma_f32_16x16x32_f16 v[92:95], v[128:131], v[206:209], v[92:95]
	v_mfma_f32_16x16x32_f16 v[88:91], v[136:139], v[206:209], v[88:91]
	v_mfma_f32_16x16x32_f16 v[76:79], v[128:131], v[214:217], v[76:79]
	v_mfma_f32_16x16x32_f16 v[72:75], v[136:139], v[214:217], v[72:75]
	v_mfma_f32_16x16x32_f16 v[124:127], v[132:135], v[194:197], v[124:127]
	v_mfma_f32_16x16x32_f16 v[120:123], v[140:143], v[194:197], v[120:123]
	v_mfma_f32_16x16x32_f16 v[108:111], v[132:135], v[202:205], v[108:111]
	v_mfma_f32_16x16x32_f16 v[104:107], v[140:143], v[202:205], v[104:107]
	v_mfma_f32_16x16x32_f16 v[92:95], v[132:135], v[210:213], v[92:95]
	v_mfma_f32_16x16x32_f16 v[88:91], v[140:143], v[210:213], v[88:91]
	v_mfma_f32_16x16x32_f16 v[76:79], v[132:135], v[218:221], v[76:79]
	v_mfma_f32_16x16x32_f16 v[72:75], v[140:143], v[218:221], v[72:75]
	s_setprio 0
	s_setprio 1
	v_mfma_f32_16x16x32_f16 v[116:119], v[144:147], v[190:193], v[116:119]
	v_mfma_f32_16x16x32_f16 v[112:115], v[152:155], v[190:193], v[112:115]
	v_mfma_f32_16x16x32_f16 v[100:103], v[144:147], v[198:201], v[100:103]
	v_mfma_f32_16x16x32_f16 v[96:99], v[152:155], v[198:201], v[96:99]
	v_mfma_f32_16x16x32_f16 v[84:87], v[144:147], v[206:209], v[84:87]
	v_mfma_f32_16x16x32_f16 v[80:83], v[152:155], v[206:209], v[80:83]
	v_mfma_f32_16x16x32_f16 v[68:71], v[144:147], v[214:217], v[68:71]
	v_mfma_f32_16x16x32_f16 v[64:67], v[152:155], v[214:217], v[64:67]
	v_mfma_f32_16x16x32_f16 v[116:119], v[148:151], v[194:197], v[116:119]
	v_mfma_f32_16x16x32_f16 v[112:115], v[174:177], v[194:197], v[112:115]
	v_mfma_f32_16x16x32_f16 v[100:103], v[148:151], v[202:205], v[100:103]
	v_mfma_f32_16x16x32_f16 v[96:99], v[174:177], v[202:205], v[96:99]
	s_barrier
; #define PG8_STAGE(bufoff, gbase, voff) do { _Pragma("unroll") for (int _i = 0; _i < 2; ++_i) \
;         __builtin_amdgcn_global_load_lds((const unsigned*)((const char*)(gbase) + (voff)[_i]), (PG8_LAS unsigned*)(lds + (bufoff) + ldsw + _i * 8192), 16, 0, 0); } while (0)
; #define PG8_LDA(dst, b, h) do { _Pragma("unroll") for (int m = 0; m < 4; ++m) _Pragma("unroll") for (int k = 0; k < 2; ++k) dst[m][k] = *(const PG8_LAS bf16x8*)(lds + PG8_SA(b, h) + aoff + m * 2048 + k * 1024); } while (0)
; #define PG8_LDB(dst, b, h) do { _Pragma("unroll") for (int n = 0; n < 2; ++n) _Pragma("unroll") for (int k = 0; k < 2; ++k) dst[n][k] = *(const PG8_LAS bf16x8*)(lds + PG8_SB(b, h) + boff + n * 2048 + k * 1024); } while (0)
; #define PG8_MMA(ai, bj, At, Bt) do { __builtin_amdgcn_s_setprio(1); _Pragma("unroll") for (int m = 0; m < 4; ++m) _Pragma("unroll") for (int n = 0; n < 2; ++n) _Pragma("unroll") for (int k = 0; k < 2; ++k) \
;         acc[ai][bj][m][n] = mma16<F16>(Bt[n][k], At[m][k], acc[ai][bj][m][n]); __builtin_amdgcn_s_setprio(0); } while (0)
; #define PG8_WAIT_V(n) asm volatile("s_waitcnt vmcnt(" #n ")" ::: "memory")
; template <class Epi, class Sched, bool ALIGN_EPI = false, bool SP2 = false, bool F16 = false>
; __device__ __forceinline__ void gemm_phase(PG8_LAS unsigned char* lds, const Gemm g, const Sched& S, const Epi& E, const int wid_in) {
;     ...
;             PG8_LDB(B0, 0, 0); PG8_LDB(B1, 0, 1); PG8_SCHED; PG8_LDA(At, 0, 0); PG8_STAGE(PG8_SA(1, 1), a1 + hstep, voffA);
;             PG8_WAIT_V(8); PG8_WAIT_L(0); PG8_BAR; PG8_MMA(0, 0, At, B0); PG8_MMA(0, 1, At, B1); PG8_BAR; PG8_SCHED;
;             PG8_LDA(At, 0, 1); PG8_STAGE(PG8_SB(0, 0), b2, voffB); PG8_STAGE(PG8_SB(0, 1), b2 + hstep, voffB); PG8_STAGE(PG8_SA(0, 0), a2, voffA);
;             PG8_WAIT_V(8); PG8_WAIT_L(0); PG8_BAR; PG8_MMA(1, 0, At, B0); PG8_MMA(1, 1, At, B1); PG8_BAR; PG8_SCHED;
;             PG8_LDB(B0, 1, 0); PG8_LDB(B1, 1, 1); PG8_SCHED; PG8_LDA(At, 1, 0); PG8_STAGE(PG8_SA(0, 1), a2 + hstep, voffA);
;             PG8_WAIT_V(8); PG8_WAIT_L(0); PG8_BAR; PG8_MMA(0, 0, At, B0); PG8_MMA(0, 1, At, B1); PG8_BAR; PG8_SCHED;
;             PG8_LDA(At, 1, 1); PG8_STAGE(PG8_SB(1, 0), b3, voffB); PG8_STAGE(PG8_SB(1, 1), b3 + hstep, voffB); PG8_STAGE(PG8_SA(1, 0), a3, voffA);
;             PG8_WAIT_V(8); PG8_WAIT_L(0); PG8_BAR; PG8_MMA(1, 0, At, B0); PG8_MMA(1, 1, At, B1); PG8_BAR; PG8_SCHED;
	v_mfma_f32_16x16x32_f16 v[84:87], v[148:151], v[210:213], v[84:87]
	v_mfma_f32_16x16x32_f16 v[80:83], v[174:177], v[210:213], v[80:83]
	v_mfma_f32_16x16x32_f16 v[68:71], v[148:151], v[218:221], v[68:71]
	v_mfma_f32_16x16x32_f16 v[64:67], v[174:177], v[218:221], v[64:67]
	s_setprio 0
	s_add_i32 s60, s63, s68
	v_lshl_add_u64 v[178:179], v[178:179], 0, s[24:25]
	s_mov_b32 m0, s60
	ds_read_b128 v[190:193], v186 offset:49152
	ds_read_b128 v[194:197], v186 offset:50176
	ds_read_b128 v[198:201], v186 offset:51200
	ds_read_b128 v[202:205], v186 offset:52224
	ds_read_b128 v[206:209], v186 offset:53248
	ds_read_b128 v[210:213], v186 offset:54272
	ds_read_b128 v[214:217], v186 offset:55296
	ds_read_b128 v[218:221], v186 offset:56320
	global_load_lds_dwordx4 v[178:179], off
	s_add_i32 m0, s60, 0x2000
	s_add_u32 s58, s58, 0x40080
	v_lshl_add_u64 v[178:179], v[222:223], 0, s[24:25]
	s_addc_u32 s59, s59, 0
	s_add_i32 s60, s64, s68
	global_load_lds_dwordx4 v[178:179], off
	v_lshl_add_u64 v[178:179], s[58:59], 0, v[158:159]
	s_mov_b32 m0, s60
	s_nop 0
	global_load_lds_dwordx4 v[178:179], off
	v_lshl_add_u64 v[178:179], s[58:59], 0, v[162:163]
	s_add_i32 m0, s60, 0x2000
	s_nop 0
	global_load_lds_dwordx4 v[178:179], off
	v_lshl_add_u64 v[178:179], v[224:225], 0, s[24:25]
	s_mov_b32 m0, s90
	s_nop 0
	global_load_lds_dwordx4 v[178:179], off
	v_lshl_add_u64 v[178:179], v[226:227], 0, s[24:25]
	s_mov_b32 m0, s91
	s_nop 0
	global_load_lds_dwordx4 v[178:179], off
	s_waitcnt vmcnt(8)
	s_waitcnt lgkmcnt(0)
	s_barrier
	s_setprio 1
	s_waitcnt lgkmcnt(0)
	v_mfma_f32_16x16x32_f16 v[60:63], v[128:131], v[190:193], v[60:63]
	v_mfma_f32_16x16x32_f16 v[56:59], v[136:139], v[190:193], v[56:59]
	v_mfma_f32_16x16x32_f16 v[44:47], v[128:131], v[198:201], v[44:47]
	v_mfma_f32_16x16x32_f16 v[40:43], v[136:139], v[198:201], v[40:43]
	v_mfma_f32_16x16x32_f16 v[28:31], v[128:131], v[206:209], v[28:31]
	v_mfma_f32_16x16x32_f16 v[24:27], v[136:139], v[206:209], v[24:27]
	v_mfma_f32_16x16x32_f16 v[12:15], v[128:131], v[214:217], v[12:15]
	v_mfma_f32_16x16x32_f16 v[8:11], v[136:139], v[214:217], v[8:11]
	v_mfma_f32_16x16x32_f16 v[60:63], v[132:135], v[194:197], v[60:63]
	v_mfma_f32_16x16x32_f16 v[56:59], v[140:143], v[194:197], v[56:59]
	v_mfma_f32_16x16x32_f16 v[44:47], v[132:135], v[202:205], v[44:47]
	v_mfma_f32_16x16x32_f16 v[40:43], v[140:143], v[202:205], v[40:43]
	v_mfma_f32_16x16x32_f16 v[28:31], v[132:135], v[210:213], v[28:31]
	v_mfma_f32_16x16x32_f16 v[24:27], v[140:143], v[210:213], v[24:27]
	v_mfma_f32_16x16x32_f16 v[12:15], v[132:135], v[218:221], v[12:15]
	v_mfma_f32_16x16x32_f16 v[8:11], v[140:143], v[218:221], v[8:11]
	s_setprio 0
	s_setprio 1
	v_mfma_f32_16x16x32_f16 v[52:55], v[144:147], v[190:193], v[52:55]
	v_mfma_f32_16x16x32_f16 v[48:51], v[152:155], v[190:193], v[48:51]
	v_mfma_f32_16x16x32_f16 v[36:39], v[144:147], v[198:201], v[36:39]
	v_mfma_f32_16x16x32_f16 v[32:35], v[152:155], v[198:201], v[32:35]
	v_mfma_f32_16x16x32_f16 v[20:23], v[144:147], v[206:209], v[20:23]
	v_mfma_f32_16x16x32_f16 v[16:19], v[152:155], v[206:209], v[16:19]
	v_mfma_f32_16x16x32_f16 v[4:7], v[144:147], v[214:217], v[4:7]
	v_mfma_f32_16x16x32_f16 v[0:3], v[152:155], v[214:217], v[0:3]
	v_mfma_f32_16x16x32_f16 v[52:55], v[148:151], v[194:197], v[52:55]
	v_mfma_f32_16x16x32_f16 v[48:51], v[174:177], v[194:197], v[48:51]
	v_mfma_f32_16x16x32_f16 v[36:39], v[148:151], v[202:205], v[36:39]
	v_mfma_f32_16x16x32_f16 v[32:35], v[174:177], v[202:205], v[32:35]
	s_barrier
	v_mfma_f32_16x16x32_f16 v[20:23], v[148:151], v[210:213], v[20:23]
	v_mfma_f32_16x16x32_f16 v[16:19], v[174:177], v[210:213], v[16:19]
	v_mfma_f32_16x16x32_f16 v[4:7], v[148:151], v[218:221], v[4:7]
	v_mfma_f32_16x16x32_f16 v[0:3], v[174:177], v[218:221], v[0:3]
	s_setprio 0
	s_add_i32 s62, s62, 2
	s_add_u32 s56, s56, 0x100
	s_addc_u32 s57, s57, 0
	s_add_u32 s49, s49, 0x100
	s_addc_u32 s51, s51, 0
	s_cmp_gt_u32 s62, 13
	s_cbranch_scc0 .LBB0_224
	s_and_b64 vcc, exec, s[26:27]
	s_cbranch_vccz .LBB0_227
	s_barrier

; #define PG8_STAGE(bufoff, gbase, voff) do { _Pragma("unroll") for (int _i = 0; _i < 2; ++_i) \
;         __builtin_amdgcn_global_load_lds((const unsigned*)((const char*)(gbase) + (voff)[_i]), (PG8_LAS unsigned*)(lds + (bufoff) + ldsw + _i * 8192), 16, 0, 0); } while (0)
; #define PG8_LDA(dst, b, h) do { _Pragma("unroll") for (int m = 0; m < 4; ++m) _Pragma("unroll") for (int k = 0; k < 2; ++k) dst[m][k] = *(const PG8_LAS bf16x8*)(lds + PG8_SA(b, h) + aoff + m * 2048 + k * 1024); } while (0)
; #define PG8_LDB(dst, b, h) do { _Pragma("unroll") for (int n = 0; n < 2; ++n) _Pragma("unroll") for (int k = 0; k < 2; ++k) dst[n][k] = *(const PG8_LAS bf16x8*)(lds + PG8_SB(b, h) + boff + n * 2048 + k * 1024); } while (0)
; #define PG8_MMA(ai, bj, At, Bt) do { __builtin_amdgcn_s_setprio(1); _Pragma("unroll") for (int m = 0; m < 4; ++m) _Pragma("unroll") for (int n = 0; n < 2; ++n) _Pragma("unroll") for (int k = 0; k < 2; ++k) \
;         acc[ai][bj][m][n] = mma16<F16>(Bt[n][k], At[m][k], acc[ai][bj][m][n]); __builtin_amdgcn_s_setprio(0); } while (0)
; #define PG8_WAIT_V(n) asm volatile("s_waitcnt vmcnt(" #n ")" ::: "memory")
; template <class Epi, class Sched, bool ALIGN_EPI = false, bool SP2 = false, bool F16 = false>
; __device__ __forceinline__ void gemm_phase(PG8_LAS unsigned char* lds, const Gemm g, const Sched& S, const Epi& E, const int wid_in) {
;     ...
;             PG8_LDB(B0, 0, 0); PG8_LDB(B1, 0, 1); PG8_SCHED; PG8_LDA(At, 0, 0); PG8_STAGE(PG8_SA(1, 1), a1 + hstep, voffA);
;             PG8_WAIT_V(8); PG8_WAIT_L(0); PG8_BAR; PG8_MMA(0, 0, At, B0); PG8_MMA(0, 1, At, B1); PG8_BAR; PG8_SCHED;
;             PG8_LDA(At, 0, 1); PG8_STAGE(PG8_SB(0, 0), b2, voffB); PG8_STAGE(PG8_SB(0, 1), b2 + hstep, voffB); PG8_STAGE(PG8_SA(0, 0), a2, voffA);
;             PG8_WAIT_V(8); PG8_WAIT_L(0); PG8_BAR; PG8_MMA(1, 0, At, B0); PG8_MMA(1, 1, At, B1); PG8_BAR; PG8_SCHED;
;             PG8_LDB(B0, 1, 0); PG8_LDB(B1, 1, 1); PG8_SCHED; PG8_LDA(At, 1, 0); PG8_STAGE(PG8_SA(0, 1), a2 + hstep, voffA);
;             PG8_WAIT_V(8); PG8_WAIT_L(0); PG8_BAR; PG8_MMA(0, 0, At, B0); PG8_MMA(0, 1, At, B1); PG8_BAR; PG8_SCHED;
;             PG8_LDA(At, 1, 1); PG8_STAGE(PG8_SB(1, 0), b3, voffB); PG8_STAGE(PG8_SB(1, 1), b3 + hstep, voffB); PG8_STAGE(PG8_SA(1, 0), a3, voffA);
;             PG8_WAIT_V(8); PG8_WAIT_L(0); PG8_BAR; PG8_MMA(1, 0, At, B0); PG8_MMA(1, 1, At, B1); PG8_BAR; PG8_SCHED;
.LBB0_508:
	ds_read_b128 v[128:131], v189
	ds_read_b128 v[132:135], v189 offset:1024
	ds_read_b128 v[136:139], v189 offset:2048
	ds_read_b128 v[140:143], v189 offset:3072
	ds_read_b128 v[144:147], v190
	ds_read_b128 v[148:151], v190 offset:1024
	ds_read_b128 v[168:171], v190 offset:2048
	ds_read_b128 v[172:175], v190 offset:3072
	s_add_u32 s46, s44, 0xfffc0080
	s_addc_u32 s47, s45, -1
	s_cmp_eq_u32 s43, 12
	s_cselect_b32 s49, s10, s47
	s_cselect_b32 s48, s27, s46
	s_cselect_b32 s47, s25, s42
	s_cselect_b32 s46, s35, s37
	v_lshl_add_u64 v[184:185], s[44:45], 0, v[160:161]
	s_add_i32 m0, s74, 0xc000
	ds_read_b128 v[176:179], v191
	ds_read_b128 v[180:183], v191 offset:1024
	ds_read_b128 v[192:195], v191 offset:2048
	ds_read_b128 v[196:199], v191 offset:3072
	ds_read_b128 v[200:203], v191 offset:4096
	ds_read_b128 v[204:207], v191 offset:5120
	ds_read_b128 v[208:211], v191 offset:6144
	ds_read_b128 v[212:215], v191 offset:7168
	global_load_lds_dwordx4 v[184:185], off
	v_lshl_add_u64 v[184:185], s[44:45], 0, v[162:163]
	s_add_i32 m0, s74, 0xe000
	s_nop 0
	global_load_lds_dwordx4 v[184:185], off
	s_waitcnt vmcnt(8)
	s_waitcnt lgkmcnt(0)
	s_barrier
	s_setprio 1
	s_waitcnt lgkmcnt(0)
	v_mfma_f32_16x16x32_bf16 v[124:127], v[128:131], v[176:179], v[124:127]
	v_mfma_f32_16x16x32_bf16 v[120:123], v[136:139], v[176:179], v[120:123]
	v_mfma_f32_16x16x32_bf16 v[108:111], v[128:131], v[192:195], v[108:111]
	v_mfma_f32_16x16x32_bf16 v[104:107], v[136:139], v[192:195], v[104:107]
	v_mfma_f32_16x16x32_bf16 v[92:95], v[128:131], v[200:203], v[92:95]
	v_mfma_f32_16x16x32_bf16 v[88:91], v[136:139], v[200:203], v[88:91]
	v_mfma_f32_16x16x32_bf16 v[76:79], v[128:131], v[208:211], v[76:79]
	v_mfma_f32_16x16x32_bf16 v[72:75], v[136:139], v[208:211], v[72:75]
	v_mfma_f32_16x16x32_bf16 v[124:127], v[132:135], v[180:183], v[124:127]
	v_mfma_f32_16x16x32_bf16 v[120:123], v[140:143], v[180:183], v[120:123]
	v_mfma_f32_16x16x32_bf16 v[108:111], v[132:135], v[196:199], v[108:111]
	v_mfma_f32_16x16x32_bf16 v[104:107], v[140:143], v[196:199], v[104:107]
	v_mfma_f32_16x16x32_bf16 v[92:95], v[132:135], v[204:207], v[92:95]
	v_mfma_f32_16x16x32_bf16 v[88:91], v[140:143], v[204:207], v[88:91]
	v_mfma_f32_16x16x32_bf16 v[76:79], v[132:135], v[212:215], v[76:79]
	v_mfma_f32_16x16x32_bf16 v[72:75], v[140:143], v[212:215], v[72:75]
	s_setprio 0
	s_setprio 1
	v_mfma_f32_16x16x32_bf16 v[116:119], v[144:147], v[176:179], v[116:119]
	v_mfma_f32_16x16x32_bf16 v[112:115], v[168:171], v[176:179], v[112:115]
	v_mfma_f32_16x16x32_bf16 v[100:103], v[144:147], v[192:195], v[100:103]
	v_mfma_f32_16x16x32_bf16 v[96:99], v[168:171], v[192:195], v[96:99]
	v_mfma_f32_16x16x32_bf16 v[84:87], v[144:147], v[200:203], v[84:87]
	v_mfma_f32_16x16x32_bf16 v[80:83], v[168:171], v[200:203], v[80:83]
	v_mfma_f32_16x16x32_bf16 v[68:71], v[144:147], v[208:211], v[68:71]
	v_mfma_f32_16x16x32_bf16 v[64:67], v[168:171], v[208:211], v[64:67]
	v_mfma_f32_16x16x32_bf16 v[116:119], v[148:151], v[180:183], v[116:119]
	v_mfma_f32_16x16x32_bf16 v[112:115], v[172:175], v[180:183], v[112:115]
	v_mfma_f32_16x16x32_bf16 v[100:103], v[148:151], v[196:199], v[100:103]
	v_mfma_f32_16x16x32_bf16 v[96:99], v[172:175], v[196:199], v[96:99]
	s_barrier
	v_mfma_f32_16x16x32_bf16 v[84:87], v[148:151], v[204:207], v[84:87]
	v_mfma_f32_16x16x32_bf16 v[80:83], v[172:175], v[204:207], v[80:83]
	v_mfma_f32_16x16x32_bf16 v[68:71], v[148:151], v[212:215], v[68:71]
	v_mfma_f32_16x16x32_bf16 v[64:67], v[172:175], v[212:215], v[64:67]
	s_setprio 0
	s_add_i32 s63, s60, s68
	v_lshl_add_u64 v[184:185], s[46:47], 0, v[154:155]
	s_mov_b32 m0, s63
	ds_read_b128 v[176:179], v191 offset:16384
	ds_read_b128 v[180:183], v191 offset:17408
	ds_read_b128 v[192:195], v191 offset:18432
	ds_read_b128 v[196:199], v191 offset:19456
	ds_read_b128 v[200:203], v191 offset:20480
	ds_read_b128 v[204:207], v191 offset:21504
	ds_read_b128 v[208:211], v191 offset:22528
	ds_read_b128 v[212:215], v191 offset:23552
	global_load_lds_dwordx4 v[184:185], off
	s_add_i32 m0, s63, 0x2000
	s_add_u32 s64, s46, 0x40000
	v_lshl_add_u64 v[216:217], s[46:47], 0, v[158:159]
	s_addc_u32 s65, s47, 0
	s_add_i32 s63, s61, s68
	global_load_lds_dwordx4 v[216:217], off
	v_lshl_add_u64 v[218:219], s[64:65], 0, v[154:155]
	s_mov_b32 m0, s63
	v_lshl_add_u64 v[220:221], s[48:49], 0, v[156:157]
	global_load_lds_dwordx4 v[218:219], off
	v_lshl_add_u64 v[218:219], s[64:65], 0, v[158:159]
	s_add_i32 m0, s63, 0x2000
	s_nop 0
	global_load_lds_dwordx4 v[218:219], off
	v_lshl_add_u64 v[218:219], s[48:49], 0, v[152:153]
	s_mov_b32 m0, s74
	s_nop 0
	global_load_lds_dwordx4 v[218:219], off
	s_mov_b32 m0, s51
	s_nop 0
	global_load_lds_dwordx4 v[220:221], off
	s_waitcnt vmcnt(8)
	s_waitcnt lgkmcnt(0)
	s_barrier
; #define PG8_STAGE(bufoff, gbase, voff) do { _Pragma("unroll") for (int _i = 0; _i < 2; ++_i) \
;         __builtin_amdgcn_global_load_lds((const unsigned*)((const char*)(gbase) + (voff)[_i]), (PG8_LAS unsigned*)(lds + (bufoff) + ldsw + _i * 8192), 16, 0, 0); } while (0)
; #define PG8_LDA(dst, b, h) do { _Pragma("unroll") for (int m = 0; m < 4; ++m) _Pragma("unroll") for (int k = 0; k < 2; ++k) dst[m][k] = *(const PG8_LAS bf16x8*)(lds + PG8_SA(b, h) + aoff + m * 2048 + k * 1024); } while (0)
; #define PG8_LDB(dst, b, h) do { _Pragma("unroll") for (int n = 0; n < 2; ++n) _Pragma("unroll") for (int k = 0; k < 2; ++k) dst[n][k] = *(const PG8_LAS bf16x8*)(lds + PG8_SB(b, h) + boff + n * 2048 + k * 1024); } while (0)
; #define PG8_MMA(ai, bj, At, Bt) do { __builtin_amdgcn_s_setprio(1); _Pragma("unroll") for (int m = 0; m < 4; ++m) _Pragma("unroll") for (int n = 0; n < 2; ++n) _Pragma("unroll") for (int k = 0; k < 2; ++k) \
;         acc[ai][bj][m][n] = mma16<F16>(Bt[n][k], At[m][k], acc[ai][bj][m][n]); __builtin_amdgcn_s_setprio(0); } while (0)
; #define PG8_WAIT_V(n) asm volatile("s_waitcnt vmcnt(" #n ")" ::: "memory")
; template <class Epi, class Sched, bool ALIGN_EPI = false, bool SP2 = false, bool F16 = false>
; __device__ __forceinline__ void gemm_phase(PG8_LAS unsigned char* lds, const Gemm g, const Sched& S, const Epi& E, const int wid_in) {
;     ...
;             PG8_LDB(B0, 0, 0); PG8_LDB(B1, 0, 1); PG8_SCHED; PG8_LDA(At, 0, 0); PG8_STAGE(PG8_SA(1, 1), a1 + hstep, voffA);
;             PG8_WAIT_V(8); PG8_WAIT_L(0); PG8_BAR; PG8_MMA(0, 0, At, B0); PG8_MMA(0, 1, At, B1); PG8_BAR; PG8_SCHED;
;             PG8_LDA(At, 0, 1); PG8_STAGE(PG8_SB(0, 0), b2, voffB); PG8_STAGE(PG8_SB(0, 1), b2 + hstep, voffB); PG8_STAGE(PG8_SA(0, 0), a2, voffA);
;             PG8_WAIT_V(8); PG8_WAIT_L(0); PG8_BAR; PG8_MMA(1, 0, At, B0); PG8_MMA(1, 1, At, B1); PG8_BAR; PG8_SCHED;
;             PG8_LDB(B0, 1, 0); PG8_LDB(B1, 1, 1); PG8_SCHED; PG8_LDA(At, 1, 0); PG8_STAGE(PG8_SA(0, 1), a2 + hstep, voffA);
;             PG8_WAIT_V(8); PG8_WAIT_L(0); PG8_BAR; PG8_MMA(0, 0, At, B0); PG8_MMA(0, 1, At, B1); PG8_BAR; PG8_SCHED;
;             PG8_LDA(At, 1, 1); PG8_STAGE(PG8_SB(1, 0), b3, voffB); PG8_STAGE(PG8_SB(1, 1), b3 + hstep, voffB); PG8_STAGE(PG8_SA(1, 0), a3, voffA);
;             PG8_WAIT_V(8); PG8_WAIT_L(0); PG8_BAR; PG8_MMA(1, 0, At, B0); PG8_MMA(1, 1, At, B1); PG8_BAR; PG8_SCHED;
	s_setprio 1
	s_waitcnt lgkmcnt(0)
	v_mfma_f32_16x16x32_bf16 v[60:63], v[128:131], v[176:179], v[60:63]
	v_mfma_f32_16x16x32_bf16 v[56:59], v[136:139], v[176:179], v[56:59]
	v_mfma_f32_16x16x32_bf16 v[44:47], v[128:131], v[192:195], v[44:47]
	v_mfma_f32_16x16x32_bf16 v[40:43], v[136:139], v[192:195], v[40:43]
	v_mfma_f32_16x16x32_bf16 v[28:31], v[128:131], v[200:203], v[28:31]
	v_mfma_f32_16x16x32_bf16 v[24:27], v[136:139], v[200:203], v[24:27]
	v_mfma_f32_16x16x32_bf16 v[12:15], v[128:131], v[208:211], v[12:15]
	v_mfma_f32_16x16x32_bf16 v[8:11], v[136:139], v[208:211], v[8:11]
	v_mfma_f32_16x16x32_bf16 v[60:63], v[132:135], v[180:183], v[60:63]
	v_mfma_f32_16x16x32_bf16 v[56:59], v[140:143], v[180:183], v[56:59]
	v_mfma_f32_16x16x32_bf16 v[44:47], v[132:135], v[196:199], v[44:47]
	v_mfma_f32_16x16x32_bf16 v[40:43], v[140:143], v[196:199], v[40:43]
	v_mfma_f32_16x16x32_bf16 v[28:31], v[132:135], v[204:207], v[28:31]
	v_mfma_f32_16x16x32_bf16 v[24:27], v[140:143], v[204:207], v[24:27]
	v_mfma_f32_16x16x32_bf16 v[12:15], v[132:135], v[212:215], v[12:15]
	v_mfma_f32_16x16x32_bf16 v[8:11], v[140:143], v[212:215], v[8:11]
	s_setprio 0
	s_setprio 1
	v_mfma_f32_16x16x32_bf16 v[52:55], v[144:147], v[176:179], v[52:55]
	v_mfma_f32_16x16x32_bf16 v[48:51], v[168:171], v[176:179], v[48:51]
	v_mfma_f32_16x16x32_bf16 v[36:39], v[144:147], v[192:195], v[36:39]
	v_mfma_f32_16x16x32_bf16 v[32:35], v[168:171], v[192:195], v[32:35]
	v_mfma_f32_16x16x32_bf16 v[20:23], v[144:147], v[200:203], v[20:23]
	v_mfma_f32_16x16x32_bf16 v[16:19], v[168:171], v[200:203], v[16:19]
	v_mfma_f32_16x16x32_bf16 v[4:7], v[144:147], v[208:211], v[4:7]
	v_mfma_f32_16x16x32_bf16 v[0:3], v[168:171], v[208:211], v[0:3]
	v_mfma_f32_16x16x32_bf16 v[52:55], v[148:151], v[180:183], v[52:55]
	v_mfma_f32_16x16x32_bf16 v[48:51], v[172:175], v[180:183], v[48:51]
	v_mfma_f32_16x16x32_bf16 v[36:39], v[148:151], v[196:199], v[36:39]
	v_mfma_f32_16x16x32_bf16 v[32:35], v[172:175], v[196:199], v[32:35]
	s_barrier
	v_mfma_f32_16x16x32_bf16 v[20:23], v[148:151], v[204:207], v[20:23]
	v_mfma_f32_16x16x32_bf16 v[16:19], v[172:175], v[204:207], v[16:19]
	v_mfma_f32_16x16x32_bf16 v[4:7], v[148:151], v[212:215], v[4:7]
	v_mfma_f32_16x16x32_bf16 v[0:3], v[172:175], v[212:215], v[0:3]
	s_setprio 0
	s_add_i32 s63, 0, 0x18000
	s_add_i32 s64, 0, 0x1c000
	v_add_u32_e32 v140, s63, v188
	v_add_u32_e32 v172, s64, v188
	ds_read_b128 v[128:131], v140
	ds_read_b128 v[132:135], v140 offset:1024
	ds_read_b128 v[136:139], v140 offset:2048
	ds_read_b128 v[140:143], v140 offset:3072
	ds_read_b128 v[144:147], v172
	ds_read_b128 v[148:151], v172 offset:1024
	ds_read_b128 v[168:171], v172 offset:2048
	ds_read_b128 v[172:175], v172 offset:3072
	s_add_u32 s48, s48, 0x40000
	s_addc_u32 s49, s49, 0
	s_mov_b32 m0, s52
	v_lshl_add_u64 v[222:223], s[48:49], 0, v[152:153]
	ds_read_b128 v[176:179], v191 offset:32768
	ds_read_b128 v[180:183], v191 offset:33792
	ds_read_b128 v[192:195], v191 offset:34816
	ds_read_b128 v[196:199], v191 offset:35840
	ds_read_b128 v[200:203], v191 offset:36864
	ds_read_b128 v[204:207], v191 offset:37888
	ds_read_b128 v[208:211], v191 offset:38912
	ds_read_b128 v[212:215], v191 offset:39936
	global_load_lds_dwordx4 v[222:223], off
	v_lshl_add_u64 v[222:223], s[48:49], 0, v[156:157]
	s_mov_b32 m0, s53
	s_nop 0
	global_load_lds_dwordx4 v[222:223], off
	s_waitcnt vmcnt(8)
	s_waitcnt lgkmcnt(0)
	s_barrier
	s_setprio 1
	s_waitcnt lgkmcnt(0)
	v_mfma_f32_16x16x32_bf16 v[124:127], v[128:131], v[176:179], v[124:127]
	v_mfma_f32_16x16x32_bf16 v[120:123], v[136:139], v[176:179], v[120:123]
	v_mfma_f32_16x16x32_bf16 v[108:111], v[128:131], v[192:195], v[108:111]
	v_mfma_f32_16x16x32_bf16 v[104:107], v[136:139], v[192:195], v[104:107]
	v_mfma_f32_16x16x32_bf16 v[92:95], v[128:131], v[200:203], v[92:95]
	v_mfma_f32_16x16x32_bf16 v[88:91], v[136:139], v[200:203], v[88:91]
	v_mfma_f32_16x16x32_bf16 v[76:79], v[128:131], v[208:211], v[76:79]
	v_mfma_f32_16x16x32_bf16 v[72:75], v[136:139], v[208:211], v[72:75]
	v_mfma_f32_16x16x32_bf16 v[124:127], v[132:135], v[180:183], v[124:127]
	v_mfma_f32_16x16x32_bf16 v[120:123], v[140:143], v[180:183], v[120:123]
	v_mfma_f32_16x16x32_bf16 v[108:111], v[132:135], v[196:199], v[108:111]
	v_mfma_f32_16x16x32_bf16 v[104:107], v[140:143], v[196:199], v[104:107]
	v_mfma_f32_16x16x32_bf16 v[92:95], v[132:135], v[204:207], v[92:95]
	v_mfma_f32_16x16x32_bf16 v[88:91], v[140:143], v[204:207], v[88:91]
	v_mfma_f32_16x16x32_bf16 v[76:79], v[132:135], v[212:215], v[76:79]
	v_mfma_f32_16x16x32_bf16 v[72:75], v[140:143], v[212:215], v[72:75]
	s_setprio 0
	s_setprio 1
	v_mfma_f32_16x16x32_bf16 v[116:119], v[144:147], v[176:179], v[116:119]
	v_mfma_f32_16x16x32_bf16 v[112:115], v[168:171], v[176:179], v[112:115]
	v_mfma_f32_16x16x32_bf16 v[100:103], v[144:147], v[192:195], v[100:103]
	v_mfma_f32_16x16x32_bf16 v[96:99], v[168:171], v[192:195], v[96:99]
	v_mfma_f32_16x16x32_bf16 v[84:87], v[144:147], v[200:203], v[84:87]
	v_mfma_f32_16x16x32_bf16 v[80:83], v[168:171], v[200:203], v[80:83]
	v_mfma_f32_16x16x32_bf16 v[68:71], v[144:147], v[208:211], v[68:71]
	v_mfma_f32_16x16x32_bf16 v[64:67], v[168:171], v[208:211], v[64:67]
	v_mfma_f32_16x16x32_bf16 v[116:119], v[148:151], v[180:183], v[116:119]
	v_mfma_f32_16x16x32_bf16 v[112:115], v[172:175], v[180:183], v[112:115]
	v_mfma_f32_16x16x32_bf16 v[100:103], v[148:151], v[196:199], v[100:103]
	v_mfma_f32_16x16x32_bf16 v[96:99], v[172:175], v[196:199], v[96:99]
	s_barrier
; #define PG8_STAGE(bufoff, gbase, voff) do { _Pragma("unroll") for (int _i = 0; _i < 2; ++_i) \
;         __builtin_amdgcn_global_load_lds((const unsigned*)((const char*)(gbase) + (voff)[_i]), (PG8_LAS unsigned*)(lds + (bufoff) + ldsw + _i * 8192), 16, 0, 0); } while (0)
; #define PG8_LDA(dst, b, h) do { _Pragma("unroll") for (int m = 0; m < 4; ++m) _Pragma("unroll") for (int k = 0; k < 2; ++k) dst[m][k] = *(const PG8_LAS bf16x8*)(lds + PG8_SA(b, h) + aoff + m * 2048 + k * 1024); } while (0)
; #define PG8_LDB(dst, b, h) do { _Pragma("unroll") for (int n = 0; n < 2; ++n) _Pragma("unroll") for (int k = 0; k < 2; ++k) dst[n][k] = *(const PG8_LAS bf16x8*)(lds + PG8_SB(b, h) + boff + n * 2048 + k * 1024); } while (0)
; #define PG8_MMA(ai, bj, At, Bt) do { __builtin_amdgcn_s_setprio(1); _Pragma("unroll") for (int m = 0; m < 4; ++m) _Pragma("unroll") for (int n = 0; n < 2; ++n) _Pragma("unroll") for (int k = 0; k < 2; ++k) \
;         acc[ai][bj][m][n] = mma16<F16>(Bt[n][k], At[m][k], acc[ai][bj][m][n]); __builtin_amdgcn_s_setprio(0); } while (0)
; #define PG8_WAIT_V(n) asm volatile("s_waitcnt vmcnt(" #n ")" ::: "memory")
; template <class Epi, class Sched, bool ALIGN_EPI = false, bool SP2 = false, bool F16 = false>
; __device__ __forceinline__ void gemm_phase(PG8_LAS unsigned char* lds, const Gemm g, const Sched& S, const Epi& E, const int wid_in) {
;     ...
;             PG8_LDB(B0, 0, 0); PG8_LDB(B1, 0, 1); PG8_SCHED; PG8_LDA(At, 0, 0); PG8_STAGE(PG8_SA(1, 1), a1 + hstep, voffA);
;             PG8_WAIT_V(8); PG8_WAIT_L(0); PG8_BAR; PG8_MMA(0, 0, At, B0); PG8_MMA(0, 1, At, B1); PG8_BAR; PG8_SCHED;
;             PG8_LDA(At, 0, 1); PG8_STAGE(PG8_SB(0, 0), b2, voffB); PG8_STAGE(PG8_SB(0, 1), b2 + hstep, voffB); PG8_STAGE(PG8_SA(0, 0), a2, voffA);
;             PG8_WAIT_V(8); PG8_WAIT_L(0); PG8_BAR; PG8_MMA(1, 0, At, B0); PG8_MMA(1, 1, At, B1); PG8_BAR; PG8_SCHED;
;             PG8_LDB(B0, 1, 0); PG8_LDB(B1, 1, 1); PG8_SCHED; PG8_LDA(At, 1, 0); PG8_STAGE(PG8_SA(0, 1), a2 + hstep, voffA);
;             PG8_WAIT_V(8); PG8_WAIT_L(0); PG8_BAR; PG8_MMA(0, 0, At, B0); PG8_MMA(0, 1, At, B1); PG8_BAR; PG8_SCHED;
;             PG8_LDA(At, 1, 1); PG8_STAGE(PG8_SB(1, 0), b3, voffB); PG8_STAGE(PG8_SB(1, 1), b3 + hstep, voffB); PG8_STAGE(PG8_SA(1, 0), a3, voffA);
;             PG8_WAIT_V(8); PG8_WAIT_L(0); PG8_BAR; PG8_MMA(1, 0, At, B0); PG8_MMA(1, 1, At, B1); PG8_BAR; PG8_SCHED;
	v_mfma_f32_16x16x32_bf16 v[84:87], v[148:151], v[204:207], v[84:87]
	v_mfma_f32_16x16x32_bf16 v[80:83], v[172:175], v[204:207], v[80:83]
	v_mfma_f32_16x16x32_bf16 v[68:71], v[148:151], v[212:215], v[68:71]
	v_mfma_f32_16x16x32_bf16 v[64:67], v[172:175], v[212:215], v[64:67]
	s_setprio 0
	s_add_i32 s48, s63, s68
	v_lshl_add_u64 v[184:185], v[184:185], 0, s[22:23]
	s_mov_b32 m0, s48
	ds_read_b128 v[176:179], v191 offset:49152
	ds_read_b128 v[180:183], v191 offset:50176
	ds_read_b128 v[192:195], v191 offset:51200
	ds_read_b128 v[196:199], v191 offset:52224
	ds_read_b128 v[200:203], v191 offset:53248
	ds_read_b128 v[204:207], v191 offset:54272
	ds_read_b128 v[208:211], v191 offset:55296
	ds_read_b128 v[212:215], v191 offset:56320
	global_load_lds_dwordx4 v[184:185], off
	s_add_i32 m0, s48, 0x2000
	s_add_u32 s46, s46, 0x40080
	v_lshl_add_u64 v[184:185], v[216:217], 0, s[22:23]
	s_addc_u32 s47, s47, 0
	s_add_i32 s48, s64, s68
	global_load_lds_dwordx4 v[184:185], off
	v_lshl_add_u64 v[184:185], s[46:47], 0, v[154:155]
	s_mov_b32 m0, s48
	s_nop 0
	global_load_lds_dwordx4 v[184:185], off
	v_lshl_add_u64 v[184:185], s[46:47], 0, v[158:159]
	s_add_i32 m0, s48, 0x2000
	s_nop 0
	global_load_lds_dwordx4 v[184:185], off
	v_lshl_add_u64 v[184:185], v[218:219], 0, s[22:23]
	s_mov_b32 m0, s75
	s_nop 0
	global_load_lds_dwordx4 v[184:185], off
	v_lshl_add_u64 v[184:185], v[220:221], 0, s[22:23]
	s_mov_b32 m0, s54
	s_nop 0
	global_load_lds_dwordx4 v[184:185], off
	s_waitcnt vmcnt(8)
	s_waitcnt lgkmcnt(0)
	s_barrier
	s_setprio 1
	s_waitcnt lgkmcnt(0)
	v_mfma_f32_16x16x32_bf16 v[60:63], v[128:131], v[176:179], v[60:63]
	v_mfma_f32_16x16x32_bf16 v[56:59], v[136:139], v[176:179], v[56:59]
	v_mfma_f32_16x16x32_bf16 v[44:47], v[128:131], v[192:195], v[44:47]
	v_mfma_f32_16x16x32_bf16 v[40:43], v[136:139], v[192:195], v[40:43]
	v_mfma_f32_16x16x32_bf16 v[28:31], v[128:131], v[200:203], v[28:31]
	v_mfma_f32_16x16x32_bf16 v[24:27], v[136:139], v[200:203], v[24:27]
	v_mfma_f32_16x16x32_bf16 v[12:15], v[128:131], v[208:211], v[12:15]
	v_mfma_f32_16x16x32_bf16 v[8:11], v[136:139], v[208:211], v[8:11]
	v_mfma_f32_16x16x32_bf16 v[60:63], v[132:135], v[180:183], v[60:63]
	v_mfma_f32_16x16x32_bf16 v[56:59], v[140:143], v[180:183], v[56:59]
	v_mfma_f32_16x16x32_bf16 v[44:47], v[132:135], v[196:199], v[44:47]
	v_mfma_f32_16x16x32_bf16 v[40:43], v[140:143], v[196:199], v[40:43]
	v_mfma_f32_16x16x32_bf16 v[28:31], v[132:135], v[204:207], v[28:31]
	v_mfma_f32_16x16x32_bf16 v[24:27], v[140:143], v[204:207], v[24:27]
	v_mfma_f32_16x16x32_bf16 v[12:15], v[132:135], v[212:215], v[12:15]
	v_mfma_f32_16x16x32_bf16 v[8:11], v[140:143], v[212:215], v[8:11]
	s_setprio 0
	s_setprio 1
	v_mfma_f32_16x16x32_bf16 v[52:55], v[144:147], v[176:179], v[52:55]
	v_mfma_f32_16x16x32_bf16 v[48:51], v[168:171], v[176:179], v[48:51]
	v_mfma_f32_16x16x32_bf16 v[36:39], v[144:147], v[192:195], v[36:39]
	v_mfma_f32_16x16x32_bf16 v[32:35], v[168:171], v[192:195], v[32:35]
	v_mfma_f32_16x16x32_bf16 v[20:23], v[144:147], v[200:203], v[20:23]
	v_mfma_f32_16x16x32_bf16 v[16:19], v[168:171], v[200:203], v[16:19]
	v_mfma_f32_16x16x32_bf16 v[4:7], v[144:147], v[208:211], v[4:7]
	v_mfma_f32_16x16x32_bf16 v[0:3], v[168:171], v[208:211], v[0:3]
	v_mfma_f32_16x16x32_bf16 v[52:55], v[148:151], v[180:183], v[52:55]
	v_mfma_f32_16x16x32_bf16 v[48:51], v[172:175], v[180:183], v[48:51]
	v_mfma_f32_16x16x32_bf16 v[36:39], v[148:151], v[196:199], v[36:39]
	v_mfma_f32_16x16x32_bf16 v[32:35], v[172:175], v[196:199], v[32:35]
	s_barrier
	v_mfma_f32_16x16x32_bf16 v[20:23], v[148:151], v[204:207], v[20:23]
	v_mfma_f32_16x16x32_bf16 v[16:19], v[172:175], v[204:207], v[16:19]
	v_mfma_f32_16x16x32_bf16 v[4:7], v[148:151], v[212:215], v[4:7]
	v_mfma_f32_16x16x32_bf16 v[0:3], v[172:175], v[212:215], v[0:3]
	s_setprio 0
	s_add_i32 s43, s43, 2
	s_add_u32 s44, s44, 0x100
	s_addc_u32 s45, s45, 0
	s_add_u32 s37, s37, 0x100
	s_addc_u32 s42, s42, 0
	s_cmp_gt_u32 s43, 13
	s_cbranch_scc0 .LBB0_508
	s_and_b64 vcc, exec, s[16:17]
	s_cbranch_vccz .LBB0_511
	s_barrier

; #define PG8_STAGE(bufoff, gbase, voff) do { _Pragma("unroll") for (int _i = 0; _i < 2; ++_i) \
;         __builtin_amdgcn_global_load_lds((const unsigned*)((const char*)(gbase) + (voff)[_i]), (PG8_LAS unsigned*)(lds + (bufoff) + ldsw + _i * 8192), 16, 0, 0); } while (0)
; #define PG8_LDA(dst, b, h) do { _Pragma("unroll") for (int m = 0; m < 4; ++m) _Pragma("unroll") for (int k = 0; k < 2; ++k) dst[m][k] = *(const PG8_LAS bf16x8*)(lds + PG8_SA(b, h) + aoff + m * 2048 + k * 1024); } while (0)
; #define PG8_LDB(dst, b, h) do { _Pragma("unroll") for (int n = 0; n < 2; ++n) _Pragma("unroll") for (int k = 0; k < 2; ++k) dst[n][k] = *(const PG8_LAS bf16x8*)(lds + PG8_SB(b, h) + boff + n * 2048 + k * 1024); } while (0)
; #define PG8_MMA(ai, bj, At, Bt) do { __builtin_amdgcn_s_setprio(1); _Pragma("unroll") for (int m = 0; m < 4; ++m) _Pragma("unroll") for (int n = 0; n < 2; ++n) _Pragma("unroll") for (int k = 0; k < 2; ++k) \
;         acc[ai][bj][m][n] = mma16<F16>(Bt[n][k], At[m][k], acc[ai][bj][m][n]); __builtin_amdgcn_s_setprio(0); } while (0)
; #define PG8_WAIT_V(n) asm volatile("s_waitcnt vmcnt(" #n ")" ::: "memory")
; template <class Epi, class Sched, bool ALIGN_EPI = false, bool SP2 = false, bool F16 = false>
; __device__ __forceinline__ void gemm_phase(PG8_LAS unsigned char* lds, const Gemm g, const Sched& S, const Epi& E, const int wid_in) {
;     ...
;             PG8_LDB(B0, 0, 0); PG8_LDB(B1, 0, 1); PG8_SCHED; PG8_LDA(At, 0, 0); PG8_STAGE(PG8_SA(1, 1), a1 + hstep, voffA);
;             PG8_WAIT_V(8); PG8_WAIT_L(0); PG8_BAR; PG8_MMA(0, 0, At, B0); PG8_MMA(0, 1, At, B1); PG8_BAR; PG8_SCHED;
;             PG8_LDA(At, 0, 1); PG8_STAGE(PG8_SB(0, 0), b2, voffB); PG8_STAGE(PG8_SB(0, 1), b2 + hstep, voffB); PG8_STAGE(PG8_SA(0, 0), a2, voffA);
;             PG8_WAIT_V(8); PG8_WAIT_L(0); PG8_BAR; PG8_MMA(1, 0, At, B0); PG8_MMA(1, 1, At, B1); PG8_BAR; PG8_SCHED;
;             PG8_LDB(B0, 1, 0); PG8_LDB(B1, 1, 1); PG8_SCHED; PG8_LDA(At, 1, 0); PG8_STAGE(PG8_SA(0, 1), a2 + hstep, voffA);
;             PG8_WAIT_V(8); PG8_WAIT_L(0); PG8_BAR; PG8_MMA(0, 0, At, B0); PG8_MMA(0, 1, At, B1); PG8_BAR; PG8_SCHED;
;             PG8_LDA(At, 1, 1); PG8_STAGE(PG8_SB(1, 0), b3, voffB); PG8_STAGE(PG8_SB(1, 1), b3 + hstep, voffB); PG8_STAGE(PG8_SA(1, 0), a3, voffA);
;             PG8_WAIT_V(8); PG8_WAIT_L(0); PG8_BAR; PG8_MMA(1, 0, At, B0); PG8_MMA(1, 1, At, B1); PG8_BAR; PG8_SCHED;
.LBB0_585:
	ds_read_b128 v[0:3], v193
	ds_read_b128 v[4:7], v193 offset:1024
	ds_read_b128 v[136:139], v193 offset:2048
	ds_read_b128 v[140:143], v193 offset:3072
	ds_read_b128 v[144:147], v194
	ds_read_b128 v[148:151], v194 offset:1024
	ds_read_b128 v[152:155], v194 offset:2048
	ds_read_b128 v[156:159], v194 offset:3072
	s_add_u32 s36, s34, 0xfffc0080
	s_addc_u32 s37, s35, -1
	s_cmp_eq_u32 s65, 12
	s_cselect_b32 s45, s23, s37
	s_cselect_b32 s44, s31, s36
	s_cselect_b32 s37, s21, s64
	s_cselect_b32 s36, s42, s43
	v_lshl_add_u64 v[188:189], s[34:35], 0, v[168:169]
	s_add_i32 m0, s74, 0xc000
	ds_read_b128 v[176:179], v195
	ds_read_b128 v[180:183], v195 offset:1024
	ds_read_b128 v[184:187], v195 offset:2048
	ds_read_b128 v[198:201], v195 offset:3072
	ds_read_b128 v[202:205], v195 offset:4096
	ds_read_b128 v[206:209], v195 offset:5120
	ds_read_b128 v[210:213], v195 offset:6144
	ds_read_b128 v[214:217], v195 offset:7168
	global_load_lds_dwordx4 v[188:189], off
	v_lshl_add_u64 v[188:189], s[34:35], 0, v[170:171]
	s_add_i32 m0, s74, 0xe000
	s_nop 0
	global_load_lds_dwordx4 v[188:189], off
	s_waitcnt vmcnt(8)
	s_waitcnt lgkmcnt(0)
	s_barrier
	s_setprio 1
	s_waitcnt lgkmcnt(0)
	v_mfma_f32_16x16x32_f16 v[132:135], v[0:3], v[176:179], v[132:135]
	v_mfma_f32_16x16x32_f16 v[128:131], v[136:139], v[176:179], v[128:131]
	v_mfma_f32_16x16x32_f16 v[116:119], v[0:3], v[184:187], v[116:119]
	v_mfma_f32_16x16x32_f16 v[112:115], v[136:139], v[184:187], v[112:115]
	v_mfma_f32_16x16x32_f16 v[100:103], v[0:3], v[202:205], v[100:103]
	v_mfma_f32_16x16x32_f16 v[96:99], v[136:139], v[202:205], v[96:99]
	v_mfma_f32_16x16x32_f16 v[84:87], v[0:3], v[210:213], v[84:87]
	v_mfma_f32_16x16x32_f16 v[80:83], v[136:139], v[210:213], v[80:83]
	v_mfma_f32_16x16x32_f16 v[132:135], v[4:7], v[180:183], v[132:135]
	v_mfma_f32_16x16x32_f16 v[128:131], v[140:143], v[180:183], v[128:131]
	v_mfma_f32_16x16x32_f16 v[116:119], v[4:7], v[198:201], v[116:119]
	v_mfma_f32_16x16x32_f16 v[112:115], v[140:143], v[198:201], v[112:115]
	v_mfma_f32_16x16x32_f16 v[100:103], v[4:7], v[206:209], v[100:103]
	v_mfma_f32_16x16x32_f16 v[96:99], v[140:143], v[206:209], v[96:99]
	v_mfma_f32_16x16x32_f16 v[84:87], v[4:7], v[214:217], v[84:87]
	v_mfma_f32_16x16x32_f16 v[80:83], v[140:143], v[214:217], v[80:83]
	s_setprio 0
	s_setprio 1
	v_mfma_f32_16x16x32_f16 v[124:127], v[144:147], v[176:179], v[124:127]
	v_mfma_f32_16x16x32_f16 v[120:123], v[152:155], v[176:179], v[120:123]
	v_mfma_f32_16x16x32_f16 v[108:111], v[144:147], v[184:187], v[108:111]
	v_mfma_f32_16x16x32_f16 v[104:107], v[152:155], v[184:187], v[104:107]
	v_mfma_f32_16x16x32_f16 v[92:95], v[144:147], v[202:205], v[92:95]
	v_mfma_f32_16x16x32_f16 v[88:91], v[152:155], v[202:205], v[88:91]
	v_mfma_f32_16x16x32_f16 v[76:79], v[144:147], v[210:213], v[76:79]
	v_mfma_f32_16x16x32_f16 v[72:75], v[152:155], v[210:213], v[72:75]
	v_mfma_f32_16x16x32_f16 v[124:127], v[148:151], v[180:183], v[124:127]
	v_mfma_f32_16x16x32_f16 v[120:123], v[156:159], v[180:183], v[120:123]
	v_mfma_f32_16x16x32_f16 v[108:111], v[148:151], v[198:201], v[108:111]
	v_mfma_f32_16x16x32_f16 v[104:107], v[156:159], v[198:201], v[104:107]
	s_barrier
	v_mfma_f32_16x16x32_f16 v[92:95], v[148:151], v[206:209], v[92:95]
	v_mfma_f32_16x16x32_f16 v[88:91], v[156:159], v[206:209], v[88:91]
	v_mfma_f32_16x16x32_f16 v[76:79], v[148:151], v[214:217], v[76:79]
	v_mfma_f32_16x16x32_f16 v[72:75], v[156:159], v[214:217], v[72:75]
	s_setprio 0
	s_add_i32 s66, s61, s68
	v_lshl_add_u64 v[188:189], s[36:37], 0, v[162:163]
	s_mov_b32 m0, s66
	ds_read_b128 v[176:179], v195 offset:16384
	ds_read_b128 v[180:183], v195 offset:17408
	ds_read_b128 v[184:187], v195 offset:18432
	ds_read_b128 v[198:201], v195 offset:19456
	ds_read_b128 v[202:205], v195 offset:20480
	ds_read_b128 v[206:209], v195 offset:21504
	ds_read_b128 v[210:213], v195 offset:22528
	ds_read_b128 v[214:217], v195 offset:23552
	global_load_lds_dwordx4 v[188:189], off
	s_add_i32 m0, s66, 0x2000
	s_add_u32 s66, s36, 0x40000
	v_lshl_add_u64 v[218:219], s[36:37], 0, v[166:167]
	s_addc_u32 s67, s37, 0
	s_add_i32 s76, s62, s68
	global_load_lds_dwordx4 v[218:219], off
	v_lshl_add_u64 v[220:221], s[66:67], 0, v[162:163]
	s_mov_b32 m0, s76
	v_lshl_add_u64 v[222:223], s[44:45], 0, v[164:165]
	global_load_lds_dwordx4 v[220:221], off
	v_lshl_add_u64 v[220:221], s[66:67], 0, v[166:167]
	s_add_i32 m0, s76, 0x2000
	s_nop 0
	global_load_lds_dwordx4 v[220:221], off
	v_lshl_add_u64 v[220:221], s[44:45], 0, v[160:161]
	s_mov_b32 m0, s74
	s_nop 0
	global_load_lds_dwordx4 v[220:221], off
	s_mov_b32 m0, s29
	s_nop 0
	global_load_lds_dwordx4 v[222:223], off
	s_waitcnt vmcnt(8)
	s_waitcnt lgkmcnt(0)
	s_barrier
; #define PG8_STAGE(bufoff, gbase, voff) do { _Pragma("unroll") for (int _i = 0; _i < 2; ++_i) \
;         __builtin_amdgcn_global_load_lds((const unsigned*)((const char*)(gbase) + (voff)[_i]), (PG8_LAS unsigned*)(lds + (bufoff) + ldsw + _i * 8192), 16, 0, 0); } while (0)
; #define PG8_LDA(dst, b, h) do { _Pragma("unroll") for (int m = 0; m < 4; ++m) _Pragma("unroll") for (int k = 0; k < 2; ++k) dst[m][k] = *(const PG8_LAS bf16x8*)(lds + PG8_SA(b, h) + aoff + m * 2048 + k * 1024); } while (0)
; #define PG8_LDB(dst, b, h) do { _Pragma("unroll") for (int n = 0; n < 2; ++n) _Pragma("unroll") for (int k = 0; k < 2; ++k) dst[n][k] = *(const PG8_LAS bf16x8*)(lds + PG8_SB(b, h) + boff + n * 2048 + k * 1024); } while (0)
; #define PG8_MMA(ai, bj, At, Bt) do { __builtin_amdgcn_s_setprio(1); _Pragma("unroll") for (int m = 0; m < 4; ++m) _Pragma("unroll") for (int n = 0; n < 2; ++n) _Pragma("unroll") for (int k = 0; k < 2; ++k) \
;         acc[ai][bj][m][n] = mma16<F16>(Bt[n][k], At[m][k], acc[ai][bj][m][n]); __builtin_amdgcn_s_setprio(0); } while (0)
; #define PG8_WAIT_V(n) asm volatile("s_waitcnt vmcnt(" #n ")" ::: "memory")
; template <class Epi, class Sched, bool ALIGN_EPI = false, bool SP2 = false, bool F16 = false>
; __device__ __forceinline__ void gemm_phase(PG8_LAS unsigned char* lds, const Gemm g, const Sched& S, const Epi& E, const int wid_in) {
;     ...
;             PG8_LDB(B0, 0, 0); PG8_LDB(B1, 0, 1); PG8_SCHED; PG8_LDA(At, 0, 0); PG8_STAGE(PG8_SA(1, 1), a1 + hstep, voffA);
;             PG8_WAIT_V(8); PG8_WAIT_L(0); PG8_BAR; PG8_MMA(0, 0, At, B0); PG8_MMA(0, 1, At, B1); PG8_BAR; PG8_SCHED;
;             PG8_LDA(At, 0, 1); PG8_STAGE(PG8_SB(0, 0), b2, voffB); PG8_STAGE(PG8_SB(0, 1), b2 + hstep, voffB); PG8_STAGE(PG8_SA(0, 0), a2, voffA);
;             PG8_WAIT_V(8); PG8_WAIT_L(0); PG8_BAR; PG8_MMA(1, 0, At, B0); PG8_MMA(1, 1, At, B1); PG8_BAR; PG8_SCHED;
;             PG8_LDB(B0, 1, 0); PG8_LDB(B1, 1, 1); PG8_SCHED; PG8_LDA(At, 1, 0); PG8_STAGE(PG8_SA(0, 1), a2 + hstep, voffA);
;             PG8_WAIT_V(8); PG8_WAIT_L(0); PG8_BAR; PG8_MMA(0, 0, At, B0); PG8_MMA(0, 1, At, B1); PG8_BAR; PG8_SCHED;
;             PG8_LDA(At, 1, 1); PG8_STAGE(PG8_SB(1, 0), b3, voffB); PG8_STAGE(PG8_SB(1, 1), b3 + hstep, voffB); PG8_STAGE(PG8_SA(1, 0), a3, voffA);
;             PG8_WAIT_V(8); PG8_WAIT_L(0); PG8_BAR; PG8_MMA(1, 0, At, B0); PG8_MMA(1, 1, At, B1); PG8_BAR; PG8_SCHED;
	s_setprio 1
	s_waitcnt lgkmcnt(0)
	v_mfma_f32_16x16x32_f16 v[68:71], v[0:3], v[176:179], v[68:71]
	v_mfma_f32_16x16x32_f16 v[64:67], v[136:139], v[176:179], v[64:67]
	v_mfma_f32_16x16x32_f16 v[52:55], v[0:3], v[184:187], v[52:55]
	v_mfma_f32_16x16x32_f16 v[48:51], v[136:139], v[184:187], v[48:51]
	v_mfma_f32_16x16x32_f16 v[36:39], v[0:3], v[202:205], v[36:39]
	v_mfma_f32_16x16x32_f16 v[32:35], v[136:139], v[202:205], v[32:35]
	v_mfma_f32_16x16x32_f16 v[0:3], v[0:3], v[210:213], v[20:23]
	v_mfma_f32_16x16x32_f16 v[68:71], v[4:7], v[180:183], v[68:71]
	v_mfma_f32_16x16x32_f16 v[64:67], v[140:143], v[180:183], v[64:67]
	v_mfma_f32_16x16x32_f16 v[52:55], v[4:7], v[198:201], v[52:55]
	v_mfma_f32_16x16x32_f16 v[48:51], v[140:143], v[198:201], v[48:51]
	v_mfma_f32_16x16x32_f16 v[36:39], v[4:7], v[206:209], v[36:39]
	v_mfma_f32_16x16x32_f16 v[32:35], v[140:143], v[206:209], v[32:35]
	v_mfma_f32_16x16x32_f16 v[0:3], v[4:7], v[214:217], v[0:3]
	v_mfma_f32_16x16x32_f16 v[4:7], v[136:139], v[210:213], v[16:19]
	v_mfma_f32_16x16x32_f16 v[4:7], v[140:143], v[214:217], v[4:7]
	s_setprio 0
	s_setprio 1
	v_mfma_f32_16x16x32_f16 v[16:19], v[144:147], v[176:179], v[60:63]
	v_mfma_f32_16x16x32_f16 v[60:63], v[148:151], v[180:183], v[16:19]
	v_mfma_f32_16x16x32_f16 v[16:19], v[152:155], v[176:179], v[56:59]
	v_mfma_f32_16x16x32_f16 v[56:59], v[156:159], v[180:183], v[16:19]
	v_mfma_f32_16x16x32_f16 v[16:19], v[144:147], v[184:187], v[44:47]
	v_mfma_f32_16x16x32_f16 v[44:47], v[148:151], v[198:201], v[16:19]
	v_mfma_f32_16x16x32_f16 v[16:19], v[152:155], v[184:187], v[40:43]
	v_mfma_f32_16x16x32_f16 v[40:43], v[156:159], v[198:201], v[16:19]
	v_mfma_f32_16x16x32_f16 v[16:19], v[144:147], v[202:205], v[28:31]
	v_mfma_f32_16x16x32_f16 v[28:31], v[148:151], v[206:209], v[16:19]
	v_mfma_f32_16x16x32_f16 v[16:19], v[152:155], v[202:205], v[24:27]
	v_mfma_f32_16x16x32_f16 v[12:15], v[144:147], v[210:213], v[12:15]
	s_barrier
	v_mfma_f32_16x16x32_f16 v[8:11], v[152:155], v[210:213], v[8:11]
	v_mfma_f32_16x16x32_f16 v[24:27], v[156:159], v[206:209], v[16:19]
	v_mfma_f32_16x16x32_f16 v[12:15], v[148:151], v[214:217], v[12:15]
	v_mfma_f32_16x16x32_f16 v[8:11], v[156:159], v[214:217], v[8:11]
	s_setprio 0
	s_add_i32 s66, 0, 0x18000
	s_add_i32 s67, 0, 0x1c000
	v_add_u32_e32 v140, s66, v192
	v_add_u32_e32 v156, s67, v192
	ds_read_b128 v[16:19], v140
	ds_read_b128 v[20:23], v140 offset:1024
	ds_read_b128 v[136:139], v140 offset:2048
	ds_read_b128 v[140:143], v140 offset:3072
	ds_read_b128 v[144:147], v156
	ds_read_b128 v[148:151], v156 offset:1024
	ds_read_b128 v[152:155], v156 offset:2048
	ds_read_b128 v[156:159], v156 offset:3072
	s_add_u32 s44, s44, 0x40000
	s_addc_u32 s45, s45, 0
	s_mov_b32 m0, s49
	v_lshl_add_u64 v[224:225], s[44:45], 0, v[160:161]
	ds_read_b128 v[176:179], v195 offset:32768
	ds_read_b128 v[180:183], v195 offset:33792
	ds_read_b128 v[184:187], v195 offset:34816
	ds_read_b128 v[198:201], v195 offset:35840
	ds_read_b128 v[202:205], v195 offset:36864
	ds_read_b128 v[206:209], v195 offset:37888
	ds_read_b128 v[210:213], v195 offset:38912
	ds_read_b128 v[214:217], v195 offset:39936
	global_load_lds_dwordx4 v[224:225], off
	v_lshl_add_u64 v[224:225], s[44:45], 0, v[164:165]
	s_mov_b32 m0, s50
	s_nop 0
	global_load_lds_dwordx4 v[224:225], off
	s_waitcnt vmcnt(8)
	s_waitcnt lgkmcnt(0)
	s_barrier
	s_setprio 1
	s_waitcnt lgkmcnt(0)
	v_mfma_f32_16x16x32_f16 v[132:135], v[16:19], v[176:179], v[132:135]
	v_mfma_f32_16x16x32_f16 v[128:131], v[136:139], v[176:179], v[128:131]
	v_mfma_f32_16x16x32_f16 v[116:119], v[16:19], v[184:187], v[116:119]
	v_mfma_f32_16x16x32_f16 v[112:115], v[136:139], v[184:187], v[112:115]
	v_mfma_f32_16x16x32_f16 v[100:103], v[16:19], v[202:205], v[100:103]
	v_mfma_f32_16x16x32_f16 v[96:99], v[136:139], v[202:205], v[96:99]
	v_mfma_f32_16x16x32_f16 v[84:87], v[16:19], v[210:213], v[84:87]
	v_mfma_f32_16x16x32_f16 v[80:83], v[136:139], v[210:213], v[80:83]
	v_mfma_f32_16x16x32_f16 v[132:135], v[20:23], v[180:183], v[132:135]
	v_mfma_f32_16x16x32_f16 v[128:131], v[140:143], v[180:183], v[128:131]
	v_mfma_f32_16x16x32_f16 v[116:119], v[20:23], v[198:201], v[116:119]
	v_mfma_f32_16x16x32_f16 v[112:115], v[140:143], v[198:201], v[112:115]
	v_mfma_f32_16x16x32_f16 v[100:103], v[20:23], v[206:209], v[100:103]
	v_mfma_f32_16x16x32_f16 v[96:99], v[140:143], v[206:209], v[96:99]
	v_mfma_f32_16x16x32_f16 v[84:87], v[20:23], v[214:217], v[84:87]
	v_mfma_f32_16x16x32_f16 v[80:83], v[140:143], v[214:217], v[80:83]
	s_setprio 0
	s_setprio 1
	v_mfma_f32_16x16x32_f16 v[124:127], v[144:147], v[176:179], v[124:127]
	v_mfma_f32_16x16x32_f16 v[120:123], v[152:155], v[176:179], v[120:123]
	v_mfma_f32_16x16x32_f16 v[108:111], v[144:147], v[184:187], v[108:111]
	v_mfma_f32_16x16x32_f16 v[104:107], v[152:155], v[184:187], v[104:107]
	v_mfma_f32_16x16x32_f16 v[92:95], v[144:147], v[202:205], v[92:95]
	v_mfma_f32_16x16x32_f16 v[88:91], v[152:155], v[202:205], v[88:91]
	v_mfma_f32_16x16x32_f16 v[76:79], v[144:147], v[210:213], v[76:79]
	v_mfma_f32_16x16x32_f16 v[72:75], v[152:155], v[210:213], v[72:75]
	v_mfma_f32_16x16x32_f16 v[124:127], v[148:151], v[180:183], v[124:127]
	v_mfma_f32_16x16x32_f16 v[120:123], v[156:159], v[180:183], v[120:123]
	v_mfma_f32_16x16x32_f16 v[108:111], v[148:151], v[198:201], v[108:111]
	v_mfma_f32_16x16x32_f16 v[104:107], v[156:159], v[198:201], v[104:107]
	s_barrier
; #define PG8_STAGE(bufoff, gbase, voff) do { _Pragma("unroll") for (int _i = 0; _i < 2; ++_i) \
;         __builtin_amdgcn_global_load_lds((const unsigned*)((const char*)(gbase) + (voff)[_i]), (PG8_LAS unsigned*)(lds + (bufoff) + ldsw + _i * 8192), 16, 0, 0); } while (0)
; #define PG8_LDA(dst, b, h) do { _Pragma("unroll") for (int m = 0; m < 4; ++m) _Pragma("unroll") for (int k = 0; k < 2; ++k) dst[m][k] = *(const PG8_LAS bf16x8*)(lds + PG8_SA(b, h) + aoff + m * 2048 + k * 1024); } while (0)
; #define PG8_LDB(dst, b, h) do { _Pragma("unroll") for (int n = 0; n < 2; ++n) _Pragma("unroll") for (int k = 0; k < 2; ++k) dst[n][k] = *(const PG8_LAS bf16x8*)(lds + PG8_SB(b, h) + boff + n * 2048 + k * 1024); } while (0)
; #define PG8_MMA(ai, bj, At, Bt) do { __builtin_amdgcn_s_setprio(1); _Pragma("unroll") for (int m = 0; m < 4; ++m) _Pragma("unroll") for (int n = 0; n < 2; ++n) _Pragma("unroll") for (int k = 0; k < 2; ++k) \
;         acc[ai][bj][m][n] = mma16<F16>(Bt[n][k], At[m][k], acc[ai][bj][m][n]); __builtin_amdgcn_s_setprio(0); } while (0)
; #define PG8_WAIT_V(n) asm volatile("s_waitcnt vmcnt(" #n ")" ::: "memory")
; template <class Epi, class Sched, bool ALIGN_EPI = false, bool SP2 = false, bool F16 = false>
; __device__ __forceinline__ void gemm_phase(PG8_LAS unsigned char* lds, const Gemm g, const Sched& S, const Epi& E, const int wid_in) {
;     ...
;             PG8_LDB(B0, 0, 0); PG8_LDB(B1, 0, 1); PG8_SCHED; PG8_LDA(At, 0, 0); PG8_STAGE(PG8_SA(1, 1), a1 + hstep, voffA);
;             PG8_WAIT_V(8); PG8_WAIT_L(0); PG8_BAR; PG8_MMA(0, 0, At, B0); PG8_MMA(0, 1, At, B1); PG8_BAR; PG8_SCHED;
;             PG8_LDA(At, 0, 1); PG8_STAGE(PG8_SB(0, 0), b2, voffB); PG8_STAGE(PG8_SB(0, 1), b2 + hstep, voffB); PG8_STAGE(PG8_SA(0, 0), a2, voffA);
;             PG8_WAIT_V(8); PG8_WAIT_L(0); PG8_BAR; PG8_MMA(1, 0, At, B0); PG8_MMA(1, 1, At, B1); PG8_BAR; PG8_SCHED;
;             PG8_LDB(B0, 1, 0); PG8_LDB(B1, 1, 1); PG8_SCHED; PG8_LDA(At, 1, 0); PG8_STAGE(PG8_SA(0, 1), a2 + hstep, voffA);
;             PG8_WAIT_V(8); PG8_WAIT_L(0); PG8_BAR; PG8_MMA(0, 0, At, B0); PG8_MMA(0, 1, At, B1); PG8_BAR; PG8_SCHED;
;             PG8_LDA(At, 1, 1); PG8_STAGE(PG8_SB(1, 0), b3, voffB); PG8_STAGE(PG8_SB(1, 1), b3 + hstep, voffB); PG8_STAGE(PG8_SA(1, 0), a3, voffA);
;             PG8_WAIT_V(8); PG8_WAIT_L(0); PG8_BAR; PG8_MMA(1, 0, At, B0); PG8_MMA(1, 1, At, B1); PG8_BAR; PG8_SCHED;
	v_mfma_f32_16x16x32_f16 v[92:95], v[148:151], v[206:209], v[92:95]
	v_mfma_f32_16x16x32_f16 v[88:91], v[156:159], v[206:209], v[88:91]
	v_mfma_f32_16x16x32_f16 v[76:79], v[148:151], v[214:217], v[76:79]
	v_mfma_f32_16x16x32_f16 v[72:75], v[156:159], v[214:217], v[72:75]
	s_setprio 0
	s_add_i32 s44, s66, s68
	v_lshl_add_u64 v[188:189], v[188:189], 0, s[18:19]
	s_mov_b32 m0, s44
	ds_read_b128 v[176:179], v195 offset:49152
	ds_read_b128 v[180:183], v195 offset:50176
	ds_read_b128 v[184:187], v195 offset:51200
	ds_read_b128 v[198:201], v195 offset:52224
	ds_read_b128 v[202:205], v195 offset:53248
	ds_read_b128 v[206:209], v195 offset:54272
	ds_read_b128 v[210:213], v195 offset:55296
	ds_read_b128 v[214:217], v195 offset:56320
	global_load_lds_dwordx4 v[188:189], off
	s_add_i32 m0, s44, 0x2000
	s_add_u32 s36, s36, 0x40080
	v_lshl_add_u64 v[188:189], v[218:219], 0, s[18:19]
	s_addc_u32 s37, s37, 0
	s_add_i32 s44, s67, s68
	global_load_lds_dwordx4 v[188:189], off
	v_lshl_add_u64 v[188:189], s[36:37], 0, v[162:163]
	s_mov_b32 m0, s44
	s_nop 0
	global_load_lds_dwordx4 v[188:189], off
	v_lshl_add_u64 v[188:189], s[36:37], 0, v[166:167]
	s_add_i32 m0, s44, 0x2000
	s_nop 0
	global_load_lds_dwordx4 v[188:189], off
	v_lshl_add_u64 v[188:189], v[220:221], 0, s[18:19]
	s_mov_b32 m0, s75
	s_nop 0
	global_load_lds_dwordx4 v[188:189], off
	v_lshl_add_u64 v[188:189], v[222:223], 0, s[18:19]
	s_mov_b32 m0, s53
	s_nop 0
	global_load_lds_dwordx4 v[188:189], off
	s_waitcnt vmcnt(8)
	s_waitcnt lgkmcnt(0)
	s_barrier
	s_setprio 1
	s_waitcnt lgkmcnt(0)
	v_mfma_f32_16x16x32_f16 v[68:71], v[16:19], v[176:179], v[68:71]
	v_mfma_f32_16x16x32_f16 v[52:55], v[16:19], v[184:187], v[52:55]
	v_mfma_f32_16x16x32_f16 v[36:39], v[16:19], v[202:205], v[36:39]
	v_mfma_f32_16x16x32_f16 v[0:3], v[16:19], v[210:213], v[0:3]
	v_mfma_f32_16x16x32_f16 v[68:71], v[20:23], v[180:183], v[68:71]
	v_mfma_f32_16x16x32_f16 v[64:67], v[136:139], v[176:179], v[64:67]
	v_mfma_f32_16x16x32_f16 v[52:55], v[20:23], v[198:201], v[52:55]
	v_mfma_f32_16x16x32_f16 v[48:51], v[136:139], v[184:187], v[48:51]
	v_mfma_f32_16x16x32_f16 v[36:39], v[20:23], v[206:209], v[36:39]
	v_mfma_f32_16x16x32_f16 v[32:35], v[136:139], v[202:205], v[32:35]
	v_mfma_f32_16x16x32_f16 v[20:23], v[20:23], v[214:217], v[0:3]
	v_mfma_f32_16x16x32_f16 v[0:3], v[136:139], v[210:213], v[4:7]
	v_mfma_f32_16x16x32_f16 v[64:67], v[140:143], v[180:183], v[64:67]
	v_mfma_f32_16x16x32_f16 v[48:51], v[140:143], v[198:201], v[48:51]
	v_mfma_f32_16x16x32_f16 v[32:35], v[140:143], v[206:209], v[32:35]
	v_mfma_f32_16x16x32_f16 v[16:19], v[140:143], v[214:217], v[0:3]
	s_setprio 0
	s_setprio 1
	v_mfma_f32_16x16x32_f16 v[0:3], v[144:147], v[176:179], v[60:63]
	v_mfma_f32_16x16x32_f16 v[60:63], v[148:151], v[180:183], v[0:3]
	v_mfma_f32_16x16x32_f16 v[0:3], v[152:155], v[176:179], v[56:59]
	v_mfma_f32_16x16x32_f16 v[56:59], v[156:159], v[180:183], v[0:3]
	v_mfma_f32_16x16x32_f16 v[0:3], v[144:147], v[184:187], v[44:47]
	v_mfma_f32_16x16x32_f16 v[44:47], v[148:151], v[198:201], v[0:3]
	v_mfma_f32_16x16x32_f16 v[0:3], v[152:155], v[184:187], v[40:43]
	v_mfma_f32_16x16x32_f16 v[40:43], v[156:159], v[198:201], v[0:3]
	v_mfma_f32_16x16x32_f16 v[0:3], v[144:147], v[202:205], v[28:31]
	v_mfma_f32_16x16x32_f16 v[28:31], v[148:151], v[206:209], v[0:3]
	v_mfma_f32_16x16x32_f16 v[0:3], v[152:155], v[202:205], v[24:27]
	v_mfma_f32_16x16x32_f16 v[24:27], v[156:159], v[206:209], v[0:3]
	s_barrier
	v_mfma_f32_16x16x32_f16 v[0:3], v[144:147], v[210:213], v[12:15]
	v_mfma_f32_16x16x32_f16 v[12:15], v[148:151], v[214:217], v[0:3]
	v_mfma_f32_16x16x32_f16 v[0:3], v[152:155], v[210:213], v[8:11]
	v_mfma_f32_16x16x32_f16 v[8:11], v[156:159], v[214:217], v[0:3]
	s_setprio 0
	s_add_i32 s65, s65, 2
	s_add_u32 s34, s34, 0x100
	s_addc_u32 s35, s35, 0
	s_add_u32 s43, s43, 0x100
	s_addc_u32 s64, s64, 0
	s_cmp_gt_u32 s65, 13
	s_cbranch_scc0 .LBB0_585
	s_and_b64 vcc, exec, s[16:17]
	s_cbranch_vccz .LBB0_588
	s_barrier

; #define PG8_STAGE(bufoff, gbase, voff) do { _Pragma("unroll") for (int _i = 0; _i < 2; ++_i) \
;         __builtin_amdgcn_global_load_lds((const unsigned*)((const char*)(gbase) + (voff)[_i]), (PG8_LAS unsigned*)(lds + (bufoff) + ldsw + _i * 8192), 16, 0, 0); } while (0)
; #define PG8_LDA(dst, b, h) do { _Pragma("unroll") for (int m = 0; m < 4; ++m) _Pragma("unroll") for (int k = 0; k < 2; ++k) dst[m][k] = *(const PG8_LAS bf16x8*)(lds + PG8_SA(b, h) + aoff + m * 2048 + k * 1024); } while (0)
; #define PG8_LDB(dst, b, h) do { _Pragma("unroll") for (int n = 0; n < 2; ++n) _Pragma("unroll") for (int k = 0; k < 2; ++k) dst[n][k] = *(const PG8_LAS bf16x8*)(lds + PG8_SB(b, h) + boff + n * 2048 + k * 1024); } while (0)
; #define PG8_WAIT_V(n) asm volatile("s_waitcnt vmcnt(" #n ")" ::: "memory")
; #define PG8_WAIT_L(n) asm volatile("s_waitcnt lgkmcnt(" #n ")" ::: "memory")
; #define PG8_BAR __builtin_amdgcn_s_barrier()
; #define PG8_SCHED __builtin_amdgcn_sched_barrier(0)
; template <class Epi, class Sched, bool ALIGN_EPI = false, bool SP2 = false, bool F16 = false>
; __device__ __forceinline__ void gemm_phase(PG8_LAS unsigned char* lds, const Gemm g, const Sched& S, const Epi& E, const int wid_in) {
;     ...
;         const bool has_next = S.next(ui + 1, nxt);
;         const char* nA = has_next ? (const char*)g.A + (size_t)nxt.pm * tstep : cA; const char* nB = has_next ? (const char*)g.Bt + (size_t)nxt.pn * tstep : cB;
;         for (int t = 0; t < nt; t += 2) {
;             const bool last = (t == nt - 2);
;             const char* a1 = cA + (size_t)(t + 1) * kstep;
;             const char* a2 = last ? nA : cA + (size_t)(t + 2) * kstep; const char* b2 = last ? nB : cB + (size_t)(t + 2) * kstep;
;             const char* a3 = a2 + kstep; const char* b3 = b2 + kstep;
;             if (last && has_next) S.a_ready(nxt);
;             if constexpr (SP2) {
;             PG8_LDB(B0, 0, 0); PG8_LDB(B1, 0, 1); PG8_SCHED; PG8_LDA(At, 0, 0); PG8_STAGE(PG8_SA(1, 1), a1 + hstep, voffA);
;             PG8_WAIT_V(8); PG8_WAIT_L(0); PG8_BAR; PG8_MMA(0, 0, At, B0); PG8_MMA(0, 1, At, B1); PG8_BAR; PG8_SCHED;
;             PG8_LDA(At, 0, 1); PG8_STAGE(PG8_SB(0, 0), b2, voffB); PG8_STAGE(PG8_SB(0, 1), b2 + hstep, voffB); PG8_STAGE(PG8_SA(0, 0), a2, voffA);
;             PG8_WAIT_V(8); PG8_WAIT_L(0); PG8_BAR; PG8_MMA(1, 0, At, B0); PG8_MMA(1, 1, At, B1); PG8_BAR; PG8_SCHED;
.LBB0_620:
	s_mov_b64 s[44:45], s[10:11]
	s_add_i32 s10, s30, s40
	s_mov_b64 s[36:37], s[12:13]
	s_mov_b32 s12, s62
	s_mov_b32 s13, s61
	s_and_b32 s61, s10, 3
	s_ashr_i32 s62, s10, 2
	s_and_b64 s[10:11], s[26:27], exec
	s_cselect_b32 s12, s62, s12
	ds_read_b128 v[0:3], v134
	ds_read_b128 v[4:7], v134 offset:1024
	ds_read_b128 v[8:11], v134 offset:2048
	ds_read_b128 v[12:15], v134 offset:3072
	ds_read_b128 v[16:19], v135
	ds_read_b128 v[20:23], v135 offset:1024
	ds_read_b128 v[24:27], v135 offset:2048
	ds_read_b128 v[28:31], v135 offset:3072
	s_cselect_b32 s10, s61, s13
	s_ashr_i32 s13, s12, 31
	s_lshl_b64 s[12:13], s[12:13], 17
	s_add_u32 s12, s43, s12
	s_addc_u32 s13, s46, s13
	s_and_b64 s[30:31], s[26:27], exec
	s_cselect_b32 s35, s13, s37
	s_cselect_b32 s34, s12, s36
	s_ashr_i32 s11, s10, 31
	s_lshl_b64 s[10:11], s[10:11], 17
	s_add_u32 s10, s41, s10
	s_addc_u32 s11, s42, s11
	s_and_b64 s[30:31], s[26:27], exec
	s_cselect_b32 s31, s11, s45
	s_cselect_b32 s30, s10, s44
	s_add_u32 s64, s36, 0x10080
	s_addc_u32 s65, s37, 0
	s_mov_b32 m0, s15
	v_lshl_add_u64 v[64:65], s[64:65], 0, v[130:131]
	ds_read_b128 v[32:35], v136
	ds_read_b128 v[36:39], v136 offset:1024
	ds_read_b128 v[40:43], v136 offset:2048
	ds_read_b128 v[44:47], v136 offset:3072
	ds_read_b128 v[48:51], v136 offset:4096
	ds_read_b128 v[52:55], v136 offset:5120
	ds_read_b128 v[56:59], v136 offset:6144
	ds_read_b128 v[60:63], v136 offset:7168
	global_load_lds_dwordx4 v[64:65], off
	v_lshl_add_u64 v[64:65], s[64:65], 0, v[128:129]
	s_mov_b32 m0, s50
	s_nop 0
	global_load_lds_dwordx4 v[64:65], off
	s_waitcnt vmcnt(8)
	s_waitcnt lgkmcnt(0)
	s_barrier
	s_setprio 1
	s_waitcnt lgkmcnt(0)
	v_mfma_f32_16x16x32_bf16 v[64:67], v[0:3], v[32:35], 0
	v_mfma_f32_16x16x32_bf16 v[68:71], v[8:11], v[32:35], 0
	v_mfma_f32_16x16x32_bf16 v[72:75], v[0:3], v[40:43], 0
	v_mfma_f32_16x16x32_bf16 v[76:79], v[8:11], v[40:43], 0
	v_mfma_f32_16x16x32_bf16 v[80:83], v[0:3], v[48:51], 0
	v_mfma_f32_16x16x32_bf16 v[84:87], v[8:11], v[48:51], 0
	v_mfma_f32_16x16x32_bf16 v[88:91], v[0:3], v[56:59], 0
	v_mfma_f32_16x16x32_bf16 v[92:95], v[8:11], v[56:59], 0
	v_mfma_f32_16x16x32_bf16 v[64:67], v[4:7], v[36:39], v[64:67]
	v_mfma_f32_16x16x32_bf16 v[68:71], v[12:15], v[36:39], v[68:71]
	v_mfma_f32_16x16x32_bf16 v[72:75], v[4:7], v[44:47], v[72:75]
	v_mfma_f32_16x16x32_bf16 v[76:79], v[12:15], v[44:47], v[76:79]
	v_mfma_f32_16x16x32_bf16 v[80:83], v[4:7], v[52:55], v[80:83]
	v_mfma_f32_16x16x32_bf16 v[84:87], v[12:15], v[52:55], v[84:87]
	v_mfma_f32_16x16x32_bf16 v[88:91], v[4:7], v[60:63], v[88:91]
	v_mfma_f32_16x16x32_bf16 v[92:95], v[12:15], v[60:63], v[92:95]
	s_setprio 0
	s_setprio 1
	v_mfma_f32_16x16x32_bf16 v[96:99], v[16:19], v[32:35], 0
	v_mfma_f32_16x16x32_bf16 v[32:35], v[24:27], v[32:35], 0
	v_mfma_f32_16x16x32_bf16 v[96:99], v[20:23], v[36:39], v[96:99]
	v_mfma_f32_16x16x32_bf16 v[32:35], v[28:31], v[36:39], v[32:35]
	v_mfma_f32_16x16x32_bf16 v[36:39], v[16:19], v[40:43], 0
	v_mfma_f32_16x16x32_bf16 v[40:43], v[24:27], v[40:43], 0
	v_mfma_f32_16x16x32_bf16 v[36:39], v[20:23], v[44:47], v[36:39]
	v_mfma_f32_16x16x32_bf16 v[40:43], v[28:31], v[44:47], v[40:43]
	v_mfma_f32_16x16x32_bf16 v[44:47], v[16:19], v[48:51], 0
	v_mfma_f32_16x16x32_bf16 v[48:51], v[24:27], v[48:51], 0
	v_mfma_f32_16x16x32_bf16 v[44:47], v[20:23], v[52:55], v[44:47]
	v_mfma_f32_16x16x32_bf16 v[48:51], v[28:31], v[52:55], v[48:51]
	s_barrier
	v_mfma_f32_16x16x32_bf16 v[52:55], v[16:19], v[56:59], 0
	v_mfma_f32_16x16x32_bf16 v[56:59], v[24:27], v[56:59], 0
	v_mfma_f32_16x16x32_bf16 v[52:55], v[20:23], v[60:63], v[52:55]
	v_mfma_f32_16x16x32_bf16 v[56:59], v[28:31], v[60:63], v[56:59]
	s_setprio 0
	v_lshl_add_u64 v[204:205], s[44:45], 0, v[130:131]
	s_mov_b32 m0, s51
	v_lshl_add_u64 v[140:141], v[204:205], 0, s[22:23]
	v_lshl_add_u64 v[206:207], s[44:45], 0, v[128:129]
	s_add_u32 s64, s44, 0x10100
	ds_read_b128 v[60:63], v136 offset:16384
	ds_read_b128 v[100:103], v136 offset:17408
	ds_read_b128 v[104:107], v136 offset:18432
	ds_read_b128 v[108:111], v136 offset:19456
	ds_read_b128 v[112:115], v136 offset:20480
	ds_read_b128 v[116:119], v136 offset:21504
	ds_read_b128 v[120:123], v136 offset:22528
	ds_read_b128 v[124:127], v136 offset:23552
	global_load_lds_dwordx4 v[140:141], off
	v_lshl_add_u64 v[140:141], v[206:207], 0, s[22:23]
	s_mov_b32 m0, s52
	s_addc_u32 s65, s45, 0
	global_load_lds_dwordx4 v[140:141], off
	v_lshl_add_u64 v[140:141], s[64:65], 0, v[130:131]
	s_mov_b32 m0, s53
	v_lshl_add_u64 v[208:209], s[36:37], 0, v[130:131]
	global_load_lds_dwordx4 v[140:141], off
	v_lshl_add_u64 v[140:141], s[64:65], 0, v[128:129]
	s_mov_b32 m0, s54
	v_lshl_add_u64 v[210:211], s[36:37], 0, v[128:129]
	global_load_lds_dwordx4 v[140:141], off
	v_lshl_add_u64 v[140:141], v[208:209], 0, s[22:23]
	s_mov_b32 m0, s74
	s_nop 0
	global_load_lds_dwordx4 v[140:141], off
	v_lshl_add_u64 v[140:141], v[210:211], 0, s[22:23]
	s_mov_b32 m0, s47
	s_nop 0
	global_load_lds_dwordx4 v[140:141], off
	s_waitcnt vmcnt(8)
	s_waitcnt lgkmcnt(0)
	s_barrier
; #define PG8_STAGE(bufoff, gbase, voff) do { _Pragma("unroll") for (int _i = 0; _i < 2; ++_i) \
;         __builtin_amdgcn_global_load_lds((const unsigned*)((const char*)(gbase) + (voff)[_i]), (PG8_LAS unsigned*)(lds + (bufoff) + ldsw + _i * 8192), 16, 0, 0); } while (0)
; #define PG8_LDA(dst, b, h) do { _Pragma("unroll") for (int m = 0; m < 4; ++m) _Pragma("unroll") for (int k = 0; k < 2; ++k) dst[m][k] = *(const PG8_LAS bf16x8*)(lds + PG8_SA(b, h) + aoff + m * 2048 + k * 1024); } while (0)
; #define PG8_LDB(dst, b, h) do { _Pragma("unroll") for (int n = 0; n < 2; ++n) _Pragma("unroll") for (int k = 0; k < 2; ++k) dst[n][k] = *(const PG8_LAS bf16x8*)(lds + PG8_SB(b, h) + boff + n * 2048 + k * 1024); } while (0)
; #define PG8_MMA(ai, bj, At, Bt) do { __builtin_amdgcn_s_setprio(1); _Pragma("unroll") for (int m = 0; m < 4; ++m) _Pragma("unroll") for (int n = 0; n < 2; ++n) _Pragma("unroll") for (int k = 0; k < 2; ++k) \
;         acc[ai][bj][m][n] = mma16<F16>(Bt[n][k], At[m][k], acc[ai][bj][m][n]); __builtin_amdgcn_s_setprio(0); } while (0)
; #define PG8_WAIT_V(n) asm volatile("s_waitcnt vmcnt(" #n ")" ::: "memory")
; #define PG8_WAIT_L(n) asm volatile("s_waitcnt lgkmcnt(" #n ")" ::: "memory")
; #define PG8_BAR __builtin_amdgcn_s_barrier()
; #define PG8_SCHED __builtin_amdgcn_sched_barrier(0)
; template <class Epi, class Sched, bool ALIGN_EPI = false, bool SP2 = false, bool F16 = false>
; __device__ __forceinline__ void gemm_phase(PG8_LAS unsigned char* lds, const Gemm g, const Sched& S, const Epi& E, const int wid_in) {
;     ...
;             PG8_WAIT_V(8); PG8_WAIT_L(0); PG8_BAR; PG8_MMA(1, 0, At, B0); PG8_MMA(1, 1, At, B1); PG8_BAR; PG8_SCHED;
;             PG8_LDB(B0, 1, 0); PG8_LDB(B1, 1, 1); PG8_SCHED; PG8_LDA(At, 1, 0); PG8_STAGE(PG8_SA(0, 1), a2 + hstep, voffA);
;             PG8_WAIT_V(8); PG8_WAIT_L(0); PG8_BAR; PG8_MMA(0, 0, At, B0); PG8_MMA(0, 1, At, B1); PG8_BAR; PG8_SCHED;
	s_setprio 1
	s_waitcnt lgkmcnt(0)
	v_mfma_f32_16x16x32_bf16 v[140:143], v[0:3], v[60:63], 0
	v_mfma_f32_16x16x32_bf16 v[148:151], v[0:3], v[104:107], 0
	v_mfma_f32_16x16x32_bf16 v[156:159], v[0:3], v[112:115], 0
	v_mfma_f32_16x16x32_bf16 v[0:3], v[0:3], v[120:123], 0
	v_mfma_f32_16x16x32_bf16 v[140:143], v[4:7], v[100:103], v[140:143]
	v_mfma_f32_16x16x32_bf16 v[148:151], v[4:7], v[108:111], v[148:151]
	v_mfma_f32_16x16x32_bf16 v[156:159], v[4:7], v[116:119], v[156:159]
	v_mfma_f32_16x16x32_bf16 v[0:3], v[4:7], v[124:127], v[0:3]
	v_mfma_f32_16x16x32_bf16 v[4:7], v[8:11], v[120:123], 0
	v_mfma_f32_16x16x32_bf16 v[144:147], v[8:11], v[60:63], 0
	v_mfma_f32_16x16x32_bf16 v[152:155], v[8:11], v[104:107], 0
	v_mfma_f32_16x16x32_bf16 v[160:163], v[8:11], v[112:115], 0
	v_mfma_f32_16x16x32_bf16 v[4:7], v[12:15], v[124:127], v[4:7]
	v_mfma_f32_16x16x32_bf16 v[144:147], v[12:15], v[100:103], v[144:147]
	v_mfma_f32_16x16x32_bf16 v[152:155], v[12:15], v[108:111], v[152:155]
	v_mfma_f32_16x16x32_bf16 v[160:163], v[12:15], v[116:119], v[160:163]
	s_setprio 0
	s_setprio 1
	v_mfma_f32_16x16x32_bf16 v[8:11], v[16:19], v[60:63], 0
	v_mfma_f32_16x16x32_bf16 v[12:15], v[24:27], v[60:63], 0
	v_mfma_f32_16x16x32_bf16 v[8:11], v[20:23], v[100:103], v[8:11]
	v_mfma_f32_16x16x32_bf16 v[12:15], v[28:31], v[100:103], v[12:15]
	v_mfma_f32_16x16x32_bf16 v[60:63], v[16:19], v[104:107], 0
	v_mfma_f32_16x16x32_bf16 v[100:103], v[24:27], v[104:107], 0
	v_mfma_f32_16x16x32_bf16 v[104:107], v[16:19], v[112:115], 0
	v_mfma_f32_16x16x32_bf16 v[16:19], v[16:19], v[120:123], 0
	v_mfma_f32_16x16x32_bf16 v[60:63], v[20:23], v[108:111], v[60:63]
	v_mfma_f32_16x16x32_bf16 v[100:103], v[28:31], v[108:111], v[100:103]
	v_mfma_f32_16x16x32_bf16 v[104:107], v[20:23], v[116:119], v[104:107]
	v_mfma_f32_16x16x32_bf16 v[108:111], v[24:27], v[112:115], 0
	s_barrier
	v_mfma_f32_16x16x32_bf16 v[16:19], v[20:23], v[124:127], v[16:19]
	v_mfma_f32_16x16x32_bf16 v[20:23], v[24:27], v[120:123], 0
	v_mfma_f32_16x16x32_bf16 v[108:111], v[28:31], v[116:119], v[108:111]
	v_mfma_f32_16x16x32_bf16 v[20:23], v[28:31], v[124:127], v[20:23]
	s_setprio 0
	ds_read_b128 v[24:27], v137
	ds_read_b128 v[28:31], v137 offset:1024
	ds_read_b128 v[112:115], v137 offset:2048
	ds_read_b128 v[116:119], v137 offset:3072
	ds_read_b128 v[120:123], v138
	ds_read_b128 v[124:127], v138 offset:1024
	ds_read_b128 v[164:167], v138 offset:2048
	ds_read_b128 v[168:171], v138 offset:3072
	s_add_u32 s64, s36, 0x10100
	s_addc_u32 s65, s37, 0
	s_mov_b32 m0, s48
	v_lshl_add_u64 v[212:213], s[64:65], 0, v[130:131]
	ds_read_b128 v[172:175], v136 offset:32768
	ds_read_b128 v[176:179], v136 offset:33792
	ds_read_b128 v[180:183], v136 offset:34816
	ds_read_b128 v[184:187], v136 offset:35840
	ds_read_b128 v[188:191], v136 offset:36864
	ds_read_b128 v[192:195], v136 offset:37888
	ds_read_b128 v[196:199], v136 offset:38912
	ds_read_b128 v[200:203], v136 offset:39936
	global_load_lds_dwordx4 v[212:213], off
	v_lshl_add_u64 v[212:213], s[64:65], 0, v[128:129]
	s_mov_b32 m0, s49
	s_nop 0
	global_load_lds_dwordx4 v[212:213], off
	s_waitcnt vmcnt(8)
	s_waitcnt lgkmcnt(0)
	s_barrier
	s_setprio 1
	s_waitcnt lgkmcnt(0)
	v_mfma_f32_16x16x32_bf16 v[64:67], v[24:27], v[172:175], v[64:67]
	v_mfma_f32_16x16x32_bf16 v[68:71], v[112:115], v[172:175], v[68:71]
	v_mfma_f32_16x16x32_bf16 v[72:75], v[24:27], v[180:183], v[72:75]
	v_mfma_f32_16x16x32_bf16 v[76:79], v[112:115], v[180:183], v[76:79]
	v_mfma_f32_16x16x32_bf16 v[80:83], v[24:27], v[188:191], v[80:83]
	v_mfma_f32_16x16x32_bf16 v[84:87], v[112:115], v[188:191], v[84:87]
	v_mfma_f32_16x16x32_bf16 v[88:91], v[24:27], v[196:199], v[88:91]
	v_mfma_f32_16x16x32_bf16 v[92:95], v[112:115], v[196:199], v[92:95]
	v_mfma_f32_16x16x32_bf16 v[64:67], v[28:31], v[176:179], v[64:67]
	v_mfma_f32_16x16x32_bf16 v[68:71], v[116:119], v[176:179], v[68:71]
	v_mfma_f32_16x16x32_bf16 v[72:75], v[28:31], v[184:187], v[72:75]
	v_mfma_f32_16x16x32_bf16 v[76:79], v[116:119], v[184:187], v[76:79]
	v_mfma_f32_16x16x32_bf16 v[80:83], v[28:31], v[192:195], v[80:83]
	v_mfma_f32_16x16x32_bf16 v[84:87], v[116:119], v[192:195], v[84:87]
	v_mfma_f32_16x16x32_bf16 v[88:91], v[28:31], v[200:203], v[88:91]
	v_mfma_f32_16x16x32_bf16 v[92:95], v[116:119], v[200:203], v[92:95]
	s_setprio 0
	s_setprio 1
	v_mfma_f32_16x16x32_bf16 v[96:99], v[120:123], v[172:175], v[96:99]
	v_mfma_f32_16x16x32_bf16 v[32:35], v[164:167], v[172:175], v[32:35]
	v_mfma_f32_16x16x32_bf16 v[36:39], v[120:123], v[180:183], v[36:39]
	v_mfma_f32_16x16x32_bf16 v[40:43], v[164:167], v[180:183], v[40:43]
	v_mfma_f32_16x16x32_bf16 v[44:47], v[120:123], v[188:191], v[44:47]
	v_mfma_f32_16x16x32_bf16 v[48:51], v[164:167], v[188:191], v[48:51]
	v_mfma_f32_16x16x32_bf16 v[52:55], v[120:123], v[196:199], v[52:55]
	v_mfma_f32_16x16x32_bf16 v[56:59], v[164:167], v[196:199], v[56:59]
	v_mfma_f32_16x16x32_bf16 v[96:99], v[124:127], v[176:179], v[96:99]
	v_mfma_f32_16x16x32_bf16 v[32:35], v[168:171], v[176:179], v[32:35]
	v_mfma_f32_16x16x32_bf16 v[36:39], v[124:127], v[184:187], v[36:39]
	v_mfma_f32_16x16x32_bf16 v[40:43], v[168:171], v[184:187], v[40:43]
	s_barrier
; #define PG8_STAGE(bufoff, gbase, voff) do { _Pragma("unroll") for (int _i = 0; _i < 2; ++_i) \
;         __builtin_amdgcn_global_load_lds((const unsigned*)((const char*)(gbase) + (voff)[_i]), (PG8_LAS unsigned*)(lds + (bufoff) + ldsw + _i * 8192), 16, 0, 0); } while (0)
; #define PG8_LDA(dst, b, h) do { _Pragma("unroll") for (int m = 0; m < 4; ++m) _Pragma("unroll") for (int k = 0; k < 2; ++k) dst[m][k] = *(const PG8_LAS bf16x8*)(lds + PG8_SA(b, h) + aoff + m * 2048 + k * 1024); } while (0)
; #define PG8_LDB(dst, b, h) do { _Pragma("unroll") for (int n = 0; n < 2; ++n) _Pragma("unroll") for (int k = 0; k < 2; ++k) dst[n][k] = *(const PG8_LAS bf16x8*)(lds + PG8_SB(b, h) + boff + n * 2048 + k * 1024); } while (0)
; #define PG8_MMA(ai, bj, At, Bt) do { __builtin_amdgcn_s_setprio(1); _Pragma("unroll") for (int m = 0; m < 4; ++m) _Pragma("unroll") for (int n = 0; n < 2; ++n) _Pragma("unroll") for (int k = 0; k < 2; ++k) \
;         acc[ai][bj][m][n] = mma16<F16>(Bt[n][k], At[m][k], acc[ai][bj][m][n]); __builtin_amdgcn_s_setprio(0); } while (0)
; #define PG8_WAIT_V(n) asm volatile("s_waitcnt vmcnt(" #n ")" ::: "memory")
; template <class Epi, class Sched, bool ALIGN_EPI = false, bool SP2 = false, bool F16 = false>
; __device__ __forceinline__ void gemm_phase(PG8_LAS unsigned char* lds, const Gemm g, const Sched& S, const Epi& E, const int wid_in) {
;     ...
;             PG8_LDB(B0, 0, 0); PG8_LDB(B1, 0, 1); PG8_SCHED; PG8_LDA(At, 0, 0); PG8_STAGE(PG8_SA(1, 1), a1 + hstep, voffA);
;             PG8_WAIT_V(8); PG8_WAIT_L(0); PG8_BAR; PG8_MMA(0, 0, At, B0); PG8_MMA(0, 1, At, B1); PG8_BAR; PG8_SCHED;
;             PG8_LDA(At, 0, 1); PG8_STAGE(PG8_SB(0, 0), b2, voffB); PG8_STAGE(PG8_SB(0, 1), b2 + hstep, voffB); PG8_STAGE(PG8_SA(0, 0), a2, voffA);
;             PG8_WAIT_V(8); PG8_WAIT_L(0); PG8_BAR; PG8_MMA(1, 0, At, B0); PG8_MMA(1, 1, At, B1); PG8_BAR; PG8_SCHED;
;             PG8_LDB(B0, 1, 0); PG8_LDB(B1, 1, 1); PG8_SCHED; PG8_LDA(At, 1, 0); PG8_STAGE(PG8_SA(0, 1), a2 + hstep, voffA);
;             PG8_WAIT_V(8); PG8_WAIT_L(0); PG8_BAR; PG8_MMA(0, 0, At, B0); PG8_MMA(0, 1, At, B1); PG8_BAR; PG8_SCHED;
;             PG8_LDA(At, 1, 1); PG8_STAGE(PG8_SB(1, 0), b3, voffB); PG8_STAGE(PG8_SB(1, 1), b3 + hstep, voffB); PG8_STAGE(PG8_SA(1, 0), a3, voffA);
;             PG8_WAIT_V(8); PG8_WAIT_L(0); PG8_BAR; PG8_MMA(1, 0, At, B0); PG8_MMA(1, 1, At, B1); PG8_BAR; PG8_SCHED;
	v_mfma_f32_16x16x32_bf16 v[44:47], v[124:127], v[192:195], v[44:47]
	v_mfma_f32_16x16x32_bf16 v[48:51], v[168:171], v[192:195], v[48:51]
	v_mfma_f32_16x16x32_bf16 v[52:55], v[124:127], v[200:203], v[52:55]
	v_mfma_f32_16x16x32_bf16 v[56:59], v[168:171], v[200:203], v[56:59]
	s_setprio 0
	s_mov_b32 m0, s55
	v_lshl_add_u64 v[204:205], v[204:205], 0, s[24:25]
	s_add_u32 s44, s44, 0x10180
	ds_read_b128 v[172:175], v136 offset:49152
	ds_read_b128 v[176:179], v136 offset:50176
	ds_read_b128 v[180:183], v136 offset:51200
	ds_read_b128 v[184:187], v136 offset:52224
	ds_read_b128 v[188:191], v136 offset:53248
	ds_read_b128 v[192:195], v136 offset:54272
	ds_read_b128 v[196:199], v136 offset:55296
	ds_read_b128 v[200:203], v136 offset:56320
	global_load_lds_dwordx4 v[204:205], off
	v_lshl_add_u64 v[204:205], v[206:207], 0, s[24:25]
	s_mov_b32 m0, s58
	s_addc_u32 s45, s45, 0
	global_load_lds_dwordx4 v[204:205], off
	v_lshl_add_u64 v[204:205], s[44:45], 0, v[130:131]
	s_mov_b32 m0, s59
	s_nop 0
	global_load_lds_dwordx4 v[204:205], off
	v_lshl_add_u64 v[204:205], s[44:45], 0, v[128:129]
	s_mov_b32 m0, s60
	s_nop 0
	global_load_lds_dwordx4 v[204:205], off
	v_lshl_add_u64 v[204:205], v[208:209], 0, s[24:25]
	s_mov_b32 m0, s75
	s_nop 0
	global_load_lds_dwordx4 v[204:205], off
	v_lshl_add_u64 v[204:205], v[210:211], 0, s[24:25]
	s_mov_b32 m0, s14
	s_nop 0
	global_load_lds_dwordx4 v[204:205], off
	s_waitcnt vmcnt(8)
	s_waitcnt lgkmcnt(0)
	s_barrier
	s_setprio 1
	s_waitcnt lgkmcnt(0)
	v_mfma_f32_16x16x32_bf16 v[0:3], v[24:27], v[196:199], v[0:3]
	v_mfma_f32_16x16x32_bf16 v[4:7], v[112:115], v[196:199], v[4:7]
	v_mfma_f32_16x16x32_bf16 v[140:143], v[24:27], v[172:175], v[140:143]
	v_mfma_f32_16x16x32_bf16 v[144:147], v[112:115], v[172:175], v[144:147]
	v_mfma_f32_16x16x32_bf16 v[148:151], v[24:27], v[180:183], v[148:151]
	v_mfma_f32_16x16x32_bf16 v[152:155], v[112:115], v[180:183], v[152:155]
	v_mfma_f32_16x16x32_bf16 v[156:159], v[24:27], v[188:191], v[156:159]
	v_mfma_f32_16x16x32_bf16 v[160:163], v[112:115], v[188:191], v[160:163]
	v_mfma_f32_16x16x32_bf16 v[0:3], v[28:31], v[200:203], v[0:3]
	v_mfma_f32_16x16x32_bf16 v[4:7], v[116:119], v[200:203], v[4:7]
	v_mfma_f32_16x16x32_bf16 v[140:143], v[28:31], v[176:179], v[140:143]
	v_mfma_f32_16x16x32_bf16 v[144:147], v[116:119], v[176:179], v[144:147]
	v_mfma_f32_16x16x32_bf16 v[148:151], v[28:31], v[184:187], v[148:151]
	v_mfma_f32_16x16x32_bf16 v[152:155], v[116:119], v[184:187], v[152:155]
	v_mfma_f32_16x16x32_bf16 v[156:159], v[28:31], v[192:195], v[156:159]
	v_mfma_f32_16x16x32_bf16 v[160:163], v[116:119], v[192:195], v[160:163]
	s_setprio 0
	s_setprio 1
	v_mfma_f32_16x16x32_bf16 v[8:11], v[120:123], v[172:175], v[8:11]
	v_mfma_f32_16x16x32_bf16 v[12:15], v[164:167], v[172:175], v[12:15]
	v_mfma_f32_16x16x32_bf16 v[24:27], v[120:123], v[180:183], v[60:63]
	v_mfma_f32_16x16x32_bf16 v[28:31], v[164:167], v[180:183], v[100:103]
	v_mfma_f32_16x16x32_bf16 v[60:63], v[120:123], v[188:191], v[104:107]
	v_mfma_f32_16x16x32_bf16 v[100:103], v[164:167], v[188:191], v[108:111]
	v_mfma_f32_16x16x32_bf16 v[16:19], v[120:123], v[196:199], v[16:19]
	v_mfma_f32_16x16x32_bf16 v[20:23], v[164:167], v[196:199], v[20:23]
	v_mfma_f32_16x16x32_bf16 v[8:11], v[124:127], v[176:179], v[8:11]
	v_mfma_f32_16x16x32_bf16 v[12:15], v[168:171], v[176:179], v[12:15]
	v_mfma_f32_16x16x32_bf16 v[24:27], v[124:127], v[184:187], v[24:27]
	v_mfma_f32_16x16x32_bf16 v[28:31], v[168:171], v[184:187], v[28:31]
	s_barrier
	v_mfma_f32_16x16x32_bf16 v[60:63], v[124:127], v[192:195], v[60:63]
	v_mfma_f32_16x16x32_bf16 v[100:103], v[168:171], v[192:195], v[100:103]
	v_mfma_f32_16x16x32_bf16 v[16:19], v[124:127], v[200:203], v[16:19]
	v_mfma_f32_16x16x32_bf16 v[20:23], v[168:171], v[200:203], v[20:23]
	s_setprio 0
	ds_read_b128 v[104:107], v134
	ds_read_b128 v[108:111], v134 offset:1024
	ds_read_b128 v[112:115], v134 offset:2048
	ds_read_b128 v[116:119], v134 offset:3072
	ds_read_b128 v[120:123], v135
	ds_read_b128 v[124:127], v135 offset:1024
	ds_read_b128 v[164:167], v135 offset:2048
	ds_read_b128 v[168:171], v135 offset:3072
	s_add_u32 s36, s36, 0x10180
	s_addc_u32 s37, s37, 0
	s_mov_b32 m0, s15
	v_lshl_add_u64 v[204:205], s[36:37], 0, v[130:131]
	ds_read_b128 v[172:175], v136
	ds_read_b128 v[176:179], v136 offset:1024
	ds_read_b128 v[180:183], v136 offset:2048
	ds_read_b128 v[184:187], v136 offset:3072
	ds_read_b128 v[188:191], v136 offset:4096
	ds_read_b128 v[192:195], v136 offset:5120
	ds_read_b128 v[196:199], v136 offset:6144
	ds_read_b128 v[200:203], v136 offset:7168
	global_load_lds_dwordx4 v[204:205], off
	v_lshl_add_u64 v[204:205], s[36:37], 0, v[128:129]
	s_mov_b32 m0, s50
	s_nop 0
	global_load_lds_dwordx4 v[204:205], off
	s_waitcnt vmcnt(8)
	s_waitcnt lgkmcnt(0)
	s_barrier
; #define PG8_STAGE(bufoff, gbase, voff) do { _Pragma("unroll") for (int _i = 0; _i < 2; ++_i) \
;         __builtin_amdgcn_global_load_lds((const unsigned*)((const char*)(gbase) + (voff)[_i]), (PG8_LAS unsigned*)(lds + (bufoff) + ldsw + _i * 8192), 16, 0, 0); } while (0)
; #define PG8_LDA(dst, b, h) do { _Pragma("unroll") for (int m = 0; m < 4; ++m) _Pragma("unroll") for (int k = 0; k < 2; ++k) dst[m][k] = *(const PG8_LAS bf16x8*)(lds + PG8_SA(b, h) + aoff + m * 2048 + k * 1024); } while (0)
; #define PG8_LDB(dst, b, h) do { _Pragma("unroll") for (int n = 0; n < 2; ++n) _Pragma("unroll") for (int k = 0; k < 2; ++k) dst[n][k] = *(const PG8_LAS bf16x8*)(lds + PG8_SB(b, h) + boff + n * 2048 + k * 1024); } while (0)
; #define PG8_MMA(ai, bj, At, Bt) do { __builtin_amdgcn_s_setprio(1); _Pragma("unroll") for (int m = 0; m < 4; ++m) _Pragma("unroll") for (int n = 0; n < 2; ++n) _Pragma("unroll") for (int k = 0; k < 2; ++k) \
;         acc[ai][bj][m][n] = mma16<F16>(Bt[n][k], At[m][k], acc[ai][bj][m][n]); __builtin_amdgcn_s_setprio(0); } while (0)
; #define PG8_WAIT_V(n) asm volatile("s_waitcnt vmcnt(" #n ")" ::: "memory")
; #define PG8_WAIT_L(n) asm volatile("s_waitcnt lgkmcnt(" #n ")" ::: "memory")
; #define PG8_BAR __builtin_amdgcn_s_barrier()
; #define PG8_SCHED __builtin_amdgcn_sched_barrier(0)
; template <class Epi, class Sched, bool ALIGN_EPI = false, bool SP2 = false, bool F16 = false>
; __device__ __forceinline__ void gemm_phase(PG8_LAS unsigned char* lds, const Gemm g, const Sched& S, const Epi& E, const int wid_in) {
;     ...
;             PG8_LDB(B0, 0, 0); PG8_LDB(B1, 0, 1); PG8_SCHED; PG8_LDA(At, 0, 0); PG8_STAGE(PG8_SA(1, 1), a1 + hstep, voffA);
;             PG8_WAIT_V(8); PG8_WAIT_L(0); PG8_BAR; PG8_MMA(0, 0, At, B0); PG8_MMA(0, 1, At, B1); PG8_BAR; PG8_SCHED;
;             PG8_LDA(At, 0, 1); PG8_STAGE(PG8_SB(0, 0), b2, voffB); PG8_STAGE(PG8_SB(0, 1), b2 + hstep, voffB); PG8_STAGE(PG8_SA(0, 0), a2, voffA);
;             PG8_WAIT_V(8); PG8_WAIT_L(0); PG8_BAR; PG8_MMA(1, 0, At, B0); PG8_MMA(1, 1, At, B1); PG8_BAR; PG8_SCHED;
	s_setprio 1
	s_waitcnt lgkmcnt(0)
	v_mfma_f32_16x16x32_bf16 v[64:67], v[104:107], v[172:175], v[64:67]
	v_mfma_f32_16x16x32_bf16 v[68:71], v[112:115], v[172:175], v[68:71]
	v_mfma_f32_16x16x32_bf16 v[72:75], v[104:107], v[180:183], v[72:75]
	v_mfma_f32_16x16x32_bf16 v[76:79], v[112:115], v[180:183], v[76:79]
	v_mfma_f32_16x16x32_bf16 v[80:83], v[104:107], v[188:191], v[80:83]
	v_mfma_f32_16x16x32_bf16 v[84:87], v[112:115], v[188:191], v[84:87]
	v_mfma_f32_16x16x32_bf16 v[88:91], v[104:107], v[196:199], v[88:91]
	v_mfma_f32_16x16x32_bf16 v[92:95], v[112:115], v[196:199], v[92:95]
	v_mfma_f32_16x16x32_bf16 v[64:67], v[108:111], v[176:179], v[64:67]
	v_mfma_f32_16x16x32_bf16 v[68:71], v[116:119], v[176:179], v[68:71]
	v_mfma_f32_16x16x32_bf16 v[72:75], v[108:111], v[184:187], v[72:75]
	v_mfma_f32_16x16x32_bf16 v[76:79], v[116:119], v[184:187], v[76:79]
	v_mfma_f32_16x16x32_bf16 v[80:83], v[108:111], v[192:195], v[80:83]
	v_mfma_f32_16x16x32_bf16 v[84:87], v[116:119], v[192:195], v[84:87]
	v_mfma_f32_16x16x32_bf16 v[88:91], v[108:111], v[200:203], v[88:91]
	v_mfma_f32_16x16x32_bf16 v[92:95], v[116:119], v[200:203], v[92:95]
	s_setprio 0
	s_setprio 1
	v_mfma_f32_16x16x32_bf16 v[32:35], v[164:167], v[172:175], v[32:35]
	v_mfma_f32_16x16x32_bf16 v[96:99], v[120:123], v[172:175], v[96:99]
	v_mfma_f32_16x16x32_bf16 v[172:175], v[168:171], v[176:179], v[32:35]
	v_mfma_f32_16x16x32_bf16 v[32:35], v[120:123], v[180:183], v[36:39]
	v_mfma_f32_16x16x32_bf16 v[204:207], v[124:127], v[176:179], v[96:99]
	v_mfma_f32_16x16x32_bf16 v[176:179], v[124:127], v[184:187], v[32:35]
	v_mfma_f32_16x16x32_bf16 v[32:35], v[164:167], v[180:183], v[40:43]
	v_mfma_f32_16x16x32_bf16 v[40:43], v[168:171], v[184:187], v[32:35]
	v_mfma_f32_16x16x32_bf16 v[32:35], v[120:123], v[188:191], v[44:47]
	v_mfma_f32_16x16x32_bf16 v[44:47], v[124:127], v[192:195], v[32:35]
	v_mfma_f32_16x16x32_bf16 v[32:35], v[164:167], v[188:191], v[48:51]
	v_mfma_f32_16x16x32_bf16 v[48:51], v[168:171], v[192:195], v[32:35]
	s_barrier
	v_mfma_f32_16x16x32_bf16 v[32:35], v[120:123], v[196:199], v[52:55]
	v_mfma_f32_16x16x32_bf16 v[52:55], v[124:127], v[200:203], v[32:35]
	v_mfma_f32_16x16x32_bf16 v[32:35], v[164:167], v[196:199], v[56:59]
	v_mfma_f32_16x16x32_bf16 v[56:59], v[168:171], v[200:203], v[32:35]
	s_setprio 0
	s_mov_b32 m0, s51
	v_lshl_add_u64 v[240:241], s[30:31], 0, v[130:131]
	s_add_u32 s36, s30, 0x10000
	s_nop 1
	ds_read_b128 v[32:35], v136 offset:16384
	ds_read_b128 v[36:39], v136 offset:17408
	ds_read_b128 v[96:99], v136 offset:18432
	ds_read_b128 v[180:183], v136 offset:19456
	ds_read_b128 v[184:187], v136 offset:20480
	ds_read_b128 v[188:191], v136 offset:21504
	ds_read_b128 v[192:195], v136 offset:22528
	ds_read_b128 v[196:199], v136 offset:23552
	global_load_lds_dwordx4 v[240:241], off
	v_lshl_add_u64 v[242:243], s[30:31], 0, v[128:129]
	s_mov_b32 m0, s52
	s_addc_u32 s37, s31, 0
	global_load_lds_dwordx4 v[242:243], off
	v_lshl_add_u64 v[200:201], s[36:37], 0, v[130:131]
	s_mov_b32 m0, s53
	v_lshl_add_u64 v[244:245], s[34:35], 0, v[130:131]
	global_load_lds_dwordx4 v[200:201], off
	v_lshl_add_u64 v[200:201], s[36:37], 0, v[128:129]
	s_mov_b32 m0, s54
	v_lshl_add_u64 v[246:247], s[34:35], 0, v[128:129]
	global_load_lds_dwordx4 v[200:201], off
	s_mov_b32 m0, s74
	s_nop 0
	global_load_lds_dwordx4 v[244:245], off
	s_mov_b32 m0, s47
	s_nop 0
	global_load_lds_dwordx4 v[246:247], off
	s_waitcnt vmcnt(8)
	s_waitcnt lgkmcnt(0)
	s_barrier
	s_setprio 1
	s_waitcnt lgkmcnt(0)
	v_mfma_f32_16x16x32_bf16 v[0:3], v[104:107], v[192:195], v[0:3]
	v_mfma_f32_16x16x32_bf16 v[140:143], v[104:107], v[32:35], v[140:143]
	v_mfma_f32_16x16x32_bf16 v[144:147], v[112:115], v[32:35], v[144:147]
	v_mfma_f32_16x16x32_bf16 v[148:151], v[104:107], v[96:99], v[148:151]
	v_mfma_f32_16x16x32_bf16 v[152:155], v[112:115], v[96:99], v[152:155]
	v_mfma_f32_16x16x32_bf16 v[156:159], v[104:107], v[184:187], v[156:159]
	v_mfma_f32_16x16x32_bf16 v[160:163], v[112:115], v[184:187], v[160:163]
	v_mfma_f32_16x16x32_bf16 v[0:3], v[108:111], v[196:199], v[0:3]
	v_mfma_f32_16x16x32_bf16 v[4:7], v[112:115], v[192:195], v[4:7]
	v_mfma_f32_16x16x32_bf16 v[140:143], v[108:111], v[36:39], v[140:143]
	v_mfma_f32_16x16x32_bf16 v[144:147], v[116:119], v[36:39], v[144:147]
	v_mfma_f32_16x16x32_bf16 v[148:151], v[108:111], v[180:183], v[148:151]
	v_mfma_f32_16x16x32_bf16 v[152:155], v[116:119], v[180:183], v[152:155]
	v_mfma_f32_16x16x32_bf16 v[156:159], v[108:111], v[188:191], v[156:159]
	v_mfma_f32_16x16x32_bf16 v[160:163], v[116:119], v[188:191], v[160:163]
	v_mfma_f32_16x16x32_bf16 v[200:203], v[116:119], v[196:199], v[4:7]
	s_setprio 0
	s_setprio 1
	v_mfma_f32_16x16x32_bf16 v[4:7], v[120:123], v[32:35], v[8:11]
	v_mfma_f32_16x16x32_bf16 v[8:11], v[124:127], v[36:39], v[4:7]
	v_mfma_f32_16x16x32_bf16 v[4:7], v[164:167], v[32:35], v[12:15]
	v_mfma_f32_16x16x32_bf16 v[12:15], v[168:171], v[36:39], v[4:7]
	v_mfma_f32_16x16x32_bf16 v[4:7], v[120:123], v[96:99], v[24:27]
	v_mfma_f32_16x16x32_bf16 v[24:27], v[124:127], v[180:183], v[4:7]
	v_mfma_f32_16x16x32_bf16 v[4:7], v[164:167], v[96:99], v[28:31]
	v_mfma_f32_16x16x32_bf16 v[28:31], v[168:171], v[180:183], v[4:7]
	v_mfma_f32_16x16x32_bf16 v[4:7], v[120:123], v[184:187], v[60:63]
	v_mfma_f32_16x16x32_bf16 v[180:183], v[124:127], v[188:191], v[4:7]
	v_mfma_f32_16x16x32_bf16 v[4:7], v[164:167], v[184:187], v[100:103]
	v_mfma_f32_16x16x32_bf16 v[184:187], v[168:171], v[188:191], v[4:7]
	s_barrier
; #define PG8_STAGE(bufoff, gbase, voff) do { _Pragma("unroll") for (int _i = 0; _i < 2; ++_i) \
;         __builtin_amdgcn_global_load_lds((const unsigned*)((const char*)(gbase) + (voff)[_i]), (PG8_LAS unsigned*)(lds + (bufoff) + ldsw + _i * 8192), 16, 0, 0); } while (0)
; #define PG8_LDA(dst, b, h) do { _Pragma("unroll") for (int m = 0; m < 4; ++m) _Pragma("unroll") for (int k = 0; k < 2; ++k) dst[m][k] = *(const PG8_LAS bf16x8*)(lds + PG8_SA(b, h) + aoff + m * 2048 + k * 1024); } while (0)
; #define PG8_LDB(dst, b, h) do { _Pragma("unroll") for (int n = 0; n < 2; ++n) _Pragma("unroll") for (int k = 0; k < 2; ++k) dst[n][k] = *(const PG8_LAS bf16x8*)(lds + PG8_SB(b, h) + boff + n * 2048 + k * 1024); } while (0)
; #define PG8_MMA(ai, bj, At, Bt) do { __builtin_amdgcn_s_setprio(1); _Pragma("unroll") for (int m = 0; m < 4; ++m) _Pragma("unroll") for (int n = 0; n < 2; ++n) _Pragma("unroll") for (int k = 0; k < 2; ++k) \
;         acc[ai][bj][m][n] = mma16<F16>(Bt[n][k], At[m][k], acc[ai][bj][m][n]); __builtin_amdgcn_s_setprio(0); } while (0)
; #define PG8_WAIT_V(n) asm volatile("s_waitcnt vmcnt(" #n ")" ::: "memory")
; #define PG8_WAIT_L(n) asm volatile("s_waitcnt lgkmcnt(" #n ")" ::: "memory")
; #define PG8_BAR __builtin_amdgcn_s_barrier()
; #define PG8_SCHED __builtin_amdgcn_sched_barrier(0)
; template <class Epi, class Sched, bool ALIGN_EPI = false, bool SP2 = false, bool F16 = false>
; __device__ __forceinline__ void gemm_phase(PG8_LAS unsigned char* lds, const Gemm g, const Sched& S, const Epi& E, const int wid_in) {
;     ...
;             PG8_LDB(B0, 1, 0); PG8_LDB(B1, 1, 1); PG8_SCHED; PG8_LDA(At, 1, 0); PG8_STAGE(PG8_SA(0, 1), a2 + hstep, voffA);
;             PG8_WAIT_V(8); PG8_WAIT_L(0); PG8_BAR; PG8_MMA(0, 0, At, B0); PG8_MMA(0, 1, At, B1); PG8_BAR; PG8_SCHED;
;             PG8_LDA(At, 1, 1); PG8_STAGE(PG8_SB(1, 0), b3, voffB); PG8_STAGE(PG8_SB(1, 1), b3 + hstep, voffB); PG8_STAGE(PG8_SA(1, 0), a3, voffA);
;             PG8_WAIT_V(8); PG8_WAIT_L(0); PG8_BAR; PG8_MMA(1, 0, At, B0); PG8_MMA(1, 1, At, B1); PG8_BAR; PG8_SCHED;
;     ...
;         if constexpr (ALIGN_EPI) { if (wr == 0) PG8_BAR; }
	v_mfma_f32_16x16x32_bf16 v[4:7], v[120:123], v[192:195], v[16:19]
	v_mfma_f32_16x16x32_bf16 v[188:191], v[124:127], v[196:199], v[4:7]
	v_mfma_f32_16x16x32_bf16 v[4:7], v[164:167], v[192:195], v[20:23]
	v_mfma_f32_16x16x32_bf16 v[164:167], v[168:171], v[196:199], v[4:7]
	s_setprio 0
	s_nop 4
	ds_read_b128 v[4:7], v137
	ds_read_b128 v[60:63], v137 offset:1024
	ds_read_b128 v[168:171], v137 offset:2048
	ds_read_b128 v[192:195], v137 offset:3072
	ds_read_b128 v[196:199], v138
	ds_read_b128 v[208:211], v138 offset:1024
	ds_read_b128 v[212:215], v138 offset:2048
	ds_read_b128 v[216:219], v138 offset:3072
	s_add_u32 s34, s34, 0x10000
	s_addc_u32 s35, s35, 0
	s_mov_b32 m0, s48
	v_lshl_add_u64 v[32:33], s[34:35], 0, v[130:131]
	ds_read_b128 v[16:19], v136 offset:32768
	ds_read_b128 v[20:23], v136 offset:33792
	ds_read_b128 v[104:107], v136 offset:34816
	ds_read_b128 v[220:223], v136 offset:35840
	ds_read_b128 v[224:227], v136 offset:36864
	ds_read_b128 v[228:231], v136 offset:37888
	ds_read_b128 v[232:235], v136 offset:38912
	ds_read_b128 v[236:239], v136 offset:39936
	global_load_lds_dwordx4 v[32:33], off
	v_lshl_add_u64 v[32:33], s[34:35], 0, v[128:129]
	s_mov_b32 m0, s49
	s_nop 0
	global_load_lds_dwordx4 v[32:33], off
	s_waitcnt vmcnt(8)
	s_waitcnt lgkmcnt(0)
	s_barrier
	s_setprio 1
	s_waitcnt lgkmcnt(0)
	v_mfma_f32_16x16x32_bf16 v[32:35], v[4:7], v[16:19], v[64:67]
	v_mfma_f32_16x16x32_bf16 v[116:119], v[60:63], v[20:23], v[32:35]
	v_mfma_f32_16x16x32_bf16 v[32:35], v[168:171], v[16:19], v[68:71]
	v_mfma_f32_16x16x32_bf16 v[112:115], v[192:195], v[20:23], v[32:35]
	v_mfma_f32_16x16x32_bf16 v[32:35], v[4:7], v[104:107], v[72:75]
	v_mfma_f32_16x16x32_bf16 v[100:103], v[60:63], v[220:223], v[32:35]
	v_mfma_f32_16x16x32_bf16 v[32:35], v[168:171], v[104:107], v[76:79]
	v_mfma_f32_16x16x32_bf16 v[96:99], v[192:195], v[220:223], v[32:35]
	v_mfma_f32_16x16x32_bf16 v[32:35], v[4:7], v[224:227], v[80:83]
	v_mfma_f32_16x16x32_bf16 v[68:71], v[60:63], v[228:231], v[32:35]
	v_mfma_f32_16x16x32_bf16 v[32:35], v[168:171], v[224:227], v[84:87]
	v_mfma_f32_16x16x32_bf16 v[64:67], v[192:195], v[228:231], v[32:35]
	v_mfma_f32_16x16x32_bf16 v[32:35], v[4:7], v[232:235], v[88:91]
	v_mfma_f32_16x16x32_bf16 v[36:39], v[60:63], v[236:239], v[32:35]
	v_mfma_f32_16x16x32_bf16 v[32:35], v[168:171], v[232:235], v[92:95]
	v_mfma_f32_16x16x32_bf16 v[32:35], v[192:195], v[236:239], v[32:35]
	s_setprio 0
	s_setprio 1
	v_mfma_f32_16x16x32_bf16 v[72:75], v[196:199], v[16:19], v[204:207]
	v_mfma_f32_16x16x32_bf16 v[16:19], v[212:215], v[16:19], v[172:175]
	v_mfma_f32_16x16x32_bf16 v[120:123], v[216:219], v[20:23], v[16:19]
	v_mfma_f32_16x16x32_bf16 v[16:19], v[196:199], v[104:107], v[176:179]
	v_mfma_f32_16x16x32_bf16 v[108:111], v[208:211], v[220:223], v[16:19]
	v_mfma_f32_16x16x32_bf16 v[16:19], v[212:215], v[104:107], v[40:43]
	v_mfma_f32_16x16x32_bf16 v[104:107], v[216:219], v[220:223], v[16:19]
	v_mfma_f32_16x16x32_bf16 v[16:19], v[196:199], v[224:227], v[44:47]
	v_mfma_f32_16x16x32_bf16 v[80:83], v[208:211], v[228:231], v[16:19]
	v_mfma_f32_16x16x32_bf16 v[16:19], v[212:215], v[224:227], v[48:51]
	v_mfma_f32_16x16x32_bf16 v[124:127], v[208:211], v[20:23], v[72:75]
	v_mfma_f32_16x16x32_bf16 v[72:75], v[216:219], v[228:231], v[16:19]
	s_barrier
	v_mfma_f32_16x16x32_bf16 v[16:19], v[196:199], v[232:235], v[52:55]
	v_mfma_f32_16x16x32_bf16 v[48:51], v[208:211], v[236:239], v[16:19]
	v_mfma_f32_16x16x32_bf16 v[16:19], v[212:215], v[232:235], v[56:59]
	v_mfma_f32_16x16x32_bf16 v[40:43], v[216:219], v[236:239], v[16:19]
	s_setprio 0
	s_mov_b32 m0, s55
	s_nop 3
	v_lshl_add_u64 v[16:17], v[240:241], 0, s[20:21]
	s_add_u32 s30, s30, 0x10080
	ds_read_b128 v[56:59], v136 offset:49152
	ds_read_b128 v[88:91], v136 offset:50176
	ds_read_b128 v[172:175], v136 offset:51200
	ds_read_b128 v[176:179], v136 offset:52224
	ds_read_b128 v[204:207], v136 offset:53248
	ds_read_b128 v[220:223], v136 offset:54272
	ds_read_b128 v[224:227], v136 offset:55296
	ds_read_b128 v[228:231], v136 offset:56320
	global_load_lds_dwordx4 v[16:17], off
	v_lshl_add_u64 v[16:17], v[242:243], 0, s[20:21]
	s_mov_b32 m0, s58
	s_addc_u32 s31, s31, 0
	global_load_lds_dwordx4 v[16:17], off
	v_lshl_add_u64 v[16:17], s[30:31], 0, v[130:131]
	s_mov_b32 m0, s59
	s_nop 0
	global_load_lds_dwordx4 v[16:17], off
	v_lshl_add_u64 v[16:17], s[30:31], 0, v[128:129]
	s_mov_b32 m0, s60
	s_nop 0
	global_load_lds_dwordx4 v[16:17], off
	v_lshl_add_u64 v[16:17], v[244:245], 0, s[20:21]
	s_mov_b32 m0, s75
	s_nop 0
	global_load_lds_dwordx4 v[16:17], off
	v_lshl_add_u64 v[16:17], v[246:247], 0, s[20:21]
	s_mov_b32 m0, s14
	s_nop 0
	global_load_lds_dwordx4 v[16:17], off
	s_waitcnt vmcnt(8)
	s_waitcnt lgkmcnt(0)
	s_barrier
	s_setprio 1
	s_waitcnt lgkmcnt(0)
	v_mfma_f32_16x16x32_bf16 v[16:19], v[4:7], v[56:59], v[140:143]
	v_mfma_f32_16x16x32_bf16 v[84:87], v[60:63], v[88:91], v[16:19]
	v_mfma_f32_16x16x32_bf16 v[16:19], v[168:171], v[56:59], v[144:147]
	v_mfma_f32_16x16x32_bf16 v[76:79], v[192:195], v[88:91], v[16:19]
	v_mfma_f32_16x16x32_bf16 v[16:19], v[4:7], v[172:175], v[148:151]
	v_mfma_f32_16x16x32_bf16 v[52:55], v[60:63], v[176:179], v[16:19]
	v_mfma_f32_16x16x32_bf16 v[16:19], v[168:171], v[172:175], v[152:155]
	v_mfma_f32_16x16x32_bf16 v[44:47], v[192:195], v[176:179], v[16:19]
	v_mfma_f32_16x16x32_bf16 v[16:19], v[4:7], v[204:207], v[156:159]
	v_mfma_f32_16x16x32_bf16 v[0:3], v[4:7], v[224:227], v[0:3]
	v_mfma_f32_16x16x32_bf16 v[20:23], v[60:63], v[220:223], v[16:19]
	v_mfma_f32_16x16x32_bf16 v[16:19], v[168:171], v[204:207], v[160:163]
	v_mfma_f32_16x16x32_bf16 v[4:7], v[60:63], v[228:231], v[0:3]
	v_mfma_f32_16x16x32_bf16 v[0:3], v[168:171], v[224:227], v[200:203]
	v_mfma_f32_16x16x32_bf16 v[16:19], v[192:195], v[220:223], v[16:19]
	v_mfma_f32_16x16x32_bf16 v[0:3], v[192:195], v[228:231], v[0:3]
	s_setprio 0
	s_setprio 1
	v_mfma_f32_16x16x32_bf16 v[8:11], v[196:199], v[56:59], v[8:11]
	v_mfma_f32_16x16x32_bf16 v[92:95], v[208:211], v[88:91], v[8:11]
	v_mfma_f32_16x16x32_bf16 v[8:11], v[212:215], v[56:59], v[12:15]
	v_mfma_f32_16x16x32_bf16 v[88:91], v[216:219], v[88:91], v[8:11]
	v_mfma_f32_16x16x32_bf16 v[8:11], v[196:199], v[172:175], v[24:27]
	v_mfma_f32_16x16x32_bf16 v[60:63], v[208:211], v[176:179], v[8:11]
	v_mfma_f32_16x16x32_bf16 v[8:11], v[212:215], v[172:175], v[28:31]
	v_mfma_f32_16x16x32_bf16 v[56:59], v[216:219], v[176:179], v[8:11]
	v_mfma_f32_16x16x32_bf16 v[8:11], v[196:199], v[204:207], v[180:183]
	v_mfma_f32_16x16x32_bf16 v[28:31], v[208:211], v[220:223], v[8:11]
	v_mfma_f32_16x16x32_bf16 v[8:11], v[212:215], v[204:207], v[184:187]
	v_mfma_f32_16x16x32_bf16 v[24:27], v[216:219], v[220:223], v[8:11]
	s_barrier
	v_mfma_f32_16x16x32_bf16 v[8:11], v[196:199], v[224:227], v[188:191]
	v_mfma_f32_16x16x32_bf16 v[12:15], v[208:211], v[228:231], v[8:11]
	v_mfma_f32_16x16x32_bf16 v[8:11], v[212:215], v[224:227], v[164:167]
	v_mfma_f32_16x16x32_bf16 v[8:11], v[216:219], v[228:231], v[8:11]
	s_setprio 0
	s_and_b64 vcc, exec, s[8:9]
	s_cbranch_vccnz .LBB0_622
	s_barrier

; #define PG8_STAGE(bufoff, gbase, voff) do { _Pragma("unroll") for (int _i = 0; _i < 2; ++_i) \
;         __builtin_amdgcn_global_load_lds((const unsigned*)((const char*)(gbase) + (voff)[_i]), (PG8_LAS unsigned*)(lds + (bufoff) + ldsw + _i * 8192), 16, 0, 0); } while (0)
; #define PG8_LDA(dst, b, h) do { _Pragma("unroll") for (int m = 0; m < 4; ++m) _Pragma("unroll") for (int k = 0; k < 2; ++k) dst[m][k] = *(const PG8_LAS bf16x8*)(lds + PG8_SA(b, h) + aoff + m * 2048 + k * 1024); } while (0)
; #define PG8_LDB(dst, b, h) do { _Pragma("unroll") for (int n = 0; n < 2; ++n) _Pragma("unroll") for (int k = 0; k < 2; ++k) dst[n][k] = *(const PG8_LAS bf16x8*)(lds + PG8_SB(b, h) + boff + n * 2048 + k * 1024); } while (0)
; #define PG8_MMA(ai, bj, At, Bt) do { __builtin_amdgcn_s_setprio(1); _Pragma("unroll") for (int m = 0; m < 4; ++m) _Pragma("unroll") for (int n = 0; n < 2; ++n) _Pragma("unroll") for (int k = 0; k < 2; ++k) \
;         acc[ai][bj][m][n] = mma16<F16>(Bt[n][k], At[m][k], acc[ai][bj][m][n]); __builtin_amdgcn_s_setprio(0); } while (0)
; #define PG8_WAIT_V(n) asm volatile("s_waitcnt vmcnt(" #n ")" ::: "memory")
; #define PG8_WAIT_L(n) asm volatile("s_waitcnt lgkmcnt(" #n ")" ::: "memory")
; template <class Epi, class Sched, bool ALIGN_EPI = false, bool SP2 = false, bool F16 = false>
; __device__ __forceinline__ void gemm_phase(PG8_LAS unsigned char* lds, const Gemm g, const Sched& S, const Epi& E, const int wid_in) {
;     ...
;             const bool last = (t == nt - 2);
;             const char* a1 = cA + (size_t)(t + 1) * kstep;
;             const char* a2 = last ? nA : cA + (size_t)(t + 2) * kstep; const char* b2 = last ? nB : cB + (size_t)(t + 2) * kstep;
;             const char* a3 = a2 + kstep; const char* b3 = b2 + kstep;
;             if (last && has_next) S.a_ready(nxt);
;             if constexpr (SP2) {
;             PG8_LDB(B0, 0, 0); PG8_LDB(B1, 0, 1); PG8_SCHED; PG8_LDA(At, 0, 0); PG8_STAGE(PG8_SA(1, 1), a1 + hstep, voffA);
;             PG8_WAIT_V(8); PG8_WAIT_L(0); PG8_BAR; PG8_MMA(0, 0, At, B0); PG8_MMA(0, 1, At, B1); PG8_BAR; PG8_SCHED;
;             PG8_LDA(At, 0, 1); PG8_STAGE(PG8_SB(0, 0), b2, voffB); PG8_STAGE(PG8_SB(0, 1), b2 + hstep, voffB); PG8_STAGE(PG8_SA(0, 0), a2, voffA);
;             PG8_WAIT_V(8); PG8_WAIT_L(0); PG8_BAR; PG8_MMA(1, 0, At, B0); PG8_MMA(1, 1, At, B1); PG8_BAR; PG8_SCHED;
.LBB0_716:
	ds_read_b128 v[128:131], v189
	ds_read_b128 v[132:135], v189 offset:1024
	ds_read_b128 v[136:139], v189 offset:2048
	ds_read_b128 v[140:143], v189 offset:3072
	ds_read_b128 v[144:147], v190
	ds_read_b128 v[148:151], v190 offset:1024
	ds_read_b128 v[168:171], v190 offset:2048
	ds_read_b128 v[172:175], v190 offset:3072
	s_add_u32 s30, s28, 0x100
	s_addc_u32 s31, s29, 0
	s_cmp_eq_u32 s60, 40
	s_cselect_b32 s37, s11, s31
	s_cselect_b32 s36, s10, s30
	s_cselect_b32 s35, s27, s59
	s_cselect_b32 s34, s26, s43
	v_lshl_add_u64 v[184:185], s[28:29], 0, v[160:161]
	s_add_i32 m0, s74, 0xc000
	ds_read_b128 v[176:179], v191
	ds_read_b128 v[180:183], v191 offset:1024
	ds_read_b128 v[192:195], v191 offset:2048
	ds_read_b128 v[196:199], v191 offset:3072
	ds_read_b128 v[200:203], v191 offset:4096
	ds_read_b128 v[204:207], v191 offset:5120
	ds_read_b128 v[208:211], v191 offset:6144
	ds_read_b128 v[212:215], v191 offset:7168
	global_load_lds_dwordx4 v[184:185], off
	v_lshl_add_u64 v[184:185], s[28:29], 0, v[162:163]
	s_add_i32 m0, s74, 0xe000
	s_nop 0
	global_load_lds_dwordx4 v[184:185], off
	s_waitcnt vmcnt(8)
	s_waitcnt lgkmcnt(0)
	s_barrier
	s_setprio 1
	s_waitcnt lgkmcnt(0)
	v_mfma_f32_16x16x32_bf16 v[124:127], v[128:131], v[176:179], v[124:127]
	v_mfma_f32_16x16x32_bf16 v[120:123], v[136:139], v[176:179], v[120:123]
	v_mfma_f32_16x16x32_bf16 v[108:111], v[128:131], v[192:195], v[108:111]
	v_mfma_f32_16x16x32_bf16 v[104:107], v[136:139], v[192:195], v[104:107]
	v_mfma_f32_16x16x32_bf16 v[92:95], v[128:131], v[200:203], v[92:95]
	v_mfma_f32_16x16x32_bf16 v[88:91], v[136:139], v[200:203], v[88:91]
	v_mfma_f32_16x16x32_bf16 v[76:79], v[128:131], v[208:211], v[76:79]
	v_mfma_f32_16x16x32_bf16 v[72:75], v[136:139], v[208:211], v[72:75]
	v_mfma_f32_16x16x32_bf16 v[124:127], v[132:135], v[180:183], v[124:127]
	v_mfma_f32_16x16x32_bf16 v[120:123], v[140:143], v[180:183], v[120:123]
	v_mfma_f32_16x16x32_bf16 v[108:111], v[132:135], v[196:199], v[108:111]
	v_mfma_f32_16x16x32_bf16 v[104:107], v[140:143], v[196:199], v[104:107]
	v_mfma_f32_16x16x32_bf16 v[92:95], v[132:135], v[204:207], v[92:95]
	v_mfma_f32_16x16x32_bf16 v[88:91], v[140:143], v[204:207], v[88:91]
	v_mfma_f32_16x16x32_bf16 v[76:79], v[132:135], v[212:215], v[76:79]
	v_mfma_f32_16x16x32_bf16 v[72:75], v[140:143], v[212:215], v[72:75]
	s_setprio 0
	s_setprio 1
	v_mfma_f32_16x16x32_bf16 v[116:119], v[144:147], v[176:179], v[116:119]
	v_mfma_f32_16x16x32_bf16 v[112:115], v[168:171], v[176:179], v[112:115]
	v_mfma_f32_16x16x32_bf16 v[100:103], v[144:147], v[192:195], v[100:103]
	v_mfma_f32_16x16x32_bf16 v[96:99], v[168:171], v[192:195], v[96:99]
	v_mfma_f32_16x16x32_bf16 v[84:87], v[144:147], v[200:203], v[84:87]
	v_mfma_f32_16x16x32_bf16 v[80:83], v[168:171], v[200:203], v[80:83]
	v_mfma_f32_16x16x32_bf16 v[68:71], v[144:147], v[208:211], v[68:71]
	v_mfma_f32_16x16x32_bf16 v[64:67], v[168:171], v[208:211], v[64:67]
	v_mfma_f32_16x16x32_bf16 v[116:119], v[148:151], v[180:183], v[116:119]
	v_mfma_f32_16x16x32_bf16 v[112:115], v[172:175], v[180:183], v[112:115]
	v_mfma_f32_16x16x32_bf16 v[100:103], v[148:151], v[196:199], v[100:103]
	v_mfma_f32_16x16x32_bf16 v[96:99], v[172:175], v[196:199], v[96:99]
	s_barrier
	v_mfma_f32_16x16x32_bf16 v[84:87], v[148:151], v[204:207], v[84:87]
	v_mfma_f32_16x16x32_bf16 v[80:83], v[172:175], v[204:207], v[80:83]
	v_mfma_f32_16x16x32_bf16 v[68:71], v[148:151], v[212:215], v[68:71]
	v_mfma_f32_16x16x32_bf16 v[64:67], v[172:175], v[212:215], v[64:67]
	s_setprio 0
	s_add_i32 s28, s52, s68
	v_lshl_add_u64 v[184:185], s[34:35], 0, v[154:155]
	s_mov_b32 m0, s28
	ds_read_b128 v[176:179], v191 offset:16384
	ds_read_b128 v[180:183], v191 offset:17408
	ds_read_b128 v[192:195], v191 offset:18432
	ds_read_b128 v[196:199], v191 offset:19456
	ds_read_b128 v[200:203], v191 offset:20480
	ds_read_b128 v[204:207], v191 offset:21504
	ds_read_b128 v[208:211], v191 offset:22528
	ds_read_b128 v[212:215], v191 offset:23552
	global_load_lds_dwordx4 v[184:185], off
	s_add_i32 m0, s28, 0x2000
	s_add_u32 s28, s34, 0xb0000
	v_lshl_add_u64 v[216:217], s[34:35], 0, v[158:159]
	s_addc_u32 s29, s35, 0
	s_add_i32 s61, s53, s68
	global_load_lds_dwordx4 v[216:217], off
	v_lshl_add_u64 v[218:219], s[28:29], 0, v[154:155]
	s_mov_b32 m0, s61
	v_lshl_add_u64 v[220:221], s[36:37], 0, v[156:157]
	global_load_lds_dwordx4 v[218:219], off
	v_lshl_add_u64 v[218:219], s[28:29], 0, v[158:159]
	s_add_i32 m0, s61, 0x2000
	s_nop 0
	global_load_lds_dwordx4 v[218:219], off
	v_lshl_add_u64 v[218:219], s[36:37], 0, v[152:153]
	s_mov_b32 m0, s74
	s_nop 0
	global_load_lds_dwordx4 v[218:219], off
	s_mov_b32 m0, s45
	s_nop 0
	global_load_lds_dwordx4 v[220:221], off
	s_waitcnt vmcnt(8)
	s_waitcnt lgkmcnt(0)
	s_barrier
; #define PG8_STAGE(bufoff, gbase, voff) do { _Pragma("unroll") for (int _i = 0; _i < 2; ++_i) \
;         __builtin_amdgcn_global_load_lds((const unsigned*)((const char*)(gbase) + (voff)[_i]), (PG8_LAS unsigned*)(lds + (bufoff) + ldsw + _i * 8192), 16, 0, 0); } while (0)
; #define PG8_LDA(dst, b, h) do { _Pragma("unroll") for (int m = 0; m < 4; ++m) _Pragma("unroll") for (int k = 0; k < 2; ++k) dst[m][k] = *(const PG8_LAS bf16x8*)(lds + PG8_SA(b, h) + aoff + m * 2048 + k * 1024); } while (0)
; #define PG8_LDB(dst, b, h) do { _Pragma("unroll") for (int n = 0; n < 2; ++n) _Pragma("unroll") for (int k = 0; k < 2; ++k) dst[n][k] = *(const PG8_LAS bf16x8*)(lds + PG8_SB(b, h) + boff + n * 2048 + k * 1024); } while (0)
; #define PG8_MMA(ai, bj, At, Bt) do { __builtin_amdgcn_s_setprio(1); _Pragma("unroll") for (int m = 0; m < 4; ++m) _Pragma("unroll") for (int n = 0; n < 2; ++n) _Pragma("unroll") for (int k = 0; k < 2; ++k) \
;         acc[ai][bj][m][n] = mma16<F16>(Bt[n][k], At[m][k], acc[ai][bj][m][n]); __builtin_amdgcn_s_setprio(0); } while (0)
; #define PG8_WAIT_V(n) asm volatile("s_waitcnt vmcnt(" #n ")" ::: "memory")
; #define PG8_WAIT_L(n) asm volatile("s_waitcnt lgkmcnt(" #n ")" ::: "memory")
; #define PG8_BAR __builtin_amdgcn_s_barrier()
; #define PG8_SCHED __builtin_amdgcn_sched_barrier(0)
; template <class Epi, class Sched, bool ALIGN_EPI = false, bool SP2 = false, bool F16 = false>
; __device__ __forceinline__ void gemm_phase(PG8_LAS unsigned char* lds, const Gemm g, const Sched& S, const Epi& E, const int wid_in) {
;     ...
;             PG8_WAIT_V(8); PG8_WAIT_L(0); PG8_BAR; PG8_MMA(1, 0, At, B0); PG8_MMA(1, 1, At, B1); PG8_BAR; PG8_SCHED;
;             PG8_LDB(B0, 1, 0); PG8_LDB(B1, 1, 1); PG8_SCHED; PG8_LDA(At, 1, 0); PG8_STAGE(PG8_SA(0, 1), a2 + hstep, voffA);
;             PG8_WAIT_V(8); PG8_WAIT_L(0); PG8_BAR; PG8_MMA(0, 0, At, B0); PG8_MMA(0, 1, At, B1); PG8_BAR; PG8_SCHED;
	s_setprio 1
	s_waitcnt lgkmcnt(0)
	v_mfma_f32_16x16x32_bf16 v[60:63], v[128:131], v[176:179], v[60:63]
	v_mfma_f32_16x16x32_bf16 v[56:59], v[136:139], v[176:179], v[56:59]
	v_mfma_f32_16x16x32_bf16 v[44:47], v[128:131], v[192:195], v[44:47]
	v_mfma_f32_16x16x32_bf16 v[40:43], v[136:139], v[192:195], v[40:43]
	v_mfma_f32_16x16x32_bf16 v[28:31], v[128:131], v[200:203], v[28:31]
	v_mfma_f32_16x16x32_bf16 v[24:27], v[136:139], v[200:203], v[24:27]
	v_mfma_f32_16x16x32_bf16 v[12:15], v[128:131], v[208:211], v[12:15]
	v_mfma_f32_16x16x32_bf16 v[8:11], v[136:139], v[208:211], v[8:11]
	v_mfma_f32_16x16x32_bf16 v[60:63], v[132:135], v[180:183], v[60:63]
	v_mfma_f32_16x16x32_bf16 v[56:59], v[140:143], v[180:183], v[56:59]
	v_mfma_f32_16x16x32_bf16 v[44:47], v[132:135], v[196:199], v[44:47]
	v_mfma_f32_16x16x32_bf16 v[40:43], v[140:143], v[196:199], v[40:43]
	v_mfma_f32_16x16x32_bf16 v[28:31], v[132:135], v[204:207], v[28:31]
	v_mfma_f32_16x16x32_bf16 v[24:27], v[140:143], v[204:207], v[24:27]
	v_mfma_f32_16x16x32_bf16 v[12:15], v[132:135], v[212:215], v[12:15]
	v_mfma_f32_16x16x32_bf16 v[8:11], v[140:143], v[212:215], v[8:11]
	s_setprio 0
	s_setprio 1
	v_mfma_f32_16x16x32_bf16 v[52:55], v[144:147], v[176:179], v[52:55]
	v_mfma_f32_16x16x32_bf16 v[48:51], v[168:171], v[176:179], v[48:51]
	v_mfma_f32_16x16x32_bf16 v[36:39], v[144:147], v[192:195], v[36:39]
	v_mfma_f32_16x16x32_bf16 v[32:35], v[168:171], v[192:195], v[32:35]
	v_mfma_f32_16x16x32_bf16 v[20:23], v[144:147], v[200:203], v[20:23]
	v_mfma_f32_16x16x32_bf16 v[16:19], v[168:171], v[200:203], v[16:19]
	v_mfma_f32_16x16x32_bf16 v[4:7], v[144:147], v[208:211], v[4:7]
	v_mfma_f32_16x16x32_bf16 v[0:3], v[168:171], v[208:211], v[0:3]
	v_mfma_f32_16x16x32_bf16 v[52:55], v[148:151], v[180:183], v[52:55]
	v_mfma_f32_16x16x32_bf16 v[48:51], v[172:175], v[180:183], v[48:51]
	v_mfma_f32_16x16x32_bf16 v[36:39], v[148:151], v[196:199], v[36:39]
	v_mfma_f32_16x16x32_bf16 v[32:35], v[172:175], v[196:199], v[32:35]
	s_barrier
	v_mfma_f32_16x16x32_bf16 v[20:23], v[148:151], v[204:207], v[20:23]
	v_mfma_f32_16x16x32_bf16 v[16:19], v[172:175], v[204:207], v[16:19]
	v_mfma_f32_16x16x32_bf16 v[4:7], v[148:151], v[212:215], v[4:7]
	v_mfma_f32_16x16x32_bf16 v[0:3], v[172:175], v[212:215], v[0:3]
	s_setprio 0
	s_add_i32 s61, 0, 0x18000
	s_add_i32 s62, 0, 0x1c000
	v_add_u32_e32 v140, s61, v188
	v_add_u32_e32 v172, s62, v188
	ds_read_b128 v[128:131], v140
	ds_read_b128 v[132:135], v140 offset:1024
	ds_read_b128 v[136:139], v140 offset:2048
	ds_read_b128 v[140:143], v140 offset:3072
	ds_read_b128 v[144:147], v172
	ds_read_b128 v[148:151], v172 offset:1024
	ds_read_b128 v[168:171], v172 offset:2048
	ds_read_b128 v[172:175], v172 offset:3072
	s_add_u32 s28, s36, 0xb0000
	s_addc_u32 s29, s37, 0
	s_mov_b32 m0, s46
	v_lshl_add_u64 v[222:223], s[28:29], 0, v[152:153]
	ds_read_b128 v[176:179], v191 offset:32768
	ds_read_b128 v[180:183], v191 offset:33792
	ds_read_b128 v[192:195], v191 offset:34816
	ds_read_b128 v[196:199], v191 offset:35840
	ds_read_b128 v[200:203], v191 offset:36864
	ds_read_b128 v[204:207], v191 offset:37888
	ds_read_b128 v[208:211], v191 offset:38912
	ds_read_b128 v[212:215], v191 offset:39936
	global_load_lds_dwordx4 v[222:223], off
	v_lshl_add_u64 v[222:223], s[28:29], 0, v[156:157]
	s_mov_b32 m0, s47
	s_nop 0
	global_load_lds_dwordx4 v[222:223], off
	s_waitcnt vmcnt(8)
	s_waitcnt lgkmcnt(0)
	s_barrier
	s_setprio 1
	s_waitcnt lgkmcnt(0)
	v_mfma_f32_16x16x32_bf16 v[124:127], v[128:131], v[176:179], v[124:127]
	v_mfma_f32_16x16x32_bf16 v[120:123], v[136:139], v[176:179], v[120:123]
	v_mfma_f32_16x16x32_bf16 v[108:111], v[128:131], v[192:195], v[108:111]
	v_mfma_f32_16x16x32_bf16 v[104:107], v[136:139], v[192:195], v[104:107]
	v_mfma_f32_16x16x32_bf16 v[92:95], v[128:131], v[200:203], v[92:95]
	v_mfma_f32_16x16x32_bf16 v[88:91], v[136:139], v[200:203], v[88:91]
	v_mfma_f32_16x16x32_bf16 v[76:79], v[128:131], v[208:211], v[76:79]
	v_mfma_f32_16x16x32_bf16 v[72:75], v[136:139], v[208:211], v[72:75]
	v_mfma_f32_16x16x32_bf16 v[124:127], v[132:135], v[180:183], v[124:127]
	v_mfma_f32_16x16x32_bf16 v[120:123], v[140:143], v[180:183], v[120:123]
	v_mfma_f32_16x16x32_bf16 v[108:111], v[132:135], v[196:199], v[108:111]
	v_mfma_f32_16x16x32_bf16 v[104:107], v[140:143], v[196:199], v[104:107]
	v_mfma_f32_16x16x32_bf16 v[92:95], v[132:135], v[204:207], v[92:95]
	v_mfma_f32_16x16x32_bf16 v[88:91], v[140:143], v[204:207], v[88:91]
	v_mfma_f32_16x16x32_bf16 v[76:79], v[132:135], v[212:215], v[76:79]
	v_mfma_f32_16x16x32_bf16 v[72:75], v[140:143], v[212:215], v[72:75]
	s_setprio 0
	s_setprio 1
	v_mfma_f32_16x16x32_bf16 v[116:119], v[144:147], v[176:179], v[116:119]
	v_mfma_f32_16x16x32_bf16 v[112:115], v[168:171], v[176:179], v[112:115]
	v_mfma_f32_16x16x32_bf16 v[100:103], v[144:147], v[192:195], v[100:103]
	v_mfma_f32_16x16x32_bf16 v[96:99], v[168:171], v[192:195], v[96:99]
	v_mfma_f32_16x16x32_bf16 v[84:87], v[144:147], v[200:203], v[84:87]
	v_mfma_f32_16x16x32_bf16 v[80:83], v[168:171], v[200:203], v[80:83]
	v_mfma_f32_16x16x32_bf16 v[68:71], v[144:147], v[208:211], v[68:71]
	v_mfma_f32_16x16x32_bf16 v[64:67], v[168:171], v[208:211], v[64:67]
	v_mfma_f32_16x16x32_bf16 v[116:119], v[148:151], v[180:183], v[116:119]
	v_mfma_f32_16x16x32_bf16 v[112:115], v[172:175], v[180:183], v[112:115]
	v_mfma_f32_16x16x32_bf16 v[100:103], v[148:151], v[196:199], v[100:103]
	v_mfma_f32_16x16x32_bf16 v[96:99], v[172:175], v[196:199], v[96:99]
	s_barrier
; #define PG8_STAGE(bufoff, gbase, voff) do { _Pragma("unroll") for (int _i = 0; _i < 2; ++_i) \
;         __builtin_amdgcn_global_load_lds((const unsigned*)((const char*)(gbase) + (voff)[_i]), (PG8_LAS unsigned*)(lds + (bufoff) + ldsw + _i * 8192), 16, 0, 0); } while (0)
; #define PG8_LDA(dst, b, h) do { _Pragma("unroll") for (int m = 0; m < 4; ++m) _Pragma("unroll") for (int k = 0; k < 2; ++k) dst[m][k] = *(const PG8_LAS bf16x8*)(lds + PG8_SA(b, h) + aoff + m * 2048 + k * 1024); } while (0)
; #define PG8_MMA(ai, bj, At, Bt) do { __builtin_amdgcn_s_setprio(1); _Pragma("unroll") for (int m = 0; m < 4; ++m) _Pragma("unroll") for (int n = 0; n < 2; ++n) _Pragma("unroll") for (int k = 0; k < 2; ++k) \
;         acc[ai][bj][m][n] = mma16<F16>(Bt[n][k], At[m][k], acc[ai][bj][m][n]); __builtin_amdgcn_s_setprio(0); } while (0)
; #define PG8_WAIT_V(n) asm volatile("s_waitcnt vmcnt(" #n ")" ::: "memory")
; #define PG8_WAIT_L(n) asm volatile("s_waitcnt lgkmcnt(" #n ")" ::: "memory")
; #define PG8_BAR __builtin_amdgcn_s_barrier()
; #define PG8_SCHED __builtin_amdgcn_sched_barrier(0)
; template <class Epi, class Sched, bool ALIGN_EPI = false, bool SP2 = false, bool F16 = false>
; __device__ __forceinline__ void gemm_phase(PG8_LAS unsigned char* lds, const Gemm g, const Sched& S, const Epi& E, const int wid_in) {
;     ...
;             PG8_WAIT_V(8); PG8_WAIT_L(0); PG8_BAR; PG8_MMA(0, 0, At, B0); PG8_MMA(0, 1, At, B1); PG8_BAR; PG8_SCHED;
;             PG8_LDA(At, 1, 1); PG8_STAGE(PG8_SB(1, 0), b3, voffB); PG8_STAGE(PG8_SB(1, 1), b3 + hstep, voffB); PG8_STAGE(PG8_SA(1, 0), a3, voffA);
;             PG8_WAIT_V(8); PG8_WAIT_L(0); PG8_BAR; PG8_MMA(1, 0, At, B0); PG8_MMA(1, 1, At, B1); PG8_BAR; PG8_SCHED;
;     ...
;         if constexpr (ALIGN_EPI) { if (wr == 0) PG8_BAR; }
	v_mfma_f32_16x16x32_bf16 v[84:87], v[148:151], v[204:207], v[84:87]
	v_mfma_f32_16x16x32_bf16 v[80:83], v[172:175], v[204:207], v[80:83]
	v_mfma_f32_16x16x32_bf16 v[68:71], v[148:151], v[212:215], v[68:71]
	v_mfma_f32_16x16x32_bf16 v[64:67], v[172:175], v[212:215], v[64:67]
	s_setprio 0
	s_add_i32 s28, s61, s68
	v_lshl_add_u64 v[184:185], v[184:185], 0, s[24:25]
	s_mov_b32 m0, s28
	ds_read_b128 v[176:179], v191 offset:49152
	ds_read_b128 v[180:183], v191 offset:50176
	ds_read_b128 v[192:195], v191 offset:51200
	ds_read_b128 v[196:199], v191 offset:52224
	ds_read_b128 v[200:203], v191 offset:53248
	ds_read_b128 v[204:207], v191 offset:54272
	ds_read_b128 v[208:211], v191 offset:55296
	ds_read_b128 v[212:215], v191 offset:56320
	global_load_lds_dwordx4 v[184:185], off
	s_add_i32 m0, s28, 0x2000
	s_add_u32 s28, s34, 0xb0080
	v_lshl_add_u64 v[184:185], v[216:217], 0, s[24:25]
	s_addc_u32 s29, s35, 0
	s_add_i32 s34, s62, s68
	global_load_lds_dwordx4 v[184:185], off
	v_lshl_add_u64 v[184:185], s[28:29], 0, v[154:155]
	s_mov_b32 m0, s34
	s_nop 0
	global_load_lds_dwordx4 v[184:185], off
	v_lshl_add_u64 v[184:185], s[28:29], 0, v[158:159]
	s_add_i32 m0, s34, 0x2000
	s_nop 0
	global_load_lds_dwordx4 v[184:185], off
	v_lshl_add_u64 v[184:185], v[218:219], 0, s[24:25]
	s_mov_b32 m0, s75
	s_nop 0
	global_load_lds_dwordx4 v[184:185], off
	v_lshl_add_u64 v[184:185], v[220:221], 0, s[24:25]
	s_mov_b32 m0, s48
	s_nop 0
	global_load_lds_dwordx4 v[184:185], off
	s_waitcnt vmcnt(8)
	s_waitcnt lgkmcnt(0)
	s_barrier
	s_setprio 1
	s_waitcnt lgkmcnt(0)
	v_mfma_f32_16x16x32_bf16 v[60:63], v[128:131], v[176:179], v[60:63]
	v_mfma_f32_16x16x32_bf16 v[56:59], v[136:139], v[176:179], v[56:59]
	v_mfma_f32_16x16x32_bf16 v[44:47], v[128:131], v[192:195], v[44:47]
	v_mfma_f32_16x16x32_bf16 v[40:43], v[136:139], v[192:195], v[40:43]
	v_mfma_f32_16x16x32_bf16 v[28:31], v[128:131], v[200:203], v[28:31]
	v_mfma_f32_16x16x32_bf16 v[24:27], v[136:139], v[200:203], v[24:27]
	v_mfma_f32_16x16x32_bf16 v[12:15], v[128:131], v[208:211], v[12:15]
	v_mfma_f32_16x16x32_bf16 v[8:11], v[136:139], v[208:211], v[8:11]
	v_mfma_f32_16x16x32_bf16 v[60:63], v[132:135], v[180:183], v[60:63]
	v_mfma_f32_16x16x32_bf16 v[56:59], v[140:143], v[180:183], v[56:59]
	v_mfma_f32_16x16x32_bf16 v[44:47], v[132:135], v[196:199], v[44:47]
	v_mfma_f32_16x16x32_bf16 v[40:43], v[140:143], v[196:199], v[40:43]
	v_mfma_f32_16x16x32_bf16 v[28:31], v[132:135], v[204:207], v[28:31]
	v_mfma_f32_16x16x32_bf16 v[24:27], v[140:143], v[204:207], v[24:27]
	v_mfma_f32_16x16x32_bf16 v[12:15], v[132:135], v[212:215], v[12:15]
	v_mfma_f32_16x16x32_bf16 v[8:11], v[140:143], v[212:215], v[8:11]
	s_setprio 0
	s_setprio 1
	v_mfma_f32_16x16x32_bf16 v[52:55], v[144:147], v[176:179], v[52:55]
	v_mfma_f32_16x16x32_bf16 v[48:51], v[168:171], v[176:179], v[48:51]
	v_mfma_f32_16x16x32_bf16 v[36:39], v[144:147], v[192:195], v[36:39]
	v_mfma_f32_16x16x32_bf16 v[32:35], v[168:171], v[192:195], v[32:35]
	v_mfma_f32_16x16x32_bf16 v[20:23], v[144:147], v[200:203], v[20:23]
	v_mfma_f32_16x16x32_bf16 v[16:19], v[168:171], v[200:203], v[16:19]
	v_mfma_f32_16x16x32_bf16 v[4:7], v[144:147], v[208:211], v[4:7]
	v_mfma_f32_16x16x32_bf16 v[0:3], v[168:171], v[208:211], v[0:3]
	v_mfma_f32_16x16x32_bf16 v[52:55], v[148:151], v[180:183], v[52:55]
	v_mfma_f32_16x16x32_bf16 v[48:51], v[172:175], v[180:183], v[48:51]
	v_mfma_f32_16x16x32_bf16 v[36:39], v[148:151], v[196:199], v[36:39]
	v_mfma_f32_16x16x32_bf16 v[32:35], v[172:175], v[196:199], v[32:35]
	s_barrier
	v_mfma_f32_16x16x32_bf16 v[20:23], v[148:151], v[204:207], v[20:23]
	v_mfma_f32_16x16x32_bf16 v[16:19], v[172:175], v[204:207], v[16:19]
	v_mfma_f32_16x16x32_bf16 v[4:7], v[148:151], v[212:215], v[4:7]
	v_mfma_f32_16x16x32_bf16 v[0:3], v[172:175], v[212:215], v[0:3]
	s_setprio 0
	s_add_i32 s60, s60, 2
	s_add_u32 s43, s43, 0x100
	s_addc_u32 s59, s59, 0
	s_cmp_gt_u32 s60, 41
	s_mov_b64 s[28:29], s[30:31]
	s_cbranch_scc0 .LBB0_716
	s_and_b64 vcc, exec, s[16:17]
	s_cbranch_vccz .LBB0_719
	s_barrier

; #define PG8_STAGE(bufoff, gbase, voff) do { _Pragma("unroll") for (int _i = 0; _i < 2; ++_i) \
;         __builtin_amdgcn_global_load_lds((const unsigned*)((const char*)(gbase) + (voff)[_i]), (PG8_LAS unsigned*)(lds + (bufoff) + ldsw + _i * 8192), 16, 0, 0); } while (0)
; #define PG8_LDA(dst, b, h) do { _Pragma("unroll") for (int m = 0; m < 4; ++m) _Pragma("unroll") for (int k = 0; k < 2; ++k) dst[m][k] = *(const PG8_LAS bf16x8*)(lds + PG8_SA(b, h) + aoff + m * 2048 + k * 1024); } while (0)
; #define PG8_LDB(dst, b, h) do { _Pragma("unroll") for (int n = 0; n < 2; ++n) _Pragma("unroll") for (int k = 0; k < 2; ++k) dst[n][k] = *(const PG8_LAS bf16x8*)(lds + PG8_SB(b, h) + boff + n * 2048 + k * 1024); } while (0)
; #define PG8_MMA(ai, bj, At, Bt) do { __builtin_amdgcn_s_setprio(1); _Pragma("unroll") for (int m = 0; m < 4; ++m) _Pragma("unroll") for (int n = 0; n < 2; ++n) _Pragma("unroll") for (int k = 0; k < 2; ++k) \
;         acc[ai][bj][m][n] = mma16<F16>(Bt[n][k], At[m][k], acc[ai][bj][m][n]); __builtin_amdgcn_s_setprio(0); } while (0)
; #define PG8_WAIT_V(n) asm volatile("s_waitcnt vmcnt(" #n ")" ::: "memory")
; #define PG8_WAIT_L(n) asm volatile("s_waitcnt lgkmcnt(" #n ")" ::: "memory")
; template <class Epi, class Sched, bool ALIGN_EPI = false, bool SP2 = false, bool F16 = false>
; __device__ __forceinline__ void gemm_phase(PG8_LAS unsigned char* lds, const Gemm g, const Sched& S, const Epi& E, const int wid_in) {
;     ...
;             const bool last = (t == nt - 2);
;             const char* a1 = cA + (size_t)(t + 1) * kstep;
;             const char* a2 = last ? nA : cA + (size_t)(t + 2) * kstep; const char* b2 = last ? nB : cB + (size_t)(t + 2) * kstep;
;             const char* a3 = a2 + kstep; const char* b3 = b2 + kstep;
;             if (last && has_next) S.a_ready(nxt);
;             if constexpr (SP2) {
;             PG8_LDB(B0, 0, 0); PG8_LDB(B1, 0, 1); PG8_SCHED; PG8_LDA(At, 0, 0); PG8_STAGE(PG8_SA(1, 1), a1 + hstep, voffA);
;             PG8_WAIT_V(8); PG8_WAIT_L(0); PG8_BAR; PG8_MMA(0, 0, At, B0); PG8_MMA(0, 1, At, B1); PG8_BAR; PG8_SCHED;
;             PG8_LDA(At, 0, 1); PG8_STAGE(PG8_SB(0, 0), b2, voffB); PG8_STAGE(PG8_SB(0, 1), b2 + hstep, voffB); PG8_STAGE(PG8_SA(0, 0), a2, voffA);
;             PG8_WAIT_V(8); PG8_WAIT_L(0); PG8_BAR; PG8_MMA(1, 0, At, B0); PG8_MMA(1, 1, At, B1); PG8_BAR; PG8_SCHED;
.LBB0_812:
	ds_read_b128 v[112:115], v235
	ds_read_b128 v[116:119], v235 offset:1024
	ds_read_b128 v[128:131], v235 offset:2048
	ds_read_b128 v[132:135], v235 offset:3072
	ds_read_b128 v[144:147], v236
	ds_read_b128 v[148:151], v236 offset:1024
	ds_read_b128 v[152:155], v236 offset:2048
	ds_read_b128 v[156:159], v236 offset:3072
	s_add_u32 s43, s46, 0xfffc0080
	s_addc_u32 s45, s47, -1
	s_cmp_eq_u32 s42, 12
	s_cselect_b32 s51, s14, s45
	s_cselect_b32 s50, s15, s43
	s_cselect_b32 s49, s29, s41
	s_cselect_b32 s48, s31, s40
	v_lshl_add_u64 v[192:193], s[46:47], 0, v[204:205]
	s_add_i32 m0, s74, 0xc000
	ds_read_b128 v[160:163], v237
	ds_read_b128 v[164:167], v237 offset:1024
	ds_read_b128 v[168:171], v237 offset:2048
	ds_read_b128 v[172:175], v237 offset:3072
	ds_read_b128 v[176:179], v237 offset:4096
	ds_read_b128 v[180:183], v237 offset:5120
	ds_read_b128 v[184:187], v237 offset:6144
	ds_read_b128 v[188:191], v237 offset:7168
	global_load_lds_dwordx4 v[192:193], off
	v_lshl_add_u64 v[192:193], s[46:47], 0, v[206:207]
	s_add_i32 m0, s74, 0xe000
	s_nop 0
	global_load_lds_dwordx4 v[192:193], off
	s_waitcnt vmcnt(8)
	s_waitcnt lgkmcnt(0)
	s_barrier
	s_setprio 1
	s_waitcnt lgkmcnt(0)
	v_mfma_f32_16x16x32_f16 v[140:143], v[112:115], v[160:163], v[140:143]
	v_mfma_f32_16x16x32_f16 v[136:139], v[128:131], v[160:163], v[136:139]
	v_mfma_f32_16x16x32_f16 v[108:111], v[112:115], v[168:171], v[108:111]
	v_mfma_f32_16x16x32_f16 v[104:107], v[128:131], v[168:171], v[104:107]
	v_mfma_f32_16x16x32_f16 v[92:95], v[112:115], v[176:179], v[92:95]
	v_mfma_f32_16x16x32_f16 v[88:91], v[128:131], v[176:179], v[88:91]
	v_mfma_f32_16x16x32_f16 v[76:79], v[112:115], v[184:187], v[76:79]
	v_mfma_f32_16x16x32_f16 v[72:75], v[128:131], v[184:187], v[72:75]
	v_mfma_f32_16x16x32_f16 v[140:143], v[116:119], v[164:167], v[140:143]
	v_mfma_f32_16x16x32_f16 v[136:139], v[132:135], v[164:167], v[136:139]
	v_mfma_f32_16x16x32_f16 v[108:111], v[116:119], v[172:175], v[108:111]
	v_mfma_f32_16x16x32_f16 v[104:107], v[132:135], v[172:175], v[104:107]
	v_mfma_f32_16x16x32_f16 v[92:95], v[116:119], v[180:183], v[92:95]
	v_mfma_f32_16x16x32_f16 v[88:91], v[132:135], v[180:183], v[88:91]
	v_mfma_f32_16x16x32_f16 v[76:79], v[116:119], v[188:191], v[76:79]
	v_mfma_f32_16x16x32_f16 v[72:75], v[132:135], v[188:191], v[72:75]
	s_setprio 0
	s_setprio 1
	v_mfma_f32_16x16x32_f16 v[124:127], v[144:147], v[160:163], v[124:127]
	v_mfma_f32_16x16x32_f16 v[120:123], v[152:155], v[160:163], v[120:123]
	v_mfma_f32_16x16x32_f16 v[100:103], v[144:147], v[168:171], v[100:103]
	v_mfma_f32_16x16x32_f16 v[96:99], v[152:155], v[168:171], v[96:99]
	v_mfma_f32_16x16x32_f16 v[84:87], v[144:147], v[176:179], v[84:87]
	v_mfma_f32_16x16x32_f16 v[80:83], v[152:155], v[176:179], v[80:83]
	v_mfma_f32_16x16x32_f16 v[68:71], v[144:147], v[184:187], v[68:71]
	v_mfma_f32_16x16x32_f16 v[64:67], v[152:155], v[184:187], v[64:67]
	v_mfma_f32_16x16x32_f16 v[124:127], v[148:151], v[164:167], v[124:127]
	v_mfma_f32_16x16x32_f16 v[120:123], v[156:159], v[164:167], v[120:123]
	v_mfma_f32_16x16x32_f16 v[100:103], v[148:151], v[172:175], v[100:103]
	v_mfma_f32_16x16x32_f16 v[96:99], v[156:159], v[172:175], v[96:99]
	s_barrier
	v_mfma_f32_16x16x32_f16 v[84:87], v[148:151], v[180:183], v[84:87]
	v_mfma_f32_16x16x32_f16 v[80:83], v[156:159], v[180:183], v[80:83]
	v_mfma_f32_16x16x32_f16 v[68:71], v[148:151], v[188:191], v[68:71]
	v_mfma_f32_16x16x32_f16 v[64:67], v[156:159], v[188:191], v[64:67]
	s_setprio 0
	s_add_i32 s43, s64, s68
	v_lshl_add_u64 v[192:193], s[48:49], 0, v[198:199]
	s_mov_b32 m0, s43
	ds_read_b128 v[160:163], v237 offset:16384
	ds_read_b128 v[164:167], v237 offset:17408
	ds_read_b128 v[168:171], v237 offset:18432
	ds_read_b128 v[172:175], v237 offset:19456
	ds_read_b128 v[176:179], v237 offset:20480
	ds_read_b128 v[180:183], v237 offset:21504
	ds_read_b128 v[184:187], v237 offset:22528
	ds_read_b128 v[188:191], v237 offset:23552
	global_load_lds_dwordx4 v[192:193], off
	s_add_i32 m0, s43, 0x2000
	s_add_u32 s86, s48, 0x40000
	v_lshl_add_u64 v[194:195], s[48:49], 0, v[202:203]
	s_addc_u32 s87, s49, 0
	s_add_i32 s43, s65, s68
	global_load_lds_dwordx4 v[194:195], off
	v_lshl_add_u64 v[212:213], s[86:87], 0, v[198:199]
	s_mov_b32 m0, s43
	v_lshl_add_u64 v[214:215], s[50:51], 0, v[200:201]
	global_load_lds_dwordx4 v[212:213], off
	v_lshl_add_u64 v[212:213], s[86:87], 0, v[202:203]
	s_add_i32 m0, s43, 0x2000
	s_nop 0
	global_load_lds_dwordx4 v[212:213], off
	v_lshl_add_u64 v[212:213], s[50:51], 0, v[196:197]
	s_mov_b32 m0, s74
	s_nop 0
	global_load_lds_dwordx4 v[212:213], off
	s_mov_b32 m0, s55
	s_nop 0
	global_load_lds_dwordx4 v[214:215], off
	s_waitcnt vmcnt(8)
	s_waitcnt lgkmcnt(0)
	s_barrier
; #define PG8_STAGE(bufoff, gbase, voff) do { _Pragma("unroll") for (int _i = 0; _i < 2; ++_i) \
;         __builtin_amdgcn_global_load_lds((const unsigned*)((const char*)(gbase) + (voff)[_i]), (PG8_LAS unsigned*)(lds + (bufoff) + ldsw + _i * 8192), 16, 0, 0); } while (0)
; #define PG8_LDA(dst, b, h) do { _Pragma("unroll") for (int m = 0; m < 4; ++m) _Pragma("unroll") for (int k = 0; k < 2; ++k) dst[m][k] = *(const PG8_LAS bf16x8*)(lds + PG8_SA(b, h) + aoff + m * 2048 + k * 1024); } while (0)
; #define PG8_LDB(dst, b, h) do { _Pragma("unroll") for (int n = 0; n < 2; ++n) _Pragma("unroll") for (int k = 0; k < 2; ++k) dst[n][k] = *(const PG8_LAS bf16x8*)(lds + PG8_SB(b, h) + boff + n * 2048 + k * 1024); } while (0)
; #define PG8_MMA(ai, bj, At, Bt) do { __builtin_amdgcn_s_setprio(1); _Pragma("unroll") for (int m = 0; m < 4; ++m) _Pragma("unroll") for (int n = 0; n < 2; ++n) _Pragma("unroll") for (int k = 0; k < 2; ++k) \
;         acc[ai][bj][m][n] = mma16<F16>(Bt[n][k], At[m][k], acc[ai][bj][m][n]); __builtin_amdgcn_s_setprio(0); } while (0)
; #define PG8_WAIT_V(n) asm volatile("s_waitcnt vmcnt(" #n ")" ::: "memory")
; #define PG8_WAIT_L(n) asm volatile("s_waitcnt lgkmcnt(" #n ")" ::: "memory")
; #define PG8_BAR __builtin_amdgcn_s_barrier()
; #define PG8_SCHED __builtin_amdgcn_sched_barrier(0)
; template <class Epi, class Sched, bool ALIGN_EPI = false, bool SP2 = false, bool F16 = false>
; __device__ __forceinline__ void gemm_phase(PG8_LAS unsigned char* lds, const Gemm g, const Sched& S, const Epi& E, const int wid_in) {
;     ...
;             PG8_WAIT_V(8); PG8_WAIT_L(0); PG8_BAR; PG8_MMA(1, 0, At, B0); PG8_MMA(1, 1, At, B1); PG8_BAR; PG8_SCHED;
;             PG8_LDB(B0, 1, 0); PG8_LDB(B1, 1, 1); PG8_SCHED; PG8_LDA(At, 1, 0); PG8_STAGE(PG8_SA(0, 1), a2 + hstep, voffA);
;             PG8_WAIT_V(8); PG8_WAIT_L(0); PG8_BAR; PG8_MMA(0, 0, At, B0); PG8_MMA(0, 1, At, B1); PG8_BAR; PG8_SCHED;
	s_setprio 1
	s_waitcnt lgkmcnt(0)
	v_mfma_f32_16x16x32_f16 v[60:63], v[112:115], v[160:163], v[60:63]
	v_mfma_f32_16x16x32_f16 v[56:59], v[128:131], v[160:163], v[56:59]
	v_mfma_f32_16x16x32_f16 v[44:47], v[112:115], v[168:171], v[44:47]
	v_mfma_f32_16x16x32_f16 v[40:43], v[128:131], v[168:171], v[40:43]
	v_mfma_f32_16x16x32_f16 v[28:31], v[112:115], v[176:179], v[28:31]
	v_mfma_f32_16x16x32_f16 v[24:27], v[128:131], v[176:179], v[24:27]
	v_mfma_f32_16x16x32_f16 v[12:15], v[112:115], v[184:187], v[12:15]
	v_mfma_f32_16x16x32_f16 v[8:11], v[128:131], v[184:187], v[8:11]
	v_mfma_f32_16x16x32_f16 v[60:63], v[116:119], v[164:167], v[60:63]
	v_mfma_f32_16x16x32_f16 v[56:59], v[132:135], v[164:167], v[56:59]
	v_mfma_f32_16x16x32_f16 v[44:47], v[116:119], v[172:175], v[44:47]
	v_mfma_f32_16x16x32_f16 v[40:43], v[132:135], v[172:175], v[40:43]
	v_mfma_f32_16x16x32_f16 v[28:31], v[116:119], v[180:183], v[28:31]
	v_mfma_f32_16x16x32_f16 v[24:27], v[132:135], v[180:183], v[24:27]
	v_mfma_f32_16x16x32_f16 v[12:15], v[116:119], v[188:191], v[12:15]
	v_mfma_f32_16x16x32_f16 v[8:11], v[132:135], v[188:191], v[8:11]
	s_setprio 0
	s_setprio 1
	v_mfma_f32_16x16x32_f16 v[52:55], v[144:147], v[160:163], v[52:55]
	v_mfma_f32_16x16x32_f16 v[48:51], v[152:155], v[160:163], v[48:51]
	v_mfma_f32_16x16x32_f16 v[36:39], v[144:147], v[168:171], v[36:39]
	v_mfma_f32_16x16x32_f16 v[32:35], v[152:155], v[168:171], v[32:35]
	v_mfma_f32_16x16x32_f16 v[20:23], v[144:147], v[176:179], v[20:23]
	v_mfma_f32_16x16x32_f16 v[16:19], v[152:155], v[176:179], v[16:19]
	v_mfma_f32_16x16x32_f16 v[4:7], v[144:147], v[184:187], v[4:7]
	v_mfma_f32_16x16x32_f16 v[0:3], v[152:155], v[184:187], v[0:3]
	v_mfma_f32_16x16x32_f16 v[52:55], v[148:151], v[164:167], v[52:55]
	v_mfma_f32_16x16x32_f16 v[48:51], v[156:159], v[164:167], v[48:51]
	v_mfma_f32_16x16x32_f16 v[36:39], v[148:151], v[172:175], v[36:39]
	v_mfma_f32_16x16x32_f16 v[32:35], v[156:159], v[172:175], v[32:35]
	s_barrier
	v_mfma_f32_16x16x32_f16 v[20:23], v[148:151], v[180:183], v[20:23]
	v_mfma_f32_16x16x32_f16 v[16:19], v[156:159], v[180:183], v[16:19]
	v_mfma_f32_16x16x32_f16 v[4:7], v[148:151], v[188:191], v[4:7]
	v_mfma_f32_16x16x32_f16 v[0:3], v[156:159], v[188:191], v[0:3]
	s_setprio 0
	s_add_i32 s43, 0, 0x18000
	s_add_i32 s45, 0, 0x1c000
	v_add_u32_e32 v132, s43, v234
	v_add_u32_e32 v156, s45, v234
	ds_read_b128 v[112:115], v132
	ds_read_b128 v[116:119], v132 offset:1024
	ds_read_b128 v[128:131], v132 offset:2048
	ds_read_b128 v[132:135], v132 offset:3072
	ds_read_b128 v[144:147], v156
	ds_read_b128 v[148:151], v156 offset:1024
	ds_read_b128 v[152:155], v156 offset:2048
	ds_read_b128 v[156:159], v156 offset:3072
	s_add_u32 s50, s50, 0x40000
	s_addc_u32 s51, s51, 0
	s_mov_b32 m0, s58
	v_lshl_add_u64 v[216:217], s[50:51], 0, v[196:197]
	ds_read_b128 v[160:163], v237 offset:32768
	ds_read_b128 v[164:167], v237 offset:33792
	ds_read_b128 v[168:171], v237 offset:34816
	ds_read_b128 v[172:175], v237 offset:35840
	ds_read_b128 v[176:179], v237 offset:36864
	ds_read_b128 v[180:183], v237 offset:37888
	ds_read_b128 v[184:187], v237 offset:38912
	ds_read_b128 v[188:191], v237 offset:39936
	global_load_lds_dwordx4 v[216:217], off
	v_lshl_add_u64 v[216:217], s[50:51], 0, v[200:201]
	s_mov_b32 m0, s59
	s_nop 0
	global_load_lds_dwordx4 v[216:217], off
	s_waitcnt vmcnt(8)
	s_waitcnt lgkmcnt(0)
	s_barrier
	s_setprio 1
	s_waitcnt lgkmcnt(0)
	v_mfma_f32_16x16x32_f16 v[140:143], v[112:115], v[160:163], v[140:143]
	v_mfma_f32_16x16x32_f16 v[136:139], v[128:131], v[160:163], v[136:139]
	v_mfma_f32_16x16x32_f16 v[108:111], v[112:115], v[168:171], v[108:111]
	v_mfma_f32_16x16x32_f16 v[104:107], v[128:131], v[168:171], v[104:107]
	v_mfma_f32_16x16x32_f16 v[92:95], v[112:115], v[176:179], v[92:95]
	v_mfma_f32_16x16x32_f16 v[88:91], v[128:131], v[176:179], v[88:91]
	v_mfma_f32_16x16x32_f16 v[76:79], v[112:115], v[184:187], v[76:79]
	v_mfma_f32_16x16x32_f16 v[72:75], v[128:131], v[184:187], v[72:75]
	v_mfma_f32_16x16x32_f16 v[140:143], v[116:119], v[164:167], v[140:143]
	v_mfma_f32_16x16x32_f16 v[136:139], v[132:135], v[164:167], v[136:139]
	v_mfma_f32_16x16x32_f16 v[108:111], v[116:119], v[172:175], v[108:111]
	v_mfma_f32_16x16x32_f16 v[104:107], v[132:135], v[172:175], v[104:107]
	v_mfma_f32_16x16x32_f16 v[92:95], v[116:119], v[180:183], v[92:95]
	v_mfma_f32_16x16x32_f16 v[88:91], v[132:135], v[180:183], v[88:91]
	v_mfma_f32_16x16x32_f16 v[76:79], v[116:119], v[188:191], v[76:79]
	v_mfma_f32_16x16x32_f16 v[72:75], v[132:135], v[188:191], v[72:75]
	s_setprio 0
	s_setprio 1
	v_mfma_f32_16x16x32_f16 v[124:127], v[144:147], v[160:163], v[124:127]
	v_mfma_f32_16x16x32_f16 v[120:123], v[152:155], v[160:163], v[120:123]
	v_mfma_f32_16x16x32_f16 v[100:103], v[144:147], v[168:171], v[100:103]
	v_mfma_f32_16x16x32_f16 v[96:99], v[152:155], v[168:171], v[96:99]
	v_mfma_f32_16x16x32_f16 v[84:87], v[144:147], v[176:179], v[84:87]
	v_mfma_f32_16x16x32_f16 v[80:83], v[152:155], v[176:179], v[80:83]
	v_mfma_f32_16x16x32_f16 v[68:71], v[144:147], v[184:187], v[68:71]
	v_mfma_f32_16x16x32_f16 v[64:67], v[152:155], v[184:187], v[64:67]
	v_mfma_f32_16x16x32_f16 v[124:127], v[148:151], v[164:167], v[124:127]
	v_mfma_f32_16x16x32_f16 v[120:123], v[156:159], v[164:167], v[120:123]
	v_mfma_f32_16x16x32_f16 v[100:103], v[148:151], v[172:175], v[100:103]
	v_mfma_f32_16x16x32_f16 v[96:99], v[156:159], v[172:175], v[96:99]
	s_barrier
; #define PG8_STAGE(bufoff, gbase, voff) do { _Pragma("unroll") for (int _i = 0; _i < 2; ++_i) \
;         __builtin_amdgcn_global_load_lds((const unsigned*)((const char*)(gbase) + (voff)[_i]), (PG8_LAS unsigned*)(lds + (bufoff) + ldsw + _i * 8192), 16, 0, 0); } while (0)
; #define PG8_LDA(dst, b, h) do { _Pragma("unroll") for (int m = 0; m < 4; ++m) _Pragma("unroll") for (int k = 0; k < 2; ++k) dst[m][k] = *(const PG8_LAS bf16x8*)(lds + PG8_SA(b, h) + aoff + m * 2048 + k * 1024); } while (0)
; #define PG8_MMA(ai, bj, At, Bt) do { __builtin_amdgcn_s_setprio(1); _Pragma("unroll") for (int m = 0; m < 4; ++m) _Pragma("unroll") for (int n = 0; n < 2; ++n) _Pragma("unroll") for (int k = 0; k < 2; ++k) \
;         acc[ai][bj][m][n] = mma16<F16>(Bt[n][k], At[m][k], acc[ai][bj][m][n]); __builtin_amdgcn_s_setprio(0); } while (0)
; #define PG8_WAIT_V(n) asm volatile("s_waitcnt vmcnt(" #n ")" ::: "memory")
; #define PG8_WAIT_L(n) asm volatile("s_waitcnt lgkmcnt(" #n ")" ::: "memory")
; #define PG8_BAR __builtin_amdgcn_s_barrier()
; #define PG8_SCHED __builtin_amdgcn_sched_barrier(0)
; template <class Epi, class Sched, bool ALIGN_EPI = false, bool SP2 = false, bool F16 = false>
; __device__ __forceinline__ void gemm_phase(PG8_LAS unsigned char* lds, const Gemm g, const Sched& S, const Epi& E, const int wid_in) {
;     ...
;             PG8_WAIT_V(8); PG8_WAIT_L(0); PG8_BAR; PG8_MMA(0, 0, At, B0); PG8_MMA(0, 1, At, B1); PG8_BAR; PG8_SCHED;
;             PG8_LDA(At, 1, 1); PG8_STAGE(PG8_SB(1, 0), b3, voffB); PG8_STAGE(PG8_SB(1, 1), b3 + hstep, voffB); PG8_STAGE(PG8_SA(1, 0), a3, voffA);
;             PG8_WAIT_V(8); PG8_WAIT_L(0); PG8_BAR; PG8_MMA(1, 0, At, B0); PG8_MMA(1, 1, At, B1); PG8_BAR; PG8_SCHED;
;     ...
;         if constexpr (ALIGN_EPI) { if (wr == 0) PG8_BAR; }
	v_mfma_f32_16x16x32_f16 v[84:87], v[148:151], v[180:183], v[84:87]
	v_mfma_f32_16x16x32_f16 v[80:83], v[156:159], v[180:183], v[80:83]
	v_mfma_f32_16x16x32_f16 v[68:71], v[148:151], v[188:191], v[68:71]
	v_mfma_f32_16x16x32_f16 v[64:67], v[156:159], v[188:191], v[64:67]
	s_setprio 0
	s_add_i32 s43, s43, s68
	v_lshl_add_u64 v[192:193], v[192:193], 0, s[26:27]
	s_mov_b32 m0, s43
	ds_read_b128 v[160:163], v237 offset:49152
	ds_read_b128 v[164:167], v237 offset:50176
	ds_read_b128 v[168:171], v237 offset:51200
	ds_read_b128 v[172:175], v237 offset:52224
	ds_read_b128 v[176:179], v237 offset:53248
	ds_read_b128 v[180:183], v237 offset:54272
	ds_read_b128 v[184:187], v237 offset:55296
	ds_read_b128 v[188:191], v237 offset:56320
	global_load_lds_dwordx4 v[192:193], off
	s_add_i32 m0, s43, 0x2000
	s_add_u32 s48, s48, 0x40080
	v_lshl_add_u64 v[192:193], v[194:195], 0, s[26:27]
	s_addc_u32 s49, s49, 0
	s_add_i32 s43, s45, s68
	global_load_lds_dwordx4 v[192:193], off
	v_lshl_add_u64 v[192:193], s[48:49], 0, v[198:199]
	s_mov_b32 m0, s43
	s_nop 0
	global_load_lds_dwordx4 v[192:193], off
	v_lshl_add_u64 v[192:193], s[48:49], 0, v[202:203]
	s_add_i32 m0, s43, 0x2000
	s_nop 0
	global_load_lds_dwordx4 v[192:193], off
	v_lshl_add_u64 v[192:193], v[212:213], 0, s[26:27]
	s_mov_b32 m0, s75
	s_nop 0
	global_load_lds_dwordx4 v[192:193], off
	v_lshl_add_u64 v[192:193], v[214:215], 0, s[26:27]
	s_mov_b32 m0, s60
	s_nop 0
	global_load_lds_dwordx4 v[192:193], off
	s_waitcnt vmcnt(8)
	s_waitcnt lgkmcnt(0)
	s_barrier
	s_setprio 1
	s_waitcnt lgkmcnt(0)
	v_mfma_f32_16x16x32_f16 v[60:63], v[112:115], v[160:163], v[60:63]
	v_mfma_f32_16x16x32_f16 v[56:59], v[128:131], v[160:163], v[56:59]
	v_mfma_f32_16x16x32_f16 v[44:47], v[112:115], v[168:171], v[44:47]
	v_mfma_f32_16x16x32_f16 v[40:43], v[128:131], v[168:171], v[40:43]
	v_mfma_f32_16x16x32_f16 v[28:31], v[112:115], v[176:179], v[28:31]
	v_mfma_f32_16x16x32_f16 v[24:27], v[128:131], v[176:179], v[24:27]
	v_mfma_f32_16x16x32_f16 v[12:15], v[112:115], v[184:187], v[12:15]
	v_mfma_f32_16x16x32_f16 v[8:11], v[128:131], v[184:187], v[8:11]
	v_mfma_f32_16x16x32_f16 v[60:63], v[116:119], v[164:167], v[60:63]
	v_mfma_f32_16x16x32_f16 v[56:59], v[132:135], v[164:167], v[56:59]
	v_mfma_f32_16x16x32_f16 v[44:47], v[116:119], v[172:175], v[44:47]
	v_mfma_f32_16x16x32_f16 v[40:43], v[132:135], v[172:175], v[40:43]
	v_mfma_f32_16x16x32_f16 v[28:31], v[116:119], v[180:183], v[28:31]
	v_mfma_f32_16x16x32_f16 v[24:27], v[132:135], v[180:183], v[24:27]
	v_mfma_f32_16x16x32_f16 v[12:15], v[116:119], v[188:191], v[12:15]
	v_mfma_f32_16x16x32_f16 v[8:11], v[132:135], v[188:191], v[8:11]
	s_setprio 0
	s_setprio 1
	v_mfma_f32_16x16x32_f16 v[52:55], v[144:147], v[160:163], v[52:55]
	v_mfma_f32_16x16x32_f16 v[48:51], v[152:155], v[160:163], v[48:51]
	v_mfma_f32_16x16x32_f16 v[36:39], v[144:147], v[168:171], v[36:39]
	v_mfma_f32_16x16x32_f16 v[32:35], v[152:155], v[168:171], v[32:35]
	v_mfma_f32_16x16x32_f16 v[20:23], v[144:147], v[176:179], v[20:23]
	v_mfma_f32_16x16x32_f16 v[16:19], v[152:155], v[176:179], v[16:19]
	v_mfma_f32_16x16x32_f16 v[4:7], v[144:147], v[184:187], v[4:7]
	v_mfma_f32_16x16x32_f16 v[0:3], v[152:155], v[184:187], v[0:3]
	v_mfma_f32_16x16x32_f16 v[52:55], v[148:151], v[164:167], v[52:55]
	v_mfma_f32_16x16x32_f16 v[48:51], v[156:159], v[164:167], v[48:51]
	v_mfma_f32_16x16x32_f16 v[36:39], v[148:151], v[172:175], v[36:39]
	v_mfma_f32_16x16x32_f16 v[32:35], v[156:159], v[172:175], v[32:35]
	s_barrier
	v_mfma_f32_16x16x32_f16 v[20:23], v[148:151], v[180:183], v[20:23]
	v_mfma_f32_16x16x32_f16 v[16:19], v[156:159], v[180:183], v[16:19]
	v_mfma_f32_16x16x32_f16 v[4:7], v[148:151], v[188:191], v[4:7]
	v_mfma_f32_16x16x32_f16 v[0:3], v[156:159], v[188:191], v[0:3]
	s_setprio 0
	s_add_i32 s42, s42, 2
	s_add_u32 s46, s46, 0x100
	s_addc_u32 s47, s47, 0
	s_add_u32 s40, s40, 0x100
	s_addc_u32 s41, s41, 0
	s_cmp_gt_u32 s42, 13
	s_cbranch_scc0 .LBB0_812
	s_and_b64 vcc, exec, s[16:17]
	s_cbranch_vccz .LBB0_815
	s_barrier

; #define PG8_STAGE(bufoff, gbase, voff) do { _Pragma("unroll") for (int _i = 0; _i < 2; ++_i) \
;         __builtin_amdgcn_global_load_lds((const unsigned*)((const char*)(gbase) + (voff)[_i]), (PG8_LAS unsigned*)(lds + (bufoff) + ldsw + _i * 8192), 16, 0, 0); } while (0)
; #define PG8_LDA(dst, b, h) do { _Pragma("unroll") for (int m = 0; m < 4; ++m) _Pragma("unroll") for (int k = 0; k < 2; ++k) dst[m][k] = *(const PG8_LAS bf16x8*)(lds + PG8_SA(b, h) + aoff + m * 2048 + k * 1024); } while (0)
; #define PG8_LDB(dst, b, h) do { _Pragma("unroll") for (int n = 0; n < 2; ++n) _Pragma("unroll") for (int k = 0; k < 2; ++k) dst[n][k] = *(const PG8_LAS bf16x8*)(lds + PG8_SB(b, h) + boff + n * 2048 + k * 1024); } while (0)
; #define PG8_MMA(ai, bj, At, Bt) do { __builtin_amdgcn_s_setprio(1); _Pragma("unroll") for (int m = 0; m < 4; ++m) _Pragma("unroll") for (int n = 0; n < 2; ++n) _Pragma("unroll") for (int k = 0; k < 2; ++k) \
;         acc[ai][bj][m][n] = mma16<F16>(Bt[n][k], At[m][k], acc[ai][bj][m][n]); __builtin_amdgcn_s_setprio(0); } while (0)
; #define PG8_WAIT_V(n) asm volatile("s_waitcnt vmcnt(" #n ")" ::: "memory")
; #define PG8_WAIT_L(n) asm volatile("s_waitcnt lgkmcnt(" #n ")" ::: "memory")
; template <class Epi, class Sched, bool ALIGN_EPI = false, bool SP2 = false, bool F16 = false>
; __device__ __forceinline__ void gemm_phase(PG8_LAS unsigned char* lds, const Gemm g, const Sched& S, const Epi& E, const int wid_in) {
;     ...
;             const bool last = (t == nt - 2);
;             const char* a1 = cA + (size_t)(t + 1) * kstep;
;             const char* a2 = last ? nA : cA + (size_t)(t + 2) * kstep; const char* b2 = last ? nB : cB + (size_t)(t + 2) * kstep;
;             const char* a3 = a2 + kstep; const char* b3 = b2 + kstep;
;             if (last && has_next) S.a_ready(nxt);
;             if constexpr (SP2) {
;             PG8_LDB(B0, 0, 0); PG8_LDB(B1, 0, 1); PG8_SCHED; PG8_LDA(At, 0, 0); PG8_STAGE(PG8_SA(1, 1), a1 + hstep, voffA);
;             PG8_WAIT_V(8); PG8_WAIT_L(0); PG8_BAR; PG8_MMA(0, 0, At, B0); PG8_MMA(0, 1, At, B1); PG8_BAR; PG8_SCHED;
;             PG8_LDA(At, 0, 1); PG8_STAGE(PG8_SB(0, 0), b2, voffB); PG8_STAGE(PG8_SB(0, 1), b2 + hstep, voffB); PG8_STAGE(PG8_SA(0, 0), a2, voffA);
;             PG8_WAIT_V(8); PG8_WAIT_L(0); PG8_BAR; PG8_MMA(1, 0, At, B0); PG8_MMA(1, 1, At, B1); PG8_BAR; PG8_SCHED;
.LBB0_902:
	ds_read_b128 v[128:131], v183
	ds_read_b128 v[132:135], v183 offset:1024
	ds_read_b128 v[136:139], v183 offset:2048
	ds_read_b128 v[140:143], v183 offset:3072
	ds_read_b128 v[144:147], v184
	ds_read_b128 v[148:151], v184 offset:1024
	ds_read_b128 v[152:155], v184 offset:2048
	ds_read_b128 v[174:177], v184 offset:3072
	s_add_u32 s48, s46, 0xfffc0080
	s_addc_u32 s49, s47, -1
	s_cmp_eq_u32 s52, 12
	s_cselect_b32 s51, s11, s49
	s_cselect_b32 s50, s13, s48
	s_cselect_b32 s49, s31, s43
	s_cselect_b32 s48, s35, s42
	v_lshl_add_u64 v[178:179], s[46:47], 0, v[166:167]
	s_add_i32 m0, s74, 0xc000
	ds_read_b128 v[188:191], v185
	ds_read_b128 v[192:195], v185 offset:1024
	ds_read_b128 v[196:199], v185 offset:2048
	ds_read_b128 v[200:203], v185 offset:3072
	ds_read_b128 v[204:207], v185 offset:4096
	ds_read_b128 v[208:211], v185 offset:5120
	ds_read_b128 v[212:215], v185 offset:6144
	ds_read_b128 v[216:219], v185 offset:7168
	global_load_lds_dwordx4 v[178:179], off
	v_lshl_add_u64 v[178:179], s[46:47], 0, v[168:169]
	s_add_i32 m0, s74, 0xe000
	s_nop 0
	global_load_lds_dwordx4 v[178:179], off
	s_waitcnt vmcnt(8)
	s_waitcnt lgkmcnt(0)
	s_barrier
	s_setprio 1
	s_waitcnt lgkmcnt(0)
	v_mfma_f32_16x16x32_f16 v[124:127], v[128:131], v[188:191], v[124:127]
	v_mfma_f32_16x16x32_f16 v[120:123], v[136:139], v[188:191], v[120:123]
	v_mfma_f32_16x16x32_f16 v[108:111], v[128:131], v[196:199], v[108:111]
	v_mfma_f32_16x16x32_f16 v[104:107], v[136:139], v[196:199], v[104:107]
	v_mfma_f32_16x16x32_f16 v[92:95], v[128:131], v[204:207], v[92:95]
	v_mfma_f32_16x16x32_f16 v[88:91], v[136:139], v[204:207], v[88:91]
	v_mfma_f32_16x16x32_f16 v[76:79], v[128:131], v[212:215], v[76:79]
	v_mfma_f32_16x16x32_f16 v[72:75], v[136:139], v[212:215], v[72:75]
	v_mfma_f32_16x16x32_f16 v[124:127], v[132:135], v[192:195], v[124:127]
	v_mfma_f32_16x16x32_f16 v[120:123], v[140:143], v[192:195], v[120:123]
	v_mfma_f32_16x16x32_f16 v[108:111], v[132:135], v[200:203], v[108:111]
	v_mfma_f32_16x16x32_f16 v[104:107], v[140:143], v[200:203], v[104:107]
	v_mfma_f32_16x16x32_f16 v[92:95], v[132:135], v[208:211], v[92:95]
	v_mfma_f32_16x16x32_f16 v[88:91], v[140:143], v[208:211], v[88:91]
	v_mfma_f32_16x16x32_f16 v[76:79], v[132:135], v[216:219], v[76:79]
	v_mfma_f32_16x16x32_f16 v[72:75], v[140:143], v[216:219], v[72:75]
	s_setprio 0
	s_setprio 1
	v_mfma_f32_16x16x32_f16 v[116:119], v[144:147], v[188:191], v[116:119]
	v_mfma_f32_16x16x32_f16 v[112:115], v[152:155], v[188:191], v[112:115]
	v_mfma_f32_16x16x32_f16 v[100:103], v[144:147], v[196:199], v[100:103]
	v_mfma_f32_16x16x32_f16 v[96:99], v[152:155], v[196:199], v[96:99]
	v_mfma_f32_16x16x32_f16 v[84:87], v[144:147], v[204:207], v[84:87]
	v_mfma_f32_16x16x32_f16 v[80:83], v[152:155], v[204:207], v[80:83]
	v_mfma_f32_16x16x32_f16 v[68:71], v[144:147], v[212:215], v[68:71]
	v_mfma_f32_16x16x32_f16 v[64:67], v[152:155], v[212:215], v[64:67]
	v_mfma_f32_16x16x32_f16 v[116:119], v[148:151], v[192:195], v[116:119]
	v_mfma_f32_16x16x32_f16 v[112:115], v[174:177], v[192:195], v[112:115]
	v_mfma_f32_16x16x32_f16 v[100:103], v[148:151], v[200:203], v[100:103]
	v_mfma_f32_16x16x32_f16 v[96:99], v[174:177], v[200:203], v[96:99]
	s_barrier
	v_mfma_f32_16x16x32_f16 v[84:87], v[148:151], v[208:211], v[84:87]
	v_mfma_f32_16x16x32_f16 v[80:83], v[174:177], v[208:211], v[80:83]
	v_mfma_f32_16x16x32_f16 v[68:71], v[148:151], v[216:219], v[68:71]
	v_mfma_f32_16x16x32_f16 v[64:67], v[174:177], v[216:219], v[64:67]
	s_setprio 0
	s_add_i32 s53, s40, s68
	v_lshl_add_u64 v[178:179], s[48:49], 0, v[158:159]
	s_mov_b32 m0, s53
	ds_read_b128 v[188:191], v185 offset:16384
	ds_read_b128 v[192:195], v185 offset:17408
	ds_read_b128 v[196:199], v185 offset:18432
	ds_read_b128 v[200:203], v185 offset:19456
	ds_read_b128 v[204:207], v185 offset:20480
	ds_read_b128 v[208:211], v185 offset:21504
	ds_read_b128 v[212:215], v185 offset:22528
	ds_read_b128 v[216:219], v185 offset:23552
	global_load_lds_dwordx4 v[178:179], off
	s_add_i32 m0, s53, 0x2000
	s_add_u32 s54, s48, 0x40000
	v_lshl_add_u64 v[220:221], s[48:49], 0, v[162:163]
	s_addc_u32 s55, s49, 0
	s_add_i32 s53, s41, s68
	global_load_lds_dwordx4 v[220:221], off
	v_lshl_add_u64 v[222:223], s[54:55], 0, v[158:159]
	s_mov_b32 m0, s53
	v_lshl_add_u64 v[224:225], s[50:51], 0, v[160:161]
	global_load_lds_dwordx4 v[222:223], off
	v_lshl_add_u64 v[222:223], s[54:55], 0, v[162:163]
	s_add_i32 m0, s53, 0x2000
	s_nop 0
	global_load_lds_dwordx4 v[222:223], off
	v_lshl_add_u64 v[222:223], s[50:51], 0, v[156:157]
	s_mov_b32 m0, s74
	s_nop 0
	global_load_lds_dwordx4 v[222:223], off
	s_mov_b32 m0, s65
	s_nop 0
	global_load_lds_dwordx4 v[224:225], off
	s_waitcnt vmcnt(8)
	s_waitcnt lgkmcnt(0)
	s_barrier
; #define PG8_STAGE(bufoff, gbase, voff) do { _Pragma("unroll") for (int _i = 0; _i < 2; ++_i) \
;         __builtin_amdgcn_global_load_lds((const unsigned*)((const char*)(gbase) + (voff)[_i]), (PG8_LAS unsigned*)(lds + (bufoff) + ldsw + _i * 8192), 16, 0, 0); } while (0)
; #define PG8_LDA(dst, b, h) do { _Pragma("unroll") for (int m = 0; m < 4; ++m) _Pragma("unroll") for (int k = 0; k < 2; ++k) dst[m][k] = *(const PG8_LAS bf16x8*)(lds + PG8_SA(b, h) + aoff + m * 2048 + k * 1024); } while (0)
; #define PG8_LDB(dst, b, h) do { _Pragma("unroll") for (int n = 0; n < 2; ++n) _Pragma("unroll") for (int k = 0; k < 2; ++k) dst[n][k] = *(const PG8_LAS bf16x8*)(lds + PG8_SB(b, h) + boff + n * 2048 + k * 1024); } while (0)
; #define PG8_MMA(ai, bj, At, Bt) do { __builtin_amdgcn_s_setprio(1); _Pragma("unroll") for (int m = 0; m < 4; ++m) _Pragma("unroll") for (int n = 0; n < 2; ++n) _Pragma("unroll") for (int k = 0; k < 2; ++k) \
;         acc[ai][bj][m][n] = mma16<F16>(Bt[n][k], At[m][k], acc[ai][bj][m][n]); __builtin_amdgcn_s_setprio(0); } while (0)
; #define PG8_WAIT_V(n) asm volatile("s_waitcnt vmcnt(" #n ")" ::: "memory")
; #define PG8_WAIT_L(n) asm volatile("s_waitcnt lgkmcnt(" #n ")" ::: "memory")
; #define PG8_BAR __builtin_amdgcn_s_barrier()
; #define PG8_SCHED __builtin_amdgcn_sched_barrier(0)
; template <class Epi, class Sched, bool ALIGN_EPI = false, bool SP2 = false, bool F16 = false>
; __device__ __forceinline__ void gemm_phase(PG8_LAS unsigned char* lds, const Gemm g, const Sched& S, const Epi& E, const int wid_in) {
;     ...
;             PG8_WAIT_V(8); PG8_WAIT_L(0); PG8_BAR; PG8_MMA(1, 0, At, B0); PG8_MMA(1, 1, At, B1); PG8_BAR; PG8_SCHED;
;             PG8_LDB(B0, 1, 0); PG8_LDB(B1, 1, 1); PG8_SCHED; PG8_LDA(At, 1, 0); PG8_STAGE(PG8_SA(0, 1), a2 + hstep, voffA);
;             PG8_WAIT_V(8); PG8_WAIT_L(0); PG8_BAR; PG8_MMA(0, 0, At, B0); PG8_MMA(0, 1, At, B1); PG8_BAR; PG8_SCHED;
	s_setprio 1
	s_waitcnt lgkmcnt(0)
	v_mfma_f32_16x16x32_f16 v[60:63], v[128:131], v[188:191], v[60:63]
	v_mfma_f32_16x16x32_f16 v[56:59], v[136:139], v[188:191], v[56:59]
	v_mfma_f32_16x16x32_f16 v[44:47], v[128:131], v[196:199], v[44:47]
	v_mfma_f32_16x16x32_f16 v[40:43], v[136:139], v[196:199], v[40:43]
	v_mfma_f32_16x16x32_f16 v[28:31], v[128:131], v[204:207], v[28:31]
	v_mfma_f32_16x16x32_f16 v[24:27], v[136:139], v[204:207], v[24:27]
	v_mfma_f32_16x16x32_f16 v[12:15], v[128:131], v[212:215], v[12:15]
	v_mfma_f32_16x16x32_f16 v[8:11], v[136:139], v[212:215], v[8:11]
	v_mfma_f32_16x16x32_f16 v[60:63], v[132:135], v[192:195], v[60:63]
	v_mfma_f32_16x16x32_f16 v[56:59], v[140:143], v[192:195], v[56:59]
	v_mfma_f32_16x16x32_f16 v[44:47], v[132:135], v[200:203], v[44:47]
	v_mfma_f32_16x16x32_f16 v[40:43], v[140:143], v[200:203], v[40:43]
	v_mfma_f32_16x16x32_f16 v[28:31], v[132:135], v[208:211], v[28:31]
	v_mfma_f32_16x16x32_f16 v[24:27], v[140:143], v[208:211], v[24:27]
	v_mfma_f32_16x16x32_f16 v[12:15], v[132:135], v[216:219], v[12:15]
	v_mfma_f32_16x16x32_f16 v[8:11], v[140:143], v[216:219], v[8:11]
	s_setprio 0
	s_setprio 1
	v_mfma_f32_16x16x32_f16 v[52:55], v[144:147], v[188:191], v[52:55]
	v_mfma_f32_16x16x32_f16 v[48:51], v[152:155], v[188:191], v[48:51]
	v_mfma_f32_16x16x32_f16 v[36:39], v[144:147], v[196:199], v[36:39]
	v_mfma_f32_16x16x32_f16 v[32:35], v[152:155], v[196:199], v[32:35]
	v_mfma_f32_16x16x32_f16 v[20:23], v[144:147], v[204:207], v[20:23]
	v_mfma_f32_16x16x32_f16 v[16:19], v[152:155], v[204:207], v[16:19]
	v_mfma_f32_16x16x32_f16 v[4:7], v[144:147], v[212:215], v[4:7]
	v_mfma_f32_16x16x32_f16 v[0:3], v[152:155], v[212:215], v[0:3]
	v_mfma_f32_16x16x32_f16 v[52:55], v[148:151], v[192:195], v[52:55]
	v_mfma_f32_16x16x32_f16 v[48:51], v[174:177], v[192:195], v[48:51]
	v_mfma_f32_16x16x32_f16 v[36:39], v[148:151], v[200:203], v[36:39]
	v_mfma_f32_16x16x32_f16 v[32:35], v[174:177], v[200:203], v[32:35]
	s_barrier
	v_mfma_f32_16x16x32_f16 v[20:23], v[148:151], v[208:211], v[20:23]
	v_mfma_f32_16x16x32_f16 v[16:19], v[174:177], v[208:211], v[16:19]
	v_mfma_f32_16x16x32_f16 v[4:7], v[148:151], v[216:219], v[4:7]
	v_mfma_f32_16x16x32_f16 v[0:3], v[174:177], v[216:219], v[0:3]
	s_setprio 0
	s_add_i32 s53, 0, 0x18000
	s_add_i32 s54, 0, 0x1c000
	v_add_u32_e32 v140, s53, v182
	v_add_u32_e32 v165, s54, v182
	ds_read_b128 v[128:131], v140
	ds_read_b128 v[132:135], v140 offset:1024
	ds_read_b128 v[136:139], v140 offset:2048
	ds_read_b128 v[140:143], v140 offset:3072
	ds_read_b128 v[144:147], v165
	ds_read_b128 v[148:151], v165 offset:1024
	ds_read_b128 v[152:155], v165 offset:2048
	ds_read_b128 v[174:177], v165 offset:3072
	s_add_u32 s50, s50, 0x40000
	s_addc_u32 s51, s51, 0
	s_mov_b32 m0, s66
	v_lshl_add_u64 v[226:227], s[50:51], 0, v[156:157]
	ds_read_b128 v[188:191], v185 offset:32768
	ds_read_b128 v[192:195], v185 offset:33792
	ds_read_b128 v[196:199], v185 offset:34816
	ds_read_b128 v[200:203], v185 offset:35840
	ds_read_b128 v[204:207], v185 offset:36864
	ds_read_b128 v[208:211], v185 offset:37888
	ds_read_b128 v[212:215], v185 offset:38912
	ds_read_b128 v[216:219], v185 offset:39936
	global_load_lds_dwordx4 v[226:227], off
	v_lshl_add_u64 v[226:227], s[50:51], 0, v[160:161]
	s_mov_b32 m0, s67
	s_nop 0
	global_load_lds_dwordx4 v[226:227], off
	s_waitcnt vmcnt(8)
	s_waitcnt lgkmcnt(0)
	s_barrier
	s_setprio 1
	s_waitcnt lgkmcnt(0)
	v_mfma_f32_16x16x32_f16 v[124:127], v[128:131], v[188:191], v[124:127]
	v_mfma_f32_16x16x32_f16 v[120:123], v[136:139], v[188:191], v[120:123]
	v_mfma_f32_16x16x32_f16 v[108:111], v[128:131], v[196:199], v[108:111]
	v_mfma_f32_16x16x32_f16 v[104:107], v[136:139], v[196:199], v[104:107]
	v_mfma_f32_16x16x32_f16 v[92:95], v[128:131], v[204:207], v[92:95]
	v_mfma_f32_16x16x32_f16 v[88:91], v[136:139], v[204:207], v[88:91]
	v_mfma_f32_16x16x32_f16 v[76:79], v[128:131], v[212:215], v[76:79]
	v_mfma_f32_16x16x32_f16 v[72:75], v[136:139], v[212:215], v[72:75]
	v_mfma_f32_16x16x32_f16 v[124:127], v[132:135], v[192:195], v[124:127]
	v_mfma_f32_16x16x32_f16 v[120:123], v[140:143], v[192:195], v[120:123]
	v_mfma_f32_16x16x32_f16 v[108:111], v[132:135], v[200:203], v[108:111]
	v_mfma_f32_16x16x32_f16 v[104:107], v[140:143], v[200:203], v[104:107]
	v_mfma_f32_16x16x32_f16 v[92:95], v[132:135], v[208:211], v[92:95]
	v_mfma_f32_16x16x32_f16 v[88:91], v[140:143], v[208:211], v[88:91]
	v_mfma_f32_16x16x32_f16 v[76:79], v[132:135], v[216:219], v[76:79]
	v_mfma_f32_16x16x32_f16 v[72:75], v[140:143], v[216:219], v[72:75]
	s_setprio 0
	s_setprio 1
	v_mfma_f32_16x16x32_f16 v[116:119], v[144:147], v[188:191], v[116:119]
	v_mfma_f32_16x16x32_f16 v[112:115], v[152:155], v[188:191], v[112:115]
	v_mfma_f32_16x16x32_f16 v[100:103], v[144:147], v[196:199], v[100:103]
	v_mfma_f32_16x16x32_f16 v[96:99], v[152:155], v[196:199], v[96:99]
	v_mfma_f32_16x16x32_f16 v[84:87], v[144:147], v[204:207], v[84:87]
	v_mfma_f32_16x16x32_f16 v[80:83], v[152:155], v[204:207], v[80:83]
	v_mfma_f32_16x16x32_f16 v[68:71], v[144:147], v[212:215], v[68:71]
	v_mfma_f32_16x16x32_f16 v[64:67], v[152:155], v[212:215], v[64:67]
	v_mfma_f32_16x16x32_f16 v[116:119], v[148:151], v[192:195], v[116:119]
	v_mfma_f32_16x16x32_f16 v[112:115], v[174:177], v[192:195], v[112:115]
	v_mfma_f32_16x16x32_f16 v[100:103], v[148:151], v[200:203], v[100:103]
	v_mfma_f32_16x16x32_f16 v[96:99], v[174:177], v[200:203], v[96:99]
	s_barrier
; #define PG8_STAGE(bufoff, gbase, voff) do { _Pragma("unroll") for (int _i = 0; _i < 2; ++_i) \
;         __builtin_amdgcn_global_load_lds((const unsigned*)((const char*)(gbase) + (voff)[_i]), (PG8_LAS unsigned*)(lds + (bufoff) + ldsw + _i * 8192), 16, 0, 0); } while (0)
; #define PG8_LDA(dst, b, h) do { _Pragma("unroll") for (int m = 0; m < 4; ++m) _Pragma("unroll") for (int k = 0; k < 2; ++k) dst[m][k] = *(const PG8_LAS bf16x8*)(lds + PG8_SA(b, h) + aoff + m * 2048 + k * 1024); } while (0)
; #define PG8_MMA(ai, bj, At, Bt) do { __builtin_amdgcn_s_setprio(1); _Pragma("unroll") for (int m = 0; m < 4; ++m) _Pragma("unroll") for (int n = 0; n < 2; ++n) _Pragma("unroll") for (int k = 0; k < 2; ++k) \
;         acc[ai][bj][m][n] = mma16<F16>(Bt[n][k], At[m][k], acc[ai][bj][m][n]); __builtin_amdgcn_s_setprio(0); } while (0)
; #define PG8_WAIT_V(n) asm volatile("s_waitcnt vmcnt(" #n ")" ::: "memory")
; #define PG8_WAIT_L(n) asm volatile("s_waitcnt lgkmcnt(" #n ")" ::: "memory")
; #define PG8_BAR __builtin_amdgcn_s_barrier()
; #define PG8_SCHED __builtin_amdgcn_sched_barrier(0)
; template <class Epi, class Sched, bool ALIGN_EPI = false, bool SP2 = false, bool F16 = false>
; __device__ __forceinline__ void gemm_phase(PG8_LAS unsigned char* lds, const Gemm g, const Sched& S, const Epi& E, const int wid_in) {
;     ...
;             PG8_WAIT_V(8); PG8_WAIT_L(0); PG8_BAR; PG8_MMA(0, 0, At, B0); PG8_MMA(0, 1, At, B1); PG8_BAR; PG8_SCHED;
;             PG8_LDA(At, 1, 1); PG8_STAGE(PG8_SB(1, 0), b3, voffB); PG8_STAGE(PG8_SB(1, 1), b3 + hstep, voffB); PG8_STAGE(PG8_SA(1, 0), a3, voffA);
;             PG8_WAIT_V(8); PG8_WAIT_L(0); PG8_BAR; PG8_MMA(1, 0, At, B0); PG8_MMA(1, 1, At, B1); PG8_BAR; PG8_SCHED;
;     ...
;         if constexpr (ALIGN_EPI) { if (wr == 0) PG8_BAR; }
	v_mfma_f32_16x16x32_f16 v[84:87], v[148:151], v[208:211], v[84:87]
	v_mfma_f32_16x16x32_f16 v[80:83], v[174:177], v[208:211], v[80:83]
	v_mfma_f32_16x16x32_f16 v[68:71], v[148:151], v[216:219], v[68:71]
	v_mfma_f32_16x16x32_f16 v[64:67], v[174:177], v[216:219], v[64:67]
	s_setprio 0
	s_add_i32 s50, s53, s68
	v_lshl_add_u64 v[178:179], v[178:179], 0, s[20:21]
	s_mov_b32 m0, s50
	ds_read_b128 v[188:191], v185 offset:49152
	ds_read_b128 v[192:195], v185 offset:50176
	ds_read_b128 v[196:199], v185 offset:51200
	ds_read_b128 v[200:203], v185 offset:52224
	ds_read_b128 v[204:207], v185 offset:53248
	ds_read_b128 v[208:211], v185 offset:54272
	ds_read_b128 v[212:215], v185 offset:55296
	ds_read_b128 v[216:219], v185 offset:56320
	global_load_lds_dwordx4 v[178:179], off
	s_add_i32 m0, s50, 0x2000
	s_add_u32 s48, s48, 0x40080
	v_lshl_add_u64 v[178:179], v[220:221], 0, s[20:21]
	s_addc_u32 s49, s49, 0
	s_add_i32 s50, s54, s68
	global_load_lds_dwordx4 v[178:179], off
	v_lshl_add_u64 v[178:179], s[48:49], 0, v[158:159]
	s_mov_b32 m0, s50
	s_nop 0
	global_load_lds_dwordx4 v[178:179], off
	v_lshl_add_u64 v[178:179], s[48:49], 0, v[162:163]
	s_add_i32 m0, s50, 0x2000
	s_nop 0
	global_load_lds_dwordx4 v[178:179], off
	v_lshl_add_u64 v[178:179], v[222:223], 0, s[20:21]
	s_mov_b32 m0, s75
	s_nop 0
	global_load_lds_dwordx4 v[178:179], off
	v_lshl_add_u64 v[178:179], v[224:225], 0, s[20:21]
	s_mov_b32 m0, s89
	s_nop 0
	global_load_lds_dwordx4 v[178:179], off
	s_waitcnt vmcnt(8)
	s_waitcnt lgkmcnt(0)
	s_barrier
	s_setprio 1
	s_waitcnt lgkmcnt(0)
	v_mfma_f32_16x16x32_f16 v[60:63], v[128:131], v[188:191], v[60:63]
	v_mfma_f32_16x16x32_f16 v[56:59], v[136:139], v[188:191], v[56:59]
	v_mfma_f32_16x16x32_f16 v[44:47], v[128:131], v[196:199], v[44:47]
	v_mfma_f32_16x16x32_f16 v[40:43], v[136:139], v[196:199], v[40:43]
	v_mfma_f32_16x16x32_f16 v[28:31], v[128:131], v[204:207], v[28:31]
	v_mfma_f32_16x16x32_f16 v[24:27], v[136:139], v[204:207], v[24:27]
	v_mfma_f32_16x16x32_f16 v[12:15], v[128:131], v[212:215], v[12:15]
	v_mfma_f32_16x16x32_f16 v[8:11], v[136:139], v[212:215], v[8:11]
	v_mfma_f32_16x16x32_f16 v[60:63], v[132:135], v[192:195], v[60:63]
	v_mfma_f32_16x16x32_f16 v[56:59], v[140:143], v[192:195], v[56:59]
	v_mfma_f32_16x16x32_f16 v[44:47], v[132:135], v[200:203], v[44:47]
	v_mfma_f32_16x16x32_f16 v[40:43], v[140:143], v[200:203], v[40:43]
	v_mfma_f32_16x16x32_f16 v[28:31], v[132:135], v[208:211], v[28:31]
	v_mfma_f32_16x16x32_f16 v[24:27], v[140:143], v[208:211], v[24:27]
	v_mfma_f32_16x16x32_f16 v[12:15], v[132:135], v[216:219], v[12:15]
	v_mfma_f32_16x16x32_f16 v[8:11], v[140:143], v[216:219], v[8:11]
	s_setprio 0
	s_setprio 1
	v_mfma_f32_16x16x32_f16 v[52:55], v[144:147], v[188:191], v[52:55]
	v_mfma_f32_16x16x32_f16 v[48:51], v[152:155], v[188:191], v[48:51]
	v_mfma_f32_16x16x32_f16 v[36:39], v[144:147], v[196:199], v[36:39]
	v_mfma_f32_16x16x32_f16 v[32:35], v[152:155], v[196:199], v[32:35]
	v_mfma_f32_16x16x32_f16 v[20:23], v[144:147], v[204:207], v[20:23]
	v_mfma_f32_16x16x32_f16 v[16:19], v[152:155], v[204:207], v[16:19]
	v_mfma_f32_16x16x32_f16 v[4:7], v[144:147], v[212:215], v[4:7]
	v_mfma_f32_16x16x32_f16 v[0:3], v[152:155], v[212:215], v[0:3]
	v_mfma_f32_16x16x32_f16 v[52:55], v[148:151], v[192:195], v[52:55]
	v_mfma_f32_16x16x32_f16 v[48:51], v[174:177], v[192:195], v[48:51]
	v_mfma_f32_16x16x32_f16 v[36:39], v[148:151], v[200:203], v[36:39]
	v_mfma_f32_16x16x32_f16 v[32:35], v[174:177], v[200:203], v[32:35]
	s_barrier
	v_mfma_f32_16x16x32_f16 v[20:23], v[148:151], v[208:211], v[20:23]
	v_mfma_f32_16x16x32_f16 v[16:19], v[174:177], v[208:211], v[16:19]
	v_mfma_f32_16x16x32_f16 v[4:7], v[148:151], v[216:219], v[4:7]
	v_mfma_f32_16x16x32_f16 v[0:3], v[174:177], v[216:219], v[0:3]
	s_setprio 0
	s_add_i32 s52, s52, 2
	s_add_u32 s46, s46, 0x100
	s_addc_u32 s47, s47, 0
	s_add_u32 s42, s42, 0x100
	s_addc_u32 s43, s43, 0
	s_cmp_gt_u32 s52, 13
	s_cbranch_scc0 .LBB0_902
	s_and_b64 vcc, exec, s[16:17]
	s_cbranch_vccz .LBB0_905
	s_barrier

; #define PG8_STAGE(bufoff, gbase, voff) do { _Pragma("unroll") for (int _i = 0; _i < 2; ++_i) \
;         __builtin_amdgcn_global_load_lds((const unsigned*)((const char*)(gbase) + (voff)[_i]), (PG8_LAS unsigned*)(lds + (bufoff) + ldsw + _i * 8192), 16, 0, 0); } while (0)
; #define PG8_LDA(dst, b, h) do { _Pragma("unroll") for (int m = 0; m < 4; ++m) _Pragma("unroll") for (int k = 0; k < 2; ++k) dst[m][k] = *(const PG8_LAS bf16x8*)(lds + PG8_SA(b, h) + aoff + m * 2048 + k * 1024); } while (0)
; #define PG8_LDB(dst, b, h) do { _Pragma("unroll") for (int n = 0; n < 2; ++n) _Pragma("unroll") for (int k = 0; k < 2; ++k) dst[n][k] = *(const PG8_LAS bf16x8*)(lds + PG8_SB(b, h) + boff + n * 2048 + k * 1024); } while (0)
; #define PG8_MMA(ai, bj, At, Bt) do { __builtin_amdgcn_s_setprio(1); _Pragma("unroll") for (int m = 0; m < 4; ++m) _Pragma("unroll") for (int n = 0; n < 2; ++n) _Pragma("unroll") for (int k = 0; k < 2; ++k) \
;         acc[ai][bj][m][n] = mma16<F16>(Bt[n][k], At[m][k], acc[ai][bj][m][n]); __builtin_amdgcn_s_setprio(0); } while (0)
; #define PG8_WAIT_V(n) asm volatile("s_waitcnt vmcnt(" #n ")" ::: "memory")
; #define PG8_WAIT_L(n) asm volatile("s_waitcnt lgkmcnt(" #n ")" ::: "memory")
; template <class Epi, class Sched, bool ALIGN_EPI = false, bool SP2 = false, bool F16 = false>
; __device__ __forceinline__ void gemm_phase(PG8_LAS unsigned char* lds, const Gemm g, const Sched& S, const Epi& E, const int wid_in) {
;     ...
;             const bool last = (t == nt - 2);
;             const char* a1 = cA + (size_t)(t + 1) * kstep;
;             const char* a2 = last ? nA : cA + (size_t)(t + 2) * kstep; const char* b2 = last ? nB : cB + (size_t)(t + 2) * kstep;
;             const char* a3 = a2 + kstep; const char* b3 = b2 + kstep;
;             if (last && has_next) S.a_ready(nxt);
;             if constexpr (SP2) {
;             PG8_LDB(B0, 0, 0); PG8_LDB(B1, 0, 1); PG8_SCHED; PG8_LDA(At, 0, 0); PG8_STAGE(PG8_SA(1, 1), a1 + hstep, voffA);
;             PG8_WAIT_V(8); PG8_WAIT_L(0); PG8_BAR; PG8_MMA(0, 0, At, B0); PG8_MMA(0, 1, At, B1); PG8_BAR; PG8_SCHED;
;             PG8_LDA(At, 0, 1); PG8_STAGE(PG8_SB(0, 0), b2, voffB); PG8_STAGE(PG8_SB(0, 1), b2 + hstep, voffB); PG8_STAGE(PG8_SA(0, 0), a2, voffA);
;             PG8_WAIT_V(8); PG8_WAIT_L(0); PG8_BAR; PG8_MMA(1, 0, At, B0); PG8_MMA(1, 1, At, B1); PG8_BAR; PG8_SCHED;
.LBB0_1165:
	ds_read_b128 v[128:131], v189
	ds_read_b128 v[132:135], v189 offset:1024
	ds_read_b128 v[136:139], v189 offset:2048
	ds_read_b128 v[140:143], v189 offset:3072
	ds_read_b128 v[144:147], v190
	ds_read_b128 v[148:151], v190 offset:1024
	ds_read_b128 v[168:171], v190 offset:2048
	ds_read_b128 v[172:175], v190 offset:3072
	s_add_u32 s50, s48, 0xfffc0080
	s_addc_u32 s51, s49, -1
	s_cmp_eq_u32 s64, 12
	s_cselect_b32 s53, s35, s51
	s_cselect_b32 s52, s42, s50
	s_cselect_b32 s51, s31, s63
	s_cselect_b32 s50, s43, s47
	v_lshl_add_u64 v[184:185], s[48:49], 0, v[160:161]
	s_add_i32 m0, s74, 0xc000
	ds_read_b128 v[176:179], v191
	ds_read_b128 v[180:183], v191 offset:1024
	ds_read_b128 v[192:195], v191 offset:2048
	ds_read_b128 v[196:199], v191 offset:3072
	ds_read_b128 v[200:203], v191 offset:4096
	ds_read_b128 v[204:207], v191 offset:5120
	ds_read_b128 v[208:211], v191 offset:6144
	ds_read_b128 v[212:215], v191 offset:7168
	global_load_lds_dwordx4 v[184:185], off
	v_lshl_add_u64 v[184:185], s[48:49], 0, v[162:163]
	s_add_i32 m0, s74, 0xe000
	s_nop 0
	global_load_lds_dwordx4 v[184:185], off
	s_waitcnt vmcnt(8)
	s_waitcnt lgkmcnt(0)
	s_barrier
	s_setprio 1
	s_waitcnt lgkmcnt(0)
	v_mfma_f32_16x16x32_bf16 v[124:127], v[128:131], v[176:179], v[124:127]
	v_mfma_f32_16x16x32_bf16 v[120:123], v[136:139], v[176:179], v[120:123]
	v_mfma_f32_16x16x32_bf16 v[108:111], v[128:131], v[192:195], v[108:111]
	v_mfma_f32_16x16x32_bf16 v[104:107], v[136:139], v[192:195], v[104:107]
	v_mfma_f32_16x16x32_bf16 v[92:95], v[128:131], v[200:203], v[92:95]
	v_mfma_f32_16x16x32_bf16 v[88:91], v[136:139], v[200:203], v[88:91]
	v_mfma_f32_16x16x32_bf16 v[76:79], v[128:131], v[208:211], v[76:79]
	v_mfma_f32_16x16x32_bf16 v[72:75], v[136:139], v[208:211], v[72:75]
	v_mfma_f32_16x16x32_bf16 v[124:127], v[132:135], v[180:183], v[124:127]
	v_mfma_f32_16x16x32_bf16 v[120:123], v[140:143], v[180:183], v[120:123]
	v_mfma_f32_16x16x32_bf16 v[108:111], v[132:135], v[196:199], v[108:111]
	v_mfma_f32_16x16x32_bf16 v[104:107], v[140:143], v[196:199], v[104:107]
	v_mfma_f32_16x16x32_bf16 v[92:95], v[132:135], v[204:207], v[92:95]
	v_mfma_f32_16x16x32_bf16 v[88:91], v[140:143], v[204:207], v[88:91]
	v_mfma_f32_16x16x32_bf16 v[76:79], v[132:135], v[212:215], v[76:79]
	v_mfma_f32_16x16x32_bf16 v[72:75], v[140:143], v[212:215], v[72:75]
	s_setprio 0
	s_setprio 1
	v_mfma_f32_16x16x32_bf16 v[116:119], v[144:147], v[176:179], v[116:119]
	v_mfma_f32_16x16x32_bf16 v[112:115], v[168:171], v[176:179], v[112:115]
	v_mfma_f32_16x16x32_bf16 v[100:103], v[144:147], v[192:195], v[100:103]
	v_mfma_f32_16x16x32_bf16 v[96:99], v[168:171], v[192:195], v[96:99]
	v_mfma_f32_16x16x32_bf16 v[84:87], v[144:147], v[200:203], v[84:87]
	v_mfma_f32_16x16x32_bf16 v[80:83], v[168:171], v[200:203], v[80:83]
	v_mfma_f32_16x16x32_bf16 v[68:71], v[144:147], v[208:211], v[68:71]
	v_mfma_f32_16x16x32_bf16 v[64:67], v[168:171], v[208:211], v[64:67]
	v_mfma_f32_16x16x32_bf16 v[116:119], v[148:151], v[180:183], v[116:119]
	v_mfma_f32_16x16x32_bf16 v[112:115], v[172:175], v[180:183], v[112:115]
	v_mfma_f32_16x16x32_bf16 v[100:103], v[148:151], v[196:199], v[100:103]
	v_mfma_f32_16x16x32_bf16 v[96:99], v[172:175], v[196:199], v[96:99]
	s_barrier
	v_mfma_f32_16x16x32_bf16 v[84:87], v[148:151], v[204:207], v[84:87]
	v_mfma_f32_16x16x32_bf16 v[80:83], v[172:175], v[204:207], v[80:83]
	v_mfma_f32_16x16x32_bf16 v[68:71], v[148:151], v[212:215], v[68:71]
	v_mfma_f32_16x16x32_bf16 v[64:67], v[172:175], v[212:215], v[64:67]
	s_setprio 0
	s_add_i32 s65, s60, s68
	v_lshl_add_u64 v[184:185], s[50:51], 0, v[154:155]
	s_mov_b32 m0, s65
	ds_read_b128 v[176:179], v191 offset:16384
	ds_read_b128 v[180:183], v191 offset:17408
	ds_read_b128 v[192:195], v191 offset:18432
	ds_read_b128 v[196:199], v191 offset:19456
	ds_read_b128 v[200:203], v191 offset:20480
	ds_read_b128 v[204:207], v191 offset:21504
	ds_read_b128 v[208:211], v191 offset:22528
	ds_read_b128 v[212:215], v191 offset:23552
	global_load_lds_dwordx4 v[184:185], off
	s_add_i32 m0, s65, 0x2000
	s_add_u32 s66, s50, 0x40000
	v_lshl_add_u64 v[216:217], s[50:51], 0, v[158:159]
	s_addc_u32 s67, s51, 0
	s_add_i32 s65, s61, s68
	global_load_lds_dwordx4 v[216:217], off
	v_lshl_add_u64 v[218:219], s[66:67], 0, v[154:155]
	s_mov_b32 m0, s65
	v_lshl_add_u64 v[220:221], s[52:53], 0, v[156:157]
	global_load_lds_dwordx4 v[218:219], off
	v_lshl_add_u64 v[218:219], s[66:67], 0, v[158:159]
	s_add_i32 m0, s65, 0x2000
	s_nop 0
	global_load_lds_dwordx4 v[218:219], off
	v_lshl_add_u64 v[218:219], s[52:53], 0, v[152:153]
	s_mov_b32 m0, s74
	s_nop 0
	global_load_lds_dwordx4 v[218:219], off
	s_mov_b32 m0, s41
	s_nop 0
	global_load_lds_dwordx4 v[220:221], off
	s_waitcnt vmcnt(8)
	s_waitcnt lgkmcnt(0)
	s_barrier
; #define PG8_STAGE(bufoff, gbase, voff) do { _Pragma("unroll") for (int _i = 0; _i < 2; ++_i) \
;         __builtin_amdgcn_global_load_lds((const unsigned*)((const char*)(gbase) + (voff)[_i]), (PG8_LAS unsigned*)(lds + (bufoff) + ldsw + _i * 8192), 16, 0, 0); } while (0)
; #define PG8_LDA(dst, b, h) do { _Pragma("unroll") for (int m = 0; m < 4; ++m) _Pragma("unroll") for (int k = 0; k < 2; ++k) dst[m][k] = *(const PG8_LAS bf16x8*)(lds + PG8_SA(b, h) + aoff + m * 2048 + k * 1024); } while (0)
; #define PG8_LDB(dst, b, h) do { _Pragma("unroll") for (int n = 0; n < 2; ++n) _Pragma("unroll") for (int k = 0; k < 2; ++k) dst[n][k] = *(const PG8_LAS bf16x8*)(lds + PG8_SB(b, h) + boff + n * 2048 + k * 1024); } while (0)
; #define PG8_MMA(ai, bj, At, Bt) do { __builtin_amdgcn_s_setprio(1); _Pragma("unroll") for (int m = 0; m < 4; ++m) _Pragma("unroll") for (int n = 0; n < 2; ++n) _Pragma("unroll") for (int k = 0; k < 2; ++k) \
;         acc[ai][bj][m][n] = mma16<F16>(Bt[n][k], At[m][k], acc[ai][bj][m][n]); __builtin_amdgcn_s_setprio(0); } while (0)
; #define PG8_WAIT_V(n) asm volatile("s_waitcnt vmcnt(" #n ")" ::: "memory")
; #define PG8_WAIT_L(n) asm volatile("s_waitcnt lgkmcnt(" #n ")" ::: "memory")
; #define PG8_BAR __builtin_amdgcn_s_barrier()
; #define PG8_SCHED __builtin_amdgcn_sched_barrier(0)
; template <class Epi, class Sched, bool ALIGN_EPI = false, bool SP2 = false, bool F16 = false>
; __device__ __forceinline__ void gemm_phase(PG8_LAS unsigned char* lds, const Gemm g, const Sched& S, const Epi& E, const int wid_in) {
;     ...
;             PG8_WAIT_V(8); PG8_WAIT_L(0); PG8_BAR; PG8_MMA(1, 0, At, B0); PG8_MMA(1, 1, At, B1); PG8_BAR; PG8_SCHED;
;             PG8_LDB(B0, 1, 0); PG8_LDB(B1, 1, 1); PG8_SCHED; PG8_LDA(At, 1, 0); PG8_STAGE(PG8_SA(0, 1), a2 + hstep, voffA);
;             PG8_WAIT_V(8); PG8_WAIT_L(0); PG8_BAR; PG8_MMA(0, 0, At, B0); PG8_MMA(0, 1, At, B1); PG8_BAR; PG8_SCHED;
	s_setprio 1
	s_waitcnt lgkmcnt(0)
	v_mfma_f32_16x16x32_bf16 v[60:63], v[128:131], v[176:179], v[60:63]
	v_mfma_f32_16x16x32_bf16 v[56:59], v[136:139], v[176:179], v[56:59]
	v_mfma_f32_16x16x32_bf16 v[44:47], v[128:131], v[192:195], v[44:47]
	v_mfma_f32_16x16x32_bf16 v[40:43], v[136:139], v[192:195], v[40:43]
	v_mfma_f32_16x16x32_bf16 v[28:31], v[128:131], v[200:203], v[28:31]
	v_mfma_f32_16x16x32_bf16 v[24:27], v[136:139], v[200:203], v[24:27]
	v_mfma_f32_16x16x32_bf16 v[12:15], v[128:131], v[208:211], v[12:15]
	v_mfma_f32_16x16x32_bf16 v[8:11], v[136:139], v[208:211], v[8:11]
	v_mfma_f32_16x16x32_bf16 v[60:63], v[132:135], v[180:183], v[60:63]
	v_mfma_f32_16x16x32_bf16 v[56:59], v[140:143], v[180:183], v[56:59]
	v_mfma_f32_16x16x32_bf16 v[44:47], v[132:135], v[196:199], v[44:47]
	v_mfma_f32_16x16x32_bf16 v[40:43], v[140:143], v[196:199], v[40:43]
	v_mfma_f32_16x16x32_bf16 v[28:31], v[132:135], v[204:207], v[28:31]
	v_mfma_f32_16x16x32_bf16 v[24:27], v[140:143], v[204:207], v[24:27]
	v_mfma_f32_16x16x32_bf16 v[12:15], v[132:135], v[212:215], v[12:15]
	v_mfma_f32_16x16x32_bf16 v[8:11], v[140:143], v[212:215], v[8:11]
	s_setprio 0
	s_setprio 1
	v_mfma_f32_16x16x32_bf16 v[52:55], v[144:147], v[176:179], v[52:55]
	v_mfma_f32_16x16x32_bf16 v[48:51], v[168:171], v[176:179], v[48:51]
	v_mfma_f32_16x16x32_bf16 v[36:39], v[144:147], v[192:195], v[36:39]
	v_mfma_f32_16x16x32_bf16 v[32:35], v[168:171], v[192:195], v[32:35]
	v_mfma_f32_16x16x32_bf16 v[20:23], v[144:147], v[200:203], v[20:23]
	v_mfma_f32_16x16x32_bf16 v[16:19], v[168:171], v[200:203], v[16:19]
	v_mfma_f32_16x16x32_bf16 v[4:7], v[144:147], v[208:211], v[4:7]
	v_mfma_f32_16x16x32_bf16 v[0:3], v[168:171], v[208:211], v[0:3]
	v_mfma_f32_16x16x32_bf16 v[52:55], v[148:151], v[180:183], v[52:55]
	v_mfma_f32_16x16x32_bf16 v[48:51], v[172:175], v[180:183], v[48:51]
	v_mfma_f32_16x16x32_bf16 v[36:39], v[148:151], v[196:199], v[36:39]
	v_mfma_f32_16x16x32_bf16 v[32:35], v[172:175], v[196:199], v[32:35]
	s_barrier
	v_mfma_f32_16x16x32_bf16 v[20:23], v[148:151], v[204:207], v[20:23]
	v_mfma_f32_16x16x32_bf16 v[16:19], v[172:175], v[204:207], v[16:19]
	v_mfma_f32_16x16x32_bf16 v[4:7], v[148:151], v[212:215], v[4:7]
	v_mfma_f32_16x16x32_bf16 v[0:3], v[172:175], v[212:215], v[0:3]
	s_setprio 0
	s_add_i32 s65, 0, 0x18000
	s_add_i32 s66, 0, 0x1c000
	v_add_u32_e32 v140, s65, v188
	v_add_u32_e32 v172, s66, v188
	ds_read_b128 v[128:131], v140
	ds_read_b128 v[132:135], v140 offset:1024
	ds_read_b128 v[136:139], v140 offset:2048
	ds_read_b128 v[140:143], v140 offset:3072
	ds_read_b128 v[144:147], v172
	ds_read_b128 v[148:151], v172 offset:1024
	ds_read_b128 v[168:171], v172 offset:2048
	ds_read_b128 v[172:175], v172 offset:3072
	s_add_u32 s52, s52, 0x40000
	s_addc_u32 s53, s53, 0
	s_mov_b32 m0, s54
	v_lshl_add_u64 v[222:223], s[52:53], 0, v[152:153]
	ds_read_b128 v[176:179], v191 offset:32768
	ds_read_b128 v[180:183], v191 offset:33792
	ds_read_b128 v[192:195], v191 offset:34816
	ds_read_b128 v[196:199], v191 offset:35840
	ds_read_b128 v[200:203], v191 offset:36864
	ds_read_b128 v[204:207], v191 offset:37888
	ds_read_b128 v[208:211], v191 offset:38912
	ds_read_b128 v[212:215], v191 offset:39936
	global_load_lds_dwordx4 v[222:223], off
	v_lshl_add_u64 v[222:223], s[52:53], 0, v[156:157]
	s_mov_b32 m0, s55
	s_nop 0
	global_load_lds_dwordx4 v[222:223], off
	s_waitcnt vmcnt(8)
	s_waitcnt lgkmcnt(0)
	s_barrier
	s_setprio 1
	s_waitcnt lgkmcnt(0)
	v_mfma_f32_16x16x32_bf16 v[124:127], v[128:131], v[176:179], v[124:127]
	v_mfma_f32_16x16x32_bf16 v[120:123], v[136:139], v[176:179], v[120:123]
	v_mfma_f32_16x16x32_bf16 v[108:111], v[128:131], v[192:195], v[108:111]
	v_mfma_f32_16x16x32_bf16 v[104:107], v[136:139], v[192:195], v[104:107]
	v_mfma_f32_16x16x32_bf16 v[92:95], v[128:131], v[200:203], v[92:95]
	v_mfma_f32_16x16x32_bf16 v[88:91], v[136:139], v[200:203], v[88:91]
	v_mfma_f32_16x16x32_bf16 v[76:79], v[128:131], v[208:211], v[76:79]
	v_mfma_f32_16x16x32_bf16 v[72:75], v[136:139], v[208:211], v[72:75]
	v_mfma_f32_16x16x32_bf16 v[124:127], v[132:135], v[180:183], v[124:127]
	v_mfma_f32_16x16x32_bf16 v[120:123], v[140:143], v[180:183], v[120:123]
	v_mfma_f32_16x16x32_bf16 v[108:111], v[132:135], v[196:199], v[108:111]
	v_mfma_f32_16x16x32_bf16 v[104:107], v[140:143], v[196:199], v[104:107]
	v_mfma_f32_16x16x32_bf16 v[92:95], v[132:135], v[204:207], v[92:95]
	v_mfma_f32_16x16x32_bf16 v[88:91], v[140:143], v[204:207], v[88:91]
	v_mfma_f32_16x16x32_bf16 v[76:79], v[132:135], v[212:215], v[76:79]
	v_mfma_f32_16x16x32_bf16 v[72:75], v[140:143], v[212:215], v[72:75]
	s_setprio 0
	s_setprio 1
	v_mfma_f32_16x16x32_bf16 v[116:119], v[144:147], v[176:179], v[116:119]
	v_mfma_f32_16x16x32_bf16 v[112:115], v[168:171], v[176:179], v[112:115]
	v_mfma_f32_16x16x32_bf16 v[100:103], v[144:147], v[192:195], v[100:103]
	v_mfma_f32_16x16x32_bf16 v[96:99], v[168:171], v[192:195], v[96:99]
	v_mfma_f32_16x16x32_bf16 v[84:87], v[144:147], v[200:203], v[84:87]
	v_mfma_f32_16x16x32_bf16 v[80:83], v[168:171], v[200:203], v[80:83]
	v_mfma_f32_16x16x32_bf16 v[68:71], v[144:147], v[208:211], v[68:71]
	v_mfma_f32_16x16x32_bf16 v[64:67], v[168:171], v[208:211], v[64:67]
	v_mfma_f32_16x16x32_bf16 v[116:119], v[148:151], v[180:183], v[116:119]
	v_mfma_f32_16x16x32_bf16 v[112:115], v[172:175], v[180:183], v[112:115]
	v_mfma_f32_16x16x32_bf16 v[100:103], v[148:151], v[196:199], v[100:103]
	v_mfma_f32_16x16x32_bf16 v[96:99], v[172:175], v[196:199], v[96:99]
	s_barrier
; #define PG8_STAGE(bufoff, gbase, voff) do { _Pragma("unroll") for (int _i = 0; _i < 2; ++_i) \
;         __builtin_amdgcn_global_load_lds((const unsigned*)((const char*)(gbase) + (voff)[_i]), (PG8_LAS unsigned*)(lds + (bufoff) + ldsw + _i * 8192), 16, 0, 0); } while (0)
; #define PG8_LDA(dst, b, h) do { _Pragma("unroll") for (int m = 0; m < 4; ++m) _Pragma("unroll") for (int k = 0; k < 2; ++k) dst[m][k] = *(const PG8_LAS bf16x8*)(lds + PG8_SA(b, h) + aoff + m * 2048 + k * 1024); } while (0)
; #define PG8_MMA(ai, bj, At, Bt) do { __builtin_amdgcn_s_setprio(1); _Pragma("unroll") for (int m = 0; m < 4; ++m) _Pragma("unroll") for (int n = 0; n < 2; ++n) _Pragma("unroll") for (int k = 0; k < 2; ++k) \
;         acc[ai][bj][m][n] = mma16<F16>(Bt[n][k], At[m][k], acc[ai][bj][m][n]); __builtin_amdgcn_s_setprio(0); } while (0)
; #define PG8_WAIT_V(n) asm volatile("s_waitcnt vmcnt(" #n ")" ::: "memory")
; #define PG8_WAIT_L(n) asm volatile("s_waitcnt lgkmcnt(" #n ")" ::: "memory")
; #define PG8_BAR __builtin_amdgcn_s_barrier()
; #define PG8_SCHED __builtin_amdgcn_sched_barrier(0)
; template <class Epi, class Sched, bool ALIGN_EPI = false, bool SP2 = false, bool F16 = false>
; __device__ __forceinline__ void gemm_phase(PG8_LAS unsigned char* lds, const Gemm g, const Sched& S, const Epi& E, const int wid_in) {
;     ...
;             PG8_WAIT_V(8); PG8_WAIT_L(0); PG8_BAR; PG8_MMA(0, 0, At, B0); PG8_MMA(0, 1, At, B1); PG8_BAR; PG8_SCHED;
;             PG8_LDA(At, 1, 1); PG8_STAGE(PG8_SB(1, 0), b3, voffB); PG8_STAGE(PG8_SB(1, 1), b3 + hstep, voffB); PG8_STAGE(PG8_SA(1, 0), a3, voffA);
;             PG8_WAIT_V(8); PG8_WAIT_L(0); PG8_BAR; PG8_MMA(1, 0, At, B0); PG8_MMA(1, 1, At, B1); PG8_BAR; PG8_SCHED;
;     ...
;         if constexpr (ALIGN_EPI) { if (wr == 0) PG8_BAR; }
	v_mfma_f32_16x16x32_bf16 v[84:87], v[148:151], v[204:207], v[84:87]
	v_mfma_f32_16x16x32_bf16 v[80:83], v[172:175], v[204:207], v[80:83]
	v_mfma_f32_16x16x32_bf16 v[68:71], v[148:151], v[212:215], v[68:71]
	v_mfma_f32_16x16x32_bf16 v[64:67], v[172:175], v[212:215], v[64:67]
	s_setprio 0
	s_add_i32 s52, s65, s68
	v_lshl_add_u64 v[184:185], v[184:185], 0, s[28:29]
	s_mov_b32 m0, s52
	ds_read_b128 v[176:179], v191 offset:49152
	ds_read_b128 v[180:183], v191 offset:50176
	ds_read_b128 v[192:195], v191 offset:51200
	ds_read_b128 v[196:199], v191 offset:52224
	ds_read_b128 v[200:203], v191 offset:53248
	ds_read_b128 v[204:207], v191 offset:54272
	ds_read_b128 v[208:211], v191 offset:55296
	ds_read_b128 v[212:215], v191 offset:56320
	global_load_lds_dwordx4 v[184:185], off
	s_add_i32 m0, s52, 0x2000
	s_add_u32 s50, s50, 0x40080
	v_lshl_add_u64 v[184:185], v[216:217], 0, s[28:29]
	s_addc_u32 s51, s51, 0
	s_add_i32 s52, s66, s68
	global_load_lds_dwordx4 v[184:185], off
	v_lshl_add_u64 v[184:185], s[50:51], 0, v[154:155]
	s_mov_b32 m0, s52
	s_nop 0
	global_load_lds_dwordx4 v[184:185], off
	v_lshl_add_u64 v[184:185], s[50:51], 0, v[158:159]
	s_add_i32 m0, s52, 0x2000
	s_nop 0
	global_load_lds_dwordx4 v[184:185], off
	v_lshl_add_u64 v[184:185], v[218:219], 0, s[28:29]
	s_mov_b32 m0, s75
	s_nop 0
	global_load_lds_dwordx4 v[184:185], off
	v_lshl_add_u64 v[184:185], v[220:221], 0, s[28:29]
	s_mov_b32 m0, s56
	s_nop 0
	global_load_lds_dwordx4 v[184:185], off
	s_waitcnt vmcnt(8)
	s_waitcnt lgkmcnt(0)
	s_barrier
	s_setprio 1
	s_waitcnt lgkmcnt(0)
	v_mfma_f32_16x16x32_bf16 v[60:63], v[128:131], v[176:179], v[60:63]
	v_mfma_f32_16x16x32_bf16 v[56:59], v[136:139], v[176:179], v[56:59]
	v_mfma_f32_16x16x32_bf16 v[44:47], v[128:131], v[192:195], v[44:47]
	v_mfma_f32_16x16x32_bf16 v[40:43], v[136:139], v[192:195], v[40:43]
	v_mfma_f32_16x16x32_bf16 v[28:31], v[128:131], v[200:203], v[28:31]
	v_mfma_f32_16x16x32_bf16 v[24:27], v[136:139], v[200:203], v[24:27]
	v_mfma_f32_16x16x32_bf16 v[12:15], v[128:131], v[208:211], v[12:15]
	v_mfma_f32_16x16x32_bf16 v[8:11], v[136:139], v[208:211], v[8:11]
	v_mfma_f32_16x16x32_bf16 v[60:63], v[132:135], v[180:183], v[60:63]
	v_mfma_f32_16x16x32_bf16 v[56:59], v[140:143], v[180:183], v[56:59]
	v_mfma_f32_16x16x32_bf16 v[44:47], v[132:135], v[196:199], v[44:47]
	v_mfma_f32_16x16x32_bf16 v[40:43], v[140:143], v[196:199], v[40:43]
	v_mfma_f32_16x16x32_bf16 v[28:31], v[132:135], v[204:207], v[28:31]
	v_mfma_f32_16x16x32_bf16 v[24:27], v[140:143], v[204:207], v[24:27]
	v_mfma_f32_16x16x32_bf16 v[12:15], v[132:135], v[212:215], v[12:15]
	v_mfma_f32_16x16x32_bf16 v[8:11], v[140:143], v[212:215], v[8:11]
	s_setprio 0
	s_setprio 1
	v_mfma_f32_16x16x32_bf16 v[52:55], v[144:147], v[176:179], v[52:55]
	v_mfma_f32_16x16x32_bf16 v[48:51], v[168:171], v[176:179], v[48:51]
	v_mfma_f32_16x16x32_bf16 v[36:39], v[144:147], v[192:195], v[36:39]
	v_mfma_f32_16x16x32_bf16 v[32:35], v[168:171], v[192:195], v[32:35]
	v_mfma_f32_16x16x32_bf16 v[20:23], v[144:147], v[200:203], v[20:23]
	v_mfma_f32_16x16x32_bf16 v[16:19], v[168:171], v[200:203], v[16:19]
	v_mfma_f32_16x16x32_bf16 v[4:7], v[144:147], v[208:211], v[4:7]
	v_mfma_f32_16x16x32_bf16 v[0:3], v[168:171], v[208:211], v[0:3]
	v_mfma_f32_16x16x32_bf16 v[52:55], v[148:151], v[180:183], v[52:55]
	v_mfma_f32_16x16x32_bf16 v[48:51], v[172:175], v[180:183], v[48:51]
	v_mfma_f32_16x16x32_bf16 v[36:39], v[148:151], v[196:199], v[36:39]
	v_mfma_f32_16x16x32_bf16 v[32:35], v[172:175], v[196:199], v[32:35]
	s_barrier
	v_mfma_f32_16x16x32_bf16 v[20:23], v[148:151], v[204:207], v[20:23]
	v_mfma_f32_16x16x32_bf16 v[16:19], v[172:175], v[204:207], v[16:19]
	v_mfma_f32_16x16x32_bf16 v[4:7], v[148:151], v[212:215], v[4:7]
	v_mfma_f32_16x16x32_bf16 v[0:3], v[172:175], v[212:215], v[0:3]
	s_setprio 0
	s_add_i32 s64, s64, 2
	s_add_u32 s48, s48, 0x100
	s_addc_u32 s49, s49, 0
	s_add_u32 s47, s47, 0x100
	s_addc_u32 s63, s63, 0
	s_cmp_gt_u32 s64, 13
	s_cbranch_scc0 .LBB0_1165
	s_and_b64 vcc, exec, s[16:17]
	s_cbranch_vccz .LBB0_1168
	s_barrier

; #define PG8_STAGE(bufoff, gbase, voff) do { _Pragma("unroll") for (int _i = 0; _i < 2; ++_i) \
;         __builtin_amdgcn_global_load_lds((const unsigned*)((const char*)(gbase) + (voff)[_i]), (PG8_LAS unsigned*)(lds + (bufoff) + ldsw + _i * 8192), 16, 0, 0); } while (0)
; #define PG8_LDA(dst, b, h) do { _Pragma("unroll") for (int m = 0; m < 4; ++m) _Pragma("unroll") for (int k = 0; k < 2; ++k) dst[m][k] = *(const PG8_LAS bf16x8*)(lds + PG8_SA(b, h) + aoff + m * 2048 + k * 1024); } while (0)
; #define PG8_LDB(dst, b, h) do { _Pragma("unroll") for (int n = 0; n < 2; ++n) _Pragma("unroll") for (int k = 0; k < 2; ++k) dst[n][k] = *(const PG8_LAS bf16x8*)(lds + PG8_SB(b, h) + boff + n * 2048 + k * 1024); } while (0)
; #define PG8_MMA(ai, bj, At, Bt) do { __builtin_amdgcn_s_setprio(1); _Pragma("unroll") for (int m = 0; m < 4; ++m) _Pragma("unroll") for (int n = 0; n < 2; ++n) _Pragma("unroll") for (int k = 0; k < 2; ++k) \
;         acc[ai][bj][m][n] = mma16<F16>(Bt[n][k], At[m][k], acc[ai][bj][m][n]); __builtin_amdgcn_s_setprio(0); } while (0)
; #define PG8_WAIT_V(n) asm volatile("s_waitcnt vmcnt(" #n ")" ::: "memory")
; #define PG8_WAIT_L(n) asm volatile("s_waitcnt lgkmcnt(" #n ")" ::: "memory")
; template <class Epi, class Sched, bool ALIGN_EPI = false, bool SP2 = false, bool F16 = false>
; __device__ __forceinline__ void gemm_phase(PG8_LAS unsigned char* lds, const Gemm g, const Sched& S, const Epi& E, const int wid_in) {
;     ...
;             const bool last = (t == nt - 2);
;             const char* a1 = cA + (size_t)(t + 1) * kstep;
;             const char* a2 = last ? nA : cA + (size_t)(t + 2) * kstep; const char* b2 = last ? nB : cB + (size_t)(t + 2) * kstep;
;             const char* a3 = a2 + kstep; const char* b3 = b2 + kstep;
;             if (last && has_next) S.a_ready(nxt);
;             if constexpr (SP2) {
;             PG8_LDB(B0, 0, 0); PG8_LDB(B1, 0, 1); PG8_SCHED; PG8_LDA(At, 0, 0); PG8_STAGE(PG8_SA(1, 1), a1 + hstep, voffA);
;             PG8_WAIT_V(8); PG8_WAIT_L(0); PG8_BAR; PG8_MMA(0, 0, At, B0); PG8_MMA(0, 1, At, B1); PG8_BAR; PG8_SCHED;
;             PG8_LDA(At, 0, 1); PG8_STAGE(PG8_SB(0, 0), b2, voffB); PG8_STAGE(PG8_SB(0, 1), b2 + hstep, voffB); PG8_STAGE(PG8_SA(0, 0), a2, voffA);
;             PG8_WAIT_V(8); PG8_WAIT_L(0); PG8_BAR; PG8_MMA(1, 0, At, B0); PG8_MMA(1, 1, At, B1); PG8_BAR; PG8_SCHED;
.LBB0_1242:
	ds_read_b128 v[0:3], v193
	ds_read_b128 v[4:7], v193 offset:1024
	ds_read_b128 v[136:139], v193 offset:2048
	ds_read_b128 v[140:143], v193 offset:3072
	ds_read_b128 v[144:147], v194
	ds_read_b128 v[148:151], v194 offset:1024
	ds_read_b128 v[152:155], v194 offset:2048
	ds_read_b128 v[156:159], v194 offset:3072
	s_add_u32 s48, s46, 0xfffc0080
	s_addc_u32 s49, s47, -1
	s_cmp_eq_u32 s67, 12
	s_cselect_b32 s51, s29, s49
	s_cselect_b32 s50, s42, s48
	s_cselect_b32 s49, s27, s66
	s_cselect_b32 s48, s43, s45
	v_lshl_add_u64 v[188:189], s[46:47], 0, v[168:169]
	s_add_i32 m0, s74, 0xc000
	ds_read_b128 v[176:179], v195
	ds_read_b128 v[180:183], v195 offset:1024
	ds_read_b128 v[184:187], v195 offset:2048
	ds_read_b128 v[198:201], v195 offset:3072
	ds_read_b128 v[202:205], v195 offset:4096
	ds_read_b128 v[206:209], v195 offset:5120
	ds_read_b128 v[210:213], v195 offset:6144
	ds_read_b128 v[214:217], v195 offset:7168
	global_load_lds_dwordx4 v[188:189], off
	v_lshl_add_u64 v[188:189], s[46:47], 0, v[170:171]
	s_add_i32 m0, s74, 0xe000
	s_nop 0
	global_load_lds_dwordx4 v[188:189], off
	s_waitcnt vmcnt(8)
	s_waitcnt lgkmcnt(0)
	s_barrier
	s_setprio 1
	s_waitcnt lgkmcnt(0)
	v_mfma_f32_16x16x32_f16 v[132:135], v[0:3], v[176:179], v[132:135]
	v_mfma_f32_16x16x32_f16 v[128:131], v[136:139], v[176:179], v[128:131]
	v_mfma_f32_16x16x32_f16 v[116:119], v[0:3], v[184:187], v[116:119]
	v_mfma_f32_16x16x32_f16 v[112:115], v[136:139], v[184:187], v[112:115]
	v_mfma_f32_16x16x32_f16 v[100:103], v[0:3], v[202:205], v[100:103]
	v_mfma_f32_16x16x32_f16 v[96:99], v[136:139], v[202:205], v[96:99]
	v_mfma_f32_16x16x32_f16 v[84:87], v[0:3], v[210:213], v[84:87]
	v_mfma_f32_16x16x32_f16 v[80:83], v[136:139], v[210:213], v[80:83]
	v_mfma_f32_16x16x32_f16 v[132:135], v[4:7], v[180:183], v[132:135]
	v_mfma_f32_16x16x32_f16 v[128:131], v[140:143], v[180:183], v[128:131]
	v_mfma_f32_16x16x32_f16 v[116:119], v[4:7], v[198:201], v[116:119]
	v_mfma_f32_16x16x32_f16 v[112:115], v[140:143], v[198:201], v[112:115]
	v_mfma_f32_16x16x32_f16 v[100:103], v[4:7], v[206:209], v[100:103]
	v_mfma_f32_16x16x32_f16 v[96:99], v[140:143], v[206:209], v[96:99]
	v_mfma_f32_16x16x32_f16 v[84:87], v[4:7], v[214:217], v[84:87]
	v_mfma_f32_16x16x32_f16 v[80:83], v[140:143], v[214:217], v[80:83]
	s_setprio 0
	s_setprio 1
	v_mfma_f32_16x16x32_f16 v[124:127], v[144:147], v[176:179], v[124:127]
	v_mfma_f32_16x16x32_f16 v[120:123], v[152:155], v[176:179], v[120:123]
	v_mfma_f32_16x16x32_f16 v[108:111], v[144:147], v[184:187], v[108:111]
	v_mfma_f32_16x16x32_f16 v[104:107], v[152:155], v[184:187], v[104:107]
	v_mfma_f32_16x16x32_f16 v[92:95], v[144:147], v[202:205], v[92:95]
	v_mfma_f32_16x16x32_f16 v[88:91], v[152:155], v[202:205], v[88:91]
	v_mfma_f32_16x16x32_f16 v[76:79], v[144:147], v[210:213], v[76:79]
	v_mfma_f32_16x16x32_f16 v[72:75], v[152:155], v[210:213], v[72:75]
	v_mfma_f32_16x16x32_f16 v[124:127], v[148:151], v[180:183], v[124:127]
	v_mfma_f32_16x16x32_f16 v[120:123], v[156:159], v[180:183], v[120:123]
	v_mfma_f32_16x16x32_f16 v[108:111], v[148:151], v[198:201], v[108:111]
	v_mfma_f32_16x16x32_f16 v[104:107], v[156:159], v[198:201], v[104:107]
	s_barrier
	v_mfma_f32_16x16x32_f16 v[92:95], v[148:151], v[206:209], v[92:95]
	v_mfma_f32_16x16x32_f16 v[88:91], v[156:159], v[206:209], v[88:91]
	v_mfma_f32_16x16x32_f16 v[76:79], v[148:151], v[214:217], v[76:79]
	v_mfma_f32_16x16x32_f16 v[72:75], v[156:159], v[214:217], v[72:75]
	s_setprio 0
	s_add_i32 s76, s63, s68
	v_lshl_add_u64 v[188:189], s[48:49], 0, v[162:163]
	s_mov_b32 m0, s76
	ds_read_b128 v[176:179], v195 offset:16384
	ds_read_b128 v[180:183], v195 offset:17408
	ds_read_b128 v[184:187], v195 offset:18432
	ds_read_b128 v[198:201], v195 offset:19456
	ds_read_b128 v[202:205], v195 offset:20480
	ds_read_b128 v[206:209], v195 offset:21504
	ds_read_b128 v[210:213], v195 offset:22528
	ds_read_b128 v[214:217], v195 offset:23552
	global_load_lds_dwordx4 v[188:189], off
	s_add_i32 m0, s76, 0x2000
	s_add_u32 s90, s48, 0x40000
	v_lshl_add_u64 v[218:219], s[48:49], 0, v[166:167]
	s_addc_u32 s91, s49, 0
	s_add_i32 s76, s64, s68
	global_load_lds_dwordx4 v[218:219], off
	v_lshl_add_u64 v[220:221], s[90:91], 0, v[162:163]
	s_mov_b32 m0, s76
	v_lshl_add_u64 v[222:223], s[50:51], 0, v[164:165]
	global_load_lds_dwordx4 v[220:221], off
	v_lshl_add_u64 v[220:221], s[90:91], 0, v[166:167]
	s_add_i32 m0, s76, 0x2000
	s_nop 0
	global_load_lds_dwordx4 v[220:221], off
	v_lshl_add_u64 v[220:221], s[50:51], 0, v[160:161]
	s_mov_b32 m0, s74
	s_nop 0
	global_load_lds_dwordx4 v[220:221], off
	s_mov_b32 m0, s37
	s_nop 0
	global_load_lds_dwordx4 v[222:223], off
	s_waitcnt vmcnt(8)
	s_waitcnt lgkmcnt(0)
	s_barrier
; #define PG8_STAGE(bufoff, gbase, voff) do { _Pragma("unroll") for (int _i = 0; _i < 2; ++_i) \
;         __builtin_amdgcn_global_load_lds((const unsigned*)((const char*)(gbase) + (voff)[_i]), (PG8_LAS unsigned*)(lds + (bufoff) + ldsw + _i * 8192), 16, 0, 0); } while (0)
; #define PG8_LDA(dst, b, h) do { _Pragma("unroll") for (int m = 0; m < 4; ++m) _Pragma("unroll") for (int k = 0; k < 2; ++k) dst[m][k] = *(const PG8_LAS bf16x8*)(lds + PG8_SA(b, h) + aoff + m * 2048 + k * 1024); } while (0)
; #define PG8_LDB(dst, b, h) do { _Pragma("unroll") for (int n = 0; n < 2; ++n) _Pragma("unroll") for (int k = 0; k < 2; ++k) dst[n][k] = *(const PG8_LAS bf16x8*)(lds + PG8_SB(b, h) + boff + n * 2048 + k * 1024); } while (0)
; #define PG8_MMA(ai, bj, At, Bt) do { __builtin_amdgcn_s_setprio(1); _Pragma("unroll") for (int m = 0; m < 4; ++m) _Pragma("unroll") for (int n = 0; n < 2; ++n) _Pragma("unroll") for (int k = 0; k < 2; ++k) \
;         acc[ai][bj][m][n] = mma16<F16>(Bt[n][k], At[m][k], acc[ai][bj][m][n]); __builtin_amdgcn_s_setprio(0); } while (0)
; #define PG8_WAIT_V(n) asm volatile("s_waitcnt vmcnt(" #n ")" ::: "memory")
; #define PG8_WAIT_L(n) asm volatile("s_waitcnt lgkmcnt(" #n ")" ::: "memory")
; #define PG8_BAR __builtin_amdgcn_s_barrier()
; #define PG8_SCHED __builtin_amdgcn_sched_barrier(0)
; template <class Epi, class Sched, bool ALIGN_EPI = false, bool SP2 = false, bool F16 = false>
; __device__ __forceinline__ void gemm_phase(PG8_LAS unsigned char* lds, const Gemm g, const Sched& S, const Epi& E, const int wid_in) {
;     ...
;             PG8_WAIT_V(8); PG8_WAIT_L(0); PG8_BAR; PG8_MMA(1, 0, At, B0); PG8_MMA(1, 1, At, B1); PG8_BAR; PG8_SCHED;
;             PG8_LDB(B0, 1, 0); PG8_LDB(B1, 1, 1); PG8_SCHED; PG8_LDA(At, 1, 0); PG8_STAGE(PG8_SA(0, 1), a2 + hstep, voffA);
;             PG8_WAIT_V(8); PG8_WAIT_L(0); PG8_BAR; PG8_MMA(0, 0, At, B0); PG8_MMA(0, 1, At, B1); PG8_BAR; PG8_SCHED;
	s_setprio 1
	s_waitcnt lgkmcnt(0)
	v_mfma_f32_16x16x32_f16 v[68:71], v[0:3], v[176:179], v[68:71]
	v_mfma_f32_16x16x32_f16 v[64:67], v[136:139], v[176:179], v[64:67]
	v_mfma_f32_16x16x32_f16 v[52:55], v[0:3], v[184:187], v[52:55]
	v_mfma_f32_16x16x32_f16 v[48:51], v[136:139], v[184:187], v[48:51]
	v_mfma_f32_16x16x32_f16 v[36:39], v[0:3], v[202:205], v[36:39]
	v_mfma_f32_16x16x32_f16 v[32:35], v[136:139], v[202:205], v[32:35]
	v_mfma_f32_16x16x32_f16 v[0:3], v[0:3], v[210:213], v[20:23]
	v_mfma_f32_16x16x32_f16 v[68:71], v[4:7], v[180:183], v[68:71]
	v_mfma_f32_16x16x32_f16 v[64:67], v[140:143], v[180:183], v[64:67]
	v_mfma_f32_16x16x32_f16 v[52:55], v[4:7], v[198:201], v[52:55]
	v_mfma_f32_16x16x32_f16 v[48:51], v[140:143], v[198:201], v[48:51]
	v_mfma_f32_16x16x32_f16 v[36:39], v[4:7], v[206:209], v[36:39]
	v_mfma_f32_16x16x32_f16 v[32:35], v[140:143], v[206:209], v[32:35]
	v_mfma_f32_16x16x32_f16 v[0:3], v[4:7], v[214:217], v[0:3]
	v_mfma_f32_16x16x32_f16 v[4:7], v[136:139], v[210:213], v[16:19]
	v_mfma_f32_16x16x32_f16 v[4:7], v[140:143], v[214:217], v[4:7]
	s_setprio 0
	s_setprio 1
	v_mfma_f32_16x16x32_f16 v[16:19], v[144:147], v[176:179], v[60:63]
	v_mfma_f32_16x16x32_f16 v[60:63], v[148:151], v[180:183], v[16:19]
	v_mfma_f32_16x16x32_f16 v[16:19], v[152:155], v[176:179], v[56:59]
	v_mfma_f32_16x16x32_f16 v[56:59], v[156:159], v[180:183], v[16:19]
	v_mfma_f32_16x16x32_f16 v[16:19], v[144:147], v[184:187], v[44:47]
	v_mfma_f32_16x16x32_f16 v[44:47], v[148:151], v[198:201], v[16:19]
	v_mfma_f32_16x16x32_f16 v[16:19], v[152:155], v[184:187], v[40:43]
	v_mfma_f32_16x16x32_f16 v[40:43], v[156:159], v[198:201], v[16:19]
	v_mfma_f32_16x16x32_f16 v[16:19], v[144:147], v[202:205], v[28:31]
	v_mfma_f32_16x16x32_f16 v[28:31], v[148:151], v[206:209], v[16:19]
	v_mfma_f32_16x16x32_f16 v[16:19], v[152:155], v[202:205], v[24:27]
	v_mfma_f32_16x16x32_f16 v[12:15], v[144:147], v[210:213], v[12:15]
	s_barrier
	v_mfma_f32_16x16x32_f16 v[8:11], v[152:155], v[210:213], v[8:11]
	v_mfma_f32_16x16x32_f16 v[24:27], v[156:159], v[206:209], v[16:19]
	v_mfma_f32_16x16x32_f16 v[12:15], v[148:151], v[214:217], v[12:15]
	v_mfma_f32_16x16x32_f16 v[8:11], v[156:159], v[214:217], v[8:11]
	s_setprio 0
	s_add_i32 s76, 0, 0x18000
	s_add_i32 s83, 0, 0x1c000
	v_add_u32_e32 v140, s76, v192
	v_add_u32_e32 v156, s83, v192
	ds_read_b128 v[16:19], v140
	ds_read_b128 v[20:23], v140 offset:1024
	ds_read_b128 v[136:139], v140 offset:2048
	ds_read_b128 v[140:143], v140 offset:3072
	ds_read_b128 v[144:147], v156
	ds_read_b128 v[148:151], v156 offset:1024
	ds_read_b128 v[152:155], v156 offset:2048
	ds_read_b128 v[156:159], v156 offset:3072
	s_add_u32 s50, s50, 0x40000
	s_addc_u32 s51, s51, 0
	s_mov_b32 m0, s53
	v_lshl_add_u64 v[224:225], s[50:51], 0, v[160:161]
	ds_read_b128 v[176:179], v195 offset:32768
	ds_read_b128 v[180:183], v195 offset:33792
	ds_read_b128 v[184:187], v195 offset:34816
	ds_read_b128 v[198:201], v195 offset:35840
	ds_read_b128 v[202:205], v195 offset:36864
	ds_read_b128 v[206:209], v195 offset:37888
	ds_read_b128 v[210:213], v195 offset:38912
	ds_read_b128 v[214:217], v195 offset:39936
	global_load_lds_dwordx4 v[224:225], off
	v_lshl_add_u64 v[224:225], s[50:51], 0, v[164:165]
	s_mov_b32 m0, s54
	s_nop 0
	global_load_lds_dwordx4 v[224:225], off
	s_waitcnt vmcnt(8)
	s_waitcnt lgkmcnt(0)
	s_barrier
	s_setprio 1
	s_waitcnt lgkmcnt(0)
	v_mfma_f32_16x16x32_f16 v[132:135], v[16:19], v[176:179], v[132:135]
	v_mfma_f32_16x16x32_f16 v[128:131], v[136:139], v[176:179], v[128:131]
	v_mfma_f32_16x16x32_f16 v[116:119], v[16:19], v[184:187], v[116:119]
	v_mfma_f32_16x16x32_f16 v[112:115], v[136:139], v[184:187], v[112:115]
	v_mfma_f32_16x16x32_f16 v[100:103], v[16:19], v[202:205], v[100:103]
	v_mfma_f32_16x16x32_f16 v[96:99], v[136:139], v[202:205], v[96:99]
	v_mfma_f32_16x16x32_f16 v[84:87], v[16:19], v[210:213], v[84:87]
	v_mfma_f32_16x16x32_f16 v[80:83], v[136:139], v[210:213], v[80:83]
	v_mfma_f32_16x16x32_f16 v[132:135], v[20:23], v[180:183], v[132:135]
	v_mfma_f32_16x16x32_f16 v[128:131], v[140:143], v[180:183], v[128:131]
	v_mfma_f32_16x16x32_f16 v[116:119], v[20:23], v[198:201], v[116:119]
	v_mfma_f32_16x16x32_f16 v[112:115], v[140:143], v[198:201], v[112:115]
	v_mfma_f32_16x16x32_f16 v[100:103], v[20:23], v[206:209], v[100:103]
	v_mfma_f32_16x16x32_f16 v[96:99], v[140:143], v[206:209], v[96:99]
	v_mfma_f32_16x16x32_f16 v[84:87], v[20:23], v[214:217], v[84:87]
	v_mfma_f32_16x16x32_f16 v[80:83], v[140:143], v[214:217], v[80:83]
	s_setprio 0
	s_setprio 1
	v_mfma_f32_16x16x32_f16 v[124:127], v[144:147], v[176:179], v[124:127]
	v_mfma_f32_16x16x32_f16 v[120:123], v[152:155], v[176:179], v[120:123]
	v_mfma_f32_16x16x32_f16 v[108:111], v[144:147], v[184:187], v[108:111]
	v_mfma_f32_16x16x32_f16 v[104:107], v[152:155], v[184:187], v[104:107]
	v_mfma_f32_16x16x32_f16 v[92:95], v[144:147], v[202:205], v[92:95]
	v_mfma_f32_16x16x32_f16 v[88:91], v[152:155], v[202:205], v[88:91]
	v_mfma_f32_16x16x32_f16 v[76:79], v[144:147], v[210:213], v[76:79]
	v_mfma_f32_16x16x32_f16 v[72:75], v[152:155], v[210:213], v[72:75]
	v_mfma_f32_16x16x32_f16 v[124:127], v[148:151], v[180:183], v[124:127]
	v_mfma_f32_16x16x32_f16 v[120:123], v[156:159], v[180:183], v[120:123]
	v_mfma_f32_16x16x32_f16 v[108:111], v[148:151], v[198:201], v[108:111]
	v_mfma_f32_16x16x32_f16 v[104:107], v[156:159], v[198:201], v[104:107]
	s_barrier
; #define PG8_STAGE(bufoff, gbase, voff) do { _Pragma("unroll") for (int _i = 0; _i < 2; ++_i) \
;         __builtin_amdgcn_global_load_lds((const unsigned*)((const char*)(gbase) + (voff)[_i]), (PG8_LAS unsigned*)(lds + (bufoff) + ldsw + _i * 8192), 16, 0, 0); } while (0)
; #define PG8_LDA(dst, b, h) do { _Pragma("unroll") for (int m = 0; m < 4; ++m) _Pragma("unroll") for (int k = 0; k < 2; ++k) dst[m][k] = *(const PG8_LAS bf16x8*)(lds + PG8_SA(b, h) + aoff + m * 2048 + k * 1024); } while (0)
; #define PG8_MMA(ai, bj, At, Bt) do { __builtin_amdgcn_s_setprio(1); _Pragma("unroll") for (int m = 0; m < 4; ++m) _Pragma("unroll") for (int n = 0; n < 2; ++n) _Pragma("unroll") for (int k = 0; k < 2; ++k) \
;         acc[ai][bj][m][n] = mma16<F16>(Bt[n][k], At[m][k], acc[ai][bj][m][n]); __builtin_amdgcn_s_setprio(0); } while (0)
; #define PG8_WAIT_V(n) asm volatile("s_waitcnt vmcnt(" #n ")" ::: "memory")
; #define PG8_WAIT_L(n) asm volatile("s_waitcnt lgkmcnt(" #n ")" ::: "memory")
; #define PG8_BAR __builtin_amdgcn_s_barrier()
; #define PG8_SCHED __builtin_amdgcn_sched_barrier(0)
; template <class Epi, class Sched, bool ALIGN_EPI = false, bool SP2 = false, bool F16 = false>
; __device__ __forceinline__ void gemm_phase(PG8_LAS unsigned char* lds, const Gemm g, const Sched& S, const Epi& E, const int wid_in) {
;     ...
;             PG8_WAIT_V(8); PG8_WAIT_L(0); PG8_BAR; PG8_MMA(0, 0, At, B0); PG8_MMA(0, 1, At, B1); PG8_BAR; PG8_SCHED;
;             PG8_LDA(At, 1, 1); PG8_STAGE(PG8_SB(1, 0), b3, voffB); PG8_STAGE(PG8_SB(1, 1), b3 + hstep, voffB); PG8_STAGE(PG8_SA(1, 0), a3, voffA);
;             PG8_WAIT_V(8); PG8_WAIT_L(0); PG8_BAR; PG8_MMA(1, 0, At, B0); PG8_MMA(1, 1, At, B1); PG8_BAR; PG8_SCHED;
;     ...
;         if constexpr (ALIGN_EPI) { if (wr == 0) PG8_BAR; }
	v_mfma_f32_16x16x32_f16 v[92:95], v[148:151], v[206:209], v[92:95]
	v_mfma_f32_16x16x32_f16 v[88:91], v[156:159], v[206:209], v[88:91]
	v_mfma_f32_16x16x32_f16 v[76:79], v[148:151], v[214:217], v[76:79]
	v_mfma_f32_16x16x32_f16 v[72:75], v[156:159], v[214:217], v[72:75]
	s_setprio 0
	s_add_i32 s50, s76, s68
	v_lshl_add_u64 v[188:189], v[188:189], 0, s[24:25]
	s_mov_b32 m0, s50
	ds_read_b128 v[176:179], v195 offset:49152
	ds_read_b128 v[180:183], v195 offset:50176
	ds_read_b128 v[184:187], v195 offset:51200
	ds_read_b128 v[198:201], v195 offset:52224
	ds_read_b128 v[202:205], v195 offset:53248
	ds_read_b128 v[206:209], v195 offset:54272
	ds_read_b128 v[210:213], v195 offset:55296
	ds_read_b128 v[214:217], v195 offset:56320
	global_load_lds_dwordx4 v[188:189], off
	s_add_i32 m0, s50, 0x2000
	s_add_u32 s48, s48, 0x40080
	v_lshl_add_u64 v[188:189], v[218:219], 0, s[24:25]
	s_addc_u32 s49, s49, 0
	s_add_i32 s50, s83, s68
	global_load_lds_dwordx4 v[188:189], off
	v_lshl_add_u64 v[188:189], s[48:49], 0, v[162:163]
	s_mov_b32 m0, s50
	s_nop 0
	global_load_lds_dwordx4 v[188:189], off
	v_lshl_add_u64 v[188:189], s[48:49], 0, v[166:167]
	s_add_i32 m0, s50, 0x2000
	s_nop 0
	global_load_lds_dwordx4 v[188:189], off
	v_lshl_add_u64 v[188:189], v[220:221], 0, s[24:25]
	s_mov_b32 m0, s75
	s_nop 0
	global_load_lds_dwordx4 v[188:189], off
	v_lshl_add_u64 v[188:189], v[222:223], 0, s[24:25]
	s_mov_b32 m0, s57
	s_nop 0
	global_load_lds_dwordx4 v[188:189], off
	s_waitcnt vmcnt(8)
	s_waitcnt lgkmcnt(0)
	s_barrier
	s_setprio 1
	s_waitcnt lgkmcnt(0)
	v_mfma_f32_16x16x32_f16 v[68:71], v[16:19], v[176:179], v[68:71]
	v_mfma_f32_16x16x32_f16 v[52:55], v[16:19], v[184:187], v[52:55]
	v_mfma_f32_16x16x32_f16 v[36:39], v[16:19], v[202:205], v[36:39]
	v_mfma_f32_16x16x32_f16 v[0:3], v[16:19], v[210:213], v[0:3]
	v_mfma_f32_16x16x32_f16 v[68:71], v[20:23], v[180:183], v[68:71]
	v_mfma_f32_16x16x32_f16 v[64:67], v[136:139], v[176:179], v[64:67]
	v_mfma_f32_16x16x32_f16 v[52:55], v[20:23], v[198:201], v[52:55]
	v_mfma_f32_16x16x32_f16 v[48:51], v[136:139], v[184:187], v[48:51]
	v_mfma_f32_16x16x32_f16 v[36:39], v[20:23], v[206:209], v[36:39]
	v_mfma_f32_16x16x32_f16 v[32:35], v[136:139], v[202:205], v[32:35]
	v_mfma_f32_16x16x32_f16 v[20:23], v[20:23], v[214:217], v[0:3]
	v_mfma_f32_16x16x32_f16 v[0:3], v[136:139], v[210:213], v[4:7]
	v_mfma_f32_16x16x32_f16 v[64:67], v[140:143], v[180:183], v[64:67]
	v_mfma_f32_16x16x32_f16 v[48:51], v[140:143], v[198:201], v[48:51]
	v_mfma_f32_16x16x32_f16 v[32:35], v[140:143], v[206:209], v[32:35]
	v_mfma_f32_16x16x32_f16 v[16:19], v[140:143], v[214:217], v[0:3]
	s_setprio 0
	s_setprio 1
	v_mfma_f32_16x16x32_f16 v[0:3], v[144:147], v[176:179], v[60:63]
	v_mfma_f32_16x16x32_f16 v[60:63], v[148:151], v[180:183], v[0:3]
	v_mfma_f32_16x16x32_f16 v[0:3], v[152:155], v[176:179], v[56:59]
	v_mfma_f32_16x16x32_f16 v[56:59], v[156:159], v[180:183], v[0:3]
	v_mfma_f32_16x16x32_f16 v[0:3], v[144:147], v[184:187], v[44:47]
	v_mfma_f32_16x16x32_f16 v[44:47], v[148:151], v[198:201], v[0:3]
	v_mfma_f32_16x16x32_f16 v[0:3], v[152:155], v[184:187], v[40:43]
	v_mfma_f32_16x16x32_f16 v[40:43], v[156:159], v[198:201], v[0:3]
	v_mfma_f32_16x16x32_f16 v[0:3], v[144:147], v[202:205], v[28:31]
	v_mfma_f32_16x16x32_f16 v[28:31], v[148:151], v[206:209], v[0:3]
	v_mfma_f32_16x16x32_f16 v[0:3], v[152:155], v[202:205], v[24:27]
	v_mfma_f32_16x16x32_f16 v[24:27], v[156:159], v[206:209], v[0:3]
	s_barrier
	v_mfma_f32_16x16x32_f16 v[0:3], v[144:147], v[210:213], v[12:15]
	v_mfma_f32_16x16x32_f16 v[12:15], v[148:151], v[214:217], v[0:3]
	v_mfma_f32_16x16x32_f16 v[0:3], v[152:155], v[210:213], v[8:11]
	v_mfma_f32_16x16x32_f16 v[8:11], v[156:159], v[214:217], v[0:3]
	s_setprio 0
	s_add_i32 s67, s67, 2
	s_add_u32 s46, s46, 0x100
	s_addc_u32 s47, s47, 0
	s_add_u32 s45, s45, 0x100
	s_addc_u32 s66, s66, 0
	s_cmp_gt_u32 s67, 13
	s_cbranch_scc0 .LBB0_1242
	s_and_b64 vcc, exec, s[16:17]
	s_cbranch_vccz .LBB0_1245
	s_barrier

; #define PG8_STAGE(bufoff, gbase, voff) do { _Pragma("unroll") for (int _i = 0; _i < 2; ++_i) \
;         __builtin_amdgcn_global_load_lds((const unsigned*)((const char*)(gbase) + (voff)[_i]), (PG8_LAS unsigned*)(lds + (bufoff) + ldsw + _i * 8192), 16, 0, 0); } while (0)
; #define PG8_LDA(dst, b, h) do { _Pragma("unroll") for (int m = 0; m < 4; ++m) _Pragma("unroll") for (int k = 0; k < 2; ++k) dst[m][k] = *(const PG8_LAS bf16x8*)(lds + PG8_SA(b, h) + aoff + m * 2048 + k * 1024); } while (0)
; #define PG8_LDB(dst, b, h) do { _Pragma("unroll") for (int n = 0; n < 2; ++n) _Pragma("unroll") for (int k = 0; k < 2; ++k) dst[n][k] = *(const PG8_LAS bf16x8*)(lds + PG8_SB(b, h) + boff + n * 2048 + k * 1024); } while (0)
; #define PG8_WAIT_V(n) asm volatile("s_waitcnt vmcnt(" #n ")" ::: "memory")
; #define PG8_WAIT_L(n) asm volatile("s_waitcnt lgkmcnt(" #n ")" ::: "memory")
; #define PG8_BAR __builtin_amdgcn_s_barrier()
; #define PG8_SCHED __builtin_amdgcn_sched_barrier(0)
; template <class Epi, class Sched, bool ALIGN_EPI = false, bool SP2 = false, bool F16 = false>
; __device__ __forceinline__ void gemm_phase(PG8_LAS unsigned char* lds, const Gemm g, const Sched& S, const Epi& E, const int wid_in) {
;     ...
;         const bool has_next = S.next(ui + 1, nxt);
;         const char* nA = has_next ? (const char*)g.A + (size_t)nxt.pm * tstep : cA; const char* nB = has_next ? (const char*)g.Bt + (size_t)nxt.pn * tstep : cB;
;         for (int t = 0; t < nt; t += 2) {
;             const bool last = (t == nt - 2);
;             const char* a1 = cA + (size_t)(t + 1) * kstep;
;             const char* a2 = last ? nA : cA + (size_t)(t + 2) * kstep; const char* b2 = last ? nB : cB + (size_t)(t + 2) * kstep;
;             const char* a3 = a2 + kstep; const char* b3 = b2 + kstep;
;             if (last && has_next) S.a_ready(nxt);
;             if constexpr (SP2) {
;             PG8_LDB(B0, 0, 0); PG8_LDB(B1, 0, 1); PG8_SCHED; PG8_LDA(At, 0, 0); PG8_STAGE(PG8_SA(1, 1), a1 + hstep, voffA);
;             PG8_WAIT_V(8); PG8_WAIT_L(0); PG8_BAR; PG8_MMA(0, 0, At, B0); PG8_MMA(0, 1, At, B1); PG8_BAR; PG8_SCHED;
;             PG8_LDA(At, 0, 1); PG8_STAGE(PG8_SB(0, 0), b2, voffB); PG8_STAGE(PG8_SB(0, 1), b2 + hstep, voffB); PG8_STAGE(PG8_SA(0, 0), a2, voffA);
;             PG8_WAIT_V(8); PG8_WAIT_L(0); PG8_BAR; PG8_MMA(1, 0, At, B0); PG8_MMA(1, 1, At, B1); PG8_BAR; PG8_SCHED;
.LBB0_1277:
	s_mov_b64 s[48:49], s[10:11]
	s_add_i32 s10, s36, s19
	s_mov_b64 s[46:47], s[12:13]
	s_mov_b32 s12, s62
	s_mov_b32 s13, s61
	s_and_b32 s61, s10, 3
	s_ashr_i32 s62, s10, 2
	s_and_b64 s[10:11], s[30:31], exec
	s_cselect_b32 s12, s62, s12
	ds_read_b128 v[0:3], v134
	ds_read_b128 v[4:7], v134 offset:1024
	ds_read_b128 v[8:11], v134 offset:2048
	ds_read_b128 v[12:15], v134 offset:3072
	ds_read_b128 v[16:19], v135
	ds_read_b128 v[20:23], v135 offset:1024
	ds_read_b128 v[24:27], v135 offset:2048
	ds_read_b128 v[28:31], v135 offset:3072
	s_cselect_b32 s10, s61, s13
	s_ashr_i32 s13, s12, 31
	s_lshl_b64 s[12:13], s[12:13], 17
	s_add_u32 s12, s21, s12
	s_addc_u32 s13, s40, s13
	s_and_b64 s[36:37], s[30:31], exec
	s_cselect_b32 s45, s13, s47
	s_cselect_b32 s44, s12, s46
	s_ashr_i32 s11, s10, 31
	s_lshl_b64 s[10:11], s[10:11], 17
	s_add_u32 s10, s41, s10
	s_addc_u32 s11, s42, s11
	s_and_b64 s[36:37], s[30:31], exec
	s_cselect_b32 s37, s11, s49
	s_cselect_b32 s36, s10, s48
	s_add_u32 s64, s46, 0x10080
	s_addc_u32 s65, s47, 0
	s_mov_b32 m0, s15
	v_lshl_add_u64 v[64:65], s[64:65], 0, v[130:131]
	ds_read_b128 v[32:35], v136
	ds_read_b128 v[36:39], v136 offset:1024
	ds_read_b128 v[40:43], v136 offset:2048
	ds_read_b128 v[44:47], v136 offset:3072
	ds_read_b128 v[48:51], v136 offset:4096
	ds_read_b128 v[52:55], v136 offset:5120
	ds_read_b128 v[56:59], v136 offset:6144
	ds_read_b128 v[60:63], v136 offset:7168
	global_load_lds_dwordx4 v[64:65], off
	v_lshl_add_u64 v[64:65], s[64:65], 0, v[128:129]
	s_mov_b32 m0, s52
	s_nop 0
	global_load_lds_dwordx4 v[64:65], off
	s_waitcnt vmcnt(8)
	s_waitcnt lgkmcnt(0)
	s_barrier
	s_setprio 1
	s_waitcnt lgkmcnt(0)
	v_mfma_f32_16x16x32_bf16 v[64:67], v[0:3], v[32:35], 0
	v_mfma_f32_16x16x32_bf16 v[68:71], v[8:11], v[32:35], 0
	v_mfma_f32_16x16x32_bf16 v[72:75], v[0:3], v[40:43], 0
	v_mfma_f32_16x16x32_bf16 v[76:79], v[8:11], v[40:43], 0
	v_mfma_f32_16x16x32_bf16 v[80:83], v[0:3], v[48:51], 0
	v_mfma_f32_16x16x32_bf16 v[84:87], v[8:11], v[48:51], 0
	v_mfma_f32_16x16x32_bf16 v[88:91], v[0:3], v[56:59], 0
	v_mfma_f32_16x16x32_bf16 v[92:95], v[8:11], v[56:59], 0
	v_mfma_f32_16x16x32_bf16 v[64:67], v[4:7], v[36:39], v[64:67]
	v_mfma_f32_16x16x32_bf16 v[68:71], v[12:15], v[36:39], v[68:71]
	v_mfma_f32_16x16x32_bf16 v[72:75], v[4:7], v[44:47], v[72:75]
	v_mfma_f32_16x16x32_bf16 v[76:79], v[12:15], v[44:47], v[76:79]
	v_mfma_f32_16x16x32_bf16 v[80:83], v[4:7], v[52:55], v[80:83]
	v_mfma_f32_16x16x32_bf16 v[84:87], v[12:15], v[52:55], v[84:87]
	v_mfma_f32_16x16x32_bf16 v[88:91], v[4:7], v[60:63], v[88:91]
	v_mfma_f32_16x16x32_bf16 v[92:95], v[12:15], v[60:63], v[92:95]
	s_setprio 0
	s_setprio 1
	v_mfma_f32_16x16x32_bf16 v[96:99], v[16:19], v[32:35], 0
	v_mfma_f32_16x16x32_bf16 v[32:35], v[24:27], v[32:35], 0
	v_mfma_f32_16x16x32_bf16 v[96:99], v[20:23], v[36:39], v[96:99]
	v_mfma_f32_16x16x32_bf16 v[32:35], v[28:31], v[36:39], v[32:35]
	v_mfma_f32_16x16x32_bf16 v[36:39], v[16:19], v[40:43], 0
	v_mfma_f32_16x16x32_bf16 v[40:43], v[24:27], v[40:43], 0
	v_mfma_f32_16x16x32_bf16 v[36:39], v[20:23], v[44:47], v[36:39]
	v_mfma_f32_16x16x32_bf16 v[40:43], v[28:31], v[44:47], v[40:43]
	v_mfma_f32_16x16x32_bf16 v[44:47], v[16:19], v[48:51], 0
	v_mfma_f32_16x16x32_bf16 v[48:51], v[24:27], v[48:51], 0
	v_mfma_f32_16x16x32_bf16 v[44:47], v[20:23], v[52:55], v[44:47]
	v_mfma_f32_16x16x32_bf16 v[48:51], v[28:31], v[52:55], v[48:51]
	s_barrier
	v_mfma_f32_16x16x32_bf16 v[52:55], v[16:19], v[56:59], 0
	v_mfma_f32_16x16x32_bf16 v[56:59], v[24:27], v[56:59], 0
	v_mfma_f32_16x16x32_bf16 v[52:55], v[20:23], v[60:63], v[52:55]
	v_mfma_f32_16x16x32_bf16 v[56:59], v[28:31], v[60:63], v[56:59]
	s_setprio 0
	v_lshl_add_u64 v[204:205], s[48:49], 0, v[130:131]
	s_mov_b32 m0, s53
	v_lshl_add_u64 v[140:141], v[204:205], 0, s[26:27]
	v_lshl_add_u64 v[206:207], s[48:49], 0, v[128:129]
	s_add_u32 s64, s48, 0x10100
	ds_read_b128 v[60:63], v136 offset:16384
	ds_read_b128 v[100:103], v136 offset:17408
	ds_read_b128 v[104:107], v136 offset:18432
	ds_read_b128 v[108:111], v136 offset:19456
	ds_read_b128 v[112:115], v136 offset:20480
	ds_read_b128 v[116:119], v136 offset:21504
	ds_read_b128 v[120:123], v136 offset:22528
	ds_read_b128 v[124:127], v136 offset:23552
	global_load_lds_dwordx4 v[140:141], off
	v_lshl_add_u64 v[140:141], v[206:207], 0, s[26:27]
	s_mov_b32 m0, s54
	s_addc_u32 s65, s49, 0
	global_load_lds_dwordx4 v[140:141], off
	v_lshl_add_u64 v[140:141], s[64:65], 0, v[130:131]
	s_mov_b32 m0, s55
	v_lshl_add_u64 v[208:209], s[46:47], 0, v[130:131]
	global_load_lds_dwordx4 v[140:141], off
	v_lshl_add_u64 v[140:141], s[64:65], 0, v[128:129]
	s_mov_b32 m0, s56
	v_lshl_add_u64 v[210:211], s[46:47], 0, v[128:129]
	global_load_lds_dwordx4 v[140:141], off
	v_lshl_add_u64 v[140:141], v[208:209], 0, s[26:27]
	s_mov_b32 m0, s74
	s_nop 0
	global_load_lds_dwordx4 v[140:141], off
	v_lshl_add_u64 v[140:141], v[210:211], 0, s[26:27]
	s_mov_b32 m0, s43
	s_nop 0
	global_load_lds_dwordx4 v[140:141], off
	s_waitcnt vmcnt(8)
	s_waitcnt lgkmcnt(0)
	s_barrier
; #define PG8_STAGE(bufoff, gbase, voff) do { _Pragma("unroll") for (int _i = 0; _i < 2; ++_i) \
;         __builtin_amdgcn_global_load_lds((const unsigned*)((const char*)(gbase) + (voff)[_i]), (PG8_LAS unsigned*)(lds + (bufoff) + ldsw + _i * 8192), 16, 0, 0); } while (0)
; #define PG8_LDA(dst, b, h) do { _Pragma("unroll") for (int m = 0; m < 4; ++m) _Pragma("unroll") for (int k = 0; k < 2; ++k) dst[m][k] = *(const PG8_LAS bf16x8*)(lds + PG8_SA(b, h) + aoff + m * 2048 + k * 1024); } while (0)
; #define PG8_LDB(dst, b, h) do { _Pragma("unroll") for (int n = 0; n < 2; ++n) _Pragma("unroll") for (int k = 0; k < 2; ++k) dst[n][k] = *(const PG8_LAS bf16x8*)(lds + PG8_SB(b, h) + boff + n * 2048 + k * 1024); } while (0)
; #define PG8_MMA(ai, bj, At, Bt) do { __builtin_amdgcn_s_setprio(1); _Pragma("unroll") for (int m = 0; m < 4; ++m) _Pragma("unroll") for (int n = 0; n < 2; ++n) _Pragma("unroll") for (int k = 0; k < 2; ++k) \
;         acc[ai][bj][m][n] = mma16<F16>(Bt[n][k], At[m][k], acc[ai][bj][m][n]); __builtin_amdgcn_s_setprio(0); } while (0)
; #define PG8_WAIT_V(n) asm volatile("s_waitcnt vmcnt(" #n ")" ::: "memory")
; #define PG8_WAIT_L(n) asm volatile("s_waitcnt lgkmcnt(" #n ")" ::: "memory")
; #define PG8_BAR __builtin_amdgcn_s_barrier()
; #define PG8_SCHED __builtin_amdgcn_sched_barrier(0)
; template <class Epi, class Sched, bool ALIGN_EPI = false, bool SP2 = false, bool F16 = false>
; __device__ __forceinline__ void gemm_phase(PG8_LAS unsigned char* lds, const Gemm g, const Sched& S, const Epi& E, const int wid_in) {
;     ...
;             PG8_WAIT_V(8); PG8_WAIT_L(0); PG8_BAR; PG8_MMA(1, 0, At, B0); PG8_MMA(1, 1, At, B1); PG8_BAR; PG8_SCHED;
;             PG8_LDB(B0, 1, 0); PG8_LDB(B1, 1, 1); PG8_SCHED; PG8_LDA(At, 1, 0); PG8_STAGE(PG8_SA(0, 1), a2 + hstep, voffA);
;             PG8_WAIT_V(8); PG8_WAIT_L(0); PG8_BAR; PG8_MMA(0, 0, At, B0); PG8_MMA(0, 1, At, B1); PG8_BAR; PG8_SCHED;
	s_setprio 1
	s_waitcnt lgkmcnt(0)
	v_mfma_f32_16x16x32_bf16 v[140:143], v[0:3], v[60:63], 0
	v_mfma_f32_16x16x32_bf16 v[148:151], v[0:3], v[104:107], 0
	v_mfma_f32_16x16x32_bf16 v[156:159], v[0:3], v[112:115], 0
	v_mfma_f32_16x16x32_bf16 v[0:3], v[0:3], v[120:123], 0
	v_mfma_f32_16x16x32_bf16 v[140:143], v[4:7], v[100:103], v[140:143]
	v_mfma_f32_16x16x32_bf16 v[148:151], v[4:7], v[108:111], v[148:151]
	v_mfma_f32_16x16x32_bf16 v[156:159], v[4:7], v[116:119], v[156:159]
	v_mfma_f32_16x16x32_bf16 v[0:3], v[4:7], v[124:127], v[0:3]
	v_mfma_f32_16x16x32_bf16 v[4:7], v[8:11], v[120:123], 0
	v_mfma_f32_16x16x32_bf16 v[144:147], v[8:11], v[60:63], 0
	v_mfma_f32_16x16x32_bf16 v[152:155], v[8:11], v[104:107], 0
	v_mfma_f32_16x16x32_bf16 v[160:163], v[8:11], v[112:115], 0
	v_mfma_f32_16x16x32_bf16 v[4:7], v[12:15], v[124:127], v[4:7]
	v_mfma_f32_16x16x32_bf16 v[144:147], v[12:15], v[100:103], v[144:147]
	v_mfma_f32_16x16x32_bf16 v[152:155], v[12:15], v[108:111], v[152:155]
	v_mfma_f32_16x16x32_bf16 v[160:163], v[12:15], v[116:119], v[160:163]
	s_setprio 0
	s_setprio 1
	v_mfma_f32_16x16x32_bf16 v[8:11], v[16:19], v[60:63], 0
	v_mfma_f32_16x16x32_bf16 v[12:15], v[24:27], v[60:63], 0
	v_mfma_f32_16x16x32_bf16 v[8:11], v[20:23], v[100:103], v[8:11]
	v_mfma_f32_16x16x32_bf16 v[12:15], v[28:31], v[100:103], v[12:15]
	v_mfma_f32_16x16x32_bf16 v[60:63], v[16:19], v[104:107], 0
	v_mfma_f32_16x16x32_bf16 v[100:103], v[24:27], v[104:107], 0
	v_mfma_f32_16x16x32_bf16 v[104:107], v[16:19], v[112:115], 0
	v_mfma_f32_16x16x32_bf16 v[16:19], v[16:19], v[120:123], 0
	v_mfma_f32_16x16x32_bf16 v[60:63], v[20:23], v[108:111], v[60:63]
	v_mfma_f32_16x16x32_bf16 v[100:103], v[28:31], v[108:111], v[100:103]
	v_mfma_f32_16x16x32_bf16 v[104:107], v[20:23], v[116:119], v[104:107]
	v_mfma_f32_16x16x32_bf16 v[108:111], v[24:27], v[112:115], 0
	s_barrier
	v_mfma_f32_16x16x32_bf16 v[16:19], v[20:23], v[124:127], v[16:19]
	v_mfma_f32_16x16x32_bf16 v[20:23], v[24:27], v[120:123], 0
	v_mfma_f32_16x16x32_bf16 v[108:111], v[28:31], v[116:119], v[108:111]
	v_mfma_f32_16x16x32_bf16 v[20:23], v[28:31], v[124:127], v[20:23]
	s_setprio 0
	ds_read_b128 v[24:27], v137
	ds_read_b128 v[28:31], v137 offset:1024
	ds_read_b128 v[112:115], v137 offset:2048
	ds_read_b128 v[116:119], v137 offset:3072
	ds_read_b128 v[120:123], v138
	ds_read_b128 v[124:127], v138 offset:1024
	ds_read_b128 v[164:167], v138 offset:2048
	ds_read_b128 v[168:171], v138 offset:3072
	s_add_u32 s64, s46, 0x10100
	s_addc_u32 s65, s47, 0
	s_mov_b32 m0, s50
	v_lshl_add_u64 v[212:213], s[64:65], 0, v[130:131]
	ds_read_b128 v[172:175], v136 offset:32768
	ds_read_b128 v[176:179], v136 offset:33792
	ds_read_b128 v[180:183], v136 offset:34816
	ds_read_b128 v[184:187], v136 offset:35840
	ds_read_b128 v[188:191], v136 offset:36864
	ds_read_b128 v[192:195], v136 offset:37888
	ds_read_b128 v[196:199], v136 offset:38912
	ds_read_b128 v[200:203], v136 offset:39936
	global_load_lds_dwordx4 v[212:213], off
	v_lshl_add_u64 v[212:213], s[64:65], 0, v[128:129]
	s_mov_b32 m0, s51
	s_nop 0
	global_load_lds_dwordx4 v[212:213], off
	s_waitcnt vmcnt(8)
	s_waitcnt lgkmcnt(0)
	s_barrier
	s_setprio 1
	s_waitcnt lgkmcnt(0)
	v_mfma_f32_16x16x32_bf16 v[64:67], v[24:27], v[172:175], v[64:67]
	v_mfma_f32_16x16x32_bf16 v[68:71], v[112:115], v[172:175], v[68:71]
	v_mfma_f32_16x16x32_bf16 v[72:75], v[24:27], v[180:183], v[72:75]
	v_mfma_f32_16x16x32_bf16 v[76:79], v[112:115], v[180:183], v[76:79]
	v_mfma_f32_16x16x32_bf16 v[80:83], v[24:27], v[188:191], v[80:83]
	v_mfma_f32_16x16x32_bf16 v[84:87], v[112:115], v[188:191], v[84:87]
	v_mfma_f32_16x16x32_bf16 v[88:91], v[24:27], v[196:199], v[88:91]
	v_mfma_f32_16x16x32_bf16 v[92:95], v[112:115], v[196:199], v[92:95]
	v_mfma_f32_16x16x32_bf16 v[64:67], v[28:31], v[176:179], v[64:67]
	v_mfma_f32_16x16x32_bf16 v[68:71], v[116:119], v[176:179], v[68:71]
	v_mfma_f32_16x16x32_bf16 v[72:75], v[28:31], v[184:187], v[72:75]
	v_mfma_f32_16x16x32_bf16 v[76:79], v[116:119], v[184:187], v[76:79]
	v_mfma_f32_16x16x32_bf16 v[80:83], v[28:31], v[192:195], v[80:83]
	v_mfma_f32_16x16x32_bf16 v[84:87], v[116:119], v[192:195], v[84:87]
	v_mfma_f32_16x16x32_bf16 v[88:91], v[28:31], v[200:203], v[88:91]
	v_mfma_f32_16x16x32_bf16 v[92:95], v[116:119], v[200:203], v[92:95]
	s_setprio 0
	s_setprio 1
	v_mfma_f32_16x16x32_bf16 v[96:99], v[120:123], v[172:175], v[96:99]
	v_mfma_f32_16x16x32_bf16 v[32:35], v[164:167], v[172:175], v[32:35]
	v_mfma_f32_16x16x32_bf16 v[36:39], v[120:123], v[180:183], v[36:39]
	v_mfma_f32_16x16x32_bf16 v[40:43], v[164:167], v[180:183], v[40:43]
	v_mfma_f32_16x16x32_bf16 v[44:47], v[120:123], v[188:191], v[44:47]
	v_mfma_f32_16x16x32_bf16 v[48:51], v[164:167], v[188:191], v[48:51]
	v_mfma_f32_16x16x32_bf16 v[52:55], v[120:123], v[196:199], v[52:55]
	v_mfma_f32_16x16x32_bf16 v[56:59], v[164:167], v[196:199], v[56:59]
	v_mfma_f32_16x16x32_bf16 v[96:99], v[124:127], v[176:179], v[96:99]
	v_mfma_f32_16x16x32_bf16 v[32:35], v[168:171], v[176:179], v[32:35]
	v_mfma_f32_16x16x32_bf16 v[36:39], v[124:127], v[184:187], v[36:39]
	v_mfma_f32_16x16x32_bf16 v[40:43], v[168:171], v[184:187], v[40:43]
	s_barrier
; #define PG8_STAGE(bufoff, gbase, voff) do { _Pragma("unroll") for (int _i = 0; _i < 2; ++_i) \
;         __builtin_amdgcn_global_load_lds((const unsigned*)((const char*)(gbase) + (voff)[_i]), (PG8_LAS unsigned*)(lds + (bufoff) + ldsw + _i * 8192), 16, 0, 0); } while (0)
; #define PG8_LDA(dst, b, h) do { _Pragma("unroll") for (int m = 0; m < 4; ++m) _Pragma("unroll") for (int k = 0; k < 2; ++k) dst[m][k] = *(const PG8_LAS bf16x8*)(lds + PG8_SA(b, h) + aoff + m * 2048 + k * 1024); } while (0)
; #define PG8_LDB(dst, b, h) do { _Pragma("unroll") for (int n = 0; n < 2; ++n) _Pragma("unroll") for (int k = 0; k < 2; ++k) dst[n][k] = *(const PG8_LAS bf16x8*)(lds + PG8_SB(b, h) + boff + n * 2048 + k * 1024); } while (0)
; #define PG8_MMA(ai, bj, At, Bt) do { __builtin_amdgcn_s_setprio(1); _Pragma("unroll") for (int m = 0; m < 4; ++m) _Pragma("unroll") for (int n = 0; n < 2; ++n) _Pragma("unroll") for (int k = 0; k < 2; ++k) \
;         acc[ai][bj][m][n] = mma16<F16>(Bt[n][k], At[m][k], acc[ai][bj][m][n]); __builtin_amdgcn_s_setprio(0); } while (0)
; #define PG8_WAIT_V(n) asm volatile("s_waitcnt vmcnt(" #n ")" ::: "memory")
; template <class Epi, class Sched, bool ALIGN_EPI = false, bool SP2 = false, bool F16 = false>
; __device__ __forceinline__ void gemm_phase(PG8_LAS unsigned char* lds, const Gemm g, const Sched& S, const Epi& E, const int wid_in) {
;     ...
;             PG8_LDB(B0, 0, 0); PG8_LDB(B1, 0, 1); PG8_SCHED; PG8_LDA(At, 0, 0); PG8_STAGE(PG8_SA(1, 1), a1 + hstep, voffA);
;             PG8_WAIT_V(8); PG8_WAIT_L(0); PG8_BAR; PG8_MMA(0, 0, At, B0); PG8_MMA(0, 1, At, B1); PG8_BAR; PG8_SCHED;
;             PG8_LDA(At, 0, 1); PG8_STAGE(PG8_SB(0, 0), b2, voffB); PG8_STAGE(PG8_SB(0, 1), b2 + hstep, voffB); PG8_STAGE(PG8_SA(0, 0), a2, voffA);
;             PG8_WAIT_V(8); PG8_WAIT_L(0); PG8_BAR; PG8_MMA(1, 0, At, B0); PG8_MMA(1, 1, At, B1); PG8_BAR; PG8_SCHED;
;             PG8_LDB(B0, 1, 0); PG8_LDB(B1, 1, 1); PG8_SCHED; PG8_LDA(At, 1, 0); PG8_STAGE(PG8_SA(0, 1), a2 + hstep, voffA);
;             PG8_WAIT_V(8); PG8_WAIT_L(0); PG8_BAR; PG8_MMA(0, 0, At, B0); PG8_MMA(0, 1, At, B1); PG8_BAR; PG8_SCHED;
;             PG8_LDA(At, 1, 1); PG8_STAGE(PG8_SB(1, 0), b3, voffB); PG8_STAGE(PG8_SB(1, 1), b3 + hstep, voffB); PG8_STAGE(PG8_SA(1, 0), a3, voffA);
;             PG8_WAIT_V(8); PG8_WAIT_L(0); PG8_BAR; PG8_MMA(1, 0, At, B0); PG8_MMA(1, 1, At, B1); PG8_BAR; PG8_SCHED;
	v_mfma_f32_16x16x32_bf16 v[44:47], v[124:127], v[192:195], v[44:47]
	v_mfma_f32_16x16x32_bf16 v[48:51], v[168:171], v[192:195], v[48:51]
	v_mfma_f32_16x16x32_bf16 v[52:55], v[124:127], v[200:203], v[52:55]
	v_mfma_f32_16x16x32_bf16 v[56:59], v[168:171], v[200:203], v[56:59]
	s_setprio 0
	s_mov_b32 m0, s57
	v_lshl_add_u64 v[204:205], v[204:205], 0, s[28:29]
	s_add_u32 s48, s48, 0x10180
	ds_read_b128 v[172:175], v136 offset:49152
	ds_read_b128 v[176:179], v136 offset:50176
	ds_read_b128 v[180:183], v136 offset:51200
	ds_read_b128 v[184:187], v136 offset:52224
	ds_read_b128 v[188:191], v136 offset:53248
	ds_read_b128 v[192:195], v136 offset:54272
	ds_read_b128 v[196:199], v136 offset:55296
	ds_read_b128 v[200:203], v136 offset:56320
	global_load_lds_dwordx4 v[204:205], off
	v_lshl_add_u64 v[204:205], v[206:207], 0, s[28:29]
	s_mov_b32 m0, s58
	s_addc_u32 s49, s49, 0
	global_load_lds_dwordx4 v[204:205], off
	v_lshl_add_u64 v[204:205], s[48:49], 0, v[130:131]
	s_mov_b32 m0, s59
	s_nop 0
	global_load_lds_dwordx4 v[204:205], off
	v_lshl_add_u64 v[204:205], s[48:49], 0, v[128:129]
	s_mov_b32 m0, s60
	s_nop 0
	global_load_lds_dwordx4 v[204:205], off
	v_lshl_add_u64 v[204:205], v[208:209], 0, s[28:29]
	s_mov_b32 m0, s75
	s_nop 0
	global_load_lds_dwordx4 v[204:205], off
	v_lshl_add_u64 v[204:205], v[210:211], 0, s[28:29]
	s_mov_b32 m0, s14
	s_nop 0
	global_load_lds_dwordx4 v[204:205], off
	s_waitcnt vmcnt(8)
	s_waitcnt lgkmcnt(0)
	s_barrier
	s_setprio 1
	s_waitcnt lgkmcnt(0)
	v_mfma_f32_16x16x32_bf16 v[0:3], v[24:27], v[196:199], v[0:3]
	v_mfma_f32_16x16x32_bf16 v[4:7], v[112:115], v[196:199], v[4:7]
	v_mfma_f32_16x16x32_bf16 v[140:143], v[24:27], v[172:175], v[140:143]
	v_mfma_f32_16x16x32_bf16 v[144:147], v[112:115], v[172:175], v[144:147]
	v_mfma_f32_16x16x32_bf16 v[148:151], v[24:27], v[180:183], v[148:151]
	v_mfma_f32_16x16x32_bf16 v[152:155], v[112:115], v[180:183], v[152:155]
	v_mfma_f32_16x16x32_bf16 v[156:159], v[24:27], v[188:191], v[156:159]
	v_mfma_f32_16x16x32_bf16 v[160:163], v[112:115], v[188:191], v[160:163]
	v_mfma_f32_16x16x32_bf16 v[0:3], v[28:31], v[200:203], v[0:3]
	v_mfma_f32_16x16x32_bf16 v[4:7], v[116:119], v[200:203], v[4:7]
	v_mfma_f32_16x16x32_bf16 v[140:143], v[28:31], v[176:179], v[140:143]
	v_mfma_f32_16x16x32_bf16 v[144:147], v[116:119], v[176:179], v[144:147]
	v_mfma_f32_16x16x32_bf16 v[148:151], v[28:31], v[184:187], v[148:151]
	v_mfma_f32_16x16x32_bf16 v[152:155], v[116:119], v[184:187], v[152:155]
	v_mfma_f32_16x16x32_bf16 v[156:159], v[28:31], v[192:195], v[156:159]
	v_mfma_f32_16x16x32_bf16 v[160:163], v[116:119], v[192:195], v[160:163]
	s_setprio 0
	s_setprio 1
	v_mfma_f32_16x16x32_bf16 v[8:11], v[120:123], v[172:175], v[8:11]
	v_mfma_f32_16x16x32_bf16 v[12:15], v[164:167], v[172:175], v[12:15]
	v_mfma_f32_16x16x32_bf16 v[24:27], v[120:123], v[180:183], v[60:63]
	v_mfma_f32_16x16x32_bf16 v[28:31], v[164:167], v[180:183], v[100:103]
	v_mfma_f32_16x16x32_bf16 v[60:63], v[120:123], v[188:191], v[104:107]
	v_mfma_f32_16x16x32_bf16 v[100:103], v[164:167], v[188:191], v[108:111]
	v_mfma_f32_16x16x32_bf16 v[16:19], v[120:123], v[196:199], v[16:19]
	v_mfma_f32_16x16x32_bf16 v[20:23], v[164:167], v[196:199], v[20:23]
	v_mfma_f32_16x16x32_bf16 v[8:11], v[124:127], v[176:179], v[8:11]
	v_mfma_f32_16x16x32_bf16 v[12:15], v[168:171], v[176:179], v[12:15]
	v_mfma_f32_16x16x32_bf16 v[24:27], v[124:127], v[184:187], v[24:27]
	v_mfma_f32_16x16x32_bf16 v[28:31], v[168:171], v[184:187], v[28:31]
	s_barrier
	v_mfma_f32_16x16x32_bf16 v[60:63], v[124:127], v[192:195], v[60:63]
	v_mfma_f32_16x16x32_bf16 v[100:103], v[168:171], v[192:195], v[100:103]
	v_mfma_f32_16x16x32_bf16 v[16:19], v[124:127], v[200:203], v[16:19]
	v_mfma_f32_16x16x32_bf16 v[20:23], v[168:171], v[200:203], v[20:23]
	s_setprio 0
	ds_read_b128 v[104:107], v134
	ds_read_b128 v[108:111], v134 offset:1024
	ds_read_b128 v[112:115], v134 offset:2048
	ds_read_b128 v[116:119], v134 offset:3072
	ds_read_b128 v[120:123], v135
	ds_read_b128 v[124:127], v135 offset:1024
	ds_read_b128 v[164:167], v135 offset:2048
	ds_read_b128 v[168:171], v135 offset:3072
	s_add_u32 s46, s46, 0x10180
	s_addc_u32 s47, s47, 0
	s_mov_b32 m0, s15
	v_lshl_add_u64 v[204:205], s[46:47], 0, v[130:131]
	ds_read_b128 v[172:175], v136
	ds_read_b128 v[176:179], v136 offset:1024
	ds_read_b128 v[180:183], v136 offset:2048
	ds_read_b128 v[184:187], v136 offset:3072
	ds_read_b128 v[188:191], v136 offset:4096
	ds_read_b128 v[192:195], v136 offset:5120
	ds_read_b128 v[196:199], v136 offset:6144
	ds_read_b128 v[200:203], v136 offset:7168
	global_load_lds_dwordx4 v[204:205], off
	v_lshl_add_u64 v[204:205], s[46:47], 0, v[128:129]
	s_mov_b32 m0, s52
	s_nop 0
	global_load_lds_dwordx4 v[204:205], off
	s_waitcnt vmcnt(8)
	s_waitcnt lgkmcnt(0)
	s_barrier
; #define PG8_STAGE(bufoff, gbase, voff) do { _Pragma("unroll") for (int _i = 0; _i < 2; ++_i) \
;         __builtin_amdgcn_global_load_lds((const unsigned*)((const char*)(gbase) + (voff)[_i]), (PG8_LAS unsigned*)(lds + (bufoff) + ldsw + _i * 8192), 16, 0, 0); } while (0)
; #define PG8_LDA(dst, b, h) do { _Pragma("unroll") for (int m = 0; m < 4; ++m) _Pragma("unroll") for (int k = 0; k < 2; ++k) dst[m][k] = *(const PG8_LAS bf16x8*)(lds + PG8_SA(b, h) + aoff + m * 2048 + k * 1024); } while (0)
; #define PG8_LDB(dst, b, h) do { _Pragma("unroll") for (int n = 0; n < 2; ++n) _Pragma("unroll") for (int k = 0; k < 2; ++k) dst[n][k] = *(const PG8_LAS bf16x8*)(lds + PG8_SB(b, h) + boff + n * 2048 + k * 1024); } while (0)
; #define PG8_MMA(ai, bj, At, Bt) do { __builtin_amdgcn_s_setprio(1); _Pragma("unroll") for (int m = 0; m < 4; ++m) _Pragma("unroll") for (int n = 0; n < 2; ++n) _Pragma("unroll") for (int k = 0; k < 2; ++k) \
;         acc[ai][bj][m][n] = mma16<F16>(Bt[n][k], At[m][k], acc[ai][bj][m][n]); __builtin_amdgcn_s_setprio(0); } while (0)
; #define PG8_WAIT_V(n) asm volatile("s_waitcnt vmcnt(" #n ")" ::: "memory")
; #define PG8_WAIT_L(n) asm volatile("s_waitcnt lgkmcnt(" #n ")" ::: "memory")
; #define PG8_BAR __builtin_amdgcn_s_barrier()
; #define PG8_SCHED __builtin_amdgcn_sched_barrier(0)
; template <class Epi, class Sched, bool ALIGN_EPI = false, bool SP2 = false, bool F16 = false>
; __device__ __forceinline__ void gemm_phase(PG8_LAS unsigned char* lds, const Gemm g, const Sched& S, const Epi& E, const int wid_in) {
;     ...
;             PG8_LDB(B0, 0, 0); PG8_LDB(B1, 0, 1); PG8_SCHED; PG8_LDA(At, 0, 0); PG8_STAGE(PG8_SA(1, 1), a1 + hstep, voffA);
;             PG8_WAIT_V(8); PG8_WAIT_L(0); PG8_BAR; PG8_MMA(0, 0, At, B0); PG8_MMA(0, 1, At, B1); PG8_BAR; PG8_SCHED;
;             PG8_LDA(At, 0, 1); PG8_STAGE(PG8_SB(0, 0), b2, voffB); PG8_STAGE(PG8_SB(0, 1), b2 + hstep, voffB); PG8_STAGE(PG8_SA(0, 0), a2, voffA);
;             PG8_WAIT_V(8); PG8_WAIT_L(0); PG8_BAR; PG8_MMA(1, 0, At, B0); PG8_MMA(1, 1, At, B1); PG8_BAR; PG8_SCHED;
	s_setprio 1
	s_waitcnt lgkmcnt(0)
	v_mfma_f32_16x16x32_bf16 v[64:67], v[104:107], v[172:175], v[64:67]
	v_mfma_f32_16x16x32_bf16 v[68:71], v[112:115], v[172:175], v[68:71]
	v_mfma_f32_16x16x32_bf16 v[72:75], v[104:107], v[180:183], v[72:75]
	v_mfma_f32_16x16x32_bf16 v[76:79], v[112:115], v[180:183], v[76:79]
	v_mfma_f32_16x16x32_bf16 v[80:83], v[104:107], v[188:191], v[80:83]
	v_mfma_f32_16x16x32_bf16 v[84:87], v[112:115], v[188:191], v[84:87]
	v_mfma_f32_16x16x32_bf16 v[88:91], v[104:107], v[196:199], v[88:91]
	v_mfma_f32_16x16x32_bf16 v[92:95], v[112:115], v[196:199], v[92:95]
	v_mfma_f32_16x16x32_bf16 v[64:67], v[108:111], v[176:179], v[64:67]
	v_mfma_f32_16x16x32_bf16 v[68:71], v[116:119], v[176:179], v[68:71]
	v_mfma_f32_16x16x32_bf16 v[72:75], v[108:111], v[184:187], v[72:75]
	v_mfma_f32_16x16x32_bf16 v[76:79], v[116:119], v[184:187], v[76:79]
	v_mfma_f32_16x16x32_bf16 v[80:83], v[108:111], v[192:195], v[80:83]
	v_mfma_f32_16x16x32_bf16 v[84:87], v[116:119], v[192:195], v[84:87]
	v_mfma_f32_16x16x32_bf16 v[88:91], v[108:111], v[200:203], v[88:91]
	v_mfma_f32_16x16x32_bf16 v[92:95], v[116:119], v[200:203], v[92:95]
	s_setprio 0
	s_setprio 1
	v_mfma_f32_16x16x32_bf16 v[32:35], v[164:167], v[172:175], v[32:35]
	v_mfma_f32_16x16x32_bf16 v[96:99], v[120:123], v[172:175], v[96:99]
	v_mfma_f32_16x16x32_bf16 v[172:175], v[168:171], v[176:179], v[32:35]
	v_mfma_f32_16x16x32_bf16 v[32:35], v[120:123], v[180:183], v[36:39]
	v_mfma_f32_16x16x32_bf16 v[204:207], v[124:127], v[176:179], v[96:99]
	v_mfma_f32_16x16x32_bf16 v[176:179], v[124:127], v[184:187], v[32:35]
	v_mfma_f32_16x16x32_bf16 v[32:35], v[164:167], v[180:183], v[40:43]
	v_mfma_f32_16x16x32_bf16 v[40:43], v[168:171], v[184:187], v[32:35]
	v_mfma_f32_16x16x32_bf16 v[32:35], v[120:123], v[188:191], v[44:47]
	v_mfma_f32_16x16x32_bf16 v[44:47], v[124:127], v[192:195], v[32:35]
	v_mfma_f32_16x16x32_bf16 v[32:35], v[164:167], v[188:191], v[48:51]
	v_mfma_f32_16x16x32_bf16 v[48:51], v[168:171], v[192:195], v[32:35]
	s_barrier
	v_mfma_f32_16x16x32_bf16 v[32:35], v[120:123], v[196:199], v[52:55]
	v_mfma_f32_16x16x32_bf16 v[52:55], v[124:127], v[200:203], v[32:35]
	v_mfma_f32_16x16x32_bf16 v[32:35], v[164:167], v[196:199], v[56:59]
	v_mfma_f32_16x16x32_bf16 v[56:59], v[168:171], v[200:203], v[32:35]
	s_setprio 0
	s_mov_b32 m0, s53
	v_lshl_add_u64 v[240:241], s[36:37], 0, v[130:131]
	s_add_u32 s46, s36, 0x10000
	s_nop 1
	ds_read_b128 v[32:35], v136 offset:16384
	ds_read_b128 v[36:39], v136 offset:17408
	ds_read_b128 v[96:99], v136 offset:18432
	ds_read_b128 v[180:183], v136 offset:19456
	ds_read_b128 v[184:187], v136 offset:20480
	ds_read_b128 v[188:191], v136 offset:21504
	ds_read_b128 v[192:195], v136 offset:22528
	ds_read_b128 v[196:199], v136 offset:23552
	global_load_lds_dwordx4 v[240:241], off
	v_lshl_add_u64 v[242:243], s[36:37], 0, v[128:129]
	s_mov_b32 m0, s54
	s_addc_u32 s47, s37, 0
	global_load_lds_dwordx4 v[242:243], off
	v_lshl_add_u64 v[200:201], s[46:47], 0, v[130:131]
	s_mov_b32 m0, s55
	v_lshl_add_u64 v[244:245], s[44:45], 0, v[130:131]
	global_load_lds_dwordx4 v[200:201], off
	v_lshl_add_u64 v[200:201], s[46:47], 0, v[128:129]
	s_mov_b32 m0, s56
	v_lshl_add_u64 v[246:247], s[44:45], 0, v[128:129]
	global_load_lds_dwordx4 v[200:201], off
	s_mov_b32 m0, s74
	s_nop 0
	global_load_lds_dwordx4 v[244:245], off
	s_mov_b32 m0, s43
	s_nop 0
	global_load_lds_dwordx4 v[246:247], off
	s_waitcnt vmcnt(8)
	s_waitcnt lgkmcnt(0)
	s_barrier
	s_setprio 1
	s_waitcnt lgkmcnt(0)
	v_mfma_f32_16x16x32_bf16 v[0:3], v[104:107], v[192:195], v[0:3]
	v_mfma_f32_16x16x32_bf16 v[140:143], v[104:107], v[32:35], v[140:143]
	v_mfma_f32_16x16x32_bf16 v[144:147], v[112:115], v[32:35], v[144:147]
	v_mfma_f32_16x16x32_bf16 v[148:151], v[104:107], v[96:99], v[148:151]
	v_mfma_f32_16x16x32_bf16 v[152:155], v[112:115], v[96:99], v[152:155]
	v_mfma_f32_16x16x32_bf16 v[156:159], v[104:107], v[184:187], v[156:159]
	v_mfma_f32_16x16x32_bf16 v[160:163], v[112:115], v[184:187], v[160:163]
	v_mfma_f32_16x16x32_bf16 v[0:3], v[108:111], v[196:199], v[0:3]
	v_mfma_f32_16x16x32_bf16 v[4:7], v[112:115], v[192:195], v[4:7]
	v_mfma_f32_16x16x32_bf16 v[140:143], v[108:111], v[36:39], v[140:143]
	v_mfma_f32_16x16x32_bf16 v[144:147], v[116:119], v[36:39], v[144:147]
	v_mfma_f32_16x16x32_bf16 v[148:151], v[108:111], v[180:183], v[148:151]
	v_mfma_f32_16x16x32_bf16 v[152:155], v[116:119], v[180:183], v[152:155]
	v_mfma_f32_16x16x32_bf16 v[156:159], v[108:111], v[188:191], v[156:159]
	v_mfma_f32_16x16x32_bf16 v[160:163], v[116:119], v[188:191], v[160:163]
	v_mfma_f32_16x16x32_bf16 v[200:203], v[116:119], v[196:199], v[4:7]
	s_setprio 0
	s_setprio 1
	v_mfma_f32_16x16x32_bf16 v[4:7], v[120:123], v[32:35], v[8:11]
	v_mfma_f32_16x16x32_bf16 v[8:11], v[124:127], v[36:39], v[4:7]
	v_mfma_f32_16x16x32_bf16 v[4:7], v[164:167], v[32:35], v[12:15]
	v_mfma_f32_16x16x32_bf16 v[12:15], v[168:171], v[36:39], v[4:7]
	v_mfma_f32_16x16x32_bf16 v[4:7], v[120:123], v[96:99], v[24:27]
	v_mfma_f32_16x16x32_bf16 v[24:27], v[124:127], v[180:183], v[4:7]
	v_mfma_f32_16x16x32_bf16 v[4:7], v[164:167], v[96:99], v[28:31]
	v_mfma_f32_16x16x32_bf16 v[28:31], v[168:171], v[180:183], v[4:7]
	v_mfma_f32_16x16x32_bf16 v[4:7], v[120:123], v[184:187], v[60:63]
	v_mfma_f32_16x16x32_bf16 v[180:183], v[124:127], v[188:191], v[4:7]
	v_mfma_f32_16x16x32_bf16 v[4:7], v[164:167], v[184:187], v[100:103]
	v_mfma_f32_16x16x32_bf16 v[184:187], v[168:171], v[188:191], v[4:7]
	s_barrier
; #define PG8_STAGE(bufoff, gbase, voff) do { _Pragma("unroll") for (int _i = 0; _i < 2; ++_i) \
;         __builtin_amdgcn_global_load_lds((const unsigned*)((const char*)(gbase) + (voff)[_i]), (PG8_LAS unsigned*)(lds + (bufoff) + ldsw + _i * 8192), 16, 0, 0); } while (0)
; #define PG8_LDA(dst, b, h) do { _Pragma("unroll") for (int m = 0; m < 4; ++m) _Pragma("unroll") for (int k = 0; k < 2; ++k) dst[m][k] = *(const PG8_LAS bf16x8*)(lds + PG8_SA(b, h) + aoff + m * 2048 + k * 1024); } while (0)
; #define PG8_LDB(dst, b, h) do { _Pragma("unroll") for (int n = 0; n < 2; ++n) _Pragma("unroll") for (int k = 0; k < 2; ++k) dst[n][k] = *(const PG8_LAS bf16x8*)(lds + PG8_SB(b, h) + boff + n * 2048 + k * 1024); } while (0)
; #define PG8_MMA(ai, bj, At, Bt) do { __builtin_amdgcn_s_setprio(1); _Pragma("unroll") for (int m = 0; m < 4; ++m) _Pragma("unroll") for (int n = 0; n < 2; ++n) _Pragma("unroll") for (int k = 0; k < 2; ++k) \
;         acc[ai][bj][m][n] = mma16<F16>(Bt[n][k], At[m][k], acc[ai][bj][m][n]); __builtin_amdgcn_s_setprio(0); } while (0)
; #define PG8_WAIT_V(n) asm volatile("s_waitcnt vmcnt(" #n ")" ::: "memory")
; #define PG8_WAIT_L(n) asm volatile("s_waitcnt lgkmcnt(" #n ")" ::: "memory")
; #define PG8_BAR __builtin_amdgcn_s_barrier()
; #define PG8_SCHED __builtin_amdgcn_sched_barrier(0)
; template <class Epi, class Sched, bool ALIGN_EPI = false, bool SP2 = false, bool F16 = false>
; __device__ __forceinline__ void gemm_phase(PG8_LAS unsigned char* lds, const Gemm g, const Sched& S, const Epi& E, const int wid_in) {
;     ...
;             PG8_WAIT_V(8); PG8_WAIT_L(0); PG8_BAR; PG8_MMA(1, 0, At, B0); PG8_MMA(1, 1, At, B1); PG8_BAR; PG8_SCHED;
;             PG8_LDB(B0, 1, 0); PG8_LDB(B1, 1, 1); PG8_SCHED; PG8_LDA(At, 1, 0); PG8_STAGE(PG8_SA(0, 1), a2 + hstep, voffA);
;             PG8_WAIT_V(8); PG8_WAIT_L(0); PG8_BAR; PG8_MMA(0, 0, At, B0); PG8_MMA(0, 1, At, B1); PG8_BAR; PG8_SCHED;
;             PG8_LDA(At, 1, 1); PG8_STAGE(PG8_SB(1, 0), b3, voffB); PG8_STAGE(PG8_SB(1, 1), b3 + hstep, voffB); PG8_STAGE(PG8_SA(1, 0), a3, voffA);
;             PG8_WAIT_V(8); PG8_WAIT_L(0); PG8_BAR; PG8_MMA(1, 0, At, B0); PG8_MMA(1, 1, At, B1); PG8_BAR; PG8_SCHED;
;     ...
;         if constexpr (ALIGN_EPI) { if (wr == 0) PG8_BAR; }
;         if constexpr (!Epi::AFTER_DRAIN) { E(acc, cur, wr, wc, fr, fq); S.done(cur); }
;         if (!has_next) break;
	v_mfma_f32_16x16x32_bf16 v[4:7], v[120:123], v[192:195], v[16:19]
	v_mfma_f32_16x16x32_bf16 v[188:191], v[124:127], v[196:199], v[4:7]
	v_mfma_f32_16x16x32_bf16 v[4:7], v[164:167], v[192:195], v[20:23]
	v_mfma_f32_16x16x32_bf16 v[164:167], v[168:171], v[196:199], v[4:7]
	s_setprio 0
	s_nop 4
	ds_read_b128 v[4:7], v137
	ds_read_b128 v[60:63], v137 offset:1024
	ds_read_b128 v[168:171], v137 offset:2048
	ds_read_b128 v[192:195], v137 offset:3072
	ds_read_b128 v[196:199], v138
	ds_read_b128 v[208:211], v138 offset:1024
	ds_read_b128 v[212:215], v138 offset:2048
	ds_read_b128 v[216:219], v138 offset:3072
	s_add_u32 s44, s44, 0x10000
	s_addc_u32 s45, s45, 0
	s_mov_b32 m0, s50
	v_lshl_add_u64 v[32:33], s[44:45], 0, v[130:131]
	ds_read_b128 v[16:19], v136 offset:32768
	ds_read_b128 v[20:23], v136 offset:33792
	ds_read_b128 v[104:107], v136 offset:34816
	ds_read_b128 v[220:223], v136 offset:35840
	ds_read_b128 v[224:227], v136 offset:36864
	ds_read_b128 v[228:231], v136 offset:37888
	ds_read_b128 v[232:235], v136 offset:38912
	ds_read_b128 v[236:239], v136 offset:39936
	global_load_lds_dwordx4 v[32:33], off
	v_lshl_add_u64 v[32:33], s[44:45], 0, v[128:129]
	s_mov_b32 m0, s51
	s_nop 0
	global_load_lds_dwordx4 v[32:33], off
	s_waitcnt vmcnt(8)
	s_waitcnt lgkmcnt(0)
	s_barrier
	s_setprio 1
	s_waitcnt lgkmcnt(0)
	v_mfma_f32_16x16x32_bf16 v[32:35], v[4:7], v[16:19], v[64:67]
	v_mfma_f32_16x16x32_bf16 v[116:119], v[60:63], v[20:23], v[32:35]
	v_mfma_f32_16x16x32_bf16 v[32:35], v[168:171], v[16:19], v[68:71]
	v_mfma_f32_16x16x32_bf16 v[112:115], v[192:195], v[20:23], v[32:35]
	v_mfma_f32_16x16x32_bf16 v[32:35], v[4:7], v[104:107], v[72:75]
	v_mfma_f32_16x16x32_bf16 v[100:103], v[60:63], v[220:223], v[32:35]
	v_mfma_f32_16x16x32_bf16 v[32:35], v[168:171], v[104:107], v[76:79]
	v_mfma_f32_16x16x32_bf16 v[96:99], v[192:195], v[220:223], v[32:35]
	v_mfma_f32_16x16x32_bf16 v[32:35], v[4:7], v[224:227], v[80:83]
	v_mfma_f32_16x16x32_bf16 v[68:71], v[60:63], v[228:231], v[32:35]
	v_mfma_f32_16x16x32_bf16 v[32:35], v[168:171], v[224:227], v[84:87]
	v_mfma_f32_16x16x32_bf16 v[64:67], v[192:195], v[228:231], v[32:35]
	v_mfma_f32_16x16x32_bf16 v[32:35], v[4:7], v[232:235], v[88:91]
	v_mfma_f32_16x16x32_bf16 v[36:39], v[60:63], v[236:239], v[32:35]
	v_mfma_f32_16x16x32_bf16 v[32:35], v[168:171], v[232:235], v[92:95]
	v_mfma_f32_16x16x32_bf16 v[32:35], v[192:195], v[236:239], v[32:35]
	s_setprio 0
	s_setprio 1
	v_mfma_f32_16x16x32_bf16 v[72:75], v[196:199], v[16:19], v[204:207]
	v_mfma_f32_16x16x32_bf16 v[16:19], v[212:215], v[16:19], v[172:175]
	v_mfma_f32_16x16x32_bf16 v[120:123], v[216:219], v[20:23], v[16:19]
	v_mfma_f32_16x16x32_bf16 v[16:19], v[196:199], v[104:107], v[176:179]
	v_mfma_f32_16x16x32_bf16 v[108:111], v[208:211], v[220:223], v[16:19]
	v_mfma_f32_16x16x32_bf16 v[16:19], v[212:215], v[104:107], v[40:43]
	v_mfma_f32_16x16x32_bf16 v[104:107], v[216:219], v[220:223], v[16:19]
	v_mfma_f32_16x16x32_bf16 v[16:19], v[196:199], v[224:227], v[44:47]
	v_mfma_f32_16x16x32_bf16 v[80:83], v[208:211], v[228:231], v[16:19]
	v_mfma_f32_16x16x32_bf16 v[16:19], v[212:215], v[224:227], v[48:51]
	v_mfma_f32_16x16x32_bf16 v[124:127], v[208:211], v[20:23], v[72:75]
	v_mfma_f32_16x16x32_bf16 v[72:75], v[216:219], v[228:231], v[16:19]
	s_barrier
	v_mfma_f32_16x16x32_bf16 v[16:19], v[196:199], v[232:235], v[52:55]
	v_mfma_f32_16x16x32_bf16 v[48:51], v[208:211], v[236:239], v[16:19]
	v_mfma_f32_16x16x32_bf16 v[16:19], v[212:215], v[232:235], v[56:59]
	v_mfma_f32_16x16x32_bf16 v[40:43], v[216:219], v[236:239], v[16:19]
	s_setprio 0
	s_mov_b32 m0, s57
	s_nop 3
	v_lshl_add_u64 v[16:17], v[240:241], 0, s[24:25]
	s_add_u32 s36, s36, 0x10080
	ds_read_b128 v[56:59], v136 offset:49152
	ds_read_b128 v[88:91], v136 offset:50176
	ds_read_b128 v[172:175], v136 offset:51200
	ds_read_b128 v[176:179], v136 offset:52224
	ds_read_b128 v[204:207], v136 offset:53248
	ds_read_b128 v[220:223], v136 offset:54272
	ds_read_b128 v[224:227], v136 offset:55296
	ds_read_b128 v[228:231], v136 offset:56320
	global_load_lds_dwordx4 v[16:17], off
	v_lshl_add_u64 v[16:17], v[242:243], 0, s[24:25]
	s_mov_b32 m0, s58
	s_addc_u32 s37, s37, 0
	global_load_lds_dwordx4 v[16:17], off
	v_lshl_add_u64 v[16:17], s[36:37], 0, v[130:131]
	s_mov_b32 m0, s59
	s_nop 0
	global_load_lds_dwordx4 v[16:17], off
	v_lshl_add_u64 v[16:17], s[36:37], 0, v[128:129]
	s_mov_b32 m0, s60
	s_nop 0
	global_load_lds_dwordx4 v[16:17], off
	v_lshl_add_u64 v[16:17], v[244:245], 0, s[24:25]
	s_mov_b32 m0, s75
	s_nop 0
	global_load_lds_dwordx4 v[16:17], off
	v_lshl_add_u64 v[16:17], v[246:247], 0, s[24:25]
	s_mov_b32 m0, s14
	s_nop 0
	global_load_lds_dwordx4 v[16:17], off
	s_waitcnt vmcnt(8)
	s_waitcnt lgkmcnt(0)
	s_barrier
	s_setprio 1
	s_waitcnt lgkmcnt(0)
	v_mfma_f32_16x16x32_bf16 v[16:19], v[4:7], v[56:59], v[140:143]
	v_mfma_f32_16x16x32_bf16 v[84:87], v[60:63], v[88:91], v[16:19]
	v_mfma_f32_16x16x32_bf16 v[16:19], v[168:171], v[56:59], v[144:147]
	v_mfma_f32_16x16x32_bf16 v[76:79], v[192:195], v[88:91], v[16:19]
	v_mfma_f32_16x16x32_bf16 v[16:19], v[4:7], v[172:175], v[148:151]
	v_mfma_f32_16x16x32_bf16 v[52:55], v[60:63], v[176:179], v[16:19]
	v_mfma_f32_16x16x32_bf16 v[16:19], v[168:171], v[172:175], v[152:155]
	v_mfma_f32_16x16x32_bf16 v[44:47], v[192:195], v[176:179], v[16:19]
	v_mfma_f32_16x16x32_bf16 v[16:19], v[4:7], v[204:207], v[156:159]
	v_mfma_f32_16x16x32_bf16 v[0:3], v[4:7], v[224:227], v[0:3]
	v_mfma_f32_16x16x32_bf16 v[20:23], v[60:63], v[220:223], v[16:19]
	v_mfma_f32_16x16x32_bf16 v[16:19], v[168:171], v[204:207], v[160:163]
	v_mfma_f32_16x16x32_bf16 v[4:7], v[60:63], v[228:231], v[0:3]
	v_mfma_f32_16x16x32_bf16 v[0:3], v[168:171], v[224:227], v[200:203]
	v_mfma_f32_16x16x32_bf16 v[16:19], v[192:195], v[220:223], v[16:19]
	v_mfma_f32_16x16x32_bf16 v[0:3], v[192:195], v[228:231], v[0:3]
	s_setprio 0
	s_setprio 1
	v_mfma_f32_16x16x32_bf16 v[8:11], v[196:199], v[56:59], v[8:11]
	v_mfma_f32_16x16x32_bf16 v[92:95], v[208:211], v[88:91], v[8:11]
	v_mfma_f32_16x16x32_bf16 v[8:11], v[212:215], v[56:59], v[12:15]
	v_mfma_f32_16x16x32_bf16 v[88:91], v[216:219], v[88:91], v[8:11]
	v_mfma_f32_16x16x32_bf16 v[8:11], v[196:199], v[172:175], v[24:27]
	v_mfma_f32_16x16x32_bf16 v[60:63], v[208:211], v[176:179], v[8:11]
	v_mfma_f32_16x16x32_bf16 v[8:11], v[212:215], v[172:175], v[28:31]
	v_mfma_f32_16x16x32_bf16 v[56:59], v[216:219], v[176:179], v[8:11]
	v_mfma_f32_16x16x32_bf16 v[8:11], v[196:199], v[204:207], v[180:183]
	v_mfma_f32_16x16x32_bf16 v[28:31], v[208:211], v[220:223], v[8:11]
	v_mfma_f32_16x16x32_bf16 v[8:11], v[212:215], v[204:207], v[184:187]
	v_mfma_f32_16x16x32_bf16 v[24:27], v[216:219], v[220:223], v[8:11]
	s_barrier
	v_mfma_f32_16x16x32_bf16 v[8:11], v[196:199], v[224:227], v[188:191]
	v_mfma_f32_16x16x32_bf16 v[12:15], v[208:211], v[228:231], v[8:11]
	v_mfma_f32_16x16x32_bf16 v[8:11], v[212:215], v[224:227], v[164:167]
	v_mfma_f32_16x16x32_bf16 v[8:11], v[216:219], v[228:231], v[8:11]
	s_setprio 0
	s_and_b64 vcc, exec, s[8:9]
	s_cbranch_vccnz .LBB0_1279
	s_barrier

; #define PG8_STAGE(bufoff, gbase, voff) do { _Pragma("unroll") for (int _i = 0; _i < 2; ++_i) \
;         __builtin_amdgcn_global_load_lds((const unsigned*)((const char*)(gbase) + (voff)[_i]), (PG8_LAS unsigned*)(lds + (bufoff) + ldsw + _i * 8192), 16, 0, 0); } while (0)
; #define PG8_LDA(dst, b, h) do { _Pragma("unroll") for (int m = 0; m < 4; ++m) _Pragma("unroll") for (int k = 0; k < 2; ++k) dst[m][k] = *(const PG8_LAS bf16x8*)(lds + PG8_SA(b, h) + aoff + m * 2048 + k * 1024); } while (0)
; #define PG8_LDB(dst, b, h) do { _Pragma("unroll") for (int n = 0; n < 2; ++n) _Pragma("unroll") for (int k = 0; k < 2; ++k) dst[n][k] = *(const PG8_LAS bf16x8*)(lds + PG8_SB(b, h) + boff + n * 2048 + k * 1024); } while (0)
; #define PG8_MMA(ai, bj, At, Bt) do { __builtin_amdgcn_s_setprio(1); _Pragma("unroll") for (int m = 0; m < 4; ++m) _Pragma("unroll") for (int n = 0; n < 2; ++n) _Pragma("unroll") for (int k = 0; k < 2; ++k) \
;         acc[ai][bj][m][n] = mma16<F16>(Bt[n][k], At[m][k], acc[ai][bj][m][n]); __builtin_amdgcn_s_setprio(0); } while (0)
; #define PG8_WAIT_V(n) asm volatile("s_waitcnt vmcnt(" #n ")" ::: "memory")
; #define PG8_WAIT_L(n) asm volatile("s_waitcnt lgkmcnt(" #n ")" ::: "memory")
; #define PG8_BAR __builtin_amdgcn_s_barrier()
; #define PG8_SCHED __builtin_amdgcn_sched_barrier(0)
; template <class Epi, class Sched, bool ALIGN_EPI = false, bool SP2 = false, bool F16 = false>
; __device__ __forceinline__ void gemm_phase(PG8_LAS unsigned char* lds, const Gemm g, const Sched& S, const Epi& E, const int wid_in) {
;     ...
;         for (int t = 0; t < nt; t += 2) {
;             const bool last = (t == nt - 2);
;             const char* a1 = cA + (size_t)(t + 1) * kstep;
;             const char* a2 = last ? nA : cA + (size_t)(t + 2) * kstep; const char* b2 = last ? nB : cB + (size_t)(t + 2) * kstep;
;             const char* a3 = a2 + kstep; const char* b3 = b2 + kstep;
;             if (last && has_next) S.a_ready(nxt);
;             if constexpr (SP2) {
;             PG8_LDB(B0, 0, 0); PG8_LDB(B1, 0, 1); PG8_SCHED; PG8_LDA(At, 0, 0); PG8_STAGE(PG8_SA(1, 1), a1 + hstep, voffA);
;             PG8_WAIT_V(8); PG8_WAIT_L(0); PG8_BAR; PG8_MMA(0, 0, At, B0); PG8_MMA(0, 1, At, B1); PG8_BAR; PG8_SCHED;
;             PG8_LDA(At, 0, 1); PG8_STAGE(PG8_SB(0, 0), b2, voffB); PG8_STAGE(PG8_SB(0, 1), b2 + hstep, voffB); PG8_STAGE(PG8_SA(0, 0), a2, voffA);
.LBB0_1373:
	ds_read_b128 v[128:131], v189
	ds_read_b128 v[132:135], v189 offset:1024
	ds_read_b128 v[136:139], v189 offset:2048
	ds_read_b128 v[140:143], v189 offset:3072
	ds_read_b128 v[144:147], v190
	ds_read_b128 v[148:151], v190 offset:1024
	ds_read_b128 v[168:171], v190 offset:2048
	ds_read_b128 v[172:175], v190 offset:3072
	s_add_u32 s44, s36, 0x100
	s_addc_u32 s45, s37, 0
	s_cmp_eq_u32 s62, 40
	s_cselect_b32 s49, s13, s45
	s_cselect_b32 s48, s12, s44
	s_cselect_b32 s47, s35, s61
	s_cselect_b32 s46, s34, s43
	v_lshl_add_u64 v[184:185], s[36:37], 0, v[160:161]
	s_add_i32 m0, s74, 0xc000
	ds_read_b128 v[176:179], v191
	ds_read_b128 v[180:183], v191 offset:1024
	ds_read_b128 v[192:195], v191 offset:2048
	ds_read_b128 v[196:199], v191 offset:3072
	ds_read_b128 v[200:203], v191 offset:4096
	ds_read_b128 v[204:207], v191 offset:5120
	ds_read_b128 v[208:211], v191 offset:6144
	ds_read_b128 v[212:215], v191 offset:7168
	global_load_lds_dwordx4 v[184:185], off
	v_lshl_add_u64 v[184:185], s[36:37], 0, v[162:163]
	s_add_i32 m0, s74, 0xe000
	s_nop 0
	global_load_lds_dwordx4 v[184:185], off
	s_waitcnt vmcnt(8)
	s_waitcnt lgkmcnt(0)
	s_barrier
	s_setprio 1
	s_waitcnt lgkmcnt(0)
	v_mfma_f32_16x16x32_bf16 v[124:127], v[128:131], v[176:179], v[124:127]
	v_mfma_f32_16x16x32_bf16 v[120:123], v[136:139], v[176:179], v[120:123]
	v_mfma_f32_16x16x32_bf16 v[108:111], v[128:131], v[192:195], v[108:111]
	v_mfma_f32_16x16x32_bf16 v[104:107], v[136:139], v[192:195], v[104:107]
	v_mfma_f32_16x16x32_bf16 v[92:95], v[128:131], v[200:203], v[92:95]
	v_mfma_f32_16x16x32_bf16 v[88:91], v[136:139], v[200:203], v[88:91]
	v_mfma_f32_16x16x32_bf16 v[76:79], v[128:131], v[208:211], v[76:79]
	v_mfma_f32_16x16x32_bf16 v[72:75], v[136:139], v[208:211], v[72:75]
	v_mfma_f32_16x16x32_bf16 v[124:127], v[132:135], v[180:183], v[124:127]
	v_mfma_f32_16x16x32_bf16 v[120:123], v[140:143], v[180:183], v[120:123]
	v_mfma_f32_16x16x32_bf16 v[108:111], v[132:135], v[196:199], v[108:111]
	v_mfma_f32_16x16x32_bf16 v[104:107], v[140:143], v[196:199], v[104:107]
	v_mfma_f32_16x16x32_bf16 v[92:95], v[132:135], v[204:207], v[92:95]
	v_mfma_f32_16x16x32_bf16 v[88:91], v[140:143], v[204:207], v[88:91]
	v_mfma_f32_16x16x32_bf16 v[76:79], v[132:135], v[212:215], v[76:79]
	v_mfma_f32_16x16x32_bf16 v[72:75], v[140:143], v[212:215], v[72:75]
	s_setprio 0
	s_setprio 1
	v_mfma_f32_16x16x32_bf16 v[116:119], v[144:147], v[176:179], v[116:119]
	v_mfma_f32_16x16x32_bf16 v[112:115], v[168:171], v[176:179], v[112:115]
	v_mfma_f32_16x16x32_bf16 v[100:103], v[144:147], v[192:195], v[100:103]
	v_mfma_f32_16x16x32_bf16 v[96:99], v[168:171], v[192:195], v[96:99]
	v_mfma_f32_16x16x32_bf16 v[84:87], v[144:147], v[200:203], v[84:87]
	v_mfma_f32_16x16x32_bf16 v[80:83], v[168:171], v[200:203], v[80:83]
	v_mfma_f32_16x16x32_bf16 v[68:71], v[144:147], v[208:211], v[68:71]
	v_mfma_f32_16x16x32_bf16 v[64:67], v[168:171], v[208:211], v[64:67]
	v_mfma_f32_16x16x32_bf16 v[116:119], v[148:151], v[180:183], v[116:119]
	v_mfma_f32_16x16x32_bf16 v[112:115], v[172:175], v[180:183], v[112:115]
	v_mfma_f32_16x16x32_bf16 v[100:103], v[148:151], v[196:199], v[100:103]
	v_mfma_f32_16x16x32_bf16 v[96:99], v[172:175], v[196:199], v[96:99]
	s_barrier
	v_mfma_f32_16x16x32_bf16 v[84:87], v[148:151], v[204:207], v[84:87]
	v_mfma_f32_16x16x32_bf16 v[80:83], v[172:175], v[204:207], v[80:83]
	v_mfma_f32_16x16x32_bf16 v[68:71], v[148:151], v[212:215], v[68:71]
	v_mfma_f32_16x16x32_bf16 v[64:67], v[172:175], v[212:215], v[64:67]
	s_setprio 0
	s_add_i32 s36, s56, s68
	v_lshl_add_u64 v[184:185], s[46:47], 0, v[154:155]
	s_mov_b32 m0, s36
	ds_read_b128 v[176:179], v191 offset:16384
	ds_read_b128 v[180:183], v191 offset:17408
	ds_read_b128 v[192:195], v191 offset:18432
	ds_read_b128 v[196:199], v191 offset:19456
	ds_read_b128 v[200:203], v191 offset:20480
	ds_read_b128 v[204:207], v191 offset:21504
	ds_read_b128 v[208:211], v191 offset:22528
	ds_read_b128 v[212:215], v191 offset:23552
	global_load_lds_dwordx4 v[184:185], off
	s_add_i32 m0, s36, 0x2000
	s_add_u32 s36, s46, 0xb0000
	v_lshl_add_u64 v[216:217], s[46:47], 0, v[158:159]
	s_addc_u32 s37, s47, 0
	s_add_i32 s63, s57, s68
	global_load_lds_dwordx4 v[216:217], off
	v_lshl_add_u64 v[218:219], s[36:37], 0, v[154:155]
	s_mov_b32 m0, s63
	v_lshl_add_u64 v[220:221], s[48:49], 0, v[156:157]
	global_load_lds_dwordx4 v[218:219], off
	v_lshl_add_u64 v[218:219], s[36:37], 0, v[158:159]
	s_add_i32 m0, s63, 0x2000
	s_nop 0
	global_load_lds_dwordx4 v[218:219], off
	v_lshl_add_u64 v[218:219], s[48:49], 0, v[152:153]
	s_mov_b32 m0, s74
	s_nop 0
	global_load_lds_dwordx4 v[218:219], off
	s_mov_b32 m0, s41
	s_nop 0
	global_load_lds_dwordx4 v[220:221], off
	s_waitcnt vmcnt(8)
	s_waitcnt lgkmcnt(0)
	s_barrier
; #define PG8_STAGE(bufoff, gbase, voff) do { _Pragma("unroll") for (int _i = 0; _i < 2; ++_i) \
;         __builtin_amdgcn_global_load_lds((const unsigned*)((const char*)(gbase) + (voff)[_i]), (PG8_LAS unsigned*)(lds + (bufoff) + ldsw + _i * 8192), 16, 0, 0); } while (0)
; #define PG8_LDA(dst, b, h) do { _Pragma("unroll") for (int m = 0; m < 4; ++m) _Pragma("unroll") for (int k = 0; k < 2; ++k) dst[m][k] = *(const PG8_LAS bf16x8*)(lds + PG8_SA(b, h) + aoff + m * 2048 + k * 1024); } while (0)
; #define PG8_LDB(dst, b, h) do { _Pragma("unroll") for (int n = 0; n < 2; ++n) _Pragma("unroll") for (int k = 0; k < 2; ++k) dst[n][k] = *(const PG8_LAS bf16x8*)(lds + PG8_SB(b, h) + boff + n * 2048 + k * 1024); } while (0)
; #define PG8_MMA(ai, bj, At, Bt) do { __builtin_amdgcn_s_setprio(1); _Pragma("unroll") for (int m = 0; m < 4; ++m) _Pragma("unroll") for (int n = 0; n < 2; ++n) _Pragma("unroll") for (int k = 0; k < 2; ++k) \
;         acc[ai][bj][m][n] = mma16<F16>(Bt[n][k], At[m][k], acc[ai][bj][m][n]); __builtin_amdgcn_s_setprio(0); } while (0)
; #define PG8_WAIT_V(n) asm volatile("s_waitcnt vmcnt(" #n ")" ::: "memory")
; #define PG8_WAIT_L(n) asm volatile("s_waitcnt lgkmcnt(" #n ")" ::: "memory")
; #define PG8_BAR __builtin_amdgcn_s_barrier()
; #define PG8_SCHED __builtin_amdgcn_sched_barrier(0)
; template <class Epi, class Sched, bool ALIGN_EPI = false, bool SP2 = false, bool F16 = false>
; __device__ __forceinline__ void gemm_phase(PG8_LAS unsigned char* lds, const Gemm g, const Sched& S, const Epi& E, const int wid_in) {
;     ...
;             PG8_WAIT_V(8); PG8_WAIT_L(0); PG8_BAR; PG8_MMA(1, 0, At, B0); PG8_MMA(1, 1, At, B1); PG8_BAR; PG8_SCHED;
;             PG8_LDB(B0, 1, 0); PG8_LDB(B1, 1, 1); PG8_SCHED; PG8_LDA(At, 1, 0); PG8_STAGE(PG8_SA(0, 1), a2 + hstep, voffA);
;             PG8_WAIT_V(8); PG8_WAIT_L(0); PG8_BAR; PG8_MMA(0, 0, At, B0); PG8_MMA(0, 1, At, B1); PG8_BAR; PG8_SCHED;
	s_setprio 1
	s_waitcnt lgkmcnt(0)
	v_mfma_f32_16x16x32_bf16 v[60:63], v[128:131], v[176:179], v[60:63]
	v_mfma_f32_16x16x32_bf16 v[56:59], v[136:139], v[176:179], v[56:59]
	v_mfma_f32_16x16x32_bf16 v[44:47], v[128:131], v[192:195], v[44:47]
	v_mfma_f32_16x16x32_bf16 v[40:43], v[136:139], v[192:195], v[40:43]
	v_mfma_f32_16x16x32_bf16 v[28:31], v[128:131], v[200:203], v[28:31]
	v_mfma_f32_16x16x32_bf16 v[24:27], v[136:139], v[200:203], v[24:27]
	v_mfma_f32_16x16x32_bf16 v[12:15], v[128:131], v[208:211], v[12:15]
	v_mfma_f32_16x16x32_bf16 v[8:11], v[136:139], v[208:211], v[8:11]
	v_mfma_f32_16x16x32_bf16 v[60:63], v[132:135], v[180:183], v[60:63]
	v_mfma_f32_16x16x32_bf16 v[56:59], v[140:143], v[180:183], v[56:59]
	v_mfma_f32_16x16x32_bf16 v[44:47], v[132:135], v[196:199], v[44:47]
	v_mfma_f32_16x16x32_bf16 v[40:43], v[140:143], v[196:199], v[40:43]
	v_mfma_f32_16x16x32_bf16 v[28:31], v[132:135], v[204:207], v[28:31]
	v_mfma_f32_16x16x32_bf16 v[24:27], v[140:143], v[204:207], v[24:27]
	v_mfma_f32_16x16x32_bf16 v[12:15], v[132:135], v[212:215], v[12:15]
	v_mfma_f32_16x16x32_bf16 v[8:11], v[140:143], v[212:215], v[8:11]
	s_setprio 0
	s_setprio 1
	v_mfma_f32_16x16x32_bf16 v[52:55], v[144:147], v[176:179], v[52:55]
	v_mfma_f32_16x16x32_bf16 v[48:51], v[168:171], v[176:179], v[48:51]
	v_mfma_f32_16x16x32_bf16 v[36:39], v[144:147], v[192:195], v[36:39]
	v_mfma_f32_16x16x32_bf16 v[32:35], v[168:171], v[192:195], v[32:35]
	v_mfma_f32_16x16x32_bf16 v[20:23], v[144:147], v[200:203], v[20:23]
	v_mfma_f32_16x16x32_bf16 v[16:19], v[168:171], v[200:203], v[16:19]
	v_mfma_f32_16x16x32_bf16 v[4:7], v[144:147], v[208:211], v[4:7]
	v_mfma_f32_16x16x32_bf16 v[0:3], v[168:171], v[208:211], v[0:3]
	v_mfma_f32_16x16x32_bf16 v[52:55], v[148:151], v[180:183], v[52:55]
	v_mfma_f32_16x16x32_bf16 v[48:51], v[172:175], v[180:183], v[48:51]
	v_mfma_f32_16x16x32_bf16 v[36:39], v[148:151], v[196:199], v[36:39]
	v_mfma_f32_16x16x32_bf16 v[32:35], v[172:175], v[196:199], v[32:35]
	s_barrier
	v_mfma_f32_16x16x32_bf16 v[20:23], v[148:151], v[204:207], v[20:23]
	v_mfma_f32_16x16x32_bf16 v[16:19], v[172:175], v[204:207], v[16:19]
	v_mfma_f32_16x16x32_bf16 v[4:7], v[148:151], v[212:215], v[4:7]
	v_mfma_f32_16x16x32_bf16 v[0:3], v[172:175], v[212:215], v[0:3]
	s_setprio 0
	s_add_i32 s63, 0, 0x18000
	s_add_i32 s64, 0, 0x1c000
	v_add_u32_e32 v140, s63, v188
	v_add_u32_e32 v172, s64, v188
	ds_read_b128 v[128:131], v140
	ds_read_b128 v[132:135], v140 offset:1024
	ds_read_b128 v[136:139], v140 offset:2048
	ds_read_b128 v[140:143], v140 offset:3072
	ds_read_b128 v[144:147], v172
	ds_read_b128 v[148:151], v172 offset:1024
	ds_read_b128 v[168:171], v172 offset:2048
	ds_read_b128 v[172:175], v172 offset:3072
	s_add_u32 s36, s48, 0xb0000
	s_addc_u32 s37, s49, 0
	s_mov_b32 m0, s50
	v_lshl_add_u64 v[222:223], s[36:37], 0, v[152:153]
	ds_read_b128 v[176:179], v191 offset:32768
	ds_read_b128 v[180:183], v191 offset:33792
	ds_read_b128 v[192:195], v191 offset:34816
	ds_read_b128 v[196:199], v191 offset:35840
	ds_read_b128 v[200:203], v191 offset:36864
	ds_read_b128 v[204:207], v191 offset:37888
	ds_read_b128 v[208:211], v191 offset:38912
	ds_read_b128 v[212:215], v191 offset:39936
	global_load_lds_dwordx4 v[222:223], off
	v_lshl_add_u64 v[222:223], s[36:37], 0, v[156:157]
	s_mov_b32 m0, s51
	s_nop 0
	global_load_lds_dwordx4 v[222:223], off
	s_waitcnt vmcnt(8)
	s_waitcnt lgkmcnt(0)
	s_barrier
	s_setprio 1
	s_waitcnt lgkmcnt(0)
	v_mfma_f32_16x16x32_bf16 v[124:127], v[128:131], v[176:179], v[124:127]
	v_mfma_f32_16x16x32_bf16 v[120:123], v[136:139], v[176:179], v[120:123]
	v_mfma_f32_16x16x32_bf16 v[108:111], v[128:131], v[192:195], v[108:111]
	v_mfma_f32_16x16x32_bf16 v[104:107], v[136:139], v[192:195], v[104:107]
	v_mfma_f32_16x16x32_bf16 v[92:95], v[128:131], v[200:203], v[92:95]
	v_mfma_f32_16x16x32_bf16 v[88:91], v[136:139], v[200:203], v[88:91]
	v_mfma_f32_16x16x32_bf16 v[76:79], v[128:131], v[208:211], v[76:79]
	v_mfma_f32_16x16x32_bf16 v[72:75], v[136:139], v[208:211], v[72:75]
	v_mfma_f32_16x16x32_bf16 v[124:127], v[132:135], v[180:183], v[124:127]
	v_mfma_f32_16x16x32_bf16 v[120:123], v[140:143], v[180:183], v[120:123]
	v_mfma_f32_16x16x32_bf16 v[108:111], v[132:135], v[196:199], v[108:111]
	v_mfma_f32_16x16x32_bf16 v[104:107], v[140:143], v[196:199], v[104:107]
	v_mfma_f32_16x16x32_bf16 v[92:95], v[132:135], v[204:207], v[92:95]
	v_mfma_f32_16x16x32_bf16 v[88:91], v[140:143], v[204:207], v[88:91]
	v_mfma_f32_16x16x32_bf16 v[76:79], v[132:135], v[212:215], v[76:79]
	v_mfma_f32_16x16x32_bf16 v[72:75], v[140:143], v[212:215], v[72:75]
	s_setprio 0
	s_setprio 1
	v_mfma_f32_16x16x32_bf16 v[116:119], v[144:147], v[176:179], v[116:119]
	v_mfma_f32_16x16x32_bf16 v[112:115], v[168:171], v[176:179], v[112:115]
	v_mfma_f32_16x16x32_bf16 v[100:103], v[144:147], v[192:195], v[100:103]
	v_mfma_f32_16x16x32_bf16 v[96:99], v[168:171], v[192:195], v[96:99]
	v_mfma_f32_16x16x32_bf16 v[84:87], v[144:147], v[200:203], v[84:87]
	v_mfma_f32_16x16x32_bf16 v[80:83], v[168:171], v[200:203], v[80:83]
	v_mfma_f32_16x16x32_bf16 v[68:71], v[144:147], v[208:211], v[68:71]
	v_mfma_f32_16x16x32_bf16 v[64:67], v[168:171], v[208:211], v[64:67]
	v_mfma_f32_16x16x32_bf16 v[116:119], v[148:151], v[180:183], v[116:119]
	v_mfma_f32_16x16x32_bf16 v[112:115], v[172:175], v[180:183], v[112:115]
	v_mfma_f32_16x16x32_bf16 v[100:103], v[148:151], v[196:199], v[100:103]
	v_mfma_f32_16x16x32_bf16 v[96:99], v[172:175], v[196:199], v[96:99]
	s_barrier
; #define PG8_STAGE(bufoff, gbase, voff) do { _Pragma("unroll") for (int _i = 0; _i < 2; ++_i) \
;         __builtin_amdgcn_global_load_lds((const unsigned*)((const char*)(gbase) + (voff)[_i]), (PG8_LAS unsigned*)(lds + (bufoff) + ldsw + _i * 8192), 16, 0, 0); } while (0)
; #define PG8_LDA(dst, b, h) do { _Pragma("unroll") for (int m = 0; m < 4; ++m) _Pragma("unroll") for (int k = 0; k < 2; ++k) dst[m][k] = *(const PG8_LAS bf16x8*)(lds + PG8_SA(b, h) + aoff + m * 2048 + k * 1024); } while (0)
; #define PG8_MMA(ai, bj, At, Bt) do { __builtin_amdgcn_s_setprio(1); _Pragma("unroll") for (int m = 0; m < 4; ++m) _Pragma("unroll") for (int n = 0; n < 2; ++n) _Pragma("unroll") for (int k = 0; k < 2; ++k) \
;         acc[ai][bj][m][n] = mma16<F16>(Bt[n][k], At[m][k], acc[ai][bj][m][n]); __builtin_amdgcn_s_setprio(0); } while (0)
; #define PG8_WAIT_V(n) asm volatile("s_waitcnt vmcnt(" #n ")" ::: "memory")
; #define PG8_WAIT_L(n) asm volatile("s_waitcnt lgkmcnt(" #n ")" ::: "memory")
; #define PG8_BAR __builtin_amdgcn_s_barrier()
; #define PG8_SCHED __builtin_amdgcn_sched_barrier(0)
; template <class Epi, class Sched, bool ALIGN_EPI = false, bool SP2 = false, bool F16 = false>
; __device__ __forceinline__ void gemm_phase(PG8_LAS unsigned char* lds, const Gemm g, const Sched& S, const Epi& E, const int wid_in) {
;     ...
;             PG8_WAIT_V(8); PG8_WAIT_L(0); PG8_BAR; PG8_MMA(0, 0, At, B0); PG8_MMA(0, 1, At, B1); PG8_BAR; PG8_SCHED;
;             PG8_LDA(At, 1, 1); PG8_STAGE(PG8_SB(1, 0), b3, voffB); PG8_STAGE(PG8_SB(1, 1), b3 + hstep, voffB); PG8_STAGE(PG8_SA(1, 0), a3, voffA);
;             PG8_WAIT_V(8); PG8_WAIT_L(0); PG8_BAR; PG8_MMA(1, 0, At, B0); PG8_MMA(1, 1, At, B1); PG8_BAR; PG8_SCHED;
	v_mfma_f32_16x16x32_bf16 v[84:87], v[148:151], v[204:207], v[84:87]
	v_mfma_f32_16x16x32_bf16 v[80:83], v[172:175], v[204:207], v[80:83]
	v_mfma_f32_16x16x32_bf16 v[68:71], v[148:151], v[212:215], v[68:71]
	v_mfma_f32_16x16x32_bf16 v[64:67], v[172:175], v[212:215], v[64:67]
	s_setprio 0
	s_add_i32 s36, s63, s68
	v_lshl_add_u64 v[184:185], v[184:185], 0, s[30:31]
	s_mov_b32 m0, s36
	ds_read_b128 v[176:179], v191 offset:49152
	ds_read_b128 v[180:183], v191 offset:50176
	ds_read_b128 v[192:195], v191 offset:51200
	ds_read_b128 v[196:199], v191 offset:52224
	ds_read_b128 v[200:203], v191 offset:53248
	ds_read_b128 v[204:207], v191 offset:54272
	ds_read_b128 v[208:211], v191 offset:55296
	ds_read_b128 v[212:215], v191 offset:56320
	global_load_lds_dwordx4 v[184:185], off
	s_add_i32 m0, s36, 0x2000
	s_add_u32 s36, s46, 0xb0080
	v_lshl_add_u64 v[184:185], v[216:217], 0, s[30:31]
	s_addc_u32 s37, s47, 0
	s_add_i32 s46, s64, s68
	global_load_lds_dwordx4 v[184:185], off
	v_lshl_add_u64 v[184:185], s[36:37], 0, v[154:155]
	s_mov_b32 m0, s46
	s_nop 0
	global_load_lds_dwordx4 v[184:185], off
	v_lshl_add_u64 v[184:185], s[36:37], 0, v[158:159]
	s_add_i32 m0, s46, 0x2000
	s_nop 0
	global_load_lds_dwordx4 v[184:185], off
	v_lshl_add_u64 v[184:185], v[218:219], 0, s[30:31]
	s_mov_b32 m0, s75
	s_nop 0
	global_load_lds_dwordx4 v[184:185], off
	v_lshl_add_u64 v[184:185], v[220:221], 0, s[30:31]
	s_mov_b32 m0, s52
	s_nop 0
	global_load_lds_dwordx4 v[184:185], off
	s_waitcnt vmcnt(8)
	s_waitcnt lgkmcnt(0)
	s_barrier
	s_setprio 1
	s_waitcnt lgkmcnt(0)
	v_mfma_f32_16x16x32_bf16 v[60:63], v[128:131], v[176:179], v[60:63]
	v_mfma_f32_16x16x32_bf16 v[56:59], v[136:139], v[176:179], v[56:59]
	v_mfma_f32_16x16x32_bf16 v[44:47], v[128:131], v[192:195], v[44:47]
	v_mfma_f32_16x16x32_bf16 v[40:43], v[136:139], v[192:195], v[40:43]
	v_mfma_f32_16x16x32_bf16 v[28:31], v[128:131], v[200:203], v[28:31]
	v_mfma_f32_16x16x32_bf16 v[24:27], v[136:139], v[200:203], v[24:27]
	v_mfma_f32_16x16x32_bf16 v[12:15], v[128:131], v[208:211], v[12:15]
	v_mfma_f32_16x16x32_bf16 v[8:11], v[136:139], v[208:211], v[8:11]
	v_mfma_f32_16x16x32_bf16 v[60:63], v[132:135], v[180:183], v[60:63]
	v_mfma_f32_16x16x32_bf16 v[56:59], v[140:143], v[180:183], v[56:59]
	v_mfma_f32_16x16x32_bf16 v[44:47], v[132:135], v[196:199], v[44:47]
	v_mfma_f32_16x16x32_bf16 v[40:43], v[140:143], v[196:199], v[40:43]
	v_mfma_f32_16x16x32_bf16 v[28:31], v[132:135], v[204:207], v[28:31]
	v_mfma_f32_16x16x32_bf16 v[24:27], v[140:143], v[204:207], v[24:27]
	v_mfma_f32_16x16x32_bf16 v[12:15], v[132:135], v[212:215], v[12:15]
	v_mfma_f32_16x16x32_bf16 v[8:11], v[140:143], v[212:215], v[8:11]
	s_setprio 0
	s_setprio 1
	v_mfma_f32_16x16x32_bf16 v[52:55], v[144:147], v[176:179], v[52:55]
	v_mfma_f32_16x16x32_bf16 v[48:51], v[168:171], v[176:179], v[48:51]
	v_mfma_f32_16x16x32_bf16 v[36:39], v[144:147], v[192:195], v[36:39]
	v_mfma_f32_16x16x32_bf16 v[32:35], v[168:171], v[192:195], v[32:35]
	v_mfma_f32_16x16x32_bf16 v[20:23], v[144:147], v[200:203], v[20:23]
	v_mfma_f32_16x16x32_bf16 v[16:19], v[168:171], v[200:203], v[16:19]
	v_mfma_f32_16x16x32_bf16 v[4:7], v[144:147], v[208:211], v[4:7]
	v_mfma_f32_16x16x32_bf16 v[0:3], v[168:171], v[208:211], v[0:3]
	v_mfma_f32_16x16x32_bf16 v[52:55], v[148:151], v[180:183], v[52:55]
	v_mfma_f32_16x16x32_bf16 v[48:51], v[172:175], v[180:183], v[48:51]
	v_mfma_f32_16x16x32_bf16 v[36:39], v[148:151], v[196:199], v[36:39]
	v_mfma_f32_16x16x32_bf16 v[32:35], v[172:175], v[196:199], v[32:35]
	s_barrier
	v_mfma_f32_16x16x32_bf16 v[20:23], v[148:151], v[204:207], v[20:23]
	v_mfma_f32_16x16x32_bf16 v[16:19], v[172:175], v[204:207], v[16:19]
	v_mfma_f32_16x16x32_bf16 v[4:7], v[148:151], v[212:215], v[4:7]
	v_mfma_f32_16x16x32_bf16 v[0:3], v[172:175], v[212:215], v[0:3]
	s_setprio 0
	s_add_i32 s62, s62, 2
	s_add_u32 s43, s43, 0x100
	s_addc_u32 s61, s61, 0
	s_cmp_gt_u32 s62, 41
	s_mov_b64 s[36:37], s[44:45]
	s_cbranch_scc0 .LBB0_1373
	s_and_b64 vcc, exec, s[16:17]
	s_cbranch_vccz .LBB0_1376
	s_barrier

; #define PG8_STAGE(bufoff, gbase, voff) do { _Pragma("unroll") for (int _i = 0; _i < 2; ++_i) \
;         __builtin_amdgcn_global_load_lds((const unsigned*)((const char*)(gbase) + (voff)[_i]), (PG8_LAS unsigned*)(lds + (bufoff) + ldsw + _i * 8192), 16, 0, 0); } while (0)
; #define PG8_LDA(dst, b, h) do { _Pragma("unroll") for (int m = 0; m < 4; ++m) _Pragma("unroll") for (int k = 0; k < 2; ++k) dst[m][k] = *(const PG8_LAS bf16x8*)(lds + PG8_SA(b, h) + aoff + m * 2048 + k * 1024); } while (0)
; #define PG8_LDB(dst, b, h) do { _Pragma("unroll") for (int n = 0; n < 2; ++n) _Pragma("unroll") for (int k = 0; k < 2; ++k) dst[n][k] = *(const PG8_LAS bf16x8*)(lds + PG8_SB(b, h) + boff + n * 2048 + k * 1024); } while (0)
; #define PG8_MMA(ai, bj, At, Bt) do { __builtin_amdgcn_s_setprio(1); _Pragma("unroll") for (int m = 0; m < 4; ++m) _Pragma("unroll") for (int n = 0; n < 2; ++n) _Pragma("unroll") for (int k = 0; k < 2; ++k) \
;         acc[ai][bj][m][n] = mma16<F16>(Bt[n][k], At[m][k], acc[ai][bj][m][n]); __builtin_amdgcn_s_setprio(0); } while (0)
; #define PG8_WAIT_V(n) asm volatile("s_waitcnt vmcnt(" #n ")" ::: "memory")
; #define PG8_WAIT_L(n) asm volatile("s_waitcnt lgkmcnt(" #n ")" ::: "memory")
; #define PG8_BAR __builtin_amdgcn_s_barrier()
; #define PG8_SCHED __builtin_amdgcn_sched_barrier(0)
; template <class Epi, class Sched, bool ALIGN_EPI = false, bool SP2 = false, bool F16 = false>
; __device__ __forceinline__ void gemm_phase(PG8_LAS unsigned char* lds, const Gemm g, const Sched& S, const Epi& E, const int wid_in) {
;     ...
;         for (int t = 0; t < nt; t += 2) {
;             const bool last = (t == nt - 2);
;             const char* a1 = cA + (size_t)(t + 1) * kstep;
;             const char* a2 = last ? nA : cA + (size_t)(t + 2) * kstep; const char* b2 = last ? nB : cB + (size_t)(t + 2) * kstep;
;             const char* a3 = a2 + kstep; const char* b3 = b2 + kstep;
;             if (last && has_next) S.a_ready(nxt);
;             if constexpr (SP2) {
;             PG8_LDB(B0, 0, 0); PG8_LDB(B1, 0, 1); PG8_SCHED; PG8_LDA(At, 0, 0); PG8_STAGE(PG8_SA(1, 1), a1 + hstep, voffA);
;             PG8_WAIT_V(8); PG8_WAIT_L(0); PG8_BAR; PG8_MMA(0, 0, At, B0); PG8_MMA(0, 1, At, B1); PG8_BAR; PG8_SCHED;
;             PG8_LDA(At, 0, 1); PG8_STAGE(PG8_SB(0, 0), b2, voffB); PG8_STAGE(PG8_SB(0, 1), b2 + hstep, voffB); PG8_STAGE(PG8_SA(0, 0), a2, voffA);
.LBB0_1469:
	ds_read_b128 v[112:115], v235
	ds_read_b128 v[116:119], v235 offset:1024
	ds_read_b128 v[128:131], v235 offset:2048
	ds_read_b128 v[132:135], v235 offset:3072
	ds_read_b128 v[144:147], v236
	ds_read_b128 v[148:151], v236 offset:1024
	ds_read_b128 v[152:155], v236 offset:2048
	ds_read_b128 v[156:159], v236 offset:3072
	s_add_u32 s45, s52, 0xfffc0080
	s_addc_u32 s51, s53, -1
	s_cmp_eq_u32 s43, 12
	s_cselect_b32 s57, s14, s51
	s_cselect_b32 s56, s15, s45
	s_cselect_b32 s55, s37, s42
	s_cselect_b32 s54, s40, s41
	v_lshl_add_u64 v[192:193], s[52:53], 0, v[204:205]
	s_add_i32 m0, s74, 0xc000
	ds_read_b128 v[160:163], v237
	ds_read_b128 v[164:167], v237 offset:1024
	ds_read_b128 v[168:171], v237 offset:2048
	ds_read_b128 v[172:175], v237 offset:3072
	ds_read_b128 v[176:179], v237 offset:4096
	ds_read_b128 v[180:183], v237 offset:5120
	ds_read_b128 v[184:187], v237 offset:6144
	ds_read_b128 v[188:191], v237 offset:7168
	global_load_lds_dwordx4 v[192:193], off
	v_lshl_add_u64 v[192:193], s[52:53], 0, v[206:207]
	s_add_i32 m0, s74, 0xe000
	s_nop 0
	global_load_lds_dwordx4 v[192:193], off
	s_waitcnt vmcnt(8)
	s_waitcnt lgkmcnt(0)
	s_barrier
	s_setprio 1
	s_waitcnt lgkmcnt(0)
	v_mfma_f32_16x16x32_f16 v[140:143], v[112:115], v[160:163], v[140:143]
	v_mfma_f32_16x16x32_f16 v[136:139], v[128:131], v[160:163], v[136:139]
	v_mfma_f32_16x16x32_f16 v[108:111], v[112:115], v[168:171], v[108:111]
	v_mfma_f32_16x16x32_f16 v[104:107], v[128:131], v[168:171], v[104:107]
	v_mfma_f32_16x16x32_f16 v[92:95], v[112:115], v[176:179], v[92:95]
	v_mfma_f32_16x16x32_f16 v[88:91], v[128:131], v[176:179], v[88:91]
	v_mfma_f32_16x16x32_f16 v[76:79], v[112:115], v[184:187], v[76:79]
	v_mfma_f32_16x16x32_f16 v[72:75], v[128:131], v[184:187], v[72:75]
	v_mfma_f32_16x16x32_f16 v[140:143], v[116:119], v[164:167], v[140:143]
	v_mfma_f32_16x16x32_f16 v[136:139], v[132:135], v[164:167], v[136:139]
	v_mfma_f32_16x16x32_f16 v[108:111], v[116:119], v[172:175], v[108:111]
	v_mfma_f32_16x16x32_f16 v[104:107], v[132:135], v[172:175], v[104:107]
	v_mfma_f32_16x16x32_f16 v[92:95], v[116:119], v[180:183], v[92:95]
	v_mfma_f32_16x16x32_f16 v[88:91], v[132:135], v[180:183], v[88:91]
	v_mfma_f32_16x16x32_f16 v[76:79], v[116:119], v[188:191], v[76:79]
	v_mfma_f32_16x16x32_f16 v[72:75], v[132:135], v[188:191], v[72:75]
	s_setprio 0
	s_setprio 1
	v_mfma_f32_16x16x32_f16 v[124:127], v[144:147], v[160:163], v[124:127]
	v_mfma_f32_16x16x32_f16 v[120:123], v[152:155], v[160:163], v[120:123]
	v_mfma_f32_16x16x32_f16 v[100:103], v[144:147], v[168:171], v[100:103]
	v_mfma_f32_16x16x32_f16 v[96:99], v[152:155], v[168:171], v[96:99]
	v_mfma_f32_16x16x32_f16 v[84:87], v[144:147], v[176:179], v[84:87]
	v_mfma_f32_16x16x32_f16 v[80:83], v[152:155], v[176:179], v[80:83]
	v_mfma_f32_16x16x32_f16 v[68:71], v[144:147], v[184:187], v[68:71]
	v_mfma_f32_16x16x32_f16 v[64:67], v[152:155], v[184:187], v[64:67]
	v_mfma_f32_16x16x32_f16 v[124:127], v[148:151], v[164:167], v[124:127]
	v_mfma_f32_16x16x32_f16 v[120:123], v[156:159], v[164:167], v[120:123]
	v_mfma_f32_16x16x32_f16 v[100:103], v[148:151], v[172:175], v[100:103]
	v_mfma_f32_16x16x32_f16 v[96:99], v[156:159], v[172:175], v[96:99]
	s_barrier
	v_mfma_f32_16x16x32_f16 v[84:87], v[148:151], v[180:183], v[84:87]
	v_mfma_f32_16x16x32_f16 v[80:83], v[156:159], v[180:183], v[80:83]
	v_mfma_f32_16x16x32_f16 v[68:71], v[148:151], v[188:191], v[68:71]
	v_mfma_f32_16x16x32_f16 v[64:67], v[156:159], v[188:191], v[64:67]
	s_setprio 0
	s_add_i32 s45, s66, s68
	v_lshl_add_u64 v[192:193], s[54:55], 0, v[198:199]
	s_mov_b32 m0, s45
	ds_read_b128 v[160:163], v237 offset:16384
	ds_read_b128 v[164:167], v237 offset:17408
	ds_read_b128 v[168:171], v237 offset:18432
	ds_read_b128 v[172:175], v237 offset:19456
	ds_read_b128 v[176:179], v237 offset:20480
	ds_read_b128 v[180:183], v237 offset:21504
	ds_read_b128 v[184:187], v237 offset:22528
	ds_read_b128 v[188:191], v237 offset:23552
	global_load_lds_dwordx4 v[192:193], off
	s_add_i32 m0, s45, 0x2000
	s_add_u32 s94, s54, 0x40000
	v_lshl_add_u64 v[194:195], s[54:55], 0, v[202:203]
	s_addc_u32 s95, s55, 0
	s_add_i32 s45, s67, s68
	global_load_lds_dwordx4 v[194:195], off
	v_lshl_add_u64 v[212:213], s[94:95], 0, v[198:199]
	s_mov_b32 m0, s45
	v_lshl_add_u64 v[214:215], s[56:57], 0, v[200:201]
	global_load_lds_dwordx4 v[212:213], off
	v_lshl_add_u64 v[212:213], s[94:95], 0, v[202:203]
	s_add_i32 m0, s45, 0x2000
	s_nop 0
	global_load_lds_dwordx4 v[212:213], off
	v_lshl_add_u64 v[212:213], s[56:57], 0, v[196:197]
	s_mov_b32 m0, s74
	s_nop 0
	global_load_lds_dwordx4 v[212:213], off
	s_mov_b32 m0, s59
	s_nop 0
	global_load_lds_dwordx4 v[214:215], off
	s_waitcnt vmcnt(8)
	s_waitcnt lgkmcnt(0)
	s_barrier
; #define PG8_STAGE(bufoff, gbase, voff) do { _Pragma("unroll") for (int _i = 0; _i < 2; ++_i) \
;         __builtin_amdgcn_global_load_lds((const unsigned*)((const char*)(gbase) + (voff)[_i]), (PG8_LAS unsigned*)(lds + (bufoff) + ldsw + _i * 8192), 16, 0, 0); } while (0)
; #define PG8_LDA(dst, b, h) do { _Pragma("unroll") for (int m = 0; m < 4; ++m) _Pragma("unroll") for (int k = 0; k < 2; ++k) dst[m][k] = *(const PG8_LAS bf16x8*)(lds + PG8_SA(b, h) + aoff + m * 2048 + k * 1024); } while (0)
; #define PG8_LDB(dst, b, h) do { _Pragma("unroll") for (int n = 0; n < 2; ++n) _Pragma("unroll") for (int k = 0; k < 2; ++k) dst[n][k] = *(const PG8_LAS bf16x8*)(lds + PG8_SB(b, h) + boff + n * 2048 + k * 1024); } while (0)
; #define PG8_MMA(ai, bj, At, Bt) do { __builtin_amdgcn_s_setprio(1); _Pragma("unroll") for (int m = 0; m < 4; ++m) _Pragma("unroll") for (int n = 0; n < 2; ++n) _Pragma("unroll") for (int k = 0; k < 2; ++k) \
;         acc[ai][bj][m][n] = mma16<F16>(Bt[n][k], At[m][k], acc[ai][bj][m][n]); __builtin_amdgcn_s_setprio(0); } while (0)
; #define PG8_WAIT_V(n) asm volatile("s_waitcnt vmcnt(" #n ")" ::: "memory")
; #define PG8_WAIT_L(n) asm volatile("s_waitcnt lgkmcnt(" #n ")" ::: "memory")
; #define PG8_BAR __builtin_amdgcn_s_barrier()
; #define PG8_SCHED __builtin_amdgcn_sched_barrier(0)
; template <class Epi, class Sched, bool ALIGN_EPI = false, bool SP2 = false, bool F16 = false>
; __device__ __forceinline__ void gemm_phase(PG8_LAS unsigned char* lds, const Gemm g, const Sched& S, const Epi& E, const int wid_in) {
;     ...
;             PG8_WAIT_V(8); PG8_WAIT_L(0); PG8_BAR; PG8_MMA(1, 0, At, B0); PG8_MMA(1, 1, At, B1); PG8_BAR; PG8_SCHED;
;             PG8_LDB(B0, 1, 0); PG8_LDB(B1, 1, 1); PG8_SCHED; PG8_LDA(At, 1, 0); PG8_STAGE(PG8_SA(0, 1), a2 + hstep, voffA);
;             PG8_WAIT_V(8); PG8_WAIT_L(0); PG8_BAR; PG8_MMA(0, 0, At, B0); PG8_MMA(0, 1, At, B1); PG8_BAR; PG8_SCHED;
	s_setprio 1
	s_waitcnt lgkmcnt(0)
	v_mfma_f32_16x16x32_f16 v[60:63], v[112:115], v[160:163], v[60:63]
	v_mfma_f32_16x16x32_f16 v[56:59], v[128:131], v[160:163], v[56:59]
	v_mfma_f32_16x16x32_f16 v[44:47], v[112:115], v[168:171], v[44:47]
	v_mfma_f32_16x16x32_f16 v[40:43], v[128:131], v[168:171], v[40:43]
	v_mfma_f32_16x16x32_f16 v[28:31], v[112:115], v[176:179], v[28:31]
	v_mfma_f32_16x16x32_f16 v[24:27], v[128:131], v[176:179], v[24:27]
	v_mfma_f32_16x16x32_f16 v[12:15], v[112:115], v[184:187], v[12:15]
	v_mfma_f32_16x16x32_f16 v[8:11], v[128:131], v[184:187], v[8:11]
	v_mfma_f32_16x16x32_f16 v[60:63], v[116:119], v[164:167], v[60:63]
	v_mfma_f32_16x16x32_f16 v[56:59], v[132:135], v[164:167], v[56:59]
	v_mfma_f32_16x16x32_f16 v[44:47], v[116:119], v[172:175], v[44:47]
	v_mfma_f32_16x16x32_f16 v[40:43], v[132:135], v[172:175], v[40:43]
	v_mfma_f32_16x16x32_f16 v[28:31], v[116:119], v[180:183], v[28:31]
	v_mfma_f32_16x16x32_f16 v[24:27], v[132:135], v[180:183], v[24:27]
	v_mfma_f32_16x16x32_f16 v[12:15], v[116:119], v[188:191], v[12:15]
	v_mfma_f32_16x16x32_f16 v[8:11], v[132:135], v[188:191], v[8:11]
	s_setprio 0
	s_setprio 1
	v_mfma_f32_16x16x32_f16 v[52:55], v[144:147], v[160:163], v[52:55]
	v_mfma_f32_16x16x32_f16 v[48:51], v[152:155], v[160:163], v[48:51]
	v_mfma_f32_16x16x32_f16 v[36:39], v[144:147], v[168:171], v[36:39]
	v_mfma_f32_16x16x32_f16 v[32:35], v[152:155], v[168:171], v[32:35]
	v_mfma_f32_16x16x32_f16 v[20:23], v[144:147], v[176:179], v[20:23]
	v_mfma_f32_16x16x32_f16 v[16:19], v[152:155], v[176:179], v[16:19]
	v_mfma_f32_16x16x32_f16 v[4:7], v[144:147], v[184:187], v[4:7]
	v_mfma_f32_16x16x32_f16 v[0:3], v[152:155], v[184:187], v[0:3]
	v_mfma_f32_16x16x32_f16 v[52:55], v[148:151], v[164:167], v[52:55]
	v_mfma_f32_16x16x32_f16 v[48:51], v[156:159], v[164:167], v[48:51]
	v_mfma_f32_16x16x32_f16 v[36:39], v[148:151], v[172:175], v[36:39]
	v_mfma_f32_16x16x32_f16 v[32:35], v[156:159], v[172:175], v[32:35]
	s_barrier
	v_mfma_f32_16x16x32_f16 v[20:23], v[148:151], v[180:183], v[20:23]
	v_mfma_f32_16x16x32_f16 v[16:19], v[156:159], v[180:183], v[16:19]
	v_mfma_f32_16x16x32_f16 v[4:7], v[148:151], v[188:191], v[4:7]
	v_mfma_f32_16x16x32_f16 v[0:3], v[156:159], v[188:191], v[0:3]
	s_setprio 0
	s_add_i32 s45, 0, 0x18000
	s_add_i32 s51, 0, 0x1c000
	v_add_u32_e32 v132, s45, v234
	v_add_u32_e32 v156, s51, v234
	ds_read_b128 v[112:115], v132
	ds_read_b128 v[116:119], v132 offset:1024
	ds_read_b128 v[128:131], v132 offset:2048
	ds_read_b128 v[132:135], v132 offset:3072
	ds_read_b128 v[144:147], v156
	ds_read_b128 v[148:151], v156 offset:1024
	ds_read_b128 v[152:155], v156 offset:2048
	ds_read_b128 v[156:159], v156 offset:3072
	s_add_u32 s56, s56, 0x40000
	s_addc_u32 s57, s57, 0
	s_mov_b32 m0, s60
	v_lshl_add_u64 v[216:217], s[56:57], 0, v[196:197]
	ds_read_b128 v[160:163], v237 offset:32768
	ds_read_b128 v[164:167], v237 offset:33792
	ds_read_b128 v[168:171], v237 offset:34816
	ds_read_b128 v[172:175], v237 offset:35840
	ds_read_b128 v[176:179], v237 offset:36864
	ds_read_b128 v[180:183], v237 offset:37888
	ds_read_b128 v[184:187], v237 offset:38912
	ds_read_b128 v[188:191], v237 offset:39936
	global_load_lds_dwordx4 v[216:217], off
	v_lshl_add_u64 v[216:217], s[56:57], 0, v[200:201]
	s_mov_b32 m0, s61
	s_nop 0
	global_load_lds_dwordx4 v[216:217], off
	s_waitcnt vmcnt(8)
	s_waitcnt lgkmcnt(0)
	s_barrier
	s_setprio 1
	s_waitcnt lgkmcnt(0)
	v_mfma_f32_16x16x32_f16 v[140:143], v[112:115], v[160:163], v[140:143]
	v_mfma_f32_16x16x32_f16 v[136:139], v[128:131], v[160:163], v[136:139]
	v_mfma_f32_16x16x32_f16 v[108:111], v[112:115], v[168:171], v[108:111]
	v_mfma_f32_16x16x32_f16 v[104:107], v[128:131], v[168:171], v[104:107]
	v_mfma_f32_16x16x32_f16 v[92:95], v[112:115], v[176:179], v[92:95]
	v_mfma_f32_16x16x32_f16 v[88:91], v[128:131], v[176:179], v[88:91]
	v_mfma_f32_16x16x32_f16 v[76:79], v[112:115], v[184:187], v[76:79]
	v_mfma_f32_16x16x32_f16 v[72:75], v[128:131], v[184:187], v[72:75]
	v_mfma_f32_16x16x32_f16 v[140:143], v[116:119], v[164:167], v[140:143]
	v_mfma_f32_16x16x32_f16 v[136:139], v[132:135], v[164:167], v[136:139]
	v_mfma_f32_16x16x32_f16 v[108:111], v[116:119], v[172:175], v[108:111]
	v_mfma_f32_16x16x32_f16 v[104:107], v[132:135], v[172:175], v[104:107]
	v_mfma_f32_16x16x32_f16 v[92:95], v[116:119], v[180:183], v[92:95]
	v_mfma_f32_16x16x32_f16 v[88:91], v[132:135], v[180:183], v[88:91]
	v_mfma_f32_16x16x32_f16 v[76:79], v[116:119], v[188:191], v[76:79]
	v_mfma_f32_16x16x32_f16 v[72:75], v[132:135], v[188:191], v[72:75]
	s_setprio 0
	s_setprio 1
	v_mfma_f32_16x16x32_f16 v[124:127], v[144:147], v[160:163], v[124:127]
	v_mfma_f32_16x16x32_f16 v[120:123], v[152:155], v[160:163], v[120:123]
	v_mfma_f32_16x16x32_f16 v[100:103], v[144:147], v[168:171], v[100:103]
	v_mfma_f32_16x16x32_f16 v[96:99], v[152:155], v[168:171], v[96:99]
	v_mfma_f32_16x16x32_f16 v[84:87], v[144:147], v[176:179], v[84:87]
	v_mfma_f32_16x16x32_f16 v[80:83], v[152:155], v[176:179], v[80:83]
	v_mfma_f32_16x16x32_f16 v[68:71], v[144:147], v[184:187], v[68:71]
	v_mfma_f32_16x16x32_f16 v[64:67], v[152:155], v[184:187], v[64:67]
	v_mfma_f32_16x16x32_f16 v[124:127], v[148:151], v[164:167], v[124:127]
	v_mfma_f32_16x16x32_f16 v[120:123], v[156:159], v[164:167], v[120:123]
	v_mfma_f32_16x16x32_f16 v[100:103], v[148:151], v[172:175], v[100:103]
	v_mfma_f32_16x16x32_f16 v[96:99], v[156:159], v[172:175], v[96:99]
	s_barrier
; #define PG8_STAGE(bufoff, gbase, voff) do { _Pragma("unroll") for (int _i = 0; _i < 2; ++_i) \
;         __builtin_amdgcn_global_load_lds((const unsigned*)((const char*)(gbase) + (voff)[_i]), (PG8_LAS unsigned*)(lds + (bufoff) + ldsw + _i * 8192), 16, 0, 0); } while (0)
; #define PG8_LDA(dst, b, h) do { _Pragma("unroll") for (int m = 0; m < 4; ++m) _Pragma("unroll") for (int k = 0; k < 2; ++k) dst[m][k] = *(const PG8_LAS bf16x8*)(lds + PG8_SA(b, h) + aoff + m * 2048 + k * 1024); } while (0)
; #define PG8_MMA(ai, bj, At, Bt) do { __builtin_amdgcn_s_setprio(1); _Pragma("unroll") for (int m = 0; m < 4; ++m) _Pragma("unroll") for (int n = 0; n < 2; ++n) _Pragma("unroll") for (int k = 0; k < 2; ++k) \
;         acc[ai][bj][m][n] = mma16<F16>(Bt[n][k], At[m][k], acc[ai][bj][m][n]); __builtin_amdgcn_s_setprio(0); } while (0)
; #define PG8_WAIT_V(n) asm volatile("s_waitcnt vmcnt(" #n ")" ::: "memory")
; #define PG8_WAIT_L(n) asm volatile("s_waitcnt lgkmcnt(" #n ")" ::: "memory")
; #define PG8_BAR __builtin_amdgcn_s_barrier()
; #define PG8_SCHED __builtin_amdgcn_sched_barrier(0)
; template <class Epi, class Sched, bool ALIGN_EPI = false, bool SP2 = false, bool F16 = false>
; __device__ __forceinline__ void gemm_phase(PG8_LAS unsigned char* lds, const Gemm g, const Sched& S, const Epi& E, const int wid_in) {
;     ...
;             PG8_WAIT_V(8); PG8_WAIT_L(0); PG8_BAR; PG8_MMA(0, 0, At, B0); PG8_MMA(0, 1, At, B1); PG8_BAR; PG8_SCHED;
;             PG8_LDA(At, 1, 1); PG8_STAGE(PG8_SB(1, 0), b3, voffB); PG8_STAGE(PG8_SB(1, 1), b3 + hstep, voffB); PG8_STAGE(PG8_SA(1, 0), a3, voffA);
;             PG8_WAIT_V(8); PG8_WAIT_L(0); PG8_BAR; PG8_MMA(1, 0, At, B0); PG8_MMA(1, 1, At, B1); PG8_BAR; PG8_SCHED;
	v_mfma_f32_16x16x32_f16 v[84:87], v[148:151], v[180:183], v[84:87]
	v_mfma_f32_16x16x32_f16 v[80:83], v[156:159], v[180:183], v[80:83]
	v_mfma_f32_16x16x32_f16 v[68:71], v[148:151], v[188:191], v[68:71]
	v_mfma_f32_16x16x32_f16 v[64:67], v[156:159], v[188:191], v[64:67]
	s_setprio 0
	s_add_i32 s45, s45, s68
	v_lshl_add_u64 v[192:193], v[192:193], 0, s[34:35]
	s_mov_b32 m0, s45
	ds_read_b128 v[160:163], v237 offset:49152
	ds_read_b128 v[164:167], v237 offset:50176
	ds_read_b128 v[168:171], v237 offset:51200
	ds_read_b128 v[172:175], v237 offset:52224
	ds_read_b128 v[176:179], v237 offset:53248
	ds_read_b128 v[180:183], v237 offset:54272
	ds_read_b128 v[184:187], v237 offset:55296
	ds_read_b128 v[188:191], v237 offset:56320
	global_load_lds_dwordx4 v[192:193], off
	s_add_i32 m0, s45, 0x2000
	s_add_u32 s54, s54, 0x40080
	v_lshl_add_u64 v[192:193], v[194:195], 0, s[34:35]
	s_addc_u32 s55, s55, 0
	s_add_i32 s45, s51, s68
	global_load_lds_dwordx4 v[192:193], off
	v_lshl_add_u64 v[192:193], s[54:55], 0, v[198:199]
	s_mov_b32 m0, s45
	s_nop 0
	global_load_lds_dwordx4 v[192:193], off
	v_lshl_add_u64 v[192:193], s[54:55], 0, v[202:203]
	s_add_i32 m0, s45, 0x2000
	s_nop 0
	global_load_lds_dwordx4 v[192:193], off
	v_lshl_add_u64 v[192:193], v[212:213], 0, s[34:35]
	s_mov_b32 m0, s75
	s_nop 0
	global_load_lds_dwordx4 v[192:193], off
	v_lshl_add_u64 v[192:193], v[214:215], 0, s[34:35]
	s_mov_b32 m0, s62
	s_nop 0
	global_load_lds_dwordx4 v[192:193], off
	s_waitcnt vmcnt(8)
	s_waitcnt lgkmcnt(0)
	s_barrier
	s_setprio 1
	s_waitcnt lgkmcnt(0)
	v_mfma_f32_16x16x32_f16 v[60:63], v[112:115], v[160:163], v[60:63]
	v_mfma_f32_16x16x32_f16 v[56:59], v[128:131], v[160:163], v[56:59]
	v_mfma_f32_16x16x32_f16 v[44:47], v[112:115], v[168:171], v[44:47]
	v_mfma_f32_16x16x32_f16 v[40:43], v[128:131], v[168:171], v[40:43]
	v_mfma_f32_16x16x32_f16 v[28:31], v[112:115], v[176:179], v[28:31]
	v_mfma_f32_16x16x32_f16 v[24:27], v[128:131], v[176:179], v[24:27]
	v_mfma_f32_16x16x32_f16 v[12:15], v[112:115], v[184:187], v[12:15]
	v_mfma_f32_16x16x32_f16 v[8:11], v[128:131], v[184:187], v[8:11]
	v_mfma_f32_16x16x32_f16 v[60:63], v[116:119], v[164:167], v[60:63]
	v_mfma_f32_16x16x32_f16 v[56:59], v[132:135], v[164:167], v[56:59]
	v_mfma_f32_16x16x32_f16 v[44:47], v[116:119], v[172:175], v[44:47]
	v_mfma_f32_16x16x32_f16 v[40:43], v[132:135], v[172:175], v[40:43]
	v_mfma_f32_16x16x32_f16 v[28:31], v[116:119], v[180:183], v[28:31]
	v_mfma_f32_16x16x32_f16 v[24:27], v[132:135], v[180:183], v[24:27]
	v_mfma_f32_16x16x32_f16 v[12:15], v[116:119], v[188:191], v[12:15]
	v_mfma_f32_16x16x32_f16 v[8:11], v[132:135], v[188:191], v[8:11]
	s_setprio 0
	s_setprio 1
	v_mfma_f32_16x16x32_f16 v[52:55], v[144:147], v[160:163], v[52:55]
	v_mfma_f32_16x16x32_f16 v[48:51], v[152:155], v[160:163], v[48:51]
	v_mfma_f32_16x16x32_f16 v[36:39], v[144:147], v[168:171], v[36:39]
	v_mfma_f32_16x16x32_f16 v[32:35], v[152:155], v[168:171], v[32:35]
	v_mfma_f32_16x16x32_f16 v[20:23], v[144:147], v[176:179], v[20:23]
	v_mfma_f32_16x16x32_f16 v[16:19], v[152:155], v[176:179], v[16:19]
	v_mfma_f32_16x16x32_f16 v[4:7], v[144:147], v[184:187], v[4:7]
	v_mfma_f32_16x16x32_f16 v[0:3], v[152:155], v[184:187], v[0:3]
	v_mfma_f32_16x16x32_f16 v[52:55], v[148:151], v[164:167], v[52:55]
	v_mfma_f32_16x16x32_f16 v[48:51], v[156:159], v[164:167], v[48:51]
	v_mfma_f32_16x16x32_f16 v[36:39], v[148:151], v[172:175], v[36:39]
	v_mfma_f32_16x16x32_f16 v[32:35], v[156:159], v[172:175], v[32:35]
	s_barrier
	v_mfma_f32_16x16x32_f16 v[20:23], v[148:151], v[180:183], v[20:23]
	v_mfma_f32_16x16x32_f16 v[16:19], v[156:159], v[180:183], v[16:19]
	v_mfma_f32_16x16x32_f16 v[4:7], v[148:151], v[188:191], v[4:7]
	v_mfma_f32_16x16x32_f16 v[0:3], v[156:159], v[188:191], v[0:3]
	s_setprio 0
	s_add_i32 s43, s43, 2
	s_add_u32 s52, s52, 0x100
	s_addc_u32 s53, s53, 0
	s_add_u32 s41, s41, 0x100
	s_addc_u32 s42, s42, 0
	s_cmp_gt_u32 s43, 13
	s_cbranch_scc0 .LBB0_1469
	s_and_b64 vcc, exec, s[16:17]
	s_cbranch_vccz .LBB0_1472
	s_barrier

; #define PG8_STAGE(bufoff, gbase, voff) do { _Pragma("unroll") for (int _i = 0; _i < 2; ++_i) \
;         __builtin_amdgcn_global_load_lds((const unsigned*)((const char*)(gbase) + (voff)[_i]), (PG8_LAS unsigned*)(lds + (bufoff) + ldsw + _i * 8192), 16, 0, 0); } while (0)
; #define PG8_LDA(dst, b, h) do { _Pragma("unroll") for (int m = 0; m < 4; ++m) _Pragma("unroll") for (int k = 0; k < 2; ++k) dst[m][k] = *(const PG8_LAS bf16x8*)(lds + PG8_SA(b, h) + aoff + m * 2048 + k * 1024); } while (0)
; #define PG8_LDB(dst, b, h) do { _Pragma("unroll") for (int n = 0; n < 2; ++n) _Pragma("unroll") for (int k = 0; k < 2; ++k) dst[n][k] = *(const PG8_LAS bf16x8*)(lds + PG8_SB(b, h) + boff + n * 2048 + k * 1024); } while (0)
; #define PG8_MMA(ai, bj, At, Bt) do { __builtin_amdgcn_s_setprio(1); _Pragma("unroll") for (int m = 0; m < 4; ++m) _Pragma("unroll") for (int n = 0; n < 2; ++n) _Pragma("unroll") for (int k = 0; k < 2; ++k) \
;         acc[ai][bj][m][n] = mma16<F16>(Bt[n][k], At[m][k], acc[ai][bj][m][n]); __builtin_amdgcn_s_setprio(0); } while (0)
; #define PG8_WAIT_V(n) asm volatile("s_waitcnt vmcnt(" #n ")" ::: "memory")
; #define PG8_WAIT_L(n) asm volatile("s_waitcnt lgkmcnt(" #n ")" ::: "memory")
; #define PG8_BAR __builtin_amdgcn_s_barrier()
; #define PG8_SCHED __builtin_amdgcn_sched_barrier(0)
; template <class Epi, class Sched, bool ALIGN_EPI = false, bool SP2 = false, bool F16 = false>
; __device__ __forceinline__ void gemm_phase(PG8_LAS unsigned char* lds, const Gemm g, const Sched& S, const Epi& E, const int wid_in) {
;     ...
;         for (int t = 0; t < nt; t += 2) {
;             const bool last = (t == nt - 2);
;             const char* a1 = cA + (size_t)(t + 1) * kstep;
;             const char* a2 = last ? nA : cA + (size_t)(t + 2) * kstep; const char* b2 = last ? nB : cB + (size_t)(t + 2) * kstep;
;             const char* a3 = a2 + kstep; const char* b3 = b2 + kstep;
;             if (last && has_next) S.a_ready(nxt);
;             if constexpr (SP2) {
;             PG8_LDB(B0, 0, 0); PG8_LDB(B1, 0, 1); PG8_SCHED; PG8_LDA(At, 0, 0); PG8_STAGE(PG8_SA(1, 1), a1 + hstep, voffA);
;             PG8_WAIT_V(8); PG8_WAIT_L(0); PG8_BAR; PG8_MMA(0, 0, At, B0); PG8_MMA(0, 1, At, B1); PG8_BAR; PG8_SCHED;
;             PG8_LDA(At, 0, 1); PG8_STAGE(PG8_SB(0, 0), b2, voffB); PG8_STAGE(PG8_SB(0, 1), b2 + hstep, voffB); PG8_STAGE(PG8_SA(0, 0), a2, voffA);
.LBB0_1548:
	ds_read_b128 v[128:131], v184
	ds_read_b128 v[132:135], v184 offset:1024
	ds_read_b128 v[136:139], v184 offset:2048
	ds_read_b128 v[140:143], v184 offset:3072
	ds_read_b128 v[144:147], v185
	ds_read_b128 v[148:151], v185 offset:1024
	ds_read_b128 v[152:155], v185 offset:2048
	ds_read_b128 v[174:177], v185 offset:3072
	s_add_u32 s45, s50, 0xfffc0080
	s_addc_u32 s52, s51, -1
	s_cmp_eq_u32 s43, 12
	s_cselect_b32 s55, s13, s52
	s_cselect_b32 s54, s31, s45
	s_cselect_b32 s53, s37, s42
	s_cselect_b32 s52, s40, s41
	v_lshl_add_u64 v[178:179], s[50:51], 0, v[166:167]
	s_add_i32 m0, s74, 0xc000
	ds_read_b128 v[190:193], v186
	ds_read_b128 v[194:197], v186 offset:1024
	ds_read_b128 v[198:201], v186 offset:2048
	ds_read_b128 v[202:205], v186 offset:3072
	ds_read_b128 v[206:209], v186 offset:4096
	ds_read_b128 v[210:213], v186 offset:5120
	ds_read_b128 v[214:217], v186 offset:6144
	ds_read_b128 v[218:221], v186 offset:7168
	global_load_lds_dwordx4 v[178:179], off
	v_lshl_add_u64 v[178:179], s[50:51], 0, v[168:169]
	s_add_i32 m0, s74, 0xe000
	s_nop 0
	global_load_lds_dwordx4 v[178:179], off
	s_waitcnt vmcnt(8)
	s_waitcnt lgkmcnt(0)
	s_barrier
	s_setprio 1
	s_waitcnt lgkmcnt(0)
	v_mfma_f32_16x16x32_f16 v[124:127], v[128:131], v[190:193], v[124:127]
	v_mfma_f32_16x16x32_f16 v[120:123], v[136:139], v[190:193], v[120:123]
	v_mfma_f32_16x16x32_f16 v[108:111], v[128:131], v[198:201], v[108:111]
	v_mfma_f32_16x16x32_f16 v[104:107], v[136:139], v[198:201], v[104:107]
	v_mfma_f32_16x16x32_f16 v[92:95], v[128:131], v[206:209], v[92:95]
	v_mfma_f32_16x16x32_f16 v[88:91], v[136:139], v[206:209], v[88:91]
	v_mfma_f32_16x16x32_f16 v[76:79], v[128:131], v[214:217], v[76:79]
	v_mfma_f32_16x16x32_f16 v[72:75], v[136:139], v[214:217], v[72:75]
	v_mfma_f32_16x16x32_f16 v[124:127], v[132:135], v[194:197], v[124:127]
	v_mfma_f32_16x16x32_f16 v[120:123], v[140:143], v[194:197], v[120:123]
	v_mfma_f32_16x16x32_f16 v[108:111], v[132:135], v[202:205], v[108:111]
	v_mfma_f32_16x16x32_f16 v[104:107], v[140:143], v[202:205], v[104:107]
	v_mfma_f32_16x16x32_f16 v[92:95], v[132:135], v[210:213], v[92:95]
	v_mfma_f32_16x16x32_f16 v[88:91], v[140:143], v[210:213], v[88:91]
	v_mfma_f32_16x16x32_f16 v[76:79], v[132:135], v[218:221], v[76:79]
	v_mfma_f32_16x16x32_f16 v[72:75], v[140:143], v[218:221], v[72:75]
	s_setprio 0
	s_setprio 1
	v_mfma_f32_16x16x32_f16 v[116:119], v[144:147], v[190:193], v[116:119]
	v_mfma_f32_16x16x32_f16 v[112:115], v[152:155], v[190:193], v[112:115]
	v_mfma_f32_16x16x32_f16 v[100:103], v[144:147], v[198:201], v[100:103]
	v_mfma_f32_16x16x32_f16 v[96:99], v[152:155], v[198:201], v[96:99]
	v_mfma_f32_16x16x32_f16 v[84:87], v[144:147], v[206:209], v[84:87]
	v_mfma_f32_16x16x32_f16 v[80:83], v[152:155], v[206:209], v[80:83]
	v_mfma_f32_16x16x32_f16 v[68:71], v[144:147], v[214:217], v[68:71]
	v_mfma_f32_16x16x32_f16 v[64:67], v[152:155], v[214:217], v[64:67]
	v_mfma_f32_16x16x32_f16 v[116:119], v[148:151], v[194:197], v[116:119]
	v_mfma_f32_16x16x32_f16 v[112:115], v[174:177], v[194:197], v[112:115]
	v_mfma_f32_16x16x32_f16 v[100:103], v[148:151], v[202:205], v[100:103]
	v_mfma_f32_16x16x32_f16 v[96:99], v[174:177], v[202:205], v[96:99]
	s_barrier
	v_mfma_f32_16x16x32_f16 v[84:87], v[148:151], v[210:213], v[84:87]
	v_mfma_f32_16x16x32_f16 v[80:83], v[174:177], v[210:213], v[80:83]
	v_mfma_f32_16x16x32_f16 v[68:71], v[148:151], v[218:221], v[68:71]
	v_mfma_f32_16x16x32_f16 v[64:67], v[174:177], v[218:221], v[64:67]
	s_setprio 0
	s_add_i32 s45, s90, s68
	v_lshl_add_u64 v[178:179], s[52:53], 0, v[158:159]
	s_mov_b32 m0, s45
	ds_read_b128 v[190:193], v186 offset:16384
	ds_read_b128 v[194:197], v186 offset:17408
	ds_read_b128 v[198:201], v186 offset:18432
	ds_read_b128 v[202:205], v186 offset:19456
	ds_read_b128 v[206:209], v186 offset:20480
	ds_read_b128 v[210:213], v186 offset:21504
	ds_read_b128 v[214:217], v186 offset:22528
	ds_read_b128 v[218:221], v186 offset:23552
	global_load_lds_dwordx4 v[178:179], off
	s_add_i32 m0, s45, 0x2000
	s_add_u32 s56, s52, 0x40000
	v_lshl_add_u64 v[222:223], s[52:53], 0, v[162:163]
	s_addc_u32 s57, s53, 0
	s_add_i32 s45, s84, s68
	global_load_lds_dwordx4 v[222:223], off
	v_lshl_add_u64 v[224:225], s[56:57], 0, v[158:159]
	s_mov_b32 m0, s45
	v_lshl_add_u64 v[226:227], s[54:55], 0, v[160:161]
	global_load_lds_dwordx4 v[224:225], off
	v_lshl_add_u64 v[224:225], s[56:57], 0, v[162:163]
	s_add_i32 m0, s45, 0x2000
	s_nop 0
	global_load_lds_dwordx4 v[224:225], off
	v_lshl_add_u64 v[224:225], s[54:55], 0, v[156:157]
	s_mov_b32 m0, s74
	s_nop 0
	global_load_lds_dwordx4 v[224:225], off
	s_mov_b32 m0, s66
	s_nop 0
	global_load_lds_dwordx4 v[226:227], off
	s_waitcnt vmcnt(8)
	s_waitcnt lgkmcnt(0)
	s_barrier
; #define PG8_STAGE(bufoff, gbase, voff) do { _Pragma("unroll") for (int _i = 0; _i < 2; ++_i) \
;         __builtin_amdgcn_global_load_lds((const unsigned*)((const char*)(gbase) + (voff)[_i]), (PG8_LAS unsigned*)(lds + (bufoff) + ldsw + _i * 8192), 16, 0, 0); } while (0)
; #define PG8_LDA(dst, b, h) do { _Pragma("unroll") for (int m = 0; m < 4; ++m) _Pragma("unroll") for (int k = 0; k < 2; ++k) dst[m][k] = *(const PG8_LAS bf16x8*)(lds + PG8_SA(b, h) + aoff + m * 2048 + k * 1024); } while (0)
; #define PG8_LDB(dst, b, h) do { _Pragma("unroll") for (int n = 0; n < 2; ++n) _Pragma("unroll") for (int k = 0; k < 2; ++k) dst[n][k] = *(const PG8_LAS bf16x8*)(lds + PG8_SB(b, h) + boff + n * 2048 + k * 1024); } while (0)
; #define PG8_MMA(ai, bj, At, Bt) do { __builtin_amdgcn_s_setprio(1); _Pragma("unroll") for (int m = 0; m < 4; ++m) _Pragma("unroll") for (int n = 0; n < 2; ++n) _Pragma("unroll") for (int k = 0; k < 2; ++k) \
;         acc[ai][bj][m][n] = mma16<F16>(Bt[n][k], At[m][k], acc[ai][bj][m][n]); __builtin_amdgcn_s_setprio(0); } while (0)
; #define PG8_WAIT_V(n) asm volatile("s_waitcnt vmcnt(" #n ")" ::: "memory")
; #define PG8_WAIT_L(n) asm volatile("s_waitcnt lgkmcnt(" #n ")" ::: "memory")
; #define PG8_BAR __builtin_amdgcn_s_barrier()
; #define PG8_SCHED __builtin_amdgcn_sched_barrier(0)
; template <class Epi, class Sched, bool ALIGN_EPI = false, bool SP2 = false, bool F16 = false>
; __device__ __forceinline__ void gemm_phase(PG8_LAS unsigned char* lds, const Gemm g, const Sched& S, const Epi& E, const int wid_in) {
;     ...
;             PG8_WAIT_V(8); PG8_WAIT_L(0); PG8_BAR; PG8_MMA(1, 0, At, B0); PG8_MMA(1, 1, At, B1); PG8_BAR; PG8_SCHED;
;             PG8_LDB(B0, 1, 0); PG8_LDB(B1, 1, 1); PG8_SCHED; PG8_LDA(At, 1, 0); PG8_STAGE(PG8_SA(0, 1), a2 + hstep, voffA);
;             PG8_WAIT_V(8); PG8_WAIT_L(0); PG8_BAR; PG8_MMA(0, 0, At, B0); PG8_MMA(0, 1, At, B1); PG8_BAR; PG8_SCHED;
	s_setprio 1
	s_waitcnt lgkmcnt(0)
	v_mfma_f32_16x16x32_f16 v[60:63], v[128:131], v[190:193], v[60:63]
	v_mfma_f32_16x16x32_f16 v[56:59], v[136:139], v[190:193], v[56:59]
	v_mfma_f32_16x16x32_f16 v[44:47], v[128:131], v[198:201], v[44:47]
	v_mfma_f32_16x16x32_f16 v[40:43], v[136:139], v[198:201], v[40:43]
	v_mfma_f32_16x16x32_f16 v[28:31], v[128:131], v[206:209], v[28:31]
	v_mfma_f32_16x16x32_f16 v[24:27], v[136:139], v[206:209], v[24:27]
	v_mfma_f32_16x16x32_f16 v[12:15], v[128:131], v[214:217], v[12:15]
	v_mfma_f32_16x16x32_f16 v[8:11], v[136:139], v[214:217], v[8:11]
	v_mfma_f32_16x16x32_f16 v[60:63], v[132:135], v[194:197], v[60:63]
	v_mfma_f32_16x16x32_f16 v[56:59], v[140:143], v[194:197], v[56:59]
	v_mfma_f32_16x16x32_f16 v[44:47], v[132:135], v[202:205], v[44:47]
	v_mfma_f32_16x16x32_f16 v[40:43], v[140:143], v[202:205], v[40:43]
	v_mfma_f32_16x16x32_f16 v[28:31], v[132:135], v[210:213], v[28:31]
	v_mfma_f32_16x16x32_f16 v[24:27], v[140:143], v[210:213], v[24:27]
	v_mfma_f32_16x16x32_f16 v[12:15], v[132:135], v[218:221], v[12:15]
	v_mfma_f32_16x16x32_f16 v[8:11], v[140:143], v[218:221], v[8:11]
	s_setprio 0
	s_setprio 1
	v_mfma_f32_16x16x32_f16 v[52:55], v[144:147], v[190:193], v[52:55]
	v_mfma_f32_16x16x32_f16 v[48:51], v[152:155], v[190:193], v[48:51]
	v_mfma_f32_16x16x32_f16 v[36:39], v[144:147], v[198:201], v[36:39]
	v_mfma_f32_16x16x32_f16 v[32:35], v[152:155], v[198:201], v[32:35]
	v_mfma_f32_16x16x32_f16 v[20:23], v[144:147], v[206:209], v[20:23]
	v_mfma_f32_16x16x32_f16 v[16:19], v[152:155], v[206:209], v[16:19]
	v_mfma_f32_16x16x32_f16 v[4:7], v[144:147], v[214:217], v[4:7]
	v_mfma_f32_16x16x32_f16 v[0:3], v[152:155], v[214:217], v[0:3]
	v_mfma_f32_16x16x32_f16 v[52:55], v[148:151], v[194:197], v[52:55]
	v_mfma_f32_16x16x32_f16 v[48:51], v[174:177], v[194:197], v[48:51]
	v_mfma_f32_16x16x32_f16 v[36:39], v[148:151], v[202:205], v[36:39]
	v_mfma_f32_16x16x32_f16 v[32:35], v[174:177], v[202:205], v[32:35]
	s_barrier
	v_mfma_f32_16x16x32_f16 v[20:23], v[148:151], v[210:213], v[20:23]
	v_mfma_f32_16x16x32_f16 v[16:19], v[174:177], v[210:213], v[16:19]
	v_mfma_f32_16x16x32_f16 v[4:7], v[148:151], v[218:221], v[4:7]
	v_mfma_f32_16x16x32_f16 v[0:3], v[174:177], v[218:221], v[0:3]
	s_setprio 0
	s_add_i32 s45, 0, 0x18000
	s_add_i32 s56, 0, 0x1c000
	v_add_u32_e32 v140, s45, v183
	v_add_u32_e32 v165, s56, v183
	ds_read_b128 v[128:131], v140
	ds_read_b128 v[132:135], v140 offset:1024
	ds_read_b128 v[136:139], v140 offset:2048
	ds_read_b128 v[140:143], v140 offset:3072
	ds_read_b128 v[144:147], v165
	ds_read_b128 v[148:151], v165 offset:1024
	ds_read_b128 v[152:155], v165 offset:2048
	ds_read_b128 v[174:177], v165 offset:3072
	s_add_u32 s54, s54, 0x40000
	s_addc_u32 s55, s55, 0
	s_mov_b32 m0, s67
	v_lshl_add_u64 v[228:229], s[54:55], 0, v[156:157]
	ds_read_b128 v[190:193], v186 offset:32768
	ds_read_b128 v[194:197], v186 offset:33792
	ds_read_b128 v[198:201], v186 offset:34816
	ds_read_b128 v[202:205], v186 offset:35840
	ds_read_b128 v[206:209], v186 offset:36864
	ds_read_b128 v[210:213], v186 offset:37888
	ds_read_b128 v[214:217], v186 offset:38912
	ds_read_b128 v[218:221], v186 offset:39936
	global_load_lds_dwordx4 v[228:229], off
	v_lshl_add_u64 v[228:229], s[54:55], 0, v[160:161]
	s_mov_b32 m0, s91
	s_nop 0
	global_load_lds_dwordx4 v[228:229], off
	s_waitcnt vmcnt(8)
	s_waitcnt lgkmcnt(0)
	s_barrier
	s_setprio 1
	s_waitcnt lgkmcnt(0)
	v_mfma_f32_16x16x32_f16 v[124:127], v[128:131], v[190:193], v[124:127]
	v_mfma_f32_16x16x32_f16 v[120:123], v[136:139], v[190:193], v[120:123]
	v_mfma_f32_16x16x32_f16 v[108:111], v[128:131], v[198:201], v[108:111]
	v_mfma_f32_16x16x32_f16 v[104:107], v[136:139], v[198:201], v[104:107]
	v_mfma_f32_16x16x32_f16 v[92:95], v[128:131], v[206:209], v[92:95]
	v_mfma_f32_16x16x32_f16 v[88:91], v[136:139], v[206:209], v[88:91]
	v_mfma_f32_16x16x32_f16 v[76:79], v[128:131], v[214:217], v[76:79]
	v_mfma_f32_16x16x32_f16 v[72:75], v[136:139], v[214:217], v[72:75]
	v_mfma_f32_16x16x32_f16 v[124:127], v[132:135], v[194:197], v[124:127]
	v_mfma_f32_16x16x32_f16 v[120:123], v[140:143], v[194:197], v[120:123]
	v_mfma_f32_16x16x32_f16 v[108:111], v[132:135], v[202:205], v[108:111]
	v_mfma_f32_16x16x32_f16 v[104:107], v[140:143], v[202:205], v[104:107]
	v_mfma_f32_16x16x32_f16 v[92:95], v[132:135], v[210:213], v[92:95]
	v_mfma_f32_16x16x32_f16 v[88:91], v[140:143], v[210:213], v[88:91]
	v_mfma_f32_16x16x32_f16 v[76:79], v[132:135], v[218:221], v[76:79]
	v_mfma_f32_16x16x32_f16 v[72:75], v[140:143], v[218:221], v[72:75]
	s_setprio 0
	s_setprio 1
	v_mfma_f32_16x16x32_f16 v[116:119], v[144:147], v[190:193], v[116:119]
	v_mfma_f32_16x16x32_f16 v[112:115], v[152:155], v[190:193], v[112:115]
	v_mfma_f32_16x16x32_f16 v[100:103], v[144:147], v[198:201], v[100:103]
	v_mfma_f32_16x16x32_f16 v[96:99], v[152:155], v[198:201], v[96:99]
	v_mfma_f32_16x16x32_f16 v[84:87], v[144:147], v[206:209], v[84:87]
	v_mfma_f32_16x16x32_f16 v[80:83], v[152:155], v[206:209], v[80:83]
	v_mfma_f32_16x16x32_f16 v[68:71], v[144:147], v[214:217], v[68:71]
	v_mfma_f32_16x16x32_f16 v[64:67], v[152:155], v[214:217], v[64:67]
	v_mfma_f32_16x16x32_f16 v[116:119], v[148:151], v[194:197], v[116:119]
	v_mfma_f32_16x16x32_f16 v[112:115], v[174:177], v[194:197], v[112:115]
	v_mfma_f32_16x16x32_f16 v[100:103], v[148:151], v[202:205], v[100:103]
	v_mfma_f32_16x16x32_f16 v[96:99], v[174:177], v[202:205], v[96:99]
	s_barrier
; #define PG8_STAGE(bufoff, gbase, voff) do { _Pragma("unroll") for (int _i = 0; _i < 2; ++_i) \
;         __builtin_amdgcn_global_load_lds((const unsigned*)((const char*)(gbase) + (voff)[_i]), (PG8_LAS unsigned*)(lds + (bufoff) + ldsw + _i * 8192), 16, 0, 0); } while (0)
; #define PG8_LDA(dst, b, h) do { _Pragma("unroll") for (int m = 0; m < 4; ++m) _Pragma("unroll") for (int k = 0; k < 2; ++k) dst[m][k] = *(const PG8_LAS bf16x8*)(lds + PG8_SA(b, h) + aoff + m * 2048 + k * 1024); } while (0)
; #define PG8_MMA(ai, bj, At, Bt) do { __builtin_amdgcn_s_setprio(1); _Pragma("unroll") for (int m = 0; m < 4; ++m) _Pragma("unroll") for (int n = 0; n < 2; ++n) _Pragma("unroll") for (int k = 0; k < 2; ++k) \
;         acc[ai][bj][m][n] = mma16<F16>(Bt[n][k], At[m][k], acc[ai][bj][m][n]); __builtin_amdgcn_s_setprio(0); } while (0)
; #define PG8_WAIT_V(n) asm volatile("s_waitcnt vmcnt(" #n ")" ::: "memory")
; #define PG8_WAIT_L(n) asm volatile("s_waitcnt lgkmcnt(" #n ")" ::: "memory")
; #define PG8_BAR __builtin_amdgcn_s_barrier()
; #define PG8_SCHED __builtin_amdgcn_sched_barrier(0)
; template <class Epi, class Sched, bool ALIGN_EPI = false, bool SP2 = false, bool F16 = false>
; __device__ __forceinline__ void gemm_phase(PG8_LAS unsigned char* lds, const Gemm g, const Sched& S, const Epi& E, const int wid_in) {
;     ...
;             PG8_WAIT_V(8); PG8_WAIT_L(0); PG8_BAR; PG8_MMA(0, 0, At, B0); PG8_MMA(0, 1, At, B1); PG8_BAR; PG8_SCHED;
;             PG8_LDA(At, 1, 1); PG8_STAGE(PG8_SB(1, 0), b3, voffB); PG8_STAGE(PG8_SB(1, 1), b3 + hstep, voffB); PG8_STAGE(PG8_SA(1, 0), a3, voffA);
;             PG8_WAIT_V(8); PG8_WAIT_L(0); PG8_BAR; PG8_MMA(1, 0, At, B0); PG8_MMA(1, 1, At, B1); PG8_BAR; PG8_SCHED;
	v_mfma_f32_16x16x32_f16 v[84:87], v[148:151], v[210:213], v[84:87]
	v_mfma_f32_16x16x32_f16 v[80:83], v[174:177], v[210:213], v[80:83]
	v_mfma_f32_16x16x32_f16 v[68:71], v[148:151], v[218:221], v[68:71]
	v_mfma_f32_16x16x32_f16 v[64:67], v[174:177], v[218:221], v[64:67]
	s_setprio 0
	s_add_i32 s45, s45, s68
	v_lshl_add_u64 v[178:179], v[178:179], 0, s[34:35]
	s_mov_b32 m0, s45
	ds_read_b128 v[190:193], v186 offset:49152
	ds_read_b128 v[194:197], v186 offset:50176
	ds_read_b128 v[198:201], v186 offset:51200
	ds_read_b128 v[202:205], v186 offset:52224
	ds_read_b128 v[206:209], v186 offset:53248
	ds_read_b128 v[210:213], v186 offset:54272
	ds_read_b128 v[214:217], v186 offset:55296
	ds_read_b128 v[218:221], v186 offset:56320
	global_load_lds_dwordx4 v[178:179], off
	s_add_i32 m0, s45, 0x2000
	s_add_u32 s52, s52, 0x40080
	v_lshl_add_u64 v[178:179], v[222:223], 0, s[34:35]
	s_addc_u32 s53, s53, 0
	s_add_i32 s45, s56, s68
	global_load_lds_dwordx4 v[178:179], off
	v_lshl_add_u64 v[178:179], s[52:53], 0, v[158:159]
	s_mov_b32 m0, s45
	s_nop 0
	global_load_lds_dwordx4 v[178:179], off
	v_lshl_add_u64 v[178:179], s[52:53], 0, v[162:163]
	s_add_i32 m0, s45, 0x2000
	s_nop 0
	global_load_lds_dwordx4 v[178:179], off
	v_lshl_add_u64 v[178:179], v[224:225], 0, s[34:35]
	s_mov_b32 m0, s75
	s_nop 0
	global_load_lds_dwordx4 v[178:179], off
	v_lshl_add_u64 v[178:179], v[226:227], 0, s[34:35]
	s_mov_b32 m0, s97
	s_nop 0
	global_load_lds_dwordx4 v[178:179], off
	s_waitcnt vmcnt(8)
	s_waitcnt lgkmcnt(0)
	s_barrier
	s_setprio 1
	s_waitcnt lgkmcnt(0)
	v_mfma_f32_16x16x32_f16 v[60:63], v[128:131], v[190:193], v[60:63]
	v_mfma_f32_16x16x32_f16 v[56:59], v[136:139], v[190:193], v[56:59]
	v_mfma_f32_16x16x32_f16 v[44:47], v[128:131], v[198:201], v[44:47]
	v_mfma_f32_16x16x32_f16 v[40:43], v[136:139], v[198:201], v[40:43]
	v_mfma_f32_16x16x32_f16 v[28:31], v[128:131], v[206:209], v[28:31]
	v_mfma_f32_16x16x32_f16 v[24:27], v[136:139], v[206:209], v[24:27]
	v_mfma_f32_16x16x32_f16 v[12:15], v[128:131], v[214:217], v[12:15]
	v_mfma_f32_16x16x32_f16 v[8:11], v[136:139], v[214:217], v[8:11]
	v_mfma_f32_16x16x32_f16 v[60:63], v[132:135], v[194:197], v[60:63]
	v_mfma_f32_16x16x32_f16 v[56:59], v[140:143], v[194:197], v[56:59]
	v_mfma_f32_16x16x32_f16 v[44:47], v[132:135], v[202:205], v[44:47]
	v_mfma_f32_16x16x32_f16 v[40:43], v[140:143], v[202:205], v[40:43]
	v_mfma_f32_16x16x32_f16 v[28:31], v[132:135], v[210:213], v[28:31]
	v_mfma_f32_16x16x32_f16 v[24:27], v[140:143], v[210:213], v[24:27]
	v_mfma_f32_16x16x32_f16 v[12:15], v[132:135], v[218:221], v[12:15]
	v_mfma_f32_16x16x32_f16 v[8:11], v[140:143], v[218:221], v[8:11]
	s_setprio 0
	s_setprio 1
	v_mfma_f32_16x16x32_f16 v[52:55], v[144:147], v[190:193], v[52:55]
	v_mfma_f32_16x16x32_f16 v[48:51], v[152:155], v[190:193], v[48:51]
	v_mfma_f32_16x16x32_f16 v[36:39], v[144:147], v[198:201], v[36:39]
	v_mfma_f32_16x16x32_f16 v[32:35], v[152:155], v[198:201], v[32:35]
	v_mfma_f32_16x16x32_f16 v[20:23], v[144:147], v[206:209], v[20:23]
	v_mfma_f32_16x16x32_f16 v[16:19], v[152:155], v[206:209], v[16:19]
	v_mfma_f32_16x16x32_f16 v[4:7], v[144:147], v[214:217], v[4:7]
	v_mfma_f32_16x16x32_f16 v[0:3], v[152:155], v[214:217], v[0:3]
	v_mfma_f32_16x16x32_f16 v[52:55], v[148:151], v[194:197], v[52:55]
	v_mfma_f32_16x16x32_f16 v[48:51], v[174:177], v[194:197], v[48:51]
	v_mfma_f32_16x16x32_f16 v[36:39], v[148:151], v[202:205], v[36:39]
	v_mfma_f32_16x16x32_f16 v[32:35], v[174:177], v[202:205], v[32:35]
	s_barrier
	v_mfma_f32_16x16x32_f16 v[20:23], v[148:151], v[210:213], v[20:23]
	v_mfma_f32_16x16x32_f16 v[16:19], v[174:177], v[210:213], v[16:19]
	v_mfma_f32_16x16x32_f16 v[4:7], v[148:151], v[218:221], v[4:7]
	v_mfma_f32_16x16x32_f16 v[0:3], v[174:177], v[218:221], v[0:3]
	s_setprio 0
	s_add_i32 s43, s43, 2
	s_add_u32 s50, s50, 0x100
	s_addc_u32 s51, s51, 0
	s_add_u32 s41, s41, 0x100
	s_addc_u32 s42, s42, 0
	s_cmp_gt_u32 s43, 13
	s_cbranch_scc0 .LBB0_1548
	s_and_b64 vcc, exec, s[16:17]
	s_cbranch_vccz .LBB0_1551
	s_barrier

; #define PG8_STAGE(bufoff, gbase, voff) do { _Pragma("unroll") for (int _i = 0; _i < 2; ++_i) \
;         __builtin_amdgcn_global_load_lds((const unsigned*)((const char*)(gbase) + (voff)[_i]), (PG8_LAS unsigned*)(lds + (bufoff) + ldsw + _i * 8192), 16, 0, 0); } while (0)
; #define PG8_LDA(dst, b, h) do { _Pragma("unroll") for (int m = 0; m < 4; ++m) _Pragma("unroll") for (int k = 0; k < 2; ++k) dst[m][k] = *(const PG8_LAS bf16x8*)(lds + PG8_SA(b, h) + aoff + m * 2048 + k * 1024); } while (0)
; #define PG8_LDB(dst, b, h) do { _Pragma("unroll") for (int n = 0; n < 2; ++n) _Pragma("unroll") for (int k = 0; k < 2; ++k) dst[n][k] = *(const PG8_LAS bf16x8*)(lds + PG8_SB(b, h) + boff + n * 2048 + k * 1024); } while (0)
; #define PG8_MMA(ai, bj, At, Bt) do { __builtin_amdgcn_s_setprio(1); _Pragma("unroll") for (int m = 0; m < 4; ++m) _Pragma("unroll") for (int n = 0; n < 2; ++n) _Pragma("unroll") for (int k = 0; k < 2; ++k) \
;         acc[ai][bj][m][n] = mma16<F16>(Bt[n][k], At[m][k], acc[ai][bj][m][n]); __builtin_amdgcn_s_setprio(0); } while (0)
; #define PG8_WAIT_V(n) asm volatile("s_waitcnt vmcnt(" #n ")" ::: "memory")
; #define PG8_WAIT_L(n) asm volatile("s_waitcnt lgkmcnt(" #n ")" ::: "memory")
; #define PG8_BAR __builtin_amdgcn_s_barrier()
; #define PG8_SCHED __builtin_amdgcn_sched_barrier(0)
; template <class Epi, class Sched, bool ALIGN_EPI = false, bool SP2 = false, bool F16 = false>
; __device__ __forceinline__ void gemm_phase(PG8_LAS unsigned char* lds, const Gemm g, const Sched& S, const Epi& E, const int wid_in) {
;     ...
;         for (int t = 0; t < nt; t += 2) {
;             const bool last = (t == nt - 2);
;             const char* a1 = cA + (size_t)(t + 1) * kstep;
;             const char* a2 = last ? nA : cA + (size_t)(t + 2) * kstep; const char* b2 = last ? nB : cB + (size_t)(t + 2) * kstep;
;             const char* a3 = a2 + kstep; const char* b3 = b2 + kstep;
;             if (last && has_next) S.a_ready(nxt);
;             if constexpr (SP2) {
;             PG8_LDB(B0, 0, 0); PG8_LDB(B1, 0, 1); PG8_SCHED; PG8_LDA(At, 0, 0); PG8_STAGE(PG8_SA(1, 1), a1 + hstep, voffA);
;             PG8_WAIT_V(8); PG8_WAIT_L(0); PG8_BAR; PG8_MMA(0, 0, At, B0); PG8_MMA(0, 1, At, B1); PG8_BAR; PG8_SCHED;
;             PG8_LDA(At, 0, 1); PG8_STAGE(PG8_SB(0, 0), b2, voffB); PG8_STAGE(PG8_SB(0, 1), b2 + hstep, voffB); PG8_STAGE(PG8_SA(0, 0), a2, voffA);
.LBB0_1832:
	ds_read_b128 v[128:131], v189
	ds_read_b128 v[132:135], v189 offset:1024
	ds_read_b128 v[136:139], v189 offset:2048
	ds_read_b128 v[140:143], v189 offset:3072
	ds_read_b128 v[144:147], v190
	ds_read_b128 v[148:151], v190 offset:1024
	ds_read_b128 v[168:171], v190 offset:2048
	ds_read_b128 v[172:175], v190 offset:3072
	s_add_u32 s50, s48, 0xfffc0080
	s_addc_u32 s51, s49, -1
	s_cmp_eq_u32 s61, 12
	s_cselect_b32 s53, s35, s51
	s_cselect_b32 s52, s42, s50
	s_cselect_b32 s51, s31, s60
	s_cselect_b32 s50, s43, s47
	s_mov_b32 m0, s91
	v_lshl_add_u64 v[184:185], s[48:49], 0, v[160:161]
	ds_read_b128 v[176:179], v191
	ds_read_b128 v[180:183], v191 offset:1024
	ds_read_b128 v[192:195], v191 offset:2048
	ds_read_b128 v[196:199], v191 offset:3072
	ds_read_b128 v[200:203], v191 offset:4096
	ds_read_b128 v[204:207], v191 offset:5120
	ds_read_b128 v[208:211], v191 offset:6144
	ds_read_b128 v[212:215], v191 offset:7168
	global_load_lds_dwordx4 v[184:185], off
	v_lshl_add_u64 v[184:185], s[48:49], 0, v[162:163]
	s_add_i32 m0, s74, 0xe000
	s_nop 0
	global_load_lds_dwordx4 v[184:185], off
	s_waitcnt vmcnt(8)
	s_waitcnt lgkmcnt(0)
	s_barrier
	s_setprio 1
	s_waitcnt lgkmcnt(0)
	v_mfma_f32_16x16x32_bf16 v[124:127], v[128:131], v[176:179], v[124:127]
	v_mfma_f32_16x16x32_bf16 v[120:123], v[136:139], v[176:179], v[120:123]
	v_mfma_f32_16x16x32_bf16 v[108:111], v[128:131], v[192:195], v[108:111]
	v_mfma_f32_16x16x32_bf16 v[104:107], v[136:139], v[192:195], v[104:107]
	v_mfma_f32_16x16x32_bf16 v[92:95], v[128:131], v[200:203], v[92:95]
	v_mfma_f32_16x16x32_bf16 v[88:91], v[136:139], v[200:203], v[88:91]
	v_mfma_f32_16x16x32_bf16 v[76:79], v[128:131], v[208:211], v[76:79]
	v_mfma_f32_16x16x32_bf16 v[72:75], v[136:139], v[208:211], v[72:75]
	v_mfma_f32_16x16x32_bf16 v[124:127], v[132:135], v[180:183], v[124:127]
	v_mfma_f32_16x16x32_bf16 v[120:123], v[140:143], v[180:183], v[120:123]
	v_mfma_f32_16x16x32_bf16 v[108:111], v[132:135], v[196:199], v[108:111]
	v_mfma_f32_16x16x32_bf16 v[104:107], v[140:143], v[196:199], v[104:107]
	v_mfma_f32_16x16x32_bf16 v[92:95], v[132:135], v[204:207], v[92:95]
	v_mfma_f32_16x16x32_bf16 v[88:91], v[140:143], v[204:207], v[88:91]
	v_mfma_f32_16x16x32_bf16 v[76:79], v[132:135], v[212:215], v[76:79]
	v_mfma_f32_16x16x32_bf16 v[72:75], v[140:143], v[212:215], v[72:75]
	s_setprio 0
	s_setprio 1
	v_mfma_f32_16x16x32_bf16 v[116:119], v[144:147], v[176:179], v[116:119]
	v_mfma_f32_16x16x32_bf16 v[112:115], v[168:171], v[176:179], v[112:115]
	v_mfma_f32_16x16x32_bf16 v[100:103], v[144:147], v[192:195], v[100:103]
	v_mfma_f32_16x16x32_bf16 v[96:99], v[168:171], v[192:195], v[96:99]
	v_mfma_f32_16x16x32_bf16 v[84:87], v[144:147], v[200:203], v[84:87]
	v_mfma_f32_16x16x32_bf16 v[80:83], v[168:171], v[200:203], v[80:83]
	v_mfma_f32_16x16x32_bf16 v[68:71], v[144:147], v[208:211], v[68:71]
	v_mfma_f32_16x16x32_bf16 v[64:67], v[168:171], v[208:211], v[64:67]
	v_mfma_f32_16x16x32_bf16 v[116:119], v[148:151], v[180:183], v[116:119]
	v_mfma_f32_16x16x32_bf16 v[112:115], v[172:175], v[180:183], v[112:115]
	v_mfma_f32_16x16x32_bf16 v[100:103], v[148:151], v[196:199], v[100:103]
	v_mfma_f32_16x16x32_bf16 v[96:99], v[172:175], v[196:199], v[96:99]
	s_barrier
	v_mfma_f32_16x16x32_bf16 v[84:87], v[148:151], v[204:207], v[84:87]
	v_mfma_f32_16x16x32_bf16 v[80:83], v[172:175], v[204:207], v[80:83]
	v_mfma_f32_16x16x32_bf16 v[68:71], v[148:151], v[212:215], v[68:71]
	v_mfma_f32_16x16x32_bf16 v[64:67], v[172:175], v[212:215], v[64:67]
	s_setprio 0
	s_add_i32 s62, s57, s68
	v_lshl_add_u64 v[184:185], s[50:51], 0, v[154:155]
	s_mov_b32 m0, s62
	ds_read_b128 v[176:179], v191 offset:16384
	ds_read_b128 v[180:183], v191 offset:17408
	ds_read_b128 v[192:195], v191 offset:18432
	ds_read_b128 v[196:199], v191 offset:19456
	ds_read_b128 v[200:203], v191 offset:20480
	ds_read_b128 v[204:207], v191 offset:21504
	ds_read_b128 v[208:211], v191 offset:22528
	ds_read_b128 v[212:215], v191 offset:23552
	global_load_lds_dwordx4 v[184:185], off
	s_add_i32 m0, s62, 0x2000
	s_add_u32 s62, s50, 0x40000
	v_lshl_add_u64 v[216:217], s[50:51], 0, v[158:159]
	s_addc_u32 s63, s51, 0
	s_add_i32 s64, s58, s68
	global_load_lds_dwordx4 v[216:217], off
	v_lshl_add_u64 v[218:219], s[62:63], 0, v[154:155]
	s_mov_b32 m0, s64
	v_lshl_add_u64 v[220:221], s[52:53], 0, v[156:157]
	global_load_lds_dwordx4 v[218:219], off
	v_lshl_add_u64 v[218:219], s[62:63], 0, v[158:159]
	s_add_i32 m0, s64, 0x2000
	s_nop 0
	global_load_lds_dwordx4 v[218:219], off
	v_lshl_add_u64 v[218:219], s[52:53], 0, v[152:153]
	s_mov_b32 m0, s74
	s_nop 0
	global_load_lds_dwordx4 v[218:219], off
	s_mov_b32 m0, s66
	s_nop 0
	global_load_lds_dwordx4 v[220:221], off
	s_waitcnt vmcnt(8)
	s_waitcnt lgkmcnt(0)
	s_barrier
; #define PG8_STAGE(bufoff, gbase, voff) do { _Pragma("unroll") for (int _i = 0; _i < 2; ++_i) \
;         __builtin_amdgcn_global_load_lds((const unsigned*)((const char*)(gbase) + (voff)[_i]), (PG8_LAS unsigned*)(lds + (bufoff) + ldsw + _i * 8192), 16, 0, 0); } while (0)
; #define PG8_LDA(dst, b, h) do { _Pragma("unroll") for (int m = 0; m < 4; ++m) _Pragma("unroll") for (int k = 0; k < 2; ++k) dst[m][k] = *(const PG8_LAS bf16x8*)(lds + PG8_SA(b, h) + aoff + m * 2048 + k * 1024); } while (0)
; #define PG8_LDB(dst, b, h) do { _Pragma("unroll") for (int n = 0; n < 2; ++n) _Pragma("unroll") for (int k = 0; k < 2; ++k) dst[n][k] = *(const PG8_LAS bf16x8*)(lds + PG8_SB(b, h) + boff + n * 2048 + k * 1024); } while (0)
; #define PG8_MMA(ai, bj, At, Bt) do { __builtin_amdgcn_s_setprio(1); _Pragma("unroll") for (int m = 0; m < 4; ++m) _Pragma("unroll") for (int n = 0; n < 2; ++n) _Pragma("unroll") for (int k = 0; k < 2; ++k) \
;         acc[ai][bj][m][n] = mma16<F16>(Bt[n][k], At[m][k], acc[ai][bj][m][n]); __builtin_amdgcn_s_setprio(0); } while (0)
; #define PG8_WAIT_V(n) asm volatile("s_waitcnt vmcnt(" #n ")" ::: "memory")
; #define PG8_WAIT_L(n) asm volatile("s_waitcnt lgkmcnt(" #n ")" ::: "memory")
; #define PG8_BAR __builtin_amdgcn_s_barrier()
; #define PG8_SCHED __builtin_amdgcn_sched_barrier(0)
; template <class Epi, class Sched, bool ALIGN_EPI = false, bool SP2 = false, bool F16 = false>
; __device__ __forceinline__ void gemm_phase(PG8_LAS unsigned char* lds, const Gemm g, const Sched& S, const Epi& E, const int wid_in) {
;     ...
;             PG8_WAIT_V(8); PG8_WAIT_L(0); PG8_BAR; PG8_MMA(1, 0, At, B0); PG8_MMA(1, 1, At, B1); PG8_BAR; PG8_SCHED;
;             PG8_LDB(B0, 1, 0); PG8_LDB(B1, 1, 1); PG8_SCHED; PG8_LDA(At, 1, 0); PG8_STAGE(PG8_SA(0, 1), a2 + hstep, voffA);
;             PG8_WAIT_V(8); PG8_WAIT_L(0); PG8_BAR; PG8_MMA(0, 0, At, B0); PG8_MMA(0, 1, At, B1); PG8_BAR; PG8_SCHED;
	s_setprio 1
	s_waitcnt lgkmcnt(0)
	v_mfma_f32_16x16x32_bf16 v[60:63], v[128:131], v[176:179], v[60:63]
	v_mfma_f32_16x16x32_bf16 v[56:59], v[136:139], v[176:179], v[56:59]
	v_mfma_f32_16x16x32_bf16 v[44:47], v[128:131], v[192:195], v[44:47]
	v_mfma_f32_16x16x32_bf16 v[40:43], v[136:139], v[192:195], v[40:43]
	v_mfma_f32_16x16x32_bf16 v[28:31], v[128:131], v[200:203], v[28:31]
	v_mfma_f32_16x16x32_bf16 v[24:27], v[136:139], v[200:203], v[24:27]
	v_mfma_f32_16x16x32_bf16 v[12:15], v[128:131], v[208:211], v[12:15]
	v_mfma_f32_16x16x32_bf16 v[8:11], v[136:139], v[208:211], v[8:11]
	v_mfma_f32_16x16x32_bf16 v[60:63], v[132:135], v[180:183], v[60:63]
	v_mfma_f32_16x16x32_bf16 v[56:59], v[140:143], v[180:183], v[56:59]
	v_mfma_f32_16x16x32_bf16 v[44:47], v[132:135], v[196:199], v[44:47]
	v_mfma_f32_16x16x32_bf16 v[40:43], v[140:143], v[196:199], v[40:43]
	v_mfma_f32_16x16x32_bf16 v[28:31], v[132:135], v[204:207], v[28:31]
	v_mfma_f32_16x16x32_bf16 v[24:27], v[140:143], v[204:207], v[24:27]
	v_mfma_f32_16x16x32_bf16 v[12:15], v[132:135], v[212:215], v[12:15]
	v_mfma_f32_16x16x32_bf16 v[8:11], v[140:143], v[212:215], v[8:11]
	s_setprio 0
	s_setprio 1
	v_mfma_f32_16x16x32_bf16 v[52:55], v[144:147], v[176:179], v[52:55]
	v_mfma_f32_16x16x32_bf16 v[48:51], v[168:171], v[176:179], v[48:51]
	v_mfma_f32_16x16x32_bf16 v[36:39], v[144:147], v[192:195], v[36:39]
	v_mfma_f32_16x16x32_bf16 v[32:35], v[168:171], v[192:195], v[32:35]
	v_mfma_f32_16x16x32_bf16 v[20:23], v[144:147], v[200:203], v[20:23]
	v_mfma_f32_16x16x32_bf16 v[16:19], v[168:171], v[200:203], v[16:19]
	v_mfma_f32_16x16x32_bf16 v[4:7], v[144:147], v[208:211], v[4:7]
	v_mfma_f32_16x16x32_bf16 v[0:3], v[168:171], v[208:211], v[0:3]
	v_mfma_f32_16x16x32_bf16 v[52:55], v[148:151], v[180:183], v[52:55]
	v_mfma_f32_16x16x32_bf16 v[48:51], v[172:175], v[180:183], v[48:51]
	v_mfma_f32_16x16x32_bf16 v[36:39], v[148:151], v[196:199], v[36:39]
	v_mfma_f32_16x16x32_bf16 v[32:35], v[172:175], v[196:199], v[32:35]
	s_barrier
	v_mfma_f32_16x16x32_bf16 v[20:23], v[148:151], v[204:207], v[20:23]
	v_mfma_f32_16x16x32_bf16 v[16:19], v[172:175], v[204:207], v[16:19]
	v_mfma_f32_16x16x32_bf16 v[4:7], v[148:151], v[212:215], v[4:7]
	v_mfma_f32_16x16x32_bf16 v[0:3], v[172:175], v[212:215], v[0:3]
	s_setprio 0
	s_add_i32 s62, 0, 0x18000
	s_add_i32 s63, 0, 0x1c000
	v_add_u32_e32 v140, s62, v188
	v_add_u32_e32 v172, s63, v188
	ds_read_b128 v[128:131], v140
	ds_read_b128 v[132:135], v140 offset:1024
	ds_read_b128 v[136:139], v140 offset:2048
	ds_read_b128 v[140:143], v140 offset:3072
	ds_read_b128 v[144:147], v172
	ds_read_b128 v[148:151], v172 offset:1024
	ds_read_b128 v[168:171], v172 offset:2048
	ds_read_b128 v[172:175], v172 offset:3072
	s_add_u32 s52, s52, 0x40000
	s_addc_u32 s53, s53, 0
	s_mov_b32 m0, s90
	v_lshl_add_u64 v[222:223], s[52:53], 0, v[152:153]
	ds_read_b128 v[176:179], v191 offset:32768
	ds_read_b128 v[180:183], v191 offset:33792
	ds_read_b128 v[192:195], v191 offset:34816
	ds_read_b128 v[196:199], v191 offset:35840
	ds_read_b128 v[200:203], v191 offset:36864
	ds_read_b128 v[204:207], v191 offset:37888
	ds_read_b128 v[208:211], v191 offset:38912
	ds_read_b128 v[212:215], v191 offset:39936
	global_load_lds_dwordx4 v[222:223], off
	v_lshl_add_u64 v[222:223], s[52:53], 0, v[156:157]
	s_mov_b32 m0, s41
	s_nop 0
	global_load_lds_dwordx4 v[222:223], off
	s_waitcnt vmcnt(8)
	s_waitcnt lgkmcnt(0)
	s_barrier
	s_setprio 1
	s_waitcnt lgkmcnt(0)
	v_mfma_f32_16x16x32_bf16 v[124:127], v[128:131], v[176:179], v[124:127]
	v_mfma_f32_16x16x32_bf16 v[120:123], v[136:139], v[176:179], v[120:123]
	v_mfma_f32_16x16x32_bf16 v[108:111], v[128:131], v[192:195], v[108:111]
	v_mfma_f32_16x16x32_bf16 v[104:107], v[136:139], v[192:195], v[104:107]
	v_mfma_f32_16x16x32_bf16 v[92:95], v[128:131], v[200:203], v[92:95]
	v_mfma_f32_16x16x32_bf16 v[88:91], v[136:139], v[200:203], v[88:91]
	v_mfma_f32_16x16x32_bf16 v[76:79], v[128:131], v[208:211], v[76:79]
	v_mfma_f32_16x16x32_bf16 v[72:75], v[136:139], v[208:211], v[72:75]
	v_mfma_f32_16x16x32_bf16 v[124:127], v[132:135], v[180:183], v[124:127]
	v_mfma_f32_16x16x32_bf16 v[120:123], v[140:143], v[180:183], v[120:123]
	v_mfma_f32_16x16x32_bf16 v[108:111], v[132:135], v[196:199], v[108:111]
	v_mfma_f32_16x16x32_bf16 v[104:107], v[140:143], v[196:199], v[104:107]
	v_mfma_f32_16x16x32_bf16 v[92:95], v[132:135], v[204:207], v[92:95]
	v_mfma_f32_16x16x32_bf16 v[88:91], v[140:143], v[204:207], v[88:91]
	v_mfma_f32_16x16x32_bf16 v[76:79], v[132:135], v[212:215], v[76:79]
	v_mfma_f32_16x16x32_bf16 v[72:75], v[140:143], v[212:215], v[72:75]
	s_setprio 0
	s_setprio 1
	v_mfma_f32_16x16x32_bf16 v[116:119], v[144:147], v[176:179], v[116:119]
	v_mfma_f32_16x16x32_bf16 v[112:115], v[168:171], v[176:179], v[112:115]
	v_mfma_f32_16x16x32_bf16 v[100:103], v[144:147], v[192:195], v[100:103]
	v_mfma_f32_16x16x32_bf16 v[96:99], v[168:171], v[192:195], v[96:99]
	v_mfma_f32_16x16x32_bf16 v[84:87], v[144:147], v[200:203], v[84:87]
	v_mfma_f32_16x16x32_bf16 v[80:83], v[168:171], v[200:203], v[80:83]
	v_mfma_f32_16x16x32_bf16 v[68:71], v[144:147], v[208:211], v[68:71]
	v_mfma_f32_16x16x32_bf16 v[64:67], v[168:171], v[208:211], v[64:67]
	v_mfma_f32_16x16x32_bf16 v[116:119], v[148:151], v[180:183], v[116:119]
	v_mfma_f32_16x16x32_bf16 v[112:115], v[172:175], v[180:183], v[112:115]
	v_mfma_f32_16x16x32_bf16 v[100:103], v[148:151], v[196:199], v[100:103]
	v_mfma_f32_16x16x32_bf16 v[96:99], v[172:175], v[196:199], v[96:99]
	s_barrier
; #define PG8_STAGE(bufoff, gbase, voff) do { _Pragma("unroll") for (int _i = 0; _i < 2; ++_i) \
;         __builtin_amdgcn_global_load_lds((const unsigned*)((const char*)(gbase) + (voff)[_i]), (PG8_LAS unsigned*)(lds + (bufoff) + ldsw + _i * 8192), 16, 0, 0); } while (0)
; #define PG8_LDA(dst, b, h) do { _Pragma("unroll") for (int m = 0; m < 4; ++m) _Pragma("unroll") for (int k = 0; k < 2; ++k) dst[m][k] = *(const PG8_LAS bf16x8*)(lds + PG8_SA(b, h) + aoff + m * 2048 + k * 1024); } while (0)
; #define PG8_MMA(ai, bj, At, Bt) do { __builtin_amdgcn_s_setprio(1); _Pragma("unroll") for (int m = 0; m < 4; ++m) _Pragma("unroll") for (int n = 0; n < 2; ++n) _Pragma("unroll") for (int k = 0; k < 2; ++k) \
;         acc[ai][bj][m][n] = mma16<F16>(Bt[n][k], At[m][k], acc[ai][bj][m][n]); __builtin_amdgcn_s_setprio(0); } while (0)
; #define PG8_WAIT_V(n) asm volatile("s_waitcnt vmcnt(" #n ")" ::: "memory")
; #define PG8_WAIT_L(n) asm volatile("s_waitcnt lgkmcnt(" #n ")" ::: "memory")
; #define PG8_BAR __builtin_amdgcn_s_barrier()
; #define PG8_SCHED __builtin_amdgcn_sched_barrier(0)
; template <class Epi, class Sched, bool ALIGN_EPI = false, bool SP2 = false, bool F16 = false>
; __device__ __forceinline__ void gemm_phase(PG8_LAS unsigned char* lds, const Gemm g, const Sched& S, const Epi& E, const int wid_in) {
;     ...
;             PG8_WAIT_V(8); PG8_WAIT_L(0); PG8_BAR; PG8_MMA(0, 0, At, B0); PG8_MMA(0, 1, At, B1); PG8_BAR; PG8_SCHED;
;             PG8_LDA(At, 1, 1); PG8_STAGE(PG8_SB(1, 0), b3, voffB); PG8_STAGE(PG8_SB(1, 1), b3 + hstep, voffB); PG8_STAGE(PG8_SA(1, 0), a3, voffA);
;             PG8_WAIT_V(8); PG8_WAIT_L(0); PG8_BAR; PG8_MMA(1, 0, At, B0); PG8_MMA(1, 1, At, B1); PG8_BAR; PG8_SCHED;
	v_mfma_f32_16x16x32_bf16 v[84:87], v[148:151], v[204:207], v[84:87]
	v_mfma_f32_16x16x32_bf16 v[80:83], v[172:175], v[204:207], v[80:83]
	v_mfma_f32_16x16x32_bf16 v[68:71], v[148:151], v[212:215], v[68:71]
	v_mfma_f32_16x16x32_bf16 v[64:67], v[172:175], v[212:215], v[64:67]
	s_setprio 0
	s_add_i32 s52, s62, s68
	v_lshl_add_u64 v[184:185], v[184:185], 0, s[28:29]
	s_mov_b32 m0, s52
	ds_read_b128 v[176:179], v191 offset:49152
	ds_read_b128 v[180:183], v191 offset:50176
	ds_read_b128 v[192:195], v191 offset:51200
	ds_read_b128 v[196:199], v191 offset:52224
	ds_read_b128 v[200:203], v191 offset:53248
	ds_read_b128 v[204:207], v191 offset:54272
	ds_read_b128 v[208:211], v191 offset:55296
	ds_read_b128 v[212:215], v191 offset:56320
	global_load_lds_dwordx4 v[184:185], off
	s_add_i32 m0, s52, 0x2000
	s_add_u32 s50, s50, 0x40080
	v_lshl_add_u64 v[184:185], v[216:217], 0, s[28:29]
	s_addc_u32 s51, s51, 0
	s_add_i32 s52, s63, s68
	global_load_lds_dwordx4 v[184:185], off
	v_lshl_add_u64 v[184:185], s[50:51], 0, v[154:155]
	s_mov_b32 m0, s52
	s_nop 0
	global_load_lds_dwordx4 v[184:185], off
	v_lshl_add_u64 v[184:185], s[50:51], 0, v[158:159]
	s_add_i32 m0, s52, 0x2000
	s_nop 0
	global_load_lds_dwordx4 v[184:185], off
	v_lshl_add_u64 v[184:185], v[218:219], 0, s[28:29]
	s_mov_b32 m0, s75
	s_nop 0
	global_load_lds_dwordx4 v[184:185], off
	v_lshl_add_u64 v[184:185], v[220:221], 0, s[28:29]
	s_mov_b32 m0, s67
	s_nop 0
	global_load_lds_dwordx4 v[184:185], off
	s_waitcnt vmcnt(8)
	s_waitcnt lgkmcnt(0)
	s_barrier
	s_setprio 1
	s_waitcnt lgkmcnt(0)
	v_mfma_f32_16x16x32_bf16 v[60:63], v[128:131], v[176:179], v[60:63]
	v_mfma_f32_16x16x32_bf16 v[56:59], v[136:139], v[176:179], v[56:59]
	v_mfma_f32_16x16x32_bf16 v[44:47], v[128:131], v[192:195], v[44:47]
	v_mfma_f32_16x16x32_bf16 v[40:43], v[136:139], v[192:195], v[40:43]
	v_mfma_f32_16x16x32_bf16 v[28:31], v[128:131], v[200:203], v[28:31]
	v_mfma_f32_16x16x32_bf16 v[24:27], v[136:139], v[200:203], v[24:27]
	v_mfma_f32_16x16x32_bf16 v[12:15], v[128:131], v[208:211], v[12:15]
	v_mfma_f32_16x16x32_bf16 v[8:11], v[136:139], v[208:211], v[8:11]
	v_mfma_f32_16x16x32_bf16 v[60:63], v[132:135], v[180:183], v[60:63]
	v_mfma_f32_16x16x32_bf16 v[56:59], v[140:143], v[180:183], v[56:59]
	v_mfma_f32_16x16x32_bf16 v[44:47], v[132:135], v[196:199], v[44:47]
	v_mfma_f32_16x16x32_bf16 v[40:43], v[140:143], v[196:199], v[40:43]
	v_mfma_f32_16x16x32_bf16 v[28:31], v[132:135], v[204:207], v[28:31]
	v_mfma_f32_16x16x32_bf16 v[24:27], v[140:143], v[204:207], v[24:27]
	v_mfma_f32_16x16x32_bf16 v[12:15], v[132:135], v[212:215], v[12:15]
	v_mfma_f32_16x16x32_bf16 v[8:11], v[140:143], v[212:215], v[8:11]
	s_setprio 0
	s_setprio 1
	v_mfma_f32_16x16x32_bf16 v[52:55], v[144:147], v[176:179], v[52:55]
	v_mfma_f32_16x16x32_bf16 v[48:51], v[168:171], v[176:179], v[48:51]
	v_mfma_f32_16x16x32_bf16 v[36:39], v[144:147], v[192:195], v[36:39]
	v_mfma_f32_16x16x32_bf16 v[32:35], v[168:171], v[192:195], v[32:35]
	v_mfma_f32_16x16x32_bf16 v[20:23], v[144:147], v[200:203], v[20:23]
	v_mfma_f32_16x16x32_bf16 v[16:19], v[168:171], v[200:203], v[16:19]
	v_mfma_f32_16x16x32_bf16 v[4:7], v[144:147], v[208:211], v[4:7]
	v_mfma_f32_16x16x32_bf16 v[0:3], v[168:171], v[208:211], v[0:3]
	v_mfma_f32_16x16x32_bf16 v[52:55], v[148:151], v[180:183], v[52:55]
	v_mfma_f32_16x16x32_bf16 v[48:51], v[172:175], v[180:183], v[48:51]
	v_mfma_f32_16x16x32_bf16 v[36:39], v[148:151], v[196:199], v[36:39]
	v_mfma_f32_16x16x32_bf16 v[32:35], v[172:175], v[196:199], v[32:35]
	s_barrier
	v_mfma_f32_16x16x32_bf16 v[20:23], v[148:151], v[204:207], v[20:23]
	v_mfma_f32_16x16x32_bf16 v[16:19], v[172:175], v[204:207], v[16:19]
	v_mfma_f32_16x16x32_bf16 v[4:7], v[148:151], v[212:215], v[4:7]
	v_mfma_f32_16x16x32_bf16 v[0:3], v[172:175], v[212:215], v[0:3]
	s_setprio 0
	s_add_i32 s61, s61, 2
	s_add_u32 s48, s48, 0x100
	s_addc_u32 s49, s49, 0
	s_add_u32 s47, s47, 0x100
	s_addc_u32 s60, s60, 0
	s_cmp_gt_u32 s61, 13
	s_cbranch_scc0 .LBB0_1832
	s_and_b64 vcc, exec, s[16:17]
	s_cbranch_vccz .LBB0_1835
	s_barrier

; #define PG8_STAGE(bufoff, gbase, voff) do { _Pragma("unroll") for (int _i = 0; _i < 2; ++_i) \
;         __builtin_amdgcn_global_load_lds((const unsigned*)((const char*)(gbase) + (voff)[_i]), (PG8_LAS unsigned*)(lds + (bufoff) + ldsw + _i * 8192), 16, 0, 0); } while (0)
; #define PG8_LDA(dst, b, h) do { _Pragma("unroll") for (int m = 0; m < 4; ++m) _Pragma("unroll") for (int k = 0; k < 2; ++k) dst[m][k] = *(const PG8_LAS bf16x8*)(lds + PG8_SA(b, h) + aoff + m * 2048 + k * 1024); } while (0)
; #define PG8_LDB(dst, b, h) do { _Pragma("unroll") for (int n = 0; n < 2; ++n) _Pragma("unroll") for (int k = 0; k < 2; ++k) dst[n][k] = *(const PG8_LAS bf16x8*)(lds + PG8_SB(b, h) + boff + n * 2048 + k * 1024); } while (0)
; #define PG8_MMA(ai, bj, At, Bt) do { __builtin_amdgcn_s_setprio(1); _Pragma("unroll") for (int m = 0; m < 4; ++m) _Pragma("unroll") for (int n = 0; n < 2; ++n) _Pragma("unroll") for (int k = 0; k < 2; ++k) \
;         acc[ai][bj][m][n] = mma16<F16>(Bt[n][k], At[m][k], acc[ai][bj][m][n]); __builtin_amdgcn_s_setprio(0); } while (0)
; #define PG8_WAIT_V(n) asm volatile("s_waitcnt vmcnt(" #n ")" ::: "memory")
; #define PG8_WAIT_L(n) asm volatile("s_waitcnt lgkmcnt(" #n ")" ::: "memory")
; #define PG8_BAR __builtin_amdgcn_s_barrier()
; #define PG8_SCHED __builtin_amdgcn_sched_barrier(0)
; template <class Epi, class Sched, bool ALIGN_EPI = false, bool SP2 = false, bool F16 = false>
; __device__ __forceinline__ void gemm_phase(PG8_LAS unsigned char* lds, const Gemm g, const Sched& S, const Epi& E, const int wid_in) {
;     ...
;         for (int t = 0; t < nt; t += 2) {
;             const bool last = (t == nt - 2);
;             const char* a1 = cA + (size_t)(t + 1) * kstep;
;             const char* a2 = last ? nA : cA + (size_t)(t + 2) * kstep; const char* b2 = last ? nB : cB + (size_t)(t + 2) * kstep;
;             const char* a3 = a2 + kstep; const char* b3 = b2 + kstep;
;             if (last && has_next) S.a_ready(nxt);
;             if constexpr (SP2) {
;             PG8_LDB(B0, 0, 0); PG8_LDB(B1, 0, 1); PG8_SCHED; PG8_LDA(At, 0, 0); PG8_STAGE(PG8_SA(1, 1), a1 + hstep, voffA);
;             PG8_WAIT_V(8); PG8_WAIT_L(0); PG8_BAR; PG8_MMA(0, 0, At, B0); PG8_MMA(0, 1, At, B1); PG8_BAR; PG8_SCHED;
;             PG8_LDA(At, 0, 1); PG8_STAGE(PG8_SB(0, 0), b2, voffB); PG8_STAGE(PG8_SB(0, 1), b2 + hstep, voffB); PG8_STAGE(PG8_SA(0, 0), a2, voffA);
.LBB0_1909:
	ds_read_b128 v[0:3], v193
	ds_read_b128 v[4:7], v193 offset:1024
	ds_read_b128 v[136:139], v193 offset:2048
	ds_read_b128 v[140:143], v193 offset:3072
	ds_read_b128 v[144:147], v194
	ds_read_b128 v[148:151], v194 offset:1024
	ds_read_b128 v[152:155], v194 offset:2048
	ds_read_b128 v[156:159], v194 offset:3072
	s_add_u32 s48, s46, 0xfffc0080
	s_addc_u32 s49, s47, -1
	s_cmp_eq_u32 s64, 12
	s_cselect_b32 s51, s29, s49
	s_cselect_b32 s50, s42, s48
	s_cselect_b32 s49, s27, s63
	s_cselect_b32 s48, s43, s45
	s_mov_b32 m0, s91
	v_lshl_add_u64 v[188:189], s[46:47], 0, v[168:169]
	ds_read_b128 v[176:179], v195
	ds_read_b128 v[180:183], v195 offset:1024
	ds_read_b128 v[184:187], v195 offset:2048
	ds_read_b128 v[198:201], v195 offset:3072
	ds_read_b128 v[202:205], v195 offset:4096
	ds_read_b128 v[206:209], v195 offset:5120
	ds_read_b128 v[210:213], v195 offset:6144
	ds_read_b128 v[214:217], v195 offset:7168
	global_load_lds_dwordx4 v[188:189], off
	v_lshl_add_u64 v[188:189], s[46:47], 0, v[170:171]
	s_add_i32 m0, s74, 0xe000
	s_nop 0
	global_load_lds_dwordx4 v[188:189], off
	s_waitcnt vmcnt(8)
	s_waitcnt lgkmcnt(0)
	s_barrier
	s_setprio 1
	s_waitcnt lgkmcnt(0)
	v_mfma_f32_16x16x32_f16 v[132:135], v[0:3], v[176:179], v[132:135]
	v_mfma_f32_16x16x32_f16 v[128:131], v[136:139], v[176:179], v[128:131]
	v_mfma_f32_16x16x32_f16 v[116:119], v[0:3], v[184:187], v[116:119]
	v_mfma_f32_16x16x32_f16 v[112:115], v[136:139], v[184:187], v[112:115]
	v_mfma_f32_16x16x32_f16 v[100:103], v[0:3], v[202:205], v[100:103]
	v_mfma_f32_16x16x32_f16 v[96:99], v[136:139], v[202:205], v[96:99]
	v_mfma_f32_16x16x32_f16 v[84:87], v[0:3], v[210:213], v[84:87]
	v_mfma_f32_16x16x32_f16 v[80:83], v[136:139], v[210:213], v[80:83]
	v_mfma_f32_16x16x32_f16 v[132:135], v[4:7], v[180:183], v[132:135]
	v_mfma_f32_16x16x32_f16 v[128:131], v[140:143], v[180:183], v[128:131]
	v_mfma_f32_16x16x32_f16 v[116:119], v[4:7], v[198:201], v[116:119]
	v_mfma_f32_16x16x32_f16 v[112:115], v[140:143], v[198:201], v[112:115]
	v_mfma_f32_16x16x32_f16 v[100:103], v[4:7], v[206:209], v[100:103]
	v_mfma_f32_16x16x32_f16 v[96:99], v[140:143], v[206:209], v[96:99]
	v_mfma_f32_16x16x32_f16 v[84:87], v[4:7], v[214:217], v[84:87]
	v_mfma_f32_16x16x32_f16 v[80:83], v[140:143], v[214:217], v[80:83]
	s_setprio 0
	s_setprio 1
	v_mfma_f32_16x16x32_f16 v[124:127], v[144:147], v[176:179], v[124:127]
	v_mfma_f32_16x16x32_f16 v[120:123], v[152:155], v[176:179], v[120:123]
	v_mfma_f32_16x16x32_f16 v[108:111], v[144:147], v[184:187], v[108:111]
	v_mfma_f32_16x16x32_f16 v[104:107], v[152:155], v[184:187], v[104:107]
	v_mfma_f32_16x16x32_f16 v[92:95], v[144:147], v[202:205], v[92:95]
	v_mfma_f32_16x16x32_f16 v[88:91], v[152:155], v[202:205], v[88:91]
	v_mfma_f32_16x16x32_f16 v[76:79], v[144:147], v[210:213], v[76:79]
	v_mfma_f32_16x16x32_f16 v[72:75], v[152:155], v[210:213], v[72:75]
	v_mfma_f32_16x16x32_f16 v[124:127], v[148:151], v[180:183], v[124:127]
	v_mfma_f32_16x16x32_f16 v[120:123], v[156:159], v[180:183], v[120:123]
	v_mfma_f32_16x16x32_f16 v[108:111], v[148:151], v[198:201], v[108:111]
	v_mfma_f32_16x16x32_f16 v[104:107], v[156:159], v[198:201], v[104:107]
	s_barrier
	v_mfma_f32_16x16x32_f16 v[92:95], v[148:151], v[206:209], v[92:95]
	v_mfma_f32_16x16x32_f16 v[88:91], v[156:159], v[206:209], v[88:91]
	v_mfma_f32_16x16x32_f16 v[76:79], v[148:151], v[214:217], v[76:79]
	v_mfma_f32_16x16x32_f16 v[72:75], v[156:159], v[214:217], v[72:75]
	s_setprio 0
	s_add_i32 s65, s60, s68
	v_lshl_add_u64 v[188:189], s[48:49], 0, v[162:163]
	s_mov_b32 m0, s65
	ds_read_b128 v[176:179], v195 offset:16384
	ds_read_b128 v[180:183], v195 offset:17408
	ds_read_b128 v[184:187], v195 offset:18432
	ds_read_b128 v[198:201], v195 offset:19456
	ds_read_b128 v[202:205], v195 offset:20480
	ds_read_b128 v[206:209], v195 offset:21504
	ds_read_b128 v[210:213], v195 offset:22528
	ds_read_b128 v[214:217], v195 offset:23552
	global_load_lds_dwordx4 v[188:189], off
	s_add_i32 m0, s65, 0x2000
	s_add_u32 s84, s48, 0x40000
	v_lshl_add_u64 v[218:219], s[48:49], 0, v[166:167]
	s_addc_u32 s85, s49, 0
	s_add_i32 s65, s61, s68
	global_load_lds_dwordx4 v[218:219], off
	v_lshl_add_u64 v[220:221], s[84:85], 0, v[162:163]
	s_mov_b32 m0, s65
	v_lshl_add_u64 v[222:223], s[50:51], 0, v[164:165]
	global_load_lds_dwordx4 v[220:221], off
	v_lshl_add_u64 v[220:221], s[84:85], 0, v[166:167]
	s_add_i32 m0, s65, 0x2000
	s_nop 0
	global_load_lds_dwordx4 v[220:221], off
	v_lshl_add_u64 v[220:221], s[50:51], 0, v[160:161]
	s_mov_b32 m0, s74
	s_nop 0
	global_load_lds_dwordx4 v[220:221], off
	s_mov_b32 m0, s66
	s_nop 0
	global_load_lds_dwordx4 v[222:223], off
	s_waitcnt vmcnt(8)
	s_waitcnt lgkmcnt(0)
	s_barrier
	s_setprio 1
	s_waitcnt lgkmcnt(0)
	v_mfma_f32_16x16x32_f16 v[68:71], v[0:3], v[176:179], v[68:71]
	v_mfma_f32_16x16x32_f16 v[64:67], v[136:139], v[176:179], v[64:67]
	v_mfma_f32_16x16x32_f16 v[52:55], v[0:3], v[184:187], v[52:55]
	v_mfma_f32_16x16x32_f16 v[48:51], v[136:139], v[184:187], v[48:51]
	v_mfma_f32_16x16x32_f16 v[36:39], v[0:3], v[202:205], v[36:39]
	v_mfma_f32_16x16x32_f16 v[32:35], v[136:139], v[202:205], v[32:35]
	v_mfma_f32_16x16x32_f16 v[0:3], v[0:3], v[210:213], v[20:23]
	v_mfma_f32_16x16x32_f16 v[68:71], v[4:7], v[180:183], v[68:71]
	v_mfma_f32_16x16x32_f16 v[64:67], v[140:143], v[180:183], v[64:67]
	v_mfma_f32_16x16x32_f16 v[52:55], v[4:7], v[198:201], v[52:55]
	v_mfma_f32_16x16x32_f16 v[48:51], v[140:143], v[198:201], v[48:51]
	v_mfma_f32_16x16x32_f16 v[36:39], v[4:7], v[206:209], v[36:39]
	v_mfma_f32_16x16x32_f16 v[32:35], v[140:143], v[206:209], v[32:35]
	v_mfma_f32_16x16x32_f16 v[0:3], v[4:7], v[214:217], v[0:3]
	v_mfma_f32_16x16x32_f16 v[4:7], v[136:139], v[210:213], v[16:19]
	v_mfma_f32_16x16x32_f16 v[4:7], v[140:143], v[214:217], v[4:7]
	s_setprio 0
	s_setprio 1
	v_mfma_f32_16x16x32_f16 v[16:19], v[144:147], v[176:179], v[60:63]
	v_mfma_f32_16x16x32_f16 v[60:63], v[148:151], v[180:183], v[16:19]
	v_mfma_f32_16x16x32_f16 v[16:19], v[152:155], v[176:179], v[56:59]
	v_mfma_f32_16x16x32_f16 v[56:59], v[156:159], v[180:183], v[16:19]
	v_mfma_f32_16x16x32_f16 v[16:19], v[144:147], v[184:187], v[44:47]
	v_mfma_f32_16x16x32_f16 v[44:47], v[148:151], v[198:201], v[16:19]
	v_mfma_f32_16x16x32_f16 v[16:19], v[152:155], v[184:187], v[40:43]
	v_mfma_f32_16x16x32_f16 v[40:43], v[156:159], v[198:201], v[16:19]
	v_mfma_f32_16x16x32_f16 v[16:19], v[144:147], v[202:205], v[28:31]
	v_mfma_f32_16x16x32_f16 v[28:31], v[148:151], v[206:209], v[16:19]
	v_mfma_f32_16x16x32_f16 v[16:19], v[152:155], v[202:205], v[24:27]
	v_mfma_f32_16x16x32_f16 v[12:15], v[144:147], v[210:213], v[12:15]
	s_barrier
; #define PG8_STAGE(bufoff, gbase, voff) do { _Pragma("unroll") for (int _i = 0; _i < 2; ++_i) \
;         __builtin_amdgcn_global_load_lds((const unsigned*)((const char*)(gbase) + (voff)[_i]), (PG8_LAS unsigned*)(lds + (bufoff) + ldsw + _i * 8192), 16, 0, 0); } while (0)
; #define PG8_LDA(dst, b, h) do { _Pragma("unroll") for (int m = 0; m < 4; ++m) _Pragma("unroll") for (int k = 0; k < 2; ++k) dst[m][k] = *(const PG8_LAS bf16x8*)(lds + PG8_SA(b, h) + aoff + m * 2048 + k * 1024); } while (0)
; #define PG8_LDB(dst, b, h) do { _Pragma("unroll") for (int n = 0; n < 2; ++n) _Pragma("unroll") for (int k = 0; k < 2; ++k) dst[n][k] = *(const PG8_LAS bf16x8*)(lds + PG8_SB(b, h) + boff + n * 2048 + k * 1024); } while (0)
; #define PG8_MMA(ai, bj, At, Bt) do { __builtin_amdgcn_s_setprio(1); _Pragma("unroll") for (int m = 0; m < 4; ++m) _Pragma("unroll") for (int n = 0; n < 2; ++n) _Pragma("unroll") for (int k = 0; k < 2; ++k) \
;         acc[ai][bj][m][n] = mma16<F16>(Bt[n][k], At[m][k], acc[ai][bj][m][n]); __builtin_amdgcn_s_setprio(0); } while (0)
; #define PG8_WAIT_V(n) asm volatile("s_waitcnt vmcnt(" #n ")" ::: "memory")
; #define PG8_WAIT_L(n) asm volatile("s_waitcnt lgkmcnt(" #n ")" ::: "memory")
; #define PG8_BAR __builtin_amdgcn_s_barrier()
; #define PG8_SCHED __builtin_amdgcn_sched_barrier(0)
; template <class Epi, class Sched, bool ALIGN_EPI = false, bool SP2 = false, bool F16 = false>
; __device__ __forceinline__ void gemm_phase(PG8_LAS unsigned char* lds, const Gemm g, const Sched& S, const Epi& E, const int wid_in) {
;     ...
;             PG8_WAIT_V(8); PG8_WAIT_L(0); PG8_BAR; PG8_MMA(1, 0, At, B0); PG8_MMA(1, 1, At, B1); PG8_BAR; PG8_SCHED;
;             PG8_LDB(B0, 1, 0); PG8_LDB(B1, 1, 1); PG8_SCHED; PG8_LDA(At, 1, 0); PG8_STAGE(PG8_SA(0, 1), a2 + hstep, voffA);
;             PG8_WAIT_V(8); PG8_WAIT_L(0); PG8_BAR; PG8_MMA(0, 0, At, B0); PG8_MMA(0, 1, At, B1); PG8_BAR; PG8_SCHED;
	v_mfma_f32_16x16x32_f16 v[8:11], v[152:155], v[210:213], v[8:11]
	v_mfma_f32_16x16x32_f16 v[24:27], v[156:159], v[206:209], v[16:19]
	v_mfma_f32_16x16x32_f16 v[12:15], v[148:151], v[214:217], v[12:15]
	v_mfma_f32_16x16x32_f16 v[8:11], v[156:159], v[214:217], v[8:11]
	s_setprio 0
	s_add_i32 s65, 0, 0x18000
	s_add_i32 s76, 0, 0x1c000
	v_add_u32_e32 v140, s65, v192
	v_add_u32_e32 v156, s76, v192
	ds_read_b128 v[16:19], v140
	ds_read_b128 v[20:23], v140 offset:1024
	ds_read_b128 v[136:139], v140 offset:2048
	ds_read_b128 v[140:143], v140 offset:3072
	ds_read_b128 v[144:147], v156
	ds_read_b128 v[148:151], v156 offset:1024
	ds_read_b128 v[152:155], v156 offset:2048
	ds_read_b128 v[156:159], v156 offset:3072
	s_add_u32 s50, s50, 0x40000
	s_addc_u32 s51, s51, 0
	s_mov_b32 m0, s90
	v_lshl_add_u64 v[224:225], s[50:51], 0, v[160:161]
	ds_read_b128 v[176:179], v195 offset:32768
	ds_read_b128 v[180:183], v195 offset:33792
	ds_read_b128 v[184:187], v195 offset:34816
	ds_read_b128 v[198:201], v195 offset:35840
	ds_read_b128 v[202:205], v195 offset:36864
	ds_read_b128 v[206:209], v195 offset:37888
	ds_read_b128 v[210:213], v195 offset:38912
	ds_read_b128 v[214:217], v195 offset:39936
	global_load_lds_dwordx4 v[224:225], off
	v_lshl_add_u64 v[224:225], s[50:51], 0, v[164:165]
	s_mov_b32 m0, s37
	s_nop 0
	global_load_lds_dwordx4 v[224:225], off
	s_waitcnt vmcnt(8)
	s_waitcnt lgkmcnt(0)
	s_barrier
	s_setprio 1
	s_waitcnt lgkmcnt(0)
	v_mfma_f32_16x16x32_f16 v[132:135], v[16:19], v[176:179], v[132:135]
	v_mfma_f32_16x16x32_f16 v[128:131], v[136:139], v[176:179], v[128:131]
	v_mfma_f32_16x16x32_f16 v[116:119], v[16:19], v[184:187], v[116:119]
	v_mfma_f32_16x16x32_f16 v[112:115], v[136:139], v[184:187], v[112:115]
	v_mfma_f32_16x16x32_f16 v[100:103], v[16:19], v[202:205], v[100:103]
	v_mfma_f32_16x16x32_f16 v[96:99], v[136:139], v[202:205], v[96:99]
	v_mfma_f32_16x16x32_f16 v[84:87], v[16:19], v[210:213], v[84:87]
	v_mfma_f32_16x16x32_f16 v[80:83], v[136:139], v[210:213], v[80:83]
	v_mfma_f32_16x16x32_f16 v[132:135], v[20:23], v[180:183], v[132:135]
	v_mfma_f32_16x16x32_f16 v[128:131], v[140:143], v[180:183], v[128:131]
	v_mfma_f32_16x16x32_f16 v[116:119], v[20:23], v[198:201], v[116:119]
	v_mfma_f32_16x16x32_f16 v[112:115], v[140:143], v[198:201], v[112:115]
	v_mfma_f32_16x16x32_f16 v[100:103], v[20:23], v[206:209], v[100:103]
	v_mfma_f32_16x16x32_f16 v[96:99], v[140:143], v[206:209], v[96:99]
	v_mfma_f32_16x16x32_f16 v[84:87], v[20:23], v[214:217], v[84:87]
	v_mfma_f32_16x16x32_f16 v[80:83], v[140:143], v[214:217], v[80:83]
	s_setprio 0
	s_setprio 1
	v_mfma_f32_16x16x32_f16 v[124:127], v[144:147], v[176:179], v[124:127]
	v_mfma_f32_16x16x32_f16 v[120:123], v[152:155], v[176:179], v[120:123]
	v_mfma_f32_16x16x32_f16 v[108:111], v[144:147], v[184:187], v[108:111]
	v_mfma_f32_16x16x32_f16 v[104:107], v[152:155], v[184:187], v[104:107]
	v_mfma_f32_16x16x32_f16 v[92:95], v[144:147], v[202:205], v[92:95]
	v_mfma_f32_16x16x32_f16 v[88:91], v[152:155], v[202:205], v[88:91]
	v_mfma_f32_16x16x32_f16 v[76:79], v[144:147], v[210:213], v[76:79]
	v_mfma_f32_16x16x32_f16 v[72:75], v[152:155], v[210:213], v[72:75]
	v_mfma_f32_16x16x32_f16 v[124:127], v[148:151], v[180:183], v[124:127]
	v_mfma_f32_16x16x32_f16 v[120:123], v[156:159], v[180:183], v[120:123]
	v_mfma_f32_16x16x32_f16 v[108:111], v[148:151], v[198:201], v[108:111]
	v_mfma_f32_16x16x32_f16 v[104:107], v[156:159], v[198:201], v[104:107]
	s_barrier
; #define PG8_STAGE(bufoff, gbase, voff) do { _Pragma("unroll") for (int _i = 0; _i < 2; ++_i) \
;         __builtin_amdgcn_global_load_lds((const unsigned*)((const char*)(gbase) + (voff)[_i]), (PG8_LAS unsigned*)(lds + (bufoff) + ldsw + _i * 8192), 16, 0, 0); } while (0)
; #define PG8_LDA(dst, b, h) do { _Pragma("unroll") for (int m = 0; m < 4; ++m) _Pragma("unroll") for (int k = 0; k < 2; ++k) dst[m][k] = *(const PG8_LAS bf16x8*)(lds + PG8_SA(b, h) + aoff + m * 2048 + k * 1024); } while (0)
; #define PG8_MMA(ai, bj, At, Bt) do { __builtin_amdgcn_s_setprio(1); _Pragma("unroll") for (int m = 0; m < 4; ++m) _Pragma("unroll") for (int n = 0; n < 2; ++n) _Pragma("unroll") for (int k = 0; k < 2; ++k) \
;         acc[ai][bj][m][n] = mma16<F16>(Bt[n][k], At[m][k], acc[ai][bj][m][n]); __builtin_amdgcn_s_setprio(0); } while (0)
; #define PG8_WAIT_V(n) asm volatile("s_waitcnt vmcnt(" #n ")" ::: "memory")
; #define PG8_WAIT_L(n) asm volatile("s_waitcnt lgkmcnt(" #n ")" ::: "memory")
; #define PG8_BAR __builtin_amdgcn_s_barrier()
; #define PG8_SCHED __builtin_amdgcn_sched_barrier(0)
; template <class Epi, class Sched, bool ALIGN_EPI = false, bool SP2 = false, bool F16 = false>
; __device__ __forceinline__ void gemm_phase(PG8_LAS unsigned char* lds, const Gemm g, const Sched& S, const Epi& E, const int wid_in) {
;     ...
;             PG8_WAIT_V(8); PG8_WAIT_L(0); PG8_BAR; PG8_MMA(0, 0, At, B0); PG8_MMA(0, 1, At, B1); PG8_BAR; PG8_SCHED;
;             PG8_LDA(At, 1, 1); PG8_STAGE(PG8_SB(1, 0), b3, voffB); PG8_STAGE(PG8_SB(1, 1), b3 + hstep, voffB); PG8_STAGE(PG8_SA(1, 0), a3, voffA);
;             PG8_WAIT_V(8); PG8_WAIT_L(0); PG8_BAR; PG8_MMA(1, 0, At, B0); PG8_MMA(1, 1, At, B1); PG8_BAR; PG8_SCHED;
	v_mfma_f32_16x16x32_f16 v[92:95], v[148:151], v[206:209], v[92:95]
	v_mfma_f32_16x16x32_f16 v[88:91], v[156:159], v[206:209], v[88:91]
	v_mfma_f32_16x16x32_f16 v[76:79], v[148:151], v[214:217], v[76:79]
	v_mfma_f32_16x16x32_f16 v[72:75], v[156:159], v[214:217], v[72:75]
	s_setprio 0
	s_add_i32 s50, s65, s68
	v_lshl_add_u64 v[188:189], v[188:189], 0, s[24:25]
	s_mov_b32 m0, s50
	ds_read_b128 v[176:179], v195 offset:49152
	ds_read_b128 v[180:183], v195 offset:50176
	ds_read_b128 v[184:187], v195 offset:51200
	ds_read_b128 v[198:201], v195 offset:52224
	ds_read_b128 v[202:205], v195 offset:53248
	ds_read_b128 v[206:209], v195 offset:54272
	ds_read_b128 v[210:213], v195 offset:55296
	ds_read_b128 v[214:217], v195 offset:56320
	global_load_lds_dwordx4 v[188:189], off
	s_add_i32 m0, s50, 0x2000
	s_add_u32 s48, s48, 0x40080
	v_lshl_add_u64 v[188:189], v[218:219], 0, s[24:25]
	s_addc_u32 s49, s49, 0
	s_add_i32 s50, s76, s68
	global_load_lds_dwordx4 v[188:189], off
	v_lshl_add_u64 v[188:189], s[48:49], 0, v[162:163]
	s_mov_b32 m0, s50
	s_nop 0
	global_load_lds_dwordx4 v[188:189], off
	v_lshl_add_u64 v[188:189], s[48:49], 0, v[166:167]
	s_add_i32 m0, s50, 0x2000
	s_nop 0
	global_load_lds_dwordx4 v[188:189], off
	v_lshl_add_u64 v[188:189], v[220:221], 0, s[24:25]
	s_mov_b32 m0, s75
	s_nop 0
	global_load_lds_dwordx4 v[188:189], off
	v_lshl_add_u64 v[188:189], v[222:223], 0, s[24:25]
	s_mov_b32 m0, s67
	s_nop 0
	global_load_lds_dwordx4 v[188:189], off
	s_waitcnt vmcnt(8)
	s_waitcnt lgkmcnt(0)
	s_barrier
	s_setprio 1
	s_waitcnt lgkmcnt(0)
	v_mfma_f32_16x16x32_f16 v[68:71], v[16:19], v[176:179], v[68:71]
	v_mfma_f32_16x16x32_f16 v[52:55], v[16:19], v[184:187], v[52:55]
	v_mfma_f32_16x16x32_f16 v[36:39], v[16:19], v[202:205], v[36:39]
	v_mfma_f32_16x16x32_f16 v[0:3], v[16:19], v[210:213], v[0:3]
	v_mfma_f32_16x16x32_f16 v[68:71], v[20:23], v[180:183], v[68:71]
	v_mfma_f32_16x16x32_f16 v[64:67], v[136:139], v[176:179], v[64:67]
	v_mfma_f32_16x16x32_f16 v[52:55], v[20:23], v[198:201], v[52:55]
	v_mfma_f32_16x16x32_f16 v[48:51], v[136:139], v[184:187], v[48:51]
	v_mfma_f32_16x16x32_f16 v[36:39], v[20:23], v[206:209], v[36:39]
	v_mfma_f32_16x16x32_f16 v[32:35], v[136:139], v[202:205], v[32:35]
	v_mfma_f32_16x16x32_f16 v[20:23], v[20:23], v[214:217], v[0:3]
	v_mfma_f32_16x16x32_f16 v[0:3], v[136:139], v[210:213], v[4:7]
	v_mfma_f32_16x16x32_f16 v[64:67], v[140:143], v[180:183], v[64:67]
	v_mfma_f32_16x16x32_f16 v[48:51], v[140:143], v[198:201], v[48:51]
	v_mfma_f32_16x16x32_f16 v[32:35], v[140:143], v[206:209], v[32:35]
	v_mfma_f32_16x16x32_f16 v[16:19], v[140:143], v[214:217], v[0:3]
	s_setprio 0
	s_setprio 1
	v_mfma_f32_16x16x32_f16 v[0:3], v[144:147], v[176:179], v[60:63]
	v_mfma_f32_16x16x32_f16 v[60:63], v[148:151], v[180:183], v[0:3]
	v_mfma_f32_16x16x32_f16 v[0:3], v[152:155], v[176:179], v[56:59]
	v_mfma_f32_16x16x32_f16 v[56:59], v[156:159], v[180:183], v[0:3]
	v_mfma_f32_16x16x32_f16 v[0:3], v[144:147], v[184:187], v[44:47]
	v_mfma_f32_16x16x32_f16 v[44:47], v[148:151], v[198:201], v[0:3]
	v_mfma_f32_16x16x32_f16 v[0:3], v[152:155], v[184:187], v[40:43]
	v_mfma_f32_16x16x32_f16 v[40:43], v[156:159], v[198:201], v[0:3]
	v_mfma_f32_16x16x32_f16 v[0:3], v[144:147], v[202:205], v[28:31]
	v_mfma_f32_16x16x32_f16 v[28:31], v[148:151], v[206:209], v[0:3]
	v_mfma_f32_16x16x32_f16 v[0:3], v[152:155], v[202:205], v[24:27]
	v_mfma_f32_16x16x32_f16 v[24:27], v[156:159], v[206:209], v[0:3]
	s_barrier
	v_mfma_f32_16x16x32_f16 v[0:3], v[144:147], v[210:213], v[12:15]
	v_mfma_f32_16x16x32_f16 v[12:15], v[148:151], v[214:217], v[0:3]
	v_mfma_f32_16x16x32_f16 v[0:3], v[152:155], v[210:213], v[8:11]
	v_mfma_f32_16x16x32_f16 v[8:11], v[156:159], v[214:217], v[0:3]
	s_setprio 0
	s_add_i32 s64, s64, 2
	s_add_u32 s46, s46, 0x100
	s_addc_u32 s47, s47, 0
	s_add_u32 s45, s45, 0x100
	s_addc_u32 s63, s63, 0
	s_cmp_gt_u32 s64, 13
	s_cbranch_scc0 .LBB0_1909
	s_and_b64 vcc, exec, s[16:17]
	s_cbranch_vccz .LBB0_1912
	s_barrier

; #define PG8_STAGE(bufoff, gbase, voff) do { _Pragma("unroll") for (int _i = 0; _i < 2; ++_i) \
;         __builtin_amdgcn_global_load_lds((const unsigned*)((const char*)(gbase) + (voff)[_i]), (PG8_LAS unsigned*)(lds + (bufoff) + ldsw + _i * 8192), 16, 0, 0); } while (0)
; #define PG8_LDA(dst, b, h) do { _Pragma("unroll") for (int m = 0; m < 4; ++m) _Pragma("unroll") for (int k = 0; k < 2; ++k) dst[m][k] = *(const PG8_LAS bf16x8*)(lds + PG8_SA(b, h) + aoff + m * 2048 + k * 1024); } while (0)
; #define PG8_LDB(dst, b, h) do { _Pragma("unroll") for (int n = 0; n < 2; ++n) _Pragma("unroll") for (int k = 0; k < 2; ++k) dst[n][k] = *(const PG8_LAS bf16x8*)(lds + PG8_SB(b, h) + boff + n * 2048 + k * 1024); } while (0)
; #define PG8_MMA(ai, bj, At, Bt) do { __builtin_amdgcn_s_setprio(1); _Pragma("unroll") for (int m = 0; m < 4; ++m) _Pragma("unroll") for (int n = 0; n < 2; ++n) _Pragma("unroll") for (int k = 0; k < 2; ++k) \
;         acc[ai][bj][m][n] = mma16<F16>(Bt[n][k], At[m][k], acc[ai][bj][m][n]); __builtin_amdgcn_s_setprio(0); } while (0)
; #define PG8_BAR __builtin_amdgcn_s_barrier()
; template <class Epi, class Sched, bool ALIGN_EPI = false, bool SP2 = false, bool F16 = false>
; __device__ __forceinline__ void gemm_phase(PG8_LAS unsigned char* lds, const Gemm g, const Sched& S, const Epi& E, const int wid_in) {
;     ...
;         const bool has_next = S.next(ui + 1, nxt);
;         const char* nA = has_next ? (const char*)g.A + (size_t)nxt.pm * tstep : cA; const char* nB = has_next ? (const char*)g.Bt + (size_t)nxt.pn * tstep : cB;
;         for (int t = 0; t < nt; t += 2) {
;             const bool last = (t == nt - 2);
;             const char* a1 = cA + (size_t)(t + 1) * kstep;
;             const char* a2 = last ? nA : cA + (size_t)(t + 2) * kstep; const char* b2 = last ? nB : cB + (size_t)(t + 2) * kstep;
;             const char* a3 = a2 + kstep; const char* b3 = b2 + kstep;
;             if (last && has_next) S.a_ready(nxt);
;             if constexpr (SP2) {
;             PG8_LDB(B0, 0, 0); PG8_LDB(B1, 0, 1); PG8_SCHED; PG8_LDA(At, 0, 0); PG8_STAGE(PG8_SA(1, 1), a1 + hstep, voffA);
;             PG8_WAIT_V(8); PG8_WAIT_L(0); PG8_BAR; PG8_MMA(0, 0, At, B0); PG8_MMA(0, 1, At, B1); PG8_BAR; PG8_SCHED;
;             PG8_LDA(At, 0, 1); PG8_STAGE(PG8_SB(0, 0), b2, voffB); PG8_STAGE(PG8_SB(0, 1), b2 + hstep, voffB); PG8_STAGE(PG8_SA(0, 0), a2, voffA);
.LBB0_1944:
	s_mov_b64 s[48:49], s[10:11]
	s_add_i32 s10, s36, s19
	s_mov_b64 s[46:47], s[12:13]
	s_mov_b32 s12, s58
	s_mov_b32 s13, s57
	s_and_b32 s57, s10, 3
	s_ashr_i32 s58, s10, 2
	s_and_b64 s[10:11], s[30:31], exec
	s_cselect_b32 s12, s58, s12
	ds_read_b128 v[0:3], v134
	ds_read_b128 v[4:7], v134 offset:1024
	ds_read_b128 v[8:11], v134 offset:2048
	ds_read_b128 v[12:15], v134 offset:3072
	ds_read_b128 v[16:19], v135
	ds_read_b128 v[20:23], v135 offset:1024
	ds_read_b128 v[24:27], v135 offset:2048
	ds_read_b128 v[28:31], v135 offset:3072
	s_cselect_b32 s10, s57, s13
	s_ashr_i32 s13, s12, 31
	s_lshl_b64 s[12:13], s[12:13], 17
	s_add_u32 s12, s21, s12
	s_addc_u32 s13, s40, s13
	s_and_b64 s[36:37], s[30:31], exec
	s_cselect_b32 s45, s13, s47
	s_cselect_b32 s44, s12, s46
	s_ashr_i32 s11, s10, 31
	s_lshl_b64 s[10:11], s[10:11], 17
	s_add_u32 s10, s41, s10
	s_addc_u32 s11, s42, s11
	s_and_b64 s[36:37], s[30:31], exec
	s_cselect_b32 s37, s11, s49
	s_cselect_b32 s36, s10, s48
	s_add_u32 s60, s46, 0x10080
	s_addc_u32 s61, s47, 0
	s_mov_b32 m0, s91
	v_lshl_add_u64 v[64:65], s[60:61], 0, v[130:131]
	ds_read_b128 v[32:35], v136
	ds_read_b128 v[36:39], v136 offset:1024
	ds_read_b128 v[40:43], v136 offset:2048
	ds_read_b128 v[44:47], v136 offset:3072
	ds_read_b128 v[48:51], v136 offset:4096
	ds_read_b128 v[52:55], v136 offset:5120
	ds_read_b128 v[56:59], v136 offset:6144
	ds_read_b128 v[60:63], v136 offset:7168
	global_load_lds_dwordx4 v[64:65], off
	v_lshl_add_u64 v[64:65], s[60:61], 0, v[128:129]
	s_mov_b32 m0, s14
	s_nop 0
	global_load_lds_dwordx4 v[64:65], off
	s_waitcnt vmcnt(8)
	s_waitcnt lgkmcnt(0)
	s_barrier
	s_setprio 1
	s_waitcnt lgkmcnt(0)
	v_mfma_f32_16x16x32_bf16 v[64:67], v[0:3], v[32:35], 0
	v_mfma_f32_16x16x32_bf16 v[68:71], v[8:11], v[32:35], 0
	v_mfma_f32_16x16x32_bf16 v[72:75], v[0:3], v[40:43], 0
	v_mfma_f32_16x16x32_bf16 v[76:79], v[8:11], v[40:43], 0
	v_mfma_f32_16x16x32_bf16 v[80:83], v[0:3], v[48:51], 0
	v_mfma_f32_16x16x32_bf16 v[84:87], v[8:11], v[48:51], 0
	v_mfma_f32_16x16x32_bf16 v[88:91], v[0:3], v[56:59], 0
	v_mfma_f32_16x16x32_bf16 v[92:95], v[8:11], v[56:59], 0
	v_mfma_f32_16x16x32_bf16 v[64:67], v[4:7], v[36:39], v[64:67]
	v_mfma_f32_16x16x32_bf16 v[68:71], v[12:15], v[36:39], v[68:71]
	v_mfma_f32_16x16x32_bf16 v[72:75], v[4:7], v[44:47], v[72:75]
	v_mfma_f32_16x16x32_bf16 v[76:79], v[12:15], v[44:47], v[76:79]
	v_mfma_f32_16x16x32_bf16 v[80:83], v[4:7], v[52:55], v[80:83]
	v_mfma_f32_16x16x32_bf16 v[84:87], v[12:15], v[52:55], v[84:87]
	v_mfma_f32_16x16x32_bf16 v[88:91], v[4:7], v[60:63], v[88:91]
	v_mfma_f32_16x16x32_bf16 v[92:95], v[12:15], v[60:63], v[92:95]
	s_setprio 0
	s_setprio 1
	v_mfma_f32_16x16x32_bf16 v[96:99], v[16:19], v[32:35], 0
	v_mfma_f32_16x16x32_bf16 v[32:35], v[24:27], v[32:35], 0
	v_mfma_f32_16x16x32_bf16 v[96:99], v[20:23], v[36:39], v[96:99]
	v_mfma_f32_16x16x32_bf16 v[32:35], v[28:31], v[36:39], v[32:35]
	v_mfma_f32_16x16x32_bf16 v[36:39], v[16:19], v[40:43], 0
	v_mfma_f32_16x16x32_bf16 v[40:43], v[24:27], v[40:43], 0
	v_mfma_f32_16x16x32_bf16 v[36:39], v[20:23], v[44:47], v[36:39]
	v_mfma_f32_16x16x32_bf16 v[40:43], v[28:31], v[44:47], v[40:43]
	v_mfma_f32_16x16x32_bf16 v[44:47], v[16:19], v[48:51], 0
	v_mfma_f32_16x16x32_bf16 v[48:51], v[24:27], v[48:51], 0
	v_mfma_f32_16x16x32_bf16 v[44:47], v[20:23], v[52:55], v[44:47]
	v_mfma_f32_16x16x32_bf16 v[48:51], v[28:31], v[52:55], v[48:51]
	s_barrier
	v_mfma_f32_16x16x32_bf16 v[52:55], v[16:19], v[56:59], 0
	v_mfma_f32_16x16x32_bf16 v[56:59], v[24:27], v[56:59], 0
	v_mfma_f32_16x16x32_bf16 v[52:55], v[20:23], v[60:63], v[52:55]
	v_mfma_f32_16x16x32_bf16 v[56:59], v[28:31], v[60:63], v[56:59]
	s_setprio 0
	v_lshl_add_u64 v[204:205], s[48:49], 0, v[130:131]
	s_mov_b32 m0, s15
	v_lshl_add_u64 v[140:141], v[204:205], 0, s[26:27]
	v_lshl_add_u64 v[206:207], s[48:49], 0, v[128:129]
	s_add_u32 s60, s48, 0x10100
	ds_read_b128 v[60:63], v136 offset:16384
	ds_read_b128 v[100:103], v136 offset:17408
	ds_read_b128 v[104:107], v136 offset:18432
	ds_read_b128 v[108:111], v136 offset:19456
	ds_read_b128 v[112:115], v136 offset:20480
	ds_read_b128 v[116:119], v136 offset:21504
	ds_read_b128 v[120:123], v136 offset:22528
	ds_read_b128 v[124:127], v136 offset:23552
	global_load_lds_dwordx4 v[140:141], off
	v_lshl_add_u64 v[140:141], v[206:207], 0, s[26:27]
	s_mov_b32 m0, s50
	s_addc_u32 s61, s49, 0
	global_load_lds_dwordx4 v[140:141], off
	v_lshl_add_u64 v[140:141], s[60:61], 0, v[130:131]
	s_mov_b32 m0, s51
	v_lshl_add_u64 v[208:209], s[46:47], 0, v[130:131]
	global_load_lds_dwordx4 v[140:141], off
	v_lshl_add_u64 v[140:141], s[60:61], 0, v[128:129]
	s_mov_b32 m0, s52
	v_lshl_add_u64 v[210:211], s[46:47], 0, v[128:129]
	global_load_lds_dwordx4 v[140:141], off
	v_lshl_add_u64 v[140:141], v[208:209], 0, s[26:27]
	s_mov_b32 m0, s74
	s_nop 0
	global_load_lds_dwordx4 v[140:141], off
	v_lshl_add_u64 v[140:141], v[210:211], 0, s[26:27]
	s_mov_b32 m0, s66
	s_nop 0
	global_load_lds_dwordx4 v[140:141], off
	s_waitcnt vmcnt(8)
	s_waitcnt lgkmcnt(0)
	s_barrier
; #define PG8_STAGE(bufoff, gbase, voff) do { _Pragma("unroll") for (int _i = 0; _i < 2; ++_i) \
;         __builtin_amdgcn_global_load_lds((const unsigned*)((const char*)(gbase) + (voff)[_i]), (PG8_LAS unsigned*)(lds + (bufoff) + ldsw + _i * 8192), 16, 0, 0); } while (0)
; #define PG8_LDA(dst, b, h) do { _Pragma("unroll") for (int m = 0; m < 4; ++m) _Pragma("unroll") for (int k = 0; k < 2; ++k) dst[m][k] = *(const PG8_LAS bf16x8*)(lds + PG8_SA(b, h) + aoff + m * 2048 + k * 1024); } while (0)
; #define PG8_LDB(dst, b, h) do { _Pragma("unroll") for (int n = 0; n < 2; ++n) _Pragma("unroll") for (int k = 0; k < 2; ++k) dst[n][k] = *(const PG8_LAS bf16x8*)(lds + PG8_SB(b, h) + boff + n * 2048 + k * 1024); } while (0)
; #define PG8_MMA(ai, bj, At, Bt) do { __builtin_amdgcn_s_setprio(1); _Pragma("unroll") for (int m = 0; m < 4; ++m) _Pragma("unroll") for (int n = 0; n < 2; ++n) _Pragma("unroll") for (int k = 0; k < 2; ++k) \
;         acc[ai][bj][m][n] = mma16<F16>(Bt[n][k], At[m][k], acc[ai][bj][m][n]); __builtin_amdgcn_s_setprio(0); } while (0)
; #define PG8_WAIT_V(n) asm volatile("s_waitcnt vmcnt(" #n ")" ::: "memory")
; #define PG8_WAIT_L(n) asm volatile("s_waitcnt lgkmcnt(" #n ")" ::: "memory")
; #define PG8_BAR __builtin_amdgcn_s_barrier()
; #define PG8_SCHED __builtin_amdgcn_sched_barrier(0)
; template <class Epi, class Sched, bool ALIGN_EPI = false, bool SP2 = false, bool F16 = false>
; __device__ __forceinline__ void gemm_phase(PG8_LAS unsigned char* lds, const Gemm g, const Sched& S, const Epi& E, const int wid_in) {
;     ...
;             PG8_WAIT_V(8); PG8_WAIT_L(0); PG8_BAR; PG8_MMA(1, 0, At, B0); PG8_MMA(1, 1, At, B1); PG8_BAR; PG8_SCHED;
;             PG8_LDB(B0, 1, 0); PG8_LDB(B1, 1, 1); PG8_SCHED; PG8_LDA(At, 1, 0); PG8_STAGE(PG8_SA(0, 1), a2 + hstep, voffA);
;             PG8_WAIT_V(8); PG8_WAIT_L(0); PG8_BAR; PG8_MMA(0, 0, At, B0); PG8_MMA(0, 1, At, B1); PG8_BAR; PG8_SCHED;
	s_setprio 1
	s_waitcnt lgkmcnt(0)
	v_mfma_f32_16x16x32_bf16 v[140:143], v[0:3], v[60:63], 0
	v_mfma_f32_16x16x32_bf16 v[148:151], v[0:3], v[104:107], 0
	v_mfma_f32_16x16x32_bf16 v[156:159], v[0:3], v[112:115], 0
	v_mfma_f32_16x16x32_bf16 v[0:3], v[0:3], v[120:123], 0
	v_mfma_f32_16x16x32_bf16 v[140:143], v[4:7], v[100:103], v[140:143]
	v_mfma_f32_16x16x32_bf16 v[148:151], v[4:7], v[108:111], v[148:151]
	v_mfma_f32_16x16x32_bf16 v[156:159], v[4:7], v[116:119], v[156:159]
	v_mfma_f32_16x16x32_bf16 v[0:3], v[4:7], v[124:127], v[0:3]
	v_mfma_f32_16x16x32_bf16 v[4:7], v[8:11], v[120:123], 0
	v_mfma_f32_16x16x32_bf16 v[144:147], v[8:11], v[60:63], 0
	v_mfma_f32_16x16x32_bf16 v[152:155], v[8:11], v[104:107], 0
	v_mfma_f32_16x16x32_bf16 v[160:163], v[8:11], v[112:115], 0
	v_mfma_f32_16x16x32_bf16 v[4:7], v[12:15], v[124:127], v[4:7]
	v_mfma_f32_16x16x32_bf16 v[144:147], v[12:15], v[100:103], v[144:147]
	v_mfma_f32_16x16x32_bf16 v[152:155], v[12:15], v[108:111], v[152:155]
	v_mfma_f32_16x16x32_bf16 v[160:163], v[12:15], v[116:119], v[160:163]
	s_setprio 0
	s_setprio 1
	v_mfma_f32_16x16x32_bf16 v[8:11], v[16:19], v[60:63], 0
	v_mfma_f32_16x16x32_bf16 v[12:15], v[24:27], v[60:63], 0
	v_mfma_f32_16x16x32_bf16 v[8:11], v[20:23], v[100:103], v[8:11]
	v_mfma_f32_16x16x32_bf16 v[12:15], v[28:31], v[100:103], v[12:15]
	v_mfma_f32_16x16x32_bf16 v[60:63], v[16:19], v[104:107], 0
	v_mfma_f32_16x16x32_bf16 v[100:103], v[24:27], v[104:107], 0
	v_mfma_f32_16x16x32_bf16 v[104:107], v[16:19], v[112:115], 0
	v_mfma_f32_16x16x32_bf16 v[16:19], v[16:19], v[120:123], 0
	v_mfma_f32_16x16x32_bf16 v[60:63], v[20:23], v[108:111], v[60:63]
	v_mfma_f32_16x16x32_bf16 v[100:103], v[28:31], v[108:111], v[100:103]
	v_mfma_f32_16x16x32_bf16 v[104:107], v[20:23], v[116:119], v[104:107]
	v_mfma_f32_16x16x32_bf16 v[108:111], v[24:27], v[112:115], 0
	s_barrier
	v_mfma_f32_16x16x32_bf16 v[16:19], v[20:23], v[124:127], v[16:19]
	v_mfma_f32_16x16x32_bf16 v[20:23], v[24:27], v[120:123], 0
	v_mfma_f32_16x16x32_bf16 v[108:111], v[28:31], v[116:119], v[108:111]
	v_mfma_f32_16x16x32_bf16 v[20:23], v[28:31], v[124:127], v[20:23]
	s_setprio 0
	ds_read_b128 v[24:27], v137
	ds_read_b128 v[28:31], v137 offset:1024
	ds_read_b128 v[112:115], v137 offset:2048
	ds_read_b128 v[116:119], v137 offset:3072
	ds_read_b128 v[120:123], v138
	ds_read_b128 v[124:127], v138 offset:1024
	ds_read_b128 v[164:167], v138 offset:2048
	ds_read_b128 v[168:171], v138 offset:3072
	s_add_u32 s60, s46, 0x10100
	s_addc_u32 s61, s47, 0
	s_mov_b32 m0, s90
	v_lshl_add_u64 v[212:213], s[60:61], 0, v[130:131]
	ds_read_b128 v[172:175], v136 offset:32768
	ds_read_b128 v[176:179], v136 offset:33792
	ds_read_b128 v[180:183], v136 offset:34816
	ds_read_b128 v[184:187], v136 offset:35840
	ds_read_b128 v[188:191], v136 offset:36864
	ds_read_b128 v[192:195], v136 offset:37888
	ds_read_b128 v[196:199], v136 offset:38912
	ds_read_b128 v[200:203], v136 offset:39936
	global_load_lds_dwordx4 v[212:213], off
	v_lshl_add_u64 v[212:213], s[60:61], 0, v[128:129]
	s_mov_b32 m0, s43
	s_nop 0
	global_load_lds_dwordx4 v[212:213], off
	s_waitcnt vmcnt(8)
	s_waitcnt lgkmcnt(0)
	s_barrier
	s_setprio 1
	s_waitcnt lgkmcnt(0)
	v_mfma_f32_16x16x32_bf16 v[64:67], v[24:27], v[172:175], v[64:67]
	v_mfma_f32_16x16x32_bf16 v[68:71], v[112:115], v[172:175], v[68:71]
	v_mfma_f32_16x16x32_bf16 v[72:75], v[24:27], v[180:183], v[72:75]
	v_mfma_f32_16x16x32_bf16 v[76:79], v[112:115], v[180:183], v[76:79]
	v_mfma_f32_16x16x32_bf16 v[80:83], v[24:27], v[188:191], v[80:83]
	v_mfma_f32_16x16x32_bf16 v[84:87], v[112:115], v[188:191], v[84:87]
	v_mfma_f32_16x16x32_bf16 v[88:91], v[24:27], v[196:199], v[88:91]
	v_mfma_f32_16x16x32_bf16 v[92:95], v[112:115], v[196:199], v[92:95]
	v_mfma_f32_16x16x32_bf16 v[64:67], v[28:31], v[176:179], v[64:67]
	v_mfma_f32_16x16x32_bf16 v[68:71], v[116:119], v[176:179], v[68:71]
	v_mfma_f32_16x16x32_bf16 v[72:75], v[28:31], v[184:187], v[72:75]
	v_mfma_f32_16x16x32_bf16 v[76:79], v[116:119], v[184:187], v[76:79]
	v_mfma_f32_16x16x32_bf16 v[80:83], v[28:31], v[192:195], v[80:83]
	v_mfma_f32_16x16x32_bf16 v[84:87], v[116:119], v[192:195], v[84:87]
	v_mfma_f32_16x16x32_bf16 v[88:91], v[28:31], v[200:203], v[88:91]
	v_mfma_f32_16x16x32_bf16 v[92:95], v[116:119], v[200:203], v[92:95]
	s_setprio 0
	s_setprio 1
	v_mfma_f32_16x16x32_bf16 v[96:99], v[120:123], v[172:175], v[96:99]
	v_mfma_f32_16x16x32_bf16 v[32:35], v[164:167], v[172:175], v[32:35]
	v_mfma_f32_16x16x32_bf16 v[36:39], v[120:123], v[180:183], v[36:39]
	v_mfma_f32_16x16x32_bf16 v[40:43], v[164:167], v[180:183], v[40:43]
	v_mfma_f32_16x16x32_bf16 v[44:47], v[120:123], v[188:191], v[44:47]
	v_mfma_f32_16x16x32_bf16 v[48:51], v[164:167], v[188:191], v[48:51]
	v_mfma_f32_16x16x32_bf16 v[52:55], v[120:123], v[196:199], v[52:55]
	v_mfma_f32_16x16x32_bf16 v[56:59], v[164:167], v[196:199], v[56:59]
	v_mfma_f32_16x16x32_bf16 v[96:99], v[124:127], v[176:179], v[96:99]
	v_mfma_f32_16x16x32_bf16 v[32:35], v[168:171], v[176:179], v[32:35]
	v_mfma_f32_16x16x32_bf16 v[36:39], v[124:127], v[184:187], v[36:39]
	v_mfma_f32_16x16x32_bf16 v[40:43], v[168:171], v[184:187], v[40:43]
	s_barrier
; #define PG8_STAGE(bufoff, gbase, voff) do { _Pragma("unroll") for (int _i = 0; _i < 2; ++_i) \
;         __builtin_amdgcn_global_load_lds((const unsigned*)((const char*)(gbase) + (voff)[_i]), (PG8_LAS unsigned*)(lds + (bufoff) + ldsw + _i * 8192), 16, 0, 0); } while (0)
; #define PG8_LDA(dst, b, h) do { _Pragma("unroll") for (int m = 0; m < 4; ++m) _Pragma("unroll") for (int k = 0; k < 2; ++k) dst[m][k] = *(const PG8_LAS bf16x8*)(lds + PG8_SA(b, h) + aoff + m * 2048 + k * 1024); } while (0)
; #define PG8_LDB(dst, b, h) do { _Pragma("unroll") for (int n = 0; n < 2; ++n) _Pragma("unroll") for (int k = 0; k < 2; ++k) dst[n][k] = *(const PG8_LAS bf16x8*)(lds + PG8_SB(b, h) + boff + n * 2048 + k * 1024); } while (0)
; #define PG8_MMA(ai, bj, At, Bt) do { __builtin_amdgcn_s_setprio(1); _Pragma("unroll") for (int m = 0; m < 4; ++m) _Pragma("unroll") for (int n = 0; n < 2; ++n) _Pragma("unroll") for (int k = 0; k < 2; ++k) \
;         acc[ai][bj][m][n] = mma16<F16>(Bt[n][k], At[m][k], acc[ai][bj][m][n]); __builtin_amdgcn_s_setprio(0); } while (0)
; #define PG8_WAIT_V(n) asm volatile("s_waitcnt vmcnt(" #n ")" ::: "memory")
; template <class Epi, class Sched, bool ALIGN_EPI = false, bool SP2 = false, bool F16 = false>
; __device__ __forceinline__ void gemm_phase(PG8_LAS unsigned char* lds, const Gemm g, const Sched& S, const Epi& E, const int wid_in) {
;     ...
;             PG8_LDB(B0, 0, 0); PG8_LDB(B1, 0, 1); PG8_SCHED; PG8_LDA(At, 0, 0); PG8_STAGE(PG8_SA(1, 1), a1 + hstep, voffA);
;             PG8_WAIT_V(8); PG8_WAIT_L(0); PG8_BAR; PG8_MMA(0, 0, At, B0); PG8_MMA(0, 1, At, B1); PG8_BAR; PG8_SCHED;
;             PG8_LDA(At, 0, 1); PG8_STAGE(PG8_SB(0, 0), b2, voffB); PG8_STAGE(PG8_SB(0, 1), b2 + hstep, voffB); PG8_STAGE(PG8_SA(0, 0), a2, voffA);
;             PG8_WAIT_V(8); PG8_WAIT_L(0); PG8_BAR; PG8_MMA(1, 0, At, B0); PG8_MMA(1, 1, At, B1); PG8_BAR; PG8_SCHED;
;             PG8_LDB(B0, 1, 0); PG8_LDB(B1, 1, 1); PG8_SCHED; PG8_LDA(At, 1, 0); PG8_STAGE(PG8_SA(0, 1), a2 + hstep, voffA);
;             PG8_WAIT_V(8); PG8_WAIT_L(0); PG8_BAR; PG8_MMA(0, 0, At, B0); PG8_MMA(0, 1, At, B1); PG8_BAR; PG8_SCHED;
;             PG8_LDA(At, 1, 1); PG8_STAGE(PG8_SB(1, 0), b3, voffB); PG8_STAGE(PG8_SB(1, 1), b3 + hstep, voffB); PG8_STAGE(PG8_SA(1, 0), a3, voffA);
;             PG8_WAIT_V(8); PG8_WAIT_L(0); PG8_BAR; PG8_MMA(1, 0, At, B0); PG8_MMA(1, 1, At, B1); PG8_BAR; PG8_SCHED;
	v_mfma_f32_16x16x32_bf16 v[44:47], v[124:127], v[192:195], v[44:47]
	v_mfma_f32_16x16x32_bf16 v[48:51], v[168:171], v[192:195], v[48:51]
	v_mfma_f32_16x16x32_bf16 v[52:55], v[124:127], v[200:203], v[52:55]
	v_mfma_f32_16x16x32_bf16 v[56:59], v[168:171], v[200:203], v[56:59]
	s_setprio 0
	s_mov_b32 m0, s53
	v_lshl_add_u64 v[204:205], v[204:205], 0, s[28:29]
	s_add_u32 s48, s48, 0x10180
	ds_read_b128 v[172:175], v136 offset:49152
	ds_read_b128 v[176:179], v136 offset:50176
	ds_read_b128 v[180:183], v136 offset:51200
	ds_read_b128 v[184:187], v136 offset:52224
	ds_read_b128 v[188:191], v136 offset:53248
	ds_read_b128 v[192:195], v136 offset:54272
	ds_read_b128 v[196:199], v136 offset:55296
	ds_read_b128 v[200:203], v136 offset:56320
	global_load_lds_dwordx4 v[204:205], off
	v_lshl_add_u64 v[204:205], v[206:207], 0, s[28:29]
	s_mov_b32 m0, s54
	s_addc_u32 s49, s49, 0
	global_load_lds_dwordx4 v[204:205], off
	v_lshl_add_u64 v[204:205], s[48:49], 0, v[130:131]
	s_mov_b32 m0, s55
	s_nop 0
	global_load_lds_dwordx4 v[204:205], off
	v_lshl_add_u64 v[204:205], s[48:49], 0, v[128:129]
	s_mov_b32 m0, s56
	s_nop 0
	global_load_lds_dwordx4 v[204:205], off
	v_lshl_add_u64 v[204:205], v[208:209], 0, s[28:29]
	s_mov_b32 m0, s75
	s_nop 0
	global_load_lds_dwordx4 v[204:205], off
	v_lshl_add_u64 v[204:205], v[210:211], 0, s[28:29]
	s_mov_b32 m0, s67
	s_nop 0
	global_load_lds_dwordx4 v[204:205], off
	s_waitcnt vmcnt(8)
	s_waitcnt lgkmcnt(0)
	s_barrier
	s_setprio 1
	s_waitcnt lgkmcnt(0)
	v_mfma_f32_16x16x32_bf16 v[0:3], v[24:27], v[196:199], v[0:3]
	v_mfma_f32_16x16x32_bf16 v[4:7], v[112:115], v[196:199], v[4:7]
	v_mfma_f32_16x16x32_bf16 v[140:143], v[24:27], v[172:175], v[140:143]
	v_mfma_f32_16x16x32_bf16 v[144:147], v[112:115], v[172:175], v[144:147]
	v_mfma_f32_16x16x32_bf16 v[148:151], v[24:27], v[180:183], v[148:151]
	v_mfma_f32_16x16x32_bf16 v[152:155], v[112:115], v[180:183], v[152:155]
	v_mfma_f32_16x16x32_bf16 v[156:159], v[24:27], v[188:191], v[156:159]
	v_mfma_f32_16x16x32_bf16 v[160:163], v[112:115], v[188:191], v[160:163]
	v_mfma_f32_16x16x32_bf16 v[0:3], v[28:31], v[200:203], v[0:3]
	v_mfma_f32_16x16x32_bf16 v[4:7], v[116:119], v[200:203], v[4:7]
	v_mfma_f32_16x16x32_bf16 v[140:143], v[28:31], v[176:179], v[140:143]
	v_mfma_f32_16x16x32_bf16 v[144:147], v[116:119], v[176:179], v[144:147]
	v_mfma_f32_16x16x32_bf16 v[148:151], v[28:31], v[184:187], v[148:151]
	v_mfma_f32_16x16x32_bf16 v[152:155], v[116:119], v[184:187], v[152:155]
	v_mfma_f32_16x16x32_bf16 v[156:159], v[28:31], v[192:195], v[156:159]
	v_mfma_f32_16x16x32_bf16 v[160:163], v[116:119], v[192:195], v[160:163]
	s_setprio 0
	s_setprio 1
	v_mfma_f32_16x16x32_bf16 v[8:11], v[120:123], v[172:175], v[8:11]
	v_mfma_f32_16x16x32_bf16 v[12:15], v[164:167], v[172:175], v[12:15]
	v_mfma_f32_16x16x32_bf16 v[24:27], v[120:123], v[180:183], v[60:63]
	v_mfma_f32_16x16x32_bf16 v[28:31], v[164:167], v[180:183], v[100:103]
	v_mfma_f32_16x16x32_bf16 v[60:63], v[120:123], v[188:191], v[104:107]
	v_mfma_f32_16x16x32_bf16 v[100:103], v[164:167], v[188:191], v[108:111]
	v_mfma_f32_16x16x32_bf16 v[16:19], v[120:123], v[196:199], v[16:19]
	v_mfma_f32_16x16x32_bf16 v[20:23], v[164:167], v[196:199], v[20:23]
	v_mfma_f32_16x16x32_bf16 v[8:11], v[124:127], v[176:179], v[8:11]
	v_mfma_f32_16x16x32_bf16 v[12:15], v[168:171], v[176:179], v[12:15]
	v_mfma_f32_16x16x32_bf16 v[24:27], v[124:127], v[184:187], v[24:27]
	v_mfma_f32_16x16x32_bf16 v[28:31], v[168:171], v[184:187], v[28:31]
	s_barrier
	v_mfma_f32_16x16x32_bf16 v[60:63], v[124:127], v[192:195], v[60:63]
	v_mfma_f32_16x16x32_bf16 v[100:103], v[168:171], v[192:195], v[100:103]
	v_mfma_f32_16x16x32_bf16 v[16:19], v[124:127], v[200:203], v[16:19]
	v_mfma_f32_16x16x32_bf16 v[20:23], v[168:171], v[200:203], v[20:23]
	s_setprio 0
	ds_read_b128 v[104:107], v134
	ds_read_b128 v[108:111], v134 offset:1024
	ds_read_b128 v[112:115], v134 offset:2048
	ds_read_b128 v[116:119], v134 offset:3072
	ds_read_b128 v[120:123], v135
	ds_read_b128 v[124:127], v135 offset:1024
	ds_read_b128 v[164:167], v135 offset:2048
	ds_read_b128 v[168:171], v135 offset:3072
	s_add_u32 s46, s46, 0x10180
	s_addc_u32 s47, s47, 0
	s_mov_b32 m0, s91
	v_lshl_add_u64 v[204:205], s[46:47], 0, v[130:131]
	ds_read_b128 v[172:175], v136
	ds_read_b128 v[176:179], v136 offset:1024
	ds_read_b128 v[180:183], v136 offset:2048
	ds_read_b128 v[184:187], v136 offset:3072
	ds_read_b128 v[188:191], v136 offset:4096
	ds_read_b128 v[192:195], v136 offset:5120
	ds_read_b128 v[196:199], v136 offset:6144
	ds_read_b128 v[200:203], v136 offset:7168
	global_load_lds_dwordx4 v[204:205], off
	v_lshl_add_u64 v[204:205], s[46:47], 0, v[128:129]
	s_mov_b32 m0, s14
	s_nop 0
	global_load_lds_dwordx4 v[204:205], off
	s_waitcnt vmcnt(8)
	s_waitcnt lgkmcnt(0)
	s_barrier
; #define PG8_STAGE(bufoff, gbase, voff) do { _Pragma("unroll") for (int _i = 0; _i < 2; ++_i) \
;         __builtin_amdgcn_global_load_lds((const unsigned*)((const char*)(gbase) + (voff)[_i]), (PG8_LAS unsigned*)(lds + (bufoff) + ldsw + _i * 8192), 16, 0, 0); } while (0)
; #define PG8_LDA(dst, b, h) do { _Pragma("unroll") for (int m = 0; m < 4; ++m) _Pragma("unroll") for (int k = 0; k < 2; ++k) dst[m][k] = *(const PG8_LAS bf16x8*)(lds + PG8_SA(b, h) + aoff + m * 2048 + k * 1024); } while (0)
; #define PG8_LDB(dst, b, h) do { _Pragma("unroll") for (int n = 0; n < 2; ++n) _Pragma("unroll") for (int k = 0; k < 2; ++k) dst[n][k] = *(const PG8_LAS bf16x8*)(lds + PG8_SB(b, h) + boff + n * 2048 + k * 1024); } while (0)
; #define PG8_MMA(ai, bj, At, Bt) do { __builtin_amdgcn_s_setprio(1); _Pragma("unroll") for (int m = 0; m < 4; ++m) _Pragma("unroll") for (int n = 0; n < 2; ++n) _Pragma("unroll") for (int k = 0; k < 2; ++k) \
;         acc[ai][bj][m][n] = mma16<F16>(Bt[n][k], At[m][k], acc[ai][bj][m][n]); __builtin_amdgcn_s_setprio(0); } while (0)
; #define PG8_WAIT_V(n) asm volatile("s_waitcnt vmcnt(" #n ")" ::: "memory")
; #define PG8_WAIT_L(n) asm volatile("s_waitcnt lgkmcnt(" #n ")" ::: "memory")
; #define PG8_BAR __builtin_amdgcn_s_barrier()
; #define PG8_SCHED __builtin_amdgcn_sched_barrier(0)
; template <class Epi, class Sched, bool ALIGN_EPI = false, bool SP2 = false, bool F16 = false>
; __device__ __forceinline__ void gemm_phase(PG8_LAS unsigned char* lds, const Gemm g, const Sched& S, const Epi& E, const int wid_in) {
;     ...
;             PG8_LDB(B0, 0, 0); PG8_LDB(B1, 0, 1); PG8_SCHED; PG8_LDA(At, 0, 0); PG8_STAGE(PG8_SA(1, 1), a1 + hstep, voffA);
;             PG8_WAIT_V(8); PG8_WAIT_L(0); PG8_BAR; PG8_MMA(0, 0, At, B0); PG8_MMA(0, 1, At, B1); PG8_BAR; PG8_SCHED;
;             PG8_LDA(At, 0, 1); PG8_STAGE(PG8_SB(0, 0), b2, voffB); PG8_STAGE(PG8_SB(0, 1), b2 + hstep, voffB); PG8_STAGE(PG8_SA(0, 0), a2, voffA);
;             PG8_WAIT_V(8); PG8_WAIT_L(0); PG8_BAR; PG8_MMA(1, 0, At, B0); PG8_MMA(1, 1, At, B1); PG8_BAR; PG8_SCHED;
	s_setprio 1
	s_waitcnt lgkmcnt(0)
	v_mfma_f32_16x16x32_bf16 v[64:67], v[104:107], v[172:175], v[64:67]
	v_mfma_f32_16x16x32_bf16 v[68:71], v[112:115], v[172:175], v[68:71]
	v_mfma_f32_16x16x32_bf16 v[72:75], v[104:107], v[180:183], v[72:75]
	v_mfma_f32_16x16x32_bf16 v[76:79], v[112:115], v[180:183], v[76:79]
	v_mfma_f32_16x16x32_bf16 v[80:83], v[104:107], v[188:191], v[80:83]
	v_mfma_f32_16x16x32_bf16 v[84:87], v[112:115], v[188:191], v[84:87]
	v_mfma_f32_16x16x32_bf16 v[88:91], v[104:107], v[196:199], v[88:91]
	v_mfma_f32_16x16x32_bf16 v[92:95], v[112:115], v[196:199], v[92:95]
	v_mfma_f32_16x16x32_bf16 v[64:67], v[108:111], v[176:179], v[64:67]
	v_mfma_f32_16x16x32_bf16 v[68:71], v[116:119], v[176:179], v[68:71]
	v_mfma_f32_16x16x32_bf16 v[72:75], v[108:111], v[184:187], v[72:75]
	v_mfma_f32_16x16x32_bf16 v[76:79], v[116:119], v[184:187], v[76:79]
	v_mfma_f32_16x16x32_bf16 v[80:83], v[108:111], v[192:195], v[80:83]
	v_mfma_f32_16x16x32_bf16 v[84:87], v[116:119], v[192:195], v[84:87]
	v_mfma_f32_16x16x32_bf16 v[88:91], v[108:111], v[200:203], v[88:91]
	v_mfma_f32_16x16x32_bf16 v[92:95], v[116:119], v[200:203], v[92:95]
	s_setprio 0
	s_setprio 1
	v_mfma_f32_16x16x32_bf16 v[32:35], v[164:167], v[172:175], v[32:35]
	v_mfma_f32_16x16x32_bf16 v[96:99], v[120:123], v[172:175], v[96:99]
	v_mfma_f32_16x16x32_bf16 v[172:175], v[168:171], v[176:179], v[32:35]
	v_mfma_f32_16x16x32_bf16 v[32:35], v[120:123], v[180:183], v[36:39]
	v_mfma_f32_16x16x32_bf16 v[204:207], v[124:127], v[176:179], v[96:99]
	v_mfma_f32_16x16x32_bf16 v[176:179], v[124:127], v[184:187], v[32:35]
	v_mfma_f32_16x16x32_bf16 v[32:35], v[164:167], v[180:183], v[40:43]
	v_mfma_f32_16x16x32_bf16 v[40:43], v[168:171], v[184:187], v[32:35]
	v_mfma_f32_16x16x32_bf16 v[32:35], v[120:123], v[188:191], v[44:47]
	v_mfma_f32_16x16x32_bf16 v[44:47], v[124:127], v[192:195], v[32:35]
	v_mfma_f32_16x16x32_bf16 v[32:35], v[164:167], v[188:191], v[48:51]
	v_mfma_f32_16x16x32_bf16 v[48:51], v[168:171], v[192:195], v[32:35]
	s_barrier
	v_mfma_f32_16x16x32_bf16 v[32:35], v[120:123], v[196:199], v[52:55]
	v_mfma_f32_16x16x32_bf16 v[52:55], v[124:127], v[200:203], v[32:35]
	v_mfma_f32_16x16x32_bf16 v[32:35], v[164:167], v[196:199], v[56:59]
	v_mfma_f32_16x16x32_bf16 v[56:59], v[168:171], v[200:203], v[32:35]
	s_setprio 0
	s_mov_b32 m0, s15
	v_lshl_add_u64 v[240:241], s[36:37], 0, v[130:131]
	s_add_u32 s46, s36, 0x10000
	s_nop 1
	ds_read_b128 v[32:35], v136 offset:16384
	ds_read_b128 v[36:39], v136 offset:17408
	ds_read_b128 v[96:99], v136 offset:18432
	ds_read_b128 v[180:183], v136 offset:19456
	ds_read_b128 v[184:187], v136 offset:20480
	ds_read_b128 v[188:191], v136 offset:21504
	ds_read_b128 v[192:195], v136 offset:22528
	ds_read_b128 v[196:199], v136 offset:23552
	global_load_lds_dwordx4 v[240:241], off
	v_lshl_add_u64 v[242:243], s[36:37], 0, v[128:129]
	s_mov_b32 m0, s50
	s_addc_u32 s47, s37, 0
	global_load_lds_dwordx4 v[242:243], off
	v_lshl_add_u64 v[200:201], s[46:47], 0, v[130:131]
	s_mov_b32 m0, s51
	v_lshl_add_u64 v[244:245], s[44:45], 0, v[130:131]
	global_load_lds_dwordx4 v[200:201], off
	v_lshl_add_u64 v[200:201], s[46:47], 0, v[128:129]
	s_mov_b32 m0, s52
	v_lshl_add_u64 v[246:247], s[44:45], 0, v[128:129]
	global_load_lds_dwordx4 v[200:201], off
	s_mov_b32 m0, s74
	s_nop 0
	global_load_lds_dwordx4 v[244:245], off
	s_mov_b32 m0, s66
	s_nop 0
	global_load_lds_dwordx4 v[246:247], off
	s_waitcnt vmcnt(8)
	s_waitcnt lgkmcnt(0)
	s_barrier
	s_setprio 1
	s_waitcnt lgkmcnt(0)
	v_mfma_f32_16x16x32_bf16 v[0:3], v[104:107], v[192:195], v[0:3]
	v_mfma_f32_16x16x32_bf16 v[140:143], v[104:107], v[32:35], v[140:143]
	v_mfma_f32_16x16x32_bf16 v[144:147], v[112:115], v[32:35], v[144:147]
	v_mfma_f32_16x16x32_bf16 v[148:151], v[104:107], v[96:99], v[148:151]
	v_mfma_f32_16x16x32_bf16 v[152:155], v[112:115], v[96:99], v[152:155]
	v_mfma_f32_16x16x32_bf16 v[156:159], v[104:107], v[184:187], v[156:159]
	v_mfma_f32_16x16x32_bf16 v[160:163], v[112:115], v[184:187], v[160:163]
	v_mfma_f32_16x16x32_bf16 v[0:3], v[108:111], v[196:199], v[0:3]
	v_mfma_f32_16x16x32_bf16 v[4:7], v[112:115], v[192:195], v[4:7]
	v_mfma_f32_16x16x32_bf16 v[140:143], v[108:111], v[36:39], v[140:143]
	v_mfma_f32_16x16x32_bf16 v[144:147], v[116:119], v[36:39], v[144:147]
	v_mfma_f32_16x16x32_bf16 v[148:151], v[108:111], v[180:183], v[148:151]
	v_mfma_f32_16x16x32_bf16 v[152:155], v[116:119], v[180:183], v[152:155]
	v_mfma_f32_16x16x32_bf16 v[156:159], v[108:111], v[188:191], v[156:159]
	v_mfma_f32_16x16x32_bf16 v[160:163], v[116:119], v[188:191], v[160:163]
	v_mfma_f32_16x16x32_bf16 v[200:203], v[116:119], v[196:199], v[4:7]
	s_setprio 0
	s_setprio 1
	v_mfma_f32_16x16x32_bf16 v[4:7], v[120:123], v[32:35], v[8:11]
	v_mfma_f32_16x16x32_bf16 v[8:11], v[124:127], v[36:39], v[4:7]
	v_mfma_f32_16x16x32_bf16 v[4:7], v[164:167], v[32:35], v[12:15]
	v_mfma_f32_16x16x32_bf16 v[12:15], v[168:171], v[36:39], v[4:7]
	v_mfma_f32_16x16x32_bf16 v[4:7], v[120:123], v[96:99], v[24:27]
	v_mfma_f32_16x16x32_bf16 v[24:27], v[124:127], v[180:183], v[4:7]
	v_mfma_f32_16x16x32_bf16 v[4:7], v[164:167], v[96:99], v[28:31]
	v_mfma_f32_16x16x32_bf16 v[28:31], v[168:171], v[180:183], v[4:7]
	v_mfma_f32_16x16x32_bf16 v[4:7], v[120:123], v[184:187], v[60:63]
	v_mfma_f32_16x16x32_bf16 v[180:183], v[124:127], v[188:191], v[4:7]
	v_mfma_f32_16x16x32_bf16 v[4:7], v[164:167], v[184:187], v[100:103]
	v_mfma_f32_16x16x32_bf16 v[184:187], v[168:171], v[188:191], v[4:7]
	s_barrier
; #define PG8_STAGE(bufoff, gbase, voff) do { _Pragma("unroll") for (int _i = 0; _i < 2; ++_i) \
;         __builtin_amdgcn_global_load_lds((const unsigned*)((const char*)(gbase) + (voff)[_i]), (PG8_LAS unsigned*)(lds + (bufoff) + ldsw + _i * 8192), 16, 0, 0); } while (0)
; #define PG8_LDA(dst, b, h) do { _Pragma("unroll") for (int m = 0; m < 4; ++m) _Pragma("unroll") for (int k = 0; k < 2; ++k) dst[m][k] = *(const PG8_LAS bf16x8*)(lds + PG8_SA(b, h) + aoff + m * 2048 + k * 1024); } while (0)
; #define PG8_LDB(dst, b, h) do { _Pragma("unroll") for (int n = 0; n < 2; ++n) _Pragma("unroll") for (int k = 0; k < 2; ++k) dst[n][k] = *(const PG8_LAS bf16x8*)(lds + PG8_SB(b, h) + boff + n * 2048 + k * 1024); } while (0)
; #define PG8_MMA(ai, bj, At, Bt) do { __builtin_amdgcn_s_setprio(1); _Pragma("unroll") for (int m = 0; m < 4; ++m) _Pragma("unroll") for (int n = 0; n < 2; ++n) _Pragma("unroll") for (int k = 0; k < 2; ++k) \
;         acc[ai][bj][m][n] = mma16<F16>(Bt[n][k], At[m][k], acc[ai][bj][m][n]); __builtin_amdgcn_s_setprio(0); } while (0)
; #define PG8_WAIT_V(n) asm volatile("s_waitcnt vmcnt(" #n ")" ::: "memory")
; #define PG8_WAIT_L(n) asm volatile("s_waitcnt lgkmcnt(" #n ")" ::: "memory")
; #define PG8_BAR __builtin_amdgcn_s_barrier()
; #define PG8_SCHED __builtin_amdgcn_sched_barrier(0)
; template <class Epi, class Sched, bool ALIGN_EPI = false, bool SP2 = false, bool F16 = false>
; __device__ __forceinline__ void gemm_phase(PG8_LAS unsigned char* lds, const Gemm g, const Sched& S, const Epi& E, const int wid_in) {
;     ...
;             PG8_WAIT_V(8); PG8_WAIT_L(0); PG8_BAR; PG8_MMA(1, 0, At, B0); PG8_MMA(1, 1, At, B1); PG8_BAR; PG8_SCHED;
;             PG8_LDB(B0, 1, 0); PG8_LDB(B1, 1, 1); PG8_SCHED; PG8_LDA(At, 1, 0); PG8_STAGE(PG8_SA(0, 1), a2 + hstep, voffA);
;             PG8_WAIT_V(8); PG8_WAIT_L(0); PG8_BAR; PG8_MMA(0, 0, At, B0); PG8_MMA(0, 1, At, B1); PG8_BAR; PG8_SCHED;
;             PG8_LDA(At, 1, 1); PG8_STAGE(PG8_SB(1, 0), b3, voffB); PG8_STAGE(PG8_SB(1, 1), b3 + hstep, voffB); PG8_STAGE(PG8_SA(1, 0), a3, voffA);
;             PG8_WAIT_V(8); PG8_WAIT_L(0); PG8_BAR; PG8_MMA(1, 0, At, B0); PG8_MMA(1, 1, At, B1); PG8_BAR; PG8_SCHED;
;     ...
;         if constexpr (ALIGN_EPI) { if (wr == 0) PG8_BAR; }
;         if constexpr (!Epi::AFTER_DRAIN) { E(acc, cur, wr, wc, fr, fq); S.done(cur); }
;         if (!has_next) break;
	v_mfma_f32_16x16x32_bf16 v[4:7], v[120:123], v[192:195], v[16:19]
	v_mfma_f32_16x16x32_bf16 v[188:191], v[124:127], v[196:199], v[4:7]
	v_mfma_f32_16x16x32_bf16 v[4:7], v[164:167], v[192:195], v[20:23]
	v_mfma_f32_16x16x32_bf16 v[164:167], v[168:171], v[196:199], v[4:7]
	s_setprio 0
	s_nop 4
	ds_read_b128 v[4:7], v137
	ds_read_b128 v[60:63], v137 offset:1024
	ds_read_b128 v[168:171], v137 offset:2048
	ds_read_b128 v[192:195], v137 offset:3072
	ds_read_b128 v[196:199], v138
	ds_read_b128 v[208:211], v138 offset:1024
	ds_read_b128 v[212:215], v138 offset:2048
	ds_read_b128 v[216:219], v138 offset:3072
	s_add_u32 s44, s44, 0x10000
	s_addc_u32 s45, s45, 0
	s_mov_b32 m0, s90
	v_lshl_add_u64 v[32:33], s[44:45], 0, v[130:131]
	ds_read_b128 v[16:19], v136 offset:32768
	ds_read_b128 v[20:23], v136 offset:33792
	ds_read_b128 v[104:107], v136 offset:34816
	ds_read_b128 v[220:223], v136 offset:35840
	ds_read_b128 v[224:227], v136 offset:36864
	ds_read_b128 v[228:231], v136 offset:37888
	ds_read_b128 v[232:235], v136 offset:38912
	ds_read_b128 v[236:239], v136 offset:39936
	global_load_lds_dwordx4 v[32:33], off
	v_lshl_add_u64 v[32:33], s[44:45], 0, v[128:129]
	s_mov_b32 m0, s43
	s_nop 0
	global_load_lds_dwordx4 v[32:33], off
	s_waitcnt vmcnt(8)
	s_waitcnt lgkmcnt(0)
	s_barrier
	s_setprio 1
	s_waitcnt lgkmcnt(0)
	v_mfma_f32_16x16x32_bf16 v[32:35], v[4:7], v[16:19], v[64:67]
	v_mfma_f32_16x16x32_bf16 v[116:119], v[60:63], v[20:23], v[32:35]
	v_mfma_f32_16x16x32_bf16 v[32:35], v[168:171], v[16:19], v[68:71]
	v_mfma_f32_16x16x32_bf16 v[112:115], v[192:195], v[20:23], v[32:35]
	v_mfma_f32_16x16x32_bf16 v[32:35], v[4:7], v[104:107], v[72:75]
	v_mfma_f32_16x16x32_bf16 v[100:103], v[60:63], v[220:223], v[32:35]
	v_mfma_f32_16x16x32_bf16 v[32:35], v[168:171], v[104:107], v[76:79]
	v_mfma_f32_16x16x32_bf16 v[96:99], v[192:195], v[220:223], v[32:35]
	v_mfma_f32_16x16x32_bf16 v[32:35], v[4:7], v[224:227], v[80:83]
	v_mfma_f32_16x16x32_bf16 v[68:71], v[60:63], v[228:231], v[32:35]
	v_mfma_f32_16x16x32_bf16 v[32:35], v[168:171], v[224:227], v[84:87]
	v_mfma_f32_16x16x32_bf16 v[64:67], v[192:195], v[228:231], v[32:35]
	v_mfma_f32_16x16x32_bf16 v[32:35], v[4:7], v[232:235], v[88:91]
	v_mfma_f32_16x16x32_bf16 v[36:39], v[60:63], v[236:239], v[32:35]
	v_mfma_f32_16x16x32_bf16 v[32:35], v[168:171], v[232:235], v[92:95]
	v_mfma_f32_16x16x32_bf16 v[32:35], v[192:195], v[236:239], v[32:35]
	s_setprio 0
	s_setprio 1
	v_mfma_f32_16x16x32_bf16 v[72:75], v[196:199], v[16:19], v[204:207]
	v_mfma_f32_16x16x32_bf16 v[16:19], v[212:215], v[16:19], v[172:175]
	v_mfma_f32_16x16x32_bf16 v[120:123], v[216:219], v[20:23], v[16:19]
	v_mfma_f32_16x16x32_bf16 v[16:19], v[196:199], v[104:107], v[176:179]
	v_mfma_f32_16x16x32_bf16 v[108:111], v[208:211], v[220:223], v[16:19]
	v_mfma_f32_16x16x32_bf16 v[16:19], v[212:215], v[104:107], v[40:43]
	v_mfma_f32_16x16x32_bf16 v[104:107], v[216:219], v[220:223], v[16:19]
	v_mfma_f32_16x16x32_bf16 v[16:19], v[196:199], v[224:227], v[44:47]
	v_mfma_f32_16x16x32_bf16 v[80:83], v[208:211], v[228:231], v[16:19]
	v_mfma_f32_16x16x32_bf16 v[16:19], v[212:215], v[224:227], v[48:51]
	v_mfma_f32_16x16x32_bf16 v[124:127], v[208:211], v[20:23], v[72:75]
	v_mfma_f32_16x16x32_bf16 v[72:75], v[216:219], v[228:231], v[16:19]
	s_barrier
	v_mfma_f32_16x16x32_bf16 v[16:19], v[196:199], v[232:235], v[52:55]
	v_mfma_f32_16x16x32_bf16 v[48:51], v[208:211], v[236:239], v[16:19]
	v_mfma_f32_16x16x32_bf16 v[16:19], v[212:215], v[232:235], v[56:59]
	v_mfma_f32_16x16x32_bf16 v[40:43], v[216:219], v[236:239], v[16:19]
	s_setprio 0
	s_mov_b32 m0, s53
	s_nop 3
	v_lshl_add_u64 v[16:17], v[240:241], 0, s[24:25]
	s_add_u32 s36, s36, 0x10080
	ds_read_b128 v[56:59], v136 offset:49152
	ds_read_b128 v[88:91], v136 offset:50176
	ds_read_b128 v[172:175], v136 offset:51200
	ds_read_b128 v[176:179], v136 offset:52224
	ds_read_b128 v[204:207], v136 offset:53248
	ds_read_b128 v[220:223], v136 offset:54272
	ds_read_b128 v[224:227], v136 offset:55296
	ds_read_b128 v[228:231], v136 offset:56320
	global_load_lds_dwordx4 v[16:17], off
	v_lshl_add_u64 v[16:17], v[242:243], 0, s[24:25]
	s_mov_b32 m0, s54
	s_addc_u32 s37, s37, 0
	global_load_lds_dwordx4 v[16:17], off
	v_lshl_add_u64 v[16:17], s[36:37], 0, v[130:131]
	s_mov_b32 m0, s55
	s_nop 0
	global_load_lds_dwordx4 v[16:17], off
	v_lshl_add_u64 v[16:17], s[36:37], 0, v[128:129]
	s_mov_b32 m0, s56
	s_nop 0
	global_load_lds_dwordx4 v[16:17], off
	v_lshl_add_u64 v[16:17], v[244:245], 0, s[24:25]
	s_mov_b32 m0, s75
	s_nop 0
	global_load_lds_dwordx4 v[16:17], off
	v_lshl_add_u64 v[16:17], v[246:247], 0, s[24:25]
	s_mov_b32 m0, s67
	s_nop 0
	global_load_lds_dwordx4 v[16:17], off
	s_waitcnt vmcnt(8)
	s_waitcnt lgkmcnt(0)
	s_barrier
	s_setprio 1
	s_waitcnt lgkmcnt(0)
	v_mfma_f32_16x16x32_bf16 v[16:19], v[4:7], v[56:59], v[140:143]
	v_mfma_f32_16x16x32_bf16 v[84:87], v[60:63], v[88:91], v[16:19]
	v_mfma_f32_16x16x32_bf16 v[16:19], v[168:171], v[56:59], v[144:147]
	v_mfma_f32_16x16x32_bf16 v[76:79], v[192:195], v[88:91], v[16:19]
	v_mfma_f32_16x16x32_bf16 v[16:19], v[4:7], v[172:175], v[148:151]
	v_mfma_f32_16x16x32_bf16 v[52:55], v[60:63], v[176:179], v[16:19]
	v_mfma_f32_16x16x32_bf16 v[16:19], v[168:171], v[172:175], v[152:155]
	v_mfma_f32_16x16x32_bf16 v[44:47], v[192:195], v[176:179], v[16:19]
	v_mfma_f32_16x16x32_bf16 v[16:19], v[4:7], v[204:207], v[156:159]
	v_mfma_f32_16x16x32_bf16 v[0:3], v[4:7], v[224:227], v[0:3]
	v_mfma_f32_16x16x32_bf16 v[20:23], v[60:63], v[220:223], v[16:19]
	v_mfma_f32_16x16x32_bf16 v[16:19], v[168:171], v[204:207], v[160:163]
	v_mfma_f32_16x16x32_bf16 v[4:7], v[60:63], v[228:231], v[0:3]
	v_mfma_f32_16x16x32_bf16 v[0:3], v[168:171], v[224:227], v[200:203]
	v_mfma_f32_16x16x32_bf16 v[16:19], v[192:195], v[220:223], v[16:19]
	v_mfma_f32_16x16x32_bf16 v[0:3], v[192:195], v[228:231], v[0:3]
	s_setprio 0
	s_setprio 1
	v_mfma_f32_16x16x32_bf16 v[8:11], v[196:199], v[56:59], v[8:11]
	v_mfma_f32_16x16x32_bf16 v[92:95], v[208:211], v[88:91], v[8:11]
	v_mfma_f32_16x16x32_bf16 v[8:11], v[212:215], v[56:59], v[12:15]
	v_mfma_f32_16x16x32_bf16 v[88:91], v[216:219], v[88:91], v[8:11]
	v_mfma_f32_16x16x32_bf16 v[8:11], v[196:199], v[172:175], v[24:27]
	v_mfma_f32_16x16x32_bf16 v[60:63], v[208:211], v[176:179], v[8:11]
	v_mfma_f32_16x16x32_bf16 v[8:11], v[212:215], v[172:175], v[28:31]
	v_mfma_f32_16x16x32_bf16 v[56:59], v[216:219], v[176:179], v[8:11]
	v_mfma_f32_16x16x32_bf16 v[8:11], v[196:199], v[204:207], v[180:183]
	v_mfma_f32_16x16x32_bf16 v[28:31], v[208:211], v[220:223], v[8:11]
	v_mfma_f32_16x16x32_bf16 v[8:11], v[212:215], v[204:207], v[184:187]
	v_mfma_f32_16x16x32_bf16 v[24:27], v[216:219], v[220:223], v[8:11]
	s_barrier
	v_mfma_f32_16x16x32_bf16 v[8:11], v[196:199], v[224:227], v[188:191]
	v_mfma_f32_16x16x32_bf16 v[12:15], v[208:211], v[228:231], v[8:11]
	v_mfma_f32_16x16x32_bf16 v[8:11], v[212:215], v[224:227], v[164:167]
	v_mfma_f32_16x16x32_bf16 v[8:11], v[216:219], v[228:231], v[8:11]
	s_setprio 0
	s_and_b64 vcc, exec, s[8:9]
	s_cbranch_vccnz .LBB0_1946
	s_barrier

; #define PG8_STAGE(bufoff, gbase, voff) do { _Pragma("unroll") for (int _i = 0; _i < 2; ++_i) \
;         __builtin_amdgcn_global_load_lds((const unsigned*)((const char*)(gbase) + (voff)[_i]), (PG8_LAS unsigned*)(lds + (bufoff) + ldsw + _i * 8192), 16, 0, 0); } while (0)
; #define PG8_LDA(dst, b, h) do { _Pragma("unroll") for (int m = 0; m < 4; ++m) _Pragma("unroll") for (int k = 0; k < 2; ++k) dst[m][k] = *(const PG8_LAS bf16x8*)(lds + PG8_SA(b, h) + aoff + m * 2048 + k * 1024); } while (0)
; #define PG8_LDB(dst, b, h) do { _Pragma("unroll") for (int n = 0; n < 2; ++n) _Pragma("unroll") for (int k = 0; k < 2; ++k) dst[n][k] = *(const PG8_LAS bf16x8*)(lds + PG8_SB(b, h) + boff + n * 2048 + k * 1024); } while (0)
; #define PG8_MMA(ai, bj, At, Bt) do { __builtin_amdgcn_s_setprio(1); _Pragma("unroll") for (int m = 0; m < 4; ++m) _Pragma("unroll") for (int n = 0; n < 2; ++n) _Pragma("unroll") for (int k = 0; k < 2; ++k) \
;         acc[ai][bj][m][n] = mma16<F16>(Bt[n][k], At[m][k], acc[ai][bj][m][n]); __builtin_amdgcn_s_setprio(0); } while (0)
; #define PG8_WAIT_V(n) asm volatile("s_waitcnt vmcnt(" #n ")" ::: "memory")
; #define PG8_WAIT_L(n) asm volatile("s_waitcnt lgkmcnt(" #n ")" ::: "memory")
; #define PG8_BAR __builtin_amdgcn_s_barrier()
; #define PG8_SCHED __builtin_amdgcn_sched_barrier(0)
; template <class Epi, class Sched, bool ALIGN_EPI = false, bool SP2 = false, bool F16 = false>
; __device__ __forceinline__ void gemm_phase(PG8_LAS unsigned char* lds, const Gemm g, const Sched& S, const Epi& E, const int wid_in) {
;     ...
;         for (int t = 0; t < nt; t += 2) {
;             const bool last = (t == nt - 2);
;             const char* a1 = cA + (size_t)(t + 1) * kstep;
;             const char* a2 = last ? nA : cA + (size_t)(t + 2) * kstep; const char* b2 = last ? nB : cB + (size_t)(t + 2) * kstep;
;             const char* a3 = a2 + kstep; const char* b3 = b2 + kstep;
;             if (last && has_next) S.a_ready(nxt);
;             if constexpr (SP2) {
;             PG8_LDB(B0, 0, 0); PG8_LDB(B1, 0, 1); PG8_SCHED; PG8_LDA(At, 0, 0); PG8_STAGE(PG8_SA(1, 1), a1 + hstep, voffA);
;             PG8_WAIT_V(8); PG8_WAIT_L(0); PG8_BAR; PG8_MMA(0, 0, At, B0); PG8_MMA(0, 1, At, B1); PG8_BAR; PG8_SCHED;
;             PG8_LDA(At, 0, 1); PG8_STAGE(PG8_SB(0, 0), b2, voffB); PG8_STAGE(PG8_SB(0, 1), b2 + hstep, voffB); PG8_STAGE(PG8_SA(0, 0), a2, voffA);
.LBB0_2040:
	ds_read_b128 v[128:131], v189
	ds_read_b128 v[132:135], v189 offset:1024
	ds_read_b128 v[136:139], v189 offset:2048
	ds_read_b128 v[140:143], v189 offset:3072
	ds_read_b128 v[144:147], v190
	ds_read_b128 v[148:151], v190 offset:1024
	ds_read_b128 v[168:171], v190 offset:2048
	ds_read_b128 v[172:175], v190 offset:3072
	s_add_u32 s44, s36, 0x100
	s_addc_u32 s45, s37, 0
	s_cmp_eq_u32 s59, 40
	s_cselect_b32 s49, s13, s45
	s_cselect_b32 s48, s12, s44
	s_cselect_b32 s47, s35, s58
	s_cselect_b32 s46, s34, s43
	s_mov_b32 m0, s91
	v_lshl_add_u64 v[184:185], s[36:37], 0, v[160:161]
	ds_read_b128 v[176:179], v191
	ds_read_b128 v[180:183], v191 offset:1024
	ds_read_b128 v[192:195], v191 offset:2048
	ds_read_b128 v[196:199], v191 offset:3072
	ds_read_b128 v[200:203], v191 offset:4096
	ds_read_b128 v[204:207], v191 offset:5120
	ds_read_b128 v[208:211], v191 offset:6144
	ds_read_b128 v[212:215], v191 offset:7168
	global_load_lds_dwordx4 v[184:185], off
	v_lshl_add_u64 v[184:185], s[36:37], 0, v[162:163]
	s_add_i32 m0, s74, 0xe000
	s_nop 0
	global_load_lds_dwordx4 v[184:185], off
	s_waitcnt vmcnt(8)
	s_waitcnt lgkmcnt(0)
	s_barrier
	s_setprio 1
	s_waitcnt lgkmcnt(0)
	v_mfma_f32_16x16x32_bf16 v[124:127], v[128:131], v[176:179], v[124:127]
	v_mfma_f32_16x16x32_bf16 v[120:123], v[136:139], v[176:179], v[120:123]
	v_mfma_f32_16x16x32_bf16 v[108:111], v[128:131], v[192:195], v[108:111]
	v_mfma_f32_16x16x32_bf16 v[104:107], v[136:139], v[192:195], v[104:107]
	v_mfma_f32_16x16x32_bf16 v[92:95], v[128:131], v[200:203], v[92:95]
	v_mfma_f32_16x16x32_bf16 v[88:91], v[136:139], v[200:203], v[88:91]
	v_mfma_f32_16x16x32_bf16 v[76:79], v[128:131], v[208:211], v[76:79]
	v_mfma_f32_16x16x32_bf16 v[72:75], v[136:139], v[208:211], v[72:75]
	v_mfma_f32_16x16x32_bf16 v[124:127], v[132:135], v[180:183], v[124:127]
	v_mfma_f32_16x16x32_bf16 v[120:123], v[140:143], v[180:183], v[120:123]
	v_mfma_f32_16x16x32_bf16 v[108:111], v[132:135], v[196:199], v[108:111]
	v_mfma_f32_16x16x32_bf16 v[104:107], v[140:143], v[196:199], v[104:107]
	v_mfma_f32_16x16x32_bf16 v[92:95], v[132:135], v[204:207], v[92:95]
	v_mfma_f32_16x16x32_bf16 v[88:91], v[140:143], v[204:207], v[88:91]
	v_mfma_f32_16x16x32_bf16 v[76:79], v[132:135], v[212:215], v[76:79]
	v_mfma_f32_16x16x32_bf16 v[72:75], v[140:143], v[212:215], v[72:75]
	s_setprio 0
	s_setprio 1
	v_mfma_f32_16x16x32_bf16 v[116:119], v[144:147], v[176:179], v[116:119]
	v_mfma_f32_16x16x32_bf16 v[112:115], v[168:171], v[176:179], v[112:115]
	v_mfma_f32_16x16x32_bf16 v[100:103], v[144:147], v[192:195], v[100:103]
	v_mfma_f32_16x16x32_bf16 v[96:99], v[168:171], v[192:195], v[96:99]
	v_mfma_f32_16x16x32_bf16 v[84:87], v[144:147], v[200:203], v[84:87]
	v_mfma_f32_16x16x32_bf16 v[80:83], v[168:171], v[200:203], v[80:83]
	v_mfma_f32_16x16x32_bf16 v[68:71], v[144:147], v[208:211], v[68:71]
	v_mfma_f32_16x16x32_bf16 v[64:67], v[168:171], v[208:211], v[64:67]
	v_mfma_f32_16x16x32_bf16 v[116:119], v[148:151], v[180:183], v[116:119]
	v_mfma_f32_16x16x32_bf16 v[112:115], v[172:175], v[180:183], v[112:115]
	v_mfma_f32_16x16x32_bf16 v[100:103], v[148:151], v[196:199], v[100:103]
	v_mfma_f32_16x16x32_bf16 v[96:99], v[172:175], v[196:199], v[96:99]
	s_barrier
	v_mfma_f32_16x16x32_bf16 v[84:87], v[148:151], v[204:207], v[84:87]
	v_mfma_f32_16x16x32_bf16 v[80:83], v[172:175], v[204:207], v[80:83]
	v_mfma_f32_16x16x32_bf16 v[68:71], v[148:151], v[212:215], v[68:71]
	v_mfma_f32_16x16x32_bf16 v[64:67], v[172:175], v[212:215], v[64:67]
	s_setprio 0
	s_add_i32 s36, s53, s68
	v_lshl_add_u64 v[184:185], s[46:47], 0, v[154:155]
	s_mov_b32 m0, s36
	ds_read_b128 v[176:179], v191 offset:16384
	ds_read_b128 v[180:183], v191 offset:17408
	ds_read_b128 v[192:195], v191 offset:18432
	ds_read_b128 v[196:199], v191 offset:19456
	ds_read_b128 v[200:203], v191 offset:20480
	ds_read_b128 v[204:207], v191 offset:21504
	ds_read_b128 v[208:211], v191 offset:22528
	ds_read_b128 v[212:215], v191 offset:23552
	global_load_lds_dwordx4 v[184:185], off
	s_add_i32 m0, s36, 0x2000
	s_add_u32 s36, s46, 0xb0000
	v_lshl_add_u64 v[216:217], s[46:47], 0, v[158:159]
	s_addc_u32 s37, s47, 0
	s_add_i32 s60, s54, s68
	global_load_lds_dwordx4 v[216:217], off
	v_lshl_add_u64 v[218:219], s[36:37], 0, v[154:155]
	s_mov_b32 m0, s60
	v_lshl_add_u64 v[220:221], s[48:49], 0, v[156:157]
	global_load_lds_dwordx4 v[218:219], off
	v_lshl_add_u64 v[218:219], s[36:37], 0, v[158:159]
	s_add_i32 m0, s60, 0x2000
	s_nop 0
	global_load_lds_dwordx4 v[218:219], off
	v_lshl_add_u64 v[218:219], s[48:49], 0, v[152:153]
	s_mov_b32 m0, s74
	s_nop 0
	global_load_lds_dwordx4 v[218:219], off
	s_mov_b32 m0, s66
	s_nop 0
	global_load_lds_dwordx4 v[220:221], off
	s_waitcnt vmcnt(8)
	s_waitcnt lgkmcnt(0)
	s_barrier
; #define PG8_STAGE(bufoff, gbase, voff) do { _Pragma("unroll") for (int _i = 0; _i < 2; ++_i) \
;         __builtin_amdgcn_global_load_lds((const unsigned*)((const char*)(gbase) + (voff)[_i]), (PG8_LAS unsigned*)(lds + (bufoff) + ldsw + _i * 8192), 16, 0, 0); } while (0)
; #define PG8_LDA(dst, b, h) do { _Pragma("unroll") for (int m = 0; m < 4; ++m) _Pragma("unroll") for (int k = 0; k < 2; ++k) dst[m][k] = *(const PG8_LAS bf16x8*)(lds + PG8_SA(b, h) + aoff + m * 2048 + k * 1024); } while (0)
; #define PG8_LDB(dst, b, h) do { _Pragma("unroll") for (int n = 0; n < 2; ++n) _Pragma("unroll") for (int k = 0; k < 2; ++k) dst[n][k] = *(const PG8_LAS bf16x8*)(lds + PG8_SB(b, h) + boff + n * 2048 + k * 1024); } while (0)
; #define PG8_MMA(ai, bj, At, Bt) do { __builtin_amdgcn_s_setprio(1); _Pragma("unroll") for (int m = 0; m < 4; ++m) _Pragma("unroll") for (int n = 0; n < 2; ++n) _Pragma("unroll") for (int k = 0; k < 2; ++k) \
;         acc[ai][bj][m][n] = mma16<F16>(Bt[n][k], At[m][k], acc[ai][bj][m][n]); __builtin_amdgcn_s_setprio(0); } while (0)
; #define PG8_WAIT_V(n) asm volatile("s_waitcnt vmcnt(" #n ")" ::: "memory")
; #define PG8_WAIT_L(n) asm volatile("s_waitcnt lgkmcnt(" #n ")" ::: "memory")
; #define PG8_BAR __builtin_amdgcn_s_barrier()
; #define PG8_SCHED __builtin_amdgcn_sched_barrier(0)
; template <class Epi, class Sched, bool ALIGN_EPI = false, bool SP2 = false, bool F16 = false>
; __device__ __forceinline__ void gemm_phase(PG8_LAS unsigned char* lds, const Gemm g, const Sched& S, const Epi& E, const int wid_in) {
;     ...
;             PG8_WAIT_V(8); PG8_WAIT_L(0); PG8_BAR; PG8_MMA(1, 0, At, B0); PG8_MMA(1, 1, At, B1); PG8_BAR; PG8_SCHED;
;             PG8_LDB(B0, 1, 0); PG8_LDB(B1, 1, 1); PG8_SCHED; PG8_LDA(At, 1, 0); PG8_STAGE(PG8_SA(0, 1), a2 + hstep, voffA);
;             PG8_WAIT_V(8); PG8_WAIT_L(0); PG8_BAR; PG8_MMA(0, 0, At, B0); PG8_MMA(0, 1, At, B1); PG8_BAR; PG8_SCHED;
	s_setprio 1
	s_waitcnt lgkmcnt(0)
	v_mfma_f32_16x16x32_bf16 v[60:63], v[128:131], v[176:179], v[60:63]
	v_mfma_f32_16x16x32_bf16 v[56:59], v[136:139], v[176:179], v[56:59]
	v_mfma_f32_16x16x32_bf16 v[44:47], v[128:131], v[192:195], v[44:47]
	v_mfma_f32_16x16x32_bf16 v[40:43], v[136:139], v[192:195], v[40:43]
	v_mfma_f32_16x16x32_bf16 v[28:31], v[128:131], v[200:203], v[28:31]
	v_mfma_f32_16x16x32_bf16 v[24:27], v[136:139], v[200:203], v[24:27]
	v_mfma_f32_16x16x32_bf16 v[12:15], v[128:131], v[208:211], v[12:15]
	v_mfma_f32_16x16x32_bf16 v[8:11], v[136:139], v[208:211], v[8:11]
	v_mfma_f32_16x16x32_bf16 v[60:63], v[132:135], v[180:183], v[60:63]
	v_mfma_f32_16x16x32_bf16 v[56:59], v[140:143], v[180:183], v[56:59]
	v_mfma_f32_16x16x32_bf16 v[44:47], v[132:135], v[196:199], v[44:47]
	v_mfma_f32_16x16x32_bf16 v[40:43], v[140:143], v[196:199], v[40:43]
	v_mfma_f32_16x16x32_bf16 v[28:31], v[132:135], v[204:207], v[28:31]
	v_mfma_f32_16x16x32_bf16 v[24:27], v[140:143], v[204:207], v[24:27]
	v_mfma_f32_16x16x32_bf16 v[12:15], v[132:135], v[212:215], v[12:15]
	v_mfma_f32_16x16x32_bf16 v[8:11], v[140:143], v[212:215], v[8:11]
	s_setprio 0
	s_setprio 1
	v_mfma_f32_16x16x32_bf16 v[52:55], v[144:147], v[176:179], v[52:55]
	v_mfma_f32_16x16x32_bf16 v[48:51], v[168:171], v[176:179], v[48:51]
	v_mfma_f32_16x16x32_bf16 v[36:39], v[144:147], v[192:195], v[36:39]
	v_mfma_f32_16x16x32_bf16 v[32:35], v[168:171], v[192:195], v[32:35]
	v_mfma_f32_16x16x32_bf16 v[20:23], v[144:147], v[200:203], v[20:23]
	v_mfma_f32_16x16x32_bf16 v[16:19], v[168:171], v[200:203], v[16:19]
	v_mfma_f32_16x16x32_bf16 v[4:7], v[144:147], v[208:211], v[4:7]
	v_mfma_f32_16x16x32_bf16 v[0:3], v[168:171], v[208:211], v[0:3]
	v_mfma_f32_16x16x32_bf16 v[52:55], v[148:151], v[180:183], v[52:55]
	v_mfma_f32_16x16x32_bf16 v[48:51], v[172:175], v[180:183], v[48:51]
	v_mfma_f32_16x16x32_bf16 v[36:39], v[148:151], v[196:199], v[36:39]
	v_mfma_f32_16x16x32_bf16 v[32:35], v[172:175], v[196:199], v[32:35]
	s_barrier
	v_mfma_f32_16x16x32_bf16 v[20:23], v[148:151], v[204:207], v[20:23]
	v_mfma_f32_16x16x32_bf16 v[16:19], v[172:175], v[204:207], v[16:19]
	v_mfma_f32_16x16x32_bf16 v[4:7], v[148:151], v[212:215], v[4:7]
	v_mfma_f32_16x16x32_bf16 v[0:3], v[172:175], v[212:215], v[0:3]
	s_setprio 0
	s_add_i32 s60, 0, 0x18000
	s_add_i32 s61, 0, 0x1c000
	v_add_u32_e32 v140, s60, v188
	v_add_u32_e32 v172, s61, v188
	ds_read_b128 v[128:131], v140
	ds_read_b128 v[132:135], v140 offset:1024
	ds_read_b128 v[136:139], v140 offset:2048
	ds_read_b128 v[140:143], v140 offset:3072
	ds_read_b128 v[144:147], v172
	ds_read_b128 v[148:151], v172 offset:1024
	ds_read_b128 v[168:171], v172 offset:2048
	ds_read_b128 v[172:175], v172 offset:3072
	s_add_u32 s36, s48, 0xb0000
	s_addc_u32 s37, s49, 0
	s_mov_b32 m0, s90
	v_lshl_add_u64 v[222:223], s[36:37], 0, v[152:153]
	ds_read_b128 v[176:179], v191 offset:32768
	ds_read_b128 v[180:183], v191 offset:33792
	ds_read_b128 v[192:195], v191 offset:34816
	ds_read_b128 v[196:199], v191 offset:35840
	ds_read_b128 v[200:203], v191 offset:36864
	ds_read_b128 v[204:207], v191 offset:37888
	ds_read_b128 v[208:211], v191 offset:38912
	ds_read_b128 v[212:215], v191 offset:39936
	global_load_lds_dwordx4 v[222:223], off
	v_lshl_add_u64 v[222:223], s[36:37], 0, v[156:157]
	s_mov_b32 m0, s41
	s_nop 0
	global_load_lds_dwordx4 v[222:223], off
	s_waitcnt vmcnt(8)
	s_waitcnt lgkmcnt(0)
	s_barrier
	s_setprio 1
	s_waitcnt lgkmcnt(0)
	v_mfma_f32_16x16x32_bf16 v[124:127], v[128:131], v[176:179], v[124:127]
	v_mfma_f32_16x16x32_bf16 v[120:123], v[136:139], v[176:179], v[120:123]
	v_mfma_f32_16x16x32_bf16 v[108:111], v[128:131], v[192:195], v[108:111]
	v_mfma_f32_16x16x32_bf16 v[104:107], v[136:139], v[192:195], v[104:107]
	v_mfma_f32_16x16x32_bf16 v[92:95], v[128:131], v[200:203], v[92:95]
	v_mfma_f32_16x16x32_bf16 v[88:91], v[136:139], v[200:203], v[88:91]
	v_mfma_f32_16x16x32_bf16 v[76:79], v[128:131], v[208:211], v[76:79]
	v_mfma_f32_16x16x32_bf16 v[72:75], v[136:139], v[208:211], v[72:75]
	v_mfma_f32_16x16x32_bf16 v[124:127], v[132:135], v[180:183], v[124:127]
	v_mfma_f32_16x16x32_bf16 v[120:123], v[140:143], v[180:183], v[120:123]
	v_mfma_f32_16x16x32_bf16 v[108:111], v[132:135], v[196:199], v[108:111]
	v_mfma_f32_16x16x32_bf16 v[104:107], v[140:143], v[196:199], v[104:107]
	v_mfma_f32_16x16x32_bf16 v[92:95], v[132:135], v[204:207], v[92:95]
	v_mfma_f32_16x16x32_bf16 v[88:91], v[140:143], v[204:207], v[88:91]
	v_mfma_f32_16x16x32_bf16 v[76:79], v[132:135], v[212:215], v[76:79]
	v_mfma_f32_16x16x32_bf16 v[72:75], v[140:143], v[212:215], v[72:75]
	s_setprio 0
	s_setprio 1
	v_mfma_f32_16x16x32_bf16 v[116:119], v[144:147], v[176:179], v[116:119]
	v_mfma_f32_16x16x32_bf16 v[112:115], v[168:171], v[176:179], v[112:115]
	v_mfma_f32_16x16x32_bf16 v[100:103], v[144:147], v[192:195], v[100:103]
	v_mfma_f32_16x16x32_bf16 v[96:99], v[168:171], v[192:195], v[96:99]
	v_mfma_f32_16x16x32_bf16 v[84:87], v[144:147], v[200:203], v[84:87]
	v_mfma_f32_16x16x32_bf16 v[80:83], v[168:171], v[200:203], v[80:83]
	v_mfma_f32_16x16x32_bf16 v[68:71], v[144:147], v[208:211], v[68:71]
	v_mfma_f32_16x16x32_bf16 v[64:67], v[168:171], v[208:211], v[64:67]
	v_mfma_f32_16x16x32_bf16 v[116:119], v[148:151], v[180:183], v[116:119]
	v_mfma_f32_16x16x32_bf16 v[112:115], v[172:175], v[180:183], v[112:115]
	v_mfma_f32_16x16x32_bf16 v[100:103], v[148:151], v[196:199], v[100:103]
	v_mfma_f32_16x16x32_bf16 v[96:99], v[172:175], v[196:199], v[96:99]
	s_barrier
; #define PG8_STAGE(bufoff, gbase, voff) do { _Pragma("unroll") for (int _i = 0; _i < 2; ++_i) \
;         __builtin_amdgcn_global_load_lds((const unsigned*)((const char*)(gbase) + (voff)[_i]), (PG8_LAS unsigned*)(lds + (bufoff) + ldsw + _i * 8192), 16, 0, 0); } while (0)
; #define PG8_LDA(dst, b, h) do { _Pragma("unroll") for (int m = 0; m < 4; ++m) _Pragma("unroll") for (int k = 0; k < 2; ++k) dst[m][k] = *(const PG8_LAS bf16x8*)(lds + PG8_SA(b, h) + aoff + m * 2048 + k * 1024); } while (0)
; #define PG8_MMA(ai, bj, At, Bt) do { __builtin_amdgcn_s_setprio(1); _Pragma("unroll") for (int m = 0; m < 4; ++m) _Pragma("unroll") for (int n = 0; n < 2; ++n) _Pragma("unroll") for (int k = 0; k < 2; ++k) \
;         acc[ai][bj][m][n] = mma16<F16>(Bt[n][k], At[m][k], acc[ai][bj][m][n]); __builtin_amdgcn_s_setprio(0); } while (0)
; #define PG8_WAIT_V(n) asm volatile("s_waitcnt vmcnt(" #n ")" ::: "memory")
; #define PG8_WAIT_L(n) asm volatile("s_waitcnt lgkmcnt(" #n ")" ::: "memory")
; #define PG8_BAR __builtin_amdgcn_s_barrier()
; #define PG8_SCHED __builtin_amdgcn_sched_barrier(0)
; template <class Epi, class Sched, bool ALIGN_EPI = false, bool SP2 = false, bool F16 = false>
; __device__ __forceinline__ void gemm_phase(PG8_LAS unsigned char* lds, const Gemm g, const Sched& S, const Epi& E, const int wid_in) {
;     ...
;             PG8_WAIT_V(8); PG8_WAIT_L(0); PG8_BAR; PG8_MMA(0, 0, At, B0); PG8_MMA(0, 1, At, B1); PG8_BAR; PG8_SCHED;
;             PG8_LDA(At, 1, 1); PG8_STAGE(PG8_SB(1, 0), b3, voffB); PG8_STAGE(PG8_SB(1, 1), b3 + hstep, voffB); PG8_STAGE(PG8_SA(1, 0), a3, voffA);
;             PG8_WAIT_V(8); PG8_WAIT_L(0); PG8_BAR; PG8_MMA(1, 0, At, B0); PG8_MMA(1, 1, At, B1); PG8_BAR; PG8_SCHED;
	v_mfma_f32_16x16x32_bf16 v[84:87], v[148:151], v[204:207], v[84:87]
	v_mfma_f32_16x16x32_bf16 v[80:83], v[172:175], v[204:207], v[80:83]
	v_mfma_f32_16x16x32_bf16 v[68:71], v[148:151], v[212:215], v[68:71]
	v_mfma_f32_16x16x32_bf16 v[64:67], v[172:175], v[212:215], v[64:67]
	s_setprio 0
	s_add_i32 s36, s60, s68
	v_lshl_add_u64 v[184:185], v[184:185], 0, s[30:31]
	s_mov_b32 m0, s36
	ds_read_b128 v[176:179], v191 offset:49152
	ds_read_b128 v[180:183], v191 offset:50176
	ds_read_b128 v[192:195], v191 offset:51200
	ds_read_b128 v[196:199], v191 offset:52224
	ds_read_b128 v[200:203], v191 offset:53248
	ds_read_b128 v[204:207], v191 offset:54272
	ds_read_b128 v[208:211], v191 offset:55296
	ds_read_b128 v[212:215], v191 offset:56320
	global_load_lds_dwordx4 v[184:185], off
	s_add_i32 m0, s36, 0x2000
	s_add_u32 s36, s46, 0xb0080
	v_lshl_add_u64 v[184:185], v[216:217], 0, s[30:31]
	s_addc_u32 s37, s47, 0
	s_add_i32 s46, s61, s68
	global_load_lds_dwordx4 v[184:185], off
	v_lshl_add_u64 v[184:185], s[36:37], 0, v[154:155]
	s_mov_b32 m0, s46
	s_nop 0
	global_load_lds_dwordx4 v[184:185], off
	v_lshl_add_u64 v[184:185], s[36:37], 0, v[158:159]
	s_add_i32 m0, s46, 0x2000
	s_nop 0
	global_load_lds_dwordx4 v[184:185], off
	v_lshl_add_u64 v[184:185], v[218:219], 0, s[30:31]
	s_mov_b32 m0, s75
	s_nop 0
	global_load_lds_dwordx4 v[184:185], off
	v_lshl_add_u64 v[184:185], v[220:221], 0, s[30:31]
	s_mov_b32 m0, s67
	s_nop 0
	global_load_lds_dwordx4 v[184:185], off
	s_waitcnt vmcnt(8)
	s_waitcnt lgkmcnt(0)
	s_barrier
	s_setprio 1
	s_waitcnt lgkmcnt(0)
	v_mfma_f32_16x16x32_bf16 v[60:63], v[128:131], v[176:179], v[60:63]
	v_mfma_f32_16x16x32_bf16 v[56:59], v[136:139], v[176:179], v[56:59]
	v_mfma_f32_16x16x32_bf16 v[44:47], v[128:131], v[192:195], v[44:47]
	v_mfma_f32_16x16x32_bf16 v[40:43], v[136:139], v[192:195], v[40:43]
	v_mfma_f32_16x16x32_bf16 v[28:31], v[128:131], v[200:203], v[28:31]
	v_mfma_f32_16x16x32_bf16 v[24:27], v[136:139], v[200:203], v[24:27]
	v_mfma_f32_16x16x32_bf16 v[12:15], v[128:131], v[208:211], v[12:15]
	v_mfma_f32_16x16x32_bf16 v[8:11], v[136:139], v[208:211], v[8:11]
	v_mfma_f32_16x16x32_bf16 v[60:63], v[132:135], v[180:183], v[60:63]
	v_mfma_f32_16x16x32_bf16 v[56:59], v[140:143], v[180:183], v[56:59]
	v_mfma_f32_16x16x32_bf16 v[44:47], v[132:135], v[196:199], v[44:47]
	v_mfma_f32_16x16x32_bf16 v[40:43], v[140:143], v[196:199], v[40:43]
	v_mfma_f32_16x16x32_bf16 v[28:31], v[132:135], v[204:207], v[28:31]
	v_mfma_f32_16x16x32_bf16 v[24:27], v[140:143], v[204:207], v[24:27]
	v_mfma_f32_16x16x32_bf16 v[12:15], v[132:135], v[212:215], v[12:15]
	v_mfma_f32_16x16x32_bf16 v[8:11], v[140:143], v[212:215], v[8:11]
	s_setprio 0
	s_setprio 1
	v_mfma_f32_16x16x32_bf16 v[52:55], v[144:147], v[176:179], v[52:55]
	v_mfma_f32_16x16x32_bf16 v[48:51], v[168:171], v[176:179], v[48:51]
	v_mfma_f32_16x16x32_bf16 v[36:39], v[144:147], v[192:195], v[36:39]
	v_mfma_f32_16x16x32_bf16 v[32:35], v[168:171], v[192:195], v[32:35]
	v_mfma_f32_16x16x32_bf16 v[20:23], v[144:147], v[200:203], v[20:23]
	v_mfma_f32_16x16x32_bf16 v[16:19], v[168:171], v[200:203], v[16:19]
	v_mfma_f32_16x16x32_bf16 v[4:7], v[144:147], v[208:211], v[4:7]
	v_mfma_f32_16x16x32_bf16 v[0:3], v[168:171], v[208:211], v[0:3]
	v_mfma_f32_16x16x32_bf16 v[52:55], v[148:151], v[180:183], v[52:55]
	v_mfma_f32_16x16x32_bf16 v[48:51], v[172:175], v[180:183], v[48:51]
	v_mfma_f32_16x16x32_bf16 v[36:39], v[148:151], v[196:199], v[36:39]
	v_mfma_f32_16x16x32_bf16 v[32:35], v[172:175], v[196:199], v[32:35]
	s_barrier
	v_mfma_f32_16x16x32_bf16 v[20:23], v[148:151], v[204:207], v[20:23]
	v_mfma_f32_16x16x32_bf16 v[16:19], v[172:175], v[204:207], v[16:19]
	v_mfma_f32_16x16x32_bf16 v[4:7], v[148:151], v[212:215], v[4:7]
	v_mfma_f32_16x16x32_bf16 v[0:3], v[172:175], v[212:215], v[0:3]
	s_setprio 0
	s_add_i32 s59, s59, 2
	s_add_u32 s43, s43, 0x100
	s_addc_u32 s58, s58, 0
	s_cmp_gt_u32 s59, 41
	s_mov_b64 s[36:37], s[44:45]
	s_cbranch_scc0 .LBB0_2040
	s_and_b64 vcc, exec, s[16:17]
	s_cbranch_vccz .LBB0_2043
	s_barrier

; #define PG8_STAGE(bufoff, gbase, voff) do { _Pragma("unroll") for (int _i = 0; _i < 2; ++_i) \
;         __builtin_amdgcn_global_load_lds((const unsigned*)((const char*)(gbase) + (voff)[_i]), (PG8_LAS unsigned*)(lds + (bufoff) + ldsw + _i * 8192), 16, 0, 0); } while (0)
; #define PG8_LDA(dst, b, h) do { _Pragma("unroll") for (int m = 0; m < 4; ++m) _Pragma("unroll") for (int k = 0; k < 2; ++k) dst[m][k] = *(const PG8_LAS bf16x8*)(lds + PG8_SA(b, h) + aoff + m * 2048 + k * 1024); } while (0)
; #define PG8_LDB(dst, b, h) do { _Pragma("unroll") for (int n = 0; n < 2; ++n) _Pragma("unroll") for (int k = 0; k < 2; ++k) dst[n][k] = *(const PG8_LAS bf16x8*)(lds + PG8_SB(b, h) + boff + n * 2048 + k * 1024); } while (0)
; #define PG8_MMA(ai, bj, At, Bt) do { __builtin_amdgcn_s_setprio(1); _Pragma("unroll") for (int m = 0; m < 4; ++m) _Pragma("unroll") for (int n = 0; n < 2; ++n) _Pragma("unroll") for (int k = 0; k < 2; ++k) \
;         acc[ai][bj][m][n] = mma16<F16>(Bt[n][k], At[m][k], acc[ai][bj][m][n]); __builtin_amdgcn_s_setprio(0); } while (0)
; #define PG8_WAIT_V(n) asm volatile("s_waitcnt vmcnt(" #n ")" ::: "memory")
; #define PG8_WAIT_L(n) asm volatile("s_waitcnt lgkmcnt(" #n ")" ::: "memory")
; #define PG8_BAR __builtin_amdgcn_s_barrier()
; #define PG8_SCHED __builtin_amdgcn_sched_barrier(0)
; template <class Epi, class Sched, bool ALIGN_EPI = false, bool SP2 = false, bool F16 = false>
; __device__ __forceinline__ void gemm_phase(PG8_LAS unsigned char* lds, const Gemm g, const Sched& S, const Epi& E, const int wid_in) {
;     ...
;             PG8_LDB(B0, 0, 0); PG8_LDB(B1, 0, 1); PG8_SCHED; PG8_LDA(At, 0, 0); PG8_STAGE(PG8_SA(1, 1), a1 + hstep, voffA);
;             PG8_WAIT_V(8); PG8_WAIT_L(0); PG8_BAR; PG8_MMA(0, 0, At, B0); PG8_MMA(0, 1, At, B1); PG8_BAR; PG8_SCHED;
;             PG8_LDA(At, 0, 1); PG8_STAGE(PG8_SB(0, 0), b2, voffB); PG8_STAGE(PG8_SB(0, 1), b2 + hstep, voffB); PG8_STAGE(PG8_SA(0, 0), a2, voffA);
;             PG8_WAIT_V(8); PG8_WAIT_L(0); PG8_BAR; PG8_MMA(1, 0, At, B0); PG8_MMA(1, 1, At, B1); PG8_BAR; PG8_SCHED;
.LBB0_2136:
	ds_read_b128 v[112:115], v235
	ds_read_b128 v[116:119], v235 offset:1024
	ds_read_b128 v[128:131], v235 offset:2048
	ds_read_b128 v[132:135], v235 offset:3072
	ds_read_b128 v[144:147], v236
	ds_read_b128 v[148:151], v236 offset:1024
	ds_read_b128 v[152:155], v236 offset:2048
	ds_read_b128 v[156:159], v236 offset:3072
	s_add_u32 s45, s52, 0xfffc0080
	s_addc_u32 s51, s53, -1
	s_cmp_eq_u32 s43, 12
	s_cselect_b32 s57, s14, s51
	s_cselect_b32 s56, s15, s45
	s_cselect_b32 s55, s37, s42
	s_cselect_b32 s54, s40, s41
	s_mov_b32 m0, s91
	v_lshl_add_u64 v[192:193], s[52:53], 0, v[204:205]
	ds_read_b128 v[160:163], v237
	ds_read_b128 v[164:167], v237 offset:1024
	ds_read_b128 v[168:171], v237 offset:2048
	ds_read_b128 v[172:175], v237 offset:3072
	ds_read_b128 v[176:179], v237 offset:4096
	ds_read_b128 v[180:183], v237 offset:5120
	ds_read_b128 v[184:187], v237 offset:6144
	ds_read_b128 v[188:191], v237 offset:7168
	global_load_lds_dwordx4 v[192:193], off
	v_lshl_add_u64 v[192:193], s[52:53], 0, v[206:207]
	s_add_i32 m0, s74, 0xe000
	s_nop 0
	global_load_lds_dwordx4 v[192:193], off
	s_waitcnt vmcnt(8)
	s_waitcnt lgkmcnt(0)
	s_barrier
	s_setprio 1
	s_waitcnt lgkmcnt(0)
	v_mfma_f32_16x16x32_f16 v[140:143], v[112:115], v[160:163], v[140:143]
	v_mfma_f32_16x16x32_f16 v[136:139], v[128:131], v[160:163], v[136:139]
	v_mfma_f32_16x16x32_f16 v[108:111], v[112:115], v[168:171], v[108:111]
	v_mfma_f32_16x16x32_f16 v[104:107], v[128:131], v[168:171], v[104:107]
	v_mfma_f32_16x16x32_f16 v[92:95], v[112:115], v[176:179], v[92:95]
	v_mfma_f32_16x16x32_f16 v[88:91], v[128:131], v[176:179], v[88:91]
	v_mfma_f32_16x16x32_f16 v[76:79], v[112:115], v[184:187], v[76:79]
	v_mfma_f32_16x16x32_f16 v[72:75], v[128:131], v[184:187], v[72:75]
	v_mfma_f32_16x16x32_f16 v[140:143], v[116:119], v[164:167], v[140:143]
	v_mfma_f32_16x16x32_f16 v[136:139], v[132:135], v[164:167], v[136:139]
	v_mfma_f32_16x16x32_f16 v[108:111], v[116:119], v[172:175], v[108:111]
	v_mfma_f32_16x16x32_f16 v[104:107], v[132:135], v[172:175], v[104:107]
	v_mfma_f32_16x16x32_f16 v[92:95], v[116:119], v[180:183], v[92:95]
	v_mfma_f32_16x16x32_f16 v[88:91], v[132:135], v[180:183], v[88:91]
	v_mfma_f32_16x16x32_f16 v[76:79], v[116:119], v[188:191], v[76:79]
	v_mfma_f32_16x16x32_f16 v[72:75], v[132:135], v[188:191], v[72:75]
	s_setprio 0
	s_setprio 1
	v_mfma_f32_16x16x32_f16 v[124:127], v[144:147], v[160:163], v[124:127]
	v_mfma_f32_16x16x32_f16 v[120:123], v[152:155], v[160:163], v[120:123]
	v_mfma_f32_16x16x32_f16 v[100:103], v[144:147], v[168:171], v[100:103]
	v_mfma_f32_16x16x32_f16 v[96:99], v[152:155], v[168:171], v[96:99]
	v_mfma_f32_16x16x32_f16 v[84:87], v[144:147], v[176:179], v[84:87]
	v_mfma_f32_16x16x32_f16 v[80:83], v[152:155], v[176:179], v[80:83]
	v_mfma_f32_16x16x32_f16 v[68:71], v[144:147], v[184:187], v[68:71]
	v_mfma_f32_16x16x32_f16 v[64:67], v[152:155], v[184:187], v[64:67]
	v_mfma_f32_16x16x32_f16 v[124:127], v[148:151], v[164:167], v[124:127]
	v_mfma_f32_16x16x32_f16 v[120:123], v[156:159], v[164:167], v[120:123]
	v_mfma_f32_16x16x32_f16 v[100:103], v[148:151], v[172:175], v[100:103]
	v_mfma_f32_16x16x32_f16 v[96:99], v[156:159], v[172:175], v[96:99]
	s_barrier
	v_mfma_f32_16x16x32_f16 v[84:87], v[148:151], v[180:183], v[84:87]
	v_mfma_f32_16x16x32_f16 v[80:83], v[156:159], v[180:183], v[80:83]
	v_mfma_f32_16x16x32_f16 v[68:71], v[148:151], v[188:191], v[68:71]
	v_mfma_f32_16x16x32_f16 v[64:67], v[156:159], v[188:191], v[64:67]
	s_setprio 0
	s_add_i32 s45, s63, s68
	v_lshl_add_u64 v[192:193], s[54:55], 0, v[198:199]
	s_mov_b32 m0, s45
	ds_read_b128 v[160:163], v237 offset:16384
	ds_read_b128 v[164:167], v237 offset:17408
	ds_read_b128 v[168:171], v237 offset:18432
	ds_read_b128 v[172:175], v237 offset:19456
	ds_read_b128 v[176:179], v237 offset:20480
	ds_read_b128 v[180:183], v237 offset:21504
	ds_read_b128 v[184:187], v237 offset:22528
	ds_read_b128 v[188:191], v237 offset:23552
	global_load_lds_dwordx4 v[192:193], off
	s_add_i32 m0, s45, 0x2000
	s_add_u32 s84, s54, 0x40000
	v_lshl_add_u64 v[194:195], s[54:55], 0, v[202:203]
	s_addc_u32 s85, s55, 0
	s_add_i32 s45, s64, s68
	global_load_lds_dwordx4 v[194:195], off
	v_lshl_add_u64 v[212:213], s[84:85], 0, v[198:199]
	s_mov_b32 m0, s45
	v_lshl_add_u64 v[214:215], s[56:57], 0, v[200:201]
	global_load_lds_dwordx4 v[212:213], off
	v_lshl_add_u64 v[212:213], s[84:85], 0, v[202:203]
	s_add_i32 m0, s45, 0x2000
	s_nop 0
	global_load_lds_dwordx4 v[212:213], off
	v_lshl_add_u64 v[212:213], s[56:57], 0, v[196:197]
	s_mov_b32 m0, s74
	s_nop 0
	global_load_lds_dwordx4 v[212:213], off
	s_mov_b32 m0, s66
	s_nop 0
	global_load_lds_dwordx4 v[214:215], off
	s_waitcnt vmcnt(8)
	s_waitcnt lgkmcnt(0)
	s_barrier
; #define PG8_STAGE(bufoff, gbase, voff) do { _Pragma("unroll") for (int _i = 0; _i < 2; ++_i) \
;         __builtin_amdgcn_global_load_lds((const unsigned*)((const char*)(gbase) + (voff)[_i]), (PG8_LAS unsigned*)(lds + (bufoff) + ldsw + _i * 8192), 16, 0, 0); } while (0)
; #define PG8_LDA(dst, b, h) do { _Pragma("unroll") for (int m = 0; m < 4; ++m) _Pragma("unroll") for (int k = 0; k < 2; ++k) dst[m][k] = *(const PG8_LAS bf16x8*)(lds + PG8_SA(b, h) + aoff + m * 2048 + k * 1024); } while (0)
; #define PG8_LDB(dst, b, h) do { _Pragma("unroll") for (int n = 0; n < 2; ++n) _Pragma("unroll") for (int k = 0; k < 2; ++k) dst[n][k] = *(const PG8_LAS bf16x8*)(lds + PG8_SB(b, h) + boff + n * 2048 + k * 1024); } while (0)
; #define PG8_MMA(ai, bj, At, Bt) do { __builtin_amdgcn_s_setprio(1); _Pragma("unroll") for (int m = 0; m < 4; ++m) _Pragma("unroll") for (int n = 0; n < 2; ++n) _Pragma("unroll") for (int k = 0; k < 2; ++k) \
;         acc[ai][bj][m][n] = mma16<F16>(Bt[n][k], At[m][k], acc[ai][bj][m][n]); __builtin_amdgcn_s_setprio(0); } while (0)
; #define PG8_WAIT_V(n) asm volatile("s_waitcnt vmcnt(" #n ")" ::: "memory")
; #define PG8_WAIT_L(n) asm volatile("s_waitcnt lgkmcnt(" #n ")" ::: "memory")
; #define PG8_BAR __builtin_amdgcn_s_barrier()
; #define PG8_SCHED __builtin_amdgcn_sched_barrier(0)
; template <class Epi, class Sched, bool ALIGN_EPI = false, bool SP2 = false, bool F16 = false>
; __device__ __forceinline__ void gemm_phase(PG8_LAS unsigned char* lds, const Gemm g, const Sched& S, const Epi& E, const int wid_in) {
;     ...
;             PG8_WAIT_V(8); PG8_WAIT_L(0); PG8_BAR; PG8_MMA(1, 0, At, B0); PG8_MMA(1, 1, At, B1); PG8_BAR; PG8_SCHED;
;             PG8_LDB(B0, 1, 0); PG8_LDB(B1, 1, 1); PG8_SCHED; PG8_LDA(At, 1, 0); PG8_STAGE(PG8_SA(0, 1), a2 + hstep, voffA);
;             PG8_WAIT_V(8); PG8_WAIT_L(0); PG8_BAR; PG8_MMA(0, 0, At, B0); PG8_MMA(0, 1, At, B1); PG8_BAR; PG8_SCHED;
	s_setprio 1
	s_waitcnt lgkmcnt(0)
	v_mfma_f32_16x16x32_f16 v[60:63], v[112:115], v[160:163], v[60:63]
	v_mfma_f32_16x16x32_f16 v[56:59], v[128:131], v[160:163], v[56:59]
	v_mfma_f32_16x16x32_f16 v[44:47], v[112:115], v[168:171], v[44:47]
	v_mfma_f32_16x16x32_f16 v[40:43], v[128:131], v[168:171], v[40:43]
	v_mfma_f32_16x16x32_f16 v[28:31], v[112:115], v[176:179], v[28:31]
	v_mfma_f32_16x16x32_f16 v[24:27], v[128:131], v[176:179], v[24:27]
	v_mfma_f32_16x16x32_f16 v[12:15], v[112:115], v[184:187], v[12:15]
	v_mfma_f32_16x16x32_f16 v[8:11], v[128:131], v[184:187], v[8:11]
	v_mfma_f32_16x16x32_f16 v[60:63], v[116:119], v[164:167], v[60:63]
	v_mfma_f32_16x16x32_f16 v[56:59], v[132:135], v[164:167], v[56:59]
	v_mfma_f32_16x16x32_f16 v[44:47], v[116:119], v[172:175], v[44:47]
	v_mfma_f32_16x16x32_f16 v[40:43], v[132:135], v[172:175], v[40:43]
	v_mfma_f32_16x16x32_f16 v[28:31], v[116:119], v[180:183], v[28:31]
	v_mfma_f32_16x16x32_f16 v[24:27], v[132:135], v[180:183], v[24:27]
	v_mfma_f32_16x16x32_f16 v[12:15], v[116:119], v[188:191], v[12:15]
	v_mfma_f32_16x16x32_f16 v[8:11], v[132:135], v[188:191], v[8:11]
	s_setprio 0
	s_setprio 1
	v_mfma_f32_16x16x32_f16 v[52:55], v[144:147], v[160:163], v[52:55]
	v_mfma_f32_16x16x32_f16 v[48:51], v[152:155], v[160:163], v[48:51]
	v_mfma_f32_16x16x32_f16 v[36:39], v[144:147], v[168:171], v[36:39]
	v_mfma_f32_16x16x32_f16 v[32:35], v[152:155], v[168:171], v[32:35]
	v_mfma_f32_16x16x32_f16 v[20:23], v[144:147], v[176:179], v[20:23]
	v_mfma_f32_16x16x32_f16 v[16:19], v[152:155], v[176:179], v[16:19]
	v_mfma_f32_16x16x32_f16 v[4:7], v[144:147], v[184:187], v[4:7]
	v_mfma_f32_16x16x32_f16 v[0:3], v[152:155], v[184:187], v[0:3]
	v_mfma_f32_16x16x32_f16 v[52:55], v[148:151], v[164:167], v[52:55]
	v_mfma_f32_16x16x32_f16 v[48:51], v[156:159], v[164:167], v[48:51]
	v_mfma_f32_16x16x32_f16 v[36:39], v[148:151], v[172:175], v[36:39]
	v_mfma_f32_16x16x32_f16 v[32:35], v[156:159], v[172:175], v[32:35]
	s_barrier
	v_mfma_f32_16x16x32_f16 v[20:23], v[148:151], v[180:183], v[20:23]
	v_mfma_f32_16x16x32_f16 v[16:19], v[156:159], v[180:183], v[16:19]
	v_mfma_f32_16x16x32_f16 v[4:7], v[148:151], v[188:191], v[4:7]
	v_mfma_f32_16x16x32_f16 v[0:3], v[156:159], v[188:191], v[0:3]
	s_setprio 0
	s_add_i32 s45, 0, 0x18000
	s_add_i32 s51, 0, 0x1c000
	v_add_u32_e32 v132, s45, v234
	v_add_u32_e32 v156, s51, v234
	ds_read_b128 v[112:115], v132
	ds_read_b128 v[116:119], v132 offset:1024
	ds_read_b128 v[128:131], v132 offset:2048
	ds_read_b128 v[132:135], v132 offset:3072
	ds_read_b128 v[144:147], v156
	ds_read_b128 v[148:151], v156 offset:1024
	ds_read_b128 v[152:155], v156 offset:2048
	ds_read_b128 v[156:159], v156 offset:3072
	s_add_u32 s56, s56, 0x40000
	s_addc_u32 s57, s57, 0
	s_mov_b32 m0, s90
	v_lshl_add_u64 v[216:217], s[56:57], 0, v[196:197]
	ds_read_b128 v[160:163], v237 offset:32768
	ds_read_b128 v[164:167], v237 offset:33792
	ds_read_b128 v[168:171], v237 offset:34816
	ds_read_b128 v[172:175], v237 offset:35840
	ds_read_b128 v[176:179], v237 offset:36864
	ds_read_b128 v[180:183], v237 offset:37888
	ds_read_b128 v[184:187], v237 offset:38912
	ds_read_b128 v[188:191], v237 offset:39936
	global_load_lds_dwordx4 v[216:217], off
	v_lshl_add_u64 v[216:217], s[56:57], 0, v[200:201]
	s_mov_b32 m0, s59
	s_nop 0
	global_load_lds_dwordx4 v[216:217], off
	s_waitcnt vmcnt(8)
	s_waitcnt lgkmcnt(0)
	s_barrier
	s_setprio 1
	s_waitcnt lgkmcnt(0)
	v_mfma_f32_16x16x32_f16 v[140:143], v[112:115], v[160:163], v[140:143]
	v_mfma_f32_16x16x32_f16 v[136:139], v[128:131], v[160:163], v[136:139]
	v_mfma_f32_16x16x32_f16 v[108:111], v[112:115], v[168:171], v[108:111]
	v_mfma_f32_16x16x32_f16 v[104:107], v[128:131], v[168:171], v[104:107]
	v_mfma_f32_16x16x32_f16 v[92:95], v[112:115], v[176:179], v[92:95]
	v_mfma_f32_16x16x32_f16 v[88:91], v[128:131], v[176:179], v[88:91]
	v_mfma_f32_16x16x32_f16 v[76:79], v[112:115], v[184:187], v[76:79]
	v_mfma_f32_16x16x32_f16 v[72:75], v[128:131], v[184:187], v[72:75]
	v_mfma_f32_16x16x32_f16 v[140:143], v[116:119], v[164:167], v[140:143]
	v_mfma_f32_16x16x32_f16 v[136:139], v[132:135], v[164:167], v[136:139]
	v_mfma_f32_16x16x32_f16 v[108:111], v[116:119], v[172:175], v[108:111]
	v_mfma_f32_16x16x32_f16 v[104:107], v[132:135], v[172:175], v[104:107]
	v_mfma_f32_16x16x32_f16 v[92:95], v[116:119], v[180:183], v[92:95]
	v_mfma_f32_16x16x32_f16 v[88:91], v[132:135], v[180:183], v[88:91]
	v_mfma_f32_16x16x32_f16 v[76:79], v[116:119], v[188:191], v[76:79]
	v_mfma_f32_16x16x32_f16 v[72:75], v[132:135], v[188:191], v[72:75]
	s_setprio 0
	s_setprio 1
	v_mfma_f32_16x16x32_f16 v[124:127], v[144:147], v[160:163], v[124:127]
	v_mfma_f32_16x16x32_f16 v[120:123], v[152:155], v[160:163], v[120:123]
	v_mfma_f32_16x16x32_f16 v[100:103], v[144:147], v[168:171], v[100:103]
	v_mfma_f32_16x16x32_f16 v[96:99], v[152:155], v[168:171], v[96:99]
	v_mfma_f32_16x16x32_f16 v[84:87], v[144:147], v[176:179], v[84:87]
	v_mfma_f32_16x16x32_f16 v[80:83], v[152:155], v[176:179], v[80:83]
	v_mfma_f32_16x16x32_f16 v[68:71], v[144:147], v[184:187], v[68:71]
	v_mfma_f32_16x16x32_f16 v[64:67], v[152:155], v[184:187], v[64:67]
	v_mfma_f32_16x16x32_f16 v[124:127], v[148:151], v[164:167], v[124:127]
	v_mfma_f32_16x16x32_f16 v[120:123], v[156:159], v[164:167], v[120:123]
	v_mfma_f32_16x16x32_f16 v[100:103], v[148:151], v[172:175], v[100:103]
	v_mfma_f32_16x16x32_f16 v[96:99], v[156:159], v[172:175], v[96:99]
	s_barrier
; #define PG8_STAGE(bufoff, gbase, voff) do { _Pragma("unroll") for (int _i = 0; _i < 2; ++_i) \
;         __builtin_amdgcn_global_load_lds((const unsigned*)((const char*)(gbase) + (voff)[_i]), (PG8_LAS unsigned*)(lds + (bufoff) + ldsw + _i * 8192), 16, 0, 0); } while (0)
; #define PG8_LDA(dst, b, h) do { _Pragma("unroll") for (int m = 0; m < 4; ++m) _Pragma("unroll") for (int k = 0; k < 2; ++k) dst[m][k] = *(const PG8_LAS bf16x8*)(lds + PG8_SA(b, h) + aoff + m * 2048 + k * 1024); } while (0)
; #define PG8_MMA(ai, bj, At, Bt) do { __builtin_amdgcn_s_setprio(1); _Pragma("unroll") for (int m = 0; m < 4; ++m) _Pragma("unroll") for (int n = 0; n < 2; ++n) _Pragma("unroll") for (int k = 0; k < 2; ++k) \
;         acc[ai][bj][m][n] = mma16<F16>(Bt[n][k], At[m][k], acc[ai][bj][m][n]); __builtin_amdgcn_s_setprio(0); } while (0)
; #define PG8_WAIT_V(n) asm volatile("s_waitcnt vmcnt(" #n ")" ::: "memory")
; #define PG8_WAIT_L(n) asm volatile("s_waitcnt lgkmcnt(" #n ")" ::: "memory")
; #define PG8_BAR __builtin_amdgcn_s_barrier()
; #define PG8_SCHED __builtin_amdgcn_sched_barrier(0)
; template <class Epi, class Sched, bool ALIGN_EPI = false, bool SP2 = false, bool F16 = false>
; __device__ __forceinline__ void gemm_phase(PG8_LAS unsigned char* lds, const Gemm g, const Sched& S, const Epi& E, const int wid_in) {
;     ...
;             PG8_WAIT_V(8); PG8_WAIT_L(0); PG8_BAR; PG8_MMA(0, 0, At, B0); PG8_MMA(0, 1, At, B1); PG8_BAR; PG8_SCHED;
;             PG8_LDA(At, 1, 1); PG8_STAGE(PG8_SB(1, 0), b3, voffB); PG8_STAGE(PG8_SB(1, 1), b3 + hstep, voffB); PG8_STAGE(PG8_SA(1, 0), a3, voffA);
;             PG8_WAIT_V(8); PG8_WAIT_L(0); PG8_BAR; PG8_MMA(1, 0, At, B0); PG8_MMA(1, 1, At, B1); PG8_BAR; PG8_SCHED;
	v_mfma_f32_16x16x32_f16 v[84:87], v[148:151], v[180:183], v[84:87]
	v_mfma_f32_16x16x32_f16 v[80:83], v[156:159], v[180:183], v[80:83]
	v_mfma_f32_16x16x32_f16 v[68:71], v[148:151], v[188:191], v[68:71]
	v_mfma_f32_16x16x32_f16 v[64:67], v[156:159], v[188:191], v[64:67]
	s_setprio 0
	s_add_i32 s45, s45, s68
	v_lshl_add_u64 v[192:193], v[192:193], 0, s[34:35]
	s_mov_b32 m0, s45
	ds_read_b128 v[160:163], v237 offset:49152
	ds_read_b128 v[164:167], v237 offset:50176
	ds_read_b128 v[168:171], v237 offset:51200
	ds_read_b128 v[172:175], v237 offset:52224
	ds_read_b128 v[176:179], v237 offset:53248
	ds_read_b128 v[180:183], v237 offset:54272
	ds_read_b128 v[184:187], v237 offset:55296
	ds_read_b128 v[188:191], v237 offset:56320
	global_load_lds_dwordx4 v[192:193], off
	s_add_i32 m0, s45, 0x2000
	s_add_u32 s54, s54, 0x40080
	v_lshl_add_u64 v[192:193], v[194:195], 0, s[34:35]
	s_addc_u32 s55, s55, 0
	s_add_i32 s45, s51, s68
	global_load_lds_dwordx4 v[192:193], off
	v_lshl_add_u64 v[192:193], s[54:55], 0, v[198:199]
	s_mov_b32 m0, s45
	s_nop 0
	global_load_lds_dwordx4 v[192:193], off
	v_lshl_add_u64 v[192:193], s[54:55], 0, v[202:203]
	s_add_i32 m0, s45, 0x2000
	s_nop 0
	global_load_lds_dwordx4 v[192:193], off
	v_lshl_add_u64 v[192:193], v[212:213], 0, s[34:35]
	s_mov_b32 m0, s75
	s_nop 0
	global_load_lds_dwordx4 v[192:193], off
	v_lshl_add_u64 v[192:193], v[214:215], 0, s[34:35]
	s_mov_b32 m0, s67
	s_nop 0
	global_load_lds_dwordx4 v[192:193], off
	s_waitcnt vmcnt(8)
	s_waitcnt lgkmcnt(0)
	s_barrier
	s_setprio 1
	s_waitcnt lgkmcnt(0)
	v_mfma_f32_16x16x32_f16 v[60:63], v[112:115], v[160:163], v[60:63]
	v_mfma_f32_16x16x32_f16 v[56:59], v[128:131], v[160:163], v[56:59]
	v_mfma_f32_16x16x32_f16 v[44:47], v[112:115], v[168:171], v[44:47]
	v_mfma_f32_16x16x32_f16 v[40:43], v[128:131], v[168:171], v[40:43]
	v_mfma_f32_16x16x32_f16 v[28:31], v[112:115], v[176:179], v[28:31]
	v_mfma_f32_16x16x32_f16 v[24:27], v[128:131], v[176:179], v[24:27]
	v_mfma_f32_16x16x32_f16 v[12:15], v[112:115], v[184:187], v[12:15]
	v_mfma_f32_16x16x32_f16 v[8:11], v[128:131], v[184:187], v[8:11]
	v_mfma_f32_16x16x32_f16 v[60:63], v[116:119], v[164:167], v[60:63]
	v_mfma_f32_16x16x32_f16 v[56:59], v[132:135], v[164:167], v[56:59]
	v_mfma_f32_16x16x32_f16 v[44:47], v[116:119], v[172:175], v[44:47]
	v_mfma_f32_16x16x32_f16 v[40:43], v[132:135], v[172:175], v[40:43]
	v_mfma_f32_16x16x32_f16 v[28:31], v[116:119], v[180:183], v[28:31]
	v_mfma_f32_16x16x32_f16 v[24:27], v[132:135], v[180:183], v[24:27]
	v_mfma_f32_16x16x32_f16 v[12:15], v[116:119], v[188:191], v[12:15]
	v_mfma_f32_16x16x32_f16 v[8:11], v[132:135], v[188:191], v[8:11]
	s_setprio 0
	s_setprio 1
	v_mfma_f32_16x16x32_f16 v[52:55], v[144:147], v[160:163], v[52:55]
	v_mfma_f32_16x16x32_f16 v[48:51], v[152:155], v[160:163], v[48:51]
	v_mfma_f32_16x16x32_f16 v[36:39], v[144:147], v[168:171], v[36:39]
	v_mfma_f32_16x16x32_f16 v[32:35], v[152:155], v[168:171], v[32:35]
	v_mfma_f32_16x16x32_f16 v[20:23], v[144:147], v[176:179], v[20:23]
	v_mfma_f32_16x16x32_f16 v[16:19], v[152:155], v[176:179], v[16:19]
	v_mfma_f32_16x16x32_f16 v[4:7], v[144:147], v[184:187], v[4:7]
	v_mfma_f32_16x16x32_f16 v[0:3], v[152:155], v[184:187], v[0:3]
	v_mfma_f32_16x16x32_f16 v[52:55], v[148:151], v[164:167], v[52:55]
	v_mfma_f32_16x16x32_f16 v[48:51], v[156:159], v[164:167], v[48:51]
	v_mfma_f32_16x16x32_f16 v[36:39], v[148:151], v[172:175], v[36:39]
	v_mfma_f32_16x16x32_f16 v[32:35], v[156:159], v[172:175], v[32:35]
	s_barrier
	v_mfma_f32_16x16x32_f16 v[20:23], v[148:151], v[180:183], v[20:23]
	v_mfma_f32_16x16x32_f16 v[16:19], v[156:159], v[180:183], v[16:19]
	v_mfma_f32_16x16x32_f16 v[4:7], v[148:151], v[188:191], v[4:7]
	v_mfma_f32_16x16x32_f16 v[0:3], v[156:159], v[188:191], v[0:3]
	s_setprio 0
	s_add_i32 s43, s43, 2
	s_add_u32 s52, s52, 0x100
	s_addc_u32 s53, s53, 0
	s_add_u32 s41, s41, 0x100
	s_addc_u32 s42, s42, 0
	s_cmp_gt_u32 s43, 13
	s_cbranch_scc0 .LBB0_2136
	s_and_b64 vcc, exec, s[16:17]
	s_cbranch_vccz .LBB0_2139
	s_barrier

; #define PG8_STAGE(bufoff, gbase, voff) do { _Pragma("unroll") for (int _i = 0; _i < 2; ++_i) \
;         __builtin_amdgcn_global_load_lds((const unsigned*)((const char*)(gbase) + (voff)[_i]), (PG8_LAS unsigned*)(lds + (bufoff) + ldsw + _i * 8192), 16, 0, 0); } while (0)
; #define PG8_LDA(dst, b, h) do { _Pragma("unroll") for (int m = 0; m < 4; ++m) _Pragma("unroll") for (int k = 0; k < 2; ++k) dst[m][k] = *(const PG8_LAS bf16x8*)(lds + PG8_SA(b, h) + aoff + m * 2048 + k * 1024); } while (0)
; #define PG8_LDB(dst, b, h) do { _Pragma("unroll") for (int n = 0; n < 2; ++n) _Pragma("unroll") for (int k = 0; k < 2; ++k) dst[n][k] = *(const PG8_LAS bf16x8*)(lds + PG8_SB(b, h) + boff + n * 2048 + k * 1024); } while (0)
; #define PG8_MMA(ai, bj, At, Bt) do { __builtin_amdgcn_s_setprio(1); _Pragma("unroll") for (int m = 0; m < 4; ++m) _Pragma("unroll") for (int n = 0; n < 2; ++n) _Pragma("unroll") for (int k = 0; k < 2; ++k) \
;         acc[ai][bj][m][n] = mma16<F16>(Bt[n][k], At[m][k], acc[ai][bj][m][n]); __builtin_amdgcn_s_setprio(0); } while (0)
; #define PG8_WAIT_V(n) asm volatile("s_waitcnt vmcnt(" #n ")" ::: "memory")
; #define PG8_WAIT_L(n) asm volatile("s_waitcnt lgkmcnt(" #n ")" ::: "memory")
; #define PG8_BAR __builtin_amdgcn_s_barrier()
; #define PG8_SCHED __builtin_amdgcn_sched_barrier(0)
; template <class Epi, class Sched, bool ALIGN_EPI = false, bool SP2 = false, bool F16 = false>
; __device__ __forceinline__ void gemm_phase(PG8_LAS unsigned char* lds, const Gemm g, const Sched& S, const Epi& E, const int wid_in) {
;     ...
;             PG8_LDB(B0, 0, 0); PG8_LDB(B1, 0, 1); PG8_SCHED; PG8_LDA(At, 0, 0); PG8_STAGE(PG8_SA(1, 1), a1 + hstep, voffA);
;             PG8_WAIT_V(8); PG8_WAIT_L(0); PG8_BAR; PG8_MMA(0, 0, At, B0); PG8_MMA(0, 1, At, B1); PG8_BAR; PG8_SCHED;
;             PG8_LDA(At, 0, 1); PG8_STAGE(PG8_SB(0, 0), b2, voffB); PG8_STAGE(PG8_SB(0, 1), b2 + hstep, voffB); PG8_STAGE(PG8_SA(0, 0), a2, voffA);
;             PG8_WAIT_V(8); PG8_WAIT_L(0); PG8_BAR; PG8_MMA(1, 0, At, B0); PG8_MMA(1, 1, At, B1); PG8_BAR; PG8_SCHED;
.LBB0_2226:
	ds_read_b128 v[128:131], v183
	ds_read_b128 v[132:135], v183 offset:1024
	ds_read_b128 v[136:139], v183 offset:2048
	ds_read_b128 v[140:143], v183 offset:3072
	ds_read_b128 v[144:147], v184
	ds_read_b128 v[148:151], v184 offset:1024
	ds_read_b128 v[152:155], v184 offset:2048
	ds_read_b128 v[174:177], v184 offset:3072
	s_add_u32 s43, s48, 0xfffc0080
	s_addc_u32 s50, s49, -1
	s_cmp_eq_u32 s42, 12
	s_cselect_b32 s53, s13, s50
	s_cselect_b32 s52, s23, s43
	s_cselect_b32 s51, s35, s41
	s_cselect_b32 s50, s37, s40
	s_mov_b32 m0, s91
	v_lshl_add_u64 v[178:179], s[48:49], 0, v[166:167]
	ds_read_b128 v[188:191], v185
	ds_read_b128 v[192:195], v185 offset:1024
	ds_read_b128 v[196:199], v185 offset:2048
	ds_read_b128 v[200:203], v185 offset:3072
	ds_read_b128 v[204:207], v185 offset:4096
	ds_read_b128 v[208:211], v185 offset:5120
	ds_read_b128 v[212:215], v185 offset:6144
	ds_read_b128 v[216:219], v185 offset:7168
	global_load_lds_dwordx4 v[178:179], off
	v_lshl_add_u64 v[178:179], s[48:49], 0, v[168:169]
	s_add_i32 m0, s74, 0xe000
	s_nop 0
	global_load_lds_dwordx4 v[178:179], off
	s_waitcnt vmcnt(8)
	s_waitcnt lgkmcnt(0)
	s_barrier
	s_setprio 1
	s_waitcnt lgkmcnt(0)
	v_mfma_f32_16x16x32_f16 v[124:127], v[128:131], v[188:191], v[124:127]
	v_mfma_f32_16x16x32_f16 v[120:123], v[136:139], v[188:191], v[120:123]
	v_mfma_f32_16x16x32_f16 v[108:111], v[128:131], v[196:199], v[108:111]
	v_mfma_f32_16x16x32_f16 v[104:107], v[136:139], v[196:199], v[104:107]
	v_mfma_f32_16x16x32_f16 v[92:95], v[128:131], v[204:207], v[92:95]
	v_mfma_f32_16x16x32_f16 v[88:91], v[136:139], v[204:207], v[88:91]
	v_mfma_f32_16x16x32_f16 v[76:79], v[128:131], v[212:215], v[76:79]
	v_mfma_f32_16x16x32_f16 v[72:75], v[136:139], v[212:215], v[72:75]
	v_mfma_f32_16x16x32_f16 v[124:127], v[132:135], v[192:195], v[124:127]
	v_mfma_f32_16x16x32_f16 v[120:123], v[140:143], v[192:195], v[120:123]
	v_mfma_f32_16x16x32_f16 v[108:111], v[132:135], v[200:203], v[108:111]
	v_mfma_f32_16x16x32_f16 v[104:107], v[140:143], v[200:203], v[104:107]
	v_mfma_f32_16x16x32_f16 v[92:95], v[132:135], v[208:211], v[92:95]
	v_mfma_f32_16x16x32_f16 v[88:91], v[140:143], v[208:211], v[88:91]
	v_mfma_f32_16x16x32_f16 v[76:79], v[132:135], v[216:219], v[76:79]
	v_mfma_f32_16x16x32_f16 v[72:75], v[140:143], v[216:219], v[72:75]
	s_setprio 0
	s_setprio 1
	v_mfma_f32_16x16x32_f16 v[116:119], v[144:147], v[188:191], v[116:119]
	v_mfma_f32_16x16x32_f16 v[112:115], v[152:155], v[188:191], v[112:115]
	v_mfma_f32_16x16x32_f16 v[100:103], v[144:147], v[196:199], v[100:103]
	v_mfma_f32_16x16x32_f16 v[96:99], v[152:155], v[196:199], v[96:99]
	v_mfma_f32_16x16x32_f16 v[84:87], v[144:147], v[204:207], v[84:87]
	v_mfma_f32_16x16x32_f16 v[80:83], v[152:155], v[204:207], v[80:83]
	v_mfma_f32_16x16x32_f16 v[68:71], v[144:147], v[212:215], v[68:71]
	v_mfma_f32_16x16x32_f16 v[64:67], v[152:155], v[212:215], v[64:67]
	v_mfma_f32_16x16x32_f16 v[116:119], v[148:151], v[192:195], v[116:119]
	v_mfma_f32_16x16x32_f16 v[112:115], v[174:177], v[192:195], v[112:115]
	v_mfma_f32_16x16x32_f16 v[100:103], v[148:151], v[200:203], v[100:103]
	v_mfma_f32_16x16x32_f16 v[96:99], v[174:177], v[200:203], v[96:99]
	s_barrier
	v_mfma_f32_16x16x32_f16 v[84:87], v[148:151], v[208:211], v[84:87]
	v_mfma_f32_16x16x32_f16 v[80:83], v[174:177], v[208:211], v[80:83]
	v_mfma_f32_16x16x32_f16 v[68:71], v[148:151], v[216:219], v[68:71]
	v_mfma_f32_16x16x32_f16 v[64:67], v[174:177], v[216:219], v[64:67]
	s_setprio 0
	s_add_i32 s43, s84, s68
	v_lshl_add_u64 v[178:179], s[50:51], 0, v[158:159]
	s_mov_b32 m0, s43
	ds_read_b128 v[188:191], v185 offset:16384
	ds_read_b128 v[192:195], v185 offset:17408
	ds_read_b128 v[196:199], v185 offset:18432
	ds_read_b128 v[200:203], v185 offset:19456
	ds_read_b128 v[204:207], v185 offset:20480
	ds_read_b128 v[208:211], v185 offset:21504
	ds_read_b128 v[212:215], v185 offset:22528
	ds_read_b128 v[216:219], v185 offset:23552
	global_load_lds_dwordx4 v[178:179], off
	s_add_i32 m0, s43, 0x2000
	s_add_u32 s54, s50, 0x40000
	v_lshl_add_u64 v[220:221], s[50:51], 0, v[162:163]
	s_addc_u32 s55, s51, 0
	s_add_i32 s43, s93, s68
	global_load_lds_dwordx4 v[220:221], off
	v_lshl_add_u64 v[222:223], s[54:55], 0, v[158:159]
	s_mov_b32 m0, s43
	v_lshl_add_u64 v[224:225], s[52:53], 0, v[160:161]
	global_load_lds_dwordx4 v[222:223], off
	v_lshl_add_u64 v[222:223], s[54:55], 0, v[162:163]
	s_add_i32 m0, s43, 0x2000
	s_nop 0
	global_load_lds_dwordx4 v[222:223], off
	v_lshl_add_u64 v[222:223], s[52:53], 0, v[156:157]
	s_mov_b32 m0, s74
	s_nop 0
	global_load_lds_dwordx4 v[222:223], off
	s_mov_b32 m0, s66
	s_nop 0
	global_load_lds_dwordx4 v[224:225], off
	s_waitcnt vmcnt(8)
	s_waitcnt lgkmcnt(0)
	s_barrier
; #define PG8_STAGE(bufoff, gbase, voff) do { _Pragma("unroll") for (int _i = 0; _i < 2; ++_i) \
;         __builtin_amdgcn_global_load_lds((const unsigned*)((const char*)(gbase) + (voff)[_i]), (PG8_LAS unsigned*)(lds + (bufoff) + ldsw + _i * 8192), 16, 0, 0); } while (0)
; #define PG8_LDA(dst, b, h) do { _Pragma("unroll") for (int m = 0; m < 4; ++m) _Pragma("unroll") for (int k = 0; k < 2; ++k) dst[m][k] = *(const PG8_LAS bf16x8*)(lds + PG8_SA(b, h) + aoff + m * 2048 + k * 1024); } while (0)
; #define PG8_LDB(dst, b, h) do { _Pragma("unroll") for (int n = 0; n < 2; ++n) _Pragma("unroll") for (int k = 0; k < 2; ++k) dst[n][k] = *(const PG8_LAS bf16x8*)(lds + PG8_SB(b, h) + boff + n * 2048 + k * 1024); } while (0)
; #define PG8_MMA(ai, bj, At, Bt) do { __builtin_amdgcn_s_setprio(1); _Pragma("unroll") for (int m = 0; m < 4; ++m) _Pragma("unroll") for (int n = 0; n < 2; ++n) _Pragma("unroll") for (int k = 0; k < 2; ++k) \
;         acc[ai][bj][m][n] = mma16<F16>(Bt[n][k], At[m][k], acc[ai][bj][m][n]); __builtin_amdgcn_s_setprio(0); } while (0)
; #define PG8_WAIT_V(n) asm volatile("s_waitcnt vmcnt(" #n ")" ::: "memory")
; #define PG8_WAIT_L(n) asm volatile("s_waitcnt lgkmcnt(" #n ")" ::: "memory")
; #define PG8_BAR __builtin_amdgcn_s_barrier()
; #define PG8_SCHED __builtin_amdgcn_sched_barrier(0)
; template <class Epi, class Sched, bool ALIGN_EPI = false, bool SP2 = false, bool F16 = false>
; __device__ __forceinline__ void gemm_phase(PG8_LAS unsigned char* lds, const Gemm g, const Sched& S, const Epi& E, const int wid_in) {
;     ...
;             PG8_WAIT_V(8); PG8_WAIT_L(0); PG8_BAR; PG8_MMA(1, 0, At, B0); PG8_MMA(1, 1, At, B1); PG8_BAR; PG8_SCHED;
;             PG8_LDB(B0, 1, 0); PG8_LDB(B1, 1, 1); PG8_SCHED; PG8_LDA(At, 1, 0); PG8_STAGE(PG8_SA(0, 1), a2 + hstep, voffA);
;             PG8_WAIT_V(8); PG8_WAIT_L(0); PG8_BAR; PG8_MMA(0, 0, At, B0); PG8_MMA(0, 1, At, B1); PG8_BAR; PG8_SCHED;
	s_setprio 1
	s_waitcnt lgkmcnt(0)
	v_mfma_f32_16x16x32_f16 v[60:63], v[128:131], v[188:191], v[60:63]
	v_mfma_f32_16x16x32_f16 v[56:59], v[136:139], v[188:191], v[56:59]
	v_mfma_f32_16x16x32_f16 v[44:47], v[128:131], v[196:199], v[44:47]
	v_mfma_f32_16x16x32_f16 v[40:43], v[136:139], v[196:199], v[40:43]
	v_mfma_f32_16x16x32_f16 v[28:31], v[128:131], v[204:207], v[28:31]
	v_mfma_f32_16x16x32_f16 v[24:27], v[136:139], v[204:207], v[24:27]
	v_mfma_f32_16x16x32_f16 v[12:15], v[128:131], v[212:215], v[12:15]
	v_mfma_f32_16x16x32_f16 v[8:11], v[136:139], v[212:215], v[8:11]
	v_mfma_f32_16x16x32_f16 v[60:63], v[132:135], v[192:195], v[60:63]
	v_mfma_f32_16x16x32_f16 v[56:59], v[140:143], v[192:195], v[56:59]
	v_mfma_f32_16x16x32_f16 v[44:47], v[132:135], v[200:203], v[44:47]
	v_mfma_f32_16x16x32_f16 v[40:43], v[140:143], v[200:203], v[40:43]
	v_mfma_f32_16x16x32_f16 v[28:31], v[132:135], v[208:211], v[28:31]
	v_mfma_f32_16x16x32_f16 v[24:27], v[140:143], v[208:211], v[24:27]
	v_mfma_f32_16x16x32_f16 v[12:15], v[132:135], v[216:219], v[12:15]
	v_mfma_f32_16x16x32_f16 v[8:11], v[140:143], v[216:219], v[8:11]
	s_setprio 0
	s_setprio 1
	v_mfma_f32_16x16x32_f16 v[52:55], v[144:147], v[188:191], v[52:55]
	v_mfma_f32_16x16x32_f16 v[48:51], v[152:155], v[188:191], v[48:51]
	v_mfma_f32_16x16x32_f16 v[36:39], v[144:147], v[196:199], v[36:39]
	v_mfma_f32_16x16x32_f16 v[32:35], v[152:155], v[196:199], v[32:35]
	v_mfma_f32_16x16x32_f16 v[20:23], v[144:147], v[204:207], v[20:23]
	v_mfma_f32_16x16x32_f16 v[16:19], v[152:155], v[204:207], v[16:19]
	v_mfma_f32_16x16x32_f16 v[4:7], v[144:147], v[212:215], v[4:7]
	v_mfma_f32_16x16x32_f16 v[0:3], v[152:155], v[212:215], v[0:3]
	v_mfma_f32_16x16x32_f16 v[52:55], v[148:151], v[192:195], v[52:55]
	v_mfma_f32_16x16x32_f16 v[48:51], v[174:177], v[192:195], v[48:51]
	v_mfma_f32_16x16x32_f16 v[36:39], v[148:151], v[200:203], v[36:39]
	v_mfma_f32_16x16x32_f16 v[32:35], v[174:177], v[200:203], v[32:35]
	s_barrier
	v_mfma_f32_16x16x32_f16 v[20:23], v[148:151], v[208:211], v[20:23]
	v_mfma_f32_16x16x32_f16 v[16:19], v[174:177], v[208:211], v[16:19]
	v_mfma_f32_16x16x32_f16 v[4:7], v[148:151], v[216:219], v[4:7]
	v_mfma_f32_16x16x32_f16 v[0:3], v[174:177], v[216:219], v[0:3]
	s_setprio 0
	s_add_i32 s43, 0, 0x18000
	s_add_i32 s54, 0, 0x1c000
	v_add_u32_e32 v140, s43, v182
	v_add_u32_e32 v165, s54, v182
	ds_read_b128 v[128:131], v140
	ds_read_b128 v[132:135], v140 offset:1024
	ds_read_b128 v[136:139], v140 offset:2048
	ds_read_b128 v[140:143], v140 offset:3072
	ds_read_b128 v[144:147], v165
	ds_read_b128 v[148:151], v165 offset:1024
	ds_read_b128 v[152:155], v165 offset:2048
	ds_read_b128 v[174:177], v165 offset:3072
	s_add_u32 s52, s52, 0x40000
	s_addc_u32 s53, s53, 0
	s_mov_b32 m0, s90
	v_lshl_add_u64 v[226:227], s[52:53], 0, v[156:157]
	ds_read_b128 v[188:191], v185 offset:32768
	ds_read_b128 v[192:195], v185 offset:33792
	ds_read_b128 v[196:199], v185 offset:34816
	ds_read_b128 v[200:203], v185 offset:35840
	ds_read_b128 v[204:207], v185 offset:36864
	ds_read_b128 v[208:211], v185 offset:37888
	ds_read_b128 v[212:215], v185 offset:38912
	ds_read_b128 v[216:219], v185 offset:39936
	global_load_lds_dwordx4 v[226:227], off
	v_lshl_add_u64 v[226:227], s[52:53], 0, v[160:161]
	s_mov_b32 m0, s63
	s_nop 0
	global_load_lds_dwordx4 v[226:227], off
	s_waitcnt vmcnt(8)
	s_waitcnt lgkmcnt(0)
	s_barrier
	s_setprio 1
	s_waitcnt lgkmcnt(0)
	v_mfma_f32_16x16x32_f16 v[124:127], v[128:131], v[188:191], v[124:127]
	v_mfma_f32_16x16x32_f16 v[120:123], v[136:139], v[188:191], v[120:123]
	v_mfma_f32_16x16x32_f16 v[108:111], v[128:131], v[196:199], v[108:111]
	v_mfma_f32_16x16x32_f16 v[104:107], v[136:139], v[196:199], v[104:107]
	v_mfma_f32_16x16x32_f16 v[92:95], v[128:131], v[204:207], v[92:95]
	v_mfma_f32_16x16x32_f16 v[88:91], v[136:139], v[204:207], v[88:91]
	v_mfma_f32_16x16x32_f16 v[76:79], v[128:131], v[212:215], v[76:79]
	v_mfma_f32_16x16x32_f16 v[72:75], v[136:139], v[212:215], v[72:75]
	v_mfma_f32_16x16x32_f16 v[124:127], v[132:135], v[192:195], v[124:127]
	v_mfma_f32_16x16x32_f16 v[120:123], v[140:143], v[192:195], v[120:123]
	v_mfma_f32_16x16x32_f16 v[108:111], v[132:135], v[200:203], v[108:111]
	v_mfma_f32_16x16x32_f16 v[104:107], v[140:143], v[200:203], v[104:107]
	v_mfma_f32_16x16x32_f16 v[92:95], v[132:135], v[208:211], v[92:95]
	v_mfma_f32_16x16x32_f16 v[88:91], v[140:143], v[208:211], v[88:91]
	v_mfma_f32_16x16x32_f16 v[76:79], v[132:135], v[216:219], v[76:79]
	v_mfma_f32_16x16x32_f16 v[72:75], v[140:143], v[216:219], v[72:75]
	s_setprio 0
	s_setprio 1
	v_mfma_f32_16x16x32_f16 v[116:119], v[144:147], v[188:191], v[116:119]
	v_mfma_f32_16x16x32_f16 v[112:115], v[152:155], v[188:191], v[112:115]
	v_mfma_f32_16x16x32_f16 v[100:103], v[144:147], v[196:199], v[100:103]
	v_mfma_f32_16x16x32_f16 v[96:99], v[152:155], v[196:199], v[96:99]
	v_mfma_f32_16x16x32_f16 v[84:87], v[144:147], v[204:207], v[84:87]
	v_mfma_f32_16x16x32_f16 v[80:83], v[152:155], v[204:207], v[80:83]
	v_mfma_f32_16x16x32_f16 v[68:71], v[144:147], v[212:215], v[68:71]
	v_mfma_f32_16x16x32_f16 v[64:67], v[152:155], v[212:215], v[64:67]
	v_mfma_f32_16x16x32_f16 v[116:119], v[148:151], v[192:195], v[116:119]
	v_mfma_f32_16x16x32_f16 v[112:115], v[174:177], v[192:195], v[112:115]
	v_mfma_f32_16x16x32_f16 v[100:103], v[148:151], v[200:203], v[100:103]
	v_mfma_f32_16x16x32_f16 v[96:99], v[174:177], v[200:203], v[96:99]
	s_barrier
; #define PG8_STAGE(bufoff, gbase, voff) do { _Pragma("unroll") for (int _i = 0; _i < 2; ++_i) \
;         __builtin_amdgcn_global_load_lds((const unsigned*)((const char*)(gbase) + (voff)[_i]), (PG8_LAS unsigned*)(lds + (bufoff) + ldsw + _i * 8192), 16, 0, 0); } while (0)
; #define PG8_LDA(dst, b, h) do { _Pragma("unroll") for (int m = 0; m < 4; ++m) _Pragma("unroll") for (int k = 0; k < 2; ++k) dst[m][k] = *(const PG8_LAS bf16x8*)(lds + PG8_SA(b, h) + aoff + m * 2048 + k * 1024); } while (0)
; #define PG8_MMA(ai, bj, At, Bt) do { __builtin_amdgcn_s_setprio(1); _Pragma("unroll") for (int m = 0; m < 4; ++m) _Pragma("unroll") for (int n = 0; n < 2; ++n) _Pragma("unroll") for (int k = 0; k < 2; ++k) \
;         acc[ai][bj][m][n] = mma16<F16>(Bt[n][k], At[m][k], acc[ai][bj][m][n]); __builtin_amdgcn_s_setprio(0); } while (0)
; #define PG8_WAIT_V(n) asm volatile("s_waitcnt vmcnt(" #n ")" ::: "memory")
; #define PG8_WAIT_L(n) asm volatile("s_waitcnt lgkmcnt(" #n ")" ::: "memory")
; #define PG8_BAR __builtin_amdgcn_s_barrier()
; #define PG8_SCHED __builtin_amdgcn_sched_barrier(0)
; template <class Epi, class Sched, bool ALIGN_EPI = false, bool SP2 = false, bool F16 = false>
; __device__ __forceinline__ void gemm_phase(PG8_LAS unsigned char* lds, const Gemm g, const Sched& S, const Epi& E, const int wid_in) {
;     ...
;             PG8_WAIT_V(8); PG8_WAIT_L(0); PG8_BAR; PG8_MMA(0, 0, At, B0); PG8_MMA(0, 1, At, B1); PG8_BAR; PG8_SCHED;
;             PG8_LDA(At, 1, 1); PG8_STAGE(PG8_SB(1, 0), b3, voffB); PG8_STAGE(PG8_SB(1, 1), b3 + hstep, voffB); PG8_STAGE(PG8_SA(1, 0), a3, voffA);
;             PG8_WAIT_V(8); PG8_WAIT_L(0); PG8_BAR; PG8_MMA(1, 0, At, B0); PG8_MMA(1, 1, At, B1); PG8_BAR; PG8_SCHED;
	v_mfma_f32_16x16x32_f16 v[84:87], v[148:151], v[208:211], v[84:87]
	v_mfma_f32_16x16x32_f16 v[80:83], v[174:177], v[208:211], v[80:83]
	v_mfma_f32_16x16x32_f16 v[68:71], v[148:151], v[216:219], v[68:71]
	v_mfma_f32_16x16x32_f16 v[64:67], v[174:177], v[216:219], v[64:67]
	s_setprio 0
	s_add_i32 s43, s43, s68
	v_lshl_add_u64 v[178:179], v[178:179], 0, s[26:27]
	s_mov_b32 m0, s43
	ds_read_b128 v[188:191], v185 offset:49152
	ds_read_b128 v[192:195], v185 offset:50176
	ds_read_b128 v[196:199], v185 offset:51200
	ds_read_b128 v[200:203], v185 offset:52224
	ds_read_b128 v[204:207], v185 offset:53248
	ds_read_b128 v[208:211], v185 offset:54272
	ds_read_b128 v[212:215], v185 offset:55296
	ds_read_b128 v[216:219], v185 offset:56320
	global_load_lds_dwordx4 v[178:179], off
	s_add_i32 m0, s43, 0x2000
	s_add_u32 s50, s50, 0x40080
	v_lshl_add_u64 v[178:179], v[220:221], 0, s[26:27]
	s_addc_u32 s51, s51, 0
	s_add_i32 s43, s54, s68
	global_load_lds_dwordx4 v[178:179], off
	v_lshl_add_u64 v[178:179], s[50:51], 0, v[158:159]
	s_mov_b32 m0, s43
	s_nop 0
	global_load_lds_dwordx4 v[178:179], off
	v_lshl_add_u64 v[178:179], s[50:51], 0, v[162:163]
	s_add_i32 m0, s43, 0x2000
	s_nop 0
	global_load_lds_dwordx4 v[178:179], off
	v_lshl_add_u64 v[178:179], v[222:223], 0, s[26:27]
	s_mov_b32 m0, s75
	s_nop 0
	global_load_lds_dwordx4 v[178:179], off
	v_lshl_add_u64 v[178:179], v[224:225], 0, s[26:27]
	s_mov_b32 m0, s67
	s_nop 0
	global_load_lds_dwordx4 v[178:179], off
	s_waitcnt vmcnt(8)
	s_waitcnt lgkmcnt(0)
	s_barrier
	s_setprio 1
	s_waitcnt lgkmcnt(0)
	v_mfma_f32_16x16x32_f16 v[60:63], v[128:131], v[188:191], v[60:63]
	v_mfma_f32_16x16x32_f16 v[56:59], v[136:139], v[188:191], v[56:59]
	v_mfma_f32_16x16x32_f16 v[44:47], v[128:131], v[196:199], v[44:47]
	v_mfma_f32_16x16x32_f16 v[40:43], v[136:139], v[196:199], v[40:43]
	v_mfma_f32_16x16x32_f16 v[28:31], v[128:131], v[204:207], v[28:31]
	v_mfma_f32_16x16x32_f16 v[24:27], v[136:139], v[204:207], v[24:27]
	v_mfma_f32_16x16x32_f16 v[12:15], v[128:131], v[212:215], v[12:15]
	v_mfma_f32_16x16x32_f16 v[8:11], v[136:139], v[212:215], v[8:11]
	v_mfma_f32_16x16x32_f16 v[60:63], v[132:135], v[192:195], v[60:63]
	v_mfma_f32_16x16x32_f16 v[56:59], v[140:143], v[192:195], v[56:59]
	v_mfma_f32_16x16x32_f16 v[44:47], v[132:135], v[200:203], v[44:47]
	v_mfma_f32_16x16x32_f16 v[40:43], v[140:143], v[200:203], v[40:43]
	v_mfma_f32_16x16x32_f16 v[28:31], v[132:135], v[208:211], v[28:31]
	v_mfma_f32_16x16x32_f16 v[24:27], v[140:143], v[208:211], v[24:27]
	v_mfma_f32_16x16x32_f16 v[12:15], v[132:135], v[216:219], v[12:15]
	v_mfma_f32_16x16x32_f16 v[8:11], v[140:143], v[216:219], v[8:11]
	s_setprio 0
	s_setprio 1
	v_mfma_f32_16x16x32_f16 v[52:55], v[144:147], v[188:191], v[52:55]
	v_mfma_f32_16x16x32_f16 v[48:51], v[152:155], v[188:191], v[48:51]
	v_mfma_f32_16x16x32_f16 v[36:39], v[144:147], v[196:199], v[36:39]
	v_mfma_f32_16x16x32_f16 v[32:35], v[152:155], v[196:199], v[32:35]
	v_mfma_f32_16x16x32_f16 v[20:23], v[144:147], v[204:207], v[20:23]
	v_mfma_f32_16x16x32_f16 v[16:19], v[152:155], v[204:207], v[16:19]
	v_mfma_f32_16x16x32_f16 v[4:7], v[144:147], v[212:215], v[4:7]
	v_mfma_f32_16x16x32_f16 v[0:3], v[152:155], v[212:215], v[0:3]
	v_mfma_f32_16x16x32_f16 v[52:55], v[148:151], v[192:195], v[52:55]
	v_mfma_f32_16x16x32_f16 v[48:51], v[174:177], v[192:195], v[48:51]
	v_mfma_f32_16x16x32_f16 v[36:39], v[148:151], v[200:203], v[36:39]
	v_mfma_f32_16x16x32_f16 v[32:35], v[174:177], v[200:203], v[32:35]
	s_barrier
	v_mfma_f32_16x16x32_f16 v[20:23], v[148:151], v[208:211], v[20:23]
	v_mfma_f32_16x16x32_f16 v[16:19], v[174:177], v[208:211], v[16:19]
	v_mfma_f32_16x16x32_f16 v[4:7], v[148:151], v[216:219], v[4:7]
	v_mfma_f32_16x16x32_f16 v[0:3], v[174:177], v[216:219], v[0:3]
	s_setprio 0
	s_add_i32 s42, s42, 2
	s_add_u32 s48, s48, 0x100
	s_addc_u32 s49, s49, 0
	s_add_u32 s40, s40, 0x100
	s_addc_u32 s41, s41, 0
	s_cmp_gt_u32 s42, 13
	s_cbranch_scc0 .LBB0_2226
	s_and_b64 vcc, exec, s[16:17]
	s_cbranch_vccz .LBB0_2229
	s_barrier

; #define PG8_STAGE(bufoff, gbase, voff) do { _Pragma("unroll") for (int _i = 0; _i < 2; ++_i) \
;         __builtin_amdgcn_global_load_lds((const unsigned*)((const char*)(gbase) + (voff)[_i]), (PG8_LAS unsigned*)(lds + (bufoff) + ldsw + _i * 8192), 16, 0, 0); } while (0)
; #define PG8_LDA(dst, b, h) do { _Pragma("unroll") for (int m = 0; m < 4; ++m) _Pragma("unroll") for (int k = 0; k < 2; ++k) dst[m][k] = *(const PG8_LAS bf16x8*)(lds + PG8_SA(b, h) + aoff + m * 2048 + k * 1024); } while (0)
; #define PG8_LDB(dst, b, h) do { _Pragma("unroll") for (int n = 0; n < 2; ++n) _Pragma("unroll") for (int k = 0; k < 2; ++k) dst[n][k] = *(const PG8_LAS bf16x8*)(lds + PG8_SB(b, h) + boff + n * 2048 + k * 1024); } while (0)
; #define PG8_MMA(ai, bj, At, Bt) do { __builtin_amdgcn_s_setprio(1); _Pragma("unroll") for (int m = 0; m < 4; ++m) _Pragma("unroll") for (int n = 0; n < 2; ++n) _Pragma("unroll") for (int k = 0; k < 2; ++k) \
;         acc[ai][bj][m][n] = mma16<F16>(Bt[n][k], At[m][k], acc[ai][bj][m][n]); __builtin_amdgcn_s_setprio(0); } while (0)
; #define PG8_WAIT_V(n) asm volatile("s_waitcnt vmcnt(" #n ")" ::: "memory")
; #define PG8_WAIT_L(n) asm volatile("s_waitcnt lgkmcnt(" #n ")" ::: "memory")
; #define PG8_BAR __builtin_amdgcn_s_barrier()
; #define PG8_SCHED __builtin_amdgcn_sched_barrier(0)
; template <class Epi, class Sched, bool ALIGN_EPI = false, bool SP2 = false, bool F16 = false>
; __device__ __forceinline__ void gemm_phase(PG8_LAS unsigned char* lds, const Gemm g, const Sched& S, const Epi& E, const int wid_in) {
;     ...
;             PG8_LDB(B0, 0, 0); PG8_LDB(B1, 0, 1); PG8_SCHED; PG8_LDA(At, 0, 0); PG8_STAGE(PG8_SA(1, 1), a1 + hstep, voffA);
;             PG8_WAIT_V(8); PG8_WAIT_L(0); PG8_BAR; PG8_MMA(0, 0, At, B0); PG8_MMA(0, 1, At, B1); PG8_BAR; PG8_SCHED;
;             PG8_LDA(At, 0, 1); PG8_STAGE(PG8_SB(0, 0), b2, voffB); PG8_STAGE(PG8_SB(0, 1), b2 + hstep, voffB); PG8_STAGE(PG8_SA(0, 0), a2, voffA);
;             PG8_WAIT_V(8); PG8_WAIT_L(0); PG8_BAR; PG8_MMA(1, 0, At, B0); PG8_MMA(1, 1, At, B1); PG8_BAR; PG8_SCHED;
.LBB0_2489:
	ds_read_b128 v[128:131], v189
	ds_read_b128 v[132:135], v189 offset:1024
	ds_read_b128 v[136:139], v189 offset:2048
	ds_read_b128 v[140:143], v189 offset:3072
	ds_read_b128 v[144:147], v190
	ds_read_b128 v[148:151], v190 offset:1024
	ds_read_b128 v[168:171], v190 offset:2048
	ds_read_b128 v[172:175], v190 offset:3072
	s_add_u32 s44, s42, 0xfffc0080
	s_addc_u32 s45, s43, -1
	s_cmp_eq_u32 s59, 12
	s_cselect_b32 s47, s29, s45
	s_cselect_b32 s46, s37, s44
	s_cselect_b32 s45, s27, s58
	s_cselect_b32 s44, s56, s57
	s_mov_b32 m0, s91
	v_lshl_add_u64 v[184:185], s[42:43], 0, v[160:161]
	ds_read_b128 v[176:179], v191
	ds_read_b128 v[180:183], v191 offset:1024
	ds_read_b128 v[192:195], v191 offset:2048
	ds_read_b128 v[196:199], v191 offset:3072
	ds_read_b128 v[200:203], v191 offset:4096
	ds_read_b128 v[204:207], v191 offset:5120
	ds_read_b128 v[208:211], v191 offset:6144
	ds_read_b128 v[212:215], v191 offset:7168
	global_load_lds_dwordx4 v[184:185], off
	v_lshl_add_u64 v[184:185], s[42:43], 0, v[162:163]
	s_add_i32 m0, s74, 0xe000
	s_nop 0
	global_load_lds_dwordx4 v[184:185], off
	s_waitcnt vmcnt(8)
	s_waitcnt lgkmcnt(0)
	s_barrier
	s_setprio 1
	s_waitcnt lgkmcnt(0)
	v_mfma_f32_16x16x32_bf16 v[124:127], v[128:131], v[176:179], v[124:127]
	v_mfma_f32_16x16x32_bf16 v[120:123], v[136:139], v[176:179], v[120:123]
	v_mfma_f32_16x16x32_bf16 v[108:111], v[128:131], v[192:195], v[108:111]
	v_mfma_f32_16x16x32_bf16 v[104:107], v[136:139], v[192:195], v[104:107]
	v_mfma_f32_16x16x32_bf16 v[92:95], v[128:131], v[200:203], v[92:95]
	v_mfma_f32_16x16x32_bf16 v[88:91], v[136:139], v[200:203], v[88:91]
	v_mfma_f32_16x16x32_bf16 v[76:79], v[128:131], v[208:211], v[76:79]
	v_mfma_f32_16x16x32_bf16 v[72:75], v[136:139], v[208:211], v[72:75]
	v_mfma_f32_16x16x32_bf16 v[124:127], v[132:135], v[180:183], v[124:127]
	v_mfma_f32_16x16x32_bf16 v[120:123], v[140:143], v[180:183], v[120:123]
	v_mfma_f32_16x16x32_bf16 v[108:111], v[132:135], v[196:199], v[108:111]
	v_mfma_f32_16x16x32_bf16 v[104:107], v[140:143], v[196:199], v[104:107]
	v_mfma_f32_16x16x32_bf16 v[92:95], v[132:135], v[204:207], v[92:95]
	v_mfma_f32_16x16x32_bf16 v[88:91], v[140:143], v[204:207], v[88:91]
	v_mfma_f32_16x16x32_bf16 v[76:79], v[132:135], v[212:215], v[76:79]
	v_mfma_f32_16x16x32_bf16 v[72:75], v[140:143], v[212:215], v[72:75]
	s_setprio 0
	s_setprio 1
	v_mfma_f32_16x16x32_bf16 v[116:119], v[144:147], v[176:179], v[116:119]
	v_mfma_f32_16x16x32_bf16 v[112:115], v[168:171], v[176:179], v[112:115]
	v_mfma_f32_16x16x32_bf16 v[100:103], v[144:147], v[192:195], v[100:103]
	v_mfma_f32_16x16x32_bf16 v[96:99], v[168:171], v[192:195], v[96:99]
	v_mfma_f32_16x16x32_bf16 v[84:87], v[144:147], v[200:203], v[84:87]
	v_mfma_f32_16x16x32_bf16 v[80:83], v[168:171], v[200:203], v[80:83]
	v_mfma_f32_16x16x32_bf16 v[68:71], v[144:147], v[208:211], v[68:71]
	v_mfma_f32_16x16x32_bf16 v[64:67], v[168:171], v[208:211], v[64:67]
	v_mfma_f32_16x16x32_bf16 v[116:119], v[148:151], v[180:183], v[116:119]
	v_mfma_f32_16x16x32_bf16 v[112:115], v[172:175], v[180:183], v[112:115]
	v_mfma_f32_16x16x32_bf16 v[100:103], v[148:151], v[196:199], v[100:103]
	v_mfma_f32_16x16x32_bf16 v[96:99], v[172:175], v[196:199], v[96:99]
	s_barrier
	v_mfma_f32_16x16x32_bf16 v[84:87], v[148:151], v[204:207], v[84:87]
	v_mfma_f32_16x16x32_bf16 v[80:83], v[172:175], v[204:207], v[80:83]
	v_mfma_f32_16x16x32_bf16 v[68:71], v[148:151], v[212:215], v[68:71]
	v_mfma_f32_16x16x32_bf16 v[64:67], v[172:175], v[212:215], v[64:67]
	s_setprio 0
	s_add_i32 s60, s53, s68
	v_lshl_add_u64 v[184:185], s[44:45], 0, v[154:155]
	s_mov_b32 m0, s60
	ds_read_b128 v[176:179], v191 offset:16384
	ds_read_b128 v[180:183], v191 offset:17408
	ds_read_b128 v[192:195], v191 offset:18432
	ds_read_b128 v[196:199], v191 offset:19456
	ds_read_b128 v[200:203], v191 offset:20480
	ds_read_b128 v[204:207], v191 offset:21504
	ds_read_b128 v[208:211], v191 offset:22528
	ds_read_b128 v[212:215], v191 offset:23552
	global_load_lds_dwordx4 v[184:185], off
	s_add_i32 m0, s60, 0x2000
	s_add_u32 s60, s44, 0x40000
	v_lshl_add_u64 v[216:217], s[44:45], 0, v[158:159]
	s_addc_u32 s61, s45, 0
	s_add_i32 s62, s54, s68
	global_load_lds_dwordx4 v[216:217], off
	v_lshl_add_u64 v[218:219], s[60:61], 0, v[154:155]
	s_mov_b32 m0, s62
	v_lshl_add_u64 v[220:221], s[46:47], 0, v[156:157]
	global_load_lds_dwordx4 v[218:219], off
	v_lshl_add_u64 v[218:219], s[60:61], 0, v[158:159]
	s_add_i32 m0, s62, 0x2000
	s_nop 0
	global_load_lds_dwordx4 v[218:219], off
	v_lshl_add_u64 v[218:219], s[46:47], 0, v[152:153]
	s_mov_b32 m0, s74
	s_nop 0
	global_load_lds_dwordx4 v[218:219], off
	s_mov_b32 m0, s66
	s_nop 0
	global_load_lds_dwordx4 v[220:221], off
	s_waitcnt vmcnt(8)
	s_waitcnt lgkmcnt(0)
	s_barrier
; #define PG8_STAGE(bufoff, gbase, voff) do { _Pragma("unroll") for (int _i = 0; _i < 2; ++_i) \
;         __builtin_amdgcn_global_load_lds((const unsigned*)((const char*)(gbase) + (voff)[_i]), (PG8_LAS unsigned*)(lds + (bufoff) + ldsw + _i * 8192), 16, 0, 0); } while (0)
; #define PG8_LDA(dst, b, h) do { _Pragma("unroll") for (int m = 0; m < 4; ++m) _Pragma("unroll") for (int k = 0; k < 2; ++k) dst[m][k] = *(const PG8_LAS bf16x8*)(lds + PG8_SA(b, h) + aoff + m * 2048 + k * 1024); } while (0)
; #define PG8_LDB(dst, b, h) do { _Pragma("unroll") for (int n = 0; n < 2; ++n) _Pragma("unroll") for (int k = 0; k < 2; ++k) dst[n][k] = *(const PG8_LAS bf16x8*)(lds + PG8_SB(b, h) + boff + n * 2048 + k * 1024); } while (0)
; #define PG8_MMA(ai, bj, At, Bt) do { __builtin_amdgcn_s_setprio(1); _Pragma("unroll") for (int m = 0; m < 4; ++m) _Pragma("unroll") for (int n = 0; n < 2; ++n) _Pragma("unroll") for (int k = 0; k < 2; ++k) \
;         acc[ai][bj][m][n] = mma16<F16>(Bt[n][k], At[m][k], acc[ai][bj][m][n]); __builtin_amdgcn_s_setprio(0); } while (0)
; #define PG8_WAIT_V(n) asm volatile("s_waitcnt vmcnt(" #n ")" ::: "memory")
; #define PG8_WAIT_L(n) asm volatile("s_waitcnt lgkmcnt(" #n ")" ::: "memory")
; #define PG8_BAR __builtin_amdgcn_s_barrier()
; #define PG8_SCHED __builtin_amdgcn_sched_barrier(0)
; template <class Epi, class Sched, bool ALIGN_EPI = false, bool SP2 = false, bool F16 = false>
; __device__ __forceinline__ void gemm_phase(PG8_LAS unsigned char* lds, const Gemm g, const Sched& S, const Epi& E, const int wid_in) {
;     ...
;             PG8_WAIT_V(8); PG8_WAIT_L(0); PG8_BAR; PG8_MMA(1, 0, At, B0); PG8_MMA(1, 1, At, B1); PG8_BAR; PG8_SCHED;
;             PG8_LDB(B0, 1, 0); PG8_LDB(B1, 1, 1); PG8_SCHED; PG8_LDA(At, 1, 0); PG8_STAGE(PG8_SA(0, 1), a2 + hstep, voffA);
;             PG8_WAIT_V(8); PG8_WAIT_L(0); PG8_BAR; PG8_MMA(0, 0, At, B0); PG8_MMA(0, 1, At, B1); PG8_BAR; PG8_SCHED;
	s_setprio 1
	s_waitcnt lgkmcnt(0)
	v_mfma_f32_16x16x32_bf16 v[60:63], v[128:131], v[176:179], v[60:63]
	v_mfma_f32_16x16x32_bf16 v[56:59], v[136:139], v[176:179], v[56:59]
	v_mfma_f32_16x16x32_bf16 v[44:47], v[128:131], v[192:195], v[44:47]
	v_mfma_f32_16x16x32_bf16 v[40:43], v[136:139], v[192:195], v[40:43]
	v_mfma_f32_16x16x32_bf16 v[28:31], v[128:131], v[200:203], v[28:31]
	v_mfma_f32_16x16x32_bf16 v[24:27], v[136:139], v[200:203], v[24:27]
	v_mfma_f32_16x16x32_bf16 v[12:15], v[128:131], v[208:211], v[12:15]
	v_mfma_f32_16x16x32_bf16 v[8:11], v[136:139], v[208:211], v[8:11]
	v_mfma_f32_16x16x32_bf16 v[60:63], v[132:135], v[180:183], v[60:63]
	v_mfma_f32_16x16x32_bf16 v[56:59], v[140:143], v[180:183], v[56:59]
	v_mfma_f32_16x16x32_bf16 v[44:47], v[132:135], v[196:199], v[44:47]
	v_mfma_f32_16x16x32_bf16 v[40:43], v[140:143], v[196:199], v[40:43]
	v_mfma_f32_16x16x32_bf16 v[28:31], v[132:135], v[204:207], v[28:31]
	v_mfma_f32_16x16x32_bf16 v[24:27], v[140:143], v[204:207], v[24:27]
	v_mfma_f32_16x16x32_bf16 v[12:15], v[132:135], v[212:215], v[12:15]
	v_mfma_f32_16x16x32_bf16 v[8:11], v[140:143], v[212:215], v[8:11]
	s_setprio 0
	s_setprio 1
	v_mfma_f32_16x16x32_bf16 v[52:55], v[144:147], v[176:179], v[52:55]
	v_mfma_f32_16x16x32_bf16 v[48:51], v[168:171], v[176:179], v[48:51]
	v_mfma_f32_16x16x32_bf16 v[36:39], v[144:147], v[192:195], v[36:39]
	v_mfma_f32_16x16x32_bf16 v[32:35], v[168:171], v[192:195], v[32:35]
	v_mfma_f32_16x16x32_bf16 v[20:23], v[144:147], v[200:203], v[20:23]
	v_mfma_f32_16x16x32_bf16 v[16:19], v[168:171], v[200:203], v[16:19]
	v_mfma_f32_16x16x32_bf16 v[4:7], v[144:147], v[208:211], v[4:7]
	v_mfma_f32_16x16x32_bf16 v[0:3], v[168:171], v[208:211], v[0:3]
	v_mfma_f32_16x16x32_bf16 v[52:55], v[148:151], v[180:183], v[52:55]
	v_mfma_f32_16x16x32_bf16 v[48:51], v[172:175], v[180:183], v[48:51]
	v_mfma_f32_16x16x32_bf16 v[36:39], v[148:151], v[196:199], v[36:39]
	v_mfma_f32_16x16x32_bf16 v[32:35], v[172:175], v[196:199], v[32:35]
	s_barrier
	v_mfma_f32_16x16x32_bf16 v[20:23], v[148:151], v[204:207], v[20:23]
	v_mfma_f32_16x16x32_bf16 v[16:19], v[172:175], v[204:207], v[16:19]
	v_mfma_f32_16x16x32_bf16 v[4:7], v[148:151], v[212:215], v[4:7]
	v_mfma_f32_16x16x32_bf16 v[0:3], v[172:175], v[212:215], v[0:3]
	s_setprio 0
	s_add_i32 s60, 0, 0x18000
	s_add_i32 s61, 0, 0x1c000
	v_add_u32_e32 v140, s60, v188
	v_add_u32_e32 v172, s61, v188
	ds_read_b128 v[128:131], v140
	ds_read_b128 v[132:135], v140 offset:1024
	ds_read_b128 v[136:139], v140 offset:2048
	ds_read_b128 v[140:143], v140 offset:3072
	ds_read_b128 v[144:147], v172
	ds_read_b128 v[148:151], v172 offset:1024
	ds_read_b128 v[168:171], v172 offset:2048
	ds_read_b128 v[172:175], v172 offset:3072
	s_add_u32 s46, s46, 0x40000
	s_addc_u32 s47, s47, 0
	s_mov_b32 m0, s90
	v_lshl_add_u64 v[222:223], s[46:47], 0, v[152:153]
	ds_read_b128 v[176:179], v191 offset:32768
	ds_read_b128 v[180:183], v191 offset:33792
	ds_read_b128 v[192:195], v191 offset:34816
	ds_read_b128 v[196:199], v191 offset:35840
	ds_read_b128 v[200:203], v191 offset:36864
	ds_read_b128 v[204:207], v191 offset:37888
	ds_read_b128 v[208:211], v191 offset:38912
	ds_read_b128 v[212:215], v191 offset:39936
	global_load_lds_dwordx4 v[222:223], off
	v_lshl_add_u64 v[222:223], s[46:47], 0, v[156:157]
	s_mov_b32 m0, s49
	s_nop 0
	global_load_lds_dwordx4 v[222:223], off
	s_waitcnt vmcnt(8)
	s_waitcnt lgkmcnt(0)
	s_barrier
	s_setprio 1
	s_waitcnt lgkmcnt(0)
	v_mfma_f32_16x16x32_bf16 v[124:127], v[128:131], v[176:179], v[124:127]
	v_mfma_f32_16x16x32_bf16 v[120:123], v[136:139], v[176:179], v[120:123]
	v_mfma_f32_16x16x32_bf16 v[108:111], v[128:131], v[192:195], v[108:111]
	v_mfma_f32_16x16x32_bf16 v[104:107], v[136:139], v[192:195], v[104:107]
	v_mfma_f32_16x16x32_bf16 v[92:95], v[128:131], v[200:203], v[92:95]
	v_mfma_f32_16x16x32_bf16 v[88:91], v[136:139], v[200:203], v[88:91]
	v_mfma_f32_16x16x32_bf16 v[76:79], v[128:131], v[208:211], v[76:79]
	v_mfma_f32_16x16x32_bf16 v[72:75], v[136:139], v[208:211], v[72:75]
	v_mfma_f32_16x16x32_bf16 v[124:127], v[132:135], v[180:183], v[124:127]
	v_mfma_f32_16x16x32_bf16 v[120:123], v[140:143], v[180:183], v[120:123]
	v_mfma_f32_16x16x32_bf16 v[108:111], v[132:135], v[196:199], v[108:111]
	v_mfma_f32_16x16x32_bf16 v[104:107], v[140:143], v[196:199], v[104:107]
	v_mfma_f32_16x16x32_bf16 v[92:95], v[132:135], v[204:207], v[92:95]
	v_mfma_f32_16x16x32_bf16 v[88:91], v[140:143], v[204:207], v[88:91]
	v_mfma_f32_16x16x32_bf16 v[76:79], v[132:135], v[212:215], v[76:79]
	v_mfma_f32_16x16x32_bf16 v[72:75], v[140:143], v[212:215], v[72:75]
	s_setprio 0
	s_setprio 1
	v_mfma_f32_16x16x32_bf16 v[116:119], v[144:147], v[176:179], v[116:119]
	v_mfma_f32_16x16x32_bf16 v[112:115], v[168:171], v[176:179], v[112:115]
	v_mfma_f32_16x16x32_bf16 v[100:103], v[144:147], v[192:195], v[100:103]
	v_mfma_f32_16x16x32_bf16 v[96:99], v[168:171], v[192:195], v[96:99]
	v_mfma_f32_16x16x32_bf16 v[84:87], v[144:147], v[200:203], v[84:87]
	v_mfma_f32_16x16x32_bf16 v[80:83], v[168:171], v[200:203], v[80:83]
	v_mfma_f32_16x16x32_bf16 v[68:71], v[144:147], v[208:211], v[68:71]
	v_mfma_f32_16x16x32_bf16 v[64:67], v[168:171], v[208:211], v[64:67]
	v_mfma_f32_16x16x32_bf16 v[116:119], v[148:151], v[180:183], v[116:119]
	v_mfma_f32_16x16x32_bf16 v[112:115], v[172:175], v[180:183], v[112:115]
	v_mfma_f32_16x16x32_bf16 v[100:103], v[148:151], v[196:199], v[100:103]
	v_mfma_f32_16x16x32_bf16 v[96:99], v[172:175], v[196:199], v[96:99]
	s_barrier
; #define PG8_STAGE(bufoff, gbase, voff) do { _Pragma("unroll") for (int _i = 0; _i < 2; ++_i) \
;         __builtin_amdgcn_global_load_lds((const unsigned*)((const char*)(gbase) + (voff)[_i]), (PG8_LAS unsigned*)(lds + (bufoff) + ldsw + _i * 8192), 16, 0, 0); } while (0)
; #define PG8_LDA(dst, b, h) do { _Pragma("unroll") for (int m = 0; m < 4; ++m) _Pragma("unroll") for (int k = 0; k < 2; ++k) dst[m][k] = *(const PG8_LAS bf16x8*)(lds + PG8_SA(b, h) + aoff + m * 2048 + k * 1024); } while (0)
; #define PG8_MMA(ai, bj, At, Bt) do { __builtin_amdgcn_s_setprio(1); _Pragma("unroll") for (int m = 0; m < 4; ++m) _Pragma("unroll") for (int n = 0; n < 2; ++n) _Pragma("unroll") for (int k = 0; k < 2; ++k) \
;         acc[ai][bj][m][n] = mma16<F16>(Bt[n][k], At[m][k], acc[ai][bj][m][n]); __builtin_amdgcn_s_setprio(0); } while (0)
; #define PG8_WAIT_V(n) asm volatile("s_waitcnt vmcnt(" #n ")" ::: "memory")
; #define PG8_WAIT_L(n) asm volatile("s_waitcnt lgkmcnt(" #n ")" ::: "memory")
; #define PG8_BAR __builtin_amdgcn_s_barrier()
; #define PG8_SCHED __builtin_amdgcn_sched_barrier(0)
; template <class Epi, class Sched, bool ALIGN_EPI = false, bool SP2 = false, bool F16 = false>
; __device__ __forceinline__ void gemm_phase(PG8_LAS unsigned char* lds, const Gemm g, const Sched& S, const Epi& E, const int wid_in) {
;     ...
;             PG8_WAIT_V(8); PG8_WAIT_L(0); PG8_BAR; PG8_MMA(0, 0, At, B0); PG8_MMA(0, 1, At, B1); PG8_BAR; PG8_SCHED;
;             PG8_LDA(At, 1, 1); PG8_STAGE(PG8_SB(1, 0), b3, voffB); PG8_STAGE(PG8_SB(1, 1), b3 + hstep, voffB); PG8_STAGE(PG8_SA(1, 0), a3, voffA);
;             PG8_WAIT_V(8); PG8_WAIT_L(0); PG8_BAR; PG8_MMA(1, 0, At, B0); PG8_MMA(1, 1, At, B1); PG8_BAR; PG8_SCHED;
	v_mfma_f32_16x16x32_bf16 v[84:87], v[148:151], v[204:207], v[84:87]
	v_mfma_f32_16x16x32_bf16 v[80:83], v[172:175], v[204:207], v[80:83]
	v_mfma_f32_16x16x32_bf16 v[68:71], v[148:151], v[212:215], v[68:71]
	v_mfma_f32_16x16x32_bf16 v[64:67], v[172:175], v[212:215], v[64:67]
	s_setprio 0
	s_add_i32 s46, s60, s68
	v_lshl_add_u64 v[184:185], v[184:185], 0, s[24:25]
	s_mov_b32 m0, s46
	ds_read_b128 v[176:179], v191 offset:49152
	ds_read_b128 v[180:183], v191 offset:50176
	ds_read_b128 v[192:195], v191 offset:51200
	ds_read_b128 v[196:199], v191 offset:52224
	ds_read_b128 v[200:203], v191 offset:53248
	ds_read_b128 v[204:207], v191 offset:54272
	ds_read_b128 v[208:211], v191 offset:55296
	ds_read_b128 v[212:215], v191 offset:56320
	global_load_lds_dwordx4 v[184:185], off
	s_add_i32 m0, s46, 0x2000
	s_add_u32 s44, s44, 0x40080
	v_lshl_add_u64 v[184:185], v[216:217], 0, s[24:25]
	s_addc_u32 s45, s45, 0
	s_add_i32 s46, s61, s68
	global_load_lds_dwordx4 v[184:185], off
	v_lshl_add_u64 v[184:185], s[44:45], 0, v[154:155]
	s_mov_b32 m0, s46
	s_nop 0
	global_load_lds_dwordx4 v[184:185], off
	v_lshl_add_u64 v[184:185], s[44:45], 0, v[158:159]
	s_add_i32 m0, s46, 0x2000
	s_nop 0
	global_load_lds_dwordx4 v[184:185], off
	v_lshl_add_u64 v[184:185], v[218:219], 0, s[24:25]
	s_mov_b32 m0, s75
	s_nop 0
	global_load_lds_dwordx4 v[184:185], off
	v_lshl_add_u64 v[184:185], v[220:221], 0, s[24:25]
	s_mov_b32 m0, s67
	s_nop 0
	global_load_lds_dwordx4 v[184:185], off
	s_waitcnt vmcnt(8)
	s_waitcnt lgkmcnt(0)
	s_barrier
	s_setprio 1
	s_waitcnt lgkmcnt(0)
	v_mfma_f32_16x16x32_bf16 v[60:63], v[128:131], v[176:179], v[60:63]
	v_mfma_f32_16x16x32_bf16 v[56:59], v[136:139], v[176:179], v[56:59]
	v_mfma_f32_16x16x32_bf16 v[44:47], v[128:131], v[192:195], v[44:47]
	v_mfma_f32_16x16x32_bf16 v[40:43], v[136:139], v[192:195], v[40:43]
	v_mfma_f32_16x16x32_bf16 v[28:31], v[128:131], v[200:203], v[28:31]
	v_mfma_f32_16x16x32_bf16 v[24:27], v[136:139], v[200:203], v[24:27]
	v_mfma_f32_16x16x32_bf16 v[12:15], v[128:131], v[208:211], v[12:15]
	v_mfma_f32_16x16x32_bf16 v[8:11], v[136:139], v[208:211], v[8:11]
	v_mfma_f32_16x16x32_bf16 v[60:63], v[132:135], v[180:183], v[60:63]
	v_mfma_f32_16x16x32_bf16 v[56:59], v[140:143], v[180:183], v[56:59]
	v_mfma_f32_16x16x32_bf16 v[44:47], v[132:135], v[196:199], v[44:47]
	v_mfma_f32_16x16x32_bf16 v[40:43], v[140:143], v[196:199], v[40:43]
	v_mfma_f32_16x16x32_bf16 v[28:31], v[132:135], v[204:207], v[28:31]
	v_mfma_f32_16x16x32_bf16 v[24:27], v[140:143], v[204:207], v[24:27]
	v_mfma_f32_16x16x32_bf16 v[12:15], v[132:135], v[212:215], v[12:15]
	v_mfma_f32_16x16x32_bf16 v[8:11], v[140:143], v[212:215], v[8:11]
	s_setprio 0
	s_setprio 1
	v_mfma_f32_16x16x32_bf16 v[52:55], v[144:147], v[176:179], v[52:55]
	v_mfma_f32_16x16x32_bf16 v[48:51], v[168:171], v[176:179], v[48:51]
	v_mfma_f32_16x16x32_bf16 v[36:39], v[144:147], v[192:195], v[36:39]
	v_mfma_f32_16x16x32_bf16 v[32:35], v[168:171], v[192:195], v[32:35]
	v_mfma_f32_16x16x32_bf16 v[20:23], v[144:147], v[200:203], v[20:23]
	v_mfma_f32_16x16x32_bf16 v[16:19], v[168:171], v[200:203], v[16:19]
	v_mfma_f32_16x16x32_bf16 v[4:7], v[144:147], v[208:211], v[4:7]
	v_mfma_f32_16x16x32_bf16 v[0:3], v[168:171], v[208:211], v[0:3]
	v_mfma_f32_16x16x32_bf16 v[52:55], v[148:151], v[180:183], v[52:55]
	v_mfma_f32_16x16x32_bf16 v[48:51], v[172:175], v[180:183], v[48:51]
	v_mfma_f32_16x16x32_bf16 v[36:39], v[148:151], v[196:199], v[36:39]
	v_mfma_f32_16x16x32_bf16 v[32:35], v[172:175], v[196:199], v[32:35]
	s_barrier
	v_mfma_f32_16x16x32_bf16 v[20:23], v[148:151], v[204:207], v[20:23]
	v_mfma_f32_16x16x32_bf16 v[16:19], v[172:175], v[204:207], v[16:19]
	v_mfma_f32_16x16x32_bf16 v[4:7], v[148:151], v[212:215], v[4:7]
	v_mfma_f32_16x16x32_bf16 v[0:3], v[172:175], v[212:215], v[0:3]
	s_setprio 0
	s_add_i32 s59, s59, 2
	s_add_u32 s42, s42, 0x100
	s_addc_u32 s43, s43, 0
	s_add_u32 s57, s57, 0x100
	s_addc_u32 s58, s58, 0
	s_cmp_gt_u32 s59, 13
	s_cbranch_scc0 .LBB0_2489
	s_and_b64 vcc, exec, s[16:17]
	s_cbranch_vccz .LBB0_2492
	s_barrier

; #define PG8_STAGE(bufoff, gbase, voff) do { _Pragma("unroll") for (int _i = 0; _i < 2; ++_i) \
;         __builtin_amdgcn_global_load_lds((const unsigned*)((const char*)(gbase) + (voff)[_i]), (PG8_LAS unsigned*)(lds + (bufoff) + ldsw + _i * 8192), 16, 0, 0); } while (0)
; #define PG8_LDA(dst, b, h) do { _Pragma("unroll") for (int m = 0; m < 4; ++m) _Pragma("unroll") for (int k = 0; k < 2; ++k) dst[m][k] = *(const PG8_LAS bf16x8*)(lds + PG8_SA(b, h) + aoff + m * 2048 + k * 1024); } while (0)
; #define PG8_LDB(dst, b, h) do { _Pragma("unroll") for (int n = 0; n < 2; ++n) _Pragma("unroll") for (int k = 0; k < 2; ++k) dst[n][k] = *(const PG8_LAS bf16x8*)(lds + PG8_SB(b, h) + boff + n * 2048 + k * 1024); } while (0)
; #define PG8_MMA(ai, bj, At, Bt) do { __builtin_amdgcn_s_setprio(1); _Pragma("unroll") for (int m = 0; m < 4; ++m) _Pragma("unroll") for (int n = 0; n < 2; ++n) _Pragma("unroll") for (int k = 0; k < 2; ++k) \
;         acc[ai][bj][m][n] = mma16<F16>(Bt[n][k], At[m][k], acc[ai][bj][m][n]); __builtin_amdgcn_s_setprio(0); } while (0)
; #define PG8_WAIT_V(n) asm volatile("s_waitcnt vmcnt(" #n ")" ::: "memory")
; #define PG8_WAIT_L(n) asm volatile("s_waitcnt lgkmcnt(" #n ")" ::: "memory")
; #define PG8_BAR __builtin_amdgcn_s_barrier()
; #define PG8_SCHED __builtin_amdgcn_sched_barrier(0)
; template <class Epi, class Sched, bool ALIGN_EPI = false, bool SP2 = false, bool F16 = false>
; __device__ __forceinline__ void gemm_phase(PG8_LAS unsigned char* lds, const Gemm g, const Sched& S, const Epi& E, const int wid_in) {
;     ...
;             PG8_LDB(B0, 0, 0); PG8_LDB(B1, 0, 1); PG8_SCHED; PG8_LDA(At, 0, 0); PG8_STAGE(PG8_SA(1, 1), a1 + hstep, voffA);
;             PG8_WAIT_V(8); PG8_WAIT_L(0); PG8_BAR; PG8_MMA(0, 0, At, B0); PG8_MMA(0, 1, At, B1); PG8_BAR; PG8_SCHED;
;             PG8_LDA(At, 0, 1); PG8_STAGE(PG8_SB(0, 0), b2, voffB); PG8_STAGE(PG8_SB(0, 1), b2 + hstep, voffB); PG8_STAGE(PG8_SA(0, 0), a2, voffA);
;             PG8_WAIT_V(8); PG8_WAIT_L(0); PG8_BAR; PG8_MMA(1, 0, At, B0); PG8_MMA(1, 1, At, B1); PG8_BAR; PG8_SCHED;
;             PG8_LDB(B0, 1, 0); PG8_LDB(B1, 1, 1); PG8_SCHED; PG8_LDA(At, 1, 0); PG8_STAGE(PG8_SA(0, 1), a2 + hstep, voffA);
;             PG8_WAIT_V(8); PG8_WAIT_L(0); PG8_BAR; PG8_MMA(0, 0, At, B0); PG8_MMA(0, 1, At, B1); PG8_BAR; PG8_SCHED;
.LBB0_2566:
	ds_read_b128 v[0:3], v193
	ds_read_b128 v[4:7], v193 offset:1024
	ds_read_b128 v[136:139], v193 offset:2048
	ds_read_b128 v[140:143], v193 offset:3072
	ds_read_b128 v[144:147], v194
	ds_read_b128 v[148:151], v194 offset:1024
	ds_read_b128 v[152:155], v194 offset:2048
	ds_read_b128 v[156:159], v194 offset:3072
	s_add_u32 s42, s36, 0xfffc0080
	s_addc_u32 s43, s37, -1
	s_cmp_eq_u32 s62, 12
	s_cselect_b32 s45, s25, s43
	s_cselect_b32 s44, s35, s42
	s_cselect_b32 s43, s23, s61
	s_cselect_b32 s42, s59, s60
	s_mov_b32 m0, s91
	v_lshl_add_u64 v[188:189], s[36:37], 0, v[168:169]
	ds_read_b128 v[176:179], v195
	ds_read_b128 v[180:183], v195 offset:1024
	ds_read_b128 v[184:187], v195 offset:2048
	ds_read_b128 v[198:201], v195 offset:3072
	ds_read_b128 v[202:205], v195 offset:4096
	ds_read_b128 v[206:209], v195 offset:5120
	ds_read_b128 v[210:213], v195 offset:6144
	ds_read_b128 v[214:217], v195 offset:7168
	global_load_lds_dwordx4 v[188:189], off
	v_lshl_add_u64 v[188:189], s[36:37], 0, v[170:171]
	s_add_i32 m0, s74, 0xe000
	s_nop 0
	global_load_lds_dwordx4 v[188:189], off
	s_waitcnt vmcnt(8)
	s_waitcnt lgkmcnt(0)
	s_barrier
	s_setprio 1
	s_waitcnt lgkmcnt(0)
	v_mfma_f32_16x16x32_f16 v[132:135], v[0:3], v[176:179], v[132:135]
	v_mfma_f32_16x16x32_f16 v[128:131], v[136:139], v[176:179], v[128:131]
	v_mfma_f32_16x16x32_f16 v[116:119], v[0:3], v[184:187], v[116:119]
	v_mfma_f32_16x16x32_f16 v[112:115], v[136:139], v[184:187], v[112:115]
	v_mfma_f32_16x16x32_f16 v[100:103], v[0:3], v[202:205], v[100:103]
	v_mfma_f32_16x16x32_f16 v[96:99], v[136:139], v[202:205], v[96:99]
	v_mfma_f32_16x16x32_f16 v[84:87], v[0:3], v[210:213], v[84:87]
	v_mfma_f32_16x16x32_f16 v[80:83], v[136:139], v[210:213], v[80:83]
	v_mfma_f32_16x16x32_f16 v[132:135], v[4:7], v[180:183], v[132:135]
	v_mfma_f32_16x16x32_f16 v[128:131], v[140:143], v[180:183], v[128:131]
	v_mfma_f32_16x16x32_f16 v[116:119], v[4:7], v[198:201], v[116:119]
	v_mfma_f32_16x16x32_f16 v[112:115], v[140:143], v[198:201], v[112:115]
	v_mfma_f32_16x16x32_f16 v[100:103], v[4:7], v[206:209], v[100:103]
	v_mfma_f32_16x16x32_f16 v[96:99], v[140:143], v[206:209], v[96:99]
	v_mfma_f32_16x16x32_f16 v[84:87], v[4:7], v[214:217], v[84:87]
	v_mfma_f32_16x16x32_f16 v[80:83], v[140:143], v[214:217], v[80:83]
	s_setprio 0
	s_setprio 1
	v_mfma_f32_16x16x32_f16 v[124:127], v[144:147], v[176:179], v[124:127]
	v_mfma_f32_16x16x32_f16 v[120:123], v[152:155], v[176:179], v[120:123]
	v_mfma_f32_16x16x32_f16 v[108:111], v[144:147], v[184:187], v[108:111]
	v_mfma_f32_16x16x32_f16 v[104:107], v[152:155], v[184:187], v[104:107]
	v_mfma_f32_16x16x32_f16 v[92:95], v[144:147], v[202:205], v[92:95]
	v_mfma_f32_16x16x32_f16 v[88:91], v[152:155], v[202:205], v[88:91]
	v_mfma_f32_16x16x32_f16 v[76:79], v[144:147], v[210:213], v[76:79]
	v_mfma_f32_16x16x32_f16 v[72:75], v[152:155], v[210:213], v[72:75]
	v_mfma_f32_16x16x32_f16 v[124:127], v[148:151], v[180:183], v[124:127]
	v_mfma_f32_16x16x32_f16 v[120:123], v[156:159], v[180:183], v[120:123]
	v_mfma_f32_16x16x32_f16 v[108:111], v[148:151], v[198:201], v[108:111]
	v_mfma_f32_16x16x32_f16 v[104:107], v[156:159], v[198:201], v[104:107]
	s_barrier
	v_mfma_f32_16x16x32_f16 v[92:95], v[148:151], v[206:209], v[92:95]
	v_mfma_f32_16x16x32_f16 v[88:91], v[156:159], v[206:209], v[88:91]
	v_mfma_f32_16x16x32_f16 v[76:79], v[148:151], v[214:217], v[76:79]
	v_mfma_f32_16x16x32_f16 v[72:75], v[156:159], v[214:217], v[72:75]
	s_setprio 0
	s_add_i32 s63, s56, s68
	v_lshl_add_u64 v[188:189], s[42:43], 0, v[162:163]
	s_mov_b32 m0, s63
	ds_read_b128 v[176:179], v195 offset:16384
	ds_read_b128 v[180:183], v195 offset:17408
	ds_read_b128 v[184:187], v195 offset:18432
	ds_read_b128 v[198:201], v195 offset:19456
	ds_read_b128 v[202:205], v195 offset:20480
	ds_read_b128 v[206:209], v195 offset:21504
	ds_read_b128 v[210:213], v195 offset:22528
	ds_read_b128 v[214:217], v195 offset:23552
	global_load_lds_dwordx4 v[188:189], off
	s_add_i32 m0, s63, 0x2000
	s_add_u32 s64, s42, 0x40000
	v_lshl_add_u64 v[218:219], s[42:43], 0, v[166:167]
	s_addc_u32 s65, s43, 0
	s_add_i32 s63, s57, s68
	global_load_lds_dwordx4 v[218:219], off
	v_lshl_add_u64 v[220:221], s[64:65], 0, v[162:163]
	s_mov_b32 m0, s63
	v_lshl_add_u64 v[222:223], s[44:45], 0, v[164:165]
	global_load_lds_dwordx4 v[220:221], off
	v_lshl_add_u64 v[220:221], s[64:65], 0, v[166:167]
	s_add_i32 m0, s63, 0x2000
	s_nop 0
	global_load_lds_dwordx4 v[220:221], off
	v_lshl_add_u64 v[220:221], s[44:45], 0, v[160:161]
	s_mov_b32 m0, s74
	s_nop 0
	global_load_lds_dwordx4 v[220:221], off
	s_mov_b32 m0, s66
	s_nop 0
	global_load_lds_dwordx4 v[222:223], off
	s_waitcnt vmcnt(8)
	s_waitcnt lgkmcnt(0)
	s_barrier
	s_setprio 1
	s_waitcnt lgkmcnt(0)
	v_mfma_f32_16x16x32_f16 v[68:71], v[0:3], v[176:179], v[68:71]
	v_mfma_f32_16x16x32_f16 v[64:67], v[136:139], v[176:179], v[64:67]
	v_mfma_f32_16x16x32_f16 v[52:55], v[0:3], v[184:187], v[52:55]
	v_mfma_f32_16x16x32_f16 v[48:51], v[136:139], v[184:187], v[48:51]
	v_mfma_f32_16x16x32_f16 v[36:39], v[0:3], v[202:205], v[36:39]
	v_mfma_f32_16x16x32_f16 v[32:35], v[136:139], v[202:205], v[32:35]
	v_mfma_f32_16x16x32_f16 v[0:3], v[0:3], v[210:213], v[20:23]
	v_mfma_f32_16x16x32_f16 v[68:71], v[4:7], v[180:183], v[68:71]
	v_mfma_f32_16x16x32_f16 v[64:67], v[140:143], v[180:183], v[64:67]
	v_mfma_f32_16x16x32_f16 v[52:55], v[4:7], v[198:201], v[52:55]
	v_mfma_f32_16x16x32_f16 v[48:51], v[140:143], v[198:201], v[48:51]
	v_mfma_f32_16x16x32_f16 v[36:39], v[4:7], v[206:209], v[36:39]
	v_mfma_f32_16x16x32_f16 v[32:35], v[140:143], v[206:209], v[32:35]
	v_mfma_f32_16x16x32_f16 v[0:3], v[4:7], v[214:217], v[0:3]
	v_mfma_f32_16x16x32_f16 v[4:7], v[136:139], v[210:213], v[16:19]
	v_mfma_f32_16x16x32_f16 v[4:7], v[140:143], v[214:217], v[4:7]
	s_setprio 0
	s_setprio 1
	v_mfma_f32_16x16x32_f16 v[16:19], v[144:147], v[176:179], v[60:63]
	v_mfma_f32_16x16x32_f16 v[60:63], v[148:151], v[180:183], v[16:19]
	v_mfma_f32_16x16x32_f16 v[16:19], v[152:155], v[176:179], v[56:59]
	v_mfma_f32_16x16x32_f16 v[56:59], v[156:159], v[180:183], v[16:19]
	v_mfma_f32_16x16x32_f16 v[16:19], v[144:147], v[184:187], v[44:47]
	v_mfma_f32_16x16x32_f16 v[44:47], v[148:151], v[198:201], v[16:19]
	v_mfma_f32_16x16x32_f16 v[16:19], v[152:155], v[184:187], v[40:43]
	v_mfma_f32_16x16x32_f16 v[40:43], v[156:159], v[198:201], v[16:19]
	v_mfma_f32_16x16x32_f16 v[16:19], v[144:147], v[202:205], v[28:31]
	v_mfma_f32_16x16x32_f16 v[28:31], v[148:151], v[206:209], v[16:19]
	v_mfma_f32_16x16x32_f16 v[16:19], v[152:155], v[202:205], v[24:27]
	v_mfma_f32_16x16x32_f16 v[12:15], v[144:147], v[210:213], v[12:15]
	s_barrier
; #define PG8_STAGE(bufoff, gbase, voff) do { _Pragma("unroll") for (int _i = 0; _i < 2; ++_i) \
;         __builtin_amdgcn_global_load_lds((const unsigned*)((const char*)(gbase) + (voff)[_i]), (PG8_LAS unsigned*)(lds + (bufoff) + ldsw + _i * 8192), 16, 0, 0); } while (0)
; #define PG8_LDA(dst, b, h) do { _Pragma("unroll") for (int m = 0; m < 4; ++m) _Pragma("unroll") for (int k = 0; k < 2; ++k) dst[m][k] = *(const PG8_LAS bf16x8*)(lds + PG8_SA(b, h) + aoff + m * 2048 + k * 1024); } while (0)
; #define PG8_MMA(ai, bj, At, Bt) do { __builtin_amdgcn_s_setprio(1); _Pragma("unroll") for (int m = 0; m < 4; ++m) _Pragma("unroll") for (int n = 0; n < 2; ++n) _Pragma("unroll") for (int k = 0; k < 2; ++k) \
;         acc[ai][bj][m][n] = mma16<F16>(Bt[n][k], At[m][k], acc[ai][bj][m][n]); __builtin_amdgcn_s_setprio(0); } while (0)
; #define PG8_WAIT_V(n) asm volatile("s_waitcnt vmcnt(" #n ")" ::: "memory")
; #define PG8_WAIT_L(n) asm volatile("s_waitcnt lgkmcnt(" #n ")" ::: "memory")
; #define PG8_BAR __builtin_amdgcn_s_barrier()
; #define PG8_SCHED __builtin_amdgcn_sched_barrier(0)
; template <class Epi, class Sched, bool ALIGN_EPI = false, bool SP2 = false, bool F16 = false>
; __device__ __forceinline__ void gemm_phase(PG8_LAS unsigned char* lds, const Gemm g, const Sched& S, const Epi& E, const int wid_in) {
;     ...
;             PG8_WAIT_V(8); PG8_WAIT_L(0); PG8_BAR; PG8_MMA(0, 0, At, B0); PG8_MMA(0, 1, At, B1); PG8_BAR; PG8_SCHED;
;             PG8_LDA(At, 1, 1); PG8_STAGE(PG8_SB(1, 0), b3, voffB); PG8_STAGE(PG8_SB(1, 1), b3 + hstep, voffB); PG8_STAGE(PG8_SA(1, 0), a3, voffA);
	v_mfma_f32_16x16x32_f16 v[8:11], v[152:155], v[210:213], v[8:11]
	v_mfma_f32_16x16x32_f16 v[24:27], v[156:159], v[206:209], v[16:19]
	v_mfma_f32_16x16x32_f16 v[12:15], v[148:151], v[214:217], v[12:15]
	v_mfma_f32_16x16x32_f16 v[8:11], v[156:159], v[214:217], v[8:11]
	s_setprio 0
	s_add_i32 s63, 0, 0x18000
	s_add_i32 s64, 0, 0x1c000
	v_add_u32_e32 v140, s63, v192
	v_add_u32_e32 v156, s64, v192
	ds_read_b128 v[16:19], v140
	ds_read_b128 v[20:23], v140 offset:1024
	ds_read_b128 v[136:139], v140 offset:2048
	ds_read_b128 v[140:143], v140 offset:3072
	ds_read_b128 v[144:147], v156
	ds_read_b128 v[148:151], v156 offset:1024
	ds_read_b128 v[152:155], v156 offset:2048
	ds_read_b128 v[156:159], v156 offset:3072
	s_add_u32 s44, s44, 0x40000
	s_addc_u32 s45, s45, 0
	s_mov_b32 m0, s90
	v_lshl_add_u64 v[224:225], s[44:45], 0, v[160:161]
	ds_read_b128 v[176:179], v195 offset:32768
	ds_read_b128 v[180:183], v195 offset:33792
	ds_read_b128 v[184:187], v195 offset:34816
	ds_read_b128 v[198:201], v195 offset:35840
	ds_read_b128 v[202:205], v195 offset:36864
	ds_read_b128 v[206:209], v195 offset:37888
	ds_read_b128 v[210:213], v195 offset:38912
	ds_read_b128 v[214:217], v195 offset:39936
	global_load_lds_dwordx4 v[224:225], off
	v_lshl_add_u64 v[224:225], s[44:45], 0, v[164:165]
	s_mov_b32 m0, s31
	s_nop 0
	global_load_lds_dwordx4 v[224:225], off
	s_waitcnt vmcnt(8)
	s_waitcnt lgkmcnt(0)
	s_barrier
	s_setprio 1
	s_waitcnt lgkmcnt(0)
	v_mfma_f32_16x16x32_f16 v[132:135], v[16:19], v[176:179], v[132:135]
	v_mfma_f32_16x16x32_f16 v[128:131], v[136:139], v[176:179], v[128:131]
	v_mfma_f32_16x16x32_f16 v[116:119], v[16:19], v[184:187], v[116:119]
	v_mfma_f32_16x16x32_f16 v[112:115], v[136:139], v[184:187], v[112:115]
	v_mfma_f32_16x16x32_f16 v[100:103], v[16:19], v[202:205], v[100:103]
	v_mfma_f32_16x16x32_f16 v[96:99], v[136:139], v[202:205], v[96:99]
	v_mfma_f32_16x16x32_f16 v[84:87], v[16:19], v[210:213], v[84:87]
	v_mfma_f32_16x16x32_f16 v[80:83], v[136:139], v[210:213], v[80:83]
	v_mfma_f32_16x16x32_f16 v[132:135], v[20:23], v[180:183], v[132:135]
	v_mfma_f32_16x16x32_f16 v[128:131], v[140:143], v[180:183], v[128:131]
	v_mfma_f32_16x16x32_f16 v[116:119], v[20:23], v[198:201], v[116:119]
	v_mfma_f32_16x16x32_f16 v[112:115], v[140:143], v[198:201], v[112:115]
	v_mfma_f32_16x16x32_f16 v[100:103], v[20:23], v[206:209], v[100:103]
	v_mfma_f32_16x16x32_f16 v[96:99], v[140:143], v[206:209], v[96:99]
	v_mfma_f32_16x16x32_f16 v[84:87], v[20:23], v[214:217], v[84:87]
	v_mfma_f32_16x16x32_f16 v[80:83], v[140:143], v[214:217], v[80:83]
	s_setprio 0
	s_setprio 1
	v_mfma_f32_16x16x32_f16 v[124:127], v[144:147], v[176:179], v[124:127]
	v_mfma_f32_16x16x32_f16 v[120:123], v[152:155], v[176:179], v[120:123]
	v_mfma_f32_16x16x32_f16 v[108:111], v[144:147], v[184:187], v[108:111]
	v_mfma_f32_16x16x32_f16 v[104:107], v[152:155], v[184:187], v[104:107]
	v_mfma_f32_16x16x32_f16 v[92:95], v[144:147], v[202:205], v[92:95]
	v_mfma_f32_16x16x32_f16 v[88:91], v[152:155], v[202:205], v[88:91]
	v_mfma_f32_16x16x32_f16 v[76:79], v[144:147], v[210:213], v[76:79]
	v_mfma_f32_16x16x32_f16 v[72:75], v[152:155], v[210:213], v[72:75]
	v_mfma_f32_16x16x32_f16 v[124:127], v[148:151], v[180:183], v[124:127]
	v_mfma_f32_16x16x32_f16 v[120:123], v[156:159], v[180:183], v[120:123]
	v_mfma_f32_16x16x32_f16 v[108:111], v[148:151], v[198:201], v[108:111]
	v_mfma_f32_16x16x32_f16 v[104:107], v[156:159], v[198:201], v[104:107]
	s_barrier
; #define PG8_STAGE(bufoff, gbase, voff) do { _Pragma("unroll") for (int _i = 0; _i < 2; ++_i) \
;         __builtin_amdgcn_global_load_lds((const unsigned*)((const char*)(gbase) + (voff)[_i]), (PG8_LAS unsigned*)(lds + (bufoff) + ldsw + _i * 8192), 16, 0, 0); } while (0)
; #define PG8_LDA(dst, b, h) do { _Pragma("unroll") for (int m = 0; m < 4; ++m) _Pragma("unroll") for (int k = 0; k < 2; ++k) dst[m][k] = *(const PG8_LAS bf16x8*)(lds + PG8_SA(b, h) + aoff + m * 2048 + k * 1024); } while (0)
; #define PG8_MMA(ai, bj, At, Bt) do { __builtin_amdgcn_s_setprio(1); _Pragma("unroll") for (int m = 0; m < 4; ++m) _Pragma("unroll") for (int n = 0; n < 2; ++n) _Pragma("unroll") for (int k = 0; k < 2; ++k) \
;         acc[ai][bj][m][n] = mma16<F16>(Bt[n][k], At[m][k], acc[ai][bj][m][n]); __builtin_amdgcn_s_setprio(0); } while (0)
; #define PG8_WAIT_V(n) asm volatile("s_waitcnt vmcnt(" #n ")" ::: "memory")
; #define PG8_WAIT_L(n) asm volatile("s_waitcnt lgkmcnt(" #n ")" ::: "memory")
; #define PG8_BAR __builtin_amdgcn_s_barrier()
; #define PG8_SCHED __builtin_amdgcn_sched_barrier(0)
; template <class Epi, class Sched, bool ALIGN_EPI = false, bool SP2 = false, bool F16 = false>
; __device__ __forceinline__ void gemm_phase(PG8_LAS unsigned char* lds, const Gemm g, const Sched& S, const Epi& E, const int wid_in) {
;     ...
;             PG8_WAIT_V(8); PG8_WAIT_L(0); PG8_BAR; PG8_MMA(0, 0, At, B0); PG8_MMA(0, 1, At, B1); PG8_BAR; PG8_SCHED;
;             PG8_LDA(At, 1, 1); PG8_STAGE(PG8_SB(1, 0), b3, voffB); PG8_STAGE(PG8_SB(1, 1), b3 + hstep, voffB); PG8_STAGE(PG8_SA(1, 0), a3, voffA);
;             PG8_WAIT_V(8); PG8_WAIT_L(0); PG8_BAR; PG8_MMA(1, 0, At, B0); PG8_MMA(1, 1, At, B1); PG8_BAR; PG8_SCHED;
	v_mfma_f32_16x16x32_f16 v[92:95], v[148:151], v[206:209], v[92:95]
	v_mfma_f32_16x16x32_f16 v[88:91], v[156:159], v[206:209], v[88:91]
	v_mfma_f32_16x16x32_f16 v[76:79], v[148:151], v[214:217], v[76:79]
	v_mfma_f32_16x16x32_f16 v[72:75], v[156:159], v[214:217], v[72:75]
	s_setprio 0
	s_add_i32 s44, s63, s68
	v_lshl_add_u64 v[188:189], v[188:189], 0, s[20:21]
	s_mov_b32 m0, s44
	ds_read_b128 v[176:179], v195 offset:49152
	ds_read_b128 v[180:183], v195 offset:50176
	ds_read_b128 v[184:187], v195 offset:51200
	ds_read_b128 v[198:201], v195 offset:52224
	ds_read_b128 v[202:205], v195 offset:53248
	ds_read_b128 v[206:209], v195 offset:54272
	ds_read_b128 v[210:213], v195 offset:55296
	ds_read_b128 v[214:217], v195 offset:56320
	global_load_lds_dwordx4 v[188:189], off
	s_add_i32 m0, s44, 0x2000
	s_add_u32 s42, s42, 0x40080
	v_lshl_add_u64 v[188:189], v[218:219], 0, s[20:21]
	s_addc_u32 s43, s43, 0
	s_add_i32 s44, s64, s68
	global_load_lds_dwordx4 v[188:189], off
	v_lshl_add_u64 v[188:189], s[42:43], 0, v[162:163]
	s_mov_b32 m0, s44
	s_nop 0
	global_load_lds_dwordx4 v[188:189], off
	v_lshl_add_u64 v[188:189], s[42:43], 0, v[166:167]
	s_add_i32 m0, s44, 0x2000
	s_nop 0
	global_load_lds_dwordx4 v[188:189], off
	v_lshl_add_u64 v[188:189], v[220:221], 0, s[20:21]
	s_mov_b32 m0, s75
	s_nop 0
	global_load_lds_dwordx4 v[188:189], off
	v_lshl_add_u64 v[188:189], v[222:223], 0, s[20:21]
	s_mov_b32 m0, s67
	s_nop 0
	global_load_lds_dwordx4 v[188:189], off
	s_waitcnt vmcnt(8)
	s_waitcnt lgkmcnt(0)
	s_barrier
	s_setprio 1
	s_waitcnt lgkmcnt(0)
	v_mfma_f32_16x16x32_f16 v[68:71], v[16:19], v[176:179], v[68:71]
	v_mfma_f32_16x16x32_f16 v[52:55], v[16:19], v[184:187], v[52:55]
	v_mfma_f32_16x16x32_f16 v[36:39], v[16:19], v[202:205], v[36:39]
	v_mfma_f32_16x16x32_f16 v[0:3], v[16:19], v[210:213], v[0:3]
	v_mfma_f32_16x16x32_f16 v[68:71], v[20:23], v[180:183], v[68:71]
	v_mfma_f32_16x16x32_f16 v[64:67], v[136:139], v[176:179], v[64:67]
	v_mfma_f32_16x16x32_f16 v[52:55], v[20:23], v[198:201], v[52:55]
	v_mfma_f32_16x16x32_f16 v[48:51], v[136:139], v[184:187], v[48:51]
	v_mfma_f32_16x16x32_f16 v[36:39], v[20:23], v[206:209], v[36:39]
	v_mfma_f32_16x16x32_f16 v[32:35], v[136:139], v[202:205], v[32:35]
	v_mfma_f32_16x16x32_f16 v[20:23], v[20:23], v[214:217], v[0:3]
	v_mfma_f32_16x16x32_f16 v[0:3], v[136:139], v[210:213], v[4:7]
	v_mfma_f32_16x16x32_f16 v[64:67], v[140:143], v[180:183], v[64:67]
	v_mfma_f32_16x16x32_f16 v[48:51], v[140:143], v[198:201], v[48:51]
	v_mfma_f32_16x16x32_f16 v[32:35], v[140:143], v[206:209], v[32:35]
	v_mfma_f32_16x16x32_f16 v[16:19], v[140:143], v[214:217], v[0:3]
	s_setprio 0
	s_setprio 1
	v_mfma_f32_16x16x32_f16 v[0:3], v[144:147], v[176:179], v[60:63]
	v_mfma_f32_16x16x32_f16 v[60:63], v[148:151], v[180:183], v[0:3]
	v_mfma_f32_16x16x32_f16 v[0:3], v[152:155], v[176:179], v[56:59]
	v_mfma_f32_16x16x32_f16 v[56:59], v[156:159], v[180:183], v[0:3]
	v_mfma_f32_16x16x32_f16 v[0:3], v[144:147], v[184:187], v[44:47]
	v_mfma_f32_16x16x32_f16 v[44:47], v[148:151], v[198:201], v[0:3]
	v_mfma_f32_16x16x32_f16 v[0:3], v[152:155], v[184:187], v[40:43]
	v_mfma_f32_16x16x32_f16 v[40:43], v[156:159], v[198:201], v[0:3]
	v_mfma_f32_16x16x32_f16 v[0:3], v[144:147], v[202:205], v[28:31]
	v_mfma_f32_16x16x32_f16 v[28:31], v[148:151], v[206:209], v[0:3]
	v_mfma_f32_16x16x32_f16 v[0:3], v[152:155], v[202:205], v[24:27]
	v_mfma_f32_16x16x32_f16 v[24:27], v[156:159], v[206:209], v[0:3]
	s_barrier
	v_mfma_f32_16x16x32_f16 v[0:3], v[144:147], v[210:213], v[12:15]
	v_mfma_f32_16x16x32_f16 v[12:15], v[148:151], v[214:217], v[0:3]
	v_mfma_f32_16x16x32_f16 v[0:3], v[152:155], v[210:213], v[8:11]
	v_mfma_f32_16x16x32_f16 v[8:11], v[156:159], v[214:217], v[0:3]
	s_setprio 0
	s_add_i32 s62, s62, 2
	s_add_u32 s36, s36, 0x100
	s_addc_u32 s37, s37, 0
	s_add_u32 s60, s60, 0x100
	s_addc_u32 s61, s61, 0
	s_cmp_gt_u32 s62, 13
	s_cbranch_scc0 .LBB0_2566
	s_and_b64 vcc, exec, s[16:17]
	s_cbranch_vccz .LBB0_2569
	s_barrier

; #define PG8_STAGE(bufoff, gbase, voff) do { _Pragma("unroll") for (int _i = 0; _i < 2; ++_i) \
;         __builtin_amdgcn_global_load_lds((const unsigned*)((const char*)(gbase) + (voff)[_i]), (PG8_LAS unsigned*)(lds + (bufoff) + ldsw + _i * 8192), 16, 0, 0); } while (0)
; #define PG8_LDA(dst, b, h) do { _Pragma("unroll") for (int m = 0; m < 4; ++m) _Pragma("unroll") for (int k = 0; k < 2; ++k) dst[m][k] = *(const PG8_LAS bf16x8*)(lds + PG8_SA(b, h) + aoff + m * 2048 + k * 1024); } while (0)
; #define PG8_LDB(dst, b, h) do { _Pragma("unroll") for (int n = 0; n < 2; ++n) _Pragma("unroll") for (int k = 0; k < 2; ++k) dst[n][k] = *(const PG8_LAS bf16x8*)(lds + PG8_SB(b, h) + boff + n * 2048 + k * 1024); } while (0)
; #define PG8_WAIT_V(n) asm volatile("s_waitcnt vmcnt(" #n ")" ::: "memory")
; #define PG8_WAIT_L(n) asm volatile("s_waitcnt lgkmcnt(" #n ")" ::: "memory")
; #define PG8_BAR __builtin_amdgcn_s_barrier()
; #define PG8_SCHED __builtin_amdgcn_sched_barrier(0)
; template <class Epi, class Sched, bool ALIGN_EPI = false, bool SP2 = false, bool F16 = false>
; __device__ __forceinline__ void gemm_phase(PG8_LAS unsigned char* lds, const Gemm g, const Sched& S, const Epi& E, const int wid_in) {
;     ...
;         const bool has_next = S.next(ui + 1, nxt);
;         const char* nA = has_next ? (const char*)g.A + (size_t)nxt.pm * tstep : cA; const char* nB = has_next ? (const char*)g.Bt + (size_t)nxt.pn * tstep : cB;
;         for (int t = 0; t < nt; t += 2) {
;             const bool last = (t == nt - 2);
;             const char* a1 = cA + (size_t)(t + 1) * kstep;
;             const char* a2 = last ? nA : cA + (size_t)(t + 2) * kstep; const char* b2 = last ? nB : cB + (size_t)(t + 2) * kstep;
;             const char* a3 = a2 + kstep; const char* b3 = b2 + kstep;
;             if (last && has_next) S.a_ready(nxt);
;             if constexpr (SP2) {
;             PG8_LDB(B0, 0, 0); PG8_LDB(B1, 0, 1); PG8_SCHED; PG8_LDA(At, 0, 0); PG8_STAGE(PG8_SA(1, 1), a1 + hstep, voffA);
;             PG8_WAIT_V(8); PG8_WAIT_L(0); PG8_BAR; PG8_MMA(0, 0, At, B0); PG8_MMA(0, 1, At, B1); PG8_BAR; PG8_SCHED;
;             PG8_LDA(At, 0, 1); PG8_STAGE(PG8_SB(0, 0), b2, voffB); PG8_STAGE(PG8_SB(0, 1), b2 + hstep, voffB); PG8_STAGE(PG8_SA(0, 0), a2, voffA);
;             PG8_WAIT_V(8); PG8_WAIT_L(0); PG8_BAR; PG8_MMA(1, 0, At, B0); PG8_MMA(1, 1, At, B1); PG8_BAR; PG8_SCHED;
.LBB0_2601:
	s_mov_b64 s[42:43], s[10:11]
	s_add_i32 s10, s30, s40
	s_mov_b64 s[36:37], s[12:13]
	s_mov_b32 s12, s56
	s_mov_b32 s13, s55
	s_and_b32 s55, s10, 3
	s_ashr_i32 s56, s10, 2
	s_and_b64 s[10:11], s[26:27], exec
	s_cselect_b32 s12, s56, s12
	ds_read_b128 v[0:3], v134
	ds_read_b128 v[4:7], v134 offset:1024
	ds_read_b128 v[8:11], v134 offset:2048
	ds_read_b128 v[12:15], v134 offset:3072
	ds_read_b128 v[16:19], v135
	ds_read_b128 v[20:23], v135 offset:1024
	ds_read_b128 v[24:27], v135 offset:2048
	ds_read_b128 v[28:31], v135 offset:3072
	s_cselect_b32 s10, s55, s13
	s_ashr_i32 s13, s12, 31
	s_lshl_b64 s[12:13], s[12:13], 17
	s_add_u32 s12, s41, s12
	s_addc_u32 s13, s44, s13
	s_and_b64 s[30:31], s[26:27], exec
	s_cselect_b32 s35, s13, s37
	s_cselect_b32 s34, s12, s36
	s_ashr_i32 s11, s10, 31
	s_lshl_b64 s[10:11], s[10:11], 17
	s_add_u32 s10, s45, s10
	s_addc_u32 s11, s46, s11
	s_and_b64 s[30:31], s[26:27], exec
	s_cselect_b32 s31, s11, s43
	s_cselect_b32 s30, s10, s42
	s_add_u32 s58, s36, 0x10080
	s_addc_u32 s59, s37, 0
	s_mov_b32 m0, s91
	v_lshl_add_u64 v[64:65], s[58:59], 0, v[130:131]
	ds_read_b128 v[32:35], v136
	ds_read_b128 v[36:39], v136 offset:1024
	ds_read_b128 v[40:43], v136 offset:2048
	ds_read_b128 v[44:47], v136 offset:3072
	ds_read_b128 v[48:51], v136 offset:4096
	ds_read_b128 v[52:55], v136 offset:5120
	ds_read_b128 v[56:59], v136 offset:6144
	ds_read_b128 v[60:63], v136 offset:7168
	global_load_lds_dwordx4 v[64:65], off
	v_lshl_add_u64 v[64:65], s[58:59], 0, v[128:129]
	s_mov_b32 m0, s14
	s_nop 0
	global_load_lds_dwordx4 v[64:65], off
	s_waitcnt vmcnt(8)
	s_waitcnt lgkmcnt(0)
	s_barrier
	s_setprio 1
	s_waitcnt lgkmcnt(0)
	v_mfma_f32_16x16x32_bf16 v[64:67], v[0:3], v[32:35], 0
	v_mfma_f32_16x16x32_bf16 v[68:71], v[8:11], v[32:35], 0
	v_mfma_f32_16x16x32_bf16 v[72:75], v[0:3], v[40:43], 0
	v_mfma_f32_16x16x32_bf16 v[76:79], v[8:11], v[40:43], 0
	v_mfma_f32_16x16x32_bf16 v[80:83], v[0:3], v[48:51], 0
	v_mfma_f32_16x16x32_bf16 v[84:87], v[8:11], v[48:51], 0
	v_mfma_f32_16x16x32_bf16 v[88:91], v[0:3], v[56:59], 0
	v_mfma_f32_16x16x32_bf16 v[92:95], v[8:11], v[56:59], 0
	v_mfma_f32_16x16x32_bf16 v[64:67], v[4:7], v[36:39], v[64:67]
	v_mfma_f32_16x16x32_bf16 v[68:71], v[12:15], v[36:39], v[68:71]
	v_mfma_f32_16x16x32_bf16 v[72:75], v[4:7], v[44:47], v[72:75]
	v_mfma_f32_16x16x32_bf16 v[76:79], v[12:15], v[44:47], v[76:79]
	v_mfma_f32_16x16x32_bf16 v[80:83], v[4:7], v[52:55], v[80:83]
	v_mfma_f32_16x16x32_bf16 v[84:87], v[12:15], v[52:55], v[84:87]
	v_mfma_f32_16x16x32_bf16 v[88:91], v[4:7], v[60:63], v[88:91]
	v_mfma_f32_16x16x32_bf16 v[92:95], v[12:15], v[60:63], v[92:95]
	s_setprio 0
	s_setprio 1
	v_mfma_f32_16x16x32_bf16 v[96:99], v[16:19], v[32:35], 0
	v_mfma_f32_16x16x32_bf16 v[32:35], v[24:27], v[32:35], 0
	v_mfma_f32_16x16x32_bf16 v[96:99], v[20:23], v[36:39], v[96:99]
	v_mfma_f32_16x16x32_bf16 v[32:35], v[28:31], v[36:39], v[32:35]
	v_mfma_f32_16x16x32_bf16 v[36:39], v[16:19], v[40:43], 0
	v_mfma_f32_16x16x32_bf16 v[40:43], v[24:27], v[40:43], 0
	v_mfma_f32_16x16x32_bf16 v[36:39], v[20:23], v[44:47], v[36:39]
	v_mfma_f32_16x16x32_bf16 v[40:43], v[28:31], v[44:47], v[40:43]
	v_mfma_f32_16x16x32_bf16 v[44:47], v[16:19], v[48:51], 0
	v_mfma_f32_16x16x32_bf16 v[48:51], v[24:27], v[48:51], 0
	v_mfma_f32_16x16x32_bf16 v[44:47], v[20:23], v[52:55], v[44:47]
	v_mfma_f32_16x16x32_bf16 v[48:51], v[28:31], v[52:55], v[48:51]
	s_barrier
	v_mfma_f32_16x16x32_bf16 v[52:55], v[16:19], v[56:59], 0
	v_mfma_f32_16x16x32_bf16 v[56:59], v[24:27], v[56:59], 0
	v_mfma_f32_16x16x32_bf16 v[52:55], v[20:23], v[60:63], v[52:55]
	v_mfma_f32_16x16x32_bf16 v[56:59], v[28:31], v[60:63], v[56:59]
	s_setprio 0
	v_lshl_add_u64 v[204:205], s[42:43], 0, v[130:131]
	s_mov_b32 m0, s15
	v_lshl_add_u64 v[140:141], v[204:205], 0, s[22:23]
	v_lshl_add_u64 v[206:207], s[42:43], 0, v[128:129]
	s_add_u32 s58, s42, 0x10100
	ds_read_b128 v[60:63], v136 offset:16384
	ds_read_b128 v[100:103], v136 offset:17408
	ds_read_b128 v[104:107], v136 offset:18432
	ds_read_b128 v[108:111], v136 offset:19456
	ds_read_b128 v[112:115], v136 offset:20480
	ds_read_b128 v[116:119], v136 offset:21504
	ds_read_b128 v[120:123], v136 offset:22528
	ds_read_b128 v[124:127], v136 offset:23552
	global_load_lds_dwordx4 v[140:141], off
	v_lshl_add_u64 v[140:141], v[206:207], 0, s[22:23]
	s_mov_b32 m0, s48
	s_addc_u32 s59, s43, 0
	global_load_lds_dwordx4 v[140:141], off
	v_lshl_add_u64 v[140:141], s[58:59], 0, v[130:131]
	s_mov_b32 m0, s49
	v_lshl_add_u64 v[208:209], s[36:37], 0, v[130:131]
	global_load_lds_dwordx4 v[140:141], off
	v_lshl_add_u64 v[140:141], s[58:59], 0, v[128:129]
	s_mov_b32 m0, s50
	v_lshl_add_u64 v[210:211], s[36:37], 0, v[128:129]
	global_load_lds_dwordx4 v[140:141], off
	v_lshl_add_u64 v[140:141], v[208:209], 0, s[22:23]
	s_mov_b32 m0, s74
	s_nop 0
	global_load_lds_dwordx4 v[140:141], off
	v_lshl_add_u64 v[140:141], v[210:211], 0, s[22:23]
	s_mov_b32 m0, s66
	s_nop 0
	global_load_lds_dwordx4 v[140:141], off
	s_waitcnt vmcnt(8)
	s_waitcnt lgkmcnt(0)
	s_barrier
; #define PG8_STAGE(bufoff, gbase, voff) do { _Pragma("unroll") for (int _i = 0; _i < 2; ++_i) \
;         __builtin_amdgcn_global_load_lds((const unsigned*)((const char*)(gbase) + (voff)[_i]), (PG8_LAS unsigned*)(lds + (bufoff) + ldsw + _i * 8192), 16, 0, 0); } while (0)
; #define PG8_LDA(dst, b, h) do { _Pragma("unroll") for (int m = 0; m < 4; ++m) _Pragma("unroll") for (int k = 0; k < 2; ++k) dst[m][k] = *(const PG8_LAS bf16x8*)(lds + PG8_SA(b, h) + aoff + m * 2048 + k * 1024); } while (0)
; #define PG8_LDB(dst, b, h) do { _Pragma("unroll") for (int n = 0; n < 2; ++n) _Pragma("unroll") for (int k = 0; k < 2; ++k) dst[n][k] = *(const PG8_LAS bf16x8*)(lds + PG8_SB(b, h) + boff + n * 2048 + k * 1024); } while (0)
; #define PG8_MMA(ai, bj, At, Bt) do { __builtin_amdgcn_s_setprio(1); _Pragma("unroll") for (int m = 0; m < 4; ++m) _Pragma("unroll") for (int n = 0; n < 2; ++n) _Pragma("unroll") for (int k = 0; k < 2; ++k) \
;         acc[ai][bj][m][n] = mma16<F16>(Bt[n][k], At[m][k], acc[ai][bj][m][n]); __builtin_amdgcn_s_setprio(0); } while (0)
; #define PG8_WAIT_V(n) asm volatile("s_waitcnt vmcnt(" #n ")" ::: "memory")
; #define PG8_WAIT_L(n) asm volatile("s_waitcnt lgkmcnt(" #n ")" ::: "memory")
; #define PG8_BAR __builtin_amdgcn_s_barrier()
; #define PG8_SCHED __builtin_amdgcn_sched_barrier(0)
; template <class Epi, class Sched, bool ALIGN_EPI = false, bool SP2 = false, bool F16 = false>
; __device__ __forceinline__ void gemm_phase(PG8_LAS unsigned char* lds, const Gemm g, const Sched& S, const Epi& E, const int wid_in) {
;     ...
;             PG8_WAIT_V(8); PG8_WAIT_L(0); PG8_BAR; PG8_MMA(1, 0, At, B0); PG8_MMA(1, 1, At, B1); PG8_BAR; PG8_SCHED;
;             PG8_LDB(B0, 1, 0); PG8_LDB(B1, 1, 1); PG8_SCHED; PG8_LDA(At, 1, 0); PG8_STAGE(PG8_SA(0, 1), a2 + hstep, voffA);
;             PG8_WAIT_V(8); PG8_WAIT_L(0); PG8_BAR; PG8_MMA(0, 0, At, B0); PG8_MMA(0, 1, At, B1); PG8_BAR; PG8_SCHED;
	s_setprio 1
	s_waitcnt lgkmcnt(0)
	v_mfma_f32_16x16x32_bf16 v[140:143], v[0:3], v[60:63], 0
	v_mfma_f32_16x16x32_bf16 v[148:151], v[0:3], v[104:107], 0
	v_mfma_f32_16x16x32_bf16 v[156:159], v[0:3], v[112:115], 0
	v_mfma_f32_16x16x32_bf16 v[0:3], v[0:3], v[120:123], 0
	v_mfma_f32_16x16x32_bf16 v[140:143], v[4:7], v[100:103], v[140:143]
	v_mfma_f32_16x16x32_bf16 v[148:151], v[4:7], v[108:111], v[148:151]
	v_mfma_f32_16x16x32_bf16 v[156:159], v[4:7], v[116:119], v[156:159]
	v_mfma_f32_16x16x32_bf16 v[0:3], v[4:7], v[124:127], v[0:3]
	v_mfma_f32_16x16x32_bf16 v[4:7], v[8:11], v[120:123], 0
	v_mfma_f32_16x16x32_bf16 v[144:147], v[8:11], v[60:63], 0
	v_mfma_f32_16x16x32_bf16 v[152:155], v[8:11], v[104:107], 0
	v_mfma_f32_16x16x32_bf16 v[160:163], v[8:11], v[112:115], 0
	v_mfma_f32_16x16x32_bf16 v[4:7], v[12:15], v[124:127], v[4:7]
	v_mfma_f32_16x16x32_bf16 v[144:147], v[12:15], v[100:103], v[144:147]
	v_mfma_f32_16x16x32_bf16 v[152:155], v[12:15], v[108:111], v[152:155]
	v_mfma_f32_16x16x32_bf16 v[160:163], v[12:15], v[116:119], v[160:163]
	s_setprio 0
	s_setprio 1
	v_mfma_f32_16x16x32_bf16 v[8:11], v[16:19], v[60:63], 0
	v_mfma_f32_16x16x32_bf16 v[12:15], v[24:27], v[60:63], 0
	v_mfma_f32_16x16x32_bf16 v[8:11], v[20:23], v[100:103], v[8:11]
	v_mfma_f32_16x16x32_bf16 v[12:15], v[28:31], v[100:103], v[12:15]
	v_mfma_f32_16x16x32_bf16 v[60:63], v[16:19], v[104:107], 0
	v_mfma_f32_16x16x32_bf16 v[100:103], v[24:27], v[104:107], 0
	v_mfma_f32_16x16x32_bf16 v[104:107], v[16:19], v[112:115], 0
	v_mfma_f32_16x16x32_bf16 v[16:19], v[16:19], v[120:123], 0
	v_mfma_f32_16x16x32_bf16 v[60:63], v[20:23], v[108:111], v[60:63]
	v_mfma_f32_16x16x32_bf16 v[100:103], v[28:31], v[108:111], v[100:103]
	v_mfma_f32_16x16x32_bf16 v[104:107], v[20:23], v[116:119], v[104:107]
	v_mfma_f32_16x16x32_bf16 v[108:111], v[24:27], v[112:115], 0
	s_barrier
	v_mfma_f32_16x16x32_bf16 v[16:19], v[20:23], v[124:127], v[16:19]
	v_mfma_f32_16x16x32_bf16 v[20:23], v[24:27], v[120:123], 0
	v_mfma_f32_16x16x32_bf16 v[108:111], v[28:31], v[116:119], v[108:111]
	v_mfma_f32_16x16x32_bf16 v[20:23], v[28:31], v[124:127], v[20:23]
	s_setprio 0
	ds_read_b128 v[24:27], v137
	ds_read_b128 v[28:31], v137 offset:1024
	ds_read_b128 v[112:115], v137 offset:2048
	ds_read_b128 v[116:119], v137 offset:3072
	ds_read_b128 v[120:123], v138
	ds_read_b128 v[124:127], v138 offset:1024
	ds_read_b128 v[164:167], v138 offset:2048
	ds_read_b128 v[168:171], v138 offset:3072
	s_add_u32 s58, s36, 0x10100
	s_addc_u32 s59, s37, 0
	s_mov_b32 m0, s90
	v_lshl_add_u64 v[212:213], s[58:59], 0, v[130:131]
	ds_read_b128 v[172:175], v136 offset:32768
	ds_read_b128 v[176:179], v136 offset:33792
	ds_read_b128 v[180:183], v136 offset:34816
	ds_read_b128 v[184:187], v136 offset:35840
	ds_read_b128 v[188:191], v136 offset:36864
	ds_read_b128 v[192:195], v136 offset:37888
	ds_read_b128 v[196:199], v136 offset:38912
	ds_read_b128 v[200:203], v136 offset:39936
	global_load_lds_dwordx4 v[212:213], off
	v_lshl_add_u64 v[212:213], s[58:59], 0, v[128:129]
	s_mov_b32 m0, s47
	s_nop 0
	global_load_lds_dwordx4 v[212:213], off
	s_waitcnt vmcnt(8)
	s_waitcnt lgkmcnt(0)
	s_barrier
	s_setprio 1
	s_waitcnt lgkmcnt(0)
	v_mfma_f32_16x16x32_bf16 v[64:67], v[24:27], v[172:175], v[64:67]
	v_mfma_f32_16x16x32_bf16 v[68:71], v[112:115], v[172:175], v[68:71]
	v_mfma_f32_16x16x32_bf16 v[72:75], v[24:27], v[180:183], v[72:75]
	v_mfma_f32_16x16x32_bf16 v[76:79], v[112:115], v[180:183], v[76:79]
	v_mfma_f32_16x16x32_bf16 v[80:83], v[24:27], v[188:191], v[80:83]
	v_mfma_f32_16x16x32_bf16 v[84:87], v[112:115], v[188:191], v[84:87]
	v_mfma_f32_16x16x32_bf16 v[88:91], v[24:27], v[196:199], v[88:91]
	v_mfma_f32_16x16x32_bf16 v[92:95], v[112:115], v[196:199], v[92:95]
	v_mfma_f32_16x16x32_bf16 v[64:67], v[28:31], v[176:179], v[64:67]
	v_mfma_f32_16x16x32_bf16 v[68:71], v[116:119], v[176:179], v[68:71]
	v_mfma_f32_16x16x32_bf16 v[72:75], v[28:31], v[184:187], v[72:75]
	v_mfma_f32_16x16x32_bf16 v[76:79], v[116:119], v[184:187], v[76:79]
	v_mfma_f32_16x16x32_bf16 v[80:83], v[28:31], v[192:195], v[80:83]
	v_mfma_f32_16x16x32_bf16 v[84:87], v[116:119], v[192:195], v[84:87]
	v_mfma_f32_16x16x32_bf16 v[88:91], v[28:31], v[200:203], v[88:91]
	v_mfma_f32_16x16x32_bf16 v[92:95], v[116:119], v[200:203], v[92:95]
	s_setprio 0
	s_setprio 1
	v_mfma_f32_16x16x32_bf16 v[96:99], v[120:123], v[172:175], v[96:99]
	v_mfma_f32_16x16x32_bf16 v[32:35], v[164:167], v[172:175], v[32:35]
	v_mfma_f32_16x16x32_bf16 v[36:39], v[120:123], v[180:183], v[36:39]
	v_mfma_f32_16x16x32_bf16 v[40:43], v[164:167], v[180:183], v[40:43]
	v_mfma_f32_16x16x32_bf16 v[44:47], v[120:123], v[188:191], v[44:47]
	v_mfma_f32_16x16x32_bf16 v[48:51], v[164:167], v[188:191], v[48:51]
	v_mfma_f32_16x16x32_bf16 v[52:55], v[120:123], v[196:199], v[52:55]
	v_mfma_f32_16x16x32_bf16 v[56:59], v[164:167], v[196:199], v[56:59]
	v_mfma_f32_16x16x32_bf16 v[96:99], v[124:127], v[176:179], v[96:99]
	v_mfma_f32_16x16x32_bf16 v[32:35], v[168:171], v[176:179], v[32:35]
	v_mfma_f32_16x16x32_bf16 v[36:39], v[124:127], v[184:187], v[36:39]
	v_mfma_f32_16x16x32_bf16 v[40:43], v[168:171], v[184:187], v[40:43]
	s_barrier
; #define PG8_STAGE(bufoff, gbase, voff) do { _Pragma("unroll") for (int _i = 0; _i < 2; ++_i) \
;         __builtin_amdgcn_global_load_lds((const unsigned*)((const char*)(gbase) + (voff)[_i]), (PG8_LAS unsigned*)(lds + (bufoff) + ldsw + _i * 8192), 16, 0, 0); } while (0)
; #define PG8_LDA(dst, b, h) do { _Pragma("unroll") for (int m = 0; m < 4; ++m) _Pragma("unroll") for (int k = 0; k < 2; ++k) dst[m][k] = *(const PG8_LAS bf16x8*)(lds + PG8_SA(b, h) + aoff + m * 2048 + k * 1024); } while (0)
; #define PG8_LDB(dst, b, h) do { _Pragma("unroll") for (int n = 0; n < 2; ++n) _Pragma("unroll") for (int k = 0; k < 2; ++k) dst[n][k] = *(const PG8_LAS bf16x8*)(lds + PG8_SB(b, h) + boff + n * 2048 + k * 1024); } while (0)
; #define PG8_MMA(ai, bj, At, Bt) do { __builtin_amdgcn_s_setprio(1); _Pragma("unroll") for (int m = 0; m < 4; ++m) _Pragma("unroll") for (int n = 0; n < 2; ++n) _Pragma("unroll") for (int k = 0; k < 2; ++k) \
;         acc[ai][bj][m][n] = mma16<F16>(Bt[n][k], At[m][k], acc[ai][bj][m][n]); __builtin_amdgcn_s_setprio(0); } while (0)
; #define PG8_WAIT_V(n) asm volatile("s_waitcnt vmcnt(" #n ")" ::: "memory")
; #define PG8_WAIT_L(n) asm volatile("s_waitcnt lgkmcnt(" #n ")" ::: "memory")
; #define PG8_BAR __builtin_amdgcn_s_barrier()
; #define PG8_SCHED __builtin_amdgcn_sched_barrier(0)
; template <class Epi, class Sched, bool ALIGN_EPI = false, bool SP2 = false, bool F16 = false>
; __device__ __forceinline__ void gemm_phase(PG8_LAS unsigned char* lds, const Gemm g, const Sched& S, const Epi& E, const int wid_in) {
;     ...
;             PG8_WAIT_V(8); PG8_WAIT_L(0); PG8_BAR; PG8_MMA(0, 0, At, B0); PG8_MMA(0, 1, At, B1); PG8_BAR; PG8_SCHED;
;             PG8_LDA(At, 1, 1); PG8_STAGE(PG8_SB(1, 0), b3, voffB); PG8_STAGE(PG8_SB(1, 1), b3 + hstep, voffB); PG8_STAGE(PG8_SA(1, 0), a3, voffA);
;             PG8_WAIT_V(8); PG8_WAIT_L(0); PG8_BAR; PG8_MMA(1, 0, At, B0); PG8_MMA(1, 1, At, B1); PG8_BAR; PG8_SCHED;
;             } else {
;             PG8_LDB(B0, 0, 0); PG8_SCHED; PG8_LDA(At, 0, 0); PG8_STAGE(PG8_SA(1, 1), a1 + hstep, voffA);
	v_mfma_f32_16x16x32_bf16 v[44:47], v[124:127], v[192:195], v[44:47]
	v_mfma_f32_16x16x32_bf16 v[48:51], v[168:171], v[192:195], v[48:51]
	v_mfma_f32_16x16x32_bf16 v[52:55], v[124:127], v[200:203], v[52:55]
	v_mfma_f32_16x16x32_bf16 v[56:59], v[168:171], v[200:203], v[56:59]
	s_setprio 0
	s_mov_b32 m0, s51
	v_lshl_add_u64 v[204:205], v[204:205], 0, s[24:25]
	s_add_u32 s42, s42, 0x10180
	ds_read_b128 v[172:175], v136 offset:49152
	ds_read_b128 v[176:179], v136 offset:50176
	ds_read_b128 v[180:183], v136 offset:51200
	ds_read_b128 v[184:187], v136 offset:52224
	ds_read_b128 v[188:191], v136 offset:53248
	ds_read_b128 v[192:195], v136 offset:54272
	ds_read_b128 v[196:199], v136 offset:55296
	ds_read_b128 v[200:203], v136 offset:56320
	global_load_lds_dwordx4 v[204:205], off
	v_lshl_add_u64 v[204:205], v[206:207], 0, s[24:25]
	s_mov_b32 m0, s52
	s_addc_u32 s43, s43, 0
	global_load_lds_dwordx4 v[204:205], off
	v_lshl_add_u64 v[204:205], s[42:43], 0, v[130:131]
	s_mov_b32 m0, s53
	s_nop 0
	global_load_lds_dwordx4 v[204:205], off
	v_lshl_add_u64 v[204:205], s[42:43], 0, v[128:129]
	s_mov_b32 m0, s54
	s_nop 0
	global_load_lds_dwordx4 v[204:205], off
	v_lshl_add_u64 v[204:205], v[208:209], 0, s[24:25]
	s_mov_b32 m0, s75
	s_nop 0
	global_load_lds_dwordx4 v[204:205], off
	v_lshl_add_u64 v[204:205], v[210:211], 0, s[24:25]
	s_mov_b32 m0, s67
	s_nop 0
	global_load_lds_dwordx4 v[204:205], off
	s_waitcnt vmcnt(8)
	s_waitcnt lgkmcnt(0)
	s_barrier
	s_setprio 1
	s_waitcnt lgkmcnt(0)
	v_mfma_f32_16x16x32_bf16 v[0:3], v[24:27], v[196:199], v[0:3]
	v_mfma_f32_16x16x32_bf16 v[4:7], v[112:115], v[196:199], v[4:7]
	v_mfma_f32_16x16x32_bf16 v[140:143], v[24:27], v[172:175], v[140:143]
	v_mfma_f32_16x16x32_bf16 v[144:147], v[112:115], v[172:175], v[144:147]
	v_mfma_f32_16x16x32_bf16 v[148:151], v[24:27], v[180:183], v[148:151]
	v_mfma_f32_16x16x32_bf16 v[152:155], v[112:115], v[180:183], v[152:155]
	v_mfma_f32_16x16x32_bf16 v[156:159], v[24:27], v[188:191], v[156:159]
	v_mfma_f32_16x16x32_bf16 v[160:163], v[112:115], v[188:191], v[160:163]
	v_mfma_f32_16x16x32_bf16 v[0:3], v[28:31], v[200:203], v[0:3]
	v_mfma_f32_16x16x32_bf16 v[4:7], v[116:119], v[200:203], v[4:7]
	v_mfma_f32_16x16x32_bf16 v[140:143], v[28:31], v[176:179], v[140:143]
	v_mfma_f32_16x16x32_bf16 v[144:147], v[116:119], v[176:179], v[144:147]
	v_mfma_f32_16x16x32_bf16 v[148:151], v[28:31], v[184:187], v[148:151]
	v_mfma_f32_16x16x32_bf16 v[152:155], v[116:119], v[184:187], v[152:155]
	v_mfma_f32_16x16x32_bf16 v[156:159], v[28:31], v[192:195], v[156:159]
	v_mfma_f32_16x16x32_bf16 v[160:163], v[116:119], v[192:195], v[160:163]
	s_setprio 0
	s_setprio 1
	v_mfma_f32_16x16x32_bf16 v[8:11], v[120:123], v[172:175], v[8:11]
	v_mfma_f32_16x16x32_bf16 v[12:15], v[164:167], v[172:175], v[12:15]
	v_mfma_f32_16x16x32_bf16 v[24:27], v[120:123], v[180:183], v[60:63]
	v_mfma_f32_16x16x32_bf16 v[28:31], v[164:167], v[180:183], v[100:103]
	v_mfma_f32_16x16x32_bf16 v[60:63], v[120:123], v[188:191], v[104:107]
	v_mfma_f32_16x16x32_bf16 v[100:103], v[164:167], v[188:191], v[108:111]
	v_mfma_f32_16x16x32_bf16 v[16:19], v[120:123], v[196:199], v[16:19]
	v_mfma_f32_16x16x32_bf16 v[20:23], v[164:167], v[196:199], v[20:23]
	v_mfma_f32_16x16x32_bf16 v[8:11], v[124:127], v[176:179], v[8:11]
	v_mfma_f32_16x16x32_bf16 v[12:15], v[168:171], v[176:179], v[12:15]
	v_mfma_f32_16x16x32_bf16 v[24:27], v[124:127], v[184:187], v[24:27]
	v_mfma_f32_16x16x32_bf16 v[28:31], v[168:171], v[184:187], v[28:31]
	s_barrier
	v_mfma_f32_16x16x32_bf16 v[60:63], v[124:127], v[192:195], v[60:63]
	v_mfma_f32_16x16x32_bf16 v[100:103], v[168:171], v[192:195], v[100:103]
	v_mfma_f32_16x16x32_bf16 v[16:19], v[124:127], v[200:203], v[16:19]
	v_mfma_f32_16x16x32_bf16 v[20:23], v[168:171], v[200:203], v[20:23]
	s_setprio 0
	ds_read_b128 v[104:107], v134
	ds_read_b128 v[108:111], v134 offset:1024
	ds_read_b128 v[112:115], v134 offset:2048
	ds_read_b128 v[116:119], v134 offset:3072
	ds_read_b128 v[120:123], v135
	ds_read_b128 v[124:127], v135 offset:1024
	ds_read_b128 v[164:167], v135 offset:2048
	ds_read_b128 v[168:171], v135 offset:3072
	s_add_u32 s36, s36, 0x10180
	s_addc_u32 s37, s37, 0
	s_mov_b32 m0, s91
	v_lshl_add_u64 v[204:205], s[36:37], 0, v[130:131]
	ds_read_b128 v[172:175], v136
	ds_read_b128 v[176:179], v136 offset:1024
	ds_read_b128 v[180:183], v136 offset:2048
	ds_read_b128 v[184:187], v136 offset:3072
	ds_read_b128 v[188:191], v136 offset:4096
	ds_read_b128 v[192:195], v136 offset:5120
	ds_read_b128 v[196:199], v136 offset:6144
	ds_read_b128 v[200:203], v136 offset:7168
	global_load_lds_dwordx4 v[204:205], off
	v_lshl_add_u64 v[204:205], s[36:37], 0, v[128:129]
	s_mov_b32 m0, s14
	s_nop 0
	global_load_lds_dwordx4 v[204:205], off
	s_waitcnt vmcnt(8)
	s_waitcnt lgkmcnt(0)
	s_barrier
; #define PG8_STAGE(bufoff, gbase, voff) do { _Pragma("unroll") for (int _i = 0; _i < 2; ++_i) \
;         __builtin_amdgcn_global_load_lds((const unsigned*)((const char*)(gbase) + (voff)[_i]), (PG8_LAS unsigned*)(lds + (bufoff) + ldsw + _i * 8192), 16, 0, 0); } while (0)
; #define PG8_LDA(dst, b, h) do { _Pragma("unroll") for (int m = 0; m < 4; ++m) _Pragma("unroll") for (int k = 0; k < 2; ++k) dst[m][k] = *(const PG8_LAS bf16x8*)(lds + PG8_SA(b, h) + aoff + m * 2048 + k * 1024); } while (0)
; #define PG8_MMA(ai, bj, At, Bt) do { __builtin_amdgcn_s_setprio(1); _Pragma("unroll") for (int m = 0; m < 4; ++m) _Pragma("unroll") for (int n = 0; n < 2; ++n) _Pragma("unroll") for (int k = 0; k < 2; ++k) \
;         acc[ai][bj][m][n] = mma16<F16>(Bt[n][k], At[m][k], acc[ai][bj][m][n]); __builtin_amdgcn_s_setprio(0); } while (0)
; #define PG8_WAIT_V(n) asm volatile("s_waitcnt vmcnt(" #n ")" ::: "memory")
; #define PG8_WAIT_L(n) asm volatile("s_waitcnt lgkmcnt(" #n ")" ::: "memory")
; #define PG8_BAR __builtin_amdgcn_s_barrier()
; #define PG8_SCHED __builtin_amdgcn_sched_barrier(0)
; template <class Epi, class Sched, bool ALIGN_EPI = false, bool SP2 = false, bool F16 = false>
; __device__ __forceinline__ void gemm_phase(PG8_LAS unsigned char* lds, const Gemm g, const Sched& S, const Epi& E, const int wid_in) {
;     ...
;             PG8_WAIT_V(8); PG8_WAIT_L(0); PG8_BAR; PG8_MMA(0, 0, At, B0); PG8_MMA(0, 1, At, B1); PG8_BAR; PG8_SCHED;
;             PG8_LDA(At, 1, 1); PG8_STAGE(PG8_SB(1, 0), b3, voffB); PG8_STAGE(PG8_SB(1, 1), b3 + hstep, voffB); PG8_STAGE(PG8_SA(1, 0), a3, voffA);
;             PG8_WAIT_V(8); PG8_WAIT_L(0); PG8_BAR; PG8_MMA(1, 0, At, B0); PG8_MMA(1, 1, At, B1); PG8_BAR; PG8_SCHED;
	s_setprio 1
	s_waitcnt lgkmcnt(0)
	v_mfma_f32_16x16x32_bf16 v[64:67], v[104:107], v[172:175], v[64:67]
	v_mfma_f32_16x16x32_bf16 v[68:71], v[112:115], v[172:175], v[68:71]
	v_mfma_f32_16x16x32_bf16 v[72:75], v[104:107], v[180:183], v[72:75]
	v_mfma_f32_16x16x32_bf16 v[76:79], v[112:115], v[180:183], v[76:79]
	v_mfma_f32_16x16x32_bf16 v[80:83], v[104:107], v[188:191], v[80:83]
	v_mfma_f32_16x16x32_bf16 v[84:87], v[112:115], v[188:191], v[84:87]
	v_mfma_f32_16x16x32_bf16 v[88:91], v[104:107], v[196:199], v[88:91]
	v_mfma_f32_16x16x32_bf16 v[92:95], v[112:115], v[196:199], v[92:95]
	v_mfma_f32_16x16x32_bf16 v[64:67], v[108:111], v[176:179], v[64:67]
	v_mfma_f32_16x16x32_bf16 v[68:71], v[116:119], v[176:179], v[68:71]
	v_mfma_f32_16x16x32_bf16 v[72:75], v[108:111], v[184:187], v[72:75]
	v_mfma_f32_16x16x32_bf16 v[76:79], v[116:119], v[184:187], v[76:79]
	v_mfma_f32_16x16x32_bf16 v[80:83], v[108:111], v[192:195], v[80:83]
	v_mfma_f32_16x16x32_bf16 v[84:87], v[116:119], v[192:195], v[84:87]
	v_mfma_f32_16x16x32_bf16 v[88:91], v[108:111], v[200:203], v[88:91]
	v_mfma_f32_16x16x32_bf16 v[92:95], v[116:119], v[200:203], v[92:95]
	s_setprio 0
	s_setprio 1
	v_mfma_f32_16x16x32_bf16 v[32:35], v[164:167], v[172:175], v[32:35]
	v_mfma_f32_16x16x32_bf16 v[96:99], v[120:123], v[172:175], v[96:99]
	v_mfma_f32_16x16x32_bf16 v[172:175], v[168:171], v[176:179], v[32:35]
	v_mfma_f32_16x16x32_bf16 v[32:35], v[120:123], v[180:183], v[36:39]
	v_mfma_f32_16x16x32_bf16 v[204:207], v[124:127], v[176:179], v[96:99]
	v_mfma_f32_16x16x32_bf16 v[176:179], v[124:127], v[184:187], v[32:35]
	v_mfma_f32_16x16x32_bf16 v[32:35], v[164:167], v[180:183], v[40:43]
	v_mfma_f32_16x16x32_bf16 v[40:43], v[168:171], v[184:187], v[32:35]
	v_mfma_f32_16x16x32_bf16 v[32:35], v[120:123], v[188:191], v[44:47]
	v_mfma_f32_16x16x32_bf16 v[44:47], v[124:127], v[192:195], v[32:35]
	v_mfma_f32_16x16x32_bf16 v[32:35], v[164:167], v[188:191], v[48:51]
	v_mfma_f32_16x16x32_bf16 v[48:51], v[168:171], v[192:195], v[32:35]
	s_barrier
	v_mfma_f32_16x16x32_bf16 v[32:35], v[120:123], v[196:199], v[52:55]
	v_mfma_f32_16x16x32_bf16 v[52:55], v[124:127], v[200:203], v[32:35]
	v_mfma_f32_16x16x32_bf16 v[32:35], v[164:167], v[196:199], v[56:59]
	v_mfma_f32_16x16x32_bf16 v[56:59], v[168:171], v[200:203], v[32:35]
	s_setprio 0
	s_mov_b32 m0, s15
	v_lshl_add_u64 v[240:241], s[30:31], 0, v[130:131]
	s_add_u32 s36, s30, 0x10000
	s_nop 1
	ds_read_b128 v[32:35], v136 offset:16384
	ds_read_b128 v[36:39], v136 offset:17408
	ds_read_b128 v[96:99], v136 offset:18432
	ds_read_b128 v[180:183], v136 offset:19456
	ds_read_b128 v[184:187], v136 offset:20480
	ds_read_b128 v[188:191], v136 offset:21504
	ds_read_b128 v[192:195], v136 offset:22528
	ds_read_b128 v[196:199], v136 offset:23552
	global_load_lds_dwordx4 v[240:241], off
	v_lshl_add_u64 v[242:243], s[30:31], 0, v[128:129]
	s_mov_b32 m0, s48
	s_addc_u32 s37, s31, 0
	global_load_lds_dwordx4 v[242:243], off
	v_lshl_add_u64 v[200:201], s[36:37], 0, v[130:131]
	s_mov_b32 m0, s49
	v_lshl_add_u64 v[244:245], s[34:35], 0, v[130:131]
	global_load_lds_dwordx4 v[200:201], off
	v_lshl_add_u64 v[200:201], s[36:37], 0, v[128:129]
	s_mov_b32 m0, s50
	v_lshl_add_u64 v[246:247], s[34:35], 0, v[128:129]
	global_load_lds_dwordx4 v[200:201], off
	s_mov_b32 m0, s74
	s_nop 0
	global_load_lds_dwordx4 v[244:245], off
	s_mov_b32 m0, s66
	s_nop 0
	global_load_lds_dwordx4 v[246:247], off
	s_waitcnt vmcnt(8)
	s_waitcnt lgkmcnt(0)
	s_barrier
	s_setprio 1
	s_waitcnt lgkmcnt(0)
	v_mfma_f32_16x16x32_bf16 v[0:3], v[104:107], v[192:195], v[0:3]
	v_mfma_f32_16x16x32_bf16 v[140:143], v[104:107], v[32:35], v[140:143]
	v_mfma_f32_16x16x32_bf16 v[144:147], v[112:115], v[32:35], v[144:147]
	v_mfma_f32_16x16x32_bf16 v[148:151], v[104:107], v[96:99], v[148:151]
	v_mfma_f32_16x16x32_bf16 v[152:155], v[112:115], v[96:99], v[152:155]
	v_mfma_f32_16x16x32_bf16 v[156:159], v[104:107], v[184:187], v[156:159]
	v_mfma_f32_16x16x32_bf16 v[160:163], v[112:115], v[184:187], v[160:163]
	v_mfma_f32_16x16x32_bf16 v[0:3], v[108:111], v[196:199], v[0:3]
	v_mfma_f32_16x16x32_bf16 v[4:7], v[112:115], v[192:195], v[4:7]
	v_mfma_f32_16x16x32_bf16 v[140:143], v[108:111], v[36:39], v[140:143]
	v_mfma_f32_16x16x32_bf16 v[144:147], v[116:119], v[36:39], v[144:147]
	v_mfma_f32_16x16x32_bf16 v[148:151], v[108:111], v[180:183], v[148:151]
	v_mfma_f32_16x16x32_bf16 v[152:155], v[116:119], v[180:183], v[152:155]
	v_mfma_f32_16x16x32_bf16 v[156:159], v[108:111], v[188:191], v[156:159]
	v_mfma_f32_16x16x32_bf16 v[160:163], v[116:119], v[188:191], v[160:163]
	v_mfma_f32_16x16x32_bf16 v[200:203], v[116:119], v[196:199], v[4:7]
	s_setprio 0
	s_setprio 1
	v_mfma_f32_16x16x32_bf16 v[4:7], v[120:123], v[32:35], v[8:11]
	v_mfma_f32_16x16x32_bf16 v[8:11], v[124:127], v[36:39], v[4:7]
	v_mfma_f32_16x16x32_bf16 v[4:7], v[164:167], v[32:35], v[12:15]
	v_mfma_f32_16x16x32_bf16 v[12:15], v[168:171], v[36:39], v[4:7]
	v_mfma_f32_16x16x32_bf16 v[4:7], v[120:123], v[96:99], v[24:27]
	v_mfma_f32_16x16x32_bf16 v[24:27], v[124:127], v[180:183], v[4:7]
	v_mfma_f32_16x16x32_bf16 v[4:7], v[164:167], v[96:99], v[28:31]
	v_mfma_f32_16x16x32_bf16 v[28:31], v[168:171], v[180:183], v[4:7]
	v_mfma_f32_16x16x32_bf16 v[4:7], v[120:123], v[184:187], v[60:63]
	v_mfma_f32_16x16x32_bf16 v[180:183], v[124:127], v[188:191], v[4:7]
	v_mfma_f32_16x16x32_bf16 v[4:7], v[164:167], v[184:187], v[100:103]
	v_mfma_f32_16x16x32_bf16 v[184:187], v[168:171], v[188:191], v[4:7]
	s_barrier
; #define PG8_STAGE(bufoff, gbase, voff) do { _Pragma("unroll") for (int _i = 0; _i < 2; ++_i) \
;         __builtin_amdgcn_global_load_lds((const unsigned*)((const char*)(gbase) + (voff)[_i]), (PG8_LAS unsigned*)(lds + (bufoff) + ldsw + _i * 8192), 16, 0, 0); } while (0)
; template <class Epi, class Sched, bool ALIGN_EPI = false, bool SP2 = false, bool F16 = false>
; __device__ __forceinline__ void gemm_phase(PG8_LAS unsigned char* lds, const Gemm g, const Sched& S, const Epi& E, const int wid_in) {
;     ...
;             PG8_WAIT_V(8); PG8_WAIT_L(0); PG8_BAR; PG8_MMA(0, 0, At, B0); PG8_MMA(0, 1, At, B1); PG8_BAR; PG8_SCHED;
;             PG8_LDA(At, 1, 1); PG8_STAGE(PG8_SB(1, 0), b3, voffB); PG8_STAGE(PG8_SB(1, 1), b3 + hstep, voffB); PG8_STAGE(PG8_SA(1, 0), a3, voffA);
;             PG8_WAIT_V(8); PG8_WAIT_L(0); PG8_BAR; PG8_MMA(1, 0, At, B0); PG8_MMA(1, 1, At, B1); PG8_BAR; PG8_SCHED;
;             } else {
;             PG8_LDB(B0, 0, 0); PG8_SCHED; PG8_LDA(At, 0, 0); PG8_STAGE(PG8_SA(1, 1), a1 + hstep, voffA);
;             PG8_WAIT_L(8); PG8_BAR; PG8_WAIT_L(0); PG8_MMA(0, 0, At, B0); PG8_BAR; PG8_SCHED;
;             PG8_LDB(B1, 0, 1); PG8_STAGE(PG8_SB(0, 0), b2, voffB);
;             PG8_BAR; PG8_WAIT_L(0); PG8_MMA(0, 1, At, B1); PG8_BAR;
;             PG8_LDA(At, 0, 1); PG8_STAGE(PG8_SA(0, 0), a2, voffA);
;             PG8_BAR; PG8_WAIT_L(0); PG8_MMA(1, 0, At, B0); PG8_BAR; PG8_SCHED;
;             PG8_STAGE(PG8_SB(0, 1), b2 + hstep, voffB);
;             PG8_WAIT_V(6); PG8_BAR; PG8_MMA(1, 1, At, B1); PG8_BAR;
;             PG8_LDB(B0, 1, 0); PG8_SCHED; PG8_LDA(At, 1, 0); PG8_STAGE(PG8_SA(0, 1), a2 + hstep, voffA);
;             PG8_WAIT_L(8); PG8_BAR; PG8_WAIT_L(0); PG8_MMA(0, 0, At, B0); PG8_BAR; PG8_SCHED;
;             PG8_LDB(B1, 1, 1); PG8_STAGE(PG8_SB(1, 0), b3, voffB);
;             PG8_BAR; PG8_WAIT_L(0); PG8_MMA(0, 1, At, B1); PG8_BAR;
;             PG8_LDA(At, 1, 1); PG8_STAGE(PG8_SA(1, 0), a3, voffA);
;             PG8_BAR; PG8_WAIT_L(0); PG8_MMA(1, 0, At, B0); PG8_BAR; PG8_SCHED;
;             PG8_STAGE(PG8_SB(1, 1), b3 + hstep, voffB);
;             PG8_WAIT_V(6); PG8_BAR; PG8_MMA(1, 1, At, B1); PG8_BAR;
;             }
;         }
;         if constexpr (ALIGN_EPI) { if (wr == 0) PG8_BAR; }
;         if constexpr (!Epi::AFTER_DRAIN) { E(acc, cur, wr, wc, fr, fq); S.done(cur); }
;         if (!has_next) break;
	v_mfma_f32_16x16x32_bf16 v[4:7], v[120:123], v[192:195], v[16:19]
	v_mfma_f32_16x16x32_bf16 v[188:191], v[124:127], v[196:199], v[4:7]
	v_mfma_f32_16x16x32_bf16 v[4:7], v[164:167], v[192:195], v[20:23]
	v_mfma_f32_16x16x32_bf16 v[164:167], v[168:171], v[196:199], v[4:7]
	s_setprio 0
	s_nop 4
	ds_read_b128 v[4:7], v137
	ds_read_b128 v[60:63], v137 offset:1024
	ds_read_b128 v[168:171], v137 offset:2048
	ds_read_b128 v[192:195], v137 offset:3072
	ds_read_b128 v[196:199], v138
	ds_read_b128 v[208:211], v138 offset:1024
	ds_read_b128 v[212:215], v138 offset:2048
	ds_read_b128 v[216:219], v138 offset:3072
	s_add_u32 s34, s34, 0x10000
	s_addc_u32 s35, s35, 0
	s_mov_b32 m0, s90
	v_lshl_add_u64 v[32:33], s[34:35], 0, v[130:131]
	ds_read_b128 v[16:19], v136 offset:32768
	ds_read_b128 v[20:23], v136 offset:33792
	ds_read_b128 v[104:107], v136 offset:34816
	ds_read_b128 v[220:223], v136 offset:35840
	ds_read_b128 v[224:227], v136 offset:36864
	ds_read_b128 v[228:231], v136 offset:37888
	ds_read_b128 v[232:235], v136 offset:38912
	ds_read_b128 v[236:239], v136 offset:39936
	global_load_lds_dwordx4 v[32:33], off
	v_lshl_add_u64 v[32:33], s[34:35], 0, v[128:129]
	s_mov_b32 m0, s47
	s_nop 0
	global_load_lds_dwordx4 v[32:33], off
	s_waitcnt vmcnt(8)
	s_waitcnt lgkmcnt(0)
	s_barrier
	s_setprio 1
	s_waitcnt lgkmcnt(0)
	v_mfma_f32_16x16x32_bf16 v[32:35], v[4:7], v[16:19], v[64:67]
	v_mfma_f32_16x16x32_bf16 v[116:119], v[60:63], v[20:23], v[32:35]
	v_mfma_f32_16x16x32_bf16 v[32:35], v[168:171], v[16:19], v[68:71]
	v_mfma_f32_16x16x32_bf16 v[112:115], v[192:195], v[20:23], v[32:35]
	v_mfma_f32_16x16x32_bf16 v[32:35], v[4:7], v[104:107], v[72:75]
	v_mfma_f32_16x16x32_bf16 v[100:103], v[60:63], v[220:223], v[32:35]
	v_mfma_f32_16x16x32_bf16 v[32:35], v[168:171], v[104:107], v[76:79]
	v_mfma_f32_16x16x32_bf16 v[96:99], v[192:195], v[220:223], v[32:35]
	v_mfma_f32_16x16x32_bf16 v[32:35], v[4:7], v[224:227], v[80:83]
	v_mfma_f32_16x16x32_bf16 v[68:71], v[60:63], v[228:231], v[32:35]
	v_mfma_f32_16x16x32_bf16 v[32:35], v[168:171], v[224:227], v[84:87]
	v_mfma_f32_16x16x32_bf16 v[64:67], v[192:195], v[228:231], v[32:35]
	v_mfma_f32_16x16x32_bf16 v[32:35], v[4:7], v[232:235], v[88:91]
	v_mfma_f32_16x16x32_bf16 v[36:39], v[60:63], v[236:239], v[32:35]
	v_mfma_f32_16x16x32_bf16 v[32:35], v[168:171], v[232:235], v[92:95]
	v_mfma_f32_16x16x32_bf16 v[32:35], v[192:195], v[236:239], v[32:35]
	s_setprio 0
	s_setprio 1
	v_mfma_f32_16x16x32_bf16 v[72:75], v[196:199], v[16:19], v[204:207]
	v_mfma_f32_16x16x32_bf16 v[16:19], v[212:215], v[16:19], v[172:175]
	v_mfma_f32_16x16x32_bf16 v[120:123], v[216:219], v[20:23], v[16:19]
	v_mfma_f32_16x16x32_bf16 v[16:19], v[196:199], v[104:107], v[176:179]
	v_mfma_f32_16x16x32_bf16 v[108:111], v[208:211], v[220:223], v[16:19]
	v_mfma_f32_16x16x32_bf16 v[16:19], v[212:215], v[104:107], v[40:43]
	v_mfma_f32_16x16x32_bf16 v[104:107], v[216:219], v[220:223], v[16:19]
	v_mfma_f32_16x16x32_bf16 v[16:19], v[196:199], v[224:227], v[44:47]
	v_mfma_f32_16x16x32_bf16 v[80:83], v[208:211], v[228:231], v[16:19]
	v_mfma_f32_16x16x32_bf16 v[16:19], v[212:215], v[224:227], v[48:51]
	v_mfma_f32_16x16x32_bf16 v[124:127], v[208:211], v[20:23], v[72:75]
	v_mfma_f32_16x16x32_bf16 v[72:75], v[216:219], v[228:231], v[16:19]
	s_barrier
	v_mfma_f32_16x16x32_bf16 v[16:19], v[196:199], v[232:235], v[52:55]
	v_mfma_f32_16x16x32_bf16 v[48:51], v[208:211], v[236:239], v[16:19]
	v_mfma_f32_16x16x32_bf16 v[16:19], v[212:215], v[232:235], v[56:59]
	v_mfma_f32_16x16x32_bf16 v[40:43], v[216:219], v[236:239], v[16:19]
	s_setprio 0
	s_mov_b32 m0, s51
	s_nop 3
	v_lshl_add_u64 v[16:17], v[240:241], 0, s[20:21]
	s_add_u32 s30, s30, 0x10080
	ds_read_b128 v[56:59], v136 offset:49152
	ds_read_b128 v[88:91], v136 offset:50176
	ds_read_b128 v[172:175], v136 offset:51200
	ds_read_b128 v[176:179], v136 offset:52224
	ds_read_b128 v[204:207], v136 offset:53248
	ds_read_b128 v[220:223], v136 offset:54272
	ds_read_b128 v[224:227], v136 offset:55296
	ds_read_b128 v[228:231], v136 offset:56320
	global_load_lds_dwordx4 v[16:17], off
	v_lshl_add_u64 v[16:17], v[242:243], 0, s[20:21]
	s_mov_b32 m0, s52
	s_addc_u32 s31, s31, 0
	global_load_lds_dwordx4 v[16:17], off
	v_lshl_add_u64 v[16:17], s[30:31], 0, v[130:131]
	s_mov_b32 m0, s53
	s_nop 0
	global_load_lds_dwordx4 v[16:17], off
	v_lshl_add_u64 v[16:17], s[30:31], 0, v[128:129]
	s_mov_b32 m0, s54
	s_nop 0
	global_load_lds_dwordx4 v[16:17], off
	v_lshl_add_u64 v[16:17], v[244:245], 0, s[20:21]
	s_mov_b32 m0, s75
	s_nop 0
	global_load_lds_dwordx4 v[16:17], off
	v_lshl_add_u64 v[16:17], v[246:247], 0, s[20:21]
	s_mov_b32 m0, s67
	s_nop 0
	global_load_lds_dwordx4 v[16:17], off
	s_waitcnt vmcnt(8)
	s_waitcnt lgkmcnt(0)
	s_barrier
	s_setprio 1
	s_waitcnt lgkmcnt(0)
	v_mfma_f32_16x16x32_bf16 v[16:19], v[4:7], v[56:59], v[140:143]
	v_mfma_f32_16x16x32_bf16 v[84:87], v[60:63], v[88:91], v[16:19]
	v_mfma_f32_16x16x32_bf16 v[16:19], v[168:171], v[56:59], v[144:147]
	v_mfma_f32_16x16x32_bf16 v[76:79], v[192:195], v[88:91], v[16:19]
	v_mfma_f32_16x16x32_bf16 v[16:19], v[4:7], v[172:175], v[148:151]
	v_mfma_f32_16x16x32_bf16 v[52:55], v[60:63], v[176:179], v[16:19]
	v_mfma_f32_16x16x32_bf16 v[16:19], v[168:171], v[172:175], v[152:155]
	v_mfma_f32_16x16x32_bf16 v[44:47], v[192:195], v[176:179], v[16:19]
	v_mfma_f32_16x16x32_bf16 v[16:19], v[4:7], v[204:207], v[156:159]
	v_mfma_f32_16x16x32_bf16 v[0:3], v[4:7], v[224:227], v[0:3]
	v_mfma_f32_16x16x32_bf16 v[20:23], v[60:63], v[220:223], v[16:19]
	v_mfma_f32_16x16x32_bf16 v[16:19], v[168:171], v[204:207], v[160:163]
	v_mfma_f32_16x16x32_bf16 v[4:7], v[60:63], v[228:231], v[0:3]
	v_mfma_f32_16x16x32_bf16 v[0:3], v[168:171], v[224:227], v[200:203]
	v_mfma_f32_16x16x32_bf16 v[16:19], v[192:195], v[220:223], v[16:19]
	v_mfma_f32_16x16x32_bf16 v[0:3], v[192:195], v[228:231], v[0:3]
	s_setprio 0
	s_setprio 1
	v_mfma_f32_16x16x32_bf16 v[8:11], v[196:199], v[56:59], v[8:11]
	v_mfma_f32_16x16x32_bf16 v[92:95], v[208:211], v[88:91], v[8:11]
	v_mfma_f32_16x16x32_bf16 v[8:11], v[212:215], v[56:59], v[12:15]
	v_mfma_f32_16x16x32_bf16 v[88:91], v[216:219], v[88:91], v[8:11]
	v_mfma_f32_16x16x32_bf16 v[8:11], v[196:199], v[172:175], v[24:27]
	v_mfma_f32_16x16x32_bf16 v[60:63], v[208:211], v[176:179], v[8:11]
	v_mfma_f32_16x16x32_bf16 v[8:11], v[212:215], v[172:175], v[28:31]
	v_mfma_f32_16x16x32_bf16 v[56:59], v[216:219], v[176:179], v[8:11]
	v_mfma_f32_16x16x32_bf16 v[8:11], v[196:199], v[204:207], v[180:183]
	v_mfma_f32_16x16x32_bf16 v[28:31], v[208:211], v[220:223], v[8:11]
	v_mfma_f32_16x16x32_bf16 v[8:11], v[212:215], v[204:207], v[184:187]
	v_mfma_f32_16x16x32_bf16 v[24:27], v[216:219], v[220:223], v[8:11]
	s_barrier
	v_mfma_f32_16x16x32_bf16 v[8:11], v[196:199], v[224:227], v[188:191]
	v_mfma_f32_16x16x32_bf16 v[12:15], v[208:211], v[228:231], v[8:11]
	v_mfma_f32_16x16x32_bf16 v[8:11], v[212:215], v[224:227], v[164:167]
	v_mfma_f32_16x16x32_bf16 v[8:11], v[216:219], v[228:231], v[8:11]
	s_setprio 0
	s_and_b64 vcc, exec, s[8:9]
	s_cbranch_vccnz .LBB0_2603
	s_barrier

; #define PG8_STAGE(bufoff, gbase, voff) do { _Pragma("unroll") for (int _i = 0; _i < 2; ++_i) \
;         __builtin_amdgcn_global_load_lds((const unsigned*)((const char*)(gbase) + (voff)[_i]), (PG8_LAS unsigned*)(lds + (bufoff) + ldsw + _i * 8192), 16, 0, 0); } while (0)
; #define PG8_LDA(dst, b, h) do { _Pragma("unroll") for (int m = 0; m < 4; ++m) _Pragma("unroll") for (int k = 0; k < 2; ++k) dst[m][k] = *(const PG8_LAS bf16x8*)(lds + PG8_SA(b, h) + aoff + m * 2048 + k * 1024); } while (0)
; #define PG8_LDB(dst, b, h) do { _Pragma("unroll") for (int n = 0; n < 2; ++n) _Pragma("unroll") for (int k = 0; k < 2; ++k) dst[n][k] = *(const PG8_LAS bf16x8*)(lds + PG8_SB(b, h) + boff + n * 2048 + k * 1024); } while (0)
; #define PG8_MMA(ai, bj, At, Bt) do { __builtin_amdgcn_s_setprio(1); _Pragma("unroll") for (int m = 0; m < 4; ++m) _Pragma("unroll") for (int n = 0; n < 2; ++n) _Pragma("unroll") for (int k = 0; k < 2; ++k) \
;         acc[ai][bj][m][n] = mma16<F16>(Bt[n][k], At[m][k], acc[ai][bj][m][n]); __builtin_amdgcn_s_setprio(0); } while (0)
; #define PG8_WAIT_V(n) asm volatile("s_waitcnt vmcnt(" #n ")" ::: "memory")
; #define PG8_WAIT_L(n) asm volatile("s_waitcnt lgkmcnt(" #n ")" ::: "memory")
; #define PG8_BAR __builtin_amdgcn_s_barrier()
; #define PG8_SCHED __builtin_amdgcn_sched_barrier(0)
; template <class Epi, class Sched, bool ALIGN_EPI = false, bool SP2 = false, bool F16 = false>
; __device__ __forceinline__ void gemm_phase(PG8_LAS unsigned char* lds, const Gemm g, const Sched& S, const Epi& E, const int wid_in) {
;     ...
;             PG8_LDB(B0, 0, 0); PG8_LDB(B1, 0, 1); PG8_SCHED; PG8_LDA(At, 0, 0); PG8_STAGE(PG8_SA(1, 1), a1 + hstep, voffA);
;             PG8_WAIT_V(8); PG8_WAIT_L(0); PG8_BAR; PG8_MMA(0, 0, At, B0); PG8_MMA(0, 1, At, B1); PG8_BAR; PG8_SCHED;
;             PG8_LDA(At, 0, 1); PG8_STAGE(PG8_SB(0, 0), b2, voffB); PG8_STAGE(PG8_SB(0, 1), b2 + hstep, voffB); PG8_STAGE(PG8_SA(0, 0), a2, voffA);
;             PG8_WAIT_V(8); PG8_WAIT_L(0); PG8_BAR; PG8_MMA(1, 0, At, B0); PG8_MMA(1, 1, At, B1); PG8_BAR; PG8_SCHED;
.LBB0_2697:
	ds_read_b128 v[128:131], v189
	ds_read_b128 v[132:135], v189 offset:1024
	ds_read_b128 v[136:139], v189 offset:2048
	ds_read_b128 v[140:143], v189 offset:3072
	ds_read_b128 v[144:147], v190
	ds_read_b128 v[148:151], v190 offset:1024
	ds_read_b128 v[168:171], v190 offset:2048
	ds_read_b128 v[172:175], v190 offset:3072
	s_add_u32 s30, s28, 0x100
	s_addc_u32 s31, s29, 0
	s_cmp_eq_u32 s55, 40
	s_cselect_b32 s37, s11, s31
	s_cselect_b32 s36, s10, s30
	s_cselect_b32 s35, s27, s54
	s_cselect_b32 s34, s26, s53
	s_mov_b32 m0, s91
	v_lshl_add_u64 v[184:185], s[28:29], 0, v[160:161]
	ds_read_b128 v[176:179], v191
	ds_read_b128 v[180:183], v191 offset:1024
	ds_read_b128 v[192:195], v191 offset:2048
	ds_read_b128 v[196:199], v191 offset:3072
	ds_read_b128 v[200:203], v191 offset:4096
	ds_read_b128 v[204:207], v191 offset:5120
	ds_read_b128 v[208:211], v191 offset:6144
	ds_read_b128 v[212:215], v191 offset:7168
	global_load_lds_dwordx4 v[184:185], off
	v_lshl_add_u64 v[184:185], s[28:29], 0, v[162:163]
	s_add_i32 m0, s74, 0xe000
	s_nop 0
	global_load_lds_dwordx4 v[184:185], off
	s_waitcnt vmcnt(8)
	s_waitcnt lgkmcnt(0)
	s_barrier
	s_setprio 1
	s_waitcnt lgkmcnt(0)
	v_mfma_f32_16x16x32_bf16 v[124:127], v[128:131], v[176:179], v[124:127]
	v_mfma_f32_16x16x32_bf16 v[120:123], v[136:139], v[176:179], v[120:123]
	v_mfma_f32_16x16x32_bf16 v[108:111], v[128:131], v[192:195], v[108:111]
	v_mfma_f32_16x16x32_bf16 v[104:107], v[136:139], v[192:195], v[104:107]
	v_mfma_f32_16x16x32_bf16 v[92:95], v[128:131], v[200:203], v[92:95]
	v_mfma_f32_16x16x32_bf16 v[88:91], v[136:139], v[200:203], v[88:91]
	v_mfma_f32_16x16x32_bf16 v[76:79], v[128:131], v[208:211], v[76:79]
	v_mfma_f32_16x16x32_bf16 v[72:75], v[136:139], v[208:211], v[72:75]
	v_mfma_f32_16x16x32_bf16 v[124:127], v[132:135], v[180:183], v[124:127]
	v_mfma_f32_16x16x32_bf16 v[120:123], v[140:143], v[180:183], v[120:123]
	v_mfma_f32_16x16x32_bf16 v[108:111], v[132:135], v[196:199], v[108:111]
	v_mfma_f32_16x16x32_bf16 v[104:107], v[140:143], v[196:199], v[104:107]
	v_mfma_f32_16x16x32_bf16 v[92:95], v[132:135], v[204:207], v[92:95]
	v_mfma_f32_16x16x32_bf16 v[88:91], v[140:143], v[204:207], v[88:91]
	v_mfma_f32_16x16x32_bf16 v[76:79], v[132:135], v[212:215], v[76:79]
	v_mfma_f32_16x16x32_bf16 v[72:75], v[140:143], v[212:215], v[72:75]
	s_setprio 0
	s_setprio 1
	v_mfma_f32_16x16x32_bf16 v[116:119], v[144:147], v[176:179], v[116:119]
	v_mfma_f32_16x16x32_bf16 v[112:115], v[168:171], v[176:179], v[112:115]
	v_mfma_f32_16x16x32_bf16 v[100:103], v[144:147], v[192:195], v[100:103]
	v_mfma_f32_16x16x32_bf16 v[96:99], v[168:171], v[192:195], v[96:99]
	v_mfma_f32_16x16x32_bf16 v[84:87], v[144:147], v[200:203], v[84:87]
	v_mfma_f32_16x16x32_bf16 v[80:83], v[168:171], v[200:203], v[80:83]
	v_mfma_f32_16x16x32_bf16 v[68:71], v[144:147], v[208:211], v[68:71]
	v_mfma_f32_16x16x32_bf16 v[64:67], v[168:171], v[208:211], v[64:67]
	v_mfma_f32_16x16x32_bf16 v[116:119], v[148:151], v[180:183], v[116:119]
	v_mfma_f32_16x16x32_bf16 v[112:115], v[172:175], v[180:183], v[112:115]
	v_mfma_f32_16x16x32_bf16 v[100:103], v[148:151], v[196:199], v[100:103]
	v_mfma_f32_16x16x32_bf16 v[96:99], v[172:175], v[196:199], v[96:99]
	s_barrier
	v_mfma_f32_16x16x32_bf16 v[84:87], v[148:151], v[204:207], v[84:87]
	v_mfma_f32_16x16x32_bf16 v[80:83], v[172:175], v[204:207], v[80:83]
	v_mfma_f32_16x16x32_bf16 v[68:71], v[148:151], v[212:215], v[68:71]
	v_mfma_f32_16x16x32_bf16 v[64:67], v[172:175], v[212:215], v[64:67]
	s_setprio 0
	s_add_i32 s28, s47, s68
	v_lshl_add_u64 v[184:185], s[34:35], 0, v[154:155]
	s_mov_b32 m0, s28
	ds_read_b128 v[176:179], v191 offset:16384
	ds_read_b128 v[180:183], v191 offset:17408
	ds_read_b128 v[192:195], v191 offset:18432
	ds_read_b128 v[196:199], v191 offset:19456
	ds_read_b128 v[200:203], v191 offset:20480
	ds_read_b128 v[204:207], v191 offset:21504
	ds_read_b128 v[208:211], v191 offset:22528
	ds_read_b128 v[212:215], v191 offset:23552
	global_load_lds_dwordx4 v[184:185], off
	s_add_i32 m0, s28, 0x2000
	s_add_u32 s28, s34, 0xb0000
	v_lshl_add_u64 v[216:217], s[34:35], 0, v[158:159]
	s_addc_u32 s29, s35, 0
	s_add_i32 s56, s48, s68
	global_load_lds_dwordx4 v[216:217], off
	v_lshl_add_u64 v[218:219], s[28:29], 0, v[154:155]
	s_mov_b32 m0, s56
	v_lshl_add_u64 v[220:221], s[36:37], 0, v[156:157]
	global_load_lds_dwordx4 v[218:219], off
	v_lshl_add_u64 v[218:219], s[28:29], 0, v[158:159]
	s_add_i32 m0, s56, 0x2000
	s_nop 0
	global_load_lds_dwordx4 v[218:219], off
	v_lshl_add_u64 v[218:219], s[36:37], 0, v[152:153]
	s_mov_b32 m0, s74
	s_nop 0
	global_load_lds_dwordx4 v[218:219], off
	s_mov_b32 m0, s66
	s_nop 0
	global_load_lds_dwordx4 v[220:221], off
	s_waitcnt vmcnt(8)
	s_waitcnt lgkmcnt(0)
	s_barrier
; #define PG8_STAGE(bufoff, gbase, voff) do { _Pragma("unroll") for (int _i = 0; _i < 2; ++_i) \
;         __builtin_amdgcn_global_load_lds((const unsigned*)((const char*)(gbase) + (voff)[_i]), (PG8_LAS unsigned*)(lds + (bufoff) + ldsw + _i * 8192), 16, 0, 0); } while (0)
; #define PG8_LDA(dst, b, h) do { _Pragma("unroll") for (int m = 0; m < 4; ++m) _Pragma("unroll") for (int k = 0; k < 2; ++k) dst[m][k] = *(const PG8_LAS bf16x8*)(lds + PG8_SA(b, h) + aoff + m * 2048 + k * 1024); } while (0)
; #define PG8_LDB(dst, b, h) do { _Pragma("unroll") for (int n = 0; n < 2; ++n) _Pragma("unroll") for (int k = 0; k < 2; ++k) dst[n][k] = *(const PG8_LAS bf16x8*)(lds + PG8_SB(b, h) + boff + n * 2048 + k * 1024); } while (0)
; #define PG8_MMA(ai, bj, At, Bt) do { __builtin_amdgcn_s_setprio(1); _Pragma("unroll") for (int m = 0; m < 4; ++m) _Pragma("unroll") for (int n = 0; n < 2; ++n) _Pragma("unroll") for (int k = 0; k < 2; ++k) \
;         acc[ai][bj][m][n] = mma16<F16>(Bt[n][k], At[m][k], acc[ai][bj][m][n]); __builtin_amdgcn_s_setprio(0); } while (0)
; #define PG8_WAIT_V(n) asm volatile("s_waitcnt vmcnt(" #n ")" ::: "memory")
; #define PG8_WAIT_L(n) asm volatile("s_waitcnt lgkmcnt(" #n ")" ::: "memory")
; #define PG8_BAR __builtin_amdgcn_s_barrier()
; #define PG8_SCHED __builtin_amdgcn_sched_barrier(0)
; template <class Epi, class Sched, bool ALIGN_EPI = false, bool SP2 = false, bool F16 = false>
; __device__ __forceinline__ void gemm_phase(PG8_LAS unsigned char* lds, const Gemm g, const Sched& S, const Epi& E, const int wid_in) {
;     ...
;             PG8_WAIT_V(8); PG8_WAIT_L(0); PG8_BAR; PG8_MMA(1, 0, At, B0); PG8_MMA(1, 1, At, B1); PG8_BAR; PG8_SCHED;
;             PG8_LDB(B0, 1, 0); PG8_LDB(B1, 1, 1); PG8_SCHED; PG8_LDA(At, 1, 0); PG8_STAGE(PG8_SA(0, 1), a2 + hstep, voffA);
;             PG8_WAIT_V(8); PG8_WAIT_L(0); PG8_BAR; PG8_MMA(0, 0, At, B0); PG8_MMA(0, 1, At, B1); PG8_BAR; PG8_SCHED;
	s_setprio 1
	s_waitcnt lgkmcnt(0)
	v_mfma_f32_16x16x32_bf16 v[60:63], v[128:131], v[176:179], v[60:63]
	v_mfma_f32_16x16x32_bf16 v[56:59], v[136:139], v[176:179], v[56:59]
	v_mfma_f32_16x16x32_bf16 v[44:47], v[128:131], v[192:195], v[44:47]
	v_mfma_f32_16x16x32_bf16 v[40:43], v[136:139], v[192:195], v[40:43]
	v_mfma_f32_16x16x32_bf16 v[28:31], v[128:131], v[200:203], v[28:31]
	v_mfma_f32_16x16x32_bf16 v[24:27], v[136:139], v[200:203], v[24:27]
	v_mfma_f32_16x16x32_bf16 v[12:15], v[128:131], v[208:211], v[12:15]
	v_mfma_f32_16x16x32_bf16 v[8:11], v[136:139], v[208:211], v[8:11]
	v_mfma_f32_16x16x32_bf16 v[60:63], v[132:135], v[180:183], v[60:63]
	v_mfma_f32_16x16x32_bf16 v[56:59], v[140:143], v[180:183], v[56:59]
	v_mfma_f32_16x16x32_bf16 v[44:47], v[132:135], v[196:199], v[44:47]
	v_mfma_f32_16x16x32_bf16 v[40:43], v[140:143], v[196:199], v[40:43]
	v_mfma_f32_16x16x32_bf16 v[28:31], v[132:135], v[204:207], v[28:31]
	v_mfma_f32_16x16x32_bf16 v[24:27], v[140:143], v[204:207], v[24:27]
	v_mfma_f32_16x16x32_bf16 v[12:15], v[132:135], v[212:215], v[12:15]
	v_mfma_f32_16x16x32_bf16 v[8:11], v[140:143], v[212:215], v[8:11]
	s_setprio 0
	s_setprio 1
	v_mfma_f32_16x16x32_bf16 v[52:55], v[144:147], v[176:179], v[52:55]
	v_mfma_f32_16x16x32_bf16 v[48:51], v[168:171], v[176:179], v[48:51]
	v_mfma_f32_16x16x32_bf16 v[36:39], v[144:147], v[192:195], v[36:39]
	v_mfma_f32_16x16x32_bf16 v[32:35], v[168:171], v[192:195], v[32:35]
	v_mfma_f32_16x16x32_bf16 v[20:23], v[144:147], v[200:203], v[20:23]
	v_mfma_f32_16x16x32_bf16 v[16:19], v[168:171], v[200:203], v[16:19]
	v_mfma_f32_16x16x32_bf16 v[4:7], v[144:147], v[208:211], v[4:7]
	v_mfma_f32_16x16x32_bf16 v[0:3], v[168:171], v[208:211], v[0:3]
	v_mfma_f32_16x16x32_bf16 v[52:55], v[148:151], v[180:183], v[52:55]
	v_mfma_f32_16x16x32_bf16 v[48:51], v[172:175], v[180:183], v[48:51]
	v_mfma_f32_16x16x32_bf16 v[36:39], v[148:151], v[196:199], v[36:39]
	v_mfma_f32_16x16x32_bf16 v[32:35], v[172:175], v[196:199], v[32:35]
	s_barrier
	v_mfma_f32_16x16x32_bf16 v[20:23], v[148:151], v[204:207], v[20:23]
	v_mfma_f32_16x16x32_bf16 v[16:19], v[172:175], v[204:207], v[16:19]
	v_mfma_f32_16x16x32_bf16 v[4:7], v[148:151], v[212:215], v[4:7]
	v_mfma_f32_16x16x32_bf16 v[0:3], v[172:175], v[212:215], v[0:3]
	s_setprio 0
	s_add_i32 s56, 0, 0x18000
	s_add_i32 s57, 0, 0x1c000
	v_add_u32_e32 v140, s56, v188
	v_add_u32_e32 v172, s57, v188
	ds_read_b128 v[128:131], v140
	ds_read_b128 v[132:135], v140 offset:1024
	ds_read_b128 v[136:139], v140 offset:2048
	ds_read_b128 v[140:143], v140 offset:3072
	ds_read_b128 v[144:147], v172
	ds_read_b128 v[148:151], v172 offset:1024
	ds_read_b128 v[168:171], v172 offset:2048
	ds_read_b128 v[172:175], v172 offset:3072
	s_add_u32 s28, s36, 0xb0000
	s_addc_u32 s29, s37, 0
	s_mov_b32 m0, s90
	v_lshl_add_u64 v[222:223], s[28:29], 0, v[152:153]
	ds_read_b128 v[176:179], v191 offset:32768
	ds_read_b128 v[180:183], v191 offset:33792
	ds_read_b128 v[192:195], v191 offset:34816
	ds_read_b128 v[196:199], v191 offset:35840
	ds_read_b128 v[200:203], v191 offset:36864
	ds_read_b128 v[204:207], v191 offset:37888
	ds_read_b128 v[208:211], v191 offset:38912
	ds_read_b128 v[212:215], v191 offset:39936
	global_load_lds_dwordx4 v[222:223], off
	v_lshl_add_u64 v[222:223], s[28:29], 0, v[156:157]
	s_mov_b32 m0, s43
	s_nop 0
	global_load_lds_dwordx4 v[222:223], off
	s_waitcnt vmcnt(8)
	s_waitcnt lgkmcnt(0)
	s_barrier
	s_setprio 1
	s_waitcnt lgkmcnt(0)
	v_mfma_f32_16x16x32_bf16 v[124:127], v[128:131], v[176:179], v[124:127]
	v_mfma_f32_16x16x32_bf16 v[120:123], v[136:139], v[176:179], v[120:123]
	v_mfma_f32_16x16x32_bf16 v[108:111], v[128:131], v[192:195], v[108:111]
	v_mfma_f32_16x16x32_bf16 v[104:107], v[136:139], v[192:195], v[104:107]
	v_mfma_f32_16x16x32_bf16 v[92:95], v[128:131], v[200:203], v[92:95]
	v_mfma_f32_16x16x32_bf16 v[88:91], v[136:139], v[200:203], v[88:91]
	v_mfma_f32_16x16x32_bf16 v[76:79], v[128:131], v[208:211], v[76:79]
	v_mfma_f32_16x16x32_bf16 v[72:75], v[136:139], v[208:211], v[72:75]
	v_mfma_f32_16x16x32_bf16 v[124:127], v[132:135], v[180:183], v[124:127]
	v_mfma_f32_16x16x32_bf16 v[120:123], v[140:143], v[180:183], v[120:123]
	v_mfma_f32_16x16x32_bf16 v[108:111], v[132:135], v[196:199], v[108:111]
	v_mfma_f32_16x16x32_bf16 v[104:107], v[140:143], v[196:199], v[104:107]
	v_mfma_f32_16x16x32_bf16 v[92:95], v[132:135], v[204:207], v[92:95]
	v_mfma_f32_16x16x32_bf16 v[88:91], v[140:143], v[204:207], v[88:91]
	v_mfma_f32_16x16x32_bf16 v[76:79], v[132:135], v[212:215], v[76:79]
	v_mfma_f32_16x16x32_bf16 v[72:75], v[140:143], v[212:215], v[72:75]
	s_setprio 0
	s_setprio 1
	v_mfma_f32_16x16x32_bf16 v[116:119], v[144:147], v[176:179], v[116:119]
	v_mfma_f32_16x16x32_bf16 v[112:115], v[168:171], v[176:179], v[112:115]
	v_mfma_f32_16x16x32_bf16 v[100:103], v[144:147], v[192:195], v[100:103]
	v_mfma_f32_16x16x32_bf16 v[96:99], v[168:171], v[192:195], v[96:99]
	v_mfma_f32_16x16x32_bf16 v[84:87], v[144:147], v[200:203], v[84:87]
	v_mfma_f32_16x16x32_bf16 v[80:83], v[168:171], v[200:203], v[80:83]
	v_mfma_f32_16x16x32_bf16 v[68:71], v[144:147], v[208:211], v[68:71]
	v_mfma_f32_16x16x32_bf16 v[64:67], v[168:171], v[208:211], v[64:67]
	v_mfma_f32_16x16x32_bf16 v[116:119], v[148:151], v[180:183], v[116:119]
	v_mfma_f32_16x16x32_bf16 v[112:115], v[172:175], v[180:183], v[112:115]
	v_mfma_f32_16x16x32_bf16 v[100:103], v[148:151], v[196:199], v[100:103]
	v_mfma_f32_16x16x32_bf16 v[96:99], v[172:175], v[196:199], v[96:99]
	s_barrier
; #define PG8_STAGE(bufoff, gbase, voff) do { _Pragma("unroll") for (int _i = 0; _i < 2; ++_i) \
;         __builtin_amdgcn_global_load_lds((const unsigned*)((const char*)(gbase) + (voff)[_i]), (PG8_LAS unsigned*)(lds + (bufoff) + ldsw + _i * 8192), 16, 0, 0); } while (0)
; #define PG8_LDA(dst, b, h) do { _Pragma("unroll") for (int m = 0; m < 4; ++m) _Pragma("unroll") for (int k = 0; k < 2; ++k) dst[m][k] = *(const PG8_LAS bf16x8*)(lds + PG8_SA(b, h) + aoff + m * 2048 + k * 1024); } while (0)
; #define PG8_MMA(ai, bj, At, Bt) do { __builtin_amdgcn_s_setprio(1); _Pragma("unroll") for (int m = 0; m < 4; ++m) _Pragma("unroll") for (int n = 0; n < 2; ++n) _Pragma("unroll") for (int k = 0; k < 2; ++k) \
;         acc[ai][bj][m][n] = mma16<F16>(Bt[n][k], At[m][k], acc[ai][bj][m][n]); __builtin_amdgcn_s_setprio(0); } while (0)
; #define PG8_WAIT_V(n) asm volatile("s_waitcnt vmcnt(" #n ")" ::: "memory")
; #define PG8_WAIT_L(n) asm volatile("s_waitcnt lgkmcnt(" #n ")" ::: "memory")
; #define PG8_BAR __builtin_amdgcn_s_barrier()
; #define PG8_SCHED __builtin_amdgcn_sched_barrier(0)
; template <class Epi, class Sched, bool ALIGN_EPI = false, bool SP2 = false, bool F16 = false>
; __device__ __forceinline__ void gemm_phase(PG8_LAS unsigned char* lds, const Gemm g, const Sched& S, const Epi& E, const int wid_in) {
;     ...
;             PG8_WAIT_V(8); PG8_WAIT_L(0); PG8_BAR; PG8_MMA(0, 0, At, B0); PG8_MMA(0, 1, At, B1); PG8_BAR; PG8_SCHED;
;             PG8_LDA(At, 1, 1); PG8_STAGE(PG8_SB(1, 0), b3, voffB); PG8_STAGE(PG8_SB(1, 1), b3 + hstep, voffB); PG8_STAGE(PG8_SA(1, 0), a3, voffA);
;             PG8_WAIT_V(8); PG8_WAIT_L(0); PG8_BAR; PG8_MMA(1, 0, At, B0); PG8_MMA(1, 1, At, B1); PG8_BAR; PG8_SCHED;
	v_mfma_f32_16x16x32_bf16 v[84:87], v[148:151], v[204:207], v[84:87]
	v_mfma_f32_16x16x32_bf16 v[80:83], v[172:175], v[204:207], v[80:83]
	v_mfma_f32_16x16x32_bf16 v[68:71], v[148:151], v[212:215], v[68:71]
	v_mfma_f32_16x16x32_bf16 v[64:67], v[172:175], v[212:215], v[64:67]
	s_setprio 0
	s_add_i32 s28, s56, s68
	v_lshl_add_u64 v[184:185], v[184:185], 0, s[24:25]
	s_mov_b32 m0, s28
	ds_read_b128 v[176:179], v191 offset:49152
	ds_read_b128 v[180:183], v191 offset:50176
	ds_read_b128 v[192:195], v191 offset:51200
	ds_read_b128 v[196:199], v191 offset:52224
	ds_read_b128 v[200:203], v191 offset:53248
	ds_read_b128 v[204:207], v191 offset:54272
	ds_read_b128 v[208:211], v191 offset:55296
	ds_read_b128 v[212:215], v191 offset:56320
	global_load_lds_dwordx4 v[184:185], off
	s_add_i32 m0, s28, 0x2000
	s_add_u32 s28, s34, 0xb0080
	v_lshl_add_u64 v[184:185], v[216:217], 0, s[24:25]
	s_addc_u32 s29, s35, 0
	s_add_i32 s34, s57, s68
	global_load_lds_dwordx4 v[184:185], off
	v_lshl_add_u64 v[184:185], s[28:29], 0, v[154:155]
	s_mov_b32 m0, s34
	s_nop 0
	global_load_lds_dwordx4 v[184:185], off
	v_lshl_add_u64 v[184:185], s[28:29], 0, v[158:159]
	s_add_i32 m0, s34, 0x2000
	s_nop 0
	global_load_lds_dwordx4 v[184:185], off
	v_lshl_add_u64 v[184:185], v[218:219], 0, s[24:25]
	s_mov_b32 m0, s75
	s_nop 0
	global_load_lds_dwordx4 v[184:185], off
	v_lshl_add_u64 v[184:185], v[220:221], 0, s[24:25]
	s_mov_b32 m0, s67
	s_nop 0
	global_load_lds_dwordx4 v[184:185], off
	s_waitcnt vmcnt(8)
	s_waitcnt lgkmcnt(0)
	s_barrier
	s_setprio 1
	s_waitcnt lgkmcnt(0)
	v_mfma_f32_16x16x32_bf16 v[60:63], v[128:131], v[176:179], v[60:63]
	v_mfma_f32_16x16x32_bf16 v[56:59], v[136:139], v[176:179], v[56:59]
	v_mfma_f32_16x16x32_bf16 v[44:47], v[128:131], v[192:195], v[44:47]
	v_mfma_f32_16x16x32_bf16 v[40:43], v[136:139], v[192:195], v[40:43]
	v_mfma_f32_16x16x32_bf16 v[28:31], v[128:131], v[200:203], v[28:31]
	v_mfma_f32_16x16x32_bf16 v[24:27], v[136:139], v[200:203], v[24:27]
	v_mfma_f32_16x16x32_bf16 v[12:15], v[128:131], v[208:211], v[12:15]
	v_mfma_f32_16x16x32_bf16 v[8:11], v[136:139], v[208:211], v[8:11]
	v_mfma_f32_16x16x32_bf16 v[60:63], v[132:135], v[180:183], v[60:63]
	v_mfma_f32_16x16x32_bf16 v[56:59], v[140:143], v[180:183], v[56:59]
	v_mfma_f32_16x16x32_bf16 v[44:47], v[132:135], v[196:199], v[44:47]
	v_mfma_f32_16x16x32_bf16 v[40:43], v[140:143], v[196:199], v[40:43]
	v_mfma_f32_16x16x32_bf16 v[28:31], v[132:135], v[204:207], v[28:31]
	v_mfma_f32_16x16x32_bf16 v[24:27], v[140:143], v[204:207], v[24:27]
	v_mfma_f32_16x16x32_bf16 v[12:15], v[132:135], v[212:215], v[12:15]
	v_mfma_f32_16x16x32_bf16 v[8:11], v[140:143], v[212:215], v[8:11]
	s_setprio 0
	s_setprio 1
	v_mfma_f32_16x16x32_bf16 v[52:55], v[144:147], v[176:179], v[52:55]
	v_mfma_f32_16x16x32_bf16 v[48:51], v[168:171], v[176:179], v[48:51]
	v_mfma_f32_16x16x32_bf16 v[36:39], v[144:147], v[192:195], v[36:39]
	v_mfma_f32_16x16x32_bf16 v[32:35], v[168:171], v[192:195], v[32:35]
	v_mfma_f32_16x16x32_bf16 v[20:23], v[144:147], v[200:203], v[20:23]
	v_mfma_f32_16x16x32_bf16 v[16:19], v[168:171], v[200:203], v[16:19]
	v_mfma_f32_16x16x32_bf16 v[4:7], v[144:147], v[208:211], v[4:7]
	v_mfma_f32_16x16x32_bf16 v[0:3], v[168:171], v[208:211], v[0:3]
	v_mfma_f32_16x16x32_bf16 v[52:55], v[148:151], v[180:183], v[52:55]
	v_mfma_f32_16x16x32_bf16 v[48:51], v[172:175], v[180:183], v[48:51]
	v_mfma_f32_16x16x32_bf16 v[36:39], v[148:151], v[196:199], v[36:39]
	v_mfma_f32_16x16x32_bf16 v[32:35], v[172:175], v[196:199], v[32:35]
	s_barrier
	v_mfma_f32_16x16x32_bf16 v[20:23], v[148:151], v[204:207], v[20:23]
	v_mfma_f32_16x16x32_bf16 v[16:19], v[172:175], v[204:207], v[16:19]
	v_mfma_f32_16x16x32_bf16 v[4:7], v[148:151], v[212:215], v[4:7]
	v_mfma_f32_16x16x32_bf16 v[0:3], v[172:175], v[212:215], v[0:3]
	s_setprio 0
	s_add_i32 s55, s55, 2
	s_add_u32 s53, s53, 0x100
	s_addc_u32 s54, s54, 0
	s_cmp_gt_u32 s55, 41
	s_mov_b64 s[28:29], s[30:31]
	s_cbranch_scc0 .LBB0_2697
	s_and_b64 vcc, exec, s[16:17]
	s_cbranch_vccz .LBB0_2700
	s_barrier

; #define PG8_STAGE(bufoff, gbase, voff) do { _Pragma("unroll") for (int _i = 0; _i < 2; ++_i) \
;         __builtin_amdgcn_global_load_lds((const unsigned*)((const char*)(gbase) + (voff)[_i]), (PG8_LAS unsigned*)(lds + (bufoff) + ldsw + _i * 8192), 16, 0, 0); } while (0)
; #define PG8_LDA(dst, b, h) do { _Pragma("unroll") for (int m = 0; m < 4; ++m) _Pragma("unroll") for (int k = 0; k < 2; ++k) dst[m][k] = *(const PG8_LAS bf16x8*)(lds + PG8_SA(b, h) + aoff + m * 2048 + k * 1024); } while (0)
; #define PG8_LDB(dst, b, h) do { _Pragma("unroll") for (int n = 0; n < 2; ++n) _Pragma("unroll") for (int k = 0; k < 2; ++k) dst[n][k] = *(const PG8_LAS bf16x8*)(lds + PG8_SB(b, h) + boff + n * 2048 + k * 1024); } while (0)
; #define PG8_MMA(ai, bj, At, Bt) do { __builtin_amdgcn_s_setprio(1); _Pragma("unroll") for (int m = 0; m < 4; ++m) _Pragma("unroll") for (int n = 0; n < 2; ++n) _Pragma("unroll") for (int k = 0; k < 2; ++k) \
;         acc[ai][bj][m][n] = mma16<F16>(Bt[n][k], At[m][k], acc[ai][bj][m][n]); __builtin_amdgcn_s_setprio(0); } while (0)
; #define PG8_WAIT_V(n) asm volatile("s_waitcnt vmcnt(" #n ")" ::: "memory")
; #define PG8_WAIT_L(n) asm volatile("s_waitcnt lgkmcnt(" #n ")" ::: "memory")
; #define PG8_BAR __builtin_amdgcn_s_barrier()
; #define PG8_SCHED __builtin_amdgcn_sched_barrier(0)
; template <class Epi, class Sched, bool ALIGN_EPI = false, bool SP2 = false, bool F16 = false>
; __device__ __forceinline__ void gemm_phase(PG8_LAS unsigned char* lds, const Gemm g, const Sched& S, const Epi& E, const int wid_in) {
;     ...
;             PG8_LDB(B0, 0, 0); PG8_LDB(B1, 0, 1); PG8_SCHED; PG8_LDA(At, 0, 0); PG8_STAGE(PG8_SA(1, 1), a1 + hstep, voffA);
;             PG8_WAIT_V(8); PG8_WAIT_L(0); PG8_BAR; PG8_MMA(0, 0, At, B0); PG8_MMA(0, 1, At, B1); PG8_BAR; PG8_SCHED;
;             PG8_LDA(At, 0, 1); PG8_STAGE(PG8_SB(0, 0), b2, voffB); PG8_STAGE(PG8_SB(0, 1), b2 + hstep, voffB); PG8_STAGE(PG8_SA(0, 0), a2, voffA);
;             PG8_WAIT_V(8); PG8_WAIT_L(0); PG8_BAR; PG8_MMA(1, 0, At, B0); PG8_MMA(1, 1, At, B1); PG8_BAR; PG8_SCHED;
.LBB0_2793:
	ds_read_b128 v[112:115], v235
	ds_read_b128 v[116:119], v235 offset:1024
	ds_read_b128 v[128:131], v235 offset:2048
	ds_read_b128 v[132:135], v235 offset:3072
	ds_read_b128 v[144:147], v236
	ds_read_b128 v[148:151], v236 offset:1024
	ds_read_b128 v[152:155], v236 offset:2048
	ds_read_b128 v[156:159], v236 offset:3072
	s_add_u32 s44, s42, 0xfffc0080
	s_addc_u32 s45, s43, -1
	s_cmp_eq_u32 s59, 12
	s_cselect_b32 s47, s14, s45
	s_cselect_b32 s46, s15, s44
	s_cselect_b32 s45, s29, s58
	s_cselect_b32 s44, s31, s41
	s_mov_b32 m0, s91
	v_lshl_add_u64 v[192:193], s[42:43], 0, v[204:205]
	ds_read_b128 v[160:163], v237
	ds_read_b128 v[164:167], v237 offset:1024
	ds_read_b128 v[168:171], v237 offset:2048
	ds_read_b128 v[172:175], v237 offset:3072
	ds_read_b128 v[176:179], v237 offset:4096
	ds_read_b128 v[180:183], v237 offset:5120
	ds_read_b128 v[184:187], v237 offset:6144
	ds_read_b128 v[188:191], v237 offset:7168
	global_load_lds_dwordx4 v[192:193], off
	v_lshl_add_u64 v[192:193], s[42:43], 0, v[206:207]
	s_add_i32 m0, s74, 0xe000
	s_nop 0
	global_load_lds_dwordx4 v[192:193], off
	s_waitcnt vmcnt(8)
	s_waitcnt lgkmcnt(0)
	s_barrier
	s_setprio 1
	s_waitcnt lgkmcnt(0)
	v_mfma_f32_16x16x32_f16 v[140:143], v[112:115], v[160:163], v[140:143]
	v_mfma_f32_16x16x32_f16 v[136:139], v[128:131], v[160:163], v[136:139]
	v_mfma_f32_16x16x32_f16 v[108:111], v[112:115], v[168:171], v[108:111]
	v_mfma_f32_16x16x32_f16 v[104:107], v[128:131], v[168:171], v[104:107]
	v_mfma_f32_16x16x32_f16 v[92:95], v[112:115], v[176:179], v[92:95]
	v_mfma_f32_16x16x32_f16 v[88:91], v[128:131], v[176:179], v[88:91]
	v_mfma_f32_16x16x32_f16 v[76:79], v[112:115], v[184:187], v[76:79]
	v_mfma_f32_16x16x32_f16 v[72:75], v[128:131], v[184:187], v[72:75]
	v_mfma_f32_16x16x32_f16 v[140:143], v[116:119], v[164:167], v[140:143]
	v_mfma_f32_16x16x32_f16 v[136:139], v[132:135], v[164:167], v[136:139]
	v_mfma_f32_16x16x32_f16 v[108:111], v[116:119], v[172:175], v[108:111]
	v_mfma_f32_16x16x32_f16 v[104:107], v[132:135], v[172:175], v[104:107]
	v_mfma_f32_16x16x32_f16 v[92:95], v[116:119], v[180:183], v[92:95]
	v_mfma_f32_16x16x32_f16 v[88:91], v[132:135], v[180:183], v[88:91]
	v_mfma_f32_16x16x32_f16 v[76:79], v[116:119], v[188:191], v[76:79]
	v_mfma_f32_16x16x32_f16 v[72:75], v[132:135], v[188:191], v[72:75]
	s_setprio 0
	s_setprio 1
	v_mfma_f32_16x16x32_f16 v[124:127], v[144:147], v[160:163], v[124:127]
	v_mfma_f32_16x16x32_f16 v[120:123], v[152:155], v[160:163], v[120:123]
	v_mfma_f32_16x16x32_f16 v[100:103], v[144:147], v[168:171], v[100:103]
	v_mfma_f32_16x16x32_f16 v[96:99], v[152:155], v[168:171], v[96:99]
	v_mfma_f32_16x16x32_f16 v[84:87], v[144:147], v[176:179], v[84:87]
	v_mfma_f32_16x16x32_f16 v[80:83], v[152:155], v[176:179], v[80:83]
	v_mfma_f32_16x16x32_f16 v[68:71], v[144:147], v[184:187], v[68:71]
	v_mfma_f32_16x16x32_f16 v[64:67], v[152:155], v[184:187], v[64:67]
	v_mfma_f32_16x16x32_f16 v[124:127], v[148:151], v[164:167], v[124:127]
	v_mfma_f32_16x16x32_f16 v[120:123], v[156:159], v[164:167], v[120:123]
	v_mfma_f32_16x16x32_f16 v[100:103], v[148:151], v[172:175], v[100:103]
	v_mfma_f32_16x16x32_f16 v[96:99], v[156:159], v[172:175], v[96:99]
	s_barrier
	v_mfma_f32_16x16x32_f16 v[84:87], v[148:151], v[180:183], v[84:87]
	v_mfma_f32_16x16x32_f16 v[80:83], v[156:159], v[180:183], v[80:83]
	v_mfma_f32_16x16x32_f16 v[68:71], v[148:151], v[188:191], v[68:71]
	v_mfma_f32_16x16x32_f16 v[64:67], v[156:159], v[188:191], v[64:67]
	s_setprio 0
	s_add_i32 s60, s55, s68
	v_lshl_add_u64 v[192:193], s[44:45], 0, v[198:199]
	s_mov_b32 m0, s60
	ds_read_b128 v[160:163], v237 offset:16384
	ds_read_b128 v[164:167], v237 offset:17408
	ds_read_b128 v[168:171], v237 offset:18432
	ds_read_b128 v[172:175], v237 offset:19456
	ds_read_b128 v[176:179], v237 offset:20480
	ds_read_b128 v[180:183], v237 offset:21504
	ds_read_b128 v[184:187], v237 offset:22528
	ds_read_b128 v[188:191], v237 offset:23552
	global_load_lds_dwordx4 v[192:193], off
	s_add_i32 m0, s60, 0x2000
	s_add_u32 s60, s44, 0x40000
	v_lshl_add_u64 v[194:195], s[44:45], 0, v[202:203]
	s_addc_u32 s61, s45, 0
	s_add_i32 s62, s56, s68
	global_load_lds_dwordx4 v[194:195], off
	v_lshl_add_u64 v[212:213], s[60:61], 0, v[198:199]
	s_mov_b32 m0, s62
	v_lshl_add_u64 v[214:215], s[46:47], 0, v[200:201]
	global_load_lds_dwordx4 v[212:213], off
	v_lshl_add_u64 v[212:213], s[60:61], 0, v[202:203]
	s_add_i32 m0, s62, 0x2000
	s_nop 0
	global_load_lds_dwordx4 v[212:213], off
	v_lshl_add_u64 v[212:213], s[46:47], 0, v[196:197]
	s_mov_b32 m0, s74
	s_nop 0
	global_load_lds_dwordx4 v[212:213], off
	s_mov_b32 m0, s66
	s_nop 0
	global_load_lds_dwordx4 v[214:215], off
	s_waitcnt vmcnt(8)
	s_waitcnt lgkmcnt(0)
	s_barrier
; #define PG8_STAGE(bufoff, gbase, voff) do { _Pragma("unroll") for (int _i = 0; _i < 2; ++_i) \
;         __builtin_amdgcn_global_load_lds((const unsigned*)((const char*)(gbase) + (voff)[_i]), (PG8_LAS unsigned*)(lds + (bufoff) + ldsw + _i * 8192), 16, 0, 0); } while (0)
; #define PG8_LDA(dst, b, h) do { _Pragma("unroll") for (int m = 0; m < 4; ++m) _Pragma("unroll") for (int k = 0; k < 2; ++k) dst[m][k] = *(const PG8_LAS bf16x8*)(lds + PG8_SA(b, h) + aoff + m * 2048 + k * 1024); } while (0)
; #define PG8_LDB(dst, b, h) do { _Pragma("unroll") for (int n = 0; n < 2; ++n) _Pragma("unroll") for (int k = 0; k < 2; ++k) dst[n][k] = *(const PG8_LAS bf16x8*)(lds + PG8_SB(b, h) + boff + n * 2048 + k * 1024); } while (0)
; #define PG8_MMA(ai, bj, At, Bt) do { __builtin_amdgcn_s_setprio(1); _Pragma("unroll") for (int m = 0; m < 4; ++m) _Pragma("unroll") for (int n = 0; n < 2; ++n) _Pragma("unroll") for (int k = 0; k < 2; ++k) \
;         acc[ai][bj][m][n] = mma16<F16>(Bt[n][k], At[m][k], acc[ai][bj][m][n]); __builtin_amdgcn_s_setprio(0); } while (0)
; #define PG8_WAIT_V(n) asm volatile("s_waitcnt vmcnt(" #n ")" ::: "memory")
; #define PG8_WAIT_L(n) asm volatile("s_waitcnt lgkmcnt(" #n ")" ::: "memory")
; #define PG8_BAR __builtin_amdgcn_s_barrier()
; #define PG8_SCHED __builtin_amdgcn_sched_barrier(0)
; template <class Epi, class Sched, bool ALIGN_EPI = false, bool SP2 = false, bool F16 = false>
; __device__ __forceinline__ void gemm_phase(PG8_LAS unsigned char* lds, const Gemm g, const Sched& S, const Epi& E, const int wid_in) {
;     ...
;             PG8_WAIT_V(8); PG8_WAIT_L(0); PG8_BAR; PG8_MMA(1, 0, At, B0); PG8_MMA(1, 1, At, B1); PG8_BAR; PG8_SCHED;
;             PG8_LDB(B0, 1, 0); PG8_LDB(B1, 1, 1); PG8_SCHED; PG8_LDA(At, 1, 0); PG8_STAGE(PG8_SA(0, 1), a2 + hstep, voffA);
;             PG8_WAIT_V(8); PG8_WAIT_L(0); PG8_BAR; PG8_MMA(0, 0, At, B0); PG8_MMA(0, 1, At, B1); PG8_BAR; PG8_SCHED;
	s_setprio 1
	s_waitcnt lgkmcnt(0)
	v_mfma_f32_16x16x32_f16 v[60:63], v[112:115], v[160:163], v[60:63]
	v_mfma_f32_16x16x32_f16 v[56:59], v[128:131], v[160:163], v[56:59]
	v_mfma_f32_16x16x32_f16 v[44:47], v[112:115], v[168:171], v[44:47]
	v_mfma_f32_16x16x32_f16 v[40:43], v[128:131], v[168:171], v[40:43]
	v_mfma_f32_16x16x32_f16 v[28:31], v[112:115], v[176:179], v[28:31]
	v_mfma_f32_16x16x32_f16 v[24:27], v[128:131], v[176:179], v[24:27]
	v_mfma_f32_16x16x32_f16 v[12:15], v[112:115], v[184:187], v[12:15]
	v_mfma_f32_16x16x32_f16 v[8:11], v[128:131], v[184:187], v[8:11]
	v_mfma_f32_16x16x32_f16 v[60:63], v[116:119], v[164:167], v[60:63]
	v_mfma_f32_16x16x32_f16 v[56:59], v[132:135], v[164:167], v[56:59]
	v_mfma_f32_16x16x32_f16 v[44:47], v[116:119], v[172:175], v[44:47]
	v_mfma_f32_16x16x32_f16 v[40:43], v[132:135], v[172:175], v[40:43]
	v_mfma_f32_16x16x32_f16 v[28:31], v[116:119], v[180:183], v[28:31]
	v_mfma_f32_16x16x32_f16 v[24:27], v[132:135], v[180:183], v[24:27]
	v_mfma_f32_16x16x32_f16 v[12:15], v[116:119], v[188:191], v[12:15]
	v_mfma_f32_16x16x32_f16 v[8:11], v[132:135], v[188:191], v[8:11]
	s_setprio 0
	s_setprio 1
	v_mfma_f32_16x16x32_f16 v[52:55], v[144:147], v[160:163], v[52:55]
	v_mfma_f32_16x16x32_f16 v[48:51], v[152:155], v[160:163], v[48:51]
	v_mfma_f32_16x16x32_f16 v[36:39], v[144:147], v[168:171], v[36:39]
	v_mfma_f32_16x16x32_f16 v[32:35], v[152:155], v[168:171], v[32:35]
	v_mfma_f32_16x16x32_f16 v[20:23], v[144:147], v[176:179], v[20:23]
	v_mfma_f32_16x16x32_f16 v[16:19], v[152:155], v[176:179], v[16:19]
	v_mfma_f32_16x16x32_f16 v[4:7], v[144:147], v[184:187], v[4:7]
	v_mfma_f32_16x16x32_f16 v[0:3], v[152:155], v[184:187], v[0:3]
	v_mfma_f32_16x16x32_f16 v[52:55], v[148:151], v[164:167], v[52:55]
	v_mfma_f32_16x16x32_f16 v[48:51], v[156:159], v[164:167], v[48:51]
	v_mfma_f32_16x16x32_f16 v[36:39], v[148:151], v[172:175], v[36:39]
	v_mfma_f32_16x16x32_f16 v[32:35], v[156:159], v[172:175], v[32:35]
	s_barrier
	v_mfma_f32_16x16x32_f16 v[20:23], v[148:151], v[180:183], v[20:23]
	v_mfma_f32_16x16x32_f16 v[16:19], v[156:159], v[180:183], v[16:19]
	v_mfma_f32_16x16x32_f16 v[4:7], v[148:151], v[188:191], v[4:7]
	v_mfma_f32_16x16x32_f16 v[0:3], v[156:159], v[188:191], v[0:3]
	s_setprio 0
	s_add_i32 s60, 0, 0x18000
	s_add_i32 s61, 0, 0x1c000
	v_add_u32_e32 v132, s60, v234
	v_add_u32_e32 v156, s61, v234
	ds_read_b128 v[112:115], v132
	ds_read_b128 v[116:119], v132 offset:1024
	ds_read_b128 v[128:131], v132 offset:2048
	ds_read_b128 v[132:135], v132 offset:3072
	ds_read_b128 v[144:147], v156
	ds_read_b128 v[148:151], v156 offset:1024
	ds_read_b128 v[152:155], v156 offset:2048
	ds_read_b128 v[156:159], v156 offset:3072
	s_add_u32 s46, s46, 0x40000
	s_addc_u32 s47, s47, 0
	s_mov_b32 m0, s90
	v_lshl_add_u64 v[216:217], s[46:47], 0, v[196:197]
	ds_read_b128 v[160:163], v237 offset:32768
	ds_read_b128 v[164:167], v237 offset:33792
	ds_read_b128 v[168:171], v237 offset:34816
	ds_read_b128 v[172:175], v237 offset:35840
	ds_read_b128 v[176:179], v237 offset:36864
	ds_read_b128 v[180:183], v237 offset:37888
	ds_read_b128 v[184:187], v237 offset:38912
	ds_read_b128 v[188:191], v237 offset:39936
	global_load_lds_dwordx4 v[216:217], off
	v_lshl_add_u64 v[216:217], s[46:47], 0, v[200:201]
	s_mov_b32 m0, s51
	s_nop 0
	global_load_lds_dwordx4 v[216:217], off
	s_waitcnt vmcnt(8)
	s_waitcnt lgkmcnt(0)
	s_barrier
	s_setprio 1
	s_waitcnt lgkmcnt(0)
	v_mfma_f32_16x16x32_f16 v[140:143], v[112:115], v[160:163], v[140:143]
	v_mfma_f32_16x16x32_f16 v[136:139], v[128:131], v[160:163], v[136:139]
	v_mfma_f32_16x16x32_f16 v[108:111], v[112:115], v[168:171], v[108:111]
	v_mfma_f32_16x16x32_f16 v[104:107], v[128:131], v[168:171], v[104:107]
	v_mfma_f32_16x16x32_f16 v[92:95], v[112:115], v[176:179], v[92:95]
	v_mfma_f32_16x16x32_f16 v[88:91], v[128:131], v[176:179], v[88:91]
	v_mfma_f32_16x16x32_f16 v[76:79], v[112:115], v[184:187], v[76:79]
	v_mfma_f32_16x16x32_f16 v[72:75], v[128:131], v[184:187], v[72:75]
	v_mfma_f32_16x16x32_f16 v[140:143], v[116:119], v[164:167], v[140:143]
	v_mfma_f32_16x16x32_f16 v[136:139], v[132:135], v[164:167], v[136:139]
	v_mfma_f32_16x16x32_f16 v[108:111], v[116:119], v[172:175], v[108:111]
	v_mfma_f32_16x16x32_f16 v[104:107], v[132:135], v[172:175], v[104:107]
	v_mfma_f32_16x16x32_f16 v[92:95], v[116:119], v[180:183], v[92:95]
	v_mfma_f32_16x16x32_f16 v[88:91], v[132:135], v[180:183], v[88:91]
	v_mfma_f32_16x16x32_f16 v[76:79], v[116:119], v[188:191], v[76:79]
	v_mfma_f32_16x16x32_f16 v[72:75], v[132:135], v[188:191], v[72:75]
	s_setprio 0
	s_setprio 1
	v_mfma_f32_16x16x32_f16 v[124:127], v[144:147], v[160:163], v[124:127]
	v_mfma_f32_16x16x32_f16 v[120:123], v[152:155], v[160:163], v[120:123]
	v_mfma_f32_16x16x32_f16 v[100:103], v[144:147], v[168:171], v[100:103]
	v_mfma_f32_16x16x32_f16 v[96:99], v[152:155], v[168:171], v[96:99]
	v_mfma_f32_16x16x32_f16 v[84:87], v[144:147], v[176:179], v[84:87]
	v_mfma_f32_16x16x32_f16 v[80:83], v[152:155], v[176:179], v[80:83]
	v_mfma_f32_16x16x32_f16 v[68:71], v[144:147], v[184:187], v[68:71]
	v_mfma_f32_16x16x32_f16 v[64:67], v[152:155], v[184:187], v[64:67]
	v_mfma_f32_16x16x32_f16 v[124:127], v[148:151], v[164:167], v[124:127]
	v_mfma_f32_16x16x32_f16 v[120:123], v[156:159], v[164:167], v[120:123]
	v_mfma_f32_16x16x32_f16 v[100:103], v[148:151], v[172:175], v[100:103]
	v_mfma_f32_16x16x32_f16 v[96:99], v[156:159], v[172:175], v[96:99]
	s_barrier
; #define PG8_STAGE(bufoff, gbase, voff) do { _Pragma("unroll") for (int _i = 0; _i < 2; ++_i) \
;         __builtin_amdgcn_global_load_lds((const unsigned*)((const char*)(gbase) + (voff)[_i]), (PG8_LAS unsigned*)(lds + (bufoff) + ldsw + _i * 8192), 16, 0, 0); } while (0)
; #define PG8_LDA(dst, b, h) do { _Pragma("unroll") for (int m = 0; m < 4; ++m) _Pragma("unroll") for (int k = 0; k < 2; ++k) dst[m][k] = *(const PG8_LAS bf16x8*)(lds + PG8_SA(b, h) + aoff + m * 2048 + k * 1024); } while (0)
; #define PG8_MMA(ai, bj, At, Bt) do { __builtin_amdgcn_s_setprio(1); _Pragma("unroll") for (int m = 0; m < 4; ++m) _Pragma("unroll") for (int n = 0; n < 2; ++n) _Pragma("unroll") for (int k = 0; k < 2; ++k) \
;         acc[ai][bj][m][n] = mma16<F16>(Bt[n][k], At[m][k], acc[ai][bj][m][n]); __builtin_amdgcn_s_setprio(0); } while (0)
; #define PG8_WAIT_V(n) asm volatile("s_waitcnt vmcnt(" #n ")" ::: "memory")
; #define PG8_WAIT_L(n) asm volatile("s_waitcnt lgkmcnt(" #n ")" ::: "memory")
; #define PG8_BAR __builtin_amdgcn_s_barrier()
; #define PG8_SCHED __builtin_amdgcn_sched_barrier(0)
; template <class Epi, class Sched, bool ALIGN_EPI = false, bool SP2 = false, bool F16 = false>
; __device__ __forceinline__ void gemm_phase(PG8_LAS unsigned char* lds, const Gemm g, const Sched& S, const Epi& E, const int wid_in) {
;     ...
;             PG8_WAIT_V(8); PG8_WAIT_L(0); PG8_BAR; PG8_MMA(0, 0, At, B0); PG8_MMA(0, 1, At, B1); PG8_BAR; PG8_SCHED;
;             PG8_LDA(At, 1, 1); PG8_STAGE(PG8_SB(1, 0), b3, voffB); PG8_STAGE(PG8_SB(1, 1), b3 + hstep, voffB); PG8_STAGE(PG8_SA(1, 0), a3, voffA);
;             PG8_WAIT_V(8); PG8_WAIT_L(0); PG8_BAR; PG8_MMA(1, 0, At, B0); PG8_MMA(1, 1, At, B1); PG8_BAR; PG8_SCHED;
	v_mfma_f32_16x16x32_f16 v[84:87], v[148:151], v[180:183], v[84:87]
	v_mfma_f32_16x16x32_f16 v[80:83], v[156:159], v[180:183], v[80:83]
	v_mfma_f32_16x16x32_f16 v[68:71], v[148:151], v[188:191], v[68:71]
	v_mfma_f32_16x16x32_f16 v[64:67], v[156:159], v[188:191], v[64:67]
	s_setprio 0
	s_add_i32 s46, s60, s68
	v_lshl_add_u64 v[192:193], v[192:193], 0, s[26:27]
	s_mov_b32 m0, s46
	ds_read_b128 v[160:163], v237 offset:49152
	ds_read_b128 v[164:167], v237 offset:50176
	ds_read_b128 v[168:171], v237 offset:51200
	ds_read_b128 v[172:175], v237 offset:52224
	ds_read_b128 v[176:179], v237 offset:53248
	ds_read_b128 v[180:183], v237 offset:54272
	ds_read_b128 v[184:187], v237 offset:55296
	ds_read_b128 v[188:191], v237 offset:56320
	global_load_lds_dwordx4 v[192:193], off
	s_add_i32 m0, s46, 0x2000
	s_add_u32 s44, s44, 0x40080
	v_lshl_add_u64 v[192:193], v[194:195], 0, s[26:27]
	s_addc_u32 s45, s45, 0
	s_add_i32 s46, s61, s68
	global_load_lds_dwordx4 v[192:193], off
	v_lshl_add_u64 v[192:193], s[44:45], 0, v[198:199]
	s_mov_b32 m0, s46
	s_nop 0
	global_load_lds_dwordx4 v[192:193], off
	v_lshl_add_u64 v[192:193], s[44:45], 0, v[202:203]
	s_add_i32 m0, s46, 0x2000
	s_nop 0
	global_load_lds_dwordx4 v[192:193], off
	v_lshl_add_u64 v[192:193], v[212:213], 0, s[26:27]
	s_mov_b32 m0, s75
	s_nop 0
	global_load_lds_dwordx4 v[192:193], off
	v_lshl_add_u64 v[192:193], v[214:215], 0, s[26:27]
	s_mov_b32 m0, s67
	s_nop 0
	global_load_lds_dwordx4 v[192:193], off
	s_waitcnt vmcnt(8)
	s_waitcnt lgkmcnt(0)
	s_barrier
	s_setprio 1
	s_waitcnt lgkmcnt(0)
	v_mfma_f32_16x16x32_f16 v[60:63], v[112:115], v[160:163], v[60:63]
	v_mfma_f32_16x16x32_f16 v[56:59], v[128:131], v[160:163], v[56:59]
	v_mfma_f32_16x16x32_f16 v[44:47], v[112:115], v[168:171], v[44:47]
	v_mfma_f32_16x16x32_f16 v[40:43], v[128:131], v[168:171], v[40:43]
	v_mfma_f32_16x16x32_f16 v[28:31], v[112:115], v[176:179], v[28:31]
	v_mfma_f32_16x16x32_f16 v[24:27], v[128:131], v[176:179], v[24:27]
	v_mfma_f32_16x16x32_f16 v[12:15], v[112:115], v[184:187], v[12:15]
	v_mfma_f32_16x16x32_f16 v[8:11], v[128:131], v[184:187], v[8:11]
	v_mfma_f32_16x16x32_f16 v[60:63], v[116:119], v[164:167], v[60:63]
	v_mfma_f32_16x16x32_f16 v[56:59], v[132:135], v[164:167], v[56:59]
	v_mfma_f32_16x16x32_f16 v[44:47], v[116:119], v[172:175], v[44:47]
	v_mfma_f32_16x16x32_f16 v[40:43], v[132:135], v[172:175], v[40:43]
	v_mfma_f32_16x16x32_f16 v[28:31], v[116:119], v[180:183], v[28:31]
	v_mfma_f32_16x16x32_f16 v[24:27], v[132:135], v[180:183], v[24:27]
	v_mfma_f32_16x16x32_f16 v[12:15], v[116:119], v[188:191], v[12:15]
	v_mfma_f32_16x16x32_f16 v[8:11], v[132:135], v[188:191], v[8:11]
	s_setprio 0
	s_setprio 1
	v_mfma_f32_16x16x32_f16 v[52:55], v[144:147], v[160:163], v[52:55]
	v_mfma_f32_16x16x32_f16 v[48:51], v[152:155], v[160:163], v[48:51]
	v_mfma_f32_16x16x32_f16 v[36:39], v[144:147], v[168:171], v[36:39]
	v_mfma_f32_16x16x32_f16 v[32:35], v[152:155], v[168:171], v[32:35]
	v_mfma_f32_16x16x32_f16 v[20:23], v[144:147], v[176:179], v[20:23]
	v_mfma_f32_16x16x32_f16 v[16:19], v[152:155], v[176:179], v[16:19]
	v_mfma_f32_16x16x32_f16 v[4:7], v[144:147], v[184:187], v[4:7]
	v_mfma_f32_16x16x32_f16 v[0:3], v[152:155], v[184:187], v[0:3]
	v_mfma_f32_16x16x32_f16 v[52:55], v[148:151], v[164:167], v[52:55]
	v_mfma_f32_16x16x32_f16 v[48:51], v[156:159], v[164:167], v[48:51]
	v_mfma_f32_16x16x32_f16 v[36:39], v[148:151], v[172:175], v[36:39]
	v_mfma_f32_16x16x32_f16 v[32:35], v[156:159], v[172:175], v[32:35]
	s_barrier
	v_mfma_f32_16x16x32_f16 v[20:23], v[148:151], v[180:183], v[20:23]
	v_mfma_f32_16x16x32_f16 v[16:19], v[156:159], v[180:183], v[16:19]
	v_mfma_f32_16x16x32_f16 v[4:7], v[148:151], v[188:191], v[4:7]
	v_mfma_f32_16x16x32_f16 v[0:3], v[156:159], v[188:191], v[0:3]
	s_setprio 0
	s_add_i32 s59, s59, 2
	s_add_u32 s42, s42, 0x100
	s_addc_u32 s43, s43, 0
	s_add_u32 s41, s41, 0x100
	s_addc_u32 s58, s58, 0
	s_cmp_gt_u32 s59, 13
	s_cbranch_scc0 .LBB0_2793
	s_and_b64 vcc, exec, s[16:17]
	s_cbranch_vccz .LBB0_2796
	s_barrier
